# k21 + 222 SGPR-pair constants folded into packed-f32 operands (v_mov_b64 deleted), explicit hazard-neighbourhood check
# speedup vs baseline: 1.0038x; 1.0016x over previous
.LBB0_1231:
	s_or_b64 exec, exec, s[6:7]
	v_sub_u32_e32 v26, 1, v142
	s_waitcnt lgkmcnt(0)
	v_add_u32_e32 v27, v143, v138
	v_mul_lo_u32 v26, v26, s25
	v_lshlrev_b32_e32 v152, 3, v27
	v_cvt_f32_ubyte0_e32 v34, v138
	v_add3_u32 v149, 0, v26, v152
	v_mul_f32_e32 v26, 0x39000000, v34
	v_sin_f32_e32 v37, v26
	v_cos_f32_e32 v36, v26
	v_mov_b32_e32 v26, s86
	v_xor_b32_e32 v37, 0x80000000, v37
	v_mov_b32_e32 v38, v36
	v_mov_b32_e32 v39, v37
	s_barrier
	ds_read_b128 v[30:33], v26
	ds_read_b128 v[26:29], v26 offset:16
	ds_read_b64 v[40:41], v144
	ds_read_b64 v[44:45], v149
	s_and_saveexec_b64 s[0:1], s[4:5]
	s_xor_b64 s[0:1], exec, s[0:1]
	s_cbranch_execz .LBB0_1233
	v_pk_mul_f32 v[46:47], v[38:39], s[16:17] op_sel:[0,0] op_sel_hi:[0,1]
	s_waitcnt lgkmcnt(0)
	v_sub_f32_e32 v40, v44, v40
	v_pk_fma_f32 v[42:43], v[38:39], s[16:17], v[46:47] op_sel:[1,1,0] op_sel_hi:[1,0,1] neg_lo:[0,1,0]
	s_nop 0
	v_pk_mul_f32 v[42:43], v[40:41], v[42:43] op_sel_hi:[0,1]

.LBB0_1235:
	s_or_b64 exec, exec, s[0:1]
	s_waitcnt lgkmcnt(1)
	ds_read_b64 v[40:41], v144 offset:2176
	ds_read_b64 v[46:47], v149 offset:2176
	s_and_saveexec_b64 s[0:1], s[4:5]
	s_xor_b64 s[0:1], exec, s[0:1]
	s_cbranch_execz .LBB0_1237
	s_waitcnt lgkmcnt(2)
	v_pk_mul_f32 v[48:49], v[38:39], s[18:19] op_sel:[0,0] op_sel_hi:[0,1]
	s_waitcnt lgkmcnt(0)
	v_sub_f32_e32 v40, v46, v40
	v_pk_fma_f32 v[44:45], v[38:39], s[18:19], v[48:49] op_sel:[1,1,0] op_sel_hi:[1,0,1] neg_lo:[0,1,0]
	s_nop 0
	v_pk_mul_f32 v[44:45], v[40:41], v[44:45] op_sel_hi:[0,1]

.LBB0_1239:
	s_or_b64 exec, exec, s[0:1]
	s_waitcnt lgkmcnt(1)
	ds_read_b64 v[40:41], v144 offset:4352
	ds_read_b64 v[48:49], v149 offset:4352
	s_and_saveexec_b64 s[0:1], s[4:5]
	s_xor_b64 s[0:1], exec, s[0:1]
	s_cbranch_execz .LBB0_1241
	s_waitcnt lgkmcnt(2)
	v_pk_mul_f32 v[50:51], v[38:39], s[20:21] op_sel:[0,0] op_sel_hi:[0,1]
	s_waitcnt lgkmcnt(0)
	v_sub_f32_e32 v40, v48, v40
	v_pk_fma_f32 v[46:47], v[38:39], s[20:21], v[50:51] op_sel:[1,1,0] op_sel_hi:[1,0,1] neg_lo:[0,1,0]
	s_nop 0
	v_pk_mul_f32 v[46:47], v[40:41], v[46:47] op_sel_hi:[0,1]

.LBB0_1243:
	s_or_b64 exec, exec, s[0:1]
	s_waitcnt lgkmcnt(1)
	ds_read_b64 v[40:41], v144 offset:6528
	ds_read_b64 v[50:51], v149 offset:6528
	s_and_saveexec_b64 s[0:1], s[4:5]
	s_xor_b64 s[0:1], exec, s[0:1]
	s_cbranch_execz .LBB0_1245
	s_waitcnt lgkmcnt(2)
	v_pk_mul_f32 v[52:53], v[38:39], s[22:23] op_sel:[0,0] op_sel_hi:[0,1]
	s_waitcnt lgkmcnt(0)
	v_sub_f32_e32 v40, v50, v40
	v_pk_fma_f32 v[48:49], v[38:39], s[22:23], v[52:53] op_sel:[1,1,0] op_sel_hi:[1,0,1] neg_lo:[0,1,0]
	s_nop 0
	v_pk_mul_f32 v[48:49], v[40:41], v[48:49] op_sel_hi:[0,1]

.LBB0_1247:
	s_or_b64 exec, exec, s[0:1]
	s_waitcnt lgkmcnt(1)
	ds_read_b64 v[40:41], v144 offset:8704
	ds_read_b64 v[52:53], v149 offset:8704
	s_and_saveexec_b64 s[0:1], s[4:5]
	s_xor_b64 s[0:1], exec, s[0:1]
	s_cbranch_execz .LBB0_1249
	s_waitcnt lgkmcnt(2)
	v_pk_mul_f32 v[54:55], v[38:39], s[50:51] op_sel:[0,0] op_sel_hi:[0,1]
	s_waitcnt lgkmcnt(0)
	v_sub_f32_e32 v40, v52, v40
	v_pk_fma_f32 v[50:51], v[38:39], s[50:51], v[54:55] op_sel:[1,1,0] op_sel_hi:[1,0,1] neg_lo:[0,1,0]
	s_nop 0
	v_pk_mul_f32 v[50:51], v[40:41], v[50:51] op_sel_hi:[0,1]

.LBB0_1251:
	s_or_b64 exec, exec, s[0:1]
	s_waitcnt lgkmcnt(1)
	ds_read_b64 v[40:41], v144 offset:10880
	ds_read_b64 v[54:55], v149 offset:10880
	s_and_saveexec_b64 s[0:1], s[4:5]
	s_xor_b64 s[0:1], exec, s[0:1]
	s_cbranch_execz .LBB0_1253
	s_waitcnt lgkmcnt(2)
	v_pk_mul_f32 v[56:57], v[38:39], s[52:53] op_sel:[0,0] op_sel_hi:[0,1]
	s_waitcnt lgkmcnt(0)
	v_sub_f32_e32 v40, v54, v40
	v_pk_fma_f32 v[52:53], v[38:39], s[52:53], v[56:57] op_sel:[1,1,0] op_sel_hi:[1,0,1] neg_lo:[0,1,0]
	s_nop 0
	v_pk_mul_f32 v[52:53], v[40:41], v[52:53] op_sel_hi:[0,1]

.LBB0_1255:
	s_or_b64 exec, exec, s[0:1]
	s_waitcnt lgkmcnt(1)
	ds_read_b64 v[40:41], v144 offset:13056
	ds_read_b64 v[56:57], v149 offset:13056
	s_and_saveexec_b64 s[0:1], s[4:5]
	s_xor_b64 s[0:1], exec, s[0:1]
	s_cbranch_execz .LBB0_1257
	s_waitcnt lgkmcnt(2)
	v_pk_mul_f32 v[58:59], v[38:39], s[54:55] op_sel:[0,0] op_sel_hi:[0,1]
	s_waitcnt lgkmcnt(0)
	v_sub_f32_e32 v40, v56, v40
	v_pk_fma_f32 v[54:55], v[38:39], s[54:55], v[58:59] op_sel:[1,1,0] op_sel_hi:[1,0,1] neg_lo:[0,1,0]
	s_nop 0
	v_pk_mul_f32 v[54:55], v[40:41], v[54:55] op_sel_hi:[0,1]

.LBB0_1259:
	s_or_b64 exec, exec, s[0:1]
	s_waitcnt lgkmcnt(1)
	ds_read_b64 v[40:41], v144 offset:15232
	ds_read_b64 v[58:59], v149 offset:15232
	s_and_saveexec_b64 s[0:1], s[4:5]
	s_xor_b64 s[0:1], exec, s[0:1]
	s_cbranch_execz .LBB0_1261
	s_waitcnt lgkmcnt(2)
	v_pk_mul_f32 v[60:61], v[38:39], s[56:57] op_sel:[0,0] op_sel_hi:[0,1]
	s_waitcnt lgkmcnt(0)
	v_sub_f32_e32 v40, v58, v40
	v_pk_fma_f32 v[56:57], v[38:39], s[56:57], v[60:61] op_sel:[1,1,0] op_sel_hi:[1,0,1] neg_lo:[0,1,0]
	s_nop 0
	v_pk_mul_f32 v[56:57], v[40:41], v[56:57] op_sel_hi:[0,1]

.LBB0_1263:
	s_or_b64 exec, exec, s[0:1]
	s_waitcnt lgkmcnt(1)
	ds_read_b64 v[40:41], v144 offset:17408
	ds_read_b64 v[60:61], v149 offset:17408
	s_and_saveexec_b64 s[0:1], s[4:5]
	s_xor_b64 s[0:1], exec, s[0:1]
	s_cbranch_execz .LBB0_1265
	s_waitcnt lgkmcnt(2)
	v_pk_mul_f32 v[62:63], v[38:39], s[14:15] op_sel:[0,0] op_sel_hi:[0,1]
	s_waitcnt lgkmcnt(0)
	v_sub_f32_e32 v40, v60, v40
	v_pk_fma_f32 v[58:59], v[38:39], s[14:15], v[62:63] op_sel:[1,1,0] op_sel_hi:[1,0,1] neg_lo:[0,1,0]
	s_nop 0
	v_pk_mul_f32 v[58:59], v[40:41], v[58:59] op_sel_hi:[0,1]

.LBB0_1328:
	s_or_b64 exec, exec, s[0:1]
	s_addk_i32 s6, 0x800
	s_waitcnt lgkmcnt(0)
	ds_write_b64 v43, v[122:123]
	s_cmpk_lg_u32 s6, 0x8000
	v_add_u32_e32 v43, 0x880, v43
	v_pk_mul_f32 v[154:155], v[120:121], s[18:19] op_sel:[0,0] op_sel_hi:[0,1]
	v_pk_fma_f32 v[120:121], v[120:121], s[18:19], v[154:155] op_sel:[1,1,0] op_sel_hi:[1,0,1] neg_lo:[0,1,0]
	s_cbranch_scc0 .LBB0_1331

.LBB0_1331:
	v_mov_b32_e32 v120, v30
	v_mov_b32_e32 v121, v26
	v_mov_b32_e32 v26, v31
	v_mov_b32_e32 v30, v32
	v_mov_b32_e32 v31, v28
	v_mov_b32_e32 v28, v33
	v_pk_add_f32 v[26:27], v[120:121], v[26:27]
	v_pk_add_f32 v[28:29], v[30:31], v[28:29]
	v_pk_add_f32 v[32:33], v[90:91], v[110:111]
	v_pk_add_f32 v[26:27], v[26:27], v[28:29]
	v_pk_add_f32 v[28:29], v[80:81], v[86:87]
	v_add_f32_e32 v43, v26, v27
	v_add_f32_e32 v43, 0x358637bd, v43
	v_mul_f32_e32 v43, 0x46000000, v43
	v_div_scale_f32 v45, s[0:1], v43, v43, 1.0
	v_rcp_f32_e32 v47, v45
	v_pk_add_f32 v[26:27], v[78:79], v[82:83]
	v_fma_f32 v49, -v45, v47, 1.0
	v_fmac_f32_e32 v47, v49, v47
	v_div_scale_f32 v49, vcc, 1.0, v43, 1.0
	v_mul_f32_e32 v51, v49, v47
	v_fma_f32 v53, -v45, v51, v49
	v_pk_add_f32 v[30:31], v[26:27], v[28:29]
	v_pk_add_f32 v[26:27], v[26:27], v[28:29] neg_lo:[0,1] neg_hi:[0,1]
	v_pk_add_f32 v[28:29], v[76:77], v[94:95]
	v_fmac_f32_e32 v51, v53, v47
	v_pk_add_f32 v[76:77], v[28:29], v[32:33]
	v_pk_add_f32 v[28:29], v[28:29], v[32:33] neg_lo:[0,1] neg_hi:[0,1]
	v_pk_add_f32 v[32:33], v[72:73], v[112:113]
	v_pk_add_f32 v[72:73], v[108:109], v[116:117]
	v_fma_f32 v45, -v45, v51, v49
	v_pk_add_f32 v[78:79], v[32:33], v[72:73]
	v_pk_add_f32 v[32:33], v[32:33], v[72:73] neg_lo:[0,1] neg_hi:[0,1]
	v_pk_add_f32 v[72:73], v[74:75], v[118:119]
	v_pk_add_f32 v[74:75], v[92:93], v[114:115]
	v_div_fmas_f32 v45, v45, v47, v51
	v_pk_add_f32 v[108:109], v[72:73], v[74:75]
	v_pk_add_f32 v[110:111], v[72:73], v[74:75] neg_lo:[0,1] neg_hi:[0,1]
	v_div_fixup_f32 v112, v45, v43, 1.0
	v_pk_mul_f32 v[94:95], v[112:113], v[30:31] op_sel_hi:[0,1]
	v_pk_mul_f32 v[92:93], v[112:113], v[84:85] op_sel_hi:[0,1]
	v_pk_mul_f32 v[90:91], v[112:113], v[26:27] op_sel_hi:[0,1]
	v_pk_mul_f32 v[88:89], v[112:113], v[88:89] op_sel_hi:[0,1]
	v_pk_mul_f32 v[86:87], v[112:113], v[76:77] op_sel_hi:[0,1]
	v_pk_mul_f32 v[84:85], v[112:113], v[96:97] op_sel_hi:[0,1]
	v_pk_mul_f32 v[82:83], v[112:113], v[28:29] op_sel_hi:[0,1]
	v_pk_mul_f32 v[80:81], v[112:113], v[98:99] op_sel_hi:[0,1]
	v_pk_mul_f32 v[78:79], v[112:113], v[78:79] op_sel_hi:[0,1]
	v_pk_mul_f32 v[76:77], v[112:113], v[100:101] op_sel_hi:[0,1]
	v_pk_mul_f32 v[74:75], v[112:113], v[32:33] op_sel_hi:[0,1]
	v_pk_mul_f32 v[72:73], v[112:113], v[102:103] op_sel_hi:[0,1]
	v_pk_mul_f32 v[32:33], v[112:113], v[108:109] op_sel_hi:[0,1]
	v_pk_mul_f32 v[30:31], v[112:113], v[104:105] op_sel_hi:[0,1]
	v_pk_mul_f32 v[28:29], v[112:113], v[110:111] op_sel_hi:[0,1]
	v_pk_mul_f32 v[26:27], v[112:113], v[106:107] op_sel_hi:[0,1]
	ds_read_b64 v[96:97], v144
	ds_read_b64 v[98:99], v144 offset:2176
	ds_read_b64 v[100:101], v144 offset:4352
	ds_read_b64 v[102:103], v144 offset:6528
	ds_read_b64 v[104:105], v144 offset:8704
	ds_read_b64 v[106:107], v144 offset:10880
	ds_read_b64 v[108:109], v144 offset:13056
	ds_read_b64 v[110:111], v144 offset:15232
	ds_read_b64 v[112:113], v144 offset:17408
	ds_read_b64 v[114:115], v144 offset:19584
	ds_read_b64 v[116:117], v144 offset:21760
	ds_read_b64 v[118:119], v144 offset:23936
	ds_read_b64 v[120:121], v144 offset:26112
	ds_read_b64 v[122:123], v144 offset:28288
	ds_read_b64 v[154:155], v144 offset:30464
	ds_read_b64 v[156:157], v144 offset:32640
	s_waitcnt lgkmcnt(7)
	v_pk_add_f32 v[158:159], v[96:97], v[112:113]
	v_pk_add_f32 v[96:97], v[96:97], v[112:113] neg_lo:[0,1] neg_hi:[0,1]
	s_waitcnt lgkmcnt(3)
	v_pk_add_f32 v[112:113], v[104:105], v[120:121]
	v_pk_add_f32 v[104:105], v[104:105], v[120:121] neg_lo:[0,1] neg_hi:[0,1]
	v_pk_add_f32 v[120:121], v[158:159], v[112:113]
	v_pk_add_f32 v[112:113], v[158:159], v[112:113] neg_lo:[0,1] neg_hi:[0,1]
	v_pk_add_f32 v[158:159], v[96:97], v[104:105] op_sel:[0,1] op_sel_hi:[1,0] neg_hi:[0,1]
	v_pk_add_f32 v[160:161], v[96:97], v[104:105] op_sel:[0,1] op_sel_hi:[1,0] neg_lo:[0,1]
	v_pk_add_f32 v[96:97], v[98:99], v[114:115]
	v_pk_add_f32 v[98:99], v[98:99], v[114:115] neg_lo:[0,1] neg_hi:[0,1]
	s_waitcnt lgkmcnt(2)
	v_pk_add_f32 v[104:105], v[106:107], v[122:123]
	v_pk_add_f32 v[106:107], v[106:107], v[122:123] neg_lo:[0,1] neg_hi:[0,1]
	v_pk_add_f32 v[114:115], v[96:97], v[104:105]
	v_pk_add_f32 v[104:105], v[96:97], v[104:105] neg_lo:[0,1] neg_hi:[0,1]
	v_pk_add_f32 v[96:97], v[98:99], v[106:107] op_sel:[0,1] op_sel_hi:[1,0] neg_hi:[0,1]
	v_pk_add_f32 v[106:107], v[98:99], v[106:107] op_sel:[0,1] op_sel_hi:[1,0] neg_lo:[0,1]
	v_pk_add_f32 v[98:99], v[100:101], v[116:117]
	v_pk_add_f32 v[100:101], v[100:101], v[116:117] neg_lo:[0,1] neg_hi:[0,1]
	s_waitcnt lgkmcnt(1)
	v_pk_add_f32 v[116:117], v[108:109], v[154:155]
	v_pk_add_f32 v[108:109], v[108:109], v[154:155] neg_lo:[0,1] neg_hi:[0,1]
	v_pk_add_f32 v[122:123], v[98:99], v[116:117]
	v_pk_add_f32 v[116:117], v[98:99], v[116:117] neg_lo:[0,1] neg_hi:[0,1]
	v_pk_add_f32 v[154:155], v[100:101], v[108:109] op_sel:[0,1] op_sel_hi:[1,0] neg_hi:[0,1]
	v_pk_add_f32 v[108:109], v[100:101], v[108:109] op_sel:[0,1] op_sel_hi:[1,0] neg_lo:[0,1]
	v_pk_add_f32 v[98:99], v[102:103], v[118:119]
	v_pk_add_f32 v[100:101], v[102:103], v[118:119] neg_lo:[0,1] neg_hi:[0,1]
	s_waitcnt lgkmcnt(0)
	v_pk_add_f32 v[102:103], v[110:111], v[156:157]
	v_pk_add_f32 v[110:111], v[110:111], v[156:157] neg_lo:[0,1] neg_hi:[0,1]
	v_pk_add_f32 v[118:119], v[98:99], v[102:103]
	v_pk_add_f32 v[156:157], v[98:99], v[102:103] neg_lo:[0,1] neg_hi:[0,1]
	v_pk_mul_f32 v[98:99], v[96:97], s[20:21] op_sel:[0,0] op_sel_hi:[0,1]
	v_pk_add_f32 v[162:163], v[100:101], v[110:111] op_sel:[0,1] op_sel_hi:[1,0] neg_hi:[0,1]
	v_pk_add_f32 v[110:111], v[100:101], v[110:111] op_sel:[0,1] op_sel_hi:[1,0] neg_lo:[0,1]
	v_pk_fma_f32 v[164:165], v[96:97], s[20:21], v[98:99] op_sel:[1,1,0] op_sel_hi:[1,0,1] neg_lo:[0,1,0]
	v_pk_mul_f32 v[96:97], v[154:155], s[50:51] op_sel:[0,0] op_sel_hi:[0,1]
	v_pk_fma_f32 v[154:155], v[154:155], s[50:51], v[96:97] op_sel:[1,1,0] op_sel_hi:[1,0,1] neg_lo:[0,1,0]
	v_pk_mul_f32 v[100:101], v[162:163], s[54:55] op_sel:[0,0] op_sel_hi:[0,1]
	v_pk_fma_f32 v[162:163], v[162:163], s[54:55], v[100:101] op_sel:[1,1,0] op_sel_hi:[1,0,1] neg_lo:[0,1,0]
	v_pk_mul_f32 v[100:101], v[104:105], s[50:51] op_sel:[0,0] op_sel_hi:[0,1]
	v_pk_fma_f32 v[166:167], v[104:105], s[50:51], v[100:101] op_sel:[1,1,0] op_sel_hi:[1,0,1] neg_lo:[0,1,0]
	v_pk_mul_f32 v[100:101], v[116:117], s[14:15] op_sel:[0,0] op_sel_hi:[0,1]
	v_pk_fma_f32 v[116:117], v[116:117], s[14:15], v[100:101] op_sel:[1,1,0] op_sel_hi:[1,0,1] neg_lo:[0,1,0]
	v_pk_mul_f32 v[168:169], v[156:157], s[58:59] op_sel:[0,0] op_sel_hi:[0,1]
	v_pk_fma_f32 v[156:157], v[156:157], s[58:59], v[168:169] op_sel:[1,1,0] op_sel_hi:[1,0,1] neg_lo:[0,1,0]
	v_pk_mul_f32 v[168:169], v[106:107], s[54:55] op_sel:[0,0] op_sel_hi:[0,1]
	v_pk_fma_f32 v[168:169], v[106:107], s[54:55], v[168:169] op_sel:[1,1,0] op_sel_hi:[1,0,1] neg_lo:[0,1,0]
	v_pk_mul_f32 v[106:107], v[108:109], s[58:59] op_sel:[0,0] op_sel_hi:[0,1]
	v_pk_fma_f32 v[108:109], v[108:109], s[58:59], v[106:107] op_sel:[1,1,0] op_sel_hi:[1,0,1] neg_lo:[0,1,0]
	v_pk_mul_f32 v[170:171], v[110:111], s[60:61] op_sel:[0,0] op_sel_hi:[0,1]
	v_pk_fma_f32 v[110:111], v[110:111], s[60:61], v[170:171] op_sel:[1,1,0] op_sel_hi:[1,0,1] neg_lo:[0,1,0]
	v_pk_add_f32 v[170:171], v[120:121], v[122:123]
	v_pk_add_f32 v[120:121], v[120:121], v[122:123] neg_lo:[0,1] neg_hi:[0,1]
	v_pk_add_f32 v[122:123], v[114:115], v[118:119]
	v_pk_add_f32 v[114:115], v[114:115], v[118:119] neg_lo:[0,1] neg_hi:[0,1]
	v_pk_add_f32 v[118:119], v[170:171], v[122:123]
	v_pk_add_f32 v[122:123], v[170:171], v[122:123] neg_lo:[0,1] neg_hi:[0,1]
	v_pk_add_f32 v[170:171], v[120:121], v[114:115] op_sel:[0,1] op_sel_hi:[1,0] neg_hi:[0,1]
	v_pk_add_f32 v[114:115], v[120:121], v[114:115] op_sel:[0,1] op_sel_hi:[1,0] neg_lo:[0,1]
	v_pk_add_f32 v[120:121], v[158:159], v[154:155]
	v_pk_add_f32 v[154:155], v[158:159], v[154:155] neg_lo:[0,1] neg_hi:[0,1]
	v_pk_add_f32 v[158:159], v[164:165], v[162:163]
	v_pk_add_f32 v[162:163], v[164:165], v[162:163] neg_lo:[0,1] neg_hi:[0,1]
	v_pk_add_f32 v[164:165], v[120:121], v[158:159]
	v_pk_add_f32 v[120:121], v[120:121], v[158:159] neg_lo:[0,1] neg_hi:[0,1]
	v_pk_add_f32 v[158:159], v[154:155], v[162:163] op_sel:[0,1] op_sel_hi:[1,0] neg_hi:[0,1]
	v_pk_add_f32 v[154:155], v[154:155], v[162:163] op_sel:[0,1] op_sel_hi:[1,0] neg_lo:[0,1]
	v_pk_add_f32 v[162:163], v[112:113], v[116:117]
	v_pk_add_f32 v[112:113], v[112:113], v[116:117] neg_lo:[0,1] neg_hi:[0,1]
	v_pk_add_f32 v[116:117], v[166:167], v[156:157]
	v_pk_add_f32 v[156:157], v[166:167], v[156:157] neg_lo:[0,1] neg_hi:[0,1]
	v_pk_add_f32 v[166:167], v[162:163], v[116:117]
	v_pk_add_f32 v[116:117], v[162:163], v[116:117] neg_lo:[0,1] neg_hi:[0,1]
	v_pk_add_f32 v[162:163], v[112:113], v[156:157] op_sel:[0,1] op_sel_hi:[1,0] neg_hi:[0,1]
	v_pk_add_f32 v[112:113], v[112:113], v[156:157] op_sel:[0,1] op_sel_hi:[1,0] neg_lo:[0,1]
	v_pk_add_f32 v[156:157], v[160:161], v[108:109]
	v_pk_add_f32 v[108:109], v[160:161], v[108:109] neg_lo:[0,1] neg_hi:[0,1]
	v_pk_add_f32 v[160:161], v[168:169], v[110:111]
	v_pk_add_f32 v[110:111], v[168:169], v[110:111] neg_lo:[0,1] neg_hi:[0,1]
	v_pk_add_f32 v[168:169], v[156:157], v[160:161]
	v_pk_add_f32 v[156:157], v[156:157], v[160:161] neg_lo:[0,1] neg_hi:[0,1]
	v_pk_add_f32 v[160:161], v[108:109], v[110:111] op_sel:[0,1] op_sel_hi:[1,0] neg_hi:[0,1]
	v_pk_add_f32 v[108:109], v[108:109], v[110:111] op_sel:[0,1] op_sel_hi:[1,0] neg_lo:[0,1]
	v_mov_b32_e32 v110, v38
	v_mov_b32_e32 v111, v39
	ds_write_b64 v144, v[118:119]
	v_pk_mul_f32 v[118:119], v[164:165], v[110:111] op_sel:[0,0] op_sel_hi:[0,1]
	v_pk_fma_f32 v[118:119], v[164:165], v[110:111], v[118:119] op_sel:[1,1,0] op_sel_hi:[1,0,1] neg_lo:[0,1,0]
	ds_write_b64 v144, v[118:119] offset:2176
	v_pk_mul_f32 v[118:119], v[110:111], v[110:111] op_sel:[0,0] op_sel_hi:[0,1]
	v_pk_fma_f32 v[118:119], v[110:111], v[110:111], v[118:119] op_sel:[1,1,0] op_sel_hi:[1,0,1] neg_lo:[0,1,0]
	v_pk_mul_f32 v[164:165], v[166:167], v[118:119] op_sel:[0,0] op_sel_hi:[0,1]
	v_pk_fma_f32 v[164:165], v[166:167], v[118:119], v[164:165] op_sel:[1,1,0] op_sel_hi:[1,0,1] neg_lo:[0,1,0]
	ds_write_b64 v144, v[164:165] offset:4352
	v_pk_mul_f32 v[164:165], v[118:119], v[110:111] op_sel:[0,0] op_sel_hi:[0,1]
	v_pk_fma_f32 v[118:119], v[118:119], v[110:111], v[164:165] op_sel:[1,1,0] op_sel_hi:[1,0,1] neg_lo:[0,1,0]
	v_pk_mul_f32 v[164:165], v[168:169], v[118:119] op_sel:[0,0] op_sel_hi:[0,1]
	v_pk_fma_f32 v[164:165], v[168:169], v[118:119], v[164:165] op_sel:[1,1,0] op_sel_hi:[1,0,1] neg_lo:[0,1,0]
	ds_write_b64 v144, v[164:165] offset:6528
	v_pk_mul_f32 v[164:165], v[118:119], v[110:111] op_sel:[0,0] op_sel_hi:[0,1]
	v_pk_fma_f32 v[118:119], v[118:119], v[110:111], v[164:165] op_sel:[1,1,0] op_sel_hi:[1,0,1] neg_lo:[0,1,0]
	v_pk_mul_f32 v[164:165], v[170:171], v[118:119] op_sel:[0,0] op_sel_hi:[0,1]
	v_pk_fma_f32 v[164:165], v[170:171], v[118:119], v[164:165] op_sel:[1,1,0] op_sel_hi:[1,0,1] neg_lo:[0,1,0]
	ds_write_b64 v144, v[164:165] offset:8704
	v_pk_mul_f32 v[164:165], v[118:119], v[110:111] op_sel:[0,0] op_sel_hi:[0,1]
	v_pk_fma_f32 v[118:119], v[118:119], v[110:111], v[164:165] op_sel:[1,1,0] op_sel_hi:[1,0,1] neg_lo:[0,1,0]
	v_pk_mul_f32 v[164:165], v[158:159], v[118:119] op_sel:[0,0] op_sel_hi:[0,1]
	v_pk_fma_f32 v[158:159], v[158:159], v[118:119], v[164:165] op_sel:[1,1,0] op_sel_hi:[1,0,1] neg_lo:[0,1,0]
	ds_write_b64 v144, v[158:159] offset:10880
	v_pk_mul_f32 v[158:159], v[118:119], v[110:111] op_sel:[0,0] op_sel_hi:[0,1]
	v_pk_fma_f32 v[118:119], v[118:119], v[110:111], v[158:159] op_sel:[1,1,0] op_sel_hi:[1,0,1] neg_lo:[0,1,0]
	v_pk_mul_f32 v[158:159], v[162:163], v[118:119] op_sel:[0,0] op_sel_hi:[0,1]
	v_pk_fma_f32 v[158:159], v[162:163], v[118:119], v[158:159] op_sel:[1,1,0] op_sel_hi:[1,0,1] neg_lo:[0,1,0]
	ds_write_b64 v144, v[158:159] offset:13056
	v_pk_mul_f32 v[158:159], v[118:119], v[110:111] op_sel:[0,0] op_sel_hi:[0,1]
	v_pk_fma_f32 v[118:119], v[118:119], v[110:111], v[158:159] op_sel:[1,1,0] op_sel_hi:[1,0,1] neg_lo:[0,1,0]
	v_pk_mul_f32 v[158:159], v[160:161], v[118:119] op_sel:[0,0] op_sel_hi:[0,1]
	v_pk_fma_f32 v[158:159], v[160:161], v[118:119], v[158:159] op_sel:[1,1,0] op_sel_hi:[1,0,1] neg_lo:[0,1,0]
	ds_write_b64 v144, v[158:159] offset:15232
	v_pk_mul_f32 v[158:159], v[118:119], v[110:111] op_sel:[0,0] op_sel_hi:[0,1]
	v_pk_fma_f32 v[118:119], v[118:119], v[110:111], v[158:159] op_sel:[1,1,0] op_sel_hi:[1,0,1] neg_lo:[0,1,0]
	v_pk_mul_f32 v[158:159], v[122:123], v[118:119] op_sel:[0,0] op_sel_hi:[0,1]
	v_pk_fma_f32 v[122:123], v[122:123], v[118:119], v[158:159] op_sel:[1,1,0] op_sel_hi:[1,0,1] neg_lo:[0,1,0]
	ds_write_b64 v144, v[122:123] offset:17408
	v_pk_mul_f32 v[122:123], v[118:119], v[110:111] op_sel:[0,0] op_sel_hi:[0,1]
	v_pk_fma_f32 v[118:119], v[118:119], v[110:111], v[122:123] op_sel:[1,1,0] op_sel_hi:[1,0,1] neg_lo:[0,1,0]
	v_pk_mul_f32 v[122:123], v[120:121], v[118:119] op_sel:[0,0] op_sel_hi:[0,1]
	v_pk_fma_f32 v[120:121], v[120:121], v[118:119], v[122:123] op_sel:[1,1,0] op_sel_hi:[1,0,1] neg_lo:[0,1,0]
	ds_write_b64 v144, v[120:121] offset:19584
	v_pk_mul_f32 v[120:121], v[118:119], v[110:111] op_sel:[0,0] op_sel_hi:[0,1]
	v_pk_fma_f32 v[118:119], v[118:119], v[110:111], v[120:121] op_sel:[1,1,0] op_sel_hi:[1,0,1] neg_lo:[0,1,0]
	v_pk_mul_f32 v[120:121], v[116:117], v[118:119] op_sel:[0,0] op_sel_hi:[0,1]
	v_pk_fma_f32 v[116:117], v[116:117], v[118:119], v[120:121] op_sel:[1,1,0] op_sel_hi:[1,0,1] neg_lo:[0,1,0]
	ds_write_b64 v144, v[116:117] offset:21760
	v_pk_mul_f32 v[116:117], v[118:119], v[110:111] op_sel:[0,0] op_sel_hi:[0,1]
	v_pk_fma_f32 v[116:117], v[118:119], v[110:111], v[116:117] op_sel:[1,1,0] op_sel_hi:[1,0,1] neg_lo:[0,1,0]
	v_pk_mul_f32 v[118:119], v[156:157], v[116:117] op_sel:[0,0] op_sel_hi:[0,1]
	v_pk_fma_f32 v[118:119], v[156:157], v[116:117], v[118:119] op_sel:[1,1,0] op_sel_hi:[1,0,1] neg_lo:[0,1,0]
	ds_write_b64 v144, v[118:119] offset:23936
	v_pk_mul_f32 v[118:119], v[116:117], v[110:111] op_sel:[0,0] op_sel_hi:[0,1]
	v_pk_fma_f32 v[116:117], v[116:117], v[110:111], v[118:119] op_sel:[1,1,0] op_sel_hi:[1,0,1] neg_lo:[0,1,0]
	v_pk_mul_f32 v[118:119], v[114:115], v[116:117] op_sel:[0,0] op_sel_hi:[0,1]
	v_pk_fma_f32 v[114:115], v[114:115], v[116:117], v[118:119] op_sel:[1,1,0] op_sel_hi:[1,0,1] neg_lo:[0,1,0]
	ds_write_b64 v144, v[114:115] offset:26112
	v_pk_mul_f32 v[114:115], v[116:117], v[110:111] op_sel:[0,0] op_sel_hi:[0,1]
	v_pk_fma_f32 v[114:115], v[116:117], v[110:111], v[114:115] op_sel:[1,1,0] op_sel_hi:[1,0,1] neg_lo:[0,1,0]
	v_pk_mul_f32 v[116:117], v[154:155], v[114:115] op_sel:[0,0] op_sel_hi:[0,1]
	v_pk_fma_f32 v[116:117], v[154:155], v[114:115], v[116:117] op_sel:[1,1,0] op_sel_hi:[1,0,1] neg_lo:[0,1,0]
	ds_write_b64 v144, v[116:117] offset:28288
	v_pk_mul_f32 v[116:117], v[114:115], v[110:111] op_sel:[0,0] op_sel_hi:[0,1]
	v_pk_fma_f32 v[114:115], v[114:115], v[110:111], v[116:117] op_sel:[1,1,0] op_sel_hi:[1,0,1] neg_lo:[0,1,0]
	v_pk_mul_f32 v[116:117], v[112:113], v[114:115] op_sel:[0,0] op_sel_hi:[0,1]
	v_pk_fma_f32 v[112:113], v[112:113], v[114:115], v[116:117] op_sel:[1,1,0] op_sel_hi:[1,0,1] neg_lo:[0,1,0]
	ds_write_b64 v144, v[112:113] offset:30464
	v_pk_mul_f32 v[112:113], v[114:115], v[110:111] op_sel:[0,0] op_sel_hi:[0,1]
	v_pk_fma_f32 v[110:111], v[114:115], v[110:111], v[112:113] op_sel:[1,1,0] op_sel_hi:[1,0,1] neg_lo:[0,1,0]
	v_pk_mul_f32 v[112:113], v[108:109], v[110:111] op_sel:[0,0] op_sel_hi:[0,1]
	v_pk_fma_f32 v[108:109], v[108:109], v[110:111], v[112:113] op_sel:[1,1,0] op_sel_hi:[1,0,1] neg_lo:[0,1,0]
	ds_write_b64 v144, v[108:109] offset:32640
	s_waitcnt lgkmcnt(0)
	s_barrier
	ds_read2_b64 v[108:111], v146 offset1:17
	ds_read2_b64 v[112:115], v146 offset0:34 offset1:51
	ds_read2_b64 v[116:119], v146 offset0:68 offset1:85
	ds_read2_b64 v[120:123], v146 offset0:136 offset1:153
	ds_read2_b64 v[154:157], v146 offset0:102 offset1:119
	ds_read2_b64 v[158:161], v146 offset0:204 offset1:221
	ds_read2_b64 v[162:165], v146 offset0:170 offset1:187
	ds_read2_b64 v[166:169], v146 offset0:238 offset1:255
	s_waitcnt lgkmcnt(4)
	v_pk_add_f32 v[170:171], v[108:109], v[120:121]
	v_pk_add_f32 v[108:109], v[108:109], v[120:121] neg_lo:[0,1] neg_hi:[0,1]
	s_waitcnt lgkmcnt(2)
	v_pk_add_f32 v[120:121], v[116:117], v[158:159]
	v_pk_add_f32 v[116:117], v[116:117], v[158:159] neg_lo:[0,1] neg_hi:[0,1]
	v_pk_add_f32 v[158:159], v[170:171], v[120:121]
	v_pk_add_f32 v[120:121], v[170:171], v[120:121] neg_lo:[0,1] neg_hi:[0,1]
	v_pk_add_f32 v[170:171], v[108:109], v[116:117] op_sel:[0,1] op_sel_hi:[1,0] neg_hi:[0,1]
	v_pk_add_f32 v[108:109], v[108:109], v[116:117] op_sel:[0,1] op_sel_hi:[1,0] neg_lo:[0,1]
	v_pk_add_f32 v[116:117], v[110:111], v[122:123]
	v_pk_add_f32 v[110:111], v[110:111], v[122:123] neg_lo:[0,1] neg_hi:[0,1]
	v_pk_add_f32 v[122:123], v[118:119], v[160:161]
	v_pk_add_f32 v[118:119], v[118:119], v[160:161] neg_lo:[0,1] neg_hi:[0,1]
	v_pk_add_f32 v[160:161], v[116:117], v[122:123]
	v_pk_add_f32 v[116:117], v[116:117], v[122:123] neg_lo:[0,1] neg_hi:[0,1]
	v_pk_add_f32 v[122:123], v[110:111], v[118:119] op_sel:[0,1] op_sel_hi:[1,0] neg_hi:[0,1]
	v_pk_add_f32 v[110:111], v[110:111], v[118:119] op_sel:[0,1] op_sel_hi:[1,0] neg_lo:[0,1]
	s_waitcnt lgkmcnt(1)
	v_pk_add_f32 v[118:119], v[112:113], v[162:163]
	v_pk_add_f32 v[112:113], v[112:113], v[162:163] neg_lo:[0,1] neg_hi:[0,1]
	s_waitcnt lgkmcnt(0)
	v_pk_add_f32 v[162:163], v[154:155], v[166:167]
	v_pk_add_f32 v[154:155], v[154:155], v[166:167] neg_lo:[0,1] neg_hi:[0,1]
	v_pk_add_f32 v[166:167], v[118:119], v[162:163]
	v_pk_add_f32 v[118:119], v[118:119], v[162:163] neg_lo:[0,1] neg_hi:[0,1]
	v_pk_add_f32 v[162:163], v[112:113], v[154:155] op_sel:[0,1] op_sel_hi:[1,0] neg_hi:[0,1]
	v_pk_add_f32 v[112:113], v[112:113], v[154:155] op_sel:[0,1] op_sel_hi:[1,0] neg_lo:[0,1]
	v_pk_add_f32 v[154:155], v[114:115], v[164:165]
	v_pk_add_f32 v[114:115], v[114:115], v[164:165] neg_lo:[0,1] neg_hi:[0,1]
	v_pk_add_f32 v[164:165], v[156:157], v[168:169]
	v_pk_add_f32 v[156:157], v[156:157], v[168:169] neg_lo:[0,1] neg_hi:[0,1]
	v_pk_add_f32 v[168:169], v[154:155], v[164:165]
	v_pk_add_f32 v[154:155], v[154:155], v[164:165] neg_lo:[0,1] neg_hi:[0,1]
	v_pk_add_f32 v[164:165], v[114:115], v[156:157] op_sel:[0,1] op_sel_hi:[1,0] neg_hi:[0,1]
	v_pk_add_f32 v[114:115], v[114:115], v[156:157] op_sel:[0,1] op_sel_hi:[1,0] neg_lo:[0,1]
	v_pk_mul_f32 v[156:157], v[122:123], s[20:21] op_sel:[0,0] op_sel_hi:[0,1]
	v_pk_fma_f32 v[122:123], v[122:123], s[20:21], v[156:157] op_sel:[1,1,0] op_sel_hi:[1,0,1] neg_lo:[0,1,0]
	v_pk_mul_f32 v[156:157], v[162:163], s[50:51] op_sel:[0,0] op_sel_hi:[0,1]
	v_pk_fma_f32 v[156:157], v[162:163], s[50:51], v[156:157] op_sel:[1,1,0] op_sel_hi:[1,0,1] neg_lo:[0,1,0]
	v_pk_mul_f32 v[162:163], v[164:165], s[54:55] op_sel:[0,0] op_sel_hi:[0,1]
	v_pk_fma_f32 v[162:163], v[164:165], s[54:55], v[162:163] op_sel:[1,1,0] op_sel_hi:[1,0,1] neg_lo:[0,1,0]
	v_pk_mul_f32 v[164:165], v[116:117], s[50:51] op_sel:[0,0] op_sel_hi:[0,1]
	v_pk_fma_f32 v[116:117], v[116:117], s[50:51], v[164:165] op_sel:[1,1,0] op_sel_hi:[1,0,1] neg_lo:[0,1,0]
	v_pk_mul_f32 v[164:165], v[118:119], s[14:15] op_sel:[0,0] op_sel_hi:[0,1]
	v_pk_fma_f32 v[118:119], v[118:119], s[14:15], v[164:165] op_sel:[1,1,0] op_sel_hi:[1,0,1] neg_lo:[0,1,0]
	v_pk_mul_f32 v[164:165], v[154:155], s[58:59] op_sel:[0,0] op_sel_hi:[0,1]
	v_pk_fma_f32 v[154:155], v[154:155], s[58:59], v[164:165] op_sel:[1,1,0] op_sel_hi:[1,0,1] neg_lo:[0,1,0]
	v_pk_mul_f32 v[164:165], v[110:111], s[54:55] op_sel:[0,0] op_sel_hi:[0,1]
	v_pk_fma_f32 v[110:111], v[110:111], s[54:55], v[164:165] op_sel:[1,1,0] op_sel_hi:[1,0,1] neg_lo:[0,1,0]
	v_pk_mul_f32 v[164:165], v[112:113], s[58:59] op_sel:[0,0] op_sel_hi:[0,1]
	v_pk_fma_f32 v[112:113], v[112:113], s[58:59], v[164:165] op_sel:[1,1,0] op_sel_hi:[1,0,1] neg_lo:[0,1,0]
	v_pk_mul_f32 v[164:165], v[114:115], s[60:61] op_sel:[0,0] op_sel_hi:[0,1]
	v_pk_fma_f32 v[114:115], v[114:115], s[60:61], v[164:165] op_sel:[1,1,0] op_sel_hi:[1,0,1] neg_lo:[0,1,0]
	v_pk_add_f32 v[164:165], v[158:159], v[166:167]
	v_pk_add_f32 v[158:159], v[158:159], v[166:167] neg_lo:[0,1] neg_hi:[0,1]
	v_pk_add_f32 v[166:167], v[160:161], v[168:169]
	v_pk_add_f32 v[160:161], v[160:161], v[168:169] neg_lo:[0,1] neg_hi:[0,1]
	v_pk_add_f32 v[168:169], v[164:165], v[166:167]
	v_pk_add_f32 v[164:165], v[164:165], v[166:167] neg_lo:[0,1] neg_hi:[0,1]
	v_pk_add_f32 v[166:167], v[158:159], v[160:161] op_sel:[0,1] op_sel_hi:[1,0] neg_hi:[0,1]
	v_pk_add_f32 v[158:159], v[158:159], v[160:161] op_sel:[0,1] op_sel_hi:[1,0] neg_lo:[0,1]
	v_pk_add_f32 v[160:161], v[170:171], v[156:157]
	v_pk_add_f32 v[156:157], v[170:171], v[156:157] neg_lo:[0,1] neg_hi:[0,1]
	v_pk_add_f32 v[170:171], v[122:123], v[162:163]
	v_pk_add_f32 v[122:123], v[122:123], v[162:163] neg_lo:[0,1] neg_hi:[0,1]
	v_pk_add_f32 v[162:163], v[160:161], v[170:171]
	v_pk_add_f32 v[160:161], v[160:161], v[170:171] neg_lo:[0,1] neg_hi:[0,1]
	v_pk_add_f32 v[170:171], v[156:157], v[122:123] op_sel:[0,1] op_sel_hi:[1,0] neg_hi:[0,1]
	v_pk_add_f32 v[122:123], v[156:157], v[122:123] op_sel:[0,1] op_sel_hi:[1,0] neg_lo:[0,1]
	v_pk_add_f32 v[156:157], v[120:121], v[118:119]
	v_pk_add_f32 v[118:119], v[120:121], v[118:119] neg_lo:[0,1] neg_hi:[0,1]
	v_pk_add_f32 v[120:121], v[116:117], v[154:155]
	v_pk_add_f32 v[116:117], v[116:117], v[154:155] neg_lo:[0,1] neg_hi:[0,1]
	v_pk_add_f32 v[154:155], v[156:157], v[120:121]
	v_pk_add_f32 v[120:121], v[156:157], v[120:121] neg_lo:[0,1] neg_hi:[0,1]
	v_pk_add_f32 v[156:157], v[118:119], v[116:117] op_sel:[0,1] op_sel_hi:[1,0] neg_hi:[0,1]
	v_pk_add_f32 v[116:117], v[118:119], v[116:117] op_sel:[0,1] op_sel_hi:[1,0] neg_lo:[0,1]
	v_pk_add_f32 v[118:119], v[108:109], v[112:113]
	v_pk_add_f32 v[108:109], v[108:109], v[112:113] neg_lo:[0,1] neg_hi:[0,1]
	v_pk_add_f32 v[112:113], v[110:111], v[114:115]
	v_pk_add_f32 v[110:111], v[110:111], v[114:115] neg_lo:[0,1] neg_hi:[0,1]
	v_pk_add_f32 v[114:115], v[118:119], v[112:113]
	v_pk_add_f32 v[112:113], v[118:119], v[112:113] neg_lo:[0,1] neg_hi:[0,1]
	v_pk_add_f32 v[118:119], v[108:109], v[110:111] op_sel:[0,1] op_sel_hi:[1,0] neg_hi:[0,1]
	v_pk_add_f32 v[108:109], v[108:109], v[110:111] op_sel:[0,1] op_sel_hi:[1,0] neg_lo:[0,1]
	v_mov_b32_e32 v110, v40
	v_mov_b32_e32 v111, v41
	s_nop 0
	v_pk_mul_f32 v[172:173], v[162:163], v[110:111] op_sel:[0,0] op_sel_hi:[0,1]
	v_pk_fma_f32 v[162:163], v[162:163], v[110:111], v[172:173] op_sel:[1,1,0] op_sel_hi:[1,0,1] neg_lo:[0,1,0]
	ds_write2_b64 v146, v[168:169], v[162:163] offset1:17
	v_pk_mul_f32 v[162:163], v[110:111], v[110:111] op_sel:[0,0] op_sel_hi:[0,1]
	v_pk_fma_f32 v[162:163], v[110:111], v[110:111], v[162:163] op_sel:[1,1,0] op_sel_hi:[1,0,1] neg_lo:[0,1,0]
	v_pk_mul_f32 v[168:169], v[154:155], v[162:163] op_sel:[0,0] op_sel_hi:[0,1]
	v_pk_fma_f32 v[154:155], v[154:155], v[162:163], v[168:169] op_sel:[1,1,0] op_sel_hi:[1,0,1] neg_lo:[0,1,0]
	v_pk_mul_f32 v[168:169], v[162:163], v[110:111] op_sel:[0,0] op_sel_hi:[0,1]
	v_pk_fma_f32 v[162:163], v[162:163], v[110:111], v[168:169] op_sel:[1,1,0] op_sel_hi:[1,0,1] neg_lo:[0,1,0]
	v_pk_mul_f32 v[168:169], v[114:115], v[162:163] op_sel:[0,0] op_sel_hi:[0,1]
	v_pk_fma_f32 v[114:115], v[114:115], v[162:163], v[168:169] op_sel:[1,1,0] op_sel_hi:[1,0,1] neg_lo:[0,1,0]
	ds_write2_b64 v146, v[154:155], v[114:115] offset0:34 offset1:51
	v_pk_mul_f32 v[114:115], v[162:163], v[110:111] op_sel:[0,0] op_sel_hi:[0,1]
	v_pk_fma_f32 v[114:115], v[162:163], v[110:111], v[114:115] op_sel:[1,1,0] op_sel_hi:[1,0,1] neg_lo:[0,1,0]
	v_pk_mul_f32 v[154:155], v[166:167], v[114:115] op_sel:[0,0] op_sel_hi:[0,1]
	v_pk_mul_f32 v[162:163], v[114:115], v[110:111] op_sel:[0,0] op_sel_hi:[0,1]
	v_pk_fma_f32 v[154:155], v[166:167], v[114:115], v[154:155] op_sel:[1,1,0] op_sel_hi:[1,0,1] neg_lo:[0,1,0]
	v_pk_fma_f32 v[114:115], v[114:115], v[110:111], v[162:163] op_sel:[1,1,0] op_sel_hi:[1,0,1] neg_lo:[0,1,0]
	v_pk_mul_f32 v[162:163], v[170:171], v[114:115] op_sel:[0,0] op_sel_hi:[0,1]
	v_pk_fma_f32 v[162:163], v[170:171], v[114:115], v[162:163] op_sel:[1,1,0] op_sel_hi:[1,0,1] neg_lo:[0,1,0]
	ds_write2_b64 v146, v[154:155], v[162:163] offset0:68 offset1:85
	v_pk_mul_f32 v[154:155], v[114:115], v[110:111] op_sel:[0,0] op_sel_hi:[0,1]
	v_pk_fma_f32 v[114:115], v[114:115], v[110:111], v[154:155] op_sel:[1,1,0] op_sel_hi:[1,0,1] neg_lo:[0,1,0]
	v_pk_mul_f32 v[154:155], v[156:157], v[114:115] op_sel:[0,0] op_sel_hi:[0,1]
	v_pk_fma_f32 v[154:155], v[156:157], v[114:115], v[154:155] op_sel:[1,1,0] op_sel_hi:[1,0,1] neg_lo:[0,1,0]
	v_pk_mul_f32 v[156:157], v[114:115], v[110:111] op_sel:[0,0] op_sel_hi:[0,1]
	v_pk_fma_f32 v[114:115], v[114:115], v[110:111], v[156:157] op_sel:[1,1,0] op_sel_hi:[1,0,1] neg_lo:[0,1,0]
	v_pk_mul_f32 v[156:157], v[118:119], v[114:115] op_sel:[0,0] op_sel_hi:[0,1]
	v_pk_fma_f32 v[118:119], v[118:119], v[114:115], v[156:157] op_sel:[1,1,0] op_sel_hi:[1,0,1] neg_lo:[0,1,0]
	ds_write2_b64 v146, v[154:155], v[118:119] offset0:102 offset1:119
	v_pk_mul_f32 v[118:119], v[114:115], v[110:111] op_sel:[0,0] op_sel_hi:[0,1]
	v_pk_fma_f32 v[114:115], v[114:115], v[110:111], v[118:119] op_sel:[1,1,0] op_sel_hi:[1,0,1] neg_lo:[0,1,0]
	v_pk_mul_f32 v[118:119], v[164:165], v[114:115] op_sel:[0,0] op_sel_hi:[0,1]
	v_pk_mul_f32 v[154:155], v[114:115], v[110:111] op_sel:[0,0] op_sel_hi:[0,1]
	v_pk_fma_f32 v[118:119], v[164:165], v[114:115], v[118:119] op_sel:[1,1,0] op_sel_hi:[1,0,1] neg_lo:[0,1,0]
	v_pk_fma_f32 v[114:115], v[114:115], v[110:111], v[154:155] op_sel:[1,1,0] op_sel_hi:[1,0,1] neg_lo:[0,1,0]
	v_pk_mul_f32 v[154:155], v[160:161], v[114:115] op_sel:[0,0] op_sel_hi:[0,1]
	v_pk_fma_f32 v[154:155], v[160:161], v[114:115], v[154:155] op_sel:[1,1,0] op_sel_hi:[1,0,1] neg_lo:[0,1,0]
	ds_write2_b64 v146, v[118:119], v[154:155] offset0:136 offset1:153
	v_pk_mul_f32 v[118:119], v[114:115], v[110:111] op_sel:[0,0] op_sel_hi:[0,1]
	v_pk_fma_f32 v[114:115], v[114:115], v[110:111], v[118:119] op_sel:[1,1,0] op_sel_hi:[1,0,1] neg_lo:[0,1,0]
	v_pk_mul_f32 v[118:119], v[120:121], v[114:115] op_sel:[0,0] op_sel_hi:[0,1]
	v_pk_fma_f32 v[118:119], v[120:121], v[114:115], v[118:119] op_sel:[1,1,0] op_sel_hi:[1,0,1] neg_lo:[0,1,0]
	v_pk_mul_f32 v[120:121], v[114:115], v[110:111] op_sel:[0,0] op_sel_hi:[0,1]
	v_pk_fma_f32 v[114:115], v[114:115], v[110:111], v[120:121] op_sel:[1,1,0] op_sel_hi:[1,0,1] neg_lo:[0,1,0]
	v_pk_mul_f32 v[120:121], v[112:113], v[114:115] op_sel:[0,0] op_sel_hi:[0,1]
	v_pk_fma_f32 v[112:113], v[112:113], v[114:115], v[120:121] op_sel:[1,1,0] op_sel_hi:[1,0,1] neg_lo:[0,1,0]
	ds_write2_b64 v146, v[118:119], v[112:113] offset0:170 offset1:187
	v_pk_mul_f32 v[112:113], v[114:115], v[110:111] op_sel:[0,0] op_sel_hi:[0,1]
	v_pk_fma_f32 v[112:113], v[114:115], v[110:111], v[112:113] op_sel:[1,1,0] op_sel_hi:[1,0,1] neg_lo:[0,1,0]
	v_pk_mul_f32 v[114:115], v[158:159], v[112:113] op_sel:[0,0] op_sel_hi:[0,1]
	v_pk_mul_f32 v[118:119], v[112:113], v[110:111] op_sel:[0,0] op_sel_hi:[0,1]
	v_pk_fma_f32 v[114:115], v[158:159], v[112:113], v[114:115] op_sel:[1,1,0] op_sel_hi:[1,0,1] neg_lo:[0,1,0]
	v_pk_fma_f32 v[112:113], v[112:113], v[110:111], v[118:119] op_sel:[1,1,0] op_sel_hi:[1,0,1] neg_lo:[0,1,0]
	v_pk_mul_f32 v[118:119], v[122:123], v[112:113] op_sel:[0,0] op_sel_hi:[0,1]
	v_pk_fma_f32 v[118:119], v[122:123], v[112:113], v[118:119] op_sel:[1,1,0] op_sel_hi:[1,0,1] neg_lo:[0,1,0]
	ds_write2_b64 v146, v[114:115], v[118:119] offset0:204 offset1:221
	v_pk_mul_f32 v[114:115], v[112:113], v[110:111] op_sel:[0,0] op_sel_hi:[0,1]
	v_pk_fma_f32 v[112:113], v[112:113], v[110:111], v[114:115] op_sel:[1,1,0] op_sel_hi:[1,0,1] neg_lo:[0,1,0]
	v_pk_mul_f32 v[114:115], v[116:117], v[112:113] op_sel:[0,0] op_sel_hi:[0,1]
	v_pk_fma_f32 v[114:115], v[116:117], v[112:113], v[114:115] op_sel:[1,1,0] op_sel_hi:[1,0,1] neg_lo:[0,1,0]
	v_pk_mul_f32 v[116:117], v[112:113], v[110:111] op_sel:[0,0] op_sel_hi:[0,1]
	v_pk_fma_f32 v[110:111], v[112:113], v[110:111], v[116:117] op_sel:[1,1,0] op_sel_hi:[1,0,1] neg_lo:[0,1,0]
	v_pk_mul_f32 v[112:113], v[108:109], v[110:111] op_sel:[0,0] op_sel_hi:[0,1]
	v_pk_fma_f32 v[108:109], v[108:109], v[110:111], v[112:113] op_sel:[1,1,0] op_sel_hi:[1,0,1] neg_lo:[0,1,0]
	ds_write2_b64 v146, v[114:115], v[108:109] offset0:238 offset1:255
	s_waitcnt lgkmcnt(0)
	s_barrier
	ds_read2_b64 v[108:111], v147 offset1:1
	ds_read2_b64 v[112:115], v147 offset0:2 offset1:3
	ds_read2_b64 v[116:119], v147 offset0:8 offset1:9
	ds_read2_b64 v[120:123], v147 offset0:4 offset1:5
	ds_read2_b64 v[154:157], v147 offset0:6 offset1:7
	ds_read2_b64 v[158:161], v147 offset0:12 offset1:13
	ds_read2_b64 v[162:165], v147 offset0:10 offset1:11
	ds_read2_b64 v[166:169], v147 offset0:14 offset1:15
	s_waitcnt lgkmcnt(5)
	v_pk_add_f32 v[170:171], v[108:109], v[116:117]
	v_pk_add_f32 v[108:109], v[108:109], v[116:117] neg_lo:[0,1] neg_hi:[0,1]
	s_waitcnt lgkmcnt(2)
	v_pk_add_f32 v[116:117], v[120:121], v[158:159]
	v_pk_add_f32 v[120:121], v[120:121], v[158:159] neg_lo:[0,1] neg_hi:[0,1]
	v_pk_add_f32 v[158:159], v[170:171], v[116:117]
	v_pk_add_f32 v[116:117], v[170:171], v[116:117] neg_lo:[0,1] neg_hi:[0,1]
	v_pk_add_f32 v[170:171], v[108:109], v[120:121] op_sel:[0,1] op_sel_hi:[1,0] neg_hi:[0,1]
	v_pk_add_f32 v[108:109], v[108:109], v[120:121] op_sel:[0,1] op_sel_hi:[1,0] neg_lo:[0,1]
	v_pk_add_f32 v[120:121], v[110:111], v[118:119]
	v_pk_add_f32 v[110:111], v[110:111], v[118:119] neg_lo:[0,1] neg_hi:[0,1]
	v_pk_add_f32 v[118:119], v[122:123], v[160:161]
	v_pk_add_f32 v[122:123], v[122:123], v[160:161] neg_lo:[0,1] neg_hi:[0,1]
	v_pk_add_f32 v[160:161], v[120:121], v[118:119]
	v_pk_add_f32 v[118:119], v[120:121], v[118:119] neg_lo:[0,1] neg_hi:[0,1]
	v_pk_add_f32 v[120:121], v[110:111], v[122:123] op_sel:[0,1] op_sel_hi:[1,0] neg_hi:[0,1]
	v_pk_add_f32 v[110:111], v[110:111], v[122:123] op_sel:[0,1] op_sel_hi:[1,0] neg_lo:[0,1]
	s_waitcnt lgkmcnt(1)
	v_pk_add_f32 v[122:123], v[112:113], v[162:163]
	v_pk_add_f32 v[112:113], v[112:113], v[162:163] neg_lo:[0,1] neg_hi:[0,1]
	s_waitcnt lgkmcnt(0)
	v_pk_add_f32 v[162:163], v[154:155], v[166:167]
	v_pk_add_f32 v[154:155], v[154:155], v[166:167] neg_lo:[0,1] neg_hi:[0,1]
	v_pk_add_f32 v[166:167], v[122:123], v[162:163]
	v_pk_add_f32 v[122:123], v[122:123], v[162:163] neg_lo:[0,1] neg_hi:[0,1]
	v_pk_add_f32 v[162:163], v[112:113], v[154:155] op_sel:[0,1] op_sel_hi:[1,0] neg_hi:[0,1]
	v_pk_add_f32 v[112:113], v[112:113], v[154:155] op_sel:[0,1] op_sel_hi:[1,0] neg_lo:[0,1]
	v_pk_add_f32 v[154:155], v[114:115], v[164:165]
	v_pk_add_f32 v[114:115], v[114:115], v[164:165] neg_lo:[0,1] neg_hi:[0,1]
	v_pk_add_f32 v[164:165], v[156:157], v[168:169]
	v_pk_add_f32 v[156:157], v[156:157], v[168:169] neg_lo:[0,1] neg_hi:[0,1]
	v_pk_add_f32 v[168:169], v[154:155], v[164:165]
	v_pk_add_f32 v[154:155], v[154:155], v[164:165] neg_lo:[0,1] neg_hi:[0,1]
	v_pk_add_f32 v[164:165], v[114:115], v[156:157] op_sel:[0,1] op_sel_hi:[1,0] neg_hi:[0,1]
	v_pk_add_f32 v[114:115], v[114:115], v[156:157] op_sel:[0,1] op_sel_hi:[1,0] neg_lo:[0,1]
	v_pk_mul_f32 v[156:157], v[120:121], s[20:21] op_sel:[0,0] op_sel_hi:[0,1]
	v_pk_fma_f32 v[102:103], v[120:121], s[20:21], v[156:157] op_sel:[1,1,0] op_sel_hi:[1,0,1] neg_lo:[0,1,0]
	v_pk_mul_f32 v[120:121], v[162:163], s[50:51] op_sel:[0,0] op_sel_hi:[0,1]
	v_pk_mul_f32 v[156:157], v[164:165], s[54:55] op_sel:[0,0] op_sel_hi:[0,1]
	v_pk_fma_f32 v[120:121], v[162:163], s[50:51], v[120:121] op_sel:[1,1,0] op_sel_hi:[1,0,1] neg_lo:[0,1,0]
	v_pk_mul_f32 v[162:163], v[118:119], s[50:51] op_sel:[0,0] op_sel_hi:[0,1]
	v_pk_fma_f32 v[156:157], v[164:165], s[54:55], v[156:157] op_sel:[1,1,0] op_sel_hi:[1,0,1] neg_lo:[0,1,0]
	v_pk_fma_f32 v[98:99], v[118:119], s[50:51], v[162:163] op_sel:[1,1,0] op_sel_hi:[1,0,1] neg_lo:[0,1,0]
	v_pk_mul_f32 v[118:119], v[122:123], s[14:15] op_sel:[0,0] op_sel_hi:[0,1]
	v_pk_fma_f32 v[104:105], v[122:123], s[14:15], v[118:119] op_sel:[1,1,0] op_sel_hi:[1,0,1] neg_lo:[0,1,0]
	v_pk_mul_f32 v[118:119], v[154:155], s[58:59] op_sel:[0,0] op_sel_hi:[0,1]
	v_pk_mul_f32 v[122:123], v[110:111], s[54:55] op_sel:[0,0] op_sel_hi:[0,1]
	v_pk_fma_f32 v[96:97], v[110:111], s[54:55], v[122:123] op_sel:[1,1,0] op_sel_hi:[1,0,1] neg_lo:[0,1,0]
	v_pk_mul_f32 v[110:111], v[112:113], s[58:59] op_sel:[0,0] op_sel_hi:[0,1]
	v_pk_fma_f32 v[118:119], v[154:155], s[58:59], v[118:119] op_sel:[1,1,0] op_sel_hi:[1,0,1] neg_lo:[0,1,0]
	v_pk_add_f32 v[122:123], v[160:161], v[168:169] neg_lo:[0,1] neg_hi:[0,1]
	v_pk_fma_f32 v[100:101], v[112:113], s[58:59], v[110:111] op_sel:[1,1,0] op_sel_hi:[1,0,1] neg_lo:[0,1,0]
	v_pk_mul_f32 v[110:111], v[114:115], s[60:61] op_sel:[0,0] op_sel_hi:[0,1]
	v_pk_add_f32 v[112:113], v[158:159], v[166:167] neg_lo:[0,1] neg_hi:[0,1]
	v_pk_fma_f32 v[106:107], v[114:115], s[60:61], v[110:111] op_sel:[1,1,0] op_sel_hi:[1,0,1] neg_lo:[0,1,0]
	v_pk_add_f32 v[110:111], v[158:159], v[166:167]
	v_pk_add_f32 v[114:115], v[160:161], v[168:169]
	v_pk_add_f32 v[158:159], v[102:103], v[156:157]
	v_pk_add_f32 v[154:155], v[110:111], v[114:115]
	v_pk_add_f32 v[110:111], v[110:111], v[114:115] neg_lo:[0,1] neg_hi:[0,1]
	v_pk_add_f32 v[114:115], v[112:113], v[122:123] op_sel:[0,1] op_sel_hi:[1,0] neg_hi:[0,1]
	v_pk_add_f32 v[112:113], v[112:113], v[122:123] op_sel:[0,1] op_sel_hi:[1,0] neg_lo:[0,1]
	v_pk_add_f32 v[122:123], v[170:171], v[120:121]
	v_pk_add_f32 v[120:121], v[170:171], v[120:121] neg_lo:[0,1] neg_hi:[0,1]
	v_pk_add_f32 v[102:103], v[102:103], v[156:157] neg_lo:[0,1] neg_hi:[0,1]
	v_pk_add_f32 v[156:157], v[122:123], v[158:159]
	v_pk_add_f32 v[122:123], v[122:123], v[158:159] neg_lo:[0,1] neg_hi:[0,1]
	v_pk_add_f32 v[158:159], v[120:121], v[102:103] op_sel:[0,1] op_sel_hi:[1,0] neg_hi:[0,1]
	v_pk_add_f32 v[102:103], v[120:121], v[102:103] op_sel:[0,1] op_sel_hi:[1,0] neg_lo:[0,1]
	v_pk_add_f32 v[120:121], v[116:117], v[104:105]
	v_pk_add_f32 v[104:105], v[116:117], v[104:105] neg_lo:[0,1] neg_hi:[0,1]
	v_pk_add_f32 v[116:117], v[98:99], v[118:119]
	v_pk_add_f32 v[98:99], v[98:99], v[118:119] neg_lo:[0,1] neg_hi:[0,1]
	v_pk_add_f32 v[118:119], v[120:121], v[116:117]
	v_pk_add_f32 v[116:117], v[120:121], v[116:117] neg_lo:[0,1] neg_hi:[0,1]
	v_pk_add_f32 v[120:121], v[104:105], v[98:99] op_sel:[0,1] op_sel_hi:[1,0] neg_hi:[0,1]
	v_pk_add_f32 v[98:99], v[104:105], v[98:99] op_sel:[0,1] op_sel_hi:[1,0] neg_lo:[0,1]
	v_pk_add_f32 v[104:105], v[108:109], v[100:101]
	v_pk_add_f32 v[100:101], v[108:109], v[100:101] neg_lo:[0,1] neg_hi:[0,1]
	v_pk_add_f32 v[108:109], v[96:97], v[106:107]
	v_pk_add_f32 v[96:97], v[96:97], v[106:107] neg_lo:[0,1] neg_hi:[0,1]
	v_pk_add_f32 v[106:107], v[104:105], v[108:109]
	v_pk_add_f32 v[104:105], v[104:105], v[108:109] neg_lo:[0,1] neg_hi:[0,1]
	v_pk_add_f32 v[108:109], v[100:101], v[96:97] op_sel:[0,1] op_sel_hi:[1,0] neg_hi:[0,1]
	v_pk_add_f32 v[96:97], v[100:101], v[96:97] op_sel:[0,1] op_sel_hi:[1,0] neg_lo:[0,1]
	v_pk_mul_f32 v[100:101], v[154:155], v[94:95] op_sel:[0,0] op_sel_hi:[0,1]
	v_pk_fma_f32 v[94:95], v[154:155], v[94:95], v[100:101] op_sel:[1,1,0] op_sel_hi:[1,0,1] neg_lo:[0,1,0]
	v_pk_mul_f32 v[100:101], v[114:115], v[92:93] op_sel:[0,0] op_sel_hi:[0,1]
	v_pk_fma_f32 v[92:93], v[114:115], v[92:93], v[100:101] op_sel:[1,1,0] op_sel_hi:[1,0,1] neg_lo:[0,1,0]
	v_pk_mul_f32 v[100:101], v[110:111], v[90:91] op_sel:[0,0] op_sel_hi:[0,1]
	v_pk_fma_f32 v[90:91], v[110:111], v[90:91], v[100:101] op_sel:[1,1,0] op_sel_hi:[1,0,1] neg_lo:[0,1,0]
	v_pk_mul_f32 v[100:101], v[112:113], v[88:89] op_sel:[0,0] op_sel_hi:[0,1]
	v_pk_fma_f32 v[88:89], v[112:113], v[88:89], v[100:101] op_sel:[1,1,0] op_sel_hi:[1,0,1] neg_lo:[0,1,0]
	v_pk_mul_f32 v[100:101], v[156:157], v[86:87] op_sel:[0,0] op_sel_hi:[0,1]
	v_pk_fma_f32 v[86:87], v[156:157], v[86:87], v[100:101] op_sel:[1,1,0] op_sel_hi:[1,0,1] neg_lo:[0,1,0]
	v_pk_mul_f32 v[100:101], v[158:159], v[84:85] op_sel:[0,0] op_sel_hi:[0,1]
	v_pk_fma_f32 v[84:85], v[158:159], v[84:85], v[100:101] op_sel:[1,1,0] op_sel_hi:[1,0,1] neg_lo:[0,1,0]
	v_pk_mul_f32 v[100:101], v[122:123], v[82:83] op_sel:[0,0] op_sel_hi:[0,1]
	v_pk_fma_f32 v[82:83], v[122:123], v[82:83], v[100:101] op_sel:[1,1,0] op_sel_hi:[1,0,1] neg_lo:[0,1,0]
	v_pk_mul_f32 v[100:101], v[102:103], v[80:81] op_sel:[0,0] op_sel_hi:[0,1]
	v_pk_fma_f32 v[80:81], v[102:103], v[80:81], v[100:101] op_sel:[1,1,0] op_sel_hi:[1,0,1] neg_lo:[0,1,0]
	v_pk_mul_f32 v[100:101], v[118:119], v[78:79] op_sel:[0,0] op_sel_hi:[0,1]
	v_pk_fma_f32 v[78:79], v[118:119], v[78:79], v[100:101] op_sel:[1,1,0] op_sel_hi:[1,0,1] neg_lo:[0,1,0]
	v_pk_mul_f32 v[100:101], v[120:121], v[76:77] op_sel:[0,0] op_sel_hi:[0,1]
	v_pk_fma_f32 v[76:77], v[120:121], v[76:77], v[100:101] op_sel:[1,1,0] op_sel_hi:[1,0,1] neg_lo:[0,1,0]
	v_pk_mul_f32 v[100:101], v[116:117], v[74:75] op_sel:[0,0] op_sel_hi:[0,1]
	v_pk_fma_f32 v[74:75], v[116:117], v[74:75], v[100:101] op_sel:[1,1,0] op_sel_hi:[1,0,1] neg_lo:[0,1,0]
	v_pk_mul_f32 v[100:101], v[98:99], v[72:73] op_sel:[0,0] op_sel_hi:[0,1]
	v_pk_fma_f32 v[72:73], v[98:99], v[72:73], v[100:101] op_sel:[1,1,0] op_sel_hi:[1,0,1] neg_lo:[0,1,0]
	v_pk_mul_f32 v[98:99], v[106:107], v[32:33] op_sel:[0,0] op_sel_hi:[0,1]
	v_pk_fma_f32 v[32:33], v[106:107], v[32:33], v[98:99] op_sel:[1,1,0] op_sel_hi:[1,0,1] neg_lo:[0,1,0]
	v_pk_mul_f32 v[98:99], v[108:109], v[30:31] op_sel:[0,0] op_sel_hi:[0,1]
	v_pk_fma_f32 v[30:31], v[108:109], v[30:31], v[98:99] op_sel:[1,1,0] op_sel_hi:[1,0,1] neg_lo:[0,1,0]
	v_pk_mul_f32 v[98:99], v[104:105], v[28:29] op_sel:[0,0] op_sel_hi:[0,1]
	v_pk_fma_f32 v[28:29], v[104:105], v[28:29], v[98:99] op_sel:[1,1,0] op_sel_hi:[1,0,1] neg_lo:[0,1,0]
	v_pk_mul_f32 v[98:99], v[96:97], v[26:27] op_sel:[0,0] op_sel_hi:[0,1]
	v_pk_fma_f32 v[26:27], v[96:97], v[26:27], v[98:99] op_sel:[1,1,0] op_sel_hi:[1,0,1] neg_lo:[0,1,0]
	v_pk_add_f32 v[96:97], v[94:95], v[90:91]
	v_pk_add_f32 v[90:91], v[94:95], v[90:91] neg_lo:[0,1] neg_hi:[0,1]
	v_pk_add_f32 v[94:95], v[92:93], v[88:89]
	v_pk_add_f32 v[88:89], v[92:93], v[88:89] neg_lo:[0,1] neg_hi:[0,1]
	v_pk_add_f32 v[92:93], v[96:97], v[94:95]
	v_pk_add_f32 v[94:95], v[96:97], v[94:95] neg_lo:[0,1] neg_hi:[0,1]
	v_pk_add_f32 v[96:97], v[90:91], v[88:89] op_sel:[0,1] op_sel_hi:[1,0] neg_lo:[0,1]
	v_pk_add_f32 v[88:89], v[90:91], v[88:89] op_sel:[0,1] op_sel_hi:[1,0] neg_hi:[0,1]
	v_pk_add_f32 v[90:91], v[86:87], v[82:83]
	v_pk_add_f32 v[82:83], v[86:87], v[82:83] neg_lo:[0,1] neg_hi:[0,1]
	v_pk_add_f32 v[86:87], v[84:85], v[80:81]
	v_pk_add_f32 v[80:81], v[84:85], v[80:81] neg_lo:[0,1] neg_hi:[0,1]
	v_pk_add_f32 v[84:85], v[90:91], v[86:87]
	v_pk_add_f32 v[86:87], v[90:91], v[86:87] neg_lo:[0,1] neg_hi:[0,1]
	v_pk_add_f32 v[90:91], v[82:83], v[80:81] op_sel:[0,1] op_sel_hi:[1,0] neg_lo:[0,1]
	v_pk_add_f32 v[80:81], v[82:83], v[80:81] op_sel:[0,1] op_sel_hi:[1,0] neg_hi:[0,1]
	v_pk_add_f32 v[82:83], v[78:79], v[74:75]
	v_pk_add_f32 v[74:75], v[78:79], v[74:75] neg_lo:[0,1] neg_hi:[0,1]
	v_pk_add_f32 v[78:79], v[76:77], v[72:73]
	v_pk_add_f32 v[72:73], v[76:77], v[72:73] neg_lo:[0,1] neg_hi:[0,1]
	v_pk_add_f32 v[76:77], v[82:83], v[78:79]
	v_pk_add_f32 v[78:79], v[82:83], v[78:79] neg_lo:[0,1] neg_hi:[0,1]
	v_pk_add_f32 v[82:83], v[74:75], v[72:73] op_sel:[0,1] op_sel_hi:[1,0] neg_lo:[0,1]
	v_pk_add_f32 v[74:75], v[74:75], v[72:73] op_sel:[0,1] op_sel_hi:[1,0] neg_hi:[0,1]
	v_pk_add_f32 v[72:73], v[32:33], v[28:29]
	v_pk_add_f32 v[28:29], v[32:33], v[28:29] neg_lo:[0,1] neg_hi:[0,1]
	v_pk_add_f32 v[32:33], v[30:31], v[26:27]
	v_pk_add_f32 v[26:27], v[30:31], v[26:27] neg_lo:[0,1] neg_hi:[0,1]
	v_pk_add_f32 v[98:99], v[72:73], v[32:33]
	v_pk_add_f32 v[100:101], v[72:73], v[32:33] neg_lo:[0,1] neg_hi:[0,1]
	v_pk_add_f32 v[30:31], v[28:29], v[26:27] op_sel:[0,1] op_sel_hi:[1,0] neg_lo:[0,1]
	v_pk_add_f32 v[102:103], v[28:29], v[26:27] op_sel:[0,1] op_sel_hi:[1,0] neg_hi:[0,1]
	v_pk_mul_f32 v[26:27], v[90:91], s[62:63] op_sel:[0,0] op_sel_hi:[0,1]
	v_pk_fma_f32 v[90:91], v[90:91], s[62:63], v[26:27] op_sel:[1,1,0] op_sel_hi:[1,0,1] neg_lo:[0,1,0]
	v_pk_mul_f32 v[26:27], v[82:83], s[64:65] op_sel:[0,0] op_sel_hi:[0,1]
	v_pk_fma_f32 v[82:83], v[82:83], s[64:65], v[26:27] op_sel:[1,1,0] op_sel_hi:[1,0,1] neg_lo:[0,1,0]
	v_pk_mul_f32 v[72:73], v[30:31], s[66:67] op_sel:[0,0] op_sel_hi:[0,1]
	v_pk_fma_f32 v[104:105], v[30:31], s[66:67], v[72:73] op_sel:[1,1,0] op_sel_hi:[1,0,1] neg_lo:[0,1,0]
	v_pk_mul_f32 v[30:31], v[86:87], s[64:65] op_sel:[0,0] op_sel_hi:[0,1]
	v_pk_fma_f32 v[86:87], v[86:87], s[64:65], v[30:31] op_sel:[1,1,0] op_sel_hi:[1,0,1] neg_lo:[0,1,0]
	v_pk_mul_f32 v[30:31], v[78:79], s[68:69] op_sel:[0,0] op_sel_hi:[0,1]
	v_pk_fma_f32 v[78:79], v[78:79], s[68:69], v[30:31] op_sel:[1,1,0] op_sel_hi:[1,0,1] neg_lo:[0,1,0]
	v_pk_mul_f32 v[106:107], v[100:101], s[70:71] op_sel:[0,0] op_sel_hi:[0,1]
	v_pk_fma_f32 v[100:101], v[100:101], s[70:71], v[106:107] op_sel:[1,1,0] op_sel_hi:[1,0,1] neg_lo:[0,1,0]
	v_pk_mul_f32 v[106:107], v[80:81], s[66:67] op_sel:[0,0] op_sel_hi:[0,1]
	v_pk_fma_f32 v[80:81], v[80:81], s[66:67], v[106:107] op_sel:[1,1,0] op_sel_hi:[1,0,1] neg_lo:[0,1,0]
	v_pk_mul_f32 v[106:107], v[74:75], s[70:71] op_sel:[0,0] op_sel_hi:[0,1]
	v_pk_fma_f32 v[106:107], v[74:75], s[70:71], v[106:107] op_sel:[1,1,0] op_sel_hi:[1,0,1] neg_lo:[0,1,0]
	v_pk_mul_f32 v[108:109], v[102:103], s[72:73] op_sel:[0,0] op_sel_hi:[0,1]
	v_pk_fma_f32 v[102:103], v[102:103], s[72:73], v[108:109] op_sel:[1,1,0] op_sel_hi:[1,0,1] neg_lo:[0,1,0]
	v_pk_add_f32 v[108:109], v[92:93], v[76:77]
	v_pk_add_f32 v[76:77], v[92:93], v[76:77] neg_lo:[0,1] neg_hi:[0,1]
	v_pk_add_f32 v[92:93], v[84:85], v[98:99]
	v_pk_add_f32 v[84:85], v[84:85], v[98:99] neg_lo:[0,1] neg_hi:[0,1]
	v_pk_add_f32 v[98:99], v[108:109], v[92:93]
	v_pk_add_f32 v[92:93], v[108:109], v[92:93] neg_lo:[0,1] neg_hi:[0,1]
	v_pk_add_f32 v[108:109], v[76:77], v[84:85] op_sel:[0,1] op_sel_hi:[1,0] neg_lo:[0,1]
	v_pk_add_f32 v[76:77], v[76:77], v[84:85] op_sel:[0,1] op_sel_hi:[1,0] neg_hi:[0,1]
	v_pk_add_f32 v[84:85], v[96:97], v[82:83]
	v_pk_add_f32 v[82:83], v[96:97], v[82:83] neg_lo:[0,1] neg_hi:[0,1]
	v_pk_add_f32 v[96:97], v[90:91], v[104:105]
	v_pk_add_f32 v[90:91], v[90:91], v[104:105] neg_lo:[0,1] neg_hi:[0,1]
	v_pk_add_f32 v[104:105], v[84:85], v[96:97]
	v_pk_add_f32 v[84:85], v[84:85], v[96:97] neg_lo:[0,1] neg_hi:[0,1]
	v_pk_add_f32 v[96:97], v[82:83], v[90:91] op_sel:[0,1] op_sel_hi:[1,0] neg_lo:[0,1]
	v_pk_add_f32 v[82:83], v[82:83], v[90:91] op_sel:[0,1] op_sel_hi:[1,0] neg_hi:[0,1]
	v_pk_add_f32 v[90:91], v[94:95], v[78:79]
	v_pk_add_f32 v[78:79], v[94:95], v[78:79] neg_lo:[0,1] neg_hi:[0,1]
	v_pk_add_f32 v[94:95], v[86:87], v[100:101]
	v_pk_add_f32 v[86:87], v[86:87], v[100:101] neg_lo:[0,1] neg_hi:[0,1]
	v_pk_add_f32 v[100:101], v[90:91], v[94:95]
	v_pk_add_f32 v[90:91], v[90:91], v[94:95] neg_lo:[0,1] neg_hi:[0,1]
	v_pk_add_f32 v[94:95], v[78:79], v[86:87] op_sel:[0,1] op_sel_hi:[1,0] neg_lo:[0,1]
	v_pk_add_f32 v[78:79], v[78:79], v[86:87] op_sel:[0,1] op_sel_hi:[1,0] neg_hi:[0,1]
	v_pk_add_f32 v[86:87], v[88:89], v[106:107]
	v_pk_add_f32 v[88:89], v[88:89], v[106:107] neg_lo:[0,1] neg_hi:[0,1]
	v_pk_add_f32 v[106:107], v[80:81], v[102:103]
	v_pk_add_f32 v[80:81], v[80:81], v[102:103] neg_lo:[0,1] neg_hi:[0,1]
	v_pk_add_f32 v[102:103], v[86:87], v[106:107]
	v_pk_add_f32 v[86:87], v[86:87], v[106:107] neg_lo:[0,1] neg_hi:[0,1]
	v_pk_add_f32 v[106:107], v[88:89], v[80:81] op_sel:[0,1] op_sel_hi:[1,0] neg_lo:[0,1]
	v_pk_add_f32 v[80:81], v[88:89], v[80:81] op_sel:[0,1] op_sel_hi:[1,0] neg_hi:[0,1]
	ds_write2_b64 v147, v[98:99], v[104:105] offset1:1
	ds_write2_b64 v147, v[100:101], v[102:103] offset0:2 offset1:3
	ds_write2_b64 v147, v[108:109], v[96:97] offset0:4 offset1:5
	ds_write2_b64 v147, v[94:95], v[106:107] offset0:6 offset1:7
	ds_write2_b64 v147, v[92:93], v[84:85] offset0:8 offset1:9
	ds_write2_b64 v147, v[90:91], v[86:87] offset0:10 offset1:11
	ds_write2_b64 v147, v[76:77], v[82:83] offset0:12 offset1:13
	ds_write2_b64 v147, v[78:79], v[80:81] offset0:14 offset1:15
	v_mov_b32_e32 v86, v40
	v_mov_b32_e32 v87, v41
	s_waitcnt lgkmcnt(0)
	s_barrier
	ds_read2_b64 v[76:79], v146 offset1:17
	ds_read2_b64 v[80:83], v146 offset0:34 offset1:51
	s_waitcnt lgkmcnt(1)
	v_pk_mul_f32 v[84:85], v[78:79], v[86:87] op_sel:[0,0] op_sel_hi:[0,1] neg_hi:[0,1]
	v_pk_fma_f32 v[88:89], v[78:79], v[86:87], v[84:85] op_sel:[1,1,0] op_sel_hi:[1,0,1]
	v_pk_mul_f32 v[78:79], v[86:87], v[86:87] op_sel:[0,0] op_sel_hi:[0,1]
	v_pk_fma_f32 v[78:79], v[86:87], v[86:87], v[78:79] op_sel:[1,1,0] op_sel_hi:[1,0,1] neg_lo:[0,1,0]
	s_waitcnt lgkmcnt(0)
	v_pk_mul_f32 v[84:85], v[80:81], v[78:79] op_sel:[0,0] op_sel_hi:[0,1] neg_hi:[0,1]
	v_pk_fma_f32 v[90:91], v[80:81], v[78:79], v[84:85] op_sel:[1,1,0] op_sel_hi:[1,0,1]
	v_pk_mul_f32 v[80:81], v[78:79], v[86:87] op_sel:[0,0] op_sel_hi:[0,1]
	v_pk_fma_f32 v[84:85], v[78:79], v[86:87], v[80:81] op_sel:[1,1,0] op_sel_hi:[1,0,1] neg_lo:[0,1,0]
	ds_read2_b64 v[78:81], v146 offset0:68 offset1:85
	v_pk_mul_f32 v[92:93], v[82:83], v[84:85] op_sel:[0,0] op_sel_hi:[0,1] neg_hi:[0,1]
	v_pk_fma_f32 v[92:93], v[82:83], v[84:85], v[92:93] op_sel:[1,1,0] op_sel_hi:[1,0,1]
	v_pk_mul_f32 v[82:83], v[84:85], v[86:87] op_sel:[0,0] op_sel_hi:[0,1]
	v_pk_fma_f32 v[82:83], v[84:85], v[86:87], v[82:83] op_sel:[1,1,0] op_sel_hi:[1,0,1] neg_lo:[0,1,0]
	s_waitcnt lgkmcnt(0)
	v_pk_mul_f32 v[84:85], v[78:79], v[82:83] op_sel:[0,0] op_sel_hi:[0,1] neg_hi:[0,1]
	v_pk_fma_f32 v[94:95], v[78:79], v[82:83], v[84:85] op_sel:[1,1,0] op_sel_hi:[1,0,1]
	v_pk_mul_f32 v[78:79], v[82:83], v[86:87] op_sel:[0,0] op_sel_hi:[0,1]
	v_pk_fma_f32 v[78:79], v[82:83], v[86:87], v[78:79] op_sel:[1,1,0] op_sel_hi:[1,0,1] neg_lo:[0,1,0]
	ds_read2_b64 v[82:85], v146 offset0:102 offset1:119
	v_pk_mul_f32 v[96:97], v[80:81], v[78:79] op_sel:[0,0] op_sel_hi:[0,1] neg_hi:[0,1]
	v_pk_fma_f32 v[96:97], v[80:81], v[78:79], v[96:97] op_sel:[1,1,0] op_sel_hi:[1,0,1]
	v_pk_mul_f32 v[80:81], v[78:79], v[86:87] op_sel:[0,0] op_sel_hi:[0,1]
	v_pk_fma_f32 v[78:79], v[78:79], v[86:87], v[80:81] op_sel:[1,1,0] op_sel_hi:[1,0,1] neg_lo:[0,1,0]
	s_waitcnt lgkmcnt(0)
	v_pk_mul_f32 v[80:81], v[82:83], v[78:79] op_sel:[0,0] op_sel_hi:[0,1] neg_hi:[0,1]
	v_pk_fma_f32 v[98:99], v[82:83], v[78:79], v[80:81] op_sel:[1,1,0] op_sel_hi:[1,0,1]
	v_pk_mul_f32 v[80:81], v[78:79], v[86:87] op_sel:[0,0] op_sel_hi:[0,1]
	v_pk_fma_f32 v[82:83], v[78:79], v[86:87], v[80:81] op_sel:[1,1,0] op_sel_hi:[1,0,1] neg_lo:[0,1,0]
	ds_read2_b64 v[78:81], v146 offset0:136 offset1:153
	v_pk_mul_f32 v[100:101], v[84:85], v[82:83] op_sel:[0,0] op_sel_hi:[0,1] neg_hi:[0,1]
	v_pk_fma_f32 v[100:101], v[84:85], v[82:83], v[100:101] op_sel:[1,1,0] op_sel_hi:[1,0,1]
	v_pk_mul_f32 v[84:85], v[82:83], v[86:87] op_sel:[0,0] op_sel_hi:[0,1]
	v_pk_fma_f32 v[82:83], v[82:83], v[86:87], v[84:85] op_sel:[1,1,0] op_sel_hi:[1,0,1] neg_lo:[0,1,0]
	s_waitcnt lgkmcnt(0)
	v_pk_mul_f32 v[84:85], v[78:79], v[82:83] op_sel:[0,0] op_sel_hi:[0,1] neg_hi:[0,1]
	v_pk_fma_f32 v[102:103], v[78:79], v[82:83], v[84:85] op_sel:[1,1,0] op_sel_hi:[1,0,1]
	v_pk_mul_f32 v[78:79], v[82:83], v[86:87] op_sel:[0,0] op_sel_hi:[0,1]
	v_pk_fma_f32 v[78:79], v[82:83], v[86:87], v[78:79] op_sel:[1,1,0] op_sel_hi:[1,0,1] neg_lo:[0,1,0]
	ds_read2_b64 v[82:85], v146 offset0:170 offset1:187
	v_pk_mul_f32 v[104:105], v[80:81], v[78:79] op_sel:[0,0] op_sel_hi:[0,1] neg_hi:[0,1]
	v_pk_fma_f32 v[104:105], v[80:81], v[78:79], v[104:105] op_sel:[1,1,0] op_sel_hi:[1,0,1]
	v_pk_mul_f32 v[80:81], v[78:79], v[86:87] op_sel:[0,0] op_sel_hi:[0,1]
	v_pk_fma_f32 v[78:79], v[78:79], v[86:87], v[80:81] op_sel:[1,1,0] op_sel_hi:[1,0,1] neg_lo:[0,1,0]
	s_waitcnt lgkmcnt(0)
	v_pk_mul_f32 v[80:81], v[82:83], v[78:79] op_sel:[0,0] op_sel_hi:[0,1] neg_hi:[0,1]
	v_pk_fma_f32 v[106:107], v[82:83], v[78:79], v[80:81] op_sel:[1,1,0] op_sel_hi:[1,0,1]
	v_pk_mul_f32 v[80:81], v[78:79], v[86:87] op_sel:[0,0] op_sel_hi:[0,1]
	v_pk_fma_f32 v[82:83], v[78:79], v[86:87], v[80:81] op_sel:[1,1,0] op_sel_hi:[1,0,1] neg_lo:[0,1,0]
	ds_read2_b64 v[78:81], v146 offset0:204 offset1:221
	v_pk_mul_f32 v[108:109], v[84:85], v[82:83] op_sel:[0,0] op_sel_hi:[0,1] neg_hi:[0,1]
	v_pk_fma_f32 v[108:109], v[84:85], v[82:83], v[108:109] op_sel:[1,1,0] op_sel_hi:[1,0,1]
	v_pk_mul_f32 v[84:85], v[82:83], v[86:87] op_sel:[0,0] op_sel_hi:[0,1]
	v_pk_fma_f32 v[82:83], v[82:83], v[86:87], v[84:85] op_sel:[1,1,0] op_sel_hi:[1,0,1] neg_lo:[0,1,0]
	s_waitcnt lgkmcnt(0)
	v_pk_mul_f32 v[84:85], v[78:79], v[82:83] op_sel:[0,0] op_sel_hi:[0,1] neg_hi:[0,1]
	v_pk_fma_f32 v[78:79], v[78:79], v[82:83], v[84:85] op_sel:[1,1,0] op_sel_hi:[1,0,1]
	v_pk_mul_f32 v[84:85], v[82:83], v[86:87] op_sel:[0,0] op_sel_hi:[0,1]
	v_pk_fma_f32 v[110:111], v[82:83], v[86:87], v[84:85] op_sel:[1,1,0] op_sel_hi:[1,0,1] neg_lo:[0,1,0]
	ds_read2_b64 v[82:85], v146 offset0:238 offset1:255
	v_pk_mul_f32 v[112:113], v[80:81], v[110:111] op_sel:[0,0] op_sel_hi:[0,1] neg_hi:[0,1]
	v_pk_fma_f32 v[80:81], v[80:81], v[110:111], v[112:113] op_sel:[1,1,0] op_sel_hi:[1,0,1]
	v_pk_mul_f32 v[112:113], v[110:111], v[86:87] op_sel:[0,0] op_sel_hi:[0,1]
	v_pk_fma_f32 v[110:111], v[110:111], v[86:87], v[112:113] op_sel:[1,1,0] op_sel_hi:[1,0,1] neg_lo:[0,1,0]
	s_waitcnt lgkmcnt(0)
	v_pk_mul_f32 v[112:113], v[82:83], v[110:111] op_sel:[0,0] op_sel_hi:[0,1] neg_hi:[0,1]
	v_pk_fma_f32 v[82:83], v[82:83], v[110:111], v[112:113] op_sel:[1,1,0] op_sel_hi:[1,0,1]
	v_pk_mul_f32 v[112:113], v[110:111], v[86:87] op_sel:[0,0] op_sel_hi:[0,1]
	v_pk_fma_f32 v[86:87], v[110:111], v[86:87], v[112:113] op_sel:[1,1,0] op_sel_hi:[1,0,1] neg_lo:[0,1,0]
	v_pk_mul_f32 v[110:111], v[84:85], v[86:87] op_sel:[0,0] op_sel_hi:[0,1] neg_hi:[0,1]
	v_pk_fma_f32 v[84:85], v[84:85], v[86:87], v[110:111] op_sel:[1,1,0] op_sel_hi:[1,0,1]
	v_pk_add_f32 v[86:87], v[76:77], v[102:103]
	v_pk_add_f32 v[76:77], v[76:77], v[102:103] neg_lo:[0,1] neg_hi:[0,1]
	v_pk_add_f32 v[102:103], v[94:95], v[78:79]
	v_pk_add_f32 v[78:79], v[94:95], v[78:79] neg_lo:[0,1] neg_hi:[0,1]
	v_pk_add_f32 v[94:95], v[86:87], v[102:103]
	v_pk_add_f32 v[86:87], v[86:87], v[102:103] neg_lo:[0,1] neg_hi:[0,1]
	v_pk_add_f32 v[102:103], v[76:77], v[78:79] op_sel:[0,1] op_sel_hi:[1,0] neg_lo:[0,1]
	v_pk_add_f32 v[76:77], v[76:77], v[78:79] op_sel:[0,1] op_sel_hi:[1,0] neg_hi:[0,1]
	v_pk_add_f32 v[78:79], v[88:89], v[104:105]
	v_pk_add_f32 v[88:89], v[88:89], v[104:105] neg_lo:[0,1] neg_hi:[0,1]
	v_pk_add_f32 v[104:105], v[96:97], v[80:81]
	v_pk_add_f32 v[80:81], v[96:97], v[80:81] neg_lo:[0,1] neg_hi:[0,1]
	v_pk_add_f32 v[96:97], v[78:79], v[104:105]
	v_pk_add_f32 v[78:79], v[78:79], v[104:105] neg_lo:[0,1] neg_hi:[0,1]
	v_pk_add_f32 v[104:105], v[88:89], v[80:81] op_sel:[0,1] op_sel_hi:[1,0] neg_lo:[0,1]
	v_pk_add_f32 v[80:81], v[88:89], v[80:81] op_sel:[0,1] op_sel_hi:[1,0] neg_hi:[0,1]
	v_pk_add_f32 v[88:89], v[90:91], v[106:107]
	v_pk_add_f32 v[90:91], v[90:91], v[106:107] neg_lo:[0,1] neg_hi:[0,1]
	v_pk_add_f32 v[106:107], v[98:99], v[82:83]
	v_pk_add_f32 v[82:83], v[98:99], v[82:83] neg_lo:[0,1] neg_hi:[0,1]
	v_pk_add_f32 v[98:99], v[88:89], v[106:107]
	v_pk_add_f32 v[88:89], v[88:89], v[106:107] neg_lo:[0,1] neg_hi:[0,1]
	v_pk_add_f32 v[106:107], v[90:91], v[82:83] op_sel:[0,1] op_sel_hi:[1,0] neg_lo:[0,1]
	v_pk_add_f32 v[82:83], v[90:91], v[82:83] op_sel:[0,1] op_sel_hi:[1,0] neg_hi:[0,1]
	v_pk_add_f32 v[90:91], v[92:93], v[108:109]
	v_pk_add_f32 v[92:93], v[92:93], v[108:109] neg_lo:[0,1] neg_hi:[0,1]
	v_pk_add_f32 v[108:109], v[100:101], v[84:85]
	v_pk_add_f32 v[84:85], v[100:101], v[84:85] neg_lo:[0,1] neg_hi:[0,1]
	v_pk_add_f32 v[100:101], v[90:91], v[108:109]
	v_pk_add_f32 v[90:91], v[90:91], v[108:109] neg_lo:[0,1] neg_hi:[0,1]
	v_pk_add_f32 v[108:109], v[92:93], v[84:85] op_sel:[0,1] op_sel_hi:[1,0] neg_lo:[0,1]
	v_pk_add_f32 v[84:85], v[92:93], v[84:85] op_sel:[0,1] op_sel_hi:[1,0] neg_hi:[0,1]
	v_pk_mul_f32 v[92:93], v[104:105], s[62:63] op_sel:[0,0] op_sel_hi:[0,1]
	v_pk_fma_f32 v[92:93], v[104:105], s[62:63], v[92:93] op_sel:[1,1,0] op_sel_hi:[1,0,1] neg_lo:[0,1,0]
	v_pk_mul_f32 v[104:105], v[106:107], s[64:65] op_sel:[0,0] op_sel_hi:[0,1]
	v_pk_fma_f32 v[104:105], v[106:107], s[64:65], v[104:105] op_sel:[1,1,0] op_sel_hi:[1,0,1] neg_lo:[0,1,0]
	v_pk_mul_f32 v[106:107], v[108:109], s[66:67] op_sel:[0,0] op_sel_hi:[0,1]
	v_pk_fma_f32 v[106:107], v[108:109], s[66:67], v[106:107] op_sel:[1,1,0] op_sel_hi:[1,0,1] neg_lo:[0,1,0]
	v_pk_mul_f32 v[108:109], v[78:79], s[64:65] op_sel:[0,0] op_sel_hi:[0,1]
	v_pk_fma_f32 v[78:79], v[78:79], s[64:65], v[108:109] op_sel:[1,1,0] op_sel_hi:[1,0,1] neg_lo:[0,1,0]
	v_pk_mul_f32 v[108:109], v[88:89], s[68:69] op_sel:[0,0] op_sel_hi:[0,1]
	v_pk_fma_f32 v[88:89], v[88:89], s[68:69], v[108:109] op_sel:[1,1,0] op_sel_hi:[1,0,1] neg_lo:[0,1,0]
	v_pk_mul_f32 v[108:109], v[90:91], s[70:71] op_sel:[0,0] op_sel_hi:[0,1]
	v_pk_fma_f32 v[90:91], v[90:91], s[70:71], v[108:109] op_sel:[1,1,0] op_sel_hi:[1,0,1] neg_lo:[0,1,0]
	v_pk_mul_f32 v[108:109], v[80:81], s[66:67] op_sel:[0,0] op_sel_hi:[0,1]
	v_pk_fma_f32 v[80:81], v[80:81], s[66:67], v[108:109] op_sel:[1,1,0] op_sel_hi:[1,0,1] neg_lo:[0,1,0]
	v_pk_mul_f32 v[108:109], v[82:83], s[70:71] op_sel:[0,0] op_sel_hi:[0,1]
	v_pk_fma_f32 v[82:83], v[82:83], s[70:71], v[108:109] op_sel:[1,1,0] op_sel_hi:[1,0,1] neg_lo:[0,1,0]
	v_pk_mul_f32 v[108:109], v[84:85], s[72:73] op_sel:[0,0] op_sel_hi:[0,1]
	v_pk_fma_f32 v[84:85], v[84:85], s[72:73], v[108:109] op_sel:[1,1,0] op_sel_hi:[1,0,1] neg_lo:[0,1,0]
	v_pk_add_f32 v[108:109], v[94:95], v[98:99]
	v_pk_add_f32 v[94:95], v[94:95], v[98:99] neg_lo:[0,1] neg_hi:[0,1]
	v_pk_add_f32 v[98:99], v[96:97], v[100:101]
	v_pk_add_f32 v[96:97], v[96:97], v[100:101] neg_lo:[0,1] neg_hi:[0,1]
	v_pk_add_f32 v[100:101], v[108:109], v[98:99]
	v_pk_add_f32 v[98:99], v[108:109], v[98:99] neg_lo:[0,1] neg_hi:[0,1]
	v_pk_add_f32 v[108:109], v[94:95], v[96:97] op_sel:[0,1] op_sel_hi:[1,0] neg_lo:[0,1]
	v_pk_add_f32 v[94:95], v[94:95], v[96:97] op_sel:[0,1] op_sel_hi:[1,0] neg_hi:[0,1]
	v_pk_add_f32 v[96:97], v[102:103], v[104:105]
	v_pk_add_f32 v[102:103], v[102:103], v[104:105] neg_lo:[0,1] neg_hi:[0,1]
	v_pk_add_f32 v[104:105], v[92:93], v[106:107]
	v_pk_add_f32 v[92:93], v[92:93], v[106:107] neg_lo:[0,1] neg_hi:[0,1]
	v_pk_add_f32 v[106:107], v[96:97], v[104:105]
	v_pk_add_f32 v[96:97], v[96:97], v[104:105] neg_lo:[0,1] neg_hi:[0,1]
	v_pk_add_f32 v[104:105], v[102:103], v[92:93] op_sel:[0,1] op_sel_hi:[1,0] neg_lo:[0,1]
	v_pk_add_f32 v[92:93], v[102:103], v[92:93] op_sel:[0,1] op_sel_hi:[1,0] neg_hi:[0,1]
	v_pk_add_f32 v[102:103], v[86:87], v[88:89]
	v_pk_add_f32 v[86:87], v[86:87], v[88:89] neg_lo:[0,1] neg_hi:[0,1]
	v_pk_add_f32 v[88:89], v[78:79], v[90:91]
	v_pk_add_f32 v[78:79], v[78:79], v[90:91] neg_lo:[0,1] neg_hi:[0,1]
	v_pk_add_f32 v[90:91], v[102:103], v[88:89]
	v_pk_add_f32 v[88:89], v[102:103], v[88:89] neg_lo:[0,1] neg_hi:[0,1]
	v_pk_add_f32 v[102:103], v[86:87], v[78:79] op_sel:[0,1] op_sel_hi:[1,0] neg_lo:[0,1]
	v_pk_add_f32 v[78:79], v[86:87], v[78:79] op_sel:[0,1] op_sel_hi:[1,0] neg_hi:[0,1]
	v_pk_add_f32 v[86:87], v[76:77], v[82:83]
	v_pk_add_f32 v[76:77], v[76:77], v[82:83] neg_lo:[0,1] neg_hi:[0,1]
	v_pk_add_f32 v[82:83], v[80:81], v[84:85]
	v_pk_add_f32 v[80:81], v[80:81], v[84:85] neg_lo:[0,1] neg_hi:[0,1]
	v_pk_add_f32 v[84:85], v[86:87], v[82:83]
	v_pk_add_f32 v[82:83], v[86:87], v[82:83] neg_lo:[0,1] neg_hi:[0,1]
	v_pk_add_f32 v[86:87], v[76:77], v[80:81] op_sel:[0,1] op_sel_hi:[1,0] neg_lo:[0,1]
	v_pk_add_f32 v[76:77], v[76:77], v[80:81] op_sel:[0,1] op_sel_hi:[1,0] neg_hi:[0,1]
	ds_write2_b64 v146, v[100:101], v[106:107] offset1:17
	ds_write2_b64 v146, v[90:91], v[84:85] offset0:34 offset1:51
	ds_write2_b64 v146, v[108:109], v[104:105] offset0:68 offset1:85
	ds_write2_b64 v146, v[102:103], v[86:87] offset0:102 offset1:119
	ds_write2_b64 v146, v[98:99], v[96:97] offset0:136 offset1:153
	ds_write2_b64 v146, v[88:89], v[82:83] offset0:170 offset1:187
	ds_write2_b64 v146, v[94:95], v[92:93] offset0:204 offset1:221
	ds_write2_b64 v146, v[78:79], v[76:77] offset0:238 offset1:255
	v_mov_b32_e32 v77, v39
	v_mov_b32_e32 v76, v38
	s_waitcnt lgkmcnt(0)
	s_barrier
	ds_read_b64 v[78:79], v144 offset:2176
	ds_read_b64 v[80:81], v144 offset:4352
	ds_read_b64 v[82:83], v144 offset:6528
	ds_read_b64 v[84:85], v144
	s_waitcnt lgkmcnt(3)
	v_pk_mul_f32 v[86:87], v[78:79], v[76:77] op_sel:[0,0] op_sel_hi:[0,1] neg_hi:[0,1]
	v_pk_fma_f32 v[78:79], v[78:79], v[76:77], v[86:87] op_sel:[1,1,0] op_sel_hi:[1,0,1]
	v_pk_mul_f32 v[86:87], v[76:77], v[76:77] op_sel:[0,0] op_sel_hi:[0,1]
	ds_read_b64 v[90:91], v144 offset:8704
	v_pk_fma_f32 v[86:87], v[76:77], v[76:77], v[86:87] op_sel:[1,1,0] op_sel_hi:[1,0,1] neg_lo:[0,1,0]
	s_waitcnt lgkmcnt(3)
	v_pk_mul_f32 v[88:89], v[80:81], v[86:87] op_sel:[0,0] op_sel_hi:[0,1] neg_hi:[0,1]
	v_pk_fma_f32 v[80:81], v[80:81], v[86:87], v[88:89] op_sel:[1,1,0] op_sel_hi:[1,0,1]
	v_pk_mul_f32 v[88:89], v[86:87], v[76:77] op_sel:[0,0] op_sel_hi:[0,1]
	v_pk_fma_f32 v[86:87], v[86:87], v[76:77], v[88:89] op_sel:[1,1,0] op_sel_hi:[1,0,1] neg_lo:[0,1,0]
	s_waitcnt lgkmcnt(2)
	v_pk_mul_f32 v[88:89], v[82:83], v[86:87] op_sel:[0,0] op_sel_hi:[0,1] neg_hi:[0,1]
	v_pk_fma_f32 v[82:83], v[82:83], v[86:87], v[88:89] op_sel:[1,1,0] op_sel_hi:[1,0,1]
	v_pk_mul_f32 v[88:89], v[86:87], v[76:77] op_sel:[0,0] op_sel_hi:[0,1]
	v_pk_fma_f32 v[86:87], v[86:87], v[76:77], v[88:89] op_sel:[1,1,0] op_sel_hi:[1,0,1] neg_lo:[0,1,0]
	ds_read_b64 v[88:89], v144 offset:10880
	ds_read_b64 v[92:93], v144 offset:13056
	ds_read_b64 v[94:95], v144 offset:15232
	s_waitcnt lgkmcnt(3)
	v_pk_mul_f32 v[96:97], v[90:91], v[86:87] op_sel:[0,0] op_sel_hi:[0,1] neg_hi:[0,1]
	ds_read_b64 v[98:99], v144 offset:17408
	v_pk_fma_f32 v[90:91], v[90:91], v[86:87], v[96:97] op_sel:[1,1,0] op_sel_hi:[1,0,1]
	v_pk_mul_f32 v[96:97], v[86:87], v[76:77] op_sel:[0,0] op_sel_hi:[0,1]
	v_pk_fma_f32 v[86:87], v[86:87], v[76:77], v[96:97] op_sel:[1,1,0] op_sel_hi:[1,0,1] neg_lo:[0,1,0]
	s_waitcnt lgkmcnt(3)
	v_pk_mul_f32 v[96:97], v[88:89], v[86:87] op_sel:[0,0] op_sel_hi:[0,1] neg_hi:[0,1]
	v_pk_fma_f32 v[88:89], v[88:89], v[86:87], v[96:97] op_sel:[1,1,0] op_sel_hi:[1,0,1]
	v_pk_mul_f32 v[96:97], v[86:87], v[76:77] op_sel:[0,0] op_sel_hi:[0,1]
	v_pk_fma_f32 v[86:87], v[86:87], v[76:77], v[96:97] op_sel:[1,1,0] op_sel_hi:[1,0,1] neg_lo:[0,1,0]
	s_waitcnt lgkmcnt(2)
	v_pk_mul_f32 v[96:97], v[92:93], v[86:87] op_sel:[0,0] op_sel_hi:[0,1] neg_hi:[0,1]
	v_pk_fma_f32 v[92:93], v[92:93], v[86:87], v[96:97] op_sel:[1,1,0] op_sel_hi:[1,0,1]
	v_pk_mul_f32 v[96:97], v[86:87], v[76:77] op_sel:[0,0] op_sel_hi:[0,1]
	v_pk_fma_f32 v[86:87], v[86:87], v[76:77], v[96:97] op_sel:[1,1,0] op_sel_hi:[1,0,1] neg_lo:[0,1,0]
	s_waitcnt lgkmcnt(1)
	v_pk_mul_f32 v[96:97], v[94:95], v[86:87] op_sel:[0,0] op_sel_hi:[0,1] neg_hi:[0,1]
	v_pk_fma_f32 v[94:95], v[94:95], v[86:87], v[96:97] op_sel:[1,1,0] op_sel_hi:[1,0,1]
	v_pk_mul_f32 v[96:97], v[86:87], v[76:77] op_sel:[0,0] op_sel_hi:[0,1]
	v_pk_fma_f32 v[86:87], v[86:87], v[76:77], v[96:97] op_sel:[1,1,0] op_sel_hi:[1,0,1] neg_lo:[0,1,0]
	ds_read_b64 v[96:97], v144 offset:19584
	ds_read_b64 v[100:101], v144 offset:21760
	ds_read_b64 v[102:103], v144 offset:23936
	s_waitcnt lgkmcnt(3)
	v_pk_mul_f32 v[104:105], v[98:99], v[86:87] op_sel:[0,0] op_sel_hi:[0,1] neg_hi:[0,1]
	ds_read_b64 v[106:107], v144 offset:26112
	v_pk_fma_f32 v[98:99], v[98:99], v[86:87], v[104:105] op_sel:[1,1,0] op_sel_hi:[1,0,1]
	v_pk_mul_f32 v[104:105], v[86:87], v[76:77] op_sel:[0,0] op_sel_hi:[0,1]
	v_pk_fma_f32 v[86:87], v[86:87], v[76:77], v[104:105] op_sel:[1,1,0] op_sel_hi:[1,0,1] neg_lo:[0,1,0]
	s_waitcnt lgkmcnt(3)
	v_pk_mul_f32 v[104:105], v[96:97], v[86:87] op_sel:[0,0] op_sel_hi:[0,1] neg_hi:[0,1]
	v_pk_fma_f32 v[96:97], v[96:97], v[86:87], v[104:105] op_sel:[1,1,0] op_sel_hi:[1,0,1]
	v_pk_mul_f32 v[104:105], v[86:87], v[76:77] op_sel:[0,0] op_sel_hi:[0,1]
	v_pk_fma_f32 v[86:87], v[86:87], v[76:77], v[104:105] op_sel:[1,1,0] op_sel_hi:[1,0,1] neg_lo:[0,1,0]
	s_waitcnt lgkmcnt(2)
	v_pk_mul_f32 v[104:105], v[100:101], v[86:87] op_sel:[0,0] op_sel_hi:[0,1] neg_hi:[0,1]
	v_pk_fma_f32 v[100:101], v[100:101], v[86:87], v[104:105] op_sel:[1,1,0] op_sel_hi:[1,0,1]
	v_pk_mul_f32 v[104:105], v[86:87], v[76:77] op_sel:[0,0] op_sel_hi:[0,1]
	v_pk_fma_f32 v[86:87], v[86:87], v[76:77], v[104:105] op_sel:[1,1,0] op_sel_hi:[1,0,1] neg_lo:[0,1,0]
	s_waitcnt lgkmcnt(1)
	v_pk_mul_f32 v[104:105], v[102:103], v[86:87] op_sel:[0,0] op_sel_hi:[0,1] neg_hi:[0,1]
	v_pk_fma_f32 v[102:103], v[102:103], v[86:87], v[104:105] op_sel:[1,1,0] op_sel_hi:[1,0,1]
	v_pk_mul_f32 v[104:105], v[86:87], v[76:77] op_sel:[0,0] op_sel_hi:[0,1]
	v_pk_fma_f32 v[86:87], v[86:87], v[76:77], v[104:105] op_sel:[1,1,0] op_sel_hi:[1,0,1] neg_lo:[0,1,0]
	ds_read_b64 v[104:105], v144 offset:28288
	ds_read_b64 v[108:109], v144 offset:30464
	ds_read_b64 v[110:111], v144 offset:32640
	s_waitcnt lgkmcnt(3)
	v_pk_mul_f32 v[112:113], v[106:107], v[86:87] op_sel:[0,0] op_sel_hi:[0,1] neg_hi:[0,1]
	v_pk_fma_f32 v[106:107], v[106:107], v[86:87], v[112:113] op_sel:[1,1,0] op_sel_hi:[1,0,1]
	v_pk_mul_f32 v[112:113], v[86:87], v[76:77] op_sel:[0,0] op_sel_hi:[0,1]
	v_pk_fma_f32 v[86:87], v[86:87], v[76:77], v[112:113] op_sel:[1,1,0] op_sel_hi:[1,0,1] neg_lo:[0,1,0]
	s_waitcnt lgkmcnt(2)
	v_pk_mul_f32 v[112:113], v[104:105], v[86:87] op_sel:[0,0] op_sel_hi:[0,1] neg_hi:[0,1]
	v_pk_fma_f32 v[104:105], v[104:105], v[86:87], v[112:113] op_sel:[1,1,0] op_sel_hi:[1,0,1]
	v_pk_mul_f32 v[112:113], v[86:87], v[76:77] op_sel:[0,0] op_sel_hi:[0,1]
	v_pk_fma_f32 v[86:87], v[86:87], v[76:77], v[112:113] op_sel:[1,1,0] op_sel_hi:[1,0,1] neg_lo:[0,1,0]
	s_waitcnt lgkmcnt(1)
	v_pk_mul_f32 v[112:113], v[108:109], v[86:87] op_sel:[0,0] op_sel_hi:[0,1] neg_hi:[0,1]
	v_pk_fma_f32 v[108:109], v[108:109], v[86:87], v[112:113] op_sel:[1,1,0] op_sel_hi:[1,0,1]
	v_pk_mul_f32 v[112:113], v[86:87], v[76:77] op_sel:[0,0] op_sel_hi:[0,1]
	v_pk_fma_f32 v[76:77], v[86:87], v[76:77], v[112:113] op_sel:[1,1,0] op_sel_hi:[1,0,1] neg_lo:[0,1,0]
	s_waitcnt lgkmcnt(0)
	v_pk_mul_f32 v[86:87], v[110:111], v[76:77] op_sel:[0,0] op_sel_hi:[0,1] neg_hi:[0,1]
	v_pk_fma_f32 v[76:77], v[110:111], v[76:77], v[86:87] op_sel:[1,1,0] op_sel_hi:[1,0,1]
	v_pk_add_f32 v[86:87], v[84:85], v[98:99]
	v_pk_add_f32 v[84:85], v[84:85], v[98:99] neg_lo:[0,1] neg_hi:[0,1]
	v_pk_add_f32 v[98:99], v[90:91], v[106:107]
	v_pk_add_f32 v[90:91], v[90:91], v[106:107] neg_lo:[0,1] neg_hi:[0,1]
	v_pk_add_f32 v[106:107], v[86:87], v[98:99]
	v_pk_add_f32 v[98:99], v[86:87], v[98:99] neg_lo:[0,1] neg_hi:[0,1]
	v_pk_add_f32 v[86:87], v[84:85], v[90:91] op_sel:[0,1] op_sel_hi:[1,0] neg_lo:[0,1]
	v_pk_add_f32 v[110:111], v[84:85], v[90:91] op_sel:[0,1] op_sel_hi:[1,0] neg_hi:[0,1]
	v_pk_add_f32 v[84:85], v[78:79], v[96:97]
	v_pk_add_f32 v[78:79], v[78:79], v[96:97] neg_lo:[0,1] neg_hi:[0,1]
	v_pk_add_f32 v[90:91], v[88:89], v[104:105]
	v_pk_add_f32 v[88:89], v[88:89], v[104:105] neg_lo:[0,1] neg_hi:[0,1]
	v_pk_add_f32 v[96:97], v[84:85], v[90:91]
	v_pk_add_f32 v[84:85], v[84:85], v[90:91] neg_lo:[0,1] neg_hi:[0,1]
	v_pk_add_f32 v[90:91], v[78:79], v[88:89] op_sel:[0,1] op_sel_hi:[1,0] neg_lo:[0,1]
	v_pk_add_f32 v[78:79], v[78:79], v[88:89] op_sel:[0,1] op_sel_hi:[1,0] neg_hi:[0,1]
	v_pk_add_f32 v[88:89], v[80:81], v[100:101]
	v_pk_add_f32 v[80:81], v[80:81], v[100:101] neg_lo:[0,1] neg_hi:[0,1]
	v_pk_add_f32 v[100:101], v[92:93], v[108:109]
	v_pk_add_f32 v[92:93], v[92:93], v[108:109] neg_lo:[0,1] neg_hi:[0,1]
	v_pk_add_f32 v[104:105], v[88:89], v[100:101]
	v_pk_add_f32 v[88:89], v[88:89], v[100:101] neg_lo:[0,1] neg_hi:[0,1]
	v_pk_add_f32 v[100:101], v[80:81], v[92:93] op_sel:[0,1] op_sel_hi:[1,0] neg_lo:[0,1]
	v_pk_add_f32 v[80:81], v[80:81], v[92:93] op_sel:[0,1] op_sel_hi:[1,0] neg_hi:[0,1]
	v_pk_add_f32 v[92:93], v[82:83], v[102:103]
	v_pk_add_f32 v[82:83], v[82:83], v[102:103] neg_lo:[0,1] neg_hi:[0,1]
	v_pk_add_f32 v[102:103], v[94:95], v[76:77]
	v_pk_add_f32 v[76:77], v[94:95], v[76:77] neg_lo:[0,1] neg_hi:[0,1]
	v_pk_add_f32 v[94:95], v[92:93], v[102:103]
	v_pk_add_f32 v[92:93], v[92:93], v[102:103] neg_lo:[0,1] neg_hi:[0,1]
	v_pk_add_f32 v[102:103], v[82:83], v[76:77] op_sel:[0,1] op_sel_hi:[1,0] neg_lo:[0,1]
	v_pk_add_f32 v[76:77], v[82:83], v[76:77] op_sel:[0,1] op_sel_hi:[1,0] neg_hi:[0,1]
	v_pk_mul_f32 v[82:83], v[90:91], s[62:63] op_sel:[0,0] op_sel_hi:[0,1]
	v_pk_fma_f32 v[32:33], v[90:91], s[62:63], v[82:83] op_sel:[1,1,0] op_sel_hi:[1,0,1] neg_lo:[0,1,0]
	v_pk_mul_f32 v[82:83], v[100:101], s[64:65] op_sel:[0,0] op_sel_hi:[0,1]
	v_pk_mul_f32 v[90:91], v[102:103], s[66:67] op_sel:[0,0] op_sel_hi:[0,1]
	v_pk_fma_f32 v[82:83], v[100:101], s[64:65], v[82:83] op_sel:[1,1,0] op_sel_hi:[1,0,1] neg_lo:[0,1,0]
	v_pk_mul_f32 v[100:101], v[84:85], s[64:65] op_sel:[0,0] op_sel_hi:[0,1]
	v_pk_fma_f32 v[90:91], v[102:103], s[66:67], v[90:91] op_sel:[1,1,0] op_sel_hi:[1,0,1] neg_lo:[0,1,0]
	v_pk_fma_f32 v[108:109], v[84:85], s[64:65], v[100:101] op_sel:[1,1,0] op_sel_hi:[1,0,1] neg_lo:[0,1,0]
	v_pk_mul_f32 v[28:29], v[88:89], s[68:69] op_sel:[0,0] op_sel_hi:[0,1]
	v_pk_add_f32 v[84:85], v[32:33], v[90:91]
	v_pk_fma_f32 v[72:73], v[88:89], s[68:69], v[28:29] op_sel:[1,1,0] op_sel_hi:[1,0,1] neg_lo:[0,1,0]
	v_pk_mul_f32 v[28:29], v[92:93], s[70:71] op_sel:[0,0] op_sel_hi:[0,1]
	v_pk_fma_f32 v[88:89], v[92:93], s[70:71], v[28:29] op_sel:[1,1,0] op_sel_hi:[1,0,1] neg_lo:[0,1,0]
	v_pk_mul_f32 v[28:29], v[78:79], s[66:67] op_sel:[0,0] op_sel_hi:[0,1]
	v_pk_fma_f32 v[112:113], v[78:79], s[66:67], v[28:29] op_sel:[1,1,0] op_sel_hi:[1,0,1] neg_lo:[0,1,0]
	v_pk_mul_f32 v[26:27], v[80:81], s[70:71] op_sel:[0,0] op_sel_hi:[0,1]
	v_pk_add_f32 v[28:29], v[96:97], v[94:95] neg_lo:[0,1] neg_hi:[0,1]
	v_pk_fma_f32 v[114:115], v[80:81], s[70:71], v[26:27] op_sel:[1,1,0] op_sel_hi:[1,0,1] neg_lo:[0,1,0]
	v_pk_mul_f32 v[26:27], v[76:77], s[72:73] op_sel:[0,0] op_sel_hi:[0,1]
	v_pk_add_f32 v[30:31], v[32:33], v[90:91] neg_lo:[0,1] neg_hi:[0,1]
	v_pk_fma_f32 v[116:117], v[76:77], s[72:73], v[26:27] op_sel:[1,1,0] op_sel_hi:[1,0,1] neg_lo:[0,1,0]
	v_pk_add_f32 v[26:27], v[106:107], v[104:105] neg_lo:[0,1] neg_hi:[0,1]
	v_pk_add_f32 v[80:81], v[86:87], v[82:83]
	v_pk_add_f32 v[76:77], v[26:27], v[28:29] op_sel:[0,1] op_sel_hi:[1,0] neg_lo:[0,1]
	v_pk_add_f32 v[26:27], v[26:27], v[28:29] op_sel:[0,1] op_sel_hi:[1,0] neg_hi:[0,1]
	v_pk_add_f32 v[28:29], v[86:87], v[82:83] neg_lo:[0,1] neg_hi:[0,1]
	v_pk_add_f32 v[32:33], v[108:109], v[88:89] neg_lo:[0,1] neg_hi:[0,1]
	v_pk_add_f32 v[82:83], v[28:29], v[30:31] op_sel:[0,1] op_sel_hi:[1,0] neg_lo:[0,1]
	v_pk_add_f32 v[28:29], v[28:29], v[30:31] op_sel:[0,1] op_sel_hi:[1,0] neg_hi:[0,1]
	v_pk_add_f32 v[30:31], v[98:99], v[72:73] neg_lo:[0,1] neg_hi:[0,1]
	v_pk_add_f32 v[74:75], v[106:107], v[104:105]
	v_pk_add_f32 v[78:79], v[96:97], v[94:95]
	v_pk_add_f32 v[86:87], v[98:99], v[72:73]
	v_pk_add_f32 v[90:91], v[108:109], v[88:89]
	v_pk_add_f32 v[88:89], v[30:31], v[32:33] op_sel:[0,1] op_sel_hi:[1,0] neg_lo:[0,1]
	v_pk_add_f32 v[30:31], v[30:31], v[32:33] op_sel:[0,1] op_sel_hi:[1,0] neg_hi:[0,1]
	v_pk_add_f32 v[92:93], v[110:111], v[114:115]
	v_pk_add_f32 v[32:33], v[110:111], v[114:115] neg_lo:[0,1] neg_hi:[0,1]
	v_pk_add_f32 v[96:97], v[112:113], v[116:117]
	v_pk_add_f32 v[72:73], v[112:113], v[116:117] neg_lo:[0,1] neg_hi:[0,1]
	v_pk_add_f32 v[100:101], v[74:75], v[78:79]
	v_pk_add_f32 v[102:103], v[80:81], v[84:85]
	v_pk_add_f32 v[104:105], v[86:87], v[90:91]
	v_pk_add_f32 v[98:99], v[92:93], v[96:97]
	v_pk_add_f32 v[94:95], v[32:33], v[72:73] op_sel:[0,1] op_sel_hi:[1,0] neg_lo:[0,1]
	v_pk_add_f32 v[32:33], v[32:33], v[72:73] op_sel:[0,1] op_sel_hi:[1,0] neg_hi:[0,1]
	v_mov_b32_e32 v72, v36
	v_mov_b32_e32 v73, v37
	s_and_saveexec_b64 s[0:1], s[4:5]
	s_xor_b64 s[0:1], exec, s[0:1]
	s_cbranch_execz .LBB0_1333
	v_pk_mul_f32 v[108:109], v[72:73], s[16:17] op_sel:[0,0] op_sel_hi:[0,1]
	v_pk_fma_f32 v[106:107], v[72:73], s[16:17], v[108:109] op_sel:[1,1,0] op_sel_hi:[1,0,1] neg_lo:[0,1,0]
	v_pk_mul_f32 v[108:109], v[100:101], v[106:107] op_sel:[0,0] op_sel_hi:[0,1] neg_hi:[0,1]
	v_pk_fma_f32 v[100:101], v[100:101], v[106:107], v[108:109] op_sel:[1,1,0] op_sel_hi:[1,0,1]
	v_pk_mul_f32 v[108:109], v[72:73], s[18:19] op_sel:[0,0] op_sel_hi:[0,1]
	v_pk_fma_f32 v[106:107], v[72:73], s[18:19], v[108:109] op_sel:[1,1,0] op_sel_hi:[1,0,1] neg_lo:[0,1,0]
	v_pk_mul_f32 v[108:109], v[102:103], v[106:107] op_sel:[0,0] op_sel_hi:[0,1] neg_hi:[0,1]
	v_pk_fma_f32 v[102:103], v[102:103], v[106:107], v[108:109] op_sel:[1,1,0] op_sel_hi:[1,0,1]
	v_pk_mul_f32 v[108:109], v[72:73], s[20:21] op_sel:[0,0] op_sel_hi:[0,1]
	v_pk_fma_f32 v[106:107], v[72:73], s[20:21], v[108:109] op_sel:[1,1,0] op_sel_hi:[1,0,1] neg_lo:[0,1,0]
	v_pk_mul_f32 v[108:109], v[104:105], v[106:107] op_sel:[0,0] op_sel_hi:[0,1] neg_hi:[0,1]
	v_pk_fma_f32 v[104:105], v[104:105], v[106:107], v[108:109] op_sel:[1,1,0] op_sel_hi:[1,0,1]
	v_pk_mul_f32 v[108:109], v[72:73], s[22:23] op_sel:[0,0] op_sel_hi:[0,1]
	v_pk_fma_f32 v[106:107], v[72:73], s[22:23], v[108:109] op_sel:[1,1,0] op_sel_hi:[1,0,1] neg_lo:[0,1,0]
	v_pk_mul_f32 v[108:109], v[98:99], v[106:107] op_sel:[0,0] op_sel_hi:[0,1] neg_hi:[0,1]
	v_pk_fma_f32 v[98:99], v[98:99], v[106:107], v[108:109] op_sel:[1,1,0] op_sel_hi:[1,0,1]
	ds_write_b64 v144, v[100:101]
	ds_write_b64 v144, v[102:103] offset:2176
	ds_write_b64 v144, v[104:105] offset:4352
	ds_write_b64 v144, v[98:99] offset:6528
	v_pk_mul_f32 v[100:101], v[72:73], s[50:51] op_sel:[0,0] op_sel_hi:[0,1]
	s_nop 0
	v_pk_fma_f32 v[98:99], v[72:73], s[50:51], v[100:101] op_sel:[1,1,0] op_sel_hi:[1,0,1] neg_lo:[0,1,0]
	v_pk_mul_f32 v[100:101], v[76:77], v[98:99] op_sel:[0,0] op_sel_hi:[0,1] neg_hi:[0,1]
	v_pk_fma_f32 v[76:77], v[76:77], v[98:99], v[100:101] op_sel:[1,1,0] op_sel_hi:[1,0,1]
	v_pk_mul_f32 v[100:101], v[72:73], s[52:53] op_sel:[0,0] op_sel_hi:[0,1]
	v_pk_fma_f32 v[98:99], v[72:73], s[52:53], v[100:101] op_sel:[1,1,0] op_sel_hi:[1,0,1] neg_lo:[0,1,0]
	v_pk_mul_f32 v[100:101], v[82:83], v[98:99] op_sel:[0,0] op_sel_hi:[0,1] neg_hi:[0,1]
	v_pk_fma_f32 v[82:83], v[82:83], v[98:99], v[100:101] op_sel:[1,1,0] op_sel_hi:[1,0,1]
	v_pk_mul_f32 v[100:101], v[72:73], s[54:55] op_sel:[0,0] op_sel_hi:[0,1]
	v_pk_fma_f32 v[98:99], v[72:73], s[54:55], v[100:101] op_sel:[1,1,0] op_sel_hi:[1,0,1] neg_lo:[0,1,0]
	v_pk_mul_f32 v[100:101], v[88:89], v[98:99] op_sel:[0,0] op_sel_hi:[0,1] neg_hi:[0,1]
	v_pk_fma_f32 v[88:89], v[88:89], v[98:99], v[100:101] op_sel:[1,1,0] op_sel_hi:[1,0,1]
	v_pk_mul_f32 v[100:101], v[72:73], s[56:57] op_sel:[0,0] op_sel_hi:[0,1]
	v_pk_fma_f32 v[98:99], v[72:73], s[56:57], v[100:101] op_sel:[1,1,0] op_sel_hi:[1,0,1] neg_lo:[0,1,0]
	v_pk_mul_f32 v[100:101], v[94:95], v[98:99] op_sel:[0,0] op_sel_hi:[0,1] neg_hi:[0,1]
	s_nop 0
	v_pk_fma_f32 v[94:95], v[94:95], v[98:99], v[100:101] op_sel:[1,1,0] op_sel_hi:[1,0,1]

.LBB0_1335:
	s_or_b64 exec, exec, s[0:1]
	v_pk_add_f32 v[98:99], v[74:75], v[78:79] neg_lo:[0,1] neg_hi:[0,1]
	v_pk_add_f32 v[80:81], v[80:81], v[84:85] neg_lo:[0,1] neg_hi:[0,1]
	v_pk_add_f32 v[78:79], v[86:87], v[90:91] neg_lo:[0,1] neg_hi:[0,1]
	v_pk_add_f32 v[74:75], v[92:93], v[96:97] neg_lo:[0,1] neg_hi:[0,1]
	ds_write_b64 v144, v[76:77] offset:8704
	ds_write_b64 v144, v[82:83] offset:10880
	ds_write_b64 v144, v[88:89] offset:13056
	ds_write_b64 v144, v[94:95] offset:15232
	s_and_saveexec_b64 s[0:1], s[4:5]
	s_xor_b64 s[0:1], exec, s[0:1]
	s_cbranch_execz .LBB0_1337
	v_pk_mul_f32 v[82:83], v[72:73], s[14:15] op_sel:[0,0] op_sel_hi:[0,1]
	s_mov_b32 s6, s19
	v_pk_fma_f32 v[76:77], v[72:73], s[14:15], v[82:83] op_sel:[1,1,0] op_sel_hi:[1,0,1] neg_lo:[0,1,0]
	s_mov_b32 s7, s57
	v_pk_mul_f32 v[82:83], v[98:99], v[76:77] op_sel:[0,0] op_sel_hi:[0,1] neg_hi:[0,1]
	v_pk_fma_f32 v[76:77], v[98:99], v[76:77], v[82:83] op_sel:[1,1,0] op_sel_hi:[1,0,1]
	v_mov_b64_e32 v[82:83], s[6:7]
	v_pk_mul_f32 v[84:85], v[72:73], v[82:83] op_sel:[0,0] op_sel_hi:[0,1]
	s_mov_b32 s6, s21
	v_pk_fma_f32 v[82:83], v[72:73], v[82:83], v[84:85] op_sel:[1,1,0] op_sel_hi:[1,0,1] neg_lo:[0,1,0]
	s_mov_b32 s7, s55
	v_pk_mul_f32 v[84:85], v[80:81], v[82:83] op_sel:[0,0] op_sel_hi:[0,1] neg_hi:[0,1]
	s_nop 0
	v_pk_fma_f32 v[80:81], v[80:81], v[82:83], v[84:85] op_sel:[1,1,0] op_sel_hi:[1,0,1]
	v_mov_b64_e32 v[82:83], s[6:7]
	v_pk_mul_f32 v[84:85], v[72:73], v[82:83] op_sel:[0,0] op_sel_hi:[0,1]
	s_mov_b32 s6, s23
	v_pk_fma_f32 v[82:83], v[72:73], v[82:83], v[84:85] op_sel:[1,1,0] op_sel_hi:[1,0,1] neg_lo:[0,1,0]
	s_mov_b32 s7, s53
	v_pk_mul_f32 v[84:85], v[78:79], v[82:83] op_sel:[0,0] op_sel_hi:[0,1] neg_hi:[0,1]
	v_pk_fma_f32 v[78:79], v[78:79], v[82:83], v[84:85] op_sel:[1,1,0] op_sel_hi:[1,0,1]
	v_mov_b64_e32 v[82:83], s[6:7]
	v_pk_mul_f32 v[84:85], v[72:73], v[82:83] op_sel:[0,0] op_sel_hi:[0,1]
	s_mov_b32 s6, s53
	v_pk_fma_f32 v[82:83], v[72:73], v[82:83], v[84:85] op_sel:[1,1,0] op_sel_hi:[1,0,1] neg_lo:[0,1,0]
	s_mov_b32 s7, s23
	v_pk_mul_f32 v[84:85], v[74:75], v[82:83] op_sel:[0,0] op_sel_hi:[0,1] neg_hi:[0,1]
	v_pk_fma_f32 v[74:75], v[74:75], v[82:83], v[84:85] op_sel:[1,1,0] op_sel_hi:[1,0,1]
	ds_write_b64 v144, v[76:77] offset:17408
	ds_write_b64 v144, v[80:81] offset:19584
	ds_write_b64 v144, v[78:79] offset:21760
	ds_write_b64 v144, v[74:75] offset:23936
	v_pk_mul_f32 v[76:77], v[72:73], s[58:59] op_sel:[0,0] op_sel_hi:[0,1]
	s_nop 0
	v_pk_fma_f32 v[74:75], v[72:73], s[58:59], v[76:77] op_sel:[1,1,0] op_sel_hi:[1,0,1] neg_lo:[0,1,0]
	v_pk_mul_f32 v[76:77], v[26:27], v[74:75] op_sel:[0,0] op_sel_hi:[0,1] neg_hi:[0,1]
	v_pk_fma_f32 v[26:27], v[26:27], v[74:75], v[76:77] op_sel:[1,1,0] op_sel_hi:[1,0,1]
	v_mov_b64_e32 v[74:75], s[6:7]
	v_pk_mul_f32 v[76:77], v[72:73], v[74:75] op_sel:[0,0] op_sel_hi:[0,1]
	s_mov_b32 s6, s57
	v_pk_fma_f32 v[74:75], v[72:73], v[74:75], v[76:77] op_sel:[1,1,0] op_sel_hi:[1,0,1] neg_lo:[0,1,0]
	s_mov_b32 s7, s19
	v_pk_mul_f32 v[76:77], v[28:29], v[74:75] op_sel:[0,0] op_sel_hi:[0,1] neg_hi:[0,1]
	v_pk_fma_f32 v[28:29], v[28:29], v[74:75], v[76:77] op_sel:[1,1,0] op_sel_hi:[1,0,1]
	v_pk_mul_f32 v[76:77], v[72:73], s[72:73] op_sel:[0,0] op_sel_hi:[0,1]
	v_pk_fma_f32 v[74:75], v[72:73], s[72:73], v[76:77] op_sel:[1,1,0] op_sel_hi:[1,0,1] neg_lo:[0,1,0]
	v_pk_mul_f32 v[76:77], v[30:31], v[74:75] op_sel:[0,0] op_sel_hi:[0,1] neg_hi:[0,1]
	v_pk_fma_f32 v[30:31], v[30:31], v[74:75], v[76:77] op_sel:[1,1,0] op_sel_hi:[1,0,1]
	v_pk_mul_f32 v[76:77], v[72:73], s[6:7] op_sel:[0,0] op_sel_hi:[0,1]
	v_pk_fma_f32 v[72:73], v[72:73], s[6:7], v[76:77] op_sel:[1,1,0] op_sel_hi:[1,0,1] neg_lo:[0,1,0]
	v_pk_mul_f32 v[74:75], v[32:33], v[72:73] op_sel:[0,0] op_sel_hi:[0,1] neg_hi:[0,1]
	s_nop 0
	v_pk_fma_f32 v[32:33], v[32:33], v[72:73], v[74:75] op_sel:[1,1,0] op_sel_hi:[1,0,1]

.LBB0_1340:
	v_add_u32_e32 v51, 0, v45
	ds_read_b64 v[74:75], v51
	v_add_u32_e32 v51, 0, v47
	ds_read_b64 v[76:77], v51
	v_add_u32_e32 v51, s80, v140
	v_cmp_lt_i32_e32 vcc, 0, v51
	v_add_u32_e32 v59, 0, v49
	v_add_u32_e32 v53, 0, v43
	v_subbrev_co_u32_e64 v55, s[0:1], 0, v51, vcc
	v_lshl_add_u32 v55, v55, 1, 0
	v_add_u32_e32 v57, 0x15400, v55
	v_add_u32_e32 v61, 0x15400, v59
	v_cmp_gt_i32_e64 s[0:1], s3, v51
	v_add_u32_e32 v51, 0x17400, v55
	s_waitcnt lgkmcnt(0)
	v_pk_add_f32 v[74:75], v[74:75], v[76:77]
	ds_read_b64 v[76:77], v53
	v_add_u32_e32 v55, 0x17400, v59
	ds_read_b32 v59, v61
	ds_read_u16 v51, v51
	ds_read_u16 v57, v57
	s_addk_i32 s80, 0x100
	v_add_u32_e32 v49, 0x200, v49
	s_waitcnt lgkmcnt(3)
	v_pk_fma_f32 v[74:75], v[72:73], v[76:77], v[74:75]
	s_waitcnt lgkmcnt(1)
	v_lshlrev_b32_e32 v51, 16, v51
	v_cndmask_b32_e32 v77, 0, v51, vcc
	ds_read_b32 v51, v55
	s_waitcnt lgkmcnt(1)
	v_lshlrev_b32_e32 v57, 16, v57
	v_lshlrev_b32_e32 v78, 16, v59
	v_cndmask_b32_e32 v76, 0, v57, vcc
	v_and_b32_e32 v55, 0xffff0000, v59
	s_waitcnt lgkmcnt(0)
	v_lshlrev_b32_e32 v79, 16, v51
	v_pk_mul_f32 v[78:79], v[30:31], v[78:79]
	v_and_b32_e32 v51, 0xffff0000, v51
	v_pk_fma_f32 v[76:77], v[26:27], v[76:77], v[78:79]
	v_cndmask_b32_e64 v79, 0, v51, s[0:1]
	v_cndmask_b32_e64 v78, 0, v55, s[0:1]
	v_pk_fma_f32 v[76:77], v[32:33], v[78:79], v[76:77]
	v_add_u32_e32 v43, 0x800, v43
	v_pk_add_f32 v[76:77], v[28:29], v[76:77]
	v_add_u32_e32 v47, 0x880, v47
	v_pk_mul_f32 v[74:75], v[74:75], v[76:77]
	v_add_u32_e32 v45, 0x880, v45
	s_cmpk_eq_i32 s80, 0x800
	ds_write_b64 v53, v[74:75]
	s_cbranch_scc0 .LBB0_1340
	v_add_f32_e64 v26, |v34|, |v44|
	v_add_f32_e64 v26, v26, |v42|
	v_add_f32_e64 v26, v26, |v50|
	v_add_f32_e64 v26, v26, |v48|
	v_add_f32_e64 v26, v26, |v56|
	v_add_f32_e64 v26, v26, |v46|
	v_add_f32_e64 v26, v26, |v54|
	v_add_f32_e64 v26, v26, |v52|
	v_add_f32_e64 v26, v26, |v60|
	v_add_f32_e64 v26, v26, |v58|
	v_add_f32_e64 v26, v26, |v64|
	v_add_f32_e64 v26, v26, |v62|
	v_add_f32_e64 v26, v26, |v68|
	v_add_f32_e64 v26, v26, |v66|
	v_add_f32_e64 v26, v26, |v70|
	ds_bpermute_b32 v27, v132, v26
	v_mov_b32_e32 v45, v35
	v_mov_b32_e32 v43, v35
	v_mov_b32_e32 v51, v35
	v_mov_b32_e32 v49, v35
	s_waitcnt lgkmcnt(0)
	v_add_f32_e32 v26, v26, v27
	ds_bpermute_b32 v27, v133, v26
	v_mov_b32_e32 v57, v35
	v_mov_b32_e32 v47, v35
	v_mov_b32_e32 v55, v35
	v_mov_b32_e32 v53, v35
	s_waitcnt lgkmcnt(0)
	v_add_f32_e32 v26, v26, v27
	ds_bpermute_b32 v27, v134, v26
	v_mov_b32_e32 v61, v35
	v_mov_b32_e32 v59, v35
	v_mov_b32_e32 v65, v35
	v_mov_b32_e32 v63, v35
	s_waitcnt lgkmcnt(0)
	v_add_f32_e32 v26, v26, v27
	ds_bpermute_b32 v27, v135, v26
	v_mov_b32_e32 v69, v35
	v_mov_b32_e32 v67, v35
	v_mov_b32_e32 v71, v35
	v_mov_b32_e32 v28, v0
	s_waitcnt lgkmcnt(0)
	v_add_f32_e32 v26, v26, v27
	ds_bpermute_b32 v27, v136, v26
	s_waitcnt lgkmcnt(0)
	s_barrier
	ds_write_b64 v144, v[34:35]
	v_add_f32_e32 v26, v26, v27
	ds_bpermute_b32 v27, v137, v26
	ds_write_b64 v144, v[44:45] offset:2176
	ds_write_b64 v144, v[42:43] offset:4352
	ds_write_b64 v144, v[50:51] offset:6528
	ds_write_b64 v144, v[48:49] offset:8704
	ds_write_b64 v144, v[56:57] offset:10880
	ds_write_b64 v144, v[46:47] offset:13056
	ds_write_b64 v144, v[54:55] offset:15232
	ds_write_b64 v144, v[52:53] offset:17408
	ds_write_b64 v144, v[60:61] offset:19584
	ds_write_b64 v144, v[58:59] offset:21760
	ds_write_b64 v144, v[64:65] offset:23936
	ds_write_b64 v144, v[62:63] offset:26112
	ds_write_b64 v144, v[68:69] offset:28288
	ds_write_b64 v144, v[66:67] offset:30464
	ds_write_b64 v144, v[70:71] offset:32640
	s_waitcnt lgkmcnt(0)
	s_barrier
	s_nop 0
	v_and_b32_e32 v29, 63, v28
	v_cmp_eq_u32_e32 vcc, 0, v29
	s_and_saveexec_b64 s[0:1], vcc
	v_add_f32_e32 v26, v26, v27
	v_ashrrev_i32_e32 v27, 4, v28
	v_add_u32_e32 v27, 0, v27
	v_add_u32_e32 v27, 0x11000, v27
	ds_write_b32 v27, v26
	s_or_b64 exec, exec, s[0:1]
	v_mov_b32_e32 v26, s86
	v_mov_b32_e32 v45, v37
	v_mov_b32_e32 v44, v36
	s_waitcnt lgkmcnt(0)
	s_barrier
	ds_read_b128 v[30:33], v26
	ds_read_b128 v[26:29], v26 offset:16
	ds_read_b64 v[46:47], v144
	ds_read_b64 v[48:49], v149
	s_and_saveexec_b64 s[0:1], s[4:5]
	s_xor_b64 s[0:1], exec, s[0:1]
	s_cbranch_execz .LBB0_1345
	v_pk_mul_f32 v[50:51], v[44:45], s[16:17] op_sel:[0,0] op_sel_hi:[0,1]
	s_waitcnt lgkmcnt(0)
	v_sub_f32_e32 v34, v48, v46
	v_pk_fma_f32 v[42:43], v[44:45], s[16:17], v[50:51] op_sel:[1,1,0] op_sel_hi:[1,0,1] neg_lo:[0,1,0]
	s_nop 0
	v_pk_mul_f32 v[42:43], v[34:35], v[42:43] op_sel_hi:[0,1]

.LBB0_1347:
	s_or_b64 exec, exec, s[0:1]
	s_waitcnt lgkmcnt(0)
	ds_read_b64 v[48:49], v144 offset:2176
	ds_read_b64 v[50:51], v149 offset:2176
	s_and_saveexec_b64 s[0:1], s[4:5]
	s_xor_b64 s[0:1], exec, s[0:1]
	s_cbranch_execz .LBB0_1349
	v_pk_mul_f32 v[52:53], v[44:45], s[18:19] op_sel:[0,0] op_sel_hi:[0,1]
	s_waitcnt lgkmcnt(0)
	v_sub_f32_e32 v34, v50, v48
	v_pk_fma_f32 v[46:47], v[44:45], s[18:19], v[52:53] op_sel:[1,1,0] op_sel_hi:[1,0,1] neg_lo:[0,1,0]
	s_nop 0
	v_pk_mul_f32 v[46:47], v[34:35], v[46:47] op_sel_hi:[0,1]

.LBB0_1351:
	s_or_b64 exec, exec, s[0:1]
	s_waitcnt lgkmcnt(0)
	ds_read_b64 v[50:51], v144 offset:4352
	ds_read_b64 v[52:53], v149 offset:4352
	s_and_saveexec_b64 s[0:1], s[4:5]
	s_xor_b64 s[0:1], exec, s[0:1]
	s_cbranch_execz .LBB0_1353
	v_pk_mul_f32 v[54:55], v[44:45], s[20:21] op_sel:[0,0] op_sel_hi:[0,1]
	s_waitcnt lgkmcnt(0)
	v_sub_f32_e32 v34, v52, v50
	v_pk_fma_f32 v[48:49], v[44:45], s[20:21], v[54:55] op_sel:[1,1,0] op_sel_hi:[1,0,1] neg_lo:[0,1,0]
	s_nop 0
	v_pk_mul_f32 v[48:49], v[34:35], v[48:49] op_sel_hi:[0,1]

.LBB0_1355:
	s_or_b64 exec, exec, s[0:1]
	s_waitcnt lgkmcnt(0)
	ds_read_b64 v[52:53], v144 offset:6528
	ds_read_b64 v[54:55], v149 offset:6528
	s_and_saveexec_b64 s[0:1], s[4:5]
	s_xor_b64 s[0:1], exec, s[0:1]
	s_cbranch_execz .LBB0_1357
	v_pk_mul_f32 v[56:57], v[44:45], s[22:23] op_sel:[0,0] op_sel_hi:[0,1]
	s_waitcnt lgkmcnt(0)
	v_sub_f32_e32 v34, v54, v52
	v_pk_fma_f32 v[50:51], v[44:45], s[22:23], v[56:57] op_sel:[1,1,0] op_sel_hi:[1,0,1] neg_lo:[0,1,0]
	s_nop 0
	v_pk_mul_f32 v[50:51], v[34:35], v[50:51] op_sel_hi:[0,1]

.LBB0_1359:
	s_or_b64 exec, exec, s[0:1]
	s_waitcnt lgkmcnt(0)
	ds_read_b64 v[54:55], v144 offset:8704
	ds_read_b64 v[56:57], v149 offset:8704
	s_and_saveexec_b64 s[0:1], s[4:5]
	s_xor_b64 s[0:1], exec, s[0:1]
	s_cbranch_execz .LBB0_1361
	v_pk_mul_f32 v[58:59], v[44:45], s[50:51] op_sel:[0,0] op_sel_hi:[0,1]
	s_waitcnt lgkmcnt(0)
	v_sub_f32_e32 v34, v56, v54
	v_pk_fma_f32 v[52:53], v[44:45], s[50:51], v[58:59] op_sel:[1,1,0] op_sel_hi:[1,0,1] neg_lo:[0,1,0]
	s_nop 0
	v_pk_mul_f32 v[52:53], v[34:35], v[52:53] op_sel_hi:[0,1]

.LBB0_1363:
	s_or_b64 exec, exec, s[0:1]
	s_waitcnt lgkmcnt(0)
	ds_read_b64 v[56:57], v144 offset:10880
	ds_read_b64 v[58:59], v149 offset:10880
	s_and_saveexec_b64 s[0:1], s[4:5]
	s_xor_b64 s[0:1], exec, s[0:1]
	s_cbranch_execz .LBB0_1365
	v_pk_mul_f32 v[60:61], v[44:45], s[52:53] op_sel:[0,0] op_sel_hi:[0,1]
	s_waitcnt lgkmcnt(0)
	v_sub_f32_e32 v34, v58, v56
	v_pk_fma_f32 v[54:55], v[44:45], s[52:53], v[60:61] op_sel:[1,1,0] op_sel_hi:[1,0,1] neg_lo:[0,1,0]
	s_nop 0
	v_pk_mul_f32 v[54:55], v[34:35], v[54:55] op_sel_hi:[0,1]

.LBB0_1367:
	s_or_b64 exec, exec, s[0:1]
	s_waitcnt lgkmcnt(0)
	ds_read_b64 v[58:59], v144 offset:13056
	ds_read_b64 v[60:61], v149 offset:13056
	s_and_saveexec_b64 s[0:1], s[4:5]
	s_xor_b64 s[0:1], exec, s[0:1]
	s_cbranch_execz .LBB0_1369
	v_pk_mul_f32 v[62:63], v[44:45], s[54:55] op_sel:[0,0] op_sel_hi:[0,1]
	s_waitcnt lgkmcnt(0)
	v_sub_f32_e32 v34, v60, v58
	v_pk_fma_f32 v[56:57], v[44:45], s[54:55], v[62:63] op_sel:[1,1,0] op_sel_hi:[1,0,1] neg_lo:[0,1,0]
	s_nop 0
	v_pk_mul_f32 v[56:57], v[34:35], v[56:57] op_sel_hi:[0,1]

.LBB0_1371:
	s_or_b64 exec, exec, s[0:1]
	s_waitcnt lgkmcnt(0)
	ds_read_b64 v[60:61], v144 offset:15232
	ds_read_b64 v[62:63], v149 offset:15232
	s_and_saveexec_b64 s[0:1], s[4:5]
	s_xor_b64 s[0:1], exec, s[0:1]
	s_cbranch_execz .LBB0_1373
	v_pk_mul_f32 v[64:65], v[44:45], s[56:57] op_sel:[0,0] op_sel_hi:[0,1]
	s_waitcnt lgkmcnt(0)
	v_sub_f32_e32 v34, v62, v60
	v_pk_fma_f32 v[58:59], v[44:45], s[56:57], v[64:65] op_sel:[1,1,0] op_sel_hi:[1,0,1] neg_lo:[0,1,0]
	s_nop 0
	v_pk_mul_f32 v[58:59], v[34:35], v[58:59] op_sel_hi:[0,1]

.LBB0_1375:
	s_or_b64 exec, exec, s[0:1]
	s_waitcnt lgkmcnt(0)
	ds_read_b64 v[62:63], v144 offset:17408
	ds_read_b64 v[64:65], v149 offset:17408
	s_and_saveexec_b64 s[0:1], s[4:5]
	s_xor_b64 s[0:1], exec, s[0:1]
	s_cbranch_execz .LBB0_1377
	v_pk_mul_f32 v[66:67], v[44:45], s[14:15] op_sel:[0,0] op_sel_hi:[0,1]
	s_waitcnt lgkmcnt(0)
	v_sub_f32_e32 v34, v64, v62
	v_pk_fma_f32 v[60:61], v[44:45], s[14:15], v[66:67] op_sel:[1,1,0] op_sel_hi:[1,0,1] neg_lo:[0,1,0]
	s_nop 0
	v_pk_mul_f32 v[60:61], v[34:35], v[60:61] op_sel_hi:[0,1]

.LBB0_1379:
	s_or_b64 exec, exec, s[0:1]
	s_waitcnt lgkmcnt(0)
	ds_read_b64 v[64:65], v144 offset:19584
	ds_read_b64 v[66:67], v149 offset:19584
	s_and_saveexec_b64 s[0:1], s[4:5]
	s_xor_b64 s[0:1], exec, s[0:1]
	s_cbranch_execz .LBB0_1381
	s_mov_b32 s28, s19
	s_mov_b32 s29, s57
	v_pk_mul_f32 v[68:69], v[44:45], s[28:29] op_sel:[0,0] op_sel_hi:[0,1]
	s_waitcnt lgkmcnt(0)
	v_sub_f32_e32 v34, v66, v64
	v_pk_fma_f32 v[62:63], v[44:45], s[28:29], v[68:69] op_sel:[1,1,0] op_sel_hi:[1,0,1] neg_lo:[0,1,0]
	s_nop 0
	v_pk_mul_f32 v[62:63], v[34:35], v[62:63] op_sel_hi:[0,1]

.LBB0_1383:
	s_or_b64 exec, exec, s[0:1]
	s_waitcnt lgkmcnt(0)
	ds_read_b64 v[66:67], v144 offset:21760
	ds_read_b64 v[68:69], v149 offset:21760
	s_and_saveexec_b64 s[0:1], s[4:5]
	s_xor_b64 s[0:1], exec, s[0:1]
	s_cbranch_execz .LBB0_1385
	s_mov_b32 s28, s21
	s_mov_b32 s29, s55
	v_pk_mul_f32 v[70:71], v[44:45], s[28:29] op_sel:[0,0] op_sel_hi:[0,1]
	s_waitcnt lgkmcnt(0)
	v_sub_f32_e32 v34, v68, v66
	v_pk_fma_f32 v[64:65], v[44:45], s[28:29], v[70:71] op_sel:[1,1,0] op_sel_hi:[1,0,1] neg_lo:[0,1,0]
	s_nop 0
	v_pk_mul_f32 v[64:65], v[34:35], v[64:65] op_sel_hi:[0,1]

.LBB0_1387:
	s_or_b64 exec, exec, s[0:1]
	s_waitcnt lgkmcnt(0)
	ds_read_b64 v[68:69], v144 offset:23936
	ds_read_b64 v[70:71], v149 offset:23936
	s_and_saveexec_b64 s[0:1], s[4:5]
	s_xor_b64 s[0:1], exec, s[0:1]
	s_cbranch_execz .LBB0_1389
	s_mov_b32 s28, s23
	s_mov_b32 s29, s53
	v_pk_mul_f32 v[72:73], v[44:45], s[28:29] op_sel:[0,0] op_sel_hi:[0,1]
	s_waitcnt lgkmcnt(0)
	v_sub_f32_e32 v34, v70, v68
	v_pk_fma_f32 v[66:67], v[44:45], s[28:29], v[72:73] op_sel:[1,1,0] op_sel_hi:[1,0,1] neg_lo:[0,1,0]
	s_nop 0
	v_pk_mul_f32 v[66:67], v[34:35], v[66:67] op_sel_hi:[0,1]

.LBB0_1391:
	s_or_b64 exec, exec, s[0:1]
	s_waitcnt lgkmcnt(0)
	ds_read_b64 v[70:71], v144 offset:26112
	ds_read_b64 v[72:73], v149 offset:26112
	s_and_saveexec_b64 s[0:1], s[4:5]
	s_xor_b64 s[0:1], exec, s[0:1]
	s_cbranch_execz .LBB0_1393
	v_pk_mul_f32 v[74:75], v[44:45], s[58:59] op_sel:[0,0] op_sel_hi:[0,1]
	s_waitcnt lgkmcnt(0)
	v_sub_f32_e32 v34, v72, v70
	v_pk_fma_f32 v[68:69], v[44:45], s[58:59], v[74:75] op_sel:[1,1,0] op_sel_hi:[1,0,1] neg_lo:[0,1,0]
	s_nop 0
	v_pk_mul_f32 v[68:69], v[34:35], v[68:69] op_sel_hi:[0,1]

.LBB0_1395:
	s_or_b64 exec, exec, s[0:1]
	s_waitcnt lgkmcnt(0)
	ds_read_b64 v[72:73], v144 offset:28288
	ds_read_b64 v[74:75], v149 offset:28288
	s_and_saveexec_b64 s[0:1], s[4:5]
	s_xor_b64 s[0:1], exec, s[0:1]
	s_cbranch_execz .LBB0_1397
	s_mov_b32 s28, s53
	s_mov_b32 s29, s23
	v_pk_mul_f32 v[76:77], v[44:45], s[28:29] op_sel:[0,0] op_sel_hi:[0,1]
	s_waitcnt lgkmcnt(0)
	v_sub_f32_e32 v34, v74, v72
	v_pk_fma_f32 v[70:71], v[44:45], s[28:29], v[76:77] op_sel:[1,1,0] op_sel_hi:[1,0,1] neg_lo:[0,1,0]
	s_nop 0
	v_pk_mul_f32 v[70:71], v[34:35], v[70:71] op_sel_hi:[0,1]

.LBB0_1399:
	s_or_b64 exec, exec, s[0:1]
	s_waitcnt lgkmcnt(0)
	ds_read_b64 v[74:75], v144 offset:30464
	ds_read_b64 v[76:77], v149 offset:30464
	s_and_saveexec_b64 s[0:1], s[4:5]
	s_xor_b64 s[0:1], exec, s[0:1]
	s_cbranch_execz .LBB0_1401
	v_pk_mul_f32 v[78:79], v[44:45], s[72:73] op_sel:[0,0] op_sel_hi:[0,1]
	s_waitcnt lgkmcnt(0)
	v_sub_f32_e32 v34, v76, v74
	v_pk_fma_f32 v[72:73], v[44:45], s[72:73], v[78:79] op_sel:[1,1,0] op_sel_hi:[1,0,1] neg_lo:[0,1,0]
	s_nop 0
	v_pk_mul_f32 v[72:73], v[34:35], v[72:73] op_sel_hi:[0,1]

.LBB0_1403:
	s_or_b64 exec, exec, s[0:1]
	s_waitcnt lgkmcnt(0)
	ds_read_b64 v[76:77], v144 offset:32640
	ds_read_b64 v[78:79], v149 offset:32640
	s_and_saveexec_b64 s[0:1], s[4:5]
	s_xor_b64 s[0:1], exec, s[0:1]
	s_cbranch_execz .LBB0_1405
	s_mov_b32 s28, s57
	s_mov_b32 s29, s19
	s_waitcnt lgkmcnt(0)
	v_sub_f32_e32 v34, v78, v76
	v_pk_mul_f32 v[80:81], v[44:45], s[28:29] op_sel:[0,0] op_sel_hi:[0,1]
	s_nop 0
	v_pk_fma_f32 v[44:45], v[44:45], s[28:29], v[80:81] op_sel:[1,1,0] op_sel_hi:[1,0,1] neg_lo:[0,1,0]
	s_nop 0
	v_pk_mul_f32 v[74:75], v[34:35], v[44:45] op_sel_hi:[0,1]

.LBB0_1407:
	s_or_b64 exec, exec, s[0:1]
	v_pk_add_f32 v[44:45], v[42:43], v[60:61]
	v_pk_add_f32 v[42:43], v[42:43], v[60:61] neg_lo:[0,1] neg_hi:[0,1]
	v_pk_add_f32 v[60:61], v[52:53], v[68:69]
	v_pk_add_f32 v[52:53], v[52:53], v[68:69] neg_lo:[0,1] neg_hi:[0,1]
	v_pk_add_f32 v[68:69], v[44:45], v[60:61]
	v_pk_add_f32 v[60:61], v[44:45], v[60:61] neg_lo:[0,1] neg_hi:[0,1]
	s_waitcnt lgkmcnt(1)
	v_pk_add_f32 v[76:77], v[42:43], v[52:53] op_sel:[0,1] op_sel_hi:[1,0] neg_hi:[0,1]
	s_waitcnt lgkmcnt(0)
	v_pk_add_f32 v[78:79], v[42:43], v[52:53] op_sel:[0,1] op_sel_hi:[1,0] neg_lo:[0,1]
	v_pk_add_f32 v[42:43], v[46:47], v[62:63]
	v_pk_add_f32 v[44:45], v[46:47], v[62:63] neg_lo:[0,1] neg_hi:[0,1]
	v_pk_add_f32 v[46:47], v[54:55], v[70:71]
	v_pk_add_f32 v[52:53], v[54:55], v[70:71] neg_lo:[0,1] neg_hi:[0,1]
	v_pk_add_f32 v[54:55], v[42:43], v[46:47]
	v_pk_add_f32 v[46:47], v[42:43], v[46:47] neg_lo:[0,1] neg_hi:[0,1]
	v_pk_add_f32 v[42:43], v[44:45], v[52:53] op_sel:[0,1] op_sel_hi:[1,0] neg_hi:[0,1]
	v_pk_add_f32 v[52:53], v[44:45], v[52:53] op_sel:[0,1] op_sel_hi:[1,0] neg_lo:[0,1]
	v_pk_add_f32 v[44:45], v[48:49], v[64:65]
	v_pk_add_f32 v[48:49], v[48:49], v[64:65] neg_lo:[0,1] neg_hi:[0,1]
	v_pk_add_f32 v[62:63], v[56:57], v[72:73]
	v_pk_add_f32 v[56:57], v[56:57], v[72:73] neg_lo:[0,1] neg_hi:[0,1]
	v_pk_add_f32 v[64:65], v[44:45], v[62:63]
	v_pk_add_f32 v[62:63], v[44:45], v[62:63] neg_lo:[0,1] neg_hi:[0,1]
	v_pk_add_f32 v[70:71], v[48:49], v[56:57] op_sel:[0,1] op_sel_hi:[1,0] neg_hi:[0,1]
	v_pk_add_f32 v[56:57], v[48:49], v[56:57] op_sel:[0,1] op_sel_hi:[1,0] neg_lo:[0,1]
	v_pk_add_f32 v[44:45], v[50:51], v[66:67]
	v_pk_add_f32 v[48:49], v[50:51], v[66:67] neg_lo:[0,1] neg_hi:[0,1]
	v_pk_add_f32 v[50:51], v[58:59], v[74:75]
	v_pk_add_f32 v[58:59], v[58:59], v[74:75] neg_lo:[0,1] neg_hi:[0,1]
	v_pk_add_f32 v[66:67], v[44:45], v[50:51]
	v_pk_add_f32 v[72:73], v[44:45], v[50:51] neg_lo:[0,1] neg_hi:[0,1]
	v_pk_add_f32 v[50:51], v[48:49], v[58:59] op_sel:[0,1] op_sel_hi:[1,0] neg_hi:[0,1]
	v_pk_add_f32 v[58:59], v[48:49], v[58:59] op_sel:[0,1] op_sel_hi:[1,0] neg_lo:[0,1]
	v_pk_mul_f32 v[44:45], v[42:43], s[20:21] op_sel:[0,0] op_sel_hi:[0,1]
	v_pk_fma_f32 v[74:75], v[42:43], s[20:21], v[44:45] op_sel:[1,1,0] op_sel_hi:[1,0,1] neg_lo:[0,1,0]
	v_pk_mul_f32 v[42:43], v[70:71], s[50:51] op_sel:[0,0] op_sel_hi:[0,1]
	s_barrier
	v_pk_fma_f32 v[70:71], v[70:71], s[50:51], v[42:43] op_sel:[1,1,0] op_sel_hi:[1,0,1] neg_lo:[0,1,0]
	v_pk_mul_f32 v[80:81], v[50:51], s[54:55] op_sel:[0,0] op_sel_hi:[0,1]
	v_pk_fma_f32 v[80:81], v[50:51], s[54:55], v[80:81] op_sel:[1,1,0] op_sel_hi:[1,0,1] neg_lo:[0,1,0]
	v_pk_mul_f32 v[50:51], v[46:47], s[50:51] op_sel:[0,0] op_sel_hi:[0,1]
	s_mov_b32 s28, 0
	v_pk_fma_f32 v[82:83], v[46:47], s[50:51], v[50:51] op_sel:[1,1,0] op_sel_hi:[1,0,1] neg_lo:[0,1,0]
	v_pk_mul_f32 v[46:47], v[62:63], s[14:15] op_sel:[0,0] op_sel_hi:[0,1]
	v_mov_b32_e32 v34, v144
	v_pk_fma_f32 v[62:63], v[62:63], s[14:15], v[46:47] op_sel:[1,1,0] op_sel_hi:[1,0,1] neg_lo:[0,1,0]
	v_pk_mul_f32 v[84:85], v[72:73], s[58:59] op_sel:[0,0] op_sel_hi:[0,1]
	v_pk_fma_f32 v[72:73], v[72:73], s[58:59], v[84:85] op_sel:[1,1,0] op_sel_hi:[1,0,1] neg_lo:[0,1,0]
	v_pk_mul_f32 v[84:85], v[52:53], s[54:55] op_sel:[0,0] op_sel_hi:[0,1]
	v_pk_fma_f32 v[84:85], v[52:53], s[54:55], v[84:85] op_sel:[1,1,0] op_sel_hi:[1,0,1] neg_lo:[0,1,0]
	v_pk_mul_f32 v[52:53], v[56:57], s[58:59] op_sel:[0,0] op_sel_hi:[0,1]
	v_pk_fma_f32 v[56:57], v[56:57], s[58:59], v[52:53] op_sel:[1,1,0] op_sel_hi:[1,0,1] neg_lo:[0,1,0]
	v_pk_mul_f32 v[86:87], v[58:59], s[60:61] op_sel:[0,0] op_sel_hi:[0,1]
	v_pk_fma_f32 v[58:59], v[58:59], s[60:61], v[86:87] op_sel:[1,1,0] op_sel_hi:[1,0,1] neg_lo:[0,1,0]
	v_pk_add_f32 v[86:87], v[68:69], v[64:65]
	v_pk_add_f32 v[64:65], v[68:69], v[64:65] neg_lo:[0,1] neg_hi:[0,1]
	v_pk_add_f32 v[68:69], v[54:55], v[66:67]
	v_pk_add_f32 v[54:55], v[54:55], v[66:67] neg_lo:[0,1] neg_hi:[0,1]
	v_pk_add_f32 v[66:67], v[86:87], v[68:69]
	v_pk_add_f32 v[68:69], v[86:87], v[68:69] neg_lo:[0,1] neg_hi:[0,1]
	v_pk_add_f32 v[86:87], v[64:65], v[54:55] op_sel:[0,1] op_sel_hi:[1,0] neg_hi:[0,1]
	v_pk_add_f32 v[54:55], v[64:65], v[54:55] op_sel:[0,1] op_sel_hi:[1,0] neg_lo:[0,1]
	v_pk_add_f32 v[64:65], v[76:77], v[70:71]
	v_pk_add_f32 v[70:71], v[76:77], v[70:71] neg_lo:[0,1] neg_hi:[0,1]
	v_pk_add_f32 v[76:77], v[74:75], v[80:81]
	v_pk_add_f32 v[74:75], v[74:75], v[80:81] neg_lo:[0,1] neg_hi:[0,1]
	v_pk_add_f32 v[80:81], v[64:65], v[76:77]
	v_pk_add_f32 v[64:65], v[64:65], v[76:77] neg_lo:[0,1] neg_hi:[0,1]
	v_pk_add_f32 v[76:77], v[70:71], v[74:75] op_sel:[0,1] op_sel_hi:[1,0] neg_hi:[0,1]
	v_pk_add_f32 v[70:71], v[70:71], v[74:75] op_sel:[0,1] op_sel_hi:[1,0] neg_lo:[0,1]
	v_pk_add_f32 v[74:75], v[60:61], v[62:63]
	v_pk_add_f32 v[60:61], v[60:61], v[62:63] neg_lo:[0,1] neg_hi:[0,1]
	v_pk_add_f32 v[62:63], v[82:83], v[72:73]
	v_pk_add_f32 v[72:73], v[82:83], v[72:73] neg_lo:[0,1] neg_hi:[0,1]
	v_pk_add_f32 v[82:83], v[74:75], v[62:63]
	v_pk_add_f32 v[62:63], v[74:75], v[62:63] neg_lo:[0,1] neg_hi:[0,1]
	v_pk_add_f32 v[74:75], v[60:61], v[72:73] op_sel:[0,1] op_sel_hi:[1,0] neg_hi:[0,1]
	v_pk_add_f32 v[60:61], v[60:61], v[72:73] op_sel:[0,1] op_sel_hi:[1,0] neg_lo:[0,1]
	v_pk_add_f32 v[72:73], v[78:79], v[56:57]
	v_pk_add_f32 v[56:57], v[78:79], v[56:57] neg_lo:[0,1] neg_hi:[0,1]
	v_pk_add_f32 v[78:79], v[84:85], v[58:59]
	v_pk_add_f32 v[58:59], v[84:85], v[58:59] neg_lo:[0,1] neg_hi:[0,1]
	v_pk_add_f32 v[84:85], v[72:73], v[78:79]
	v_pk_add_f32 v[72:73], v[72:73], v[78:79] neg_lo:[0,1] neg_hi:[0,1]
	v_pk_add_f32 v[78:79], v[56:57], v[58:59] op_sel:[0,1] op_sel_hi:[1,0] neg_hi:[0,1]
	v_pk_add_f32 v[56:57], v[56:57], v[58:59] op_sel:[0,1] op_sel_hi:[1,0] neg_lo:[0,1]
	v_mov_b32_e32 v59, v39
	v_mov_b32_e32 v58, v38
	ds_write_b64 v144, v[66:67]
	v_pk_mul_f32 v[66:67], v[80:81], v[58:59] op_sel:[0,0] op_sel_hi:[0,1]
	v_pk_fma_f32 v[66:67], v[80:81], v[58:59], v[66:67] op_sel:[1,1,0] op_sel_hi:[1,0,1] neg_lo:[0,1,0]
	ds_write_b64 v144, v[66:67] offset:2176
	v_pk_mul_f32 v[66:67], v[58:59], v[58:59] op_sel:[0,0] op_sel_hi:[0,1]
	v_pk_fma_f32 v[66:67], v[58:59], v[58:59], v[66:67] op_sel:[1,1,0] op_sel_hi:[1,0,1] neg_lo:[0,1,0]
	v_pk_mul_f32 v[80:81], v[82:83], v[66:67] op_sel:[0,0] op_sel_hi:[0,1]
	v_pk_fma_f32 v[80:81], v[82:83], v[66:67], v[80:81] op_sel:[1,1,0] op_sel_hi:[1,0,1] neg_lo:[0,1,0]
	ds_write_b64 v144, v[80:81] offset:4352
	v_pk_mul_f32 v[80:81], v[66:67], v[58:59] op_sel:[0,0] op_sel_hi:[0,1]
	v_pk_fma_f32 v[66:67], v[66:67], v[58:59], v[80:81] op_sel:[1,1,0] op_sel_hi:[1,0,1] neg_lo:[0,1,0]
	v_pk_mul_f32 v[80:81], v[84:85], v[66:67] op_sel:[0,0] op_sel_hi:[0,1]
	v_pk_fma_f32 v[80:81], v[84:85], v[66:67], v[80:81] op_sel:[1,1,0] op_sel_hi:[1,0,1] neg_lo:[0,1,0]
	ds_write_b64 v144, v[80:81] offset:6528
	v_pk_mul_f32 v[80:81], v[66:67], v[58:59] op_sel:[0,0] op_sel_hi:[0,1]
	v_pk_fma_f32 v[66:67], v[66:67], v[58:59], v[80:81] op_sel:[1,1,0] op_sel_hi:[1,0,1] neg_lo:[0,1,0]
	v_pk_mul_f32 v[80:81], v[86:87], v[66:67] op_sel:[0,0] op_sel_hi:[0,1]
	v_pk_fma_f32 v[80:81], v[86:87], v[66:67], v[80:81] op_sel:[1,1,0] op_sel_hi:[1,0,1] neg_lo:[0,1,0]
	ds_write_b64 v144, v[80:81] offset:8704
	v_pk_mul_f32 v[80:81], v[66:67], v[58:59] op_sel:[0,0] op_sel_hi:[0,1]
	v_pk_fma_f32 v[66:67], v[66:67], v[58:59], v[80:81] op_sel:[1,1,0] op_sel_hi:[1,0,1] neg_lo:[0,1,0]
	v_pk_mul_f32 v[80:81], v[76:77], v[66:67] op_sel:[0,0] op_sel_hi:[0,1]
	v_pk_fma_f32 v[76:77], v[76:77], v[66:67], v[80:81] op_sel:[1,1,0] op_sel_hi:[1,0,1] neg_lo:[0,1,0]
	ds_write_b64 v144, v[76:77] offset:10880
	v_pk_mul_f32 v[76:77], v[66:67], v[58:59] op_sel:[0,0] op_sel_hi:[0,1]
	v_pk_fma_f32 v[66:67], v[66:67], v[58:59], v[76:77] op_sel:[1,1,0] op_sel_hi:[1,0,1] neg_lo:[0,1,0]
	v_pk_mul_f32 v[76:77], v[74:75], v[66:67] op_sel:[0,0] op_sel_hi:[0,1]
	v_pk_fma_f32 v[74:75], v[74:75], v[66:67], v[76:77] op_sel:[1,1,0] op_sel_hi:[1,0,1] neg_lo:[0,1,0]
	ds_write_b64 v144, v[74:75] offset:13056
	v_pk_mul_f32 v[74:75], v[66:67], v[58:59] op_sel:[0,0] op_sel_hi:[0,1]
	v_pk_fma_f32 v[66:67], v[66:67], v[58:59], v[74:75] op_sel:[1,1,0] op_sel_hi:[1,0,1] neg_lo:[0,1,0]
	v_pk_mul_f32 v[74:75], v[78:79], v[66:67] op_sel:[0,0] op_sel_hi:[0,1]
	v_pk_fma_f32 v[74:75], v[78:79], v[66:67], v[74:75] op_sel:[1,1,0] op_sel_hi:[1,0,1] neg_lo:[0,1,0]
	ds_write_b64 v144, v[74:75] offset:15232
	v_pk_mul_f32 v[74:75], v[66:67], v[58:59] op_sel:[0,0] op_sel_hi:[0,1]
	v_pk_fma_f32 v[66:67], v[66:67], v[58:59], v[74:75] op_sel:[1,1,0] op_sel_hi:[1,0,1] neg_lo:[0,1,0]
	v_pk_mul_f32 v[74:75], v[68:69], v[66:67] op_sel:[0,0] op_sel_hi:[0,1]
	v_pk_fma_f32 v[68:69], v[68:69], v[66:67], v[74:75] op_sel:[1,1,0] op_sel_hi:[1,0,1] neg_lo:[0,1,0]
	ds_write_b64 v144, v[68:69] offset:17408
	v_pk_mul_f32 v[68:69], v[66:67], v[58:59] op_sel:[0,0] op_sel_hi:[0,1]
	v_pk_fma_f32 v[66:67], v[66:67], v[58:59], v[68:69] op_sel:[1,1,0] op_sel_hi:[1,0,1] neg_lo:[0,1,0]
	v_pk_mul_f32 v[68:69], v[64:65], v[66:67] op_sel:[0,0] op_sel_hi:[0,1]
	v_pk_fma_f32 v[64:65], v[64:65], v[66:67], v[68:69] op_sel:[1,1,0] op_sel_hi:[1,0,1] neg_lo:[0,1,0]
	ds_write_b64 v144, v[64:65] offset:19584
	v_pk_mul_f32 v[64:65], v[66:67], v[58:59] op_sel:[0,0] op_sel_hi:[0,1]
	v_pk_fma_f32 v[64:65], v[66:67], v[58:59], v[64:65] op_sel:[1,1,0] op_sel_hi:[1,0,1] neg_lo:[0,1,0]
	v_pk_mul_f32 v[66:67], v[62:63], v[64:65] op_sel:[0,0] op_sel_hi:[0,1]
	v_pk_fma_f32 v[62:63], v[62:63], v[64:65], v[66:67] op_sel:[1,1,0] op_sel_hi:[1,0,1] neg_lo:[0,1,0]
	ds_write_b64 v144, v[62:63] offset:21760
	v_pk_mul_f32 v[62:63], v[64:65], v[58:59] op_sel:[0,0] op_sel_hi:[0,1]
	v_pk_fma_f32 v[62:63], v[64:65], v[58:59], v[62:63] op_sel:[1,1,0] op_sel_hi:[1,0,1] neg_lo:[0,1,0]
	v_pk_mul_f32 v[64:65], v[72:73], v[62:63] op_sel:[0,0] op_sel_hi:[0,1]
	v_pk_fma_f32 v[64:65], v[72:73], v[62:63], v[64:65] op_sel:[1,1,0] op_sel_hi:[1,0,1] neg_lo:[0,1,0]
	ds_write_b64 v144, v[64:65] offset:23936
	v_pk_mul_f32 v[64:65], v[62:63], v[58:59] op_sel:[0,0] op_sel_hi:[0,1]
	v_pk_fma_f32 v[62:63], v[62:63], v[58:59], v[64:65] op_sel:[1,1,0] op_sel_hi:[1,0,1] neg_lo:[0,1,0]
	v_pk_mul_f32 v[64:65], v[54:55], v[62:63] op_sel:[0,0] op_sel_hi:[0,1]
	v_pk_fma_f32 v[54:55], v[54:55], v[62:63], v[64:65] op_sel:[1,1,0] op_sel_hi:[1,0,1] neg_lo:[0,1,0]
	ds_write_b64 v144, v[54:55] offset:26112
	v_pk_mul_f32 v[54:55], v[62:63], v[58:59] op_sel:[0,0] op_sel_hi:[0,1]
	v_pk_fma_f32 v[54:55], v[62:63], v[58:59], v[54:55] op_sel:[1,1,0] op_sel_hi:[1,0,1] neg_lo:[0,1,0]
	v_pk_mul_f32 v[62:63], v[70:71], v[54:55] op_sel:[0,0] op_sel_hi:[0,1]
	v_pk_fma_f32 v[62:63], v[70:71], v[54:55], v[62:63] op_sel:[1,1,0] op_sel_hi:[1,0,1] neg_lo:[0,1,0]
	ds_write_b64 v144, v[62:63] offset:28288
	v_pk_mul_f32 v[62:63], v[54:55], v[58:59] op_sel:[0,0] op_sel_hi:[0,1]
	v_pk_fma_f32 v[54:55], v[54:55], v[58:59], v[62:63] op_sel:[1,1,0] op_sel_hi:[1,0,1] neg_lo:[0,1,0]
	v_pk_mul_f32 v[62:63], v[60:61], v[54:55] op_sel:[0,0] op_sel_hi:[0,1]
	v_pk_fma_f32 v[60:61], v[60:61], v[54:55], v[62:63] op_sel:[1,1,0] op_sel_hi:[1,0,1] neg_lo:[0,1,0]
	ds_write_b64 v144, v[60:61] offset:30464
	v_pk_mul_f32 v[60:61], v[54:55], v[58:59] op_sel:[0,0] op_sel_hi:[0,1]
	v_pk_fma_f32 v[54:55], v[54:55], v[58:59], v[60:61] op_sel:[1,1,0] op_sel_hi:[1,0,1] neg_lo:[0,1,0]
	v_pk_mul_f32 v[58:59], v[56:57], v[54:55] op_sel:[0,0] op_sel_hi:[0,1]
	v_pk_fma_f32 v[54:55], v[56:57], v[54:55], v[58:59] op_sel:[1,1,0] op_sel_hi:[1,0,1] neg_lo:[0,1,0]
	ds_write_b64 v144, v[54:55] offset:32640
	s_waitcnt lgkmcnt(0)
	s_barrier
	ds_read2_b64 v[54:57], v146 offset1:17
	ds_read2_b64 v[58:61], v146 offset0:34 offset1:51
	ds_read2_b64 v[62:65], v146 offset0:68 offset1:85
	ds_read2_b64 v[66:69], v146 offset0:136 offset1:153
	ds_read2_b64 v[70:73], v146 offset0:102 offset1:119
	ds_read2_b64 v[74:77], v146 offset0:204 offset1:221
	ds_read2_b64 v[78:81], v146 offset0:170 offset1:187
	ds_read2_b64 v[82:85], v146 offset0:238 offset1:255
	s_waitcnt lgkmcnt(4)
	v_pk_add_f32 v[86:87], v[54:55], v[66:67]
	v_pk_add_f32 v[54:55], v[54:55], v[66:67] neg_lo:[0,1] neg_hi:[0,1]
	s_waitcnt lgkmcnt(2)
	v_pk_add_f32 v[66:67], v[62:63], v[74:75]
	v_pk_add_f32 v[62:63], v[62:63], v[74:75] neg_lo:[0,1] neg_hi:[0,1]
	v_pk_add_f32 v[74:75], v[86:87], v[66:67]
	v_pk_add_f32 v[66:67], v[86:87], v[66:67] neg_lo:[0,1] neg_hi:[0,1]
	v_pk_add_f32 v[86:87], v[54:55], v[62:63] op_sel:[0,1] op_sel_hi:[1,0] neg_hi:[0,1]
	v_pk_add_f32 v[54:55], v[54:55], v[62:63] op_sel:[0,1] op_sel_hi:[1,0] neg_lo:[0,1]
	v_pk_add_f32 v[62:63], v[56:57], v[68:69]
	v_pk_add_f32 v[56:57], v[56:57], v[68:69] neg_lo:[0,1] neg_hi:[0,1]
	v_pk_add_f32 v[68:69], v[64:65], v[76:77]
	v_pk_add_f32 v[64:65], v[64:65], v[76:77] neg_lo:[0,1] neg_hi:[0,1]
	v_pk_add_f32 v[76:77], v[62:63], v[68:69]
	v_pk_add_f32 v[62:63], v[62:63], v[68:69] neg_lo:[0,1] neg_hi:[0,1]
	v_pk_add_f32 v[68:69], v[56:57], v[64:65] op_sel:[0,1] op_sel_hi:[1,0] neg_hi:[0,1]
	v_pk_add_f32 v[56:57], v[56:57], v[64:65] op_sel:[0,1] op_sel_hi:[1,0] neg_lo:[0,1]
	s_waitcnt lgkmcnt(1)
	v_pk_add_f32 v[64:65], v[58:59], v[78:79]
	v_pk_add_f32 v[58:59], v[58:59], v[78:79] neg_lo:[0,1] neg_hi:[0,1]
	s_waitcnt lgkmcnt(0)
	v_pk_add_f32 v[78:79], v[70:71], v[82:83]
	v_pk_add_f32 v[70:71], v[70:71], v[82:83] neg_lo:[0,1] neg_hi:[0,1]
	v_pk_add_f32 v[82:83], v[64:65], v[78:79]
	v_pk_add_f32 v[64:65], v[64:65], v[78:79] neg_lo:[0,1] neg_hi:[0,1]
	v_pk_add_f32 v[78:79], v[58:59], v[70:71] op_sel:[0,1] op_sel_hi:[1,0] neg_hi:[0,1]
	v_pk_add_f32 v[58:59], v[58:59], v[70:71] op_sel:[0,1] op_sel_hi:[1,0] neg_lo:[0,1]
	v_pk_add_f32 v[70:71], v[60:61], v[80:81]
	v_pk_add_f32 v[60:61], v[60:61], v[80:81] neg_lo:[0,1] neg_hi:[0,1]
	v_pk_add_f32 v[80:81], v[72:73], v[84:85]
	v_pk_add_f32 v[72:73], v[72:73], v[84:85] neg_lo:[0,1] neg_hi:[0,1]
	v_pk_add_f32 v[84:85], v[70:71], v[80:81]
	v_pk_add_f32 v[70:71], v[70:71], v[80:81] neg_lo:[0,1] neg_hi:[0,1]
	v_pk_add_f32 v[80:81], v[60:61], v[72:73] op_sel:[0,1] op_sel_hi:[1,0] neg_hi:[0,1]
	v_pk_add_f32 v[60:61], v[60:61], v[72:73] op_sel:[0,1] op_sel_hi:[1,0] neg_lo:[0,1]
	v_pk_mul_f32 v[72:73], v[68:69], s[20:21] op_sel:[0,0] op_sel_hi:[0,1]
	v_pk_fma_f32 v[68:69], v[68:69], s[20:21], v[72:73] op_sel:[1,1,0] op_sel_hi:[1,0,1] neg_lo:[0,1,0]
	v_pk_mul_f32 v[72:73], v[78:79], s[50:51] op_sel:[0,0] op_sel_hi:[0,1]
	v_pk_fma_f32 v[72:73], v[78:79], s[50:51], v[72:73] op_sel:[1,1,0] op_sel_hi:[1,0,1] neg_lo:[0,1,0]
	v_pk_mul_f32 v[78:79], v[80:81], s[54:55] op_sel:[0,0] op_sel_hi:[0,1]
	v_pk_fma_f32 v[78:79], v[80:81], s[54:55], v[78:79] op_sel:[1,1,0] op_sel_hi:[1,0,1] neg_lo:[0,1,0]
	v_pk_mul_f32 v[80:81], v[62:63], s[50:51] op_sel:[0,0] op_sel_hi:[0,1]
	v_pk_fma_f32 v[62:63], v[62:63], s[50:51], v[80:81] op_sel:[1,1,0] op_sel_hi:[1,0,1] neg_lo:[0,1,0]
	v_pk_mul_f32 v[80:81], v[64:65], s[14:15] op_sel:[0,0] op_sel_hi:[0,1]
	v_pk_fma_f32 v[64:65], v[64:65], s[14:15], v[80:81] op_sel:[1,1,0] op_sel_hi:[1,0,1] neg_lo:[0,1,0]
	v_pk_mul_f32 v[80:81], v[70:71], s[58:59] op_sel:[0,0] op_sel_hi:[0,1]
	v_pk_fma_f32 v[70:71], v[70:71], s[58:59], v[80:81] op_sel:[1,1,0] op_sel_hi:[1,0,1] neg_lo:[0,1,0]
	v_pk_mul_f32 v[80:81], v[56:57], s[54:55] op_sel:[0,0] op_sel_hi:[0,1]
	v_pk_fma_f32 v[56:57], v[56:57], s[54:55], v[80:81] op_sel:[1,1,0] op_sel_hi:[1,0,1] neg_lo:[0,1,0]
	v_pk_mul_f32 v[80:81], v[58:59], s[58:59] op_sel:[0,0] op_sel_hi:[0,1]
	v_pk_fma_f32 v[58:59], v[58:59], s[58:59], v[80:81] op_sel:[1,1,0] op_sel_hi:[1,0,1] neg_lo:[0,1,0]
	v_pk_mul_f32 v[80:81], v[60:61], s[60:61] op_sel:[0,0] op_sel_hi:[0,1]
	v_pk_fma_f32 v[60:61], v[60:61], s[60:61], v[80:81] op_sel:[1,1,0] op_sel_hi:[1,0,1] neg_lo:[0,1,0]
	v_pk_add_f32 v[80:81], v[74:75], v[82:83]
	v_pk_add_f32 v[74:75], v[74:75], v[82:83] neg_lo:[0,1] neg_hi:[0,1]
	v_pk_add_f32 v[82:83], v[76:77], v[84:85]
	v_pk_add_f32 v[76:77], v[76:77], v[84:85] neg_lo:[0,1] neg_hi:[0,1]
	v_pk_add_f32 v[84:85], v[80:81], v[82:83]
	v_pk_add_f32 v[80:81], v[80:81], v[82:83] neg_lo:[0,1] neg_hi:[0,1]
	v_pk_add_f32 v[82:83], v[74:75], v[76:77] op_sel:[0,1] op_sel_hi:[1,0] neg_hi:[0,1]
	v_pk_add_f32 v[74:75], v[74:75], v[76:77] op_sel:[0,1] op_sel_hi:[1,0] neg_lo:[0,1]
	v_pk_add_f32 v[76:77], v[86:87], v[72:73]
	v_pk_add_f32 v[72:73], v[86:87], v[72:73] neg_lo:[0,1] neg_hi:[0,1]
	v_pk_add_f32 v[86:87], v[68:69], v[78:79]
	v_pk_add_f32 v[68:69], v[68:69], v[78:79] neg_lo:[0,1] neg_hi:[0,1]
	v_pk_add_f32 v[78:79], v[76:77], v[86:87]
	v_pk_add_f32 v[76:77], v[76:77], v[86:87] neg_lo:[0,1] neg_hi:[0,1]
	v_pk_add_f32 v[86:87], v[72:73], v[68:69] op_sel:[0,1] op_sel_hi:[1,0] neg_hi:[0,1]
	v_pk_add_f32 v[68:69], v[72:73], v[68:69] op_sel:[0,1] op_sel_hi:[1,0] neg_lo:[0,1]
	v_pk_add_f32 v[72:73], v[66:67], v[64:65]
	v_pk_add_f32 v[64:65], v[66:67], v[64:65] neg_lo:[0,1] neg_hi:[0,1]
	v_pk_add_f32 v[66:67], v[62:63], v[70:71]
	v_pk_add_f32 v[62:63], v[62:63], v[70:71] neg_lo:[0,1] neg_hi:[0,1]
	v_pk_add_f32 v[70:71], v[72:73], v[66:67]
	v_pk_add_f32 v[66:67], v[72:73], v[66:67] neg_lo:[0,1] neg_hi:[0,1]
	v_pk_add_f32 v[72:73], v[64:65], v[62:63] op_sel:[0,1] op_sel_hi:[1,0] neg_hi:[0,1]
	v_pk_add_f32 v[62:63], v[64:65], v[62:63] op_sel:[0,1] op_sel_hi:[1,0] neg_lo:[0,1]
	v_pk_add_f32 v[64:65], v[54:55], v[58:59]
	v_pk_add_f32 v[54:55], v[54:55], v[58:59] neg_lo:[0,1] neg_hi:[0,1]
	v_pk_add_f32 v[58:59], v[56:57], v[60:61]
	v_pk_add_f32 v[56:57], v[56:57], v[60:61] neg_lo:[0,1] neg_hi:[0,1]
	v_pk_add_f32 v[60:61], v[64:65], v[58:59]
	v_pk_add_f32 v[58:59], v[64:65], v[58:59] neg_lo:[0,1] neg_hi:[0,1]
	v_pk_add_f32 v[64:65], v[54:55], v[56:57] op_sel:[0,1] op_sel_hi:[1,0] neg_hi:[0,1]
	v_pk_add_f32 v[54:55], v[54:55], v[56:57] op_sel:[0,1] op_sel_hi:[1,0] neg_lo:[0,1]
	v_mov_b32_e32 v57, v41
	v_mov_b32_e32 v56, v40
	s_nop 0
	v_pk_mul_f32 v[88:89], v[78:79], v[56:57] op_sel:[0,0] op_sel_hi:[0,1]
	v_pk_fma_f32 v[78:79], v[78:79], v[56:57], v[88:89] op_sel:[1,1,0] op_sel_hi:[1,0,1] neg_lo:[0,1,0]
	ds_write2_b64 v146, v[84:85], v[78:79] offset1:17
	v_pk_mul_f32 v[78:79], v[56:57], v[56:57] op_sel:[0,0] op_sel_hi:[0,1]
	v_pk_fma_f32 v[78:79], v[56:57], v[56:57], v[78:79] op_sel:[1,1,0] op_sel_hi:[1,0,1] neg_lo:[0,1,0]
	v_pk_mul_f32 v[84:85], v[70:71], v[78:79] op_sel:[0,0] op_sel_hi:[0,1]
	v_pk_fma_f32 v[70:71], v[70:71], v[78:79], v[84:85] op_sel:[1,1,0] op_sel_hi:[1,0,1] neg_lo:[0,1,0]
	v_pk_mul_f32 v[84:85], v[78:79], v[56:57] op_sel:[0,0] op_sel_hi:[0,1]
	v_pk_fma_f32 v[78:79], v[78:79], v[56:57], v[84:85] op_sel:[1,1,0] op_sel_hi:[1,0,1] neg_lo:[0,1,0]
	v_pk_mul_f32 v[84:85], v[60:61], v[78:79] op_sel:[0,0] op_sel_hi:[0,1]
	v_pk_fma_f32 v[60:61], v[60:61], v[78:79], v[84:85] op_sel:[1,1,0] op_sel_hi:[1,0,1] neg_lo:[0,1,0]
	ds_write2_b64 v146, v[70:71], v[60:61] offset0:34 offset1:51
	v_pk_mul_f32 v[60:61], v[78:79], v[56:57] op_sel:[0,0] op_sel_hi:[0,1]
	v_pk_fma_f32 v[60:61], v[78:79], v[56:57], v[60:61] op_sel:[1,1,0] op_sel_hi:[1,0,1] neg_lo:[0,1,0]
	v_pk_mul_f32 v[70:71], v[82:83], v[60:61] op_sel:[0,0] op_sel_hi:[0,1]
	v_pk_mul_f32 v[78:79], v[60:61], v[56:57] op_sel:[0,0] op_sel_hi:[0,1]
	v_pk_fma_f32 v[70:71], v[82:83], v[60:61], v[70:71] op_sel:[1,1,0] op_sel_hi:[1,0,1] neg_lo:[0,1,0]
	v_pk_fma_f32 v[60:61], v[60:61], v[56:57], v[78:79] op_sel:[1,1,0] op_sel_hi:[1,0,1] neg_lo:[0,1,0]
	v_pk_mul_f32 v[78:79], v[86:87], v[60:61] op_sel:[0,0] op_sel_hi:[0,1]
	v_pk_fma_f32 v[78:79], v[86:87], v[60:61], v[78:79] op_sel:[1,1,0] op_sel_hi:[1,0,1] neg_lo:[0,1,0]
	ds_write2_b64 v146, v[70:71], v[78:79] offset0:68 offset1:85
	v_pk_mul_f32 v[70:71], v[60:61], v[56:57] op_sel:[0,0] op_sel_hi:[0,1]
	v_pk_fma_f32 v[60:61], v[60:61], v[56:57], v[70:71] op_sel:[1,1,0] op_sel_hi:[1,0,1] neg_lo:[0,1,0]
	v_pk_mul_f32 v[70:71], v[72:73], v[60:61] op_sel:[0,0] op_sel_hi:[0,1]
	v_pk_fma_f32 v[70:71], v[72:73], v[60:61], v[70:71] op_sel:[1,1,0] op_sel_hi:[1,0,1] neg_lo:[0,1,0]
	v_pk_mul_f32 v[72:73], v[60:61], v[56:57] op_sel:[0,0] op_sel_hi:[0,1]
	v_pk_fma_f32 v[60:61], v[60:61], v[56:57], v[72:73] op_sel:[1,1,0] op_sel_hi:[1,0,1] neg_lo:[0,1,0]
	v_pk_mul_f32 v[72:73], v[64:65], v[60:61] op_sel:[0,0] op_sel_hi:[0,1]
	v_pk_fma_f32 v[64:65], v[64:65], v[60:61], v[72:73] op_sel:[1,1,0] op_sel_hi:[1,0,1] neg_lo:[0,1,0]
	ds_write2_b64 v146, v[70:71], v[64:65] offset0:102 offset1:119
	v_pk_mul_f32 v[64:65], v[60:61], v[56:57] op_sel:[0,0] op_sel_hi:[0,1]
	v_pk_fma_f32 v[60:61], v[60:61], v[56:57], v[64:65] op_sel:[1,1,0] op_sel_hi:[1,0,1] neg_lo:[0,1,0]
	v_pk_mul_f32 v[64:65], v[80:81], v[60:61] op_sel:[0,0] op_sel_hi:[0,1]
	v_pk_mul_f32 v[70:71], v[60:61], v[56:57] op_sel:[0,0] op_sel_hi:[0,1]
	v_pk_fma_f32 v[64:65], v[80:81], v[60:61], v[64:65] op_sel:[1,1,0] op_sel_hi:[1,0,1] neg_lo:[0,1,0]
	v_pk_fma_f32 v[60:61], v[60:61], v[56:57], v[70:71] op_sel:[1,1,0] op_sel_hi:[1,0,1] neg_lo:[0,1,0]
	v_pk_mul_f32 v[70:71], v[76:77], v[60:61] op_sel:[0,0] op_sel_hi:[0,1]
	v_pk_fma_f32 v[70:71], v[76:77], v[60:61], v[70:71] op_sel:[1,1,0] op_sel_hi:[1,0,1] neg_lo:[0,1,0]
	ds_write2_b64 v146, v[64:65], v[70:71] offset0:136 offset1:153
	v_pk_mul_f32 v[64:65], v[60:61], v[56:57] op_sel:[0,0] op_sel_hi:[0,1]
	v_pk_fma_f32 v[60:61], v[60:61], v[56:57], v[64:65] op_sel:[1,1,0] op_sel_hi:[1,0,1] neg_lo:[0,1,0]
	v_pk_mul_f32 v[64:65], v[66:67], v[60:61] op_sel:[0,0] op_sel_hi:[0,1]
	v_pk_fma_f32 v[64:65], v[66:67], v[60:61], v[64:65] op_sel:[1,1,0] op_sel_hi:[1,0,1] neg_lo:[0,1,0]
	v_pk_mul_f32 v[66:67], v[60:61], v[56:57] op_sel:[0,0] op_sel_hi:[0,1]
	v_pk_fma_f32 v[60:61], v[60:61], v[56:57], v[66:67] op_sel:[1,1,0] op_sel_hi:[1,0,1] neg_lo:[0,1,0]
	v_pk_mul_f32 v[66:67], v[58:59], v[60:61] op_sel:[0,0] op_sel_hi:[0,1]
	v_pk_fma_f32 v[58:59], v[58:59], v[60:61], v[66:67] op_sel:[1,1,0] op_sel_hi:[1,0,1] neg_lo:[0,1,0]
	ds_write2_b64 v146, v[64:65], v[58:59] offset0:170 offset1:187
	v_pk_mul_f32 v[58:59], v[60:61], v[56:57] op_sel:[0,0] op_sel_hi:[0,1]
	v_pk_fma_f32 v[58:59], v[60:61], v[56:57], v[58:59] op_sel:[1,1,0] op_sel_hi:[1,0,1] neg_lo:[0,1,0]
	v_pk_mul_f32 v[60:61], v[74:75], v[58:59] op_sel:[0,0] op_sel_hi:[0,1]
	v_pk_mul_f32 v[64:65], v[58:59], v[56:57] op_sel:[0,0] op_sel_hi:[0,1]
	v_pk_fma_f32 v[60:61], v[74:75], v[58:59], v[60:61] op_sel:[1,1,0] op_sel_hi:[1,0,1] neg_lo:[0,1,0]
	v_pk_fma_f32 v[58:59], v[58:59], v[56:57], v[64:65] op_sel:[1,1,0] op_sel_hi:[1,0,1] neg_lo:[0,1,0]
	v_pk_mul_f32 v[64:65], v[68:69], v[58:59] op_sel:[0,0] op_sel_hi:[0,1]
	v_pk_fma_f32 v[64:65], v[68:69], v[58:59], v[64:65] op_sel:[1,1,0] op_sel_hi:[1,0,1] neg_lo:[0,1,0]
	ds_write2_b64 v146, v[60:61], v[64:65] offset0:204 offset1:221
	v_pk_mul_f32 v[60:61], v[58:59], v[56:57] op_sel:[0,0] op_sel_hi:[0,1]
	v_pk_fma_f32 v[58:59], v[58:59], v[56:57], v[60:61] op_sel:[1,1,0] op_sel_hi:[1,0,1] neg_lo:[0,1,0]
	v_pk_mul_f32 v[60:61], v[62:63], v[58:59] op_sel:[0,0] op_sel_hi:[0,1]
	v_pk_fma_f32 v[60:61], v[62:63], v[58:59], v[60:61] op_sel:[1,1,0] op_sel_hi:[1,0,1] neg_lo:[0,1,0]
	v_pk_mul_f32 v[62:63], v[58:59], v[56:57] op_sel:[0,0] op_sel_hi:[0,1]
	v_pk_fma_f32 v[56:57], v[58:59], v[56:57], v[62:63] op_sel:[1,1,0] op_sel_hi:[1,0,1] neg_lo:[0,1,0]
	v_pk_mul_f32 v[58:59], v[54:55], v[56:57] op_sel:[0,0] op_sel_hi:[0,1]
	v_pk_fma_f32 v[54:55], v[54:55], v[56:57], v[58:59] op_sel:[1,1,0] op_sel_hi:[1,0,1] neg_lo:[0,1,0]
	ds_write2_b64 v146, v[60:61], v[54:55] offset0:238 offset1:255
	s_waitcnt lgkmcnt(0)
	s_barrier
	ds_read2_b64 v[60:63], v147 offset1:1
	ds_read2_b64 v[64:67], v147 offset0:2 offset1:3
	ds_read2_b64 v[68:71], v147 offset0:8 offset1:9
	ds_read2_b64 v[72:75], v147 offset0:4 offset1:5
	ds_read2_b64 v[76:79], v147 offset0:6 offset1:7
	ds_read2_b64 v[80:83], v147 offset0:12 offset1:13
	ds_read2_b64 v[84:87], v147 offset0:10 offset1:11
	ds_read2_b64 v[88:91], v147 offset0:14 offset1:15
	s_waitcnt lgkmcnt(5)
	v_pk_add_f32 v[54:55], v[60:61], v[68:69]
	v_pk_add_f32 v[68:69], v[60:61], v[68:69] neg_lo:[0,1] neg_hi:[0,1]
	s_waitcnt lgkmcnt(2)
	v_pk_add_f32 v[56:57], v[72:73], v[80:81]
	v_pk_add_f32 v[72:73], v[72:73], v[80:81] neg_lo:[0,1] neg_hi:[0,1]
	v_pk_add_f32 v[60:61], v[54:55], v[56:57]
	v_pk_add_f32 v[56:57], v[54:55], v[56:57] neg_lo:[0,1] neg_hi:[0,1]
	v_pk_add_f32 v[58:59], v[68:69], v[72:73] op_sel:[0,1] op_sel_hi:[1,0] neg_hi:[0,1]
	v_pk_add_f32 v[54:55], v[68:69], v[72:73] op_sel:[0,1] op_sel_hi:[1,0] neg_lo:[0,1]
	v_pk_add_f32 v[68:69], v[62:63], v[70:71]
	v_pk_add_f32 v[70:71], v[62:63], v[70:71] neg_lo:[0,1] neg_hi:[0,1]
	v_pk_add_f32 v[72:73], v[74:75], v[82:83]
	v_pk_add_f32 v[74:75], v[74:75], v[82:83] neg_lo:[0,1] neg_hi:[0,1]
	v_pk_add_f32 v[62:63], v[68:69], v[72:73]
	v_pk_add_f32 v[68:69], v[68:69], v[72:73] neg_lo:[0,1] neg_hi:[0,1]
	v_pk_add_f32 v[72:73], v[70:71], v[74:75] op_sel:[0,1] op_sel_hi:[1,0] neg_hi:[0,1]
	v_pk_add_f32 v[70:71], v[70:71], v[74:75] op_sel:[0,1] op_sel_hi:[1,0] neg_lo:[0,1]
	s_waitcnt lgkmcnt(1)
	v_pk_add_f32 v[74:75], v[64:65], v[84:85]
	v_pk_add_f32 v[80:81], v[64:65], v[84:85] neg_lo:[0,1] neg_hi:[0,1]
	s_waitcnt lgkmcnt(0)
	v_pk_add_f32 v[82:83], v[76:77], v[88:89]
	v_pk_add_f32 v[76:77], v[76:77], v[88:89] neg_lo:[0,1] neg_hi:[0,1]
	v_pk_add_f32 v[64:65], v[74:75], v[82:83]
	v_pk_add_f32 v[74:75], v[74:75], v[82:83] neg_lo:[0,1] neg_hi:[0,1]
	v_pk_add_f32 v[82:83], v[80:81], v[76:77] op_sel:[0,1] op_sel_hi:[1,0] neg_hi:[0,1]
	v_pk_add_f32 v[76:77], v[80:81], v[76:77] op_sel:[0,1] op_sel_hi:[1,0] neg_lo:[0,1]
	v_pk_add_f32 v[80:81], v[66:67], v[86:87]
	v_pk_add_f32 v[84:85], v[66:67], v[86:87] neg_lo:[0,1] neg_hi:[0,1]
	v_pk_add_f32 v[86:87], v[78:79], v[90:91]
	v_pk_add_f32 v[78:79], v[78:79], v[90:91] neg_lo:[0,1] neg_hi:[0,1]
	v_pk_add_f32 v[66:67], v[80:81], v[86:87]
	v_pk_add_f32 v[86:87], v[80:81], v[86:87] neg_lo:[0,1] neg_hi:[0,1]
	v_pk_add_f32 v[80:81], v[84:85], v[78:79] op_sel:[0,1] op_sel_hi:[1,0] neg_hi:[0,1]
	v_pk_add_f32 v[90:91], v[84:85], v[78:79] op_sel:[0,1] op_sel_hi:[1,0] neg_lo:[0,1]
	v_pk_mul_f32 v[78:79], v[72:73], s[20:21] op_sel:[0,0] op_sel_hi:[0,1]
	v_pk_fma_f32 v[48:49], v[72:73], s[20:21], v[78:79] op_sel:[1,1,0] op_sel_hi:[1,0,1] neg_lo:[0,1,0]
	v_pk_mul_f32 v[72:73], v[82:83], s[50:51] op_sel:[0,0] op_sel_hi:[0,1]
	s_barrier
	v_pk_fma_f32 v[78:79], v[82:83], s[50:51], v[72:73] op_sel:[1,1,0] op_sel_hi:[1,0,1] neg_lo:[0,1,0]
	v_pk_mul_f32 v[72:73], v[80:81], s[54:55] op_sel:[0,0] op_sel_hi:[0,1]
	v_pk_fma_f32 v[80:81], v[80:81], s[54:55], v[72:73] op_sel:[1,1,0] op_sel_hi:[1,0,1] neg_lo:[0,1,0]
	v_pk_mul_f32 v[72:73], v[68:69], s[50:51] op_sel:[0,0] op_sel_hi:[0,1]
	v_pk_fma_f32 v[44:45], v[68:69], s[50:51], v[72:73] op_sel:[1,1,0] op_sel_hi:[1,0,1] neg_lo:[0,1,0]
	v_pk_mul_f32 v[68:69], v[74:75], s[14:15] op_sel:[0,0] op_sel_hi:[0,1]
	v_pk_fma_f32 v[84:85], v[74:75], s[14:15], v[68:69] op_sel:[1,1,0] op_sel_hi:[1,0,1] neg_lo:[0,1,0]
	v_pk_mul_f32 v[50:51], v[86:87], s[58:59] op_sel:[0,0] op_sel_hi:[0,1]
	v_pk_add_f32 v[68:69], v[58:59], v[78:79] neg_lo:[0,1] neg_hi:[0,1]
	v_pk_fma_f32 v[88:89], v[86:87], s[58:59], v[50:51] op_sel:[1,1,0] op_sel_hi:[1,0,1] neg_lo:[0,1,0]
	v_pk_mul_f32 v[50:51], v[70:71], s[54:55] op_sel:[0,0] op_sel_hi:[0,1]
	v_pk_add_f32 v[72:73], v[56:57], v[84:85] neg_lo:[0,1] neg_hi:[0,1]
	v_pk_fma_f32 v[82:83], v[70:71], s[54:55], v[50:51] op_sel:[1,1,0] op_sel_hi:[1,0,1] neg_lo:[0,1,0]
	v_pk_mul_f32 v[42:43], v[76:77], s[58:59] op_sel:[0,0] op_sel_hi:[0,1]
	v_pk_add_f32 v[50:51], v[62:63], v[66:67] neg_lo:[0,1] neg_hi:[0,1]
	v_pk_fma_f32 v[86:87], v[76:77], s[58:59], v[42:43] op_sel:[1,1,0] op_sel_hi:[1,0,1] neg_lo:[0,1,0]
	v_pk_mul_f32 v[42:43], v[90:91], s[60:61] op_sel:[0,0] op_sel_hi:[0,1]
	v_pk_add_f32 v[46:47], v[60:61], v[64:65] neg_lo:[0,1] neg_hi:[0,1]
	v_pk_fma_f32 v[52:53], v[90:91], s[60:61], v[42:43] op_sel:[1,1,0] op_sel_hi:[1,0,1] neg_lo:[0,1,0]
	v_pk_add_f32 v[70:71], v[48:49], v[80:81] neg_lo:[0,1] neg_hi:[0,1]
	v_pk_add_f32 v[74:75], v[44:45], v[88:89] neg_lo:[0,1] neg_hi:[0,1]
	v_pk_add_f32 v[76:77], v[54:55], v[86:87] neg_lo:[0,1] neg_hi:[0,1]
	v_pk_add_f32 v[90:91], v[82:83], v[52:53] neg_lo:[0,1] neg_hi:[0,1]
	v_pk_add_f32 v[42:43], v[46:47], v[50:51] op_sel:[0,1] op_sel_hi:[1,0] neg_hi:[0,1]
	v_pk_add_f32 v[46:47], v[46:47], v[50:51] op_sel:[0,1] op_sel_hi:[1,0] neg_lo:[0,1]
	v_pk_add_f32 v[50:51], v[68:69], v[70:71] op_sel:[0,1] op_sel_hi:[1,0] neg_hi:[0,1]
	v_pk_add_f32 v[68:69], v[68:69], v[70:71] op_sel:[0,1] op_sel_hi:[1,0] neg_lo:[0,1]
	v_pk_add_f32 v[70:71], v[72:73], v[74:75] op_sel:[0,1] op_sel_hi:[1,0] neg_hi:[0,1]
	v_pk_add_f32 v[72:73], v[72:73], v[74:75] op_sel:[0,1] op_sel_hi:[1,0] neg_lo:[0,1]
	v_pk_add_f32 v[74:75], v[76:77], v[90:91] op_sel:[0,1] op_sel_hi:[1,0] neg_hi:[0,1]
	v_pk_add_f32 v[76:77], v[76:77], v[90:91] op_sel:[0,1] op_sel_hi:[1,0] neg_lo:[0,1]
	v_mov_b32_e32 v90, v36
	v_mov_b32_e32 v91, v37
	s_branch .LBB0_1409
.LBB0_1408:
	s_or_b64 exec, exec, s[0:1]
	s_addk_i32 s28, 0x800
	s_waitcnt lgkmcnt(0)
	ds_write_b64 v34, v[92:93]
	s_cmpk_lg_u32 s28, 0x8000
	v_add_u32_e32 v34, 0x880, v34
	v_pk_mul_f32 v[96:97], v[90:91], s[18:19] op_sel:[0,0] op_sel_hi:[0,1]
	v_pk_fma_f32 v[90:91], v[90:91], s[18:19], v[96:97] op_sel:[1,1,0] op_sel_hi:[1,0,1] neg_lo:[0,1,0]
	s_cbranch_scc0 .LBB0_1411

.LBB0_1411:
	v_mov_b32_e32 v90, v30
	v_mov_b32_e32 v91, v26
	v_mov_b32_e32 v26, v31
	v_mov_b32_e32 v30, v32
	v_mov_b32_e32 v31, v28
	v_mov_b32_e32 v28, v33
	v_pk_add_f32 v[26:27], v[90:91], v[26:27]
	v_pk_add_f32 v[28:29], v[30:31], v[28:29]
	v_pk_add_f32 v[30:31], v[62:63], v[66:67]
	v_pk_add_f32 v[26:27], v[26:27], v[28:29]
	v_pk_add_f32 v[28:29], v[60:61], v[64:65]
	v_add_f32_e32 v34, v26, v27
	v_add_f32_e32 v34, 0x358637bd, v34
	v_mul_f32_e32 v34, 0x46000000, v34
	v_pk_add_f32 v[60:61], v[48:49], v[80:81]
	v_div_scale_f32 v48, s[0:1], v34, v34, 1.0
	v_rcp_f32_e32 v49, v48
	v_pk_add_f32 v[62:63], v[56:57], v[84:85]
	v_pk_add_f32 v[58:59], v[58:59], v[78:79]
	v_pk_add_f32 v[44:45], v[44:45], v[88:89]
	v_fma_f32 v56, -v48, v49, 1.0
	v_fmac_f32_e32 v49, v56, v49
	v_div_scale_f32 v56, vcc, 1.0, v34, 1.0
	v_mul_f32_e32 v57, v56, v49
	v_fma_f32 v78, -v48, v57, v56
	v_fmac_f32_e32 v57, v78, v49
	v_fma_f32 v48, -v48, v57, v56
	v_pk_add_f32 v[54:55], v[54:55], v[86:87]
	v_pk_add_f32 v[52:53], v[82:83], v[52:53]
	v_div_fmas_f32 v48, v48, v49, v57
	v_pk_add_f32 v[26:27], v[28:29], v[30:31]
	v_pk_add_f32 v[32:33], v[58:59], v[60:61]
	v_pk_add_f32 v[64:65], v[62:63], v[44:45]
	v_pk_add_f32 v[66:67], v[54:55], v[52:53]
	v_div_fixup_f32 v34, v48, v34, 1.0
	v_pk_add_f32 v[28:29], v[28:29], v[30:31] neg_lo:[0,1] neg_hi:[0,1]
	v_pk_add_f32 v[30:31], v[58:59], v[60:61] neg_lo:[0,1] neg_hi:[0,1]
	v_pk_add_f32 v[54:55], v[54:55], v[52:53] neg_lo:[0,1] neg_hi:[0,1]
	v_pk_mul_f32 v[56:57], v[34:35], v[26:27] op_sel_hi:[0,1]
	v_pk_mul_f32 v[48:49], v[34:35], v[32:33] op_sel_hi:[0,1]
	v_pk_mul_f32 v[32:33], v[34:35], v[64:65] op_sel_hi:[0,1]
	v_pk_mul_f32 v[26:27], v[34:35], v[66:67] op_sel_hi:[0,1]
	v_pk_add_f32 v[44:45], v[62:63], v[44:45] neg_lo:[0,1] neg_hi:[0,1]
	v_pk_mul_f32 v[60:61], v[34:35], v[28:29] op_sel_hi:[0,1]
	v_pk_mul_f32 v[52:53], v[34:35], v[30:31] op_sel_hi:[0,1]
	v_pk_mul_f32 v[28:29], v[34:35], v[54:55] op_sel_hi:[0,1]
	v_pk_mul_f32 v[64:65], v[34:35], v[42:43] op_sel_hi:[0,1]
	v_pk_mul_f32 v[62:63], v[34:35], v[46:47] op_sel_hi:[0,1]
	v_pk_mul_f32 v[58:59], v[34:35], v[50:51] op_sel_hi:[0,1]
	v_pk_mul_f32 v[54:55], v[34:35], v[68:69] op_sel_hi:[0,1]
	v_pk_mul_f32 v[50:51], v[34:35], v[70:71] op_sel_hi:[0,1]
	v_pk_mul_f32 v[46:47], v[34:35], v[72:73] op_sel_hi:[0,1]
	v_pk_mul_f32 v[42:43], v[34:35], v[74:75] op_sel_hi:[0,1]
	v_pk_mul_f32 v[30:31], v[34:35], v[76:77] op_sel_hi:[0,1]
	ds_read_b64 v[66:67], v144
	ds_read_b64 v[68:69], v144 offset:2176
	ds_read_b64 v[70:71], v144 offset:4352
	ds_read_b64 v[72:73], v144 offset:6528
	ds_read_b64 v[74:75], v144 offset:8704
	ds_read_b64 v[76:77], v144 offset:10880
	ds_read_b64 v[78:79], v144 offset:13056
	ds_read_b64 v[80:81], v144 offset:15232
	ds_read_b64 v[82:83], v144 offset:17408
	ds_read_b64 v[84:85], v144 offset:19584
	ds_read_b64 v[86:87], v144 offset:21760
	ds_read_b64 v[88:89], v144 offset:23936
	ds_read_b64 v[90:91], v144 offset:26112
	ds_read_b64 v[92:93], v144 offset:28288
	ds_read_b64 v[96:97], v144 offset:30464
	ds_read_b64 v[98:99], v144 offset:32640
	s_waitcnt lgkmcnt(7)
	v_pk_add_f32 v[100:101], v[66:67], v[82:83]
	v_pk_add_f32 v[66:67], v[66:67], v[82:83] neg_lo:[0,1] neg_hi:[0,1]
	s_waitcnt lgkmcnt(3)
	v_pk_add_f32 v[82:83], v[74:75], v[90:91]
	v_pk_add_f32 v[74:75], v[74:75], v[90:91] neg_lo:[0,1] neg_hi:[0,1]
	v_pk_add_f32 v[90:91], v[100:101], v[82:83]
	v_pk_add_f32 v[82:83], v[100:101], v[82:83] neg_lo:[0,1] neg_hi:[0,1]
	v_pk_add_f32 v[100:101], v[66:67], v[74:75] op_sel:[0,1] op_sel_hi:[1,0] neg_hi:[0,1]
	v_pk_add_f32 v[102:103], v[66:67], v[74:75] op_sel:[0,1] op_sel_hi:[1,0] neg_lo:[0,1]
	v_pk_add_f32 v[66:67], v[68:69], v[84:85]
	v_pk_add_f32 v[68:69], v[68:69], v[84:85] neg_lo:[0,1] neg_hi:[0,1]
	s_waitcnt lgkmcnt(2)
	v_pk_add_f32 v[74:75], v[76:77], v[92:93]
	v_pk_add_f32 v[76:77], v[76:77], v[92:93] neg_lo:[0,1] neg_hi:[0,1]
	v_pk_add_f32 v[84:85], v[66:67], v[74:75]
	v_pk_add_f32 v[74:75], v[66:67], v[74:75] neg_lo:[0,1] neg_hi:[0,1]
	v_pk_add_f32 v[66:67], v[68:69], v[76:77] op_sel:[0,1] op_sel_hi:[1,0] neg_hi:[0,1]
	v_pk_add_f32 v[76:77], v[68:69], v[76:77] op_sel:[0,1] op_sel_hi:[1,0] neg_lo:[0,1]
	v_pk_add_f32 v[68:69], v[70:71], v[86:87]
	v_pk_add_f32 v[70:71], v[70:71], v[86:87] neg_lo:[0,1] neg_hi:[0,1]
	s_waitcnt lgkmcnt(1)
	v_pk_add_f32 v[86:87], v[78:79], v[96:97]
	v_pk_add_f32 v[78:79], v[78:79], v[96:97] neg_lo:[0,1] neg_hi:[0,1]
	v_pk_add_f32 v[92:93], v[68:69], v[86:87]
	v_pk_add_f32 v[86:87], v[68:69], v[86:87] neg_lo:[0,1] neg_hi:[0,1]
	v_pk_add_f32 v[96:97], v[70:71], v[78:79] op_sel:[0,1] op_sel_hi:[1,0] neg_hi:[0,1]
	v_pk_add_f32 v[78:79], v[70:71], v[78:79] op_sel:[0,1] op_sel_hi:[1,0] neg_lo:[0,1]
	v_pk_add_f32 v[68:69], v[72:73], v[88:89]
	v_pk_add_f32 v[70:71], v[72:73], v[88:89] neg_lo:[0,1] neg_hi:[0,1]
	s_waitcnt lgkmcnt(0)
	v_pk_add_f32 v[72:73], v[80:81], v[98:99]
	v_pk_add_f32 v[80:81], v[80:81], v[98:99] neg_lo:[0,1] neg_hi:[0,1]
	v_pk_add_f32 v[88:89], v[68:69], v[72:73]
	v_pk_add_f32 v[98:99], v[68:69], v[72:73] neg_lo:[0,1] neg_hi:[0,1]
	v_pk_mul_f32 v[68:69], v[66:67], s[20:21] op_sel:[0,0] op_sel_hi:[0,1]
	v_pk_add_f32 v[104:105], v[70:71], v[80:81] op_sel:[0,1] op_sel_hi:[1,0] neg_hi:[0,1]
	v_pk_add_f32 v[80:81], v[70:71], v[80:81] op_sel:[0,1] op_sel_hi:[1,0] neg_lo:[0,1]
	s_add_i32 s82, s74, s24
	v_pk_fma_f32 v[106:107], v[66:67], s[20:21], v[68:69] op_sel:[1,1,0] op_sel_hi:[1,0,1] neg_lo:[0,1,0]
	v_pk_mul_f32 v[66:67], v[96:97], s[50:51] op_sel:[0,0] op_sel_hi:[0,1]
	s_cmpk_gt_i32 s82, 0x3ff
	v_pk_fma_f32 v[96:97], v[96:97], s[50:51], v[66:67] op_sel:[1,1,0] op_sel_hi:[1,0,1] neg_lo:[0,1,0]
	v_pk_mul_f32 v[70:71], v[104:105], s[54:55] op_sel:[0,0] op_sel_hi:[0,1]
	v_pk_mul_f32 v[44:45], v[34:35], v[44:45] op_sel_hi:[0,1]
	v_pk_fma_f32 v[104:105], v[104:105], s[54:55], v[70:71] op_sel:[1,1,0] op_sel_hi:[1,0,1] neg_lo:[0,1,0]
	v_pk_mul_f32 v[70:71], v[74:75], s[50:51] op_sel:[0,0] op_sel_hi:[0,1]
	s_cselect_b64 s[80:81], -1, 0
	v_pk_fma_f32 v[108:109], v[74:75], s[50:51], v[70:71] op_sel:[1,1,0] op_sel_hi:[1,0,1] neg_lo:[0,1,0]
	v_pk_mul_f32 v[70:71], v[86:87], s[14:15] op_sel:[0,0] op_sel_hi:[0,1]
	s_cmpk_lt_i32 s82, 0x400
	v_pk_fma_f32 v[86:87], v[86:87], s[14:15], v[70:71] op_sel:[1,1,0] op_sel_hi:[1,0,1] neg_lo:[0,1,0]
	v_pk_mul_f32 v[110:111], v[98:99], s[58:59] op_sel:[0,0] op_sel_hi:[0,1]
	s_cselect_b32 s0, s82, -1
	v_pk_fma_f32 v[98:99], v[98:99], s[58:59], v[110:111] op_sel:[1,1,0] op_sel_hi:[1,0,1] neg_lo:[0,1,0]
	v_pk_mul_f32 v[110:111], v[76:77], s[54:55] op_sel:[0,0] op_sel_hi:[0,1]
	s_cmp_lt_i32 s0, 0
	v_pk_fma_f32 v[110:111], v[76:77], s[54:55], v[110:111] op_sel:[1,1,0] op_sel_hi:[1,0,1] neg_lo:[0,1,0]
	v_pk_mul_f32 v[76:77], v[78:79], s[58:59] op_sel:[0,0] op_sel_hi:[0,1]
	v_pk_fma_f32 v[78:79], v[78:79], s[58:59], v[76:77] op_sel:[1,1,0] op_sel_hi:[1,0,1] neg_lo:[0,1,0]
	v_pk_mul_f32 v[112:113], v[80:81], s[60:61] op_sel:[0,0] op_sel_hi:[0,1]
	v_pk_fma_f32 v[80:81], v[80:81], s[60:61], v[112:113] op_sel:[1,1,0] op_sel_hi:[1,0,1] neg_lo:[0,1,0]
	v_pk_add_f32 v[112:113], v[90:91], v[92:93]
	v_pk_add_f32 v[90:91], v[90:91], v[92:93] neg_lo:[0,1] neg_hi:[0,1]
	v_pk_add_f32 v[92:93], v[84:85], v[88:89]
	v_pk_add_f32 v[84:85], v[84:85], v[88:89] neg_lo:[0,1] neg_hi:[0,1]
	v_pk_add_f32 v[88:89], v[112:113], v[92:93]
	v_pk_add_f32 v[92:93], v[112:113], v[92:93] neg_lo:[0,1] neg_hi:[0,1]
	v_pk_add_f32 v[112:113], v[90:91], v[84:85] op_sel:[0,1] op_sel_hi:[1,0] neg_hi:[0,1]
	v_pk_add_f32 v[84:85], v[90:91], v[84:85] op_sel:[0,1] op_sel_hi:[1,0] neg_lo:[0,1]
	v_pk_add_f32 v[90:91], v[100:101], v[96:97]
	v_pk_add_f32 v[96:97], v[100:101], v[96:97] neg_lo:[0,1] neg_hi:[0,1]
	v_pk_add_f32 v[100:101], v[106:107], v[104:105]
	v_pk_add_f32 v[104:105], v[106:107], v[104:105] neg_lo:[0,1] neg_hi:[0,1]
	v_pk_add_f32 v[106:107], v[90:91], v[100:101]
	v_pk_add_f32 v[90:91], v[90:91], v[100:101] neg_lo:[0,1] neg_hi:[0,1]
	v_pk_add_f32 v[100:101], v[96:97], v[104:105] op_sel:[0,1] op_sel_hi:[1,0] neg_hi:[0,1]
	v_pk_add_f32 v[96:97], v[96:97], v[104:105] op_sel:[0,1] op_sel_hi:[1,0] neg_lo:[0,1]
	v_pk_add_f32 v[104:105], v[82:83], v[86:87]
	v_pk_add_f32 v[82:83], v[82:83], v[86:87] neg_lo:[0,1] neg_hi:[0,1]
	v_pk_add_f32 v[86:87], v[108:109], v[98:99]
	v_pk_add_f32 v[98:99], v[108:109], v[98:99] neg_lo:[0,1] neg_hi:[0,1]
	v_pk_add_f32 v[108:109], v[104:105], v[86:87]
	v_pk_add_f32 v[86:87], v[104:105], v[86:87] neg_lo:[0,1] neg_hi:[0,1]
	v_pk_add_f32 v[104:105], v[82:83], v[98:99] op_sel:[0,1] op_sel_hi:[1,0] neg_hi:[0,1]
	v_pk_add_f32 v[82:83], v[82:83], v[98:99] op_sel:[0,1] op_sel_hi:[1,0] neg_lo:[0,1]
	v_pk_add_f32 v[98:99], v[102:103], v[78:79]
	v_pk_add_f32 v[78:79], v[102:103], v[78:79] neg_lo:[0,1] neg_hi:[0,1]
	v_pk_add_f32 v[102:103], v[110:111], v[80:81]
	v_pk_add_f32 v[80:81], v[110:111], v[80:81] neg_lo:[0,1] neg_hi:[0,1]
	v_pk_add_f32 v[110:111], v[98:99], v[102:103]
	v_pk_add_f32 v[98:99], v[98:99], v[102:103] neg_lo:[0,1] neg_hi:[0,1]
	v_pk_add_f32 v[102:103], v[78:79], v[80:81] op_sel:[0,1] op_sel_hi:[1,0] neg_hi:[0,1]
	v_pk_add_f32 v[78:79], v[78:79], v[80:81] op_sel:[0,1] op_sel_hi:[1,0] neg_lo:[0,1]
	v_mov_b32_e32 v80, v38
	v_mov_b32_e32 v81, v39
	ds_write_b64 v144, v[88:89]
	v_pk_mul_f32 v[88:89], v[106:107], v[80:81] op_sel:[0,0] op_sel_hi:[0,1]
	v_pk_fma_f32 v[88:89], v[106:107], v[80:81], v[88:89] op_sel:[1,1,0] op_sel_hi:[1,0,1] neg_lo:[0,1,0]
	ds_write_b64 v144, v[88:89] offset:2176
	v_pk_mul_f32 v[88:89], v[80:81], v[80:81] op_sel:[0,0] op_sel_hi:[0,1]
	v_pk_fma_f32 v[88:89], v[80:81], v[80:81], v[88:89] op_sel:[1,1,0] op_sel_hi:[1,0,1] neg_lo:[0,1,0]
	v_pk_mul_f32 v[106:107], v[108:109], v[88:89] op_sel:[0,0] op_sel_hi:[0,1]
	v_pk_fma_f32 v[106:107], v[108:109], v[88:89], v[106:107] op_sel:[1,1,0] op_sel_hi:[1,0,1] neg_lo:[0,1,0]
	ds_write_b64 v144, v[106:107] offset:4352
	v_pk_mul_f32 v[106:107], v[88:89], v[80:81] op_sel:[0,0] op_sel_hi:[0,1]
	v_pk_fma_f32 v[88:89], v[88:89], v[80:81], v[106:107] op_sel:[1,1,0] op_sel_hi:[1,0,1] neg_lo:[0,1,0]
	v_pk_mul_f32 v[106:107], v[110:111], v[88:89] op_sel:[0,0] op_sel_hi:[0,1]
	v_pk_fma_f32 v[106:107], v[110:111], v[88:89], v[106:107] op_sel:[1,1,0] op_sel_hi:[1,0,1] neg_lo:[0,1,0]
	ds_write_b64 v144, v[106:107] offset:6528
	v_pk_mul_f32 v[106:107], v[88:89], v[80:81] op_sel:[0,0] op_sel_hi:[0,1]
	v_pk_fma_f32 v[88:89], v[88:89], v[80:81], v[106:107] op_sel:[1,1,0] op_sel_hi:[1,0,1] neg_lo:[0,1,0]
	v_pk_mul_f32 v[106:107], v[112:113], v[88:89] op_sel:[0,0] op_sel_hi:[0,1]
	v_pk_fma_f32 v[106:107], v[112:113], v[88:89], v[106:107] op_sel:[1,1,0] op_sel_hi:[1,0,1] neg_lo:[0,1,0]
	ds_write_b64 v144, v[106:107] offset:8704
	v_pk_mul_f32 v[106:107], v[88:89], v[80:81] op_sel:[0,0] op_sel_hi:[0,1]
	v_pk_fma_f32 v[88:89], v[88:89], v[80:81], v[106:107] op_sel:[1,1,0] op_sel_hi:[1,0,1] neg_lo:[0,1,0]
	v_pk_mul_f32 v[106:107], v[100:101], v[88:89] op_sel:[0,0] op_sel_hi:[0,1]
	v_pk_fma_f32 v[100:101], v[100:101], v[88:89], v[106:107] op_sel:[1,1,0] op_sel_hi:[1,0,1] neg_lo:[0,1,0]
	ds_write_b64 v144, v[100:101] offset:10880
	v_pk_mul_f32 v[100:101], v[88:89], v[80:81] op_sel:[0,0] op_sel_hi:[0,1]
	v_pk_fma_f32 v[88:89], v[88:89], v[80:81], v[100:101] op_sel:[1,1,0] op_sel_hi:[1,0,1] neg_lo:[0,1,0]
	v_pk_mul_f32 v[100:101], v[104:105], v[88:89] op_sel:[0,0] op_sel_hi:[0,1]
	v_pk_fma_f32 v[100:101], v[104:105], v[88:89], v[100:101] op_sel:[1,1,0] op_sel_hi:[1,0,1] neg_lo:[0,1,0]
	ds_write_b64 v144, v[100:101] offset:13056
	v_pk_mul_f32 v[100:101], v[88:89], v[80:81] op_sel:[0,0] op_sel_hi:[0,1]
	v_pk_fma_f32 v[88:89], v[88:89], v[80:81], v[100:101] op_sel:[1,1,0] op_sel_hi:[1,0,1] neg_lo:[0,1,0]
	v_pk_mul_f32 v[100:101], v[102:103], v[88:89] op_sel:[0,0] op_sel_hi:[0,1]
	v_pk_fma_f32 v[100:101], v[102:103], v[88:89], v[100:101] op_sel:[1,1,0] op_sel_hi:[1,0,1] neg_lo:[0,1,0]
	ds_write_b64 v144, v[100:101] offset:15232
	v_pk_mul_f32 v[100:101], v[88:89], v[80:81] op_sel:[0,0] op_sel_hi:[0,1]
	v_pk_fma_f32 v[88:89], v[88:89], v[80:81], v[100:101] op_sel:[1,1,0] op_sel_hi:[1,0,1] neg_lo:[0,1,0]
	v_pk_mul_f32 v[100:101], v[92:93], v[88:89] op_sel:[0,0] op_sel_hi:[0,1]
	v_pk_fma_f32 v[92:93], v[92:93], v[88:89], v[100:101] op_sel:[1,1,0] op_sel_hi:[1,0,1] neg_lo:[0,1,0]
	ds_write_b64 v144, v[92:93] offset:17408
	v_pk_mul_f32 v[92:93], v[88:89], v[80:81] op_sel:[0,0] op_sel_hi:[0,1]
	v_pk_fma_f32 v[88:89], v[88:89], v[80:81], v[92:93] op_sel:[1,1,0] op_sel_hi:[1,0,1] neg_lo:[0,1,0]
	v_pk_mul_f32 v[92:93], v[90:91], v[88:89] op_sel:[0,0] op_sel_hi:[0,1]
	v_pk_fma_f32 v[90:91], v[90:91], v[88:89], v[92:93] op_sel:[1,1,0] op_sel_hi:[1,0,1] neg_lo:[0,1,0]
	ds_write_b64 v144, v[90:91] offset:19584
	v_pk_mul_f32 v[90:91], v[88:89], v[80:81] op_sel:[0,0] op_sel_hi:[0,1]
	v_pk_fma_f32 v[88:89], v[88:89], v[80:81], v[90:91] op_sel:[1,1,0] op_sel_hi:[1,0,1] neg_lo:[0,1,0]
	v_pk_mul_f32 v[90:91], v[86:87], v[88:89] op_sel:[0,0] op_sel_hi:[0,1]
	v_pk_fma_f32 v[86:87], v[86:87], v[88:89], v[90:91] op_sel:[1,1,0] op_sel_hi:[1,0,1] neg_lo:[0,1,0]
	ds_write_b64 v144, v[86:87] offset:21760
	v_pk_mul_f32 v[86:87], v[88:89], v[80:81] op_sel:[0,0] op_sel_hi:[0,1]
	v_pk_fma_f32 v[86:87], v[88:89], v[80:81], v[86:87] op_sel:[1,1,0] op_sel_hi:[1,0,1] neg_lo:[0,1,0]
	v_pk_mul_f32 v[88:89], v[98:99], v[86:87] op_sel:[0,0] op_sel_hi:[0,1]
	v_pk_fma_f32 v[88:89], v[98:99], v[86:87], v[88:89] op_sel:[1,1,0] op_sel_hi:[1,0,1] neg_lo:[0,1,0]
	ds_write_b64 v144, v[88:89] offset:23936
	v_pk_mul_f32 v[88:89], v[86:87], v[80:81] op_sel:[0,0] op_sel_hi:[0,1]
	v_pk_fma_f32 v[86:87], v[86:87], v[80:81], v[88:89] op_sel:[1,1,0] op_sel_hi:[1,0,1] neg_lo:[0,1,0]
	v_pk_mul_f32 v[88:89], v[84:85], v[86:87] op_sel:[0,0] op_sel_hi:[0,1]
	v_pk_fma_f32 v[84:85], v[84:85], v[86:87], v[88:89] op_sel:[1,1,0] op_sel_hi:[1,0,1] neg_lo:[0,1,0]
	ds_write_b64 v144, v[84:85] offset:26112
	v_pk_mul_f32 v[84:85], v[86:87], v[80:81] op_sel:[0,0] op_sel_hi:[0,1]
	v_pk_fma_f32 v[84:85], v[86:87], v[80:81], v[84:85] op_sel:[1,1,0] op_sel_hi:[1,0,1] neg_lo:[0,1,0]
	v_pk_mul_f32 v[86:87], v[96:97], v[84:85] op_sel:[0,0] op_sel_hi:[0,1]
	v_pk_fma_f32 v[86:87], v[96:97], v[84:85], v[86:87] op_sel:[1,1,0] op_sel_hi:[1,0,1] neg_lo:[0,1,0]
	ds_write_b64 v144, v[86:87] offset:28288
	v_pk_mul_f32 v[86:87], v[84:85], v[80:81] op_sel:[0,0] op_sel_hi:[0,1]
	v_pk_fma_f32 v[84:85], v[84:85], v[80:81], v[86:87] op_sel:[1,1,0] op_sel_hi:[1,0,1] neg_lo:[0,1,0]
	v_pk_mul_f32 v[86:87], v[82:83], v[84:85] op_sel:[0,0] op_sel_hi:[0,1]
	v_pk_fma_f32 v[82:83], v[82:83], v[84:85], v[86:87] op_sel:[1,1,0] op_sel_hi:[1,0,1] neg_lo:[0,1,0]
	ds_write_b64 v144, v[82:83] offset:30464
	v_pk_mul_f32 v[82:83], v[84:85], v[80:81] op_sel:[0,0] op_sel_hi:[0,1]
	v_pk_fma_f32 v[80:81], v[84:85], v[80:81], v[82:83] op_sel:[1,1,0] op_sel_hi:[1,0,1] neg_lo:[0,1,0]
	v_pk_mul_f32 v[82:83], v[78:79], v[80:81] op_sel:[0,0] op_sel_hi:[0,1]
	v_pk_fma_f32 v[78:79], v[78:79], v[80:81], v[82:83] op_sel:[1,1,0] op_sel_hi:[1,0,1] neg_lo:[0,1,0]
	ds_write_b64 v144, v[78:79] offset:32640
	s_waitcnt lgkmcnt(0)
	s_barrier
	ds_read2_b64 v[78:81], v146 offset1:17
	ds_read2_b64 v[82:85], v146 offset0:34 offset1:51
	ds_read2_b64 v[86:89], v146 offset0:68 offset1:85
	ds_read2_b64 v[90:93], v146 offset0:136 offset1:153
	ds_read2_b64 v[96:99], v146 offset0:102 offset1:119
	ds_read2_b64 v[100:103], v146 offset0:204 offset1:221
	ds_read2_b64 v[104:107], v146 offset0:170 offset1:187
	ds_read2_b64 v[108:111], v146 offset0:238 offset1:255
	s_waitcnt lgkmcnt(4)
	v_pk_add_f32 v[112:113], v[78:79], v[90:91]
	v_pk_add_f32 v[78:79], v[78:79], v[90:91] neg_lo:[0,1] neg_hi:[0,1]
	s_waitcnt lgkmcnt(2)
	v_pk_add_f32 v[90:91], v[86:87], v[100:101]
	v_pk_add_f32 v[86:87], v[86:87], v[100:101] neg_lo:[0,1] neg_hi:[0,1]
	v_pk_add_f32 v[100:101], v[112:113], v[90:91]
	v_pk_add_f32 v[90:91], v[112:113], v[90:91] neg_lo:[0,1] neg_hi:[0,1]
	v_pk_add_f32 v[112:113], v[78:79], v[86:87] op_sel:[0,1] op_sel_hi:[1,0] neg_hi:[0,1]
	v_pk_add_f32 v[78:79], v[78:79], v[86:87] op_sel:[0,1] op_sel_hi:[1,0] neg_lo:[0,1]
	v_pk_add_f32 v[86:87], v[80:81], v[92:93]
	v_pk_add_f32 v[80:81], v[80:81], v[92:93] neg_lo:[0,1] neg_hi:[0,1]
	v_pk_add_f32 v[92:93], v[88:89], v[102:103]
	v_pk_add_f32 v[88:89], v[88:89], v[102:103] neg_lo:[0,1] neg_hi:[0,1]
	v_pk_add_f32 v[102:103], v[86:87], v[92:93]
	v_pk_add_f32 v[86:87], v[86:87], v[92:93] neg_lo:[0,1] neg_hi:[0,1]
	v_pk_add_f32 v[92:93], v[80:81], v[88:89] op_sel:[0,1] op_sel_hi:[1,0] neg_hi:[0,1]
	v_pk_add_f32 v[80:81], v[80:81], v[88:89] op_sel:[0,1] op_sel_hi:[1,0] neg_lo:[0,1]
	s_waitcnt lgkmcnt(1)
	v_pk_add_f32 v[88:89], v[82:83], v[104:105]
	v_pk_add_f32 v[82:83], v[82:83], v[104:105] neg_lo:[0,1] neg_hi:[0,1]
	s_waitcnt lgkmcnt(0)
	v_pk_add_f32 v[104:105], v[96:97], v[108:109]
	v_pk_add_f32 v[96:97], v[96:97], v[108:109] neg_lo:[0,1] neg_hi:[0,1]
	v_pk_add_f32 v[108:109], v[88:89], v[104:105]
	v_pk_add_f32 v[88:89], v[88:89], v[104:105] neg_lo:[0,1] neg_hi:[0,1]
	v_pk_add_f32 v[104:105], v[82:83], v[96:97] op_sel:[0,1] op_sel_hi:[1,0] neg_hi:[0,1]
	v_pk_add_f32 v[82:83], v[82:83], v[96:97] op_sel:[0,1] op_sel_hi:[1,0] neg_lo:[0,1]
	v_pk_add_f32 v[96:97], v[84:85], v[106:107]
	v_pk_add_f32 v[84:85], v[84:85], v[106:107] neg_lo:[0,1] neg_hi:[0,1]
	v_pk_add_f32 v[106:107], v[98:99], v[110:111]
	v_pk_add_f32 v[98:99], v[98:99], v[110:111] neg_lo:[0,1] neg_hi:[0,1]
	v_pk_add_f32 v[110:111], v[96:97], v[106:107]
	v_pk_add_f32 v[96:97], v[96:97], v[106:107] neg_lo:[0,1] neg_hi:[0,1]
	v_pk_add_f32 v[106:107], v[84:85], v[98:99] op_sel:[0,1] op_sel_hi:[1,0] neg_hi:[0,1]
	v_pk_add_f32 v[84:85], v[84:85], v[98:99] op_sel:[0,1] op_sel_hi:[1,0] neg_lo:[0,1]
	v_pk_mul_f32 v[98:99], v[92:93], s[20:21] op_sel:[0,0] op_sel_hi:[0,1]
	v_pk_fma_f32 v[92:93], v[92:93], s[20:21], v[98:99] op_sel:[1,1,0] op_sel_hi:[1,0,1] neg_lo:[0,1,0]
	v_pk_mul_f32 v[98:99], v[104:105], s[50:51] op_sel:[0,0] op_sel_hi:[0,1]
	v_pk_fma_f32 v[98:99], v[104:105], s[50:51], v[98:99] op_sel:[1,1,0] op_sel_hi:[1,0,1] neg_lo:[0,1,0]
	v_pk_mul_f32 v[104:105], v[106:107], s[54:55] op_sel:[0,0] op_sel_hi:[0,1]
	v_pk_fma_f32 v[104:105], v[106:107], s[54:55], v[104:105] op_sel:[1,1,0] op_sel_hi:[1,0,1] neg_lo:[0,1,0]
	v_pk_mul_f32 v[106:107], v[86:87], s[50:51] op_sel:[0,0] op_sel_hi:[0,1]
	v_pk_fma_f32 v[86:87], v[86:87], s[50:51], v[106:107] op_sel:[1,1,0] op_sel_hi:[1,0,1] neg_lo:[0,1,0]
	v_pk_mul_f32 v[106:107], v[88:89], s[14:15] op_sel:[0,0] op_sel_hi:[0,1]
	v_pk_fma_f32 v[88:89], v[88:89], s[14:15], v[106:107] op_sel:[1,1,0] op_sel_hi:[1,0,1] neg_lo:[0,1,0]
	v_pk_mul_f32 v[106:107], v[96:97], s[58:59] op_sel:[0,0] op_sel_hi:[0,1]
	v_pk_fma_f32 v[96:97], v[96:97], s[58:59], v[106:107] op_sel:[1,1,0] op_sel_hi:[1,0,1] neg_lo:[0,1,0]
	v_pk_mul_f32 v[106:107], v[80:81], s[54:55] op_sel:[0,0] op_sel_hi:[0,1]
	v_pk_fma_f32 v[80:81], v[80:81], s[54:55], v[106:107] op_sel:[1,1,0] op_sel_hi:[1,0,1] neg_lo:[0,1,0]
	v_pk_mul_f32 v[106:107], v[82:83], s[58:59] op_sel:[0,0] op_sel_hi:[0,1]
	v_pk_fma_f32 v[82:83], v[82:83], s[58:59], v[106:107] op_sel:[1,1,0] op_sel_hi:[1,0,1] neg_lo:[0,1,0]
	v_pk_mul_f32 v[106:107], v[84:85], s[60:61] op_sel:[0,0] op_sel_hi:[0,1]
	v_pk_fma_f32 v[84:85], v[84:85], s[60:61], v[106:107] op_sel:[1,1,0] op_sel_hi:[1,0,1] neg_lo:[0,1,0]
	v_pk_add_f32 v[106:107], v[100:101], v[108:109]
	v_pk_add_f32 v[100:101], v[100:101], v[108:109] neg_lo:[0,1] neg_hi:[0,1]
	v_pk_add_f32 v[108:109], v[102:103], v[110:111]
	v_pk_add_f32 v[102:103], v[102:103], v[110:111] neg_lo:[0,1] neg_hi:[0,1]
	v_pk_add_f32 v[110:111], v[106:107], v[108:109]
	v_pk_add_f32 v[106:107], v[106:107], v[108:109] neg_lo:[0,1] neg_hi:[0,1]
	v_pk_add_f32 v[108:109], v[100:101], v[102:103] op_sel:[0,1] op_sel_hi:[1,0] neg_hi:[0,1]
	v_pk_add_f32 v[100:101], v[100:101], v[102:103] op_sel:[0,1] op_sel_hi:[1,0] neg_lo:[0,1]
	v_pk_add_f32 v[102:103], v[112:113], v[98:99]
	v_pk_add_f32 v[98:99], v[112:113], v[98:99] neg_lo:[0,1] neg_hi:[0,1]
	v_pk_add_f32 v[112:113], v[92:93], v[104:105]
	v_pk_add_f32 v[92:93], v[92:93], v[104:105] neg_lo:[0,1] neg_hi:[0,1]
	v_pk_add_f32 v[104:105], v[102:103], v[112:113]
	v_pk_add_f32 v[102:103], v[102:103], v[112:113] neg_lo:[0,1] neg_hi:[0,1]
	v_pk_add_f32 v[112:113], v[98:99], v[92:93] op_sel:[0,1] op_sel_hi:[1,0] neg_hi:[0,1]
	v_pk_add_f32 v[92:93], v[98:99], v[92:93] op_sel:[0,1] op_sel_hi:[1,0] neg_lo:[0,1]
	v_pk_add_f32 v[98:99], v[90:91], v[88:89]
	v_pk_add_f32 v[88:89], v[90:91], v[88:89] neg_lo:[0,1] neg_hi:[0,1]
	v_pk_add_f32 v[90:91], v[86:87], v[96:97]
	v_pk_add_f32 v[86:87], v[86:87], v[96:97] neg_lo:[0,1] neg_hi:[0,1]
	v_pk_add_f32 v[96:97], v[98:99], v[90:91]
	v_pk_add_f32 v[90:91], v[98:99], v[90:91] neg_lo:[0,1] neg_hi:[0,1]
	v_pk_add_f32 v[98:99], v[88:89], v[86:87] op_sel:[0,1] op_sel_hi:[1,0] neg_hi:[0,1]
	v_pk_add_f32 v[86:87], v[88:89], v[86:87] op_sel:[0,1] op_sel_hi:[1,0] neg_lo:[0,1]
	v_pk_add_f32 v[88:89], v[78:79], v[82:83]
	v_pk_add_f32 v[78:79], v[78:79], v[82:83] neg_lo:[0,1] neg_hi:[0,1]
	v_pk_add_f32 v[82:83], v[80:81], v[84:85]
	v_pk_add_f32 v[80:81], v[80:81], v[84:85] neg_lo:[0,1] neg_hi:[0,1]
	v_pk_add_f32 v[84:85], v[88:89], v[82:83]
	v_pk_add_f32 v[82:83], v[88:89], v[82:83] neg_lo:[0,1] neg_hi:[0,1]
	v_pk_add_f32 v[88:89], v[78:79], v[80:81] op_sel:[0,1] op_sel_hi:[1,0] neg_hi:[0,1]
	v_pk_add_f32 v[78:79], v[78:79], v[80:81] op_sel:[0,1] op_sel_hi:[1,0] neg_lo:[0,1]
	v_mov_b32_e32 v80, v40
	v_mov_b32_e32 v81, v41
	s_nop 0
	v_pk_mul_f32 v[114:115], v[104:105], v[80:81] op_sel:[0,0] op_sel_hi:[0,1]
	v_pk_fma_f32 v[104:105], v[104:105], v[80:81], v[114:115] op_sel:[1,1,0] op_sel_hi:[1,0,1] neg_lo:[0,1,0]
	ds_write2_b64 v146, v[110:111], v[104:105] offset1:17
	v_pk_mul_f32 v[104:105], v[80:81], v[80:81] op_sel:[0,0] op_sel_hi:[0,1]
	v_pk_fma_f32 v[104:105], v[80:81], v[80:81], v[104:105] op_sel:[1,1,0] op_sel_hi:[1,0,1] neg_lo:[0,1,0]
	v_pk_mul_f32 v[110:111], v[96:97], v[104:105] op_sel:[0,0] op_sel_hi:[0,1]
	v_pk_fma_f32 v[96:97], v[96:97], v[104:105], v[110:111] op_sel:[1,1,0] op_sel_hi:[1,0,1] neg_lo:[0,1,0]
	v_pk_mul_f32 v[110:111], v[104:105], v[80:81] op_sel:[0,0] op_sel_hi:[0,1]
	v_pk_fma_f32 v[104:105], v[104:105], v[80:81], v[110:111] op_sel:[1,1,0] op_sel_hi:[1,0,1] neg_lo:[0,1,0]
	v_pk_mul_f32 v[110:111], v[84:85], v[104:105] op_sel:[0,0] op_sel_hi:[0,1]
	v_pk_fma_f32 v[84:85], v[84:85], v[104:105], v[110:111] op_sel:[1,1,0] op_sel_hi:[1,0,1] neg_lo:[0,1,0]
	ds_write2_b64 v146, v[96:97], v[84:85] offset0:34 offset1:51
	v_pk_mul_f32 v[84:85], v[104:105], v[80:81] op_sel:[0,0] op_sel_hi:[0,1]
	v_pk_fma_f32 v[84:85], v[104:105], v[80:81], v[84:85] op_sel:[1,1,0] op_sel_hi:[1,0,1] neg_lo:[0,1,0]
	v_pk_mul_f32 v[96:97], v[108:109], v[84:85] op_sel:[0,0] op_sel_hi:[0,1]
	v_pk_mul_f32 v[104:105], v[84:85], v[80:81] op_sel:[0,0] op_sel_hi:[0,1]
	v_pk_fma_f32 v[96:97], v[108:109], v[84:85], v[96:97] op_sel:[1,1,0] op_sel_hi:[1,0,1] neg_lo:[0,1,0]
	v_pk_fma_f32 v[84:85], v[84:85], v[80:81], v[104:105] op_sel:[1,1,0] op_sel_hi:[1,0,1] neg_lo:[0,1,0]
	v_pk_mul_f32 v[104:105], v[112:113], v[84:85] op_sel:[0,0] op_sel_hi:[0,1]
	v_pk_fma_f32 v[104:105], v[112:113], v[84:85], v[104:105] op_sel:[1,1,0] op_sel_hi:[1,0,1] neg_lo:[0,1,0]
	ds_write2_b64 v146, v[96:97], v[104:105] offset0:68 offset1:85
	v_pk_mul_f32 v[96:97], v[84:85], v[80:81] op_sel:[0,0] op_sel_hi:[0,1]
	v_pk_fma_f32 v[84:85], v[84:85], v[80:81], v[96:97] op_sel:[1,1,0] op_sel_hi:[1,0,1] neg_lo:[0,1,0]
	v_pk_mul_f32 v[96:97], v[98:99], v[84:85] op_sel:[0,0] op_sel_hi:[0,1]
	v_pk_fma_f32 v[96:97], v[98:99], v[84:85], v[96:97] op_sel:[1,1,0] op_sel_hi:[1,0,1] neg_lo:[0,1,0]
	v_pk_mul_f32 v[98:99], v[84:85], v[80:81] op_sel:[0,0] op_sel_hi:[0,1]
	v_pk_fma_f32 v[84:85], v[84:85], v[80:81], v[98:99] op_sel:[1,1,0] op_sel_hi:[1,0,1] neg_lo:[0,1,0]
	v_pk_mul_f32 v[98:99], v[88:89], v[84:85] op_sel:[0,0] op_sel_hi:[0,1]
	v_pk_fma_f32 v[88:89], v[88:89], v[84:85], v[98:99] op_sel:[1,1,0] op_sel_hi:[1,0,1] neg_lo:[0,1,0]
	ds_write2_b64 v146, v[96:97], v[88:89] offset0:102 offset1:119
	v_pk_mul_f32 v[88:89], v[84:85], v[80:81] op_sel:[0,0] op_sel_hi:[0,1]
	v_pk_fma_f32 v[84:85], v[84:85], v[80:81], v[88:89] op_sel:[1,1,0] op_sel_hi:[1,0,1] neg_lo:[0,1,0]
	v_pk_mul_f32 v[88:89], v[106:107], v[84:85] op_sel:[0,0] op_sel_hi:[0,1]
	v_pk_mul_f32 v[96:97], v[84:85], v[80:81] op_sel:[0,0] op_sel_hi:[0,1]
	v_pk_fma_f32 v[88:89], v[106:107], v[84:85], v[88:89] op_sel:[1,1,0] op_sel_hi:[1,0,1] neg_lo:[0,1,0]
	v_pk_fma_f32 v[84:85], v[84:85], v[80:81], v[96:97] op_sel:[1,1,0] op_sel_hi:[1,0,1] neg_lo:[0,1,0]
	v_pk_mul_f32 v[96:97], v[102:103], v[84:85] op_sel:[0,0] op_sel_hi:[0,1]
	v_pk_fma_f32 v[96:97], v[102:103], v[84:85], v[96:97] op_sel:[1,1,0] op_sel_hi:[1,0,1] neg_lo:[0,1,0]
	ds_write2_b64 v146, v[88:89], v[96:97] offset0:136 offset1:153
	v_pk_mul_f32 v[88:89], v[84:85], v[80:81] op_sel:[0,0] op_sel_hi:[0,1]
	v_pk_fma_f32 v[84:85], v[84:85], v[80:81], v[88:89] op_sel:[1,1,0] op_sel_hi:[1,0,1] neg_lo:[0,1,0]
	v_pk_mul_f32 v[88:89], v[90:91], v[84:85] op_sel:[0,0] op_sel_hi:[0,1]
	v_pk_fma_f32 v[88:89], v[90:91], v[84:85], v[88:89] op_sel:[1,1,0] op_sel_hi:[1,0,1] neg_lo:[0,1,0]
	v_pk_mul_f32 v[90:91], v[84:85], v[80:81] op_sel:[0,0] op_sel_hi:[0,1]
	v_pk_fma_f32 v[84:85], v[84:85], v[80:81], v[90:91] op_sel:[1,1,0] op_sel_hi:[1,0,1] neg_lo:[0,1,0]
	v_pk_mul_f32 v[90:91], v[82:83], v[84:85] op_sel:[0,0] op_sel_hi:[0,1]
	v_pk_fma_f32 v[82:83], v[82:83], v[84:85], v[90:91] op_sel:[1,1,0] op_sel_hi:[1,0,1] neg_lo:[0,1,0]
	ds_write2_b64 v146, v[88:89], v[82:83] offset0:170 offset1:187
	v_pk_mul_f32 v[82:83], v[84:85], v[80:81] op_sel:[0,0] op_sel_hi:[0,1]
	v_pk_fma_f32 v[82:83], v[84:85], v[80:81], v[82:83] op_sel:[1,1,0] op_sel_hi:[1,0,1] neg_lo:[0,1,0]
	v_pk_mul_f32 v[84:85], v[100:101], v[82:83] op_sel:[0,0] op_sel_hi:[0,1]
	v_pk_mul_f32 v[88:89], v[82:83], v[80:81] op_sel:[0,0] op_sel_hi:[0,1]
	v_pk_fma_f32 v[84:85], v[100:101], v[82:83], v[84:85] op_sel:[1,1,0] op_sel_hi:[1,0,1] neg_lo:[0,1,0]
	v_pk_fma_f32 v[82:83], v[82:83], v[80:81], v[88:89] op_sel:[1,1,0] op_sel_hi:[1,0,1] neg_lo:[0,1,0]
	v_pk_mul_f32 v[88:89], v[92:93], v[82:83] op_sel:[0,0] op_sel_hi:[0,1]
	v_pk_fma_f32 v[88:89], v[92:93], v[82:83], v[88:89] op_sel:[1,1,0] op_sel_hi:[1,0,1] neg_lo:[0,1,0]
	ds_write2_b64 v146, v[84:85], v[88:89] offset0:204 offset1:221
	v_pk_mul_f32 v[84:85], v[82:83], v[80:81] op_sel:[0,0] op_sel_hi:[0,1]
	v_pk_fma_f32 v[82:83], v[82:83], v[80:81], v[84:85] op_sel:[1,1,0] op_sel_hi:[1,0,1] neg_lo:[0,1,0]
	v_pk_mul_f32 v[84:85], v[86:87], v[82:83] op_sel:[0,0] op_sel_hi:[0,1]
	v_pk_fma_f32 v[84:85], v[86:87], v[82:83], v[84:85] op_sel:[1,1,0] op_sel_hi:[1,0,1] neg_lo:[0,1,0]
	v_pk_mul_f32 v[86:87], v[82:83], v[80:81] op_sel:[0,0] op_sel_hi:[0,1]
	v_pk_fma_f32 v[80:81], v[82:83], v[80:81], v[86:87] op_sel:[1,1,0] op_sel_hi:[1,0,1] neg_lo:[0,1,0]
	v_pk_mul_f32 v[82:83], v[78:79], v[80:81] op_sel:[0,0] op_sel_hi:[0,1]
	v_pk_fma_f32 v[78:79], v[78:79], v[80:81], v[82:83] op_sel:[1,1,0] op_sel_hi:[1,0,1] neg_lo:[0,1,0]
	ds_write2_b64 v146, v[84:85], v[78:79] offset0:238 offset1:255
	s_waitcnt lgkmcnt(0)
	s_barrier
	ds_read2_b64 v[78:81], v147 offset1:1
	ds_read2_b64 v[82:85], v147 offset0:2 offset1:3
	ds_read2_b64 v[86:89], v147 offset0:8 offset1:9
	ds_read2_b64 v[90:93], v147 offset0:4 offset1:5
	ds_read2_b64 v[96:99], v147 offset0:6 offset1:7
	ds_read2_b64 v[100:103], v147 offset0:12 offset1:13
	ds_read2_b64 v[104:107], v147 offset0:10 offset1:11
	ds_read2_b64 v[108:111], v147 offset0:14 offset1:15
	s_waitcnt lgkmcnt(5)
	v_pk_add_f32 v[112:113], v[78:79], v[86:87]
	v_pk_add_f32 v[78:79], v[78:79], v[86:87] neg_lo:[0,1] neg_hi:[0,1]
	s_waitcnt lgkmcnt(2)
	v_pk_add_f32 v[86:87], v[90:91], v[100:101]
	v_pk_add_f32 v[90:91], v[90:91], v[100:101] neg_lo:[0,1] neg_hi:[0,1]
	v_pk_add_f32 v[100:101], v[112:113], v[86:87]
	v_pk_add_f32 v[86:87], v[112:113], v[86:87] neg_lo:[0,1] neg_hi:[0,1]
	v_pk_add_f32 v[112:113], v[78:79], v[90:91] op_sel:[0,1] op_sel_hi:[1,0] neg_hi:[0,1]
	v_pk_add_f32 v[78:79], v[78:79], v[90:91] op_sel:[0,1] op_sel_hi:[1,0] neg_lo:[0,1]
	v_pk_add_f32 v[90:91], v[80:81], v[88:89]
	v_pk_add_f32 v[80:81], v[80:81], v[88:89] neg_lo:[0,1] neg_hi:[0,1]
	v_pk_add_f32 v[88:89], v[92:93], v[102:103]
	v_pk_add_f32 v[92:93], v[92:93], v[102:103] neg_lo:[0,1] neg_hi:[0,1]
	v_pk_add_f32 v[102:103], v[90:91], v[88:89]
	v_pk_add_f32 v[88:89], v[90:91], v[88:89] neg_lo:[0,1] neg_hi:[0,1]
	v_pk_add_f32 v[90:91], v[80:81], v[92:93] op_sel:[0,1] op_sel_hi:[1,0] neg_hi:[0,1]
	v_pk_add_f32 v[80:81], v[80:81], v[92:93] op_sel:[0,1] op_sel_hi:[1,0] neg_lo:[0,1]
	s_waitcnt lgkmcnt(1)
	v_pk_add_f32 v[92:93], v[82:83], v[104:105]
	v_pk_add_f32 v[82:83], v[82:83], v[104:105] neg_lo:[0,1] neg_hi:[0,1]
	s_waitcnt lgkmcnt(0)
	v_pk_add_f32 v[104:105], v[96:97], v[108:109]
	v_pk_add_f32 v[96:97], v[96:97], v[108:109] neg_lo:[0,1] neg_hi:[0,1]
	v_pk_add_f32 v[108:109], v[92:93], v[104:105]
	v_pk_add_f32 v[92:93], v[92:93], v[104:105] neg_lo:[0,1] neg_hi:[0,1]
	v_pk_add_f32 v[104:105], v[82:83], v[96:97] op_sel:[0,1] op_sel_hi:[1,0] neg_hi:[0,1]
	v_pk_add_f32 v[82:83], v[82:83], v[96:97] op_sel:[0,1] op_sel_hi:[1,0] neg_lo:[0,1]
	v_pk_add_f32 v[96:97], v[84:85], v[106:107]
	v_pk_add_f32 v[84:85], v[84:85], v[106:107] neg_lo:[0,1] neg_hi:[0,1]
	v_pk_add_f32 v[106:107], v[98:99], v[110:111]
	v_pk_add_f32 v[98:99], v[98:99], v[110:111] neg_lo:[0,1] neg_hi:[0,1]
	v_pk_add_f32 v[110:111], v[96:97], v[106:107]
	v_pk_add_f32 v[96:97], v[96:97], v[106:107] neg_lo:[0,1] neg_hi:[0,1]
	v_pk_add_f32 v[106:107], v[84:85], v[98:99] op_sel:[0,1] op_sel_hi:[1,0] neg_hi:[0,1]
	v_pk_add_f32 v[84:85], v[84:85], v[98:99] op_sel:[0,1] op_sel_hi:[1,0] neg_lo:[0,1]
	v_pk_mul_f32 v[98:99], v[90:91], s[20:21] op_sel:[0,0] op_sel_hi:[0,1]
	v_pk_fma_f32 v[72:73], v[90:91], s[20:21], v[98:99] op_sel:[1,1,0] op_sel_hi:[1,0,1] neg_lo:[0,1,0]
	v_pk_mul_f32 v[90:91], v[104:105], s[50:51] op_sel:[0,0] op_sel_hi:[0,1]
	v_pk_mul_f32 v[98:99], v[106:107], s[54:55] op_sel:[0,0] op_sel_hi:[0,1]
	v_pk_fma_f32 v[90:91], v[104:105], s[50:51], v[90:91] op_sel:[1,1,0] op_sel_hi:[1,0,1] neg_lo:[0,1,0]
	v_pk_mul_f32 v[104:105], v[88:89], s[50:51] op_sel:[0,0] op_sel_hi:[0,1]
	v_pk_fma_f32 v[98:99], v[106:107], s[54:55], v[98:99] op_sel:[1,1,0] op_sel_hi:[1,0,1] neg_lo:[0,1,0]
	v_pk_fma_f32 v[68:69], v[88:89], s[50:51], v[104:105] op_sel:[1,1,0] op_sel_hi:[1,0,1] neg_lo:[0,1,0]
	v_pk_mul_f32 v[88:89], v[92:93], s[14:15] op_sel:[0,0] op_sel_hi:[0,1]
	v_pk_fma_f32 v[74:75], v[92:93], s[14:15], v[88:89] op_sel:[1,1,0] op_sel_hi:[1,0,1] neg_lo:[0,1,0]
	v_pk_mul_f32 v[88:89], v[96:97], s[58:59] op_sel:[0,0] op_sel_hi:[0,1]
	v_pk_mul_f32 v[92:93], v[80:81], s[54:55] op_sel:[0,0] op_sel_hi:[0,1]
	v_pk_fma_f32 v[66:67], v[80:81], s[54:55], v[92:93] op_sel:[1,1,0] op_sel_hi:[1,0,1] neg_lo:[0,1,0]
	v_pk_mul_f32 v[80:81], v[82:83], s[58:59] op_sel:[0,0] op_sel_hi:[0,1]
	v_pk_fma_f32 v[88:89], v[96:97], s[58:59], v[88:89] op_sel:[1,1,0] op_sel_hi:[1,0,1] neg_lo:[0,1,0]
	v_pk_add_f32 v[92:93], v[102:103], v[110:111] neg_lo:[0,1] neg_hi:[0,1]
	v_pk_fma_f32 v[70:71], v[82:83], s[58:59], v[80:81] op_sel:[1,1,0] op_sel_hi:[1,0,1] neg_lo:[0,1,0]
	v_pk_mul_f32 v[80:81], v[84:85], s[60:61] op_sel:[0,0] op_sel_hi:[0,1]
	v_pk_add_f32 v[82:83], v[100:101], v[108:109] neg_lo:[0,1] neg_hi:[0,1]
	v_pk_fma_f32 v[76:77], v[84:85], s[60:61], v[80:81] op_sel:[1,1,0] op_sel_hi:[1,0,1] neg_lo:[0,1,0]
	v_pk_add_f32 v[80:81], v[100:101], v[108:109]
	v_pk_add_f32 v[84:85], v[102:103], v[110:111]
	v_pk_add_f32 v[100:101], v[72:73], v[98:99]
	v_pk_add_f32 v[96:97], v[80:81], v[84:85]
	v_pk_add_f32 v[80:81], v[80:81], v[84:85] neg_lo:[0,1] neg_hi:[0,1]
	v_pk_add_f32 v[84:85], v[82:83], v[92:93] op_sel:[0,1] op_sel_hi:[1,0] neg_hi:[0,1]
	v_pk_add_f32 v[82:83], v[82:83], v[92:93] op_sel:[0,1] op_sel_hi:[1,0] neg_lo:[0,1]
	v_pk_add_f32 v[92:93], v[112:113], v[90:91]
	v_pk_add_f32 v[90:91], v[112:113], v[90:91] neg_lo:[0,1] neg_hi:[0,1]
	v_pk_add_f32 v[72:73], v[72:73], v[98:99] neg_lo:[0,1] neg_hi:[0,1]
	v_pk_add_f32 v[98:99], v[92:93], v[100:101]
	v_pk_add_f32 v[92:93], v[92:93], v[100:101] neg_lo:[0,1] neg_hi:[0,1]
	v_pk_add_f32 v[100:101], v[90:91], v[72:73] op_sel:[0,1] op_sel_hi:[1,0] neg_hi:[0,1]
	v_pk_add_f32 v[72:73], v[90:91], v[72:73] op_sel:[0,1] op_sel_hi:[1,0] neg_lo:[0,1]
	v_pk_add_f32 v[90:91], v[86:87], v[74:75]
	v_pk_add_f32 v[74:75], v[86:87], v[74:75] neg_lo:[0,1] neg_hi:[0,1]
	v_pk_add_f32 v[86:87], v[68:69], v[88:89]
	v_pk_add_f32 v[68:69], v[68:69], v[88:89] neg_lo:[0,1] neg_hi:[0,1]
	v_pk_add_f32 v[88:89], v[90:91], v[86:87]
	v_pk_add_f32 v[86:87], v[90:91], v[86:87] neg_lo:[0,1] neg_hi:[0,1]
	v_pk_add_f32 v[90:91], v[74:75], v[68:69] op_sel:[0,1] op_sel_hi:[1,0] neg_hi:[0,1]
	v_pk_add_f32 v[68:69], v[74:75], v[68:69] op_sel:[0,1] op_sel_hi:[1,0] neg_lo:[0,1]
	v_pk_add_f32 v[74:75], v[78:79], v[70:71]
	v_pk_add_f32 v[70:71], v[78:79], v[70:71] neg_lo:[0,1] neg_hi:[0,1]
	v_pk_add_f32 v[78:79], v[66:67], v[76:77]
	v_pk_add_f32 v[66:67], v[66:67], v[76:77] neg_lo:[0,1] neg_hi:[0,1]
	v_pk_add_f32 v[76:77], v[74:75], v[78:79]
	v_pk_add_f32 v[74:75], v[74:75], v[78:79] neg_lo:[0,1] neg_hi:[0,1]
	v_pk_add_f32 v[78:79], v[70:71], v[66:67] op_sel:[0,1] op_sel_hi:[1,0] neg_hi:[0,1]
	v_pk_add_f32 v[66:67], v[70:71], v[66:67] op_sel:[0,1] op_sel_hi:[1,0] neg_lo:[0,1]
	v_pk_mul_f32 v[70:71], v[96:97], v[56:57] op_sel:[0,0] op_sel_hi:[0,1]
	v_pk_fma_f32 v[56:57], v[96:97], v[56:57], v[70:71] op_sel:[1,1,0] op_sel_hi:[1,0,1] neg_lo:[0,1,0]
	v_pk_mul_f32 v[70:71], v[84:85], v[64:65] op_sel:[0,0] op_sel_hi:[0,1]
	v_pk_fma_f32 v[64:65], v[84:85], v[64:65], v[70:71] op_sel:[1,1,0] op_sel_hi:[1,0,1] neg_lo:[0,1,0]
	v_pk_mul_f32 v[70:71], v[80:81], v[60:61] op_sel:[0,0] op_sel_hi:[0,1]
	v_pk_fma_f32 v[60:61], v[80:81], v[60:61], v[70:71] op_sel:[1,1,0] op_sel_hi:[1,0,1] neg_lo:[0,1,0]
	v_pk_mul_f32 v[70:71], v[82:83], v[62:63] op_sel:[0,0] op_sel_hi:[0,1]
	v_pk_fma_f32 v[62:63], v[82:83], v[62:63], v[70:71] op_sel:[1,1,0] op_sel_hi:[1,0,1] neg_lo:[0,1,0]
	v_pk_mul_f32 v[70:71], v[98:99], v[48:49] op_sel:[0,0] op_sel_hi:[0,1]
	v_pk_fma_f32 v[48:49], v[98:99], v[48:49], v[70:71] op_sel:[1,1,0] op_sel_hi:[1,0,1] neg_lo:[0,1,0]
	v_pk_mul_f32 v[70:71], v[100:101], v[58:59] op_sel:[0,0] op_sel_hi:[0,1]
	v_pk_fma_f32 v[58:59], v[100:101], v[58:59], v[70:71] op_sel:[1,1,0] op_sel_hi:[1,0,1] neg_lo:[0,1,0]
	v_pk_mul_f32 v[70:71], v[92:93], v[52:53] op_sel:[0,0] op_sel_hi:[0,1]
	v_pk_fma_f32 v[52:53], v[92:93], v[52:53], v[70:71] op_sel:[1,1,0] op_sel_hi:[1,0,1] neg_lo:[0,1,0]
	v_pk_mul_f32 v[70:71], v[72:73], v[54:55] op_sel:[0,0] op_sel_hi:[0,1]
	v_pk_fma_f32 v[54:55], v[72:73], v[54:55], v[70:71] op_sel:[1,1,0] op_sel_hi:[1,0,1] neg_lo:[0,1,0]
	v_pk_mul_f32 v[70:71], v[88:89], v[32:33] op_sel:[0,0] op_sel_hi:[0,1]
	v_pk_fma_f32 v[32:33], v[88:89], v[32:33], v[70:71] op_sel:[1,1,0] op_sel_hi:[1,0,1] neg_lo:[0,1,0]
	v_pk_mul_f32 v[70:71], v[90:91], v[50:51] op_sel:[0,0] op_sel_hi:[0,1]
	v_pk_fma_f32 v[50:51], v[90:91], v[50:51], v[70:71] op_sel:[1,1,0] op_sel_hi:[1,0,1] neg_lo:[0,1,0]
	v_pk_mul_f32 v[70:71], v[86:87], v[44:45] op_sel:[0,0] op_sel_hi:[0,1]
	v_pk_fma_f32 v[44:45], v[86:87], v[44:45], v[70:71] op_sel:[1,1,0] op_sel_hi:[1,0,1] neg_lo:[0,1,0]
	v_pk_mul_f32 v[70:71], v[68:69], v[46:47] op_sel:[0,0] op_sel_hi:[0,1]
	v_pk_fma_f32 v[46:47], v[68:69], v[46:47], v[70:71] op_sel:[1,1,0] op_sel_hi:[1,0,1] neg_lo:[0,1,0]
	v_pk_mul_f32 v[68:69], v[76:77], v[26:27] op_sel:[0,0] op_sel_hi:[0,1]
	v_pk_fma_f32 v[26:27], v[76:77], v[26:27], v[68:69] op_sel:[1,1,0] op_sel_hi:[1,0,1] neg_lo:[0,1,0]
	v_pk_mul_f32 v[68:69], v[78:79], v[42:43] op_sel:[0,0] op_sel_hi:[0,1]
	v_pk_fma_f32 v[42:43], v[78:79], v[42:43], v[68:69] op_sel:[1,1,0] op_sel_hi:[1,0,1] neg_lo:[0,1,0]
	v_pk_mul_f32 v[68:69], v[74:75], v[28:29] op_sel:[0,0] op_sel_hi:[0,1]
	v_pk_fma_f32 v[28:29], v[74:75], v[28:29], v[68:69] op_sel:[1,1,0] op_sel_hi:[1,0,1] neg_lo:[0,1,0]
	v_pk_mul_f32 v[68:69], v[66:67], v[30:31] op_sel:[0,0] op_sel_hi:[0,1]
	v_pk_fma_f32 v[30:31], v[66:67], v[30:31], v[68:69] op_sel:[1,1,0] op_sel_hi:[1,0,1] neg_lo:[0,1,0]
	s_cbranch_scc1 .LBB0_1413
	s_mul_i32 s83, s0, 0x4400
	s_mul_hi_u32 s1, s0, 0x4400
	s_add_u32 s28, s11, s83
	s_addc_u32 s29, s10, s1
	s_add_i32 s1, s0, 0x400
	s_add_i32 s87, s83, 0x1100000
	s_mul_hi_u32 s1, s1, 0x4400
	v_lshlrev_b32_e32 v2, 3, v145
	s_add_u32 s92, s11, s87
	v_ashrrev_i32_e32 v3, 31, v2
	s_addc_u32 s93, s10, s1
	s_addk_i32 s0, 0x800
	s_add_i32 s83, s83, 0x2200000
	v_lshlrev_b64 v[18:19], 1, v[2:3]
	v_add_u32_e32 v2, 0x1000, v2
	s_mul_hi_u32 s1, s0, 0x4400
	s_add_u32 s0, s11, s83
	v_ashrrev_i32_e32 v3, 31, v2
	s_addc_u32 s1, s10, s1
	v_lshlrev_b64 v[20:21], 1, v[2:3]
	v_lshl_add_u64 v[4:5], s[28:29], 0, v[18:19]
	v_lshl_add_u64 v[6:7], s[28:29], 0, v[20:21]
	v_lshl_add_u64 v[10:11], s[92:93], 0, v[18:19]
	v_lshl_add_u64 v[14:15], s[92:93], 0, v[20:21]
	v_lshl_add_u64 v[18:19], s[0:1], 0, v[18:19]
	v_lshl_add_u64 v[22:23], s[0:1], 0, v[20:21]
	global_load_dwordx4 v[2:5], v[4:5], off
	s_nop 0
	global_load_dwordx4 v[6:9], v[6:7], off
	s_nop 0
	global_load_dwordx4 v[10:13], v[10:11], off
	s_nop 0
	global_load_dwordx4 v[14:17], v[14:15], off
	s_nop 0
	global_load_dwordx4 v[18:21], v[18:19], off
	s_nop 0
	global_load_dwordx4 v[22:25], v[22:23], off
.LBB0_1413:
	v_pk_add_f32 v[66:67], v[56:57], v[60:61]
	v_pk_add_f32 v[56:57], v[56:57], v[60:61] neg_lo:[0,1] neg_hi:[0,1]
	v_pk_add_f32 v[60:61], v[64:65], v[62:63]
	v_pk_add_f32 v[62:63], v[64:65], v[62:63] neg_lo:[0,1] neg_hi:[0,1]
	v_pk_add_f32 v[64:65], v[66:67], v[60:61]
	v_pk_add_f32 v[60:61], v[66:67], v[60:61] neg_lo:[0,1] neg_hi:[0,1]
	v_pk_add_f32 v[66:67], v[56:57], v[62:63] op_sel:[0,1] op_sel_hi:[1,0] neg_lo:[0,1]
	v_pk_add_f32 v[56:57], v[56:57], v[62:63] op_sel:[0,1] op_sel_hi:[1,0] neg_hi:[0,1]
	v_pk_add_f32 v[62:63], v[48:49], v[52:53]
	v_pk_add_f32 v[48:49], v[48:49], v[52:53] neg_lo:[0,1] neg_hi:[0,1]
	v_pk_add_f32 v[52:53], v[58:59], v[54:55]
	v_pk_add_f32 v[54:55], v[58:59], v[54:55] neg_lo:[0,1] neg_hi:[0,1]
	v_pk_add_f32 v[58:59], v[62:63], v[52:53]
	v_pk_add_f32 v[52:53], v[62:63], v[52:53] neg_lo:[0,1] neg_hi:[0,1]
	v_pk_add_f32 v[62:63], v[48:49], v[54:55] op_sel:[0,1] op_sel_hi:[1,0] neg_lo:[0,1]
	v_pk_add_f32 v[48:49], v[48:49], v[54:55] op_sel:[0,1] op_sel_hi:[1,0] neg_hi:[0,1]
	v_pk_add_f32 v[54:55], v[32:33], v[44:45]
	v_pk_add_f32 v[32:33], v[32:33], v[44:45] neg_lo:[0,1] neg_hi:[0,1]
	v_pk_add_f32 v[44:45], v[50:51], v[46:47]
	v_pk_add_f32 v[46:47], v[50:51], v[46:47] neg_lo:[0,1] neg_hi:[0,1]
	v_pk_add_f32 v[50:51], v[54:55], v[44:45]
	v_pk_add_f32 v[44:45], v[54:55], v[44:45] neg_lo:[0,1] neg_hi:[0,1]
	v_pk_add_f32 v[54:55], v[32:33], v[46:47] op_sel:[0,1] op_sel_hi:[1,0] neg_lo:[0,1]
	v_pk_add_f32 v[46:47], v[32:33], v[46:47] op_sel:[0,1] op_sel_hi:[1,0] neg_hi:[0,1]
	v_pk_add_f32 v[32:33], v[26:27], v[28:29]
	v_pk_add_f32 v[26:27], v[26:27], v[28:29] neg_lo:[0,1] neg_hi:[0,1]
	v_pk_add_f32 v[28:29], v[42:43], v[30:31]
	v_pk_add_f32 v[30:31], v[42:43], v[30:31] neg_lo:[0,1] neg_hi:[0,1]
	v_pk_add_f32 v[68:69], v[32:33], v[28:29]
	v_pk_add_f32 v[70:71], v[32:33], v[28:29] neg_lo:[0,1] neg_hi:[0,1]
	v_pk_add_f32 v[42:43], v[26:27], v[30:31] op_sel:[0,1] op_sel_hi:[1,0] neg_lo:[0,1]
	v_pk_add_f32 v[72:73], v[26:27], v[30:31] op_sel:[0,1] op_sel_hi:[1,0] neg_hi:[0,1]
	v_pk_mul_f32 v[26:27], v[62:63], s[62:63] op_sel:[0,0] op_sel_hi:[0,1]
	v_pk_fma_f32 v[62:63], v[62:63], s[62:63], v[26:27] op_sel:[1,1,0] op_sel_hi:[1,0,1] neg_lo:[0,1,0]
	v_pk_mul_f32 v[26:27], v[54:55], s[64:65] op_sel:[0,0] op_sel_hi:[0,1]
	v_pk_fma_f32 v[54:55], v[54:55], s[64:65], v[26:27] op_sel:[1,1,0] op_sel_hi:[1,0,1] neg_lo:[0,1,0]
	v_pk_mul_f32 v[30:31], v[42:43], s[66:67] op_sel:[0,0] op_sel_hi:[0,1]
	v_pk_fma_f32 v[74:75], v[42:43], s[66:67], v[30:31] op_sel:[1,1,0] op_sel_hi:[1,0,1] neg_lo:[0,1,0]
	v_pk_mul_f32 v[30:31], v[52:53], s[64:65] op_sel:[0,0] op_sel_hi:[0,1]
	v_pk_fma_f32 v[52:53], v[52:53], s[64:65], v[30:31] op_sel:[1,1,0] op_sel_hi:[1,0,1] neg_lo:[0,1,0]
	v_pk_mul_f32 v[30:31], v[44:45], s[68:69] op_sel:[0,0] op_sel_hi:[0,1]
	v_pk_fma_f32 v[76:77], v[44:45], s[68:69], v[30:31] op_sel:[1,1,0] op_sel_hi:[1,0,1] neg_lo:[0,1,0]
	v_pk_mul_f32 v[44:45], v[70:71], s[70:71] op_sel:[0,0] op_sel_hi:[0,1]
	v_pk_fma_f32 v[70:71], v[70:71], s[70:71], v[44:45] op_sel:[1,1,0] op_sel_hi:[1,0,1] neg_lo:[0,1,0]
	v_pk_mul_f32 v[44:45], v[48:49], s[66:67] op_sel:[0,0] op_sel_hi:[0,1]
	v_pk_fma_f32 v[48:49], v[48:49], s[66:67], v[44:45] op_sel:[1,1,0] op_sel_hi:[1,0,1] neg_lo:[0,1,0]
	v_pk_mul_f32 v[44:45], v[46:47], s[70:71] op_sel:[0,0] op_sel_hi:[0,1]
	v_pk_fma_f32 v[46:47], v[46:47], s[70:71], v[44:45] op_sel:[1,1,0] op_sel_hi:[1,0,1] neg_lo:[0,1,0]
	v_pk_mul_f32 v[78:79], v[72:73], s[72:73] op_sel:[0,0] op_sel_hi:[0,1]
	v_pk_fma_f32 v[72:73], v[72:73], s[72:73], v[78:79] op_sel:[1,1,0] op_sel_hi:[1,0,1] neg_lo:[0,1,0]
	v_pk_add_f32 v[78:79], v[64:65], v[50:51]
	v_pk_add_f32 v[50:51], v[64:65], v[50:51] neg_lo:[0,1] neg_hi:[0,1]
	v_pk_add_f32 v[64:65], v[58:59], v[68:69]
	v_pk_add_f32 v[58:59], v[58:59], v[68:69] neg_lo:[0,1] neg_hi:[0,1]
	v_pk_add_f32 v[68:69], v[78:79], v[64:65]
	v_pk_add_f32 v[64:65], v[78:79], v[64:65] neg_lo:[0,1] neg_hi:[0,1]
	v_pk_add_f32 v[78:79], v[50:51], v[58:59] op_sel:[0,1] op_sel_hi:[1,0] neg_lo:[0,1]
	v_pk_add_f32 v[50:51], v[50:51], v[58:59] op_sel:[0,1] op_sel_hi:[1,0] neg_hi:[0,1]
	v_pk_add_f32 v[58:59], v[66:67], v[54:55]
	v_pk_add_f32 v[54:55], v[66:67], v[54:55] neg_lo:[0,1] neg_hi:[0,1]
	v_pk_add_f32 v[66:67], v[62:63], v[74:75]
	v_pk_add_f32 v[62:63], v[62:63], v[74:75] neg_lo:[0,1] neg_hi:[0,1]
	v_pk_add_f32 v[74:75], v[58:59], v[66:67]
	v_pk_add_f32 v[58:59], v[58:59], v[66:67] neg_lo:[0,1] neg_hi:[0,1]
	v_pk_add_f32 v[66:67], v[54:55], v[62:63] op_sel:[0,1] op_sel_hi:[1,0] neg_lo:[0,1]
	v_pk_add_f32 v[54:55], v[54:55], v[62:63] op_sel:[0,1] op_sel_hi:[1,0] neg_hi:[0,1]
	v_pk_add_f32 v[62:63], v[60:61], v[76:77]
	v_pk_add_f32 v[60:61], v[60:61], v[76:77] neg_lo:[0,1] neg_hi:[0,1]
	v_pk_add_f32 v[76:77], v[52:53], v[70:71]
	v_pk_add_f32 v[52:53], v[52:53], v[70:71] neg_lo:[0,1] neg_hi:[0,1]
	v_pk_add_f32 v[70:71], v[62:63], v[76:77]
	v_pk_add_f32 v[62:63], v[62:63], v[76:77] neg_lo:[0,1] neg_hi:[0,1]
	v_pk_add_f32 v[76:77], v[60:61], v[52:53] op_sel:[0,1] op_sel_hi:[1,0] neg_lo:[0,1]
	v_pk_add_f32 v[52:53], v[60:61], v[52:53] op_sel:[0,1] op_sel_hi:[1,0] neg_hi:[0,1]
	v_pk_add_f32 v[60:61], v[56:57], v[46:47]
	v_pk_add_f32 v[46:47], v[56:57], v[46:47] neg_lo:[0,1] neg_hi:[0,1]
	v_pk_add_f32 v[56:57], v[48:49], v[72:73]
	v_pk_add_f32 v[48:49], v[48:49], v[72:73] neg_lo:[0,1] neg_hi:[0,1]
	v_pk_add_f32 v[72:73], v[60:61], v[56:57]
	v_pk_add_f32 v[56:57], v[60:61], v[56:57] neg_lo:[0,1] neg_hi:[0,1]
	v_pk_add_f32 v[60:61], v[46:47], v[48:49] op_sel:[0,1] op_sel_hi:[1,0] neg_lo:[0,1]
	v_pk_add_f32 v[46:47], v[46:47], v[48:49] op_sel:[0,1] op_sel_hi:[1,0] neg_hi:[0,1]
	ds_write2_b64 v147, v[68:69], v[74:75] offset1:1
	ds_write2_b64 v147, v[70:71], v[72:73] offset0:2 offset1:3
	ds_write2_b64 v147, v[78:79], v[66:67] offset0:4 offset1:5
	ds_write2_b64 v147, v[76:77], v[60:61] offset0:6 offset1:7
	ds_write2_b64 v147, v[64:65], v[58:59] offset0:8 offset1:9
	ds_write2_b64 v147, v[62:63], v[56:57] offset0:10 offset1:11
	ds_write2_b64 v147, v[50:51], v[54:55] offset0:12 offset1:13
	ds_write2_b64 v147, v[52:53], v[46:47] offset0:14 offset1:15
	s_waitcnt lgkmcnt(0)
	s_barrier
	ds_read2_b64 v[46:49], v146 offset1:17
	ds_read2_b64 v[50:53], v146 offset0:34 offset1:51
	s_waitcnt lgkmcnt(1)
	v_pk_mul_f32 v[54:55], v[48:49], v[40:41] op_sel:[0,0] op_sel_hi:[0,1] neg_hi:[0,1]
	v_pk_fma_f32 v[56:57], v[48:49], v[40:41], v[54:55] op_sel:[1,1,0] op_sel_hi:[1,0,1]
	v_pk_mul_f32 v[48:49], v[40:41], v[40:41] op_sel:[0,0] op_sel_hi:[0,1]
	v_pk_fma_f32 v[48:49], v[40:41], v[40:41], v[48:49] op_sel:[1,1,0] op_sel_hi:[1,0,1] neg_lo:[0,1,0]
	s_waitcnt lgkmcnt(0)
	v_pk_mul_f32 v[54:55], v[50:51], v[48:49] op_sel:[0,0] op_sel_hi:[0,1] neg_hi:[0,1]
	v_pk_fma_f32 v[58:59], v[50:51], v[48:49], v[54:55] op_sel:[1,1,0] op_sel_hi:[1,0,1]
	v_pk_mul_f32 v[50:51], v[48:49], v[40:41] op_sel:[0,0] op_sel_hi:[0,1]
	v_pk_fma_f32 v[54:55], v[48:49], v[40:41], v[50:51] op_sel:[1,1,0] op_sel_hi:[1,0,1] neg_lo:[0,1,0]
	ds_read2_b64 v[48:51], v146 offset0:68 offset1:85
	v_pk_mul_f32 v[60:61], v[52:53], v[54:55] op_sel:[0,0] op_sel_hi:[0,1] neg_hi:[0,1]
	v_pk_fma_f32 v[60:61], v[52:53], v[54:55], v[60:61] op_sel:[1,1,0] op_sel_hi:[1,0,1]
	v_pk_mul_f32 v[52:53], v[54:55], v[40:41] op_sel:[0,0] op_sel_hi:[0,1]
	v_pk_fma_f32 v[52:53], v[54:55], v[40:41], v[52:53] op_sel:[1,1,0] op_sel_hi:[1,0,1] neg_lo:[0,1,0]
	s_waitcnt lgkmcnt(0)
	v_pk_mul_f32 v[54:55], v[48:49], v[52:53] op_sel:[0,0] op_sel_hi:[0,1] neg_hi:[0,1]
	v_pk_fma_f32 v[62:63], v[48:49], v[52:53], v[54:55] op_sel:[1,1,0] op_sel_hi:[1,0,1]
	v_pk_mul_f32 v[48:49], v[52:53], v[40:41] op_sel:[0,0] op_sel_hi:[0,1]
	v_pk_fma_f32 v[48:49], v[52:53], v[40:41], v[48:49] op_sel:[1,1,0] op_sel_hi:[1,0,1] neg_lo:[0,1,0]
	ds_read2_b64 v[52:55], v146 offset0:102 offset1:119
	v_pk_mul_f32 v[64:65], v[50:51], v[48:49] op_sel:[0,0] op_sel_hi:[0,1] neg_hi:[0,1]
	v_pk_fma_f32 v[64:65], v[50:51], v[48:49], v[64:65] op_sel:[1,1,0] op_sel_hi:[1,0,1]
	v_pk_mul_f32 v[50:51], v[48:49], v[40:41] op_sel:[0,0] op_sel_hi:[0,1]
	v_pk_fma_f32 v[48:49], v[48:49], v[40:41], v[50:51] op_sel:[1,1,0] op_sel_hi:[1,0,1] neg_lo:[0,1,0]
	s_waitcnt lgkmcnt(0)
	v_pk_mul_f32 v[50:51], v[52:53], v[48:49] op_sel:[0,0] op_sel_hi:[0,1] neg_hi:[0,1]
	v_pk_fma_f32 v[66:67], v[52:53], v[48:49], v[50:51] op_sel:[1,1,0] op_sel_hi:[1,0,1]
	v_pk_mul_f32 v[50:51], v[48:49], v[40:41] op_sel:[0,0] op_sel_hi:[0,1]
	v_pk_fma_f32 v[52:53], v[48:49], v[40:41], v[50:51] op_sel:[1,1,0] op_sel_hi:[1,0,1] neg_lo:[0,1,0]
	ds_read2_b64 v[48:51], v146 offset0:136 offset1:153
	v_pk_mul_f32 v[68:69], v[54:55], v[52:53] op_sel:[0,0] op_sel_hi:[0,1] neg_hi:[0,1]
	v_pk_fma_f32 v[68:69], v[54:55], v[52:53], v[68:69] op_sel:[1,1,0] op_sel_hi:[1,0,1]
	v_pk_mul_f32 v[54:55], v[52:53], v[40:41] op_sel:[0,0] op_sel_hi:[0,1]
	v_pk_fma_f32 v[52:53], v[52:53], v[40:41], v[54:55] op_sel:[1,1,0] op_sel_hi:[1,0,1] neg_lo:[0,1,0]
	s_waitcnt lgkmcnt(0)
	v_pk_mul_f32 v[54:55], v[48:49], v[52:53] op_sel:[0,0] op_sel_hi:[0,1] neg_hi:[0,1]
	v_pk_fma_f32 v[70:71], v[48:49], v[52:53], v[54:55] op_sel:[1,1,0] op_sel_hi:[1,0,1]
	v_pk_mul_f32 v[48:49], v[52:53], v[40:41] op_sel:[0,0] op_sel_hi:[0,1]
	v_pk_fma_f32 v[48:49], v[52:53], v[40:41], v[48:49] op_sel:[1,1,0] op_sel_hi:[1,0,1] neg_lo:[0,1,0]
	ds_read2_b64 v[52:55], v146 offset0:170 offset1:187
	v_pk_mul_f32 v[72:73], v[50:51], v[48:49] op_sel:[0,0] op_sel_hi:[0,1] neg_hi:[0,1]
	v_pk_fma_f32 v[72:73], v[50:51], v[48:49], v[72:73] op_sel:[1,1,0] op_sel_hi:[1,0,1]
	v_pk_mul_f32 v[50:51], v[48:49], v[40:41] op_sel:[0,0] op_sel_hi:[0,1]
	v_pk_fma_f32 v[48:49], v[48:49], v[40:41], v[50:51] op_sel:[1,1,0] op_sel_hi:[1,0,1] neg_lo:[0,1,0]
	s_waitcnt lgkmcnt(0)
	v_pk_mul_f32 v[50:51], v[52:53], v[48:49] op_sel:[0,0] op_sel_hi:[0,1] neg_hi:[0,1]
	v_pk_fma_f32 v[74:75], v[52:53], v[48:49], v[50:51] op_sel:[1,1,0] op_sel_hi:[1,0,1]
	v_pk_mul_f32 v[50:51], v[48:49], v[40:41] op_sel:[0,0] op_sel_hi:[0,1]
	v_pk_fma_f32 v[52:53], v[48:49], v[40:41], v[50:51] op_sel:[1,1,0] op_sel_hi:[1,0,1] neg_lo:[0,1,0]
	ds_read2_b64 v[48:51], v146 offset0:204 offset1:221
	v_pk_mul_f32 v[76:77], v[54:55], v[52:53] op_sel:[0,0] op_sel_hi:[0,1] neg_hi:[0,1]
	v_pk_fma_f32 v[76:77], v[54:55], v[52:53], v[76:77] op_sel:[1,1,0] op_sel_hi:[1,0,1]
	v_pk_mul_f32 v[54:55], v[52:53], v[40:41] op_sel:[0,0] op_sel_hi:[0,1]
	v_pk_fma_f32 v[52:53], v[52:53], v[40:41], v[54:55] op_sel:[1,1,0] op_sel_hi:[1,0,1] neg_lo:[0,1,0]
	s_waitcnt lgkmcnt(0)
	v_pk_mul_f32 v[54:55], v[48:49], v[52:53] op_sel:[0,0] op_sel_hi:[0,1] neg_hi:[0,1]
	v_pk_fma_f32 v[48:49], v[48:49], v[52:53], v[54:55] op_sel:[1,1,0] op_sel_hi:[1,0,1]
	v_pk_mul_f32 v[54:55], v[52:53], v[40:41] op_sel:[0,0] op_sel_hi:[0,1]
	v_pk_fma_f32 v[78:79], v[52:53], v[40:41], v[54:55] op_sel:[1,1,0] op_sel_hi:[1,0,1] neg_lo:[0,1,0]
	ds_read2_b64 v[52:55], v146 offset0:238 offset1:255
	v_pk_mul_f32 v[80:81], v[50:51], v[78:79] op_sel:[0,0] op_sel_hi:[0,1] neg_hi:[0,1]
	v_pk_fma_f32 v[50:51], v[50:51], v[78:79], v[80:81] op_sel:[1,1,0] op_sel_hi:[1,0,1]
	v_pk_mul_f32 v[80:81], v[78:79], v[40:41] op_sel:[0,0] op_sel_hi:[0,1]
	v_pk_fma_f32 v[78:79], v[78:79], v[40:41], v[80:81] op_sel:[1,1,0] op_sel_hi:[1,0,1] neg_lo:[0,1,0]
	s_waitcnt lgkmcnt(0)
	v_pk_mul_f32 v[80:81], v[52:53], v[78:79] op_sel:[0,0] op_sel_hi:[0,1] neg_hi:[0,1]
	v_pk_fma_f32 v[52:53], v[52:53], v[78:79], v[80:81] op_sel:[1,1,0] op_sel_hi:[1,0,1]
	v_pk_mul_f32 v[80:81], v[78:79], v[40:41] op_sel:[0,0] op_sel_hi:[0,1]
	v_pk_fma_f32 v[40:41], v[78:79], v[40:41], v[80:81] op_sel:[1,1,0] op_sel_hi:[1,0,1] neg_lo:[0,1,0]
	v_pk_mul_f32 v[78:79], v[54:55], v[40:41] op_sel:[0,0] op_sel_hi:[0,1] neg_hi:[0,1]
	v_pk_fma_f32 v[40:41], v[54:55], v[40:41], v[78:79] op_sel:[1,1,0] op_sel_hi:[1,0,1]
	v_pk_add_f32 v[54:55], v[46:47], v[70:71]
	v_pk_add_f32 v[46:47], v[46:47], v[70:71] neg_lo:[0,1] neg_hi:[0,1]
	v_pk_add_f32 v[70:71], v[62:63], v[48:49]
	v_pk_add_f32 v[48:49], v[62:63], v[48:49] neg_lo:[0,1] neg_hi:[0,1]
	v_pk_add_f32 v[62:63], v[54:55], v[70:71]
	v_pk_add_f32 v[54:55], v[54:55], v[70:71] neg_lo:[0,1] neg_hi:[0,1]
	v_pk_add_f32 v[70:71], v[46:47], v[48:49] op_sel:[0,1] op_sel_hi:[1,0] neg_lo:[0,1]
	v_pk_add_f32 v[46:47], v[46:47], v[48:49] op_sel:[0,1] op_sel_hi:[1,0] neg_hi:[0,1]
	v_pk_add_f32 v[48:49], v[56:57], v[72:73]
	v_pk_add_f32 v[56:57], v[56:57], v[72:73] neg_lo:[0,1] neg_hi:[0,1]
	v_pk_add_f32 v[72:73], v[64:65], v[50:51]
	v_pk_add_f32 v[50:51], v[64:65], v[50:51] neg_lo:[0,1] neg_hi:[0,1]
	v_pk_add_f32 v[64:65], v[48:49], v[72:73]
	v_pk_add_f32 v[48:49], v[48:49], v[72:73] neg_lo:[0,1] neg_hi:[0,1]
	v_pk_add_f32 v[72:73], v[56:57], v[50:51] op_sel:[0,1] op_sel_hi:[1,0] neg_lo:[0,1]
	v_pk_add_f32 v[50:51], v[56:57], v[50:51] op_sel:[0,1] op_sel_hi:[1,0] neg_hi:[0,1]
	v_pk_add_f32 v[56:57], v[58:59], v[74:75]
	v_pk_add_f32 v[58:59], v[58:59], v[74:75] neg_lo:[0,1] neg_hi:[0,1]
	v_pk_add_f32 v[74:75], v[66:67], v[52:53]
	v_pk_add_f32 v[52:53], v[66:67], v[52:53] neg_lo:[0,1] neg_hi:[0,1]
	v_pk_add_f32 v[66:67], v[56:57], v[74:75]
	v_pk_add_f32 v[56:57], v[56:57], v[74:75] neg_lo:[0,1] neg_hi:[0,1]
	v_pk_add_f32 v[74:75], v[58:59], v[52:53] op_sel:[0,1] op_sel_hi:[1,0] neg_lo:[0,1]
	v_pk_add_f32 v[52:53], v[58:59], v[52:53] op_sel:[0,1] op_sel_hi:[1,0] neg_hi:[0,1]
	v_pk_add_f32 v[58:59], v[60:61], v[76:77]
	v_pk_add_f32 v[60:61], v[60:61], v[76:77] neg_lo:[0,1] neg_hi:[0,1]
	v_pk_add_f32 v[76:77], v[68:69], v[40:41]
	v_pk_add_f32 v[40:41], v[68:69], v[40:41] neg_lo:[0,1] neg_hi:[0,1]
	v_pk_add_f32 v[68:69], v[58:59], v[76:77]
	v_pk_add_f32 v[58:59], v[58:59], v[76:77] neg_lo:[0,1] neg_hi:[0,1]
	v_pk_add_f32 v[76:77], v[60:61], v[40:41] op_sel:[0,1] op_sel_hi:[1,0] neg_lo:[0,1]
	v_pk_add_f32 v[40:41], v[60:61], v[40:41] op_sel:[0,1] op_sel_hi:[1,0] neg_hi:[0,1]
	v_pk_mul_f32 v[60:61], v[72:73], s[62:63] op_sel:[0,0] op_sel_hi:[0,1]
	v_pk_fma_f32 v[60:61], v[72:73], s[62:63], v[60:61] op_sel:[1,1,0] op_sel_hi:[1,0,1] neg_lo:[0,1,0]
	v_pk_mul_f32 v[72:73], v[74:75], s[64:65] op_sel:[0,0] op_sel_hi:[0,1]
	v_pk_fma_f32 v[72:73], v[74:75], s[64:65], v[72:73] op_sel:[1,1,0] op_sel_hi:[1,0,1] neg_lo:[0,1,0]
	v_pk_mul_f32 v[74:75], v[76:77], s[66:67] op_sel:[0,0] op_sel_hi:[0,1]
	v_pk_fma_f32 v[74:75], v[76:77], s[66:67], v[74:75] op_sel:[1,1,0] op_sel_hi:[1,0,1] neg_lo:[0,1,0]
	v_pk_mul_f32 v[76:77], v[48:49], s[64:65] op_sel:[0,0] op_sel_hi:[0,1]
	v_pk_fma_f32 v[48:49], v[48:49], s[64:65], v[76:77] op_sel:[1,1,0] op_sel_hi:[1,0,1] neg_lo:[0,1,0]
	v_pk_mul_f32 v[76:77], v[56:57], s[68:69] op_sel:[0,0] op_sel_hi:[0,1]
	v_pk_fma_f32 v[56:57], v[56:57], s[68:69], v[76:77] op_sel:[1,1,0] op_sel_hi:[1,0,1] neg_lo:[0,1,0]
	v_pk_mul_f32 v[76:77], v[58:59], s[70:71] op_sel:[0,0] op_sel_hi:[0,1]
	v_pk_fma_f32 v[58:59], v[58:59], s[70:71], v[76:77] op_sel:[1,1,0] op_sel_hi:[1,0,1] neg_lo:[0,1,0]
	v_pk_mul_f32 v[76:77], v[50:51], s[66:67] op_sel:[0,0] op_sel_hi:[0,1]
	v_pk_fma_f32 v[50:51], v[50:51], s[66:67], v[76:77] op_sel:[1,1,0] op_sel_hi:[1,0,1] neg_lo:[0,1,0]
	v_pk_mul_f32 v[76:77], v[52:53], s[70:71] op_sel:[0,0] op_sel_hi:[0,1]
	v_pk_fma_f32 v[52:53], v[52:53], s[70:71], v[76:77] op_sel:[1,1,0] op_sel_hi:[1,0,1] neg_lo:[0,1,0]
	v_pk_mul_f32 v[76:77], v[40:41], s[72:73] op_sel:[0,0] op_sel_hi:[0,1]
	v_pk_fma_f32 v[40:41], v[40:41], s[72:73], v[76:77] op_sel:[1,1,0] op_sel_hi:[1,0,1] neg_lo:[0,1,0]
	v_pk_add_f32 v[76:77], v[62:63], v[66:67]
	v_pk_add_f32 v[62:63], v[62:63], v[66:67] neg_lo:[0,1] neg_hi:[0,1]
	v_pk_add_f32 v[66:67], v[64:65], v[68:69]
	v_pk_add_f32 v[64:65], v[64:65], v[68:69] neg_lo:[0,1] neg_hi:[0,1]
	v_pk_add_f32 v[68:69], v[76:77], v[66:67]
	v_pk_add_f32 v[66:67], v[76:77], v[66:67] neg_lo:[0,1] neg_hi:[0,1]
	v_pk_add_f32 v[76:77], v[62:63], v[64:65] op_sel:[0,1] op_sel_hi:[1,0] neg_lo:[0,1]
	v_pk_add_f32 v[62:63], v[62:63], v[64:65] op_sel:[0,1] op_sel_hi:[1,0] neg_hi:[0,1]
	v_pk_add_f32 v[64:65], v[70:71], v[72:73]
	v_pk_add_f32 v[70:71], v[70:71], v[72:73] neg_lo:[0,1] neg_hi:[0,1]
	v_pk_add_f32 v[72:73], v[60:61], v[74:75]
	v_pk_add_f32 v[60:61], v[60:61], v[74:75] neg_lo:[0,1] neg_hi:[0,1]
	v_pk_add_f32 v[74:75], v[64:65], v[72:73]
	v_pk_add_f32 v[64:65], v[64:65], v[72:73] neg_lo:[0,1] neg_hi:[0,1]
	v_pk_add_f32 v[72:73], v[70:71], v[60:61] op_sel:[0,1] op_sel_hi:[1,0] neg_lo:[0,1]
	v_pk_add_f32 v[60:61], v[70:71], v[60:61] op_sel:[0,1] op_sel_hi:[1,0] neg_hi:[0,1]
	v_pk_add_f32 v[70:71], v[54:55], v[56:57]
	v_pk_add_f32 v[54:55], v[54:55], v[56:57] neg_lo:[0,1] neg_hi:[0,1]
	v_pk_add_f32 v[56:57], v[48:49], v[58:59]
	v_pk_add_f32 v[48:49], v[48:49], v[58:59] neg_lo:[0,1] neg_hi:[0,1]
	v_pk_add_f32 v[58:59], v[70:71], v[56:57]
	v_pk_add_f32 v[56:57], v[70:71], v[56:57] neg_lo:[0,1] neg_hi:[0,1]
	v_pk_add_f32 v[70:71], v[54:55], v[48:49] op_sel:[0,1] op_sel_hi:[1,0] neg_lo:[0,1]
	v_pk_add_f32 v[48:49], v[54:55], v[48:49] op_sel:[0,1] op_sel_hi:[1,0] neg_hi:[0,1]
	v_pk_add_f32 v[54:55], v[46:47], v[52:53]
	v_pk_add_f32 v[46:47], v[46:47], v[52:53] neg_lo:[0,1] neg_hi:[0,1]
	v_pk_add_f32 v[52:53], v[50:51], v[40:41]
	v_pk_add_f32 v[40:41], v[50:51], v[40:41] neg_lo:[0,1] neg_hi:[0,1]
	v_pk_add_f32 v[50:51], v[54:55], v[52:53]
	v_pk_add_f32 v[52:53], v[54:55], v[52:53] neg_lo:[0,1] neg_hi:[0,1]
	v_pk_add_f32 v[54:55], v[46:47], v[40:41] op_sel:[0,1] op_sel_hi:[1,0] neg_lo:[0,1]
	v_pk_add_f32 v[40:41], v[46:47], v[40:41] op_sel:[0,1] op_sel_hi:[1,0] neg_hi:[0,1]
	ds_write2_b64 v146, v[68:69], v[74:75] offset1:17
	ds_write2_b64 v146, v[58:59], v[50:51] offset0:34 offset1:51
	ds_write2_b64 v146, v[76:77], v[72:73] offset0:68 offset1:85
	ds_write2_b64 v146, v[70:71], v[54:55] offset0:102 offset1:119
	ds_write2_b64 v146, v[66:67], v[64:65] offset0:136 offset1:153
	ds_write2_b64 v146, v[56:57], v[52:53] offset0:170 offset1:187
	ds_write2_b64 v146, v[62:63], v[60:61] offset0:204 offset1:221
	ds_write2_b64 v146, v[48:49], v[40:41] offset0:238 offset1:255
	s_waitcnt lgkmcnt(0)
	s_barrier
	ds_read_b64 v[40:41], v144 offset:2176
	ds_read_b64 v[46:47], v144 offset:4352
	ds_read_b64 v[48:49], v144 offset:6528
	ds_read_b64 v[50:51], v144
	s_waitcnt lgkmcnt(3)
	v_pk_mul_f32 v[52:53], v[40:41], v[38:39] op_sel:[0,0] op_sel_hi:[0,1] neg_hi:[0,1]
	v_pk_fma_f32 v[40:41], v[40:41], v[38:39], v[52:53] op_sel:[1,1,0] op_sel_hi:[1,0,1]
	v_pk_mul_f32 v[52:53], v[38:39], v[38:39] op_sel:[0,0] op_sel_hi:[0,1]
	ds_read_b64 v[56:57], v144 offset:8704
	v_pk_fma_f32 v[52:53], v[38:39], v[38:39], v[52:53] op_sel:[1,1,0] op_sel_hi:[1,0,1] neg_lo:[0,1,0]
	s_waitcnt lgkmcnt(3)
	v_pk_mul_f32 v[54:55], v[46:47], v[52:53] op_sel:[0,0] op_sel_hi:[0,1] neg_hi:[0,1]
	v_pk_fma_f32 v[46:47], v[46:47], v[52:53], v[54:55] op_sel:[1,1,0] op_sel_hi:[1,0,1]
	v_pk_mul_f32 v[54:55], v[52:53], v[38:39] op_sel:[0,0] op_sel_hi:[0,1]
	v_pk_fma_f32 v[52:53], v[52:53], v[38:39], v[54:55] op_sel:[1,1,0] op_sel_hi:[1,0,1] neg_lo:[0,1,0]
	s_waitcnt lgkmcnt(2)
	v_pk_mul_f32 v[54:55], v[48:49], v[52:53] op_sel:[0,0] op_sel_hi:[0,1] neg_hi:[0,1]
	v_pk_fma_f32 v[48:49], v[48:49], v[52:53], v[54:55] op_sel:[1,1,0] op_sel_hi:[1,0,1]
	v_pk_mul_f32 v[54:55], v[52:53], v[38:39] op_sel:[0,0] op_sel_hi:[0,1]
	v_pk_fma_f32 v[52:53], v[52:53], v[38:39], v[54:55] op_sel:[1,1,0] op_sel_hi:[1,0,1] neg_lo:[0,1,0]
	ds_read_b64 v[54:55], v144 offset:10880
	ds_read_b64 v[58:59], v144 offset:13056
	ds_read_b64 v[60:61], v144 offset:15232
	s_waitcnt lgkmcnt(3)
	v_pk_mul_f32 v[62:63], v[56:57], v[52:53] op_sel:[0,0] op_sel_hi:[0,1] neg_hi:[0,1]
	ds_read_b64 v[64:65], v144 offset:17408
	v_pk_fma_f32 v[56:57], v[56:57], v[52:53], v[62:63] op_sel:[1,1,0] op_sel_hi:[1,0,1]
	v_pk_mul_f32 v[62:63], v[52:53], v[38:39] op_sel:[0,0] op_sel_hi:[0,1]
	v_pk_fma_f32 v[52:53], v[52:53], v[38:39], v[62:63] op_sel:[1,1,0] op_sel_hi:[1,0,1] neg_lo:[0,1,0]
	s_waitcnt lgkmcnt(3)
	v_pk_mul_f32 v[62:63], v[54:55], v[52:53] op_sel:[0,0] op_sel_hi:[0,1] neg_hi:[0,1]
	v_pk_fma_f32 v[54:55], v[54:55], v[52:53], v[62:63] op_sel:[1,1,0] op_sel_hi:[1,0,1]
	v_pk_mul_f32 v[62:63], v[52:53], v[38:39] op_sel:[0,0] op_sel_hi:[0,1]
	v_pk_fma_f32 v[52:53], v[52:53], v[38:39], v[62:63] op_sel:[1,1,0] op_sel_hi:[1,0,1] neg_lo:[0,1,0]
	s_waitcnt lgkmcnt(2)
	v_pk_mul_f32 v[62:63], v[58:59], v[52:53] op_sel:[0,0] op_sel_hi:[0,1] neg_hi:[0,1]
	v_pk_fma_f32 v[58:59], v[58:59], v[52:53], v[62:63] op_sel:[1,1,0] op_sel_hi:[1,0,1]
	v_pk_mul_f32 v[62:63], v[52:53], v[38:39] op_sel:[0,0] op_sel_hi:[0,1]
	v_pk_fma_f32 v[52:53], v[52:53], v[38:39], v[62:63] op_sel:[1,1,0] op_sel_hi:[1,0,1] neg_lo:[0,1,0]
	s_waitcnt lgkmcnt(1)
	v_pk_mul_f32 v[62:63], v[60:61], v[52:53] op_sel:[0,0] op_sel_hi:[0,1] neg_hi:[0,1]
	v_pk_fma_f32 v[60:61], v[60:61], v[52:53], v[62:63] op_sel:[1,1,0] op_sel_hi:[1,0,1]
	v_pk_mul_f32 v[62:63], v[52:53], v[38:39] op_sel:[0,0] op_sel_hi:[0,1]
	v_pk_fma_f32 v[52:53], v[52:53], v[38:39], v[62:63] op_sel:[1,1,0] op_sel_hi:[1,0,1] neg_lo:[0,1,0]
	ds_read_b64 v[62:63], v144 offset:19584
	ds_read_b64 v[66:67], v144 offset:21760
	ds_read_b64 v[68:69], v144 offset:23936
	s_waitcnt lgkmcnt(3)
	v_pk_mul_f32 v[70:71], v[64:65], v[52:53] op_sel:[0,0] op_sel_hi:[0,1] neg_hi:[0,1]
	ds_read_b64 v[72:73], v144 offset:26112
	v_pk_fma_f32 v[64:65], v[64:65], v[52:53], v[70:71] op_sel:[1,1,0] op_sel_hi:[1,0,1]
	v_pk_mul_f32 v[70:71], v[52:53], v[38:39] op_sel:[0,0] op_sel_hi:[0,1]
	v_pk_fma_f32 v[52:53], v[52:53], v[38:39], v[70:71] op_sel:[1,1,0] op_sel_hi:[1,0,1] neg_lo:[0,1,0]
	s_waitcnt lgkmcnt(3)
	v_pk_mul_f32 v[70:71], v[62:63], v[52:53] op_sel:[0,0] op_sel_hi:[0,1] neg_hi:[0,1]
	v_pk_fma_f32 v[62:63], v[62:63], v[52:53], v[70:71] op_sel:[1,1,0] op_sel_hi:[1,0,1]
	v_pk_mul_f32 v[70:71], v[52:53], v[38:39] op_sel:[0,0] op_sel_hi:[0,1]
	v_pk_fma_f32 v[52:53], v[52:53], v[38:39], v[70:71] op_sel:[1,1,0] op_sel_hi:[1,0,1] neg_lo:[0,1,0]
	s_waitcnt lgkmcnt(2)
	v_pk_mul_f32 v[70:71], v[66:67], v[52:53] op_sel:[0,0] op_sel_hi:[0,1] neg_hi:[0,1]
	v_pk_fma_f32 v[66:67], v[66:67], v[52:53], v[70:71] op_sel:[1,1,0] op_sel_hi:[1,0,1]
	v_pk_mul_f32 v[70:71], v[52:53], v[38:39] op_sel:[0,0] op_sel_hi:[0,1]
	v_pk_fma_f32 v[52:53], v[52:53], v[38:39], v[70:71] op_sel:[1,1,0] op_sel_hi:[1,0,1] neg_lo:[0,1,0]
	s_waitcnt lgkmcnt(1)
	v_pk_mul_f32 v[70:71], v[68:69], v[52:53] op_sel:[0,0] op_sel_hi:[0,1] neg_hi:[0,1]
	v_pk_fma_f32 v[68:69], v[68:69], v[52:53], v[70:71] op_sel:[1,1,0] op_sel_hi:[1,0,1]
	v_pk_mul_f32 v[70:71], v[52:53], v[38:39] op_sel:[0,0] op_sel_hi:[0,1]
	v_pk_fma_f32 v[52:53], v[52:53], v[38:39], v[70:71] op_sel:[1,1,0] op_sel_hi:[1,0,1] neg_lo:[0,1,0]
	ds_read_b64 v[70:71], v144 offset:28288
	ds_read_b64 v[74:75], v144 offset:30464
	ds_read_b64 v[76:77], v144 offset:32640
	s_waitcnt lgkmcnt(3)
	v_pk_mul_f32 v[78:79], v[72:73], v[52:53] op_sel:[0,0] op_sel_hi:[0,1] neg_hi:[0,1]
	s_nop 0
	v_pk_fma_f32 v[72:73], v[72:73], v[52:53], v[78:79] op_sel:[1,1,0] op_sel_hi:[1,0,1]
	v_pk_mul_f32 v[78:79], v[52:53], v[38:39] op_sel:[0,0] op_sel_hi:[0,1]
	v_pk_fma_f32 v[52:53], v[52:53], v[38:39], v[78:79] op_sel:[1,1,0] op_sel_hi:[1,0,1] neg_lo:[0,1,0]
	s_waitcnt lgkmcnt(2)
	v_pk_mul_f32 v[78:79], v[70:71], v[52:53] op_sel:[0,0] op_sel_hi:[0,1] neg_hi:[0,1]
	v_pk_fma_f32 v[70:71], v[70:71], v[52:53], v[78:79] op_sel:[1,1,0] op_sel_hi:[1,0,1]
	v_pk_mul_f32 v[78:79], v[52:53], v[38:39] op_sel:[0,0] op_sel_hi:[0,1]
	v_pk_fma_f32 v[52:53], v[52:53], v[38:39], v[78:79] op_sel:[1,1,0] op_sel_hi:[1,0,1] neg_lo:[0,1,0]
	s_waitcnt lgkmcnt(1)
	v_pk_mul_f32 v[78:79], v[74:75], v[52:53] op_sel:[0,0] op_sel_hi:[0,1] neg_hi:[0,1]
	v_pk_fma_f32 v[74:75], v[74:75], v[52:53], v[78:79] op_sel:[1,1,0] op_sel_hi:[1,0,1]
	v_pk_mul_f32 v[78:79], v[52:53], v[38:39] op_sel:[0,0] op_sel_hi:[0,1]
	v_pk_fma_f32 v[38:39], v[52:53], v[38:39], v[78:79] op_sel:[1,1,0] op_sel_hi:[1,0,1] neg_lo:[0,1,0]
	s_waitcnt lgkmcnt(0)
	v_pk_mul_f32 v[52:53], v[76:77], v[38:39] op_sel:[0,0] op_sel_hi:[0,1] neg_hi:[0,1]
	v_pk_fma_f32 v[38:39], v[76:77], v[38:39], v[52:53] op_sel:[1,1,0] op_sel_hi:[1,0,1]
	v_pk_add_f32 v[52:53], v[50:51], v[64:65]
	v_pk_add_f32 v[50:51], v[50:51], v[64:65] neg_lo:[0,1] neg_hi:[0,1]
	v_pk_add_f32 v[64:65], v[56:57], v[72:73]
	v_pk_add_f32 v[56:57], v[56:57], v[72:73] neg_lo:[0,1] neg_hi:[0,1]
	v_pk_add_f32 v[72:73], v[52:53], v[64:65]
	v_pk_add_f32 v[76:77], v[50:51], v[56:57] op_sel:[0,1] op_sel_hi:[1,0] neg_lo:[0,1]
	v_pk_add_f32 v[78:79], v[50:51], v[56:57] op_sel:[0,1] op_sel_hi:[1,0] neg_hi:[0,1]
	v_pk_add_f32 v[50:51], v[40:41], v[62:63]
	v_pk_add_f32 v[40:41], v[40:41], v[62:63] neg_lo:[0,1] neg_hi:[0,1]
	v_pk_add_f32 v[56:57], v[54:55], v[70:71]
	v_pk_add_f32 v[54:55], v[54:55], v[70:71] neg_lo:[0,1] neg_hi:[0,1]
	v_pk_add_f32 v[52:53], v[52:53], v[64:65] neg_lo:[0,1] neg_hi:[0,1]
	v_pk_add_f32 v[62:63], v[50:51], v[56:57]
	v_pk_add_f32 v[50:51], v[50:51], v[56:57] neg_lo:[0,1] neg_hi:[0,1]
	v_pk_add_f32 v[56:57], v[40:41], v[54:55] op_sel:[0,1] op_sel_hi:[1,0] neg_lo:[0,1]
	v_pk_add_f32 v[40:41], v[40:41], v[54:55] op_sel:[0,1] op_sel_hi:[1,0] neg_hi:[0,1]
	v_pk_add_f32 v[54:55], v[46:47], v[66:67]
	v_pk_add_f32 v[46:47], v[46:47], v[66:67] neg_lo:[0,1] neg_hi:[0,1]
	v_pk_add_f32 v[64:65], v[58:59], v[74:75]
	v_pk_add_f32 v[58:59], v[58:59], v[74:75] neg_lo:[0,1] neg_hi:[0,1]
	v_pk_add_f32 v[66:67], v[54:55], v[64:65]
	v_pk_add_f32 v[54:55], v[54:55], v[64:65] neg_lo:[0,1] neg_hi:[0,1]
	v_pk_add_f32 v[64:65], v[46:47], v[58:59] op_sel:[0,1] op_sel_hi:[1,0] neg_lo:[0,1]
	v_pk_add_f32 v[46:47], v[46:47], v[58:59] op_sel:[0,1] op_sel_hi:[1,0] neg_hi:[0,1]
	v_pk_add_f32 v[58:59], v[48:49], v[68:69]
	v_pk_add_f32 v[48:49], v[48:49], v[68:69] neg_lo:[0,1] neg_hi:[0,1]
	v_pk_add_f32 v[68:69], v[60:61], v[38:39]
	v_pk_add_f32 v[38:39], v[60:61], v[38:39] neg_lo:[0,1] neg_hi:[0,1]
	v_pk_add_f32 v[60:61], v[58:59], v[68:69]
	v_pk_add_f32 v[58:59], v[58:59], v[68:69] neg_lo:[0,1] neg_hi:[0,1]
	v_pk_add_f32 v[68:69], v[48:49], v[38:39] op_sel:[0,1] op_sel_hi:[1,0] neg_lo:[0,1]
	v_pk_add_f32 v[38:39], v[48:49], v[38:39] op_sel:[0,1] op_sel_hi:[1,0] neg_hi:[0,1]
	v_pk_mul_f32 v[48:49], v[56:57], s[62:63] op_sel:[0,0] op_sel_hi:[0,1]
	v_pk_fma_f32 v[32:33], v[56:57], s[62:63], v[48:49] op_sel:[1,1,0] op_sel_hi:[1,0,1] neg_lo:[0,1,0]
	v_pk_mul_f32 v[48:49], v[64:65], s[64:65] op_sel:[0,0] op_sel_hi:[0,1]
	v_pk_mul_f32 v[56:57], v[68:69], s[66:67] op_sel:[0,0] op_sel_hi:[0,1]
	v_pk_fma_f32 v[48:49], v[64:65], s[64:65], v[48:49] op_sel:[1,1,0] op_sel_hi:[1,0,1] neg_lo:[0,1,0]
	v_pk_fma_f32 v[56:57], v[68:69], s[66:67], v[56:57] op_sel:[1,1,0] op_sel_hi:[1,0,1] neg_lo:[0,1,0]
	v_pk_mul_f32 v[64:65], v[50:51], s[64:65] op_sel:[0,0] op_sel_hi:[0,1]
	v_pk_fma_f32 v[68:69], v[50:51], s[64:65], v[64:65] op_sel:[1,1,0] op_sel_hi:[1,0,1] neg_lo:[0,1,0]
	v_pk_mul_f32 v[28:29], v[54:55], s[68:69] op_sel:[0,0] op_sel_hi:[0,1]
	v_pk_fma_f32 v[54:55], v[54:55], s[68:69], v[28:29] op_sel:[1,1,0] op_sel_hi:[1,0,1] neg_lo:[0,1,0]
	v_pk_mul_f32 v[28:29], v[58:59], s[70:71] op_sel:[0,0] op_sel_hi:[0,1]
	v_pk_add_f32 v[42:43], v[62:63], v[60:61]
	v_pk_fma_f32 v[58:59], v[58:59], s[70:71], v[28:29] op_sel:[1,1,0] op_sel_hi:[1,0,1] neg_lo:[0,1,0]
	v_pk_mul_f32 v[28:29], v[40:41], s[66:67] op_sel:[0,0] op_sel_hi:[0,1]
	v_pk_add_f32 v[50:51], v[52:53], v[54:55]
	v_pk_fma_f32 v[70:71], v[40:41], s[66:67], v[28:29] op_sel:[1,1,0] op_sel_hi:[1,0,1] neg_lo:[0,1,0]
	v_pk_mul_f32 v[26:27], v[46:47], s[70:71] op_sel:[0,0] op_sel_hi:[0,1]
	v_pk_add_f32 v[28:29], v[62:63], v[60:61] neg_lo:[0,1] neg_hi:[0,1]
	v_pk_fma_f32 v[74:75], v[46:47], s[70:71], v[26:27] op_sel:[1,1,0] op_sel_hi:[1,0,1] neg_lo:[0,1,0]
	v_pk_mul_f32 v[26:27], v[38:39], s[72:73] op_sel:[0,0] op_sel_hi:[0,1]
	v_pk_add_f32 v[30:31], v[32:33], v[56:57] neg_lo:[0,1] neg_hi:[0,1]
	v_pk_fma_f32 v[80:81], v[38:39], s[72:73], v[26:27] op_sel:[1,1,0] op_sel_hi:[1,0,1] neg_lo:[0,1,0]
	v_pk_add_f32 v[26:27], v[72:73], v[66:67] neg_lo:[0,1] neg_hi:[0,1]
	v_pk_add_f32 v[38:39], v[72:73], v[66:67]
	v_pk_add_f32 v[40:41], v[26:27], v[28:29] op_sel:[0,1] op_sel_hi:[1,0] neg_lo:[0,1]
	v_pk_add_f32 v[26:27], v[26:27], v[28:29] op_sel:[0,1] op_sel_hi:[1,0] neg_hi:[0,1]
	v_pk_add_f32 v[28:29], v[76:77], v[48:49] neg_lo:[0,1] neg_hi:[0,1]
	v_pk_add_f32 v[44:45], v[76:77], v[48:49]
	v_pk_add_f32 v[48:49], v[32:33], v[56:57]
	v_pk_add_f32 v[46:47], v[28:29], v[30:31] op_sel:[0,1] op_sel_hi:[1,0] neg_lo:[0,1]
	v_pk_add_f32 v[28:29], v[28:29], v[30:31] op_sel:[0,1] op_sel_hi:[1,0] neg_hi:[0,1]
	v_pk_add_f32 v[30:31], v[52:53], v[54:55] neg_lo:[0,1] neg_hi:[0,1]
	v_pk_add_f32 v[54:55], v[68:69], v[58:59]
	v_pk_add_f32 v[32:33], v[68:69], v[58:59] neg_lo:[0,1] neg_hi:[0,1]
	v_pk_add_f32 v[56:57], v[78:79], v[74:75]
	v_pk_add_f32 v[60:61], v[70:71], v[80:81]
	v_pk_add_f32 v[64:65], v[38:39], v[42:43]
	v_pk_add_f32 v[66:67], v[44:45], v[48:49]
	v_pk_add_f32 v[68:69], v[50:51], v[54:55]
	v_pk_add_f32 v[52:53], v[30:31], v[32:33] op_sel:[0,1] op_sel_hi:[1,0] neg_lo:[0,1]
	v_pk_add_f32 v[30:31], v[30:31], v[32:33] op_sel:[0,1] op_sel_hi:[1,0] neg_hi:[0,1]
	v_pk_add_f32 v[32:33], v[78:79], v[74:75] neg_lo:[0,1] neg_hi:[0,1]
	v_pk_add_f32 v[62:63], v[56:57], v[60:61]
	v_pk_add_f32 v[70:71], v[70:71], v[80:81] neg_lo:[0,1] neg_hi:[0,1]
	s_nop 0
	v_pk_add_f32 v[58:59], v[32:33], v[70:71] op_sel:[0,1] op_sel_hi:[1,0] neg_lo:[0,1]
	v_pk_add_f32 v[32:33], v[32:33], v[70:71] op_sel:[0,1] op_sel_hi:[1,0] neg_hi:[0,1]
	s_and_saveexec_b64 s[0:1], s[4:5]
	s_xor_b64 s[0:1], exec, s[0:1]
	s_cbranch_execz .LBB0_1415
	v_pk_mul_f32 v[72:73], v[36:37], s[16:17] op_sel:[0,0] op_sel_hi:[0,1]
	v_pk_fma_f32 v[70:71], v[36:37], s[16:17], v[72:73] op_sel:[1,1,0] op_sel_hi:[1,0,1] neg_lo:[0,1,0]
	v_pk_mul_f32 v[72:73], v[64:65], v[70:71] op_sel:[0,0] op_sel_hi:[0,1] neg_hi:[0,1]
	v_pk_fma_f32 v[64:65], v[64:65], v[70:71], v[72:73] op_sel:[1,1,0] op_sel_hi:[1,0,1]
	v_pk_mul_f32 v[72:73], v[36:37], s[18:19] op_sel:[0,0] op_sel_hi:[0,1]
	v_pk_fma_f32 v[70:71], v[36:37], s[18:19], v[72:73] op_sel:[1,1,0] op_sel_hi:[1,0,1] neg_lo:[0,1,0]
	v_pk_mul_f32 v[72:73], v[66:67], v[70:71] op_sel:[0,0] op_sel_hi:[0,1] neg_hi:[0,1]
	v_pk_fma_f32 v[66:67], v[66:67], v[70:71], v[72:73] op_sel:[1,1,0] op_sel_hi:[1,0,1]
	v_pk_mul_f32 v[72:73], v[36:37], s[20:21] op_sel:[0,0] op_sel_hi:[0,1]
	v_pk_fma_f32 v[70:71], v[36:37], s[20:21], v[72:73] op_sel:[1,1,0] op_sel_hi:[1,0,1] neg_lo:[0,1,0]
	v_pk_mul_f32 v[72:73], v[68:69], v[70:71] op_sel:[0,0] op_sel_hi:[0,1] neg_hi:[0,1]
	v_pk_fma_f32 v[68:69], v[68:69], v[70:71], v[72:73] op_sel:[1,1,0] op_sel_hi:[1,0,1]
	v_pk_mul_f32 v[72:73], v[36:37], s[22:23] op_sel:[0,0] op_sel_hi:[0,1]
	v_pk_fma_f32 v[70:71], v[36:37], s[22:23], v[72:73] op_sel:[1,1,0] op_sel_hi:[1,0,1] neg_lo:[0,1,0]
	v_pk_mul_f32 v[72:73], v[62:63], v[70:71] op_sel:[0,0] op_sel_hi:[0,1] neg_hi:[0,1]
	v_pk_fma_f32 v[62:63], v[62:63], v[70:71], v[72:73] op_sel:[1,1,0] op_sel_hi:[1,0,1]
	ds_write_b64 v144, v[64:65]
	ds_write_b64 v144, v[66:67] offset:2176
	ds_write_b64 v144, v[68:69] offset:4352
	ds_write_b64 v144, v[62:63] offset:6528
	v_pk_mul_f32 v[64:65], v[36:37], s[50:51] op_sel:[0,0] op_sel_hi:[0,1]
	s_nop 0
	v_pk_fma_f32 v[62:63], v[36:37], s[50:51], v[64:65] op_sel:[1,1,0] op_sel_hi:[1,0,1] neg_lo:[0,1,0]
	v_pk_mul_f32 v[64:65], v[40:41], v[62:63] op_sel:[0,0] op_sel_hi:[0,1] neg_hi:[0,1]
	v_pk_fma_f32 v[40:41], v[40:41], v[62:63], v[64:65] op_sel:[1,1,0] op_sel_hi:[1,0,1]
	v_pk_mul_f32 v[64:65], v[36:37], s[52:53] op_sel:[0,0] op_sel_hi:[0,1]
	v_pk_fma_f32 v[62:63], v[36:37], s[52:53], v[64:65] op_sel:[1,1,0] op_sel_hi:[1,0,1] neg_lo:[0,1,0]
	v_pk_mul_f32 v[64:65], v[46:47], v[62:63] op_sel:[0,0] op_sel_hi:[0,1] neg_hi:[0,1]
	v_pk_fma_f32 v[46:47], v[46:47], v[62:63], v[64:65] op_sel:[1,1,0] op_sel_hi:[1,0,1]
	v_pk_mul_f32 v[64:65], v[36:37], s[54:55] op_sel:[0,0] op_sel_hi:[0,1]
	v_pk_fma_f32 v[62:63], v[36:37], s[54:55], v[64:65] op_sel:[1,1,0] op_sel_hi:[1,0,1] neg_lo:[0,1,0]
	v_pk_mul_f32 v[64:65], v[52:53], v[62:63] op_sel:[0,0] op_sel_hi:[0,1] neg_hi:[0,1]
	v_pk_fma_f32 v[52:53], v[52:53], v[62:63], v[64:65] op_sel:[1,1,0] op_sel_hi:[1,0,1]
	v_pk_mul_f32 v[64:65], v[36:37], s[56:57] op_sel:[0,0] op_sel_hi:[0,1]
	v_pk_fma_f32 v[62:63], v[36:37], s[56:57], v[64:65] op_sel:[1,1,0] op_sel_hi:[1,0,1] neg_lo:[0,1,0]
	v_pk_mul_f32 v[64:65], v[58:59], v[62:63] op_sel:[0,0] op_sel_hi:[0,1] neg_hi:[0,1]
	s_nop 0
	v_pk_fma_f32 v[58:59], v[58:59], v[62:63], v[64:65] op_sel:[1,1,0] op_sel_hi:[1,0,1]

.LBB0_1417:
	s_or_b64 exec, exec, s[0:1]
	v_pk_add_f32 v[62:63], v[38:39], v[42:43] neg_lo:[0,1] neg_hi:[0,1]
	v_pk_add_f32 v[44:45], v[44:45], v[48:49] neg_lo:[0,1] neg_hi:[0,1]
	v_pk_add_f32 v[42:43], v[50:51], v[54:55] neg_lo:[0,1] neg_hi:[0,1]
	v_pk_add_f32 v[38:39], v[56:57], v[60:61] neg_lo:[0,1] neg_hi:[0,1]
	ds_write_b64 v144, v[40:41] offset:8704
	ds_write_b64 v144, v[46:47] offset:10880
	ds_write_b64 v144, v[52:53] offset:13056
	ds_write_b64 v144, v[58:59] offset:15232
	s_and_saveexec_b64 s[0:1], s[4:5]
	s_xor_b64 s[0:1], exec, s[0:1]
	s_cbranch_execz .LBB0_1419
	v_pk_mul_f32 v[46:47], v[36:37], s[14:15] op_sel:[0,0] op_sel_hi:[0,1]
	s_mov_b32 s4, s19
	v_pk_fma_f32 v[40:41], v[36:37], s[14:15], v[46:47] op_sel:[1,1,0] op_sel_hi:[1,0,1] neg_lo:[0,1,0]
	s_mov_b32 s5, s57
	v_pk_mul_f32 v[46:47], v[62:63], v[40:41] op_sel:[0,0] op_sel_hi:[0,1] neg_hi:[0,1]
	v_pk_fma_f32 v[40:41], v[62:63], v[40:41], v[46:47] op_sel:[1,1,0] op_sel_hi:[1,0,1]
	v_mov_b64_e32 v[46:47], s[4:5]
	v_pk_mul_f32 v[48:49], v[36:37], v[46:47] op_sel:[0,0] op_sel_hi:[0,1]
	s_mov_b32 s4, s21
	v_pk_fma_f32 v[46:47], v[36:37], v[46:47], v[48:49] op_sel:[1,1,0] op_sel_hi:[1,0,1] neg_lo:[0,1,0]
	s_mov_b32 s5, s55
	v_pk_mul_f32 v[48:49], v[44:45], v[46:47] op_sel:[0,0] op_sel_hi:[0,1] neg_hi:[0,1]
	s_nop 0
	v_pk_fma_f32 v[44:45], v[44:45], v[46:47], v[48:49] op_sel:[1,1,0] op_sel_hi:[1,0,1]
	v_mov_b64_e32 v[46:47], s[4:5]
	v_pk_mul_f32 v[48:49], v[36:37], v[46:47] op_sel:[0,0] op_sel_hi:[0,1]
	s_mov_b32 s4, s23
	v_pk_fma_f32 v[46:47], v[36:37], v[46:47], v[48:49] op_sel:[1,1,0] op_sel_hi:[1,0,1] neg_lo:[0,1,0]
	s_mov_b32 s5, s53
	v_pk_mul_f32 v[48:49], v[42:43], v[46:47] op_sel:[0,0] op_sel_hi:[0,1] neg_hi:[0,1]
	v_pk_fma_f32 v[42:43], v[42:43], v[46:47], v[48:49] op_sel:[1,1,0] op_sel_hi:[1,0,1]
	v_mov_b64_e32 v[46:47], s[4:5]
	v_pk_mul_f32 v[48:49], v[36:37], v[46:47] op_sel:[0,0] op_sel_hi:[0,1]
	s_mov_b32 s4, s53
	v_pk_fma_f32 v[46:47], v[36:37], v[46:47], v[48:49] op_sel:[1,1,0] op_sel_hi:[1,0,1] neg_lo:[0,1,0]
	s_mov_b32 s5, s23
	v_pk_mul_f32 v[48:49], v[38:39], v[46:47] op_sel:[0,0] op_sel_hi:[0,1] neg_hi:[0,1]
	v_pk_fma_f32 v[38:39], v[38:39], v[46:47], v[48:49] op_sel:[1,1,0] op_sel_hi:[1,0,1]
	ds_write_b64 v144, v[40:41] offset:17408
	ds_write_b64 v144, v[44:45] offset:19584
	ds_write_b64 v144, v[42:43] offset:21760
	ds_write_b64 v144, v[38:39] offset:23936
	v_pk_mul_f32 v[40:41], v[36:37], s[58:59] op_sel:[0,0] op_sel_hi:[0,1]
	s_nop 0
	v_pk_fma_f32 v[38:39], v[36:37], s[58:59], v[40:41] op_sel:[1,1,0] op_sel_hi:[1,0,1] neg_lo:[0,1,0]
	v_pk_mul_f32 v[40:41], v[26:27], v[38:39] op_sel:[0,0] op_sel_hi:[0,1] neg_hi:[0,1]
	v_pk_fma_f32 v[26:27], v[26:27], v[38:39], v[40:41] op_sel:[1,1,0] op_sel_hi:[1,0,1]
	v_mov_b64_e32 v[38:39], s[4:5]
	v_pk_mul_f32 v[40:41], v[36:37], v[38:39] op_sel:[0,0] op_sel_hi:[0,1]
	s_mov_b32 s4, s57
	v_pk_fma_f32 v[38:39], v[36:37], v[38:39], v[40:41] op_sel:[1,1,0] op_sel_hi:[1,0,1] neg_lo:[0,1,0]
	s_mov_b32 s5, s19
	v_pk_mul_f32 v[40:41], v[28:29], v[38:39] op_sel:[0,0] op_sel_hi:[0,1] neg_hi:[0,1]
	v_pk_fma_f32 v[28:29], v[28:29], v[38:39], v[40:41] op_sel:[1,1,0] op_sel_hi:[1,0,1]
	v_pk_mul_f32 v[40:41], v[36:37], s[72:73] op_sel:[0,0] op_sel_hi:[0,1]
	v_pk_fma_f32 v[38:39], v[36:37], s[72:73], v[40:41] op_sel:[1,1,0] op_sel_hi:[1,0,1] neg_lo:[0,1,0]
	v_pk_mul_f32 v[40:41], v[30:31], v[38:39] op_sel:[0,0] op_sel_hi:[0,1] neg_hi:[0,1]
	v_pk_fma_f32 v[30:31], v[30:31], v[38:39], v[40:41] op_sel:[1,1,0] op_sel_hi:[1,0,1]
	v_pk_mul_f32 v[40:41], v[36:37], s[4:5] op_sel:[0,0] op_sel_hi:[0,1]
	v_pk_fma_f32 v[36:37], v[36:37], s[4:5], v[40:41] op_sel:[1,1,0] op_sel_hi:[1,0,1] neg_lo:[0,1,0]
	v_pk_mul_f32 v[38:39], v[32:33], v[36:37] op_sel:[0,0] op_sel_hi:[0,1] neg_hi:[0,1]
	s_nop 0
	v_pk_fma_f32 v[32:33], v[32:33], v[36:37], v[38:39] op_sel:[1,1,0] op_sel_hi:[1,0,1]

.LBB0_1709:
	v_ashrrev_i32_e32 v37, 8, v18
	v_and_b32_e32 v34, 0xff, v18
	v_lshlrev_b32_e32 v19, 13, v37
	v_lshlrev_b32_e32 v20, 1, v34
	v_add3_u32 v38, s25, v19, v20
	v_add3_u32 v19, s54, v19, v20
	ds_read_u16 v20, v38
	ds_read_u16 v22, v38 offset:512
	ds_read_u16 v24, v38 offset:1024
	ds_read_u16 v26, v38 offset:1536
	ds_read_u16 v28, v38 offset:2048
	ds_read_u16 v39, v38 offset:2560
	ds_read_u16 v42, v38 offset:3072
	ds_read_u16 v44, v38 offset:3584
	ds_read_u16 v21, v19
	ds_read_u16 v23, v19 offset:512
	ds_read_u16 v25, v19 offset:1024
	ds_read_u16 v27, v19 offset:1536
	ds_read_u16 v29, v19 offset:2048
	ds_read_u16 v41, v19 offset:2560
	ds_read_u16 v43, v19 offset:3072
	ds_read_u16 v45, v19 offset:3584
	s_waitcnt lgkmcnt(7)
	v_lshlrev_b32_e32 v21, 16, v21
	v_lshlrev_b32_e32 v40, 16, v39
	s_waitcnt lgkmcnt(2)
	v_lshlrev_b32_e32 v39, 16, v41
	v_xor_b32_e32 v41, 0x80000000, v39
	s_waitcnt lgkmcnt(1)
	v_lshlrev_b32_e32 v39, 16, v43
	v_xor_b32_e32 v43, 0x80000000, v39
	s_waitcnt lgkmcnt(0)
	v_lshlrev_b32_e32 v39, 16, v45
	v_xor_b32_e32 v45, 0x80000000, v39
	ds_read_u16 v39, v38 offset:4096
	ds_read_u16 v48, v38 offset:4608
	ds_read_u16 v50, v38 offset:5120
	ds_read_u16 v52, v38 offset:5632
	ds_read_u16 v54, v38 offset:6144
	ds_read_u16 v56, v38 offset:6656
	ds_read_u16 v58, v38 offset:7168
	ds_read_u16 v38, v38 offset:7680
	s_waitcnt lgkmcnt(7)
	v_lshlrev_b32_e32 v46, 16, v39
	ds_read_u16 v39, v19 offset:4096
	ds_read_u16 v49, v19 offset:4608
	ds_read_u16 v51, v19 offset:5120
	ds_read_u16 v53, v19 offset:5632
	ds_read_u16 v55, v19 offset:6144
	ds_read_u16 v57, v19 offset:6656
	ds_read_u16 v59, v19 offset:7168
	ds_read_u16 v19, v19 offset:7680
	s_waitcnt lgkmcnt(7)
	v_lshlrev_b32_e32 v39, 16, v39
	v_xor_b32_e32 v47, 0x80000000, v39
	s_waitcnt lgkmcnt(6)
	v_lshlrev_b32_e32 v39, 16, v49
	v_xor_b32_e32 v49, 0x80000000, v39
	s_waitcnt lgkmcnt(5)
	v_lshlrev_b32_e32 v39, 16, v51
	v_xor_b32_e32 v51, 0x80000000, v39
	s_waitcnt lgkmcnt(4)
	v_lshlrev_b32_e32 v39, 16, v53
	v_lshlrev_b32_e32 v29, 16, v29
	v_xor_b32_e32 v53, 0x80000000, v39
	s_waitcnt lgkmcnt(3)
	v_lshlrev_b32_e32 v39, 16, v55
	v_lshlrev_b32_e32 v20, 16, v20
	v_xor_b32_e32 v21, 0x80000000, v21
	v_lshlrev_b32_e32 v23, 16, v23
	v_lshlrev_b32_e32 v28, 16, v28
	v_xor_b32_e32 v29, 0x80000000, v29
	v_lshlrev_b32_e32 v54, 16, v54
	v_xor_b32_e32 v55, 0x80000000, v39
	s_waitcnt lgkmcnt(2)
	v_lshlrev_b32_e32 v39, 16, v57
	s_waitcnt lgkmcnt(0)
	v_lshlrev_b32_e32 v19, 16, v19
	v_lshlrev_b32_e32 v22, 16, v22
	v_xor_b32_e32 v23, 0x80000000, v23
	v_lshlrev_b32_e32 v25, 16, v25
	v_lshlrev_b32_e32 v48, 16, v48
	v_lshlrev_b32_e32 v56, 16, v56
	v_xor_b32_e32 v57, 0x80000000, v39
	v_lshlrev_b32_e32 v39, 16, v59
	v_lshlrev_b32_e32 v60, 16, v38
	v_xor_b32_e32 v61, 0x80000000, v19
	v_bfe_u32 v38, v18, 4, 4
	v_pk_add_f32 v[18:19], v[20:21], v[46:47]
	v_pk_add_f32 v[20:21], v[20:21], v[46:47] neg_lo:[0,1] neg_hi:[0,1]
	v_pk_add_f32 v[46:47], v[28:29], v[54:55]
	v_pk_add_f32 v[28:29], v[28:29], v[54:55] neg_lo:[0,1] neg_hi:[0,1]
	v_lshlrev_b32_e32 v24, 16, v24
	v_xor_b32_e32 v25, 0x80000000, v25
	v_lshlrev_b32_e32 v27, 16, v27
	v_lshlrev_b32_e32 v42, 16, v42
	v_lshlrev_b32_e32 v50, 16, v50
	v_lshlrev_b32_e32 v58, 16, v58
	v_xor_b32_e32 v59, 0x80000000, v39
	v_pk_add_f32 v[54:55], v[18:19], v[46:47]
	v_pk_add_f32 v[46:47], v[18:19], v[46:47] neg_lo:[0,1] neg_hi:[0,1]
	v_pk_add_f32 v[62:63], v[20:21], v[28:29] op_sel:[0,1] op_sel_hi:[1,0] neg_hi:[0,1]
	v_pk_add_f32 v[64:65], v[20:21], v[28:29] op_sel:[0,1] op_sel_hi:[1,0] neg_lo:[0,1]
	v_pk_add_f32 v[18:19], v[22:23], v[48:49]
	v_pk_add_f32 v[20:21], v[22:23], v[48:49] neg_lo:[0,1] neg_hi:[0,1]
	v_pk_add_f32 v[22:23], v[40:41], v[56:57]
	v_pk_add_f32 v[28:29], v[40:41], v[56:57] neg_lo:[0,1] neg_hi:[0,1]
	v_lshlrev_b32_e32 v26, 16, v26
	v_xor_b32_e32 v27, 0x80000000, v27
	v_lshlrev_b32_e32 v44, 16, v44
	v_lshlrev_b32_e32 v52, 16, v52
	v_pk_add_f32 v[40:41], v[18:19], v[22:23]
	v_pk_add_f32 v[22:23], v[18:19], v[22:23] neg_lo:[0,1] neg_hi:[0,1]
	v_pk_add_f32 v[18:19], v[20:21], v[28:29] op_sel:[0,1] op_sel_hi:[1,0] neg_hi:[0,1]
	v_pk_add_f32 v[28:29], v[20:21], v[28:29] op_sel:[0,1] op_sel_hi:[1,0] neg_lo:[0,1]
	v_pk_add_f32 v[20:21], v[24:25], v[50:51]
	v_pk_add_f32 v[24:25], v[24:25], v[50:51] neg_lo:[0,1] neg_hi:[0,1]
	v_pk_add_f32 v[48:49], v[42:43], v[58:59]
	v_pk_add_f32 v[42:43], v[42:43], v[58:59] neg_lo:[0,1] neg_hi:[0,1]
	v_pk_add_f32 v[50:51], v[20:21], v[48:49]
	v_pk_add_f32 v[48:49], v[20:21], v[48:49] neg_lo:[0,1] neg_hi:[0,1]
	v_pk_add_f32 v[56:57], v[24:25], v[42:43] op_sel:[0,1] op_sel_hi:[1,0] neg_hi:[0,1]
	v_pk_add_f32 v[42:43], v[24:25], v[42:43] op_sel:[0,1] op_sel_hi:[1,0] neg_lo:[0,1]
	v_pk_add_f32 v[20:21], v[26:27], v[52:53]
	v_pk_add_f32 v[24:25], v[26:27], v[52:53] neg_lo:[0,1] neg_hi:[0,1]
	v_pk_add_f32 v[26:27], v[44:45], v[60:61]
	v_pk_add_f32 v[44:45], v[44:45], v[60:61] neg_lo:[0,1] neg_hi:[0,1]
	v_pk_add_f32 v[52:53], v[20:21], v[26:27]
	v_pk_add_f32 v[58:59], v[20:21], v[26:27] neg_lo:[0,1] neg_hi:[0,1]
	v_pk_add_f32 v[26:27], v[24:25], v[44:45] op_sel:[0,1] op_sel_hi:[1,0] neg_hi:[0,1]
	v_pk_add_f32 v[44:45], v[24:25], v[44:45] op_sel:[0,1] op_sel_hi:[1,0] neg_lo:[0,1]
	v_pk_mul_f32 v[20:21], v[18:19], s[38:39] op_sel:[0,0] op_sel_hi:[0,1]
	v_mad_i32_i24 v35, v37, s3, 0
	v_pk_fma_f32 v[60:61], v[18:19], s[38:39], v[20:21] op_sel:[1,1,0] op_sel_hi:[1,0,1] neg_lo:[0,1,0]
	v_pk_mul_f32 v[18:19], v[56:57], s[40:41] op_sel:[0,0] op_sel_hi:[0,1]
	v_lshlrev_b32_e32 v39, 3, v34
	v_pk_fma_f32 v[56:57], v[56:57], s[40:41], v[18:19] op_sel:[1,1,0] op_sel_hi:[1,0,1] neg_lo:[0,1,0]
	v_pk_mul_f32 v[66:67], v[26:27], s[44:45] op_sel:[0,0] op_sel_hi:[0,1]
	v_lshlrev_b32_e32 v74, 3, v38
	v_pk_fma_f32 v[66:67], v[26:27], s[44:45], v[66:67] op_sel:[1,1,0] op_sel_hi:[1,0,1] neg_lo:[0,1,0]
	v_pk_mul_f32 v[26:27], v[22:23], s[40:41] op_sel:[0,0] op_sel_hi:[0,1]
	v_add3_u32 v74, v35, v39, v74
	v_pk_fma_f32 v[68:69], v[22:23], s[40:41], v[26:27] op_sel:[1,1,0] op_sel_hi:[1,0,1] neg_lo:[0,1,0]
	v_pk_mul_f32 v[22:23], v[48:49], s[36:37] op_sel:[0,0] op_sel_hi:[0,1]
	v_lshl_add_u32 v78, v38, 11, v35
	v_pk_fma_f32 v[48:49], v[48:49], s[36:37], v[22:23] op_sel:[1,1,0] op_sel_hi:[1,0,1] neg_lo:[0,1,0]
	v_pk_mul_f32 v[70:71], v[58:59], s[46:47] op_sel:[0,0] op_sel_hi:[0,1]
	v_add_u32_e32 v39, v78, v39
	v_pk_fma_f32 v[58:59], v[58:59], s[46:47], v[70:71] op_sel:[1,1,0] op_sel_hi:[1,0,1] neg_lo:[0,1,0]
	v_pk_mul_f32 v[70:71], v[28:29], s[44:45] op_sel:[0,0] op_sel_hi:[0,1]
	v_pk_fma_f32 v[70:71], v[28:29], s[44:45], v[70:71] op_sel:[1,1,0] op_sel_hi:[1,0,1] neg_lo:[0,1,0]
	v_pk_mul_f32 v[28:29], v[42:43], s[46:47] op_sel:[0,0] op_sel_hi:[0,1]
	v_pk_fma_f32 v[42:43], v[42:43], s[46:47], v[28:29] op_sel:[1,1,0] op_sel_hi:[1,0,1] neg_lo:[0,1,0]
	v_pk_mul_f32 v[72:73], v[44:45], s[48:49] op_sel:[0,0] op_sel_hi:[0,1]
	v_pk_fma_f32 v[44:45], v[44:45], s[48:49], v[72:73] op_sel:[1,1,0] op_sel_hi:[1,0,1] neg_lo:[0,1,0]
	v_pk_add_f32 v[72:73], v[54:55], v[50:51]
	v_pk_add_f32 v[50:51], v[54:55], v[50:51] neg_lo:[0,1] neg_hi:[0,1]
	v_pk_add_f32 v[54:55], v[40:41], v[52:53]
	v_pk_add_f32 v[40:41], v[40:41], v[52:53] neg_lo:[0,1] neg_hi:[0,1]
	v_pk_add_f32 v[52:53], v[72:73], v[54:55]
	v_pk_add_f32 v[54:55], v[72:73], v[54:55] neg_lo:[0,1] neg_hi:[0,1]
	v_pk_add_f32 v[72:73], v[50:51], v[40:41] op_sel:[0,1] op_sel_hi:[1,0] neg_hi:[0,1]
	v_pk_add_f32 v[40:41], v[50:51], v[40:41] op_sel:[0,1] op_sel_hi:[1,0] neg_lo:[0,1]
	v_pk_add_f32 v[50:51], v[62:63], v[56:57]
	v_pk_add_f32 v[56:57], v[62:63], v[56:57] neg_lo:[0,1] neg_hi:[0,1]
	v_pk_add_f32 v[62:63], v[60:61], v[66:67]
	v_pk_add_f32 v[60:61], v[60:61], v[66:67] neg_lo:[0,1] neg_hi:[0,1]
	v_pk_add_f32 v[66:67], v[50:51], v[62:63]
	v_pk_add_f32 v[50:51], v[50:51], v[62:63] neg_lo:[0,1] neg_hi:[0,1]
	v_pk_add_f32 v[62:63], v[56:57], v[60:61] op_sel:[0,1] op_sel_hi:[1,0] neg_hi:[0,1]
	v_pk_add_f32 v[56:57], v[56:57], v[60:61] op_sel:[0,1] op_sel_hi:[1,0] neg_lo:[0,1]
	v_pk_add_f32 v[60:61], v[46:47], v[48:49]
	v_pk_add_f32 v[46:47], v[46:47], v[48:49] neg_lo:[0,1] neg_hi:[0,1]
	v_pk_add_f32 v[48:49], v[68:69], v[58:59]
	v_pk_add_f32 v[58:59], v[68:69], v[58:59] neg_lo:[0,1] neg_hi:[0,1]
	v_pk_add_f32 v[68:69], v[60:61], v[48:49]
	v_pk_add_f32 v[48:49], v[60:61], v[48:49] neg_lo:[0,1] neg_hi:[0,1]
	v_pk_add_f32 v[60:61], v[46:47], v[58:59] op_sel:[0,1] op_sel_hi:[1,0] neg_hi:[0,1]
	v_pk_add_f32 v[46:47], v[46:47], v[58:59] op_sel:[0,1] op_sel_hi:[1,0] neg_lo:[0,1]
	v_pk_add_f32 v[58:59], v[64:65], v[42:43]
	v_pk_add_f32 v[42:43], v[64:65], v[42:43] neg_lo:[0,1] neg_hi:[0,1]
	v_pk_add_f32 v[64:65], v[70:71], v[44:45]
	v_pk_add_f32 v[44:45], v[70:71], v[44:45] neg_lo:[0,1] neg_hi:[0,1]
	v_pk_add_f32 v[70:71], v[58:59], v[64:65]
	v_pk_add_f32 v[58:59], v[58:59], v[64:65] neg_lo:[0,1] neg_hi:[0,1]
	v_pk_add_f32 v[64:65], v[42:43], v[44:45] op_sel:[0,1] op_sel_hi:[1,0] neg_hi:[0,1]
	v_pk_add_f32 v[42:43], v[42:43], v[44:45] op_sel:[0,1] op_sel_hi:[1,0] neg_lo:[0,1]
	v_mov_b32_e32 v44, v1
	v_mov_b32_e32 v45, v31
	ds_write_b64 v74, v[52:53]
	v_pk_mul_f32 v[52:53], v[66:67], v[44:45] op_sel:[0,0] op_sel_hi:[0,1]
	v_pk_fma_f32 v[52:53], v[66:67], v[44:45], v[52:53] op_sel:[1,1,0] op_sel_hi:[1,0,1] neg_lo:[0,1,0]
	ds_write_b64 v74, v[52:53] offset:2176
	v_pk_mul_f32 v[52:53], v[44:45], v[44:45] op_sel:[0,0] op_sel_hi:[0,1]
	v_pk_fma_f32 v[52:53], v[44:45], v[44:45], v[52:53] op_sel:[1,1,0] op_sel_hi:[1,0,1] neg_lo:[0,1,0]
	v_pk_mul_f32 v[66:67], v[68:69], v[52:53] op_sel:[0,0] op_sel_hi:[0,1]
	v_pk_fma_f32 v[66:67], v[68:69], v[52:53], v[66:67] op_sel:[1,1,0] op_sel_hi:[1,0,1] neg_lo:[0,1,0]
	ds_write_b64 v74, v[66:67] offset:4352
	v_pk_mul_f32 v[66:67], v[52:53], v[44:45] op_sel:[0,0] op_sel_hi:[0,1]
	v_pk_fma_f32 v[52:53], v[52:53], v[44:45], v[66:67] op_sel:[1,1,0] op_sel_hi:[1,0,1] neg_lo:[0,1,0]
	v_pk_mul_f32 v[66:67], v[70:71], v[52:53] op_sel:[0,0] op_sel_hi:[0,1]
	v_pk_fma_f32 v[66:67], v[70:71], v[52:53], v[66:67] op_sel:[1,1,0] op_sel_hi:[1,0,1] neg_lo:[0,1,0]
	ds_write_b64 v74, v[66:67] offset:6528
	v_pk_mul_f32 v[66:67], v[52:53], v[44:45] op_sel:[0,0] op_sel_hi:[0,1]
	v_pk_fma_f32 v[52:53], v[52:53], v[44:45], v[66:67] op_sel:[1,1,0] op_sel_hi:[1,0,1] neg_lo:[0,1,0]
	v_pk_mul_f32 v[66:67], v[72:73], v[52:53] op_sel:[0,0] op_sel_hi:[0,1]
	v_pk_fma_f32 v[66:67], v[72:73], v[52:53], v[66:67] op_sel:[1,1,0] op_sel_hi:[1,0,1] neg_lo:[0,1,0]
	ds_write_b64 v74, v[66:67] offset:8704
	v_pk_mul_f32 v[66:67], v[52:53], v[44:45] op_sel:[0,0] op_sel_hi:[0,1]
	v_pk_fma_f32 v[52:53], v[52:53], v[44:45], v[66:67] op_sel:[1,1,0] op_sel_hi:[1,0,1] neg_lo:[0,1,0]
	v_pk_mul_f32 v[66:67], v[62:63], v[52:53] op_sel:[0,0] op_sel_hi:[0,1]
	v_pk_fma_f32 v[62:63], v[62:63], v[52:53], v[66:67] op_sel:[1,1,0] op_sel_hi:[1,0,1] neg_lo:[0,1,0]
	ds_write_b64 v74, v[62:63] offset:10880
	v_pk_mul_f32 v[62:63], v[52:53], v[44:45] op_sel:[0,0] op_sel_hi:[0,1]
	v_pk_fma_f32 v[52:53], v[52:53], v[44:45], v[62:63] op_sel:[1,1,0] op_sel_hi:[1,0,1] neg_lo:[0,1,0]
	v_pk_mul_f32 v[62:63], v[60:61], v[52:53] op_sel:[0,0] op_sel_hi:[0,1]
	v_pk_fma_f32 v[60:61], v[60:61], v[52:53], v[62:63] op_sel:[1,1,0] op_sel_hi:[1,0,1] neg_lo:[0,1,0]
	ds_write_b64 v74, v[60:61] offset:13056
	v_pk_mul_f32 v[60:61], v[52:53], v[44:45] op_sel:[0,0] op_sel_hi:[0,1]
	v_pk_fma_f32 v[52:53], v[52:53], v[44:45], v[60:61] op_sel:[1,1,0] op_sel_hi:[1,0,1] neg_lo:[0,1,0]
	v_pk_mul_f32 v[60:61], v[64:65], v[52:53] op_sel:[0,0] op_sel_hi:[0,1]
	v_pk_fma_f32 v[60:61], v[64:65], v[52:53], v[60:61] op_sel:[1,1,0] op_sel_hi:[1,0,1] neg_lo:[0,1,0]
	ds_write_b64 v74, v[60:61] offset:15232
	v_pk_mul_f32 v[60:61], v[52:53], v[44:45] op_sel:[0,0] op_sel_hi:[0,1]
	v_pk_fma_f32 v[52:53], v[52:53], v[44:45], v[60:61] op_sel:[1,1,0] op_sel_hi:[1,0,1] neg_lo:[0,1,0]
	v_pk_mul_f32 v[60:61], v[54:55], v[52:53] op_sel:[0,0] op_sel_hi:[0,1]
	v_pk_fma_f32 v[54:55], v[54:55], v[52:53], v[60:61] op_sel:[1,1,0] op_sel_hi:[1,0,1] neg_lo:[0,1,0]
	ds_write_b64 v74, v[54:55] offset:17408
	v_pk_mul_f32 v[54:55], v[52:53], v[44:45] op_sel:[0,0] op_sel_hi:[0,1]
	v_pk_fma_f32 v[52:53], v[52:53], v[44:45], v[54:55] op_sel:[1,1,0] op_sel_hi:[1,0,1] neg_lo:[0,1,0]
	v_pk_mul_f32 v[54:55], v[50:51], v[52:53] op_sel:[0,0] op_sel_hi:[0,1]
	v_pk_fma_f32 v[50:51], v[50:51], v[52:53], v[54:55] op_sel:[1,1,0] op_sel_hi:[1,0,1] neg_lo:[0,1,0]
	ds_write_b64 v74, v[50:51] offset:19584
	v_pk_mul_f32 v[50:51], v[52:53], v[44:45] op_sel:[0,0] op_sel_hi:[0,1]
	v_pk_fma_f32 v[50:51], v[52:53], v[44:45], v[50:51] op_sel:[1,1,0] op_sel_hi:[1,0,1] neg_lo:[0,1,0]
	v_pk_mul_f32 v[52:53], v[48:49], v[50:51] op_sel:[0,0] op_sel_hi:[0,1]
	v_pk_fma_f32 v[48:49], v[48:49], v[50:51], v[52:53] op_sel:[1,1,0] op_sel_hi:[1,0,1] neg_lo:[0,1,0]
	ds_write_b64 v74, v[48:49] offset:21760
	v_pk_mul_f32 v[48:49], v[50:51], v[44:45] op_sel:[0,0] op_sel_hi:[0,1]
	v_pk_fma_f32 v[48:49], v[50:51], v[44:45], v[48:49] op_sel:[1,1,0] op_sel_hi:[1,0,1] neg_lo:[0,1,0]
	v_pk_mul_f32 v[50:51], v[58:59], v[48:49] op_sel:[0,0] op_sel_hi:[0,1]
	v_pk_fma_f32 v[50:51], v[58:59], v[48:49], v[50:51] op_sel:[1,1,0] op_sel_hi:[1,0,1] neg_lo:[0,1,0]
	ds_write_b64 v74, v[50:51] offset:23936
	v_pk_mul_f32 v[50:51], v[48:49], v[44:45] op_sel:[0,0] op_sel_hi:[0,1]
	v_pk_fma_f32 v[48:49], v[48:49], v[44:45], v[50:51] op_sel:[1,1,0] op_sel_hi:[1,0,1] neg_lo:[0,1,0]
	v_pk_mul_f32 v[50:51], v[40:41], v[48:49] op_sel:[0,0] op_sel_hi:[0,1]
	v_pk_fma_f32 v[40:41], v[40:41], v[48:49], v[50:51] op_sel:[1,1,0] op_sel_hi:[1,0,1] neg_lo:[0,1,0]
	ds_write_b64 v74, v[40:41] offset:26112
	v_pk_mul_f32 v[40:41], v[48:49], v[44:45] op_sel:[0,0] op_sel_hi:[0,1]
	v_pk_fma_f32 v[40:41], v[48:49], v[44:45], v[40:41] op_sel:[1,1,0] op_sel_hi:[1,0,1] neg_lo:[0,1,0]
	v_pk_mul_f32 v[48:49], v[56:57], v[40:41] op_sel:[0,0] op_sel_hi:[0,1]
	v_pk_fma_f32 v[48:49], v[56:57], v[40:41], v[48:49] op_sel:[1,1,0] op_sel_hi:[1,0,1] neg_lo:[0,1,0]
	ds_write_b64 v74, v[48:49] offset:28288
	v_pk_mul_f32 v[48:49], v[40:41], v[44:45] op_sel:[0,0] op_sel_hi:[0,1]
	v_pk_fma_f32 v[40:41], v[40:41], v[44:45], v[48:49] op_sel:[1,1,0] op_sel_hi:[1,0,1] neg_lo:[0,1,0]
	v_pk_mul_f32 v[48:49], v[46:47], v[40:41] op_sel:[0,0] op_sel_hi:[0,1]
	v_pk_fma_f32 v[46:47], v[46:47], v[40:41], v[48:49] op_sel:[1,1,0] op_sel_hi:[1,0,1] neg_lo:[0,1,0]
	ds_write_b64 v74, v[46:47] offset:30464
	v_pk_mul_f32 v[46:47], v[40:41], v[44:45] op_sel:[0,0] op_sel_hi:[0,1]
	v_pk_fma_f32 v[40:41], v[40:41], v[44:45], v[46:47] op_sel:[1,1,0] op_sel_hi:[1,0,1] neg_lo:[0,1,0]
	v_pk_mul_f32 v[44:45], v[42:43], v[40:41] op_sel:[0,0] op_sel_hi:[0,1]
	v_pk_fma_f32 v[40:41], v[42:43], v[40:41], v[44:45] op_sel:[1,1,0] op_sel_hi:[1,0,1] neg_lo:[0,1,0]
	ds_write_b64 v74, v[40:41] offset:32640
	s_waitcnt lgkmcnt(0)
	s_barrier
	ds_read2_b64 v[40:43], v39 offset1:17
	ds_read2_b64 v[44:47], v39 offset0:34 offset1:51
	ds_read2_b64 v[48:51], v39 offset0:68 offset1:85
	ds_read2_b64 v[52:55], v39 offset0:136 offset1:153
	ds_read2_b64 v[56:59], v39 offset0:102 offset1:119
	ds_read2_b64 v[60:63], v39 offset0:204 offset1:221
	ds_read2_b64 v[64:67], v39 offset0:170 offset1:187
	ds_read2_b64 v[68:71], v39 offset0:238 offset1:255
	s_waitcnt lgkmcnt(4)
	v_pk_add_f32 v[72:73], v[40:41], v[52:53]
	v_pk_add_f32 v[40:41], v[40:41], v[52:53] neg_lo:[0,1] neg_hi:[0,1]
	s_waitcnt lgkmcnt(2)
	v_pk_add_f32 v[52:53], v[48:49], v[60:61]
	v_pk_add_f32 v[48:49], v[48:49], v[60:61] neg_lo:[0,1] neg_hi:[0,1]
	v_pk_add_f32 v[60:61], v[72:73], v[52:53]
	v_pk_add_f32 v[52:53], v[72:73], v[52:53] neg_lo:[0,1] neg_hi:[0,1]
	v_pk_add_f32 v[72:73], v[40:41], v[48:49] op_sel:[0,1] op_sel_hi:[1,0] neg_hi:[0,1]
	v_pk_add_f32 v[40:41], v[40:41], v[48:49] op_sel:[0,1] op_sel_hi:[1,0] neg_lo:[0,1]
	v_pk_add_f32 v[48:49], v[42:43], v[54:55]
	v_pk_add_f32 v[42:43], v[42:43], v[54:55] neg_lo:[0,1] neg_hi:[0,1]
	v_pk_add_f32 v[54:55], v[50:51], v[62:63]
	v_pk_add_f32 v[50:51], v[50:51], v[62:63] neg_lo:[0,1] neg_hi:[0,1]
	v_pk_add_f32 v[62:63], v[48:49], v[54:55]
	v_pk_add_f32 v[48:49], v[48:49], v[54:55] neg_lo:[0,1] neg_hi:[0,1]
	v_pk_add_f32 v[54:55], v[42:43], v[50:51] op_sel:[0,1] op_sel_hi:[1,0] neg_hi:[0,1]
	v_pk_add_f32 v[42:43], v[42:43], v[50:51] op_sel:[0,1] op_sel_hi:[1,0] neg_lo:[0,1]
	s_waitcnt lgkmcnt(1)
	v_pk_add_f32 v[50:51], v[44:45], v[64:65]
	v_pk_add_f32 v[44:45], v[44:45], v[64:65] neg_lo:[0,1] neg_hi:[0,1]
	s_waitcnt lgkmcnt(0)
	v_pk_add_f32 v[64:65], v[56:57], v[68:69]
	v_pk_add_f32 v[56:57], v[56:57], v[68:69] neg_lo:[0,1] neg_hi:[0,1]
	v_pk_add_f32 v[68:69], v[50:51], v[64:65]
	v_pk_add_f32 v[50:51], v[50:51], v[64:65] neg_lo:[0,1] neg_hi:[0,1]
	v_pk_add_f32 v[64:65], v[44:45], v[56:57] op_sel:[0,1] op_sel_hi:[1,0] neg_hi:[0,1]
	v_pk_add_f32 v[44:45], v[44:45], v[56:57] op_sel:[0,1] op_sel_hi:[1,0] neg_lo:[0,1]
	v_pk_add_f32 v[56:57], v[46:47], v[66:67]
	v_pk_add_f32 v[46:47], v[46:47], v[66:67] neg_lo:[0,1] neg_hi:[0,1]
	v_pk_add_f32 v[66:67], v[58:59], v[70:71]
	v_pk_add_f32 v[58:59], v[58:59], v[70:71] neg_lo:[0,1] neg_hi:[0,1]
	v_pk_add_f32 v[70:71], v[56:57], v[66:67]
	v_pk_add_f32 v[56:57], v[56:57], v[66:67] neg_lo:[0,1] neg_hi:[0,1]
	v_pk_add_f32 v[66:67], v[46:47], v[58:59] op_sel:[0,1] op_sel_hi:[1,0] neg_hi:[0,1]
	v_pk_add_f32 v[46:47], v[46:47], v[58:59] op_sel:[0,1] op_sel_hi:[1,0] neg_lo:[0,1]
	v_pk_mul_f32 v[58:59], v[54:55], s[38:39] op_sel:[0,0] op_sel_hi:[0,1]
	v_pk_fma_f32 v[54:55], v[54:55], s[38:39], v[58:59] op_sel:[1,1,0] op_sel_hi:[1,0,1] neg_lo:[0,1,0]
	v_pk_mul_f32 v[58:59], v[64:65], s[40:41] op_sel:[0,0] op_sel_hi:[0,1]
	v_pk_fma_f32 v[58:59], v[64:65], s[40:41], v[58:59] op_sel:[1,1,0] op_sel_hi:[1,0,1] neg_lo:[0,1,0]
	v_pk_mul_f32 v[64:65], v[66:67], s[44:45] op_sel:[0,0] op_sel_hi:[0,1]
	v_pk_fma_f32 v[64:65], v[66:67], s[44:45], v[64:65] op_sel:[1,1,0] op_sel_hi:[1,0,1] neg_lo:[0,1,0]
	v_pk_mul_f32 v[66:67], v[48:49], s[40:41] op_sel:[0,0] op_sel_hi:[0,1]
	v_pk_fma_f32 v[48:49], v[48:49], s[40:41], v[66:67] op_sel:[1,1,0] op_sel_hi:[1,0,1] neg_lo:[0,1,0]
	v_pk_mul_f32 v[66:67], v[50:51], s[36:37] op_sel:[0,0] op_sel_hi:[0,1]
	v_pk_fma_f32 v[50:51], v[50:51], s[36:37], v[66:67] op_sel:[1,1,0] op_sel_hi:[1,0,1] neg_lo:[0,1,0]
	v_pk_mul_f32 v[66:67], v[56:57], s[46:47] op_sel:[0,0] op_sel_hi:[0,1]
	v_pk_fma_f32 v[56:57], v[56:57], s[46:47], v[66:67] op_sel:[1,1,0] op_sel_hi:[1,0,1] neg_lo:[0,1,0]
	v_pk_mul_f32 v[66:67], v[42:43], s[44:45] op_sel:[0,0] op_sel_hi:[0,1]
	v_pk_fma_f32 v[42:43], v[42:43], s[44:45], v[66:67] op_sel:[1,1,0] op_sel_hi:[1,0,1] neg_lo:[0,1,0]
	v_pk_mul_f32 v[66:67], v[44:45], s[46:47] op_sel:[0,0] op_sel_hi:[0,1]
	v_pk_fma_f32 v[44:45], v[44:45], s[46:47], v[66:67] op_sel:[1,1,0] op_sel_hi:[1,0,1] neg_lo:[0,1,0]
	v_pk_mul_f32 v[66:67], v[46:47], s[48:49] op_sel:[0,0] op_sel_hi:[0,1]
	v_pk_fma_f32 v[46:47], v[46:47], s[48:49], v[66:67] op_sel:[1,1,0] op_sel_hi:[1,0,1] neg_lo:[0,1,0]
	v_pk_add_f32 v[66:67], v[60:61], v[68:69]
	v_pk_add_f32 v[60:61], v[60:61], v[68:69] neg_lo:[0,1] neg_hi:[0,1]
	v_pk_add_f32 v[68:69], v[62:63], v[70:71]
	v_pk_add_f32 v[62:63], v[62:63], v[70:71] neg_lo:[0,1] neg_hi:[0,1]
	v_pk_add_f32 v[70:71], v[66:67], v[68:69]
	v_pk_add_f32 v[66:67], v[66:67], v[68:69] neg_lo:[0,1] neg_hi:[0,1]
	v_pk_add_f32 v[68:69], v[60:61], v[62:63] op_sel:[0,1] op_sel_hi:[1,0] neg_hi:[0,1]
	v_pk_add_f32 v[60:61], v[60:61], v[62:63] op_sel:[0,1] op_sel_hi:[1,0] neg_lo:[0,1]
	v_pk_add_f32 v[62:63], v[72:73], v[58:59]
	v_pk_add_f32 v[58:59], v[72:73], v[58:59] neg_lo:[0,1] neg_hi:[0,1]
	v_pk_add_f32 v[72:73], v[54:55], v[64:65]
	v_pk_add_f32 v[54:55], v[54:55], v[64:65] neg_lo:[0,1] neg_hi:[0,1]
	v_pk_add_f32 v[64:65], v[62:63], v[72:73]
	v_pk_add_f32 v[62:63], v[62:63], v[72:73] neg_lo:[0,1] neg_hi:[0,1]
	v_pk_add_f32 v[72:73], v[58:59], v[54:55] op_sel:[0,1] op_sel_hi:[1,0] neg_hi:[0,1]
	v_pk_add_f32 v[54:55], v[58:59], v[54:55] op_sel:[0,1] op_sel_hi:[1,0] neg_lo:[0,1]
	v_pk_add_f32 v[58:59], v[52:53], v[50:51]
	v_pk_add_f32 v[50:51], v[52:53], v[50:51] neg_lo:[0,1] neg_hi:[0,1]
	v_pk_add_f32 v[52:53], v[48:49], v[56:57]
	v_pk_add_f32 v[48:49], v[48:49], v[56:57] neg_lo:[0,1] neg_hi:[0,1]
	v_pk_add_f32 v[56:57], v[58:59], v[52:53]
	v_pk_add_f32 v[52:53], v[58:59], v[52:53] neg_lo:[0,1] neg_hi:[0,1]
	v_pk_add_f32 v[58:59], v[50:51], v[48:49] op_sel:[0,1] op_sel_hi:[1,0] neg_hi:[0,1]
	v_pk_add_f32 v[48:49], v[50:51], v[48:49] op_sel:[0,1] op_sel_hi:[1,0] neg_lo:[0,1]
	v_pk_add_f32 v[50:51], v[40:41], v[44:45]
	v_pk_add_f32 v[40:41], v[40:41], v[44:45] neg_lo:[0,1] neg_hi:[0,1]
	v_pk_add_f32 v[44:45], v[42:43], v[46:47]
	v_pk_add_f32 v[42:43], v[42:43], v[46:47] neg_lo:[0,1] neg_hi:[0,1]
	v_pk_add_f32 v[46:47], v[50:51], v[44:45]
	v_pk_add_f32 v[44:45], v[50:51], v[44:45] neg_lo:[0,1] neg_hi:[0,1]
	v_pk_add_f32 v[50:51], v[40:41], v[42:43] op_sel:[0,1] op_sel_hi:[1,0] neg_hi:[0,1]
	v_pk_add_f32 v[40:41], v[40:41], v[42:43] op_sel:[0,1] op_sel_hi:[1,0] neg_lo:[0,1]
	v_mov_b32_e32 v42, v30
	v_mov_b32_e32 v43, v32
	s_nop 0
	v_pk_mul_f32 v[74:75], v[64:65], v[42:43] op_sel:[0,0] op_sel_hi:[0,1]
	v_pk_fma_f32 v[64:65], v[64:65], v[42:43], v[74:75] op_sel:[1,1,0] op_sel_hi:[1,0,1] neg_lo:[0,1,0]
	ds_write2_b64 v39, v[70:71], v[64:65] offset1:17
	v_pk_mul_f32 v[64:65], v[42:43], v[42:43] op_sel:[0,0] op_sel_hi:[0,1]
	v_pk_fma_f32 v[64:65], v[42:43], v[42:43], v[64:65] op_sel:[1,1,0] op_sel_hi:[1,0,1] neg_lo:[0,1,0]
	v_pk_mul_f32 v[70:71], v[56:57], v[64:65] op_sel:[0,0] op_sel_hi:[0,1]
	v_pk_fma_f32 v[56:57], v[56:57], v[64:65], v[70:71] op_sel:[1,1,0] op_sel_hi:[1,0,1] neg_lo:[0,1,0]
	v_pk_mul_f32 v[70:71], v[64:65], v[42:43] op_sel:[0,0] op_sel_hi:[0,1]
	v_pk_fma_f32 v[64:65], v[64:65], v[42:43], v[70:71] op_sel:[1,1,0] op_sel_hi:[1,0,1] neg_lo:[0,1,0]
	v_pk_mul_f32 v[70:71], v[46:47], v[64:65] op_sel:[0,0] op_sel_hi:[0,1]
	v_pk_fma_f32 v[46:47], v[46:47], v[64:65], v[70:71] op_sel:[1,1,0] op_sel_hi:[1,0,1] neg_lo:[0,1,0]
	ds_write2_b64 v39, v[56:57], v[46:47] offset0:34 offset1:51
	v_pk_mul_f32 v[46:47], v[64:65], v[42:43] op_sel:[0,0] op_sel_hi:[0,1]
	v_pk_fma_f32 v[46:47], v[64:65], v[42:43], v[46:47] op_sel:[1,1,0] op_sel_hi:[1,0,1] neg_lo:[0,1,0]
	v_pk_mul_f32 v[56:57], v[68:69], v[46:47] op_sel:[0,0] op_sel_hi:[0,1]
	v_pk_mul_f32 v[64:65], v[46:47], v[42:43] op_sel:[0,0] op_sel_hi:[0,1]
	v_pk_fma_f32 v[56:57], v[68:69], v[46:47], v[56:57] op_sel:[1,1,0] op_sel_hi:[1,0,1] neg_lo:[0,1,0]
	v_pk_fma_f32 v[46:47], v[46:47], v[42:43], v[64:65] op_sel:[1,1,0] op_sel_hi:[1,0,1] neg_lo:[0,1,0]
	v_pk_mul_f32 v[64:65], v[72:73], v[46:47] op_sel:[0,0] op_sel_hi:[0,1]
	v_pk_fma_f32 v[64:65], v[72:73], v[46:47], v[64:65] op_sel:[1,1,0] op_sel_hi:[1,0,1] neg_lo:[0,1,0]
	ds_write2_b64 v39, v[56:57], v[64:65] offset0:68 offset1:85
	v_pk_mul_f32 v[56:57], v[46:47], v[42:43] op_sel:[0,0] op_sel_hi:[0,1]
	v_pk_fma_f32 v[46:47], v[46:47], v[42:43], v[56:57] op_sel:[1,1,0] op_sel_hi:[1,0,1] neg_lo:[0,1,0]
	v_pk_mul_f32 v[56:57], v[58:59], v[46:47] op_sel:[0,0] op_sel_hi:[0,1]
	v_pk_fma_f32 v[56:57], v[58:59], v[46:47], v[56:57] op_sel:[1,1,0] op_sel_hi:[1,0,1] neg_lo:[0,1,0]
	v_pk_mul_f32 v[58:59], v[46:47], v[42:43] op_sel:[0,0] op_sel_hi:[0,1]
	v_pk_fma_f32 v[46:47], v[46:47], v[42:43], v[58:59] op_sel:[1,1,0] op_sel_hi:[1,0,1] neg_lo:[0,1,0]
	v_pk_mul_f32 v[58:59], v[50:51], v[46:47] op_sel:[0,0] op_sel_hi:[0,1]
	v_pk_fma_f32 v[50:51], v[50:51], v[46:47], v[58:59] op_sel:[1,1,0] op_sel_hi:[1,0,1] neg_lo:[0,1,0]
	ds_write2_b64 v39, v[56:57], v[50:51] offset0:102 offset1:119
	v_pk_mul_f32 v[50:51], v[46:47], v[42:43] op_sel:[0,0] op_sel_hi:[0,1]
	v_pk_fma_f32 v[46:47], v[46:47], v[42:43], v[50:51] op_sel:[1,1,0] op_sel_hi:[1,0,1] neg_lo:[0,1,0]
	v_pk_mul_f32 v[50:51], v[66:67], v[46:47] op_sel:[0,0] op_sel_hi:[0,1]
	v_pk_mul_f32 v[56:57], v[46:47], v[42:43] op_sel:[0,0] op_sel_hi:[0,1]
	v_pk_fma_f32 v[50:51], v[66:67], v[46:47], v[50:51] op_sel:[1,1,0] op_sel_hi:[1,0,1] neg_lo:[0,1,0]
	v_pk_fma_f32 v[46:47], v[46:47], v[42:43], v[56:57] op_sel:[1,1,0] op_sel_hi:[1,0,1] neg_lo:[0,1,0]
	v_pk_mul_f32 v[56:57], v[62:63], v[46:47] op_sel:[0,0] op_sel_hi:[0,1]
	v_pk_fma_f32 v[56:57], v[62:63], v[46:47], v[56:57] op_sel:[1,1,0] op_sel_hi:[1,0,1] neg_lo:[0,1,0]
	ds_write2_b64 v39, v[50:51], v[56:57] offset0:136 offset1:153
	v_pk_mul_f32 v[50:51], v[46:47], v[42:43] op_sel:[0,0] op_sel_hi:[0,1]
	v_pk_fma_f32 v[46:47], v[46:47], v[42:43], v[50:51] op_sel:[1,1,0] op_sel_hi:[1,0,1] neg_lo:[0,1,0]
	v_pk_mul_f32 v[50:51], v[52:53], v[46:47] op_sel:[0,0] op_sel_hi:[0,1]
	v_pk_fma_f32 v[50:51], v[52:53], v[46:47], v[50:51] op_sel:[1,1,0] op_sel_hi:[1,0,1] neg_lo:[0,1,0]
	v_pk_mul_f32 v[52:53], v[46:47], v[42:43] op_sel:[0,0] op_sel_hi:[0,1]
	v_pk_fma_f32 v[46:47], v[46:47], v[42:43], v[52:53] op_sel:[1,1,0] op_sel_hi:[1,0,1] neg_lo:[0,1,0]
	v_pk_mul_f32 v[52:53], v[44:45], v[46:47] op_sel:[0,0] op_sel_hi:[0,1]
	v_pk_fma_f32 v[44:45], v[44:45], v[46:47], v[52:53] op_sel:[1,1,0] op_sel_hi:[1,0,1] neg_lo:[0,1,0]
	ds_write2_b64 v39, v[50:51], v[44:45] offset0:170 offset1:187
	v_pk_mul_f32 v[44:45], v[46:47], v[42:43] op_sel:[0,0] op_sel_hi:[0,1]
	v_pk_fma_f32 v[44:45], v[46:47], v[42:43], v[44:45] op_sel:[1,1,0] op_sel_hi:[1,0,1] neg_lo:[0,1,0]
	v_pk_mul_f32 v[46:47], v[60:61], v[44:45] op_sel:[0,0] op_sel_hi:[0,1]
	v_pk_mul_f32 v[50:51], v[44:45], v[42:43] op_sel:[0,0] op_sel_hi:[0,1]
	v_pk_fma_f32 v[46:47], v[60:61], v[44:45], v[46:47] op_sel:[1,1,0] op_sel_hi:[1,0,1] neg_lo:[0,1,0]
	v_pk_fma_f32 v[44:45], v[44:45], v[42:43], v[50:51] op_sel:[1,1,0] op_sel_hi:[1,0,1] neg_lo:[0,1,0]
	v_pk_mul_f32 v[50:51], v[54:55], v[44:45] op_sel:[0,0] op_sel_hi:[0,1]
	v_pk_fma_f32 v[50:51], v[54:55], v[44:45], v[50:51] op_sel:[1,1,0] op_sel_hi:[1,0,1] neg_lo:[0,1,0]
	ds_write2_b64 v39, v[46:47], v[50:51] offset0:204 offset1:221
	v_pk_mul_f32 v[46:47], v[44:45], v[42:43] op_sel:[0,0] op_sel_hi:[0,1]
	v_pk_fma_f32 v[44:45], v[44:45], v[42:43], v[46:47] op_sel:[1,1,0] op_sel_hi:[1,0,1] neg_lo:[0,1,0]
	v_pk_mul_f32 v[46:47], v[48:49], v[44:45] op_sel:[0,0] op_sel_hi:[0,1]
	v_pk_fma_f32 v[46:47], v[48:49], v[44:45], v[46:47] op_sel:[1,1,0] op_sel_hi:[1,0,1] neg_lo:[0,1,0]
	v_pk_mul_f32 v[48:49], v[44:45], v[42:43] op_sel:[0,0] op_sel_hi:[0,1]
	v_pk_fma_f32 v[42:43], v[44:45], v[42:43], v[48:49] op_sel:[1,1,0] op_sel_hi:[1,0,1] neg_lo:[0,1,0]
	v_pk_mul_f32 v[44:45], v[40:41], v[42:43] op_sel:[0,0] op_sel_hi:[0,1]
	v_pk_fma_f32 v[40:41], v[40:41], v[42:43], v[44:45] op_sel:[1,1,0] op_sel_hi:[1,0,1] neg_lo:[0,1,0]
	ds_write2_b64 v39, v[46:47], v[40:41] offset0:238 offset1:255
	v_mad_u32_u24 v39, v34, s55, v35
	s_waitcnt lgkmcnt(0)
	s_barrier
	ds_read2_b64 v[40:43], v39 offset1:1
	ds_read2_b64 v[44:47], v39 offset0:2 offset1:3
	ds_read2_b64 v[48:51], v39 offset0:8 offset1:9
	ds_read2_b64 v[52:55], v39 offset0:4 offset1:5
	ds_read2_b64 v[56:59], v39 offset0:6 offset1:7
	ds_read2_b64 v[60:63], v39 offset0:12 offset1:13
	ds_read2_b64 v[64:67], v39 offset0:10 offset1:11
	ds_read2_b64 v[68:71], v39 offset0:14 offset1:15
	s_waitcnt lgkmcnt(5)
	v_pk_add_f32 v[72:73], v[40:41], v[48:49]
	v_pk_add_f32 v[40:41], v[40:41], v[48:49] neg_lo:[0,1] neg_hi:[0,1]
	s_waitcnt lgkmcnt(2)
	v_pk_add_f32 v[48:49], v[52:53], v[60:61]
	v_pk_add_f32 v[52:53], v[52:53], v[60:61] neg_lo:[0,1] neg_hi:[0,1]
	v_pk_add_f32 v[60:61], v[72:73], v[48:49]
	v_pk_add_f32 v[48:49], v[72:73], v[48:49] neg_lo:[0,1] neg_hi:[0,1]
	v_pk_add_f32 v[72:73], v[40:41], v[52:53] op_sel:[0,1] op_sel_hi:[1,0] neg_hi:[0,1]
	v_pk_add_f32 v[40:41], v[40:41], v[52:53] op_sel:[0,1] op_sel_hi:[1,0] neg_lo:[0,1]
	v_pk_add_f32 v[52:53], v[42:43], v[50:51]
	v_pk_add_f32 v[42:43], v[42:43], v[50:51] neg_lo:[0,1] neg_hi:[0,1]
	v_pk_add_f32 v[50:51], v[54:55], v[62:63]
	v_pk_add_f32 v[54:55], v[54:55], v[62:63] neg_lo:[0,1] neg_hi:[0,1]
	v_pk_add_f32 v[62:63], v[52:53], v[50:51]
	v_pk_add_f32 v[50:51], v[52:53], v[50:51] neg_lo:[0,1] neg_hi:[0,1]
	v_pk_add_f32 v[52:53], v[42:43], v[54:55] op_sel:[0,1] op_sel_hi:[1,0] neg_hi:[0,1]
	v_pk_add_f32 v[42:43], v[42:43], v[54:55] op_sel:[0,1] op_sel_hi:[1,0] neg_lo:[0,1]
	s_waitcnt lgkmcnt(1)
	v_pk_add_f32 v[54:55], v[44:45], v[64:65]
	v_pk_add_f32 v[44:45], v[44:45], v[64:65] neg_lo:[0,1] neg_hi:[0,1]
	s_waitcnt lgkmcnt(0)
	v_pk_add_f32 v[64:65], v[56:57], v[68:69]
	v_pk_add_f32 v[56:57], v[56:57], v[68:69] neg_lo:[0,1] neg_hi:[0,1]
	v_pk_add_f32 v[68:69], v[54:55], v[64:65]
	v_pk_add_f32 v[54:55], v[54:55], v[64:65] neg_lo:[0,1] neg_hi:[0,1]
	v_pk_add_f32 v[64:65], v[44:45], v[56:57] op_sel:[0,1] op_sel_hi:[1,0] neg_hi:[0,1]
	v_pk_add_f32 v[44:45], v[44:45], v[56:57] op_sel:[0,1] op_sel_hi:[1,0] neg_lo:[0,1]
	v_pk_add_f32 v[56:57], v[46:47], v[66:67]
	v_pk_add_f32 v[46:47], v[46:47], v[66:67] neg_lo:[0,1] neg_hi:[0,1]
	v_pk_add_f32 v[66:67], v[58:59], v[70:71]
	v_pk_add_f32 v[58:59], v[58:59], v[70:71] neg_lo:[0,1] neg_hi:[0,1]
	v_pk_add_f32 v[70:71], v[56:57], v[66:67]
	v_pk_add_f32 v[56:57], v[56:57], v[66:67] neg_lo:[0,1] neg_hi:[0,1]
	v_pk_add_f32 v[66:67], v[46:47], v[58:59] op_sel:[0,1] op_sel_hi:[1,0] neg_hi:[0,1]
	v_pk_add_f32 v[46:47], v[46:47], v[58:59] op_sel:[0,1] op_sel_hi:[1,0] neg_lo:[0,1]
	v_pk_mul_f32 v[58:59], v[52:53], s[38:39] op_sel:[0,0] op_sel_hi:[0,1]
	v_pk_fma_f32 v[24:25], v[52:53], s[38:39], v[58:59] op_sel:[1,1,0] op_sel_hi:[1,0,1] neg_lo:[0,1,0]
	v_pk_mul_f32 v[52:53], v[64:65], s[40:41] op_sel:[0,0] op_sel_hi:[0,1]
	v_pk_mul_f32 v[58:59], v[66:67], s[44:45] op_sel:[0,0] op_sel_hi:[0,1]
	s_barrier
	v_pk_fma_f32 v[52:53], v[64:65], s[40:41], v[52:53] op_sel:[1,1,0] op_sel_hi:[1,0,1] neg_lo:[0,1,0]
	v_pk_mul_f32 v[64:65], v[50:51], s[40:41] op_sel:[0,0] op_sel_hi:[0,1]
	v_pk_fma_f32 v[58:59], v[66:67], s[44:45], v[58:59] op_sel:[1,1,0] op_sel_hi:[1,0,1] neg_lo:[0,1,0]
	v_pk_fma_f32 v[20:21], v[50:51], s[40:41], v[64:65] op_sel:[1,1,0] op_sel_hi:[1,0,1] neg_lo:[0,1,0]
	v_pk_mul_f32 v[50:51], v[54:55], s[36:37] op_sel:[0,0] op_sel_hi:[0,1]
	v_pk_fma_f32 v[26:27], v[54:55], s[36:37], v[50:51] op_sel:[1,1,0] op_sel_hi:[1,0,1] neg_lo:[0,1,0]
	v_pk_mul_f32 v[50:51], v[56:57], s[46:47] op_sel:[0,0] op_sel_hi:[0,1]
	v_pk_mul_f32 v[54:55], v[42:43], s[44:45] op_sel:[0,0] op_sel_hi:[0,1]
	v_pk_fma_f32 v[18:19], v[42:43], s[44:45], v[54:55] op_sel:[1,1,0] op_sel_hi:[1,0,1] neg_lo:[0,1,0]
	v_pk_mul_f32 v[42:43], v[44:45], s[46:47] op_sel:[0,0] op_sel_hi:[0,1]
	v_pk_fma_f32 v[50:51], v[56:57], s[46:47], v[50:51] op_sel:[1,1,0] op_sel_hi:[1,0,1] neg_lo:[0,1,0]
	v_pk_add_f32 v[54:55], v[24:25], v[58:59] neg_lo:[0,1] neg_hi:[0,1]
	v_pk_fma_f32 v[22:23], v[44:45], s[46:47], v[42:43] op_sel:[1,1,0] op_sel_hi:[1,0,1] neg_lo:[0,1,0]
	v_pk_mul_f32 v[42:43], v[46:47], s[48:49] op_sel:[0,0] op_sel_hi:[0,1]
	v_pk_add_f32 v[44:45], v[62:63], v[70:71] neg_lo:[0,1] neg_hi:[0,1]
	v_pk_fma_f32 v[28:29], v[46:47], s[48:49], v[42:43] op_sel:[1,1,0] op_sel_hi:[1,0,1] neg_lo:[0,1,0]
	v_pk_add_f32 v[42:43], v[60:61], v[68:69] neg_lo:[0,1] neg_hi:[0,1]
	v_pk_add_f32 v[74:75], v[18:19], v[28:29] neg_lo:[0,1] neg_hi:[0,1]
	v_pk_add_f32 v[46:47], v[42:43], v[44:45] op_sel:[0,1] op_sel_hi:[1,0] neg_hi:[0,1]
	v_pk_add_f32 v[42:43], v[42:43], v[44:45] op_sel:[0,1] op_sel_hi:[1,0] neg_lo:[0,1]
	v_pk_add_f32 v[44:45], v[72:73], v[52:53] neg_lo:[0,1] neg_hi:[0,1]
	v_and_b32_e32 v19, 0xf0, v36
	v_pk_add_f32 v[56:57], v[44:45], v[54:55] op_sel:[0,1] op_sel_hi:[1,0] neg_hi:[0,1]
	v_pk_add_f32 v[44:45], v[44:45], v[54:55] op_sel:[0,1] op_sel_hi:[1,0] neg_lo:[0,1]
	v_pk_add_f32 v[54:55], v[48:49], v[26:27] neg_lo:[0,1] neg_hi:[0,1]
	v_pk_add_f32 v[64:65], v[20:21], v[50:51] neg_lo:[0,1] neg_hi:[0,1]
	v_mul_i32_i24_e32 v21, 0xfffff804, v38
	v_lshlrev_b32_e32 v19, 2, v19
	v_pk_add_f32 v[66:67], v[54:55], v[64:65] op_sel:[0,1] op_sel_hi:[1,0] neg_hi:[0,1]
	v_pk_add_f32 v[54:55], v[54:55], v[64:65] op_sel:[0,1] op_sel_hi:[1,0] neg_lo:[0,1]
	v_pk_add_f32 v[64:65], v[40:41], v[22:23] neg_lo:[0,1] neg_hi:[0,1]
	v_add3_u32 v19, v78, v21, v19
	v_add_f32_e32 v21, v62, v70
	v_add_f32_e32 v23, v60, v68
	v_add_f32_e32 v24, v24, v58
	v_add_f32_e32 v27, v72, v52
	v_add_f32_e32 v25, v23, v21
	v_add_f32_e32 v29, v27, v24
	v_mul_f32_e32 v25, 0x3a800000, v25
	v_mul_f32_e32 v29, 0x3a800000, v29
	ds_write2st64_b32 v19, v25, v29 offset1:4
	v_add_f32_e32 v20, v20, v50
	v_add_f32_e32 v25, v48, v26
	v_add_f32_e32 v18, v18, v28
	v_add_f32_e32 v22, v40, v22
	v_add_f32_e32 v26, v25, v20
	v_add_f32_e32 v28, v22, v18
	v_sub_f32_e32 v20, v25, v20
	v_sub_f32_e32 v18, v22, v18
	v_mul_f32_e32 v26, 0x3a800000, v26
	v_mul_f32_e32 v28, 0x3a800000, v28
	v_mul_f32_e32 v20, 0x3a800000, v20
	v_mul_f32_e32 v18, 0x3a800000, v18
	ds_write2st64_b32 v19, v26, v28 offset0:8 offset1:12
	v_mul_f32_e32 v26, 0x3a800000, v46
	v_mul_f32_e32 v28, 0x3a800000, v56
	v_sub_f32_e32 v21, v23, v21
	v_sub_f32_e32 v23, v27, v24
	ds_write2st64_b32 v19, v20, v18 offset0:40 offset1:44
	v_mul_f32_e32 v18, 0x3a800000, v42
	v_mul_f32_e32 v20, 0x3a800000, v44
	v_pk_add_f32 v[76:77], v[64:65], v[74:75] op_sel:[0,1] op_sel_hi:[1,0] neg_hi:[0,1]
	v_pk_add_f32 v[64:65], v[64:65], v[74:75] op_sel:[0,1] op_sel_hi:[1,0] neg_lo:[0,1]
	ds_write2st64_b32 v19, v26, v28 offset0:16 offset1:20
	v_mul_f32_e32 v26, 0x3a800000, v66
	v_mul_f32_e32 v28, 0x3a800000, v76
	v_mul_f32_e32 v21, 0x3a800000, v21
	v_mul_f32_e32 v23, 0x3a800000, v23
	ds_write2st64_b32 v19, v18, v20 offset0:48 offset1:52
	v_mul_f32_e32 v18, 0x3a800000, v54
	v_mul_f32_e32 v20, 0x3a800000, v64
	v_mov_b32_e32 v22, v34
	ds_write2st64_b32 v19, v26, v28 offset0:24 offset1:28
	ds_write2st64_b32 v19, v21, v23 offset0:32 offset1:36
	ds_write2st64_b32 v19, v18, v20 offset0:56 offset1:60
	s_waitcnt lgkmcnt(0)
	s_barrier
	v_lshlrev_b32_e32 v26, 12, v37
	v_lshl_add_u32 v23, v22, 5, v35
	ds_read_b128 v[18:21], v23
	v_lshlrev_b32_e32 v28, 3, v22
	ds_read_b128 v[22:25], v23 offset:16
	v_ashrrev_i32_e32 v27, 31, v26
	v_lshlrev_b64 v[26:27], 1, v[26:27]
	s_waitcnt lgkmcnt(1)
	v_cvt_pk_bf16_f32 v18, v18, v18
	v_lshrrev_b32_e32 v18, 16, v18
	v_cvt_pk_bf16_f32 v19, v19, v19
	v_and_or_b32 v18, v19, s57, v18
	v_cvt_pk_bf16_f32 v19, v20, v21
	s_waitcnt lgkmcnt(0)
	v_cvt_pk_bf16_f32 v20, v22, v23
	v_cvt_pk_bf16_f32 v21, v24, v25
	v_ashrrev_i32_e32 v29, 31, v28
	v_lshl_add_u64 v[22:23], v[28:29], 1, v[26:27]
	v_lshl_add_u64 v[22:23], s[26:27], 0, v[22:23]
	global_store_dwordx4 v[22:23], v[18:21], off
	s_nop 0
	v_lshl_add_u32 v22, v34, 5, v35
	ds_read_b128 v[18:21], v22 offset:8192
	ds_read_b128 v[22:25], v22 offset:8208
	v_lshl_add_u32 v28, v34, 3, v33
	s_waitcnt lgkmcnt(1)
	v_cvt_pk_bf16_f32 v18, v18, v18
	v_lshrrev_b32_e32 v18, 16, v18
	v_cvt_pk_bf16_f32 v19, v19, v19
	v_and_or_b32 v18, v19, s57, v18
	v_cvt_pk_bf16_f32 v19, v20, v21
	s_waitcnt lgkmcnt(0)
	v_cvt_pk_bf16_f32 v20, v22, v23
	v_cvt_pk_bf16_f32 v21, v24, v25
	v_ashrrev_i32_e32 v29, 31, v28
	v_lshl_add_u64 v[22:23], v[28:29], 1, v[26:27]
	v_lshl_add_u64 v[22:23], s[26:27], 0, v[22:23]
	s_add_u32 s26, s26, s34
	s_addc_u32 s27, s27, s35
	s_andn2_b64 vcc, exec, s[50:51]
	global_store_dwordx4 v[22:23], v[18:21], off
	s_barrier
	s_cbranch_vccz .LBB0_1712

.LBB0_3100:
	s_or_b64 exec, exec, s[50:51]
	v_mov_b32_e32 v16, v6
	v_mov_b32_e32 v17, v2
	v_mov_b32_e32 v2, v7
	v_mov_b32_e32 v6, v8
	v_mov_b32_e32 v7, v4
	v_mov_b32_e32 v4, v9
	v_pk_add_f32 v[2:3], v[16:17], v[2:3]
	v_pk_add_f32 v[4:5], v[6:7], v[4:5]
	v_pk_add_f32 v[6:7], v[24:25], v[40:41]
	v_pk_add_f32 v[2:3], v[2:3], v[4:5]
	v_pk_add_f32 v[4:5], v[14:15], v[32:33] neg_lo:[0,1] neg_hi:[0,1]
	v_add_f32_e32 v10, v2, v3
	v_pk_add_f32 v[2:3], v[14:15], v[32:33]
	v_pk_add_f32 v[8:9], v[24:25], v[40:41] neg_lo:[0,1] neg_hi:[0,1]
	v_pk_add_f32 v[24:25], v[2:3], v[6:7]
	v_pk_add_f32 v[32:33], v[2:3], v[6:7] neg_lo:[0,1] neg_hi:[0,1]
	v_pk_add_f32 v[40:41], v[4:5], v[8:9] op_sel:[0,1] op_sel_hi:[1,0] neg_hi:[0,1]
	s_waitcnt lgkmcnt(1)
	v_pk_add_f32 v[48:49], v[4:5], v[8:9] op_sel:[0,1] op_sel_hi:[1,0] neg_lo:[0,1]
	v_pk_add_f32 v[2:3], v[18:19], v[34:35]
	v_pk_add_f32 v[4:5], v[18:19], v[34:35] neg_lo:[0,1] neg_hi:[0,1]
	v_pk_add_f32 v[6:7], v[26:27], v[42:43]
	v_pk_add_f32 v[8:9], v[26:27], v[42:43] neg_lo:[0,1] neg_hi:[0,1]
	v_pk_add_f32 v[18:19], v[2:3], v[6:7]
	v_pk_add_f32 v[6:7], v[2:3], v[6:7] neg_lo:[0,1] neg_hi:[0,1]
	v_pk_add_f32 v[2:3], v[4:5], v[8:9] op_sel:[0,1] op_sel_hi:[1,0] neg_hi:[0,1]
	v_pk_add_f32 v[16:17], v[4:5], v[8:9] op_sel:[0,1] op_sel_hi:[1,0] neg_lo:[0,1]
	v_pk_add_f32 v[4:5], v[20:21], v[36:37]
	v_pk_add_f32 v[8:9], v[20:21], v[36:37] neg_lo:[0,1] neg_hi:[0,1]
	v_pk_add_f32 v[14:15], v[28:29], v[44:45]
	v_pk_add_f32 v[20:21], v[28:29], v[44:45] neg_lo:[0,1] neg_hi:[0,1]
	v_pk_add_f32 v[26:27], v[4:5], v[14:15]
	v_pk_add_f32 v[28:29], v[4:5], v[14:15] neg_lo:[0,1] neg_hi:[0,1]
	v_pk_add_f32 v[14:15], v[8:9], v[20:21] op_sel:[0,1] op_sel_hi:[1,0] neg_hi:[0,1]
	v_pk_add_f32 v[20:21], v[8:9], v[20:21] op_sel:[0,1] op_sel_hi:[1,0] neg_lo:[0,1]
	v_pk_add_f32 v[4:5], v[22:23], v[38:39]
	v_pk_add_f32 v[8:9], v[22:23], v[38:39] neg_lo:[0,1] neg_hi:[0,1]
	v_pk_add_f32 v[22:23], v[30:31], v[46:47]
	v_pk_add_f32 v[30:31], v[30:31], v[46:47] neg_lo:[0,1] neg_hi:[0,1]
	v_pk_add_f32 v[34:35], v[4:5], v[22:23]
	v_pk_add_f32 v[22:23], v[4:5], v[22:23] neg_lo:[0,1] neg_hi:[0,1]
	v_pk_add_f32 v[36:37], v[8:9], v[30:31] op_sel:[0,1] op_sel_hi:[1,0] neg_hi:[0,1]
	v_pk_add_f32 v[30:31], v[8:9], v[30:31] op_sel:[0,1] op_sel_hi:[1,0] neg_lo:[0,1]
	v_pk_mul_f32 v[4:5], v[2:3], s[20:21] op_sel:[0,0] op_sel_hi:[0,1]
	s_waitcnt lgkmcnt(0)
	v_pk_fma_f32 v[38:39], v[2:3], s[20:21], v[4:5] op_sel:[1,1,0] op_sel_hi:[1,0,1] neg_lo:[0,1,0]
	v_pk_mul_f32 v[2:3], v[14:15], s[26:27] op_sel:[0,0] op_sel_hi:[0,1]
	s_barrier
	v_pk_fma_f32 v[42:43], v[14:15], s[26:27], v[2:3] op_sel:[1,1,0] op_sel_hi:[1,0,1] neg_lo:[0,1,0]
	v_pk_mul_f32 v[14:15], v[36:37], s[36:37] op_sel:[0,0] op_sel_hi:[0,1]
	v_pk_fma_f32 v[36:37], v[36:37], s[36:37], v[14:15] op_sel:[1,1,0] op_sel_hi:[1,0,1] neg_lo:[0,1,0]
	v_pk_mul_f32 v[14:15], v[6:7], s[26:27] op_sel:[0,0] op_sel_hi:[0,1]
	s_lshl_b32 s12, s9, 13
	v_pk_fma_f32 v[44:45], v[6:7], s[26:27], v[14:15] op_sel:[1,1,0] op_sel_hi:[1,0,1] neg_lo:[0,1,0]
	v_pk_mul_f32 v[6:7], v[28:29], s[40:41] op_sel:[0,0] op_sel_hi:[0,1]
	s_xor_b64 s[50:51], s[48:49], -1
	v_pk_fma_f32 v[28:29], v[28:29], s[40:41], v[6:7] op_sel:[1,1,0] op_sel_hi:[1,0,1] neg_lo:[0,1,0]
	v_pk_mul_f32 v[46:47], v[22:23], s[44:45] op_sel:[0,0] op_sel_hi:[0,1]
	s_mov_b32 s9, 1
	v_pk_fma_f32 v[22:23], v[22:23], s[44:45], v[46:47] op_sel:[1,1,0] op_sel_hi:[1,0,1] neg_lo:[0,1,0]
	v_pk_mul_f32 v[46:47], v[16:17], s[36:37] op_sel:[0,0] op_sel_hi:[0,1]
	s_mov_b64 s[48:49], 0
	v_pk_fma_f32 v[46:47], v[16:17], s[36:37], v[46:47] op_sel:[1,1,0] op_sel_hi:[1,0,1] neg_lo:[0,1,0]
	v_pk_mul_f32 v[16:17], v[20:21], s[44:45] op_sel:[0,0] op_sel_hi:[0,1]
	v_pk_fma_f32 v[20:21], v[20:21], s[44:45], v[16:17] op_sel:[1,1,0] op_sel_hi:[1,0,1] neg_lo:[0,1,0]
	v_pk_mul_f32 v[50:51], v[30:31], s[46:47] op_sel:[0,0] op_sel_hi:[0,1]
	v_pk_fma_f32 v[30:31], v[30:31], s[46:47], v[50:51] op_sel:[1,1,0] op_sel_hi:[1,0,1] neg_lo:[0,1,0]
	v_pk_add_f32 v[50:51], v[24:25], v[26:27]
	v_pk_add_f32 v[24:25], v[24:25], v[26:27] neg_lo:[0,1] neg_hi:[0,1]
	v_pk_add_f32 v[26:27], v[18:19], v[34:35]
	v_pk_add_f32 v[18:19], v[18:19], v[34:35] neg_lo:[0,1] neg_hi:[0,1]
	v_pk_add_f32 v[34:35], v[50:51], v[26:27]
	v_pk_add_f32 v[26:27], v[50:51], v[26:27] neg_lo:[0,1] neg_hi:[0,1]
	v_pk_add_f32 v[50:51], v[24:25], v[18:19] op_sel:[0,1] op_sel_hi:[1,0] neg_hi:[0,1]
	v_pk_add_f32 v[18:19], v[24:25], v[18:19] op_sel:[0,1] op_sel_hi:[1,0] neg_lo:[0,1]
	v_pk_add_f32 v[24:25], v[40:41], v[42:43]
	v_pk_add_f32 v[40:41], v[40:41], v[42:43] neg_lo:[0,1] neg_hi:[0,1]
	v_pk_add_f32 v[42:43], v[38:39], v[36:37]
	v_pk_add_f32 v[36:37], v[38:39], v[36:37] neg_lo:[0,1] neg_hi:[0,1]
	v_pk_add_f32 v[38:39], v[24:25], v[42:43]
	v_pk_add_f32 v[24:25], v[24:25], v[42:43] neg_lo:[0,1] neg_hi:[0,1]
	v_pk_add_f32 v[42:43], v[40:41], v[36:37] op_sel:[0,1] op_sel_hi:[1,0] neg_hi:[0,1]
	v_pk_add_f32 v[36:37], v[40:41], v[36:37] op_sel:[0,1] op_sel_hi:[1,0] neg_lo:[0,1]
	v_pk_add_f32 v[40:41], v[32:33], v[28:29]
	v_pk_add_f32 v[28:29], v[32:33], v[28:29] neg_lo:[0,1] neg_hi:[0,1]
	v_pk_add_f32 v[32:33], v[44:45], v[22:23]
	v_pk_add_f32 v[22:23], v[44:45], v[22:23] neg_lo:[0,1] neg_hi:[0,1]
	v_pk_add_f32 v[44:45], v[40:41], v[32:33]
	v_pk_add_f32 v[32:33], v[40:41], v[32:33] neg_lo:[0,1] neg_hi:[0,1]
	v_pk_add_f32 v[40:41], v[28:29], v[22:23] op_sel:[0,1] op_sel_hi:[1,0] neg_hi:[0,1]
	v_pk_add_f32 v[22:23], v[28:29], v[22:23] op_sel:[0,1] op_sel_hi:[1,0] neg_lo:[0,1]
	v_pk_add_f32 v[28:29], v[48:49], v[20:21]
	v_pk_add_f32 v[20:21], v[48:49], v[20:21] neg_lo:[0,1] neg_hi:[0,1]
	v_pk_add_f32 v[48:49], v[46:47], v[30:31]
	v_pk_add_f32 v[30:31], v[46:47], v[30:31] neg_lo:[0,1] neg_hi:[0,1]
	v_pk_add_f32 v[46:47], v[28:29], v[48:49]
	v_pk_add_f32 v[28:29], v[28:29], v[48:49] neg_lo:[0,1] neg_hi:[0,1]
	v_pk_add_f32 v[48:49], v[20:21], v[30:31] op_sel:[0,1] op_sel_hi:[1,0] neg_hi:[0,1]
	v_pk_add_f32 v[20:21], v[20:21], v[30:31] op_sel:[0,1] op_sel_hi:[1,0] neg_lo:[0,1]
	v_mov_b32_e32 v30, v53
	v_mov_b32_e32 v31, v62
	ds_write_b64 v59, v[34:35]
	v_pk_mul_f32 v[34:35], v[38:39], v[30:31] op_sel:[0,0] op_sel_hi:[0,1]
	v_pk_fma_f32 v[34:35], v[38:39], v[30:31], v[34:35] op_sel:[1,1,0] op_sel_hi:[1,0,1] neg_lo:[0,1,0]
	ds_write_b64 v59, v[34:35] offset:2176
	v_pk_mul_f32 v[34:35], v[30:31], v[30:31] op_sel:[0,0] op_sel_hi:[0,1]
	v_pk_fma_f32 v[34:35], v[30:31], v[30:31], v[34:35] op_sel:[1,1,0] op_sel_hi:[1,0,1] neg_lo:[0,1,0]
	v_pk_mul_f32 v[38:39], v[44:45], v[34:35] op_sel:[0,0] op_sel_hi:[0,1]
	v_pk_fma_f32 v[38:39], v[44:45], v[34:35], v[38:39] op_sel:[1,1,0] op_sel_hi:[1,0,1] neg_lo:[0,1,0]
	ds_write_b64 v59, v[38:39] offset:4352
	v_pk_mul_f32 v[38:39], v[34:35], v[30:31] op_sel:[0,0] op_sel_hi:[0,1]
	v_pk_fma_f32 v[34:35], v[34:35], v[30:31], v[38:39] op_sel:[1,1,0] op_sel_hi:[1,0,1] neg_lo:[0,1,0]
	v_pk_mul_f32 v[38:39], v[46:47], v[34:35] op_sel:[0,0] op_sel_hi:[0,1]
	v_pk_fma_f32 v[38:39], v[46:47], v[34:35], v[38:39] op_sel:[1,1,0] op_sel_hi:[1,0,1] neg_lo:[0,1,0]
	ds_write_b64 v59, v[38:39] offset:6528
	v_pk_mul_f32 v[38:39], v[34:35], v[30:31] op_sel:[0,0] op_sel_hi:[0,1]
	v_pk_fma_f32 v[34:35], v[34:35], v[30:31], v[38:39] op_sel:[1,1,0] op_sel_hi:[1,0,1] neg_lo:[0,1,0]
	v_pk_mul_f32 v[38:39], v[50:51], v[34:35] op_sel:[0,0] op_sel_hi:[0,1]
	v_pk_fma_f32 v[38:39], v[50:51], v[34:35], v[38:39] op_sel:[1,1,0] op_sel_hi:[1,0,1] neg_lo:[0,1,0]
	ds_write_b64 v59, v[38:39] offset:8704
	v_pk_mul_f32 v[38:39], v[34:35], v[30:31] op_sel:[0,0] op_sel_hi:[0,1]
	v_pk_fma_f32 v[34:35], v[34:35], v[30:31], v[38:39] op_sel:[1,1,0] op_sel_hi:[1,0,1] neg_lo:[0,1,0]
	v_pk_mul_f32 v[38:39], v[42:43], v[34:35] op_sel:[0,0] op_sel_hi:[0,1]
	v_pk_fma_f32 v[38:39], v[42:43], v[34:35], v[38:39] op_sel:[1,1,0] op_sel_hi:[1,0,1] neg_lo:[0,1,0]
	ds_write_b64 v59, v[38:39] offset:10880
	v_pk_mul_f32 v[38:39], v[34:35], v[30:31] op_sel:[0,0] op_sel_hi:[0,1]
	v_pk_fma_f32 v[34:35], v[34:35], v[30:31], v[38:39] op_sel:[1,1,0] op_sel_hi:[1,0,1] neg_lo:[0,1,0]
	v_pk_mul_f32 v[38:39], v[40:41], v[34:35] op_sel:[0,0] op_sel_hi:[0,1]
	v_pk_fma_f32 v[38:39], v[40:41], v[34:35], v[38:39] op_sel:[1,1,0] op_sel_hi:[1,0,1] neg_lo:[0,1,0]
	ds_write_b64 v59, v[38:39] offset:13056
	v_pk_mul_f32 v[38:39], v[34:35], v[30:31] op_sel:[0,0] op_sel_hi:[0,1]
	v_pk_fma_f32 v[34:35], v[34:35], v[30:31], v[38:39] op_sel:[1,1,0] op_sel_hi:[1,0,1] neg_lo:[0,1,0]
	v_pk_mul_f32 v[38:39], v[48:49], v[34:35] op_sel:[0,0] op_sel_hi:[0,1]
	v_pk_fma_f32 v[38:39], v[48:49], v[34:35], v[38:39] op_sel:[1,1,0] op_sel_hi:[1,0,1] neg_lo:[0,1,0]
	ds_write_b64 v59, v[38:39] offset:15232
	v_pk_mul_f32 v[38:39], v[34:35], v[30:31] op_sel:[0,0] op_sel_hi:[0,1]
	v_pk_fma_f32 v[34:35], v[34:35], v[30:31], v[38:39] op_sel:[1,1,0] op_sel_hi:[1,0,1] neg_lo:[0,1,0]
	v_pk_mul_f32 v[38:39], v[26:27], v[34:35] op_sel:[0,0] op_sel_hi:[0,1]
	v_pk_fma_f32 v[26:27], v[26:27], v[34:35], v[38:39] op_sel:[1,1,0] op_sel_hi:[1,0,1] neg_lo:[0,1,0]
	ds_write_b64 v59, v[26:27] offset:17408
	v_pk_mul_f32 v[26:27], v[34:35], v[30:31] op_sel:[0,0] op_sel_hi:[0,1]
	v_pk_fma_f32 v[26:27], v[34:35], v[30:31], v[26:27] op_sel:[1,1,0] op_sel_hi:[1,0,1] neg_lo:[0,1,0]
	v_pk_mul_f32 v[34:35], v[24:25], v[26:27] op_sel:[0,0] op_sel_hi:[0,1]
	v_pk_fma_f32 v[24:25], v[24:25], v[26:27], v[34:35] op_sel:[1,1,0] op_sel_hi:[1,0,1] neg_lo:[0,1,0]
	ds_write_b64 v59, v[24:25] offset:19584
	v_pk_mul_f32 v[24:25], v[26:27], v[30:31] op_sel:[0,0] op_sel_hi:[0,1]
	v_pk_fma_f32 v[24:25], v[26:27], v[30:31], v[24:25] op_sel:[1,1,0] op_sel_hi:[1,0,1] neg_lo:[0,1,0]
	v_pk_mul_f32 v[26:27], v[32:33], v[24:25] op_sel:[0,0] op_sel_hi:[0,1]
	v_pk_fma_f32 v[26:27], v[32:33], v[24:25], v[26:27] op_sel:[1,1,0] op_sel_hi:[1,0,1] neg_lo:[0,1,0]
	ds_write_b64 v59, v[26:27] offset:21760
	v_pk_mul_f32 v[26:27], v[24:25], v[30:31] op_sel:[0,0] op_sel_hi:[0,1]
	v_pk_fma_f32 v[24:25], v[24:25], v[30:31], v[26:27] op_sel:[1,1,0] op_sel_hi:[1,0,1] neg_lo:[0,1,0]
	v_pk_mul_f32 v[26:27], v[28:29], v[24:25] op_sel:[0,0] op_sel_hi:[0,1]
	v_pk_fma_f32 v[26:27], v[28:29], v[24:25], v[26:27] op_sel:[1,1,0] op_sel_hi:[1,0,1] neg_lo:[0,1,0]
	ds_write_b64 v59, v[26:27] offset:23936
	v_pk_mul_f32 v[26:27], v[24:25], v[30:31] op_sel:[0,0] op_sel_hi:[0,1]
	v_pk_fma_f32 v[24:25], v[24:25], v[30:31], v[26:27] op_sel:[1,1,0] op_sel_hi:[1,0,1] neg_lo:[0,1,0]
	v_pk_mul_f32 v[26:27], v[18:19], v[24:25] op_sel:[0,0] op_sel_hi:[0,1]
	v_pk_fma_f32 v[18:19], v[18:19], v[24:25], v[26:27] op_sel:[1,1,0] op_sel_hi:[1,0,1] neg_lo:[0,1,0]
	ds_write_b64 v59, v[18:19] offset:26112
	v_pk_mul_f32 v[18:19], v[24:25], v[30:31] op_sel:[0,0] op_sel_hi:[0,1]
	v_pk_fma_f32 v[18:19], v[24:25], v[30:31], v[18:19] op_sel:[1,1,0] op_sel_hi:[1,0,1] neg_lo:[0,1,0]
	v_pk_mul_f32 v[24:25], v[36:37], v[18:19] op_sel:[0,0] op_sel_hi:[0,1]
	v_pk_fma_f32 v[24:25], v[36:37], v[18:19], v[24:25] op_sel:[1,1,0] op_sel_hi:[1,0,1] neg_lo:[0,1,0]
	ds_write_b64 v59, v[24:25] offset:28288
	v_pk_mul_f32 v[24:25], v[18:19], v[30:31] op_sel:[0,0] op_sel_hi:[0,1]
	v_pk_fma_f32 v[18:19], v[18:19], v[30:31], v[24:25] op_sel:[1,1,0] op_sel_hi:[1,0,1] neg_lo:[0,1,0]
	v_pk_mul_f32 v[24:25], v[22:23], v[18:19] op_sel:[0,0] op_sel_hi:[0,1]
	v_pk_fma_f32 v[22:23], v[22:23], v[18:19], v[24:25] op_sel:[1,1,0] op_sel_hi:[1,0,1] neg_lo:[0,1,0]
	ds_write_b64 v59, v[22:23] offset:30464
	v_pk_mul_f32 v[22:23], v[18:19], v[30:31] op_sel:[0,0] op_sel_hi:[0,1]
	v_pk_fma_f32 v[18:19], v[18:19], v[30:31], v[22:23] op_sel:[1,1,0] op_sel_hi:[1,0,1] neg_lo:[0,1,0]
	v_pk_mul_f32 v[22:23], v[20:21], v[18:19] op_sel:[0,0] op_sel_hi:[0,1]
	v_pk_fma_f32 v[18:19], v[20:21], v[18:19], v[22:23] op_sel:[1,1,0] op_sel_hi:[1,0,1] neg_lo:[0,1,0]
	ds_write_b64 v59, v[18:19] offset:32640
	s_waitcnt lgkmcnt(0)
	s_barrier
	ds_read2_b64 v[18:21], v60 offset1:17
	ds_read2_b64 v[22:25], v60 offset0:34 offset1:51
	ds_read2_b64 v[26:29], v60 offset0:68 offset1:85
	ds_read2_b64 v[30:33], v60 offset0:136 offset1:153
	ds_read2_b64 v[34:37], v60 offset0:102 offset1:119
	ds_read2_b64 v[38:41], v60 offset0:204 offset1:221
	ds_read2_b64 v[42:45], v60 offset0:170 offset1:187
	ds_read2_b64 v[46:49], v60 offset0:238 offset1:255
	s_waitcnt lgkmcnt(4)
	v_pk_add_f32 v[50:51], v[18:19], v[30:31]
	v_pk_add_f32 v[18:19], v[18:19], v[30:31] neg_lo:[0,1] neg_hi:[0,1]
	s_waitcnt lgkmcnt(2)
	v_pk_add_f32 v[30:31], v[26:27], v[38:39]
	v_pk_add_f32 v[26:27], v[26:27], v[38:39] neg_lo:[0,1] neg_hi:[0,1]
	v_pk_add_f32 v[38:39], v[50:51], v[30:31]
	v_pk_add_f32 v[30:31], v[50:51], v[30:31] neg_lo:[0,1] neg_hi:[0,1]
	v_pk_add_f32 v[50:51], v[18:19], v[26:27] op_sel:[0,1] op_sel_hi:[1,0] neg_hi:[0,1]
	v_pk_add_f32 v[18:19], v[18:19], v[26:27] op_sel:[0,1] op_sel_hi:[1,0] neg_lo:[0,1]
	v_pk_add_f32 v[26:27], v[20:21], v[32:33]
	v_pk_add_f32 v[20:21], v[20:21], v[32:33] neg_lo:[0,1] neg_hi:[0,1]
	v_pk_add_f32 v[32:33], v[28:29], v[40:41]
	v_pk_add_f32 v[28:29], v[28:29], v[40:41] neg_lo:[0,1] neg_hi:[0,1]
	v_pk_add_f32 v[40:41], v[26:27], v[32:33]
	v_pk_add_f32 v[26:27], v[26:27], v[32:33] neg_lo:[0,1] neg_hi:[0,1]
	v_pk_add_f32 v[32:33], v[20:21], v[28:29] op_sel:[0,1] op_sel_hi:[1,0] neg_hi:[0,1]
	v_pk_add_f32 v[20:21], v[20:21], v[28:29] op_sel:[0,1] op_sel_hi:[1,0] neg_lo:[0,1]
	s_waitcnt lgkmcnt(1)
	v_pk_add_f32 v[28:29], v[22:23], v[42:43]
	v_pk_add_f32 v[22:23], v[22:23], v[42:43] neg_lo:[0,1] neg_hi:[0,1]
	s_waitcnt lgkmcnt(0)
	v_pk_add_f32 v[42:43], v[34:35], v[46:47]
	v_pk_add_f32 v[34:35], v[34:35], v[46:47] neg_lo:[0,1] neg_hi:[0,1]
	v_pk_add_f32 v[46:47], v[28:29], v[42:43]
	v_pk_add_f32 v[28:29], v[28:29], v[42:43] neg_lo:[0,1] neg_hi:[0,1]
	v_pk_add_f32 v[42:43], v[22:23], v[34:35] op_sel:[0,1] op_sel_hi:[1,0] neg_hi:[0,1]
	v_pk_add_f32 v[22:23], v[22:23], v[34:35] op_sel:[0,1] op_sel_hi:[1,0] neg_lo:[0,1]
	v_pk_add_f32 v[34:35], v[24:25], v[44:45]
	v_pk_add_f32 v[24:25], v[24:25], v[44:45] neg_lo:[0,1] neg_hi:[0,1]
	v_pk_add_f32 v[44:45], v[36:37], v[48:49]
	v_pk_add_f32 v[36:37], v[36:37], v[48:49] neg_lo:[0,1] neg_hi:[0,1]
	v_pk_add_f32 v[48:49], v[34:35], v[44:45]
	v_pk_add_f32 v[34:35], v[34:35], v[44:45] neg_lo:[0,1] neg_hi:[0,1]
	v_pk_add_f32 v[44:45], v[24:25], v[36:37] op_sel:[0,1] op_sel_hi:[1,0] neg_hi:[0,1]
	v_pk_add_f32 v[24:25], v[24:25], v[36:37] op_sel:[0,1] op_sel_hi:[1,0] neg_lo:[0,1]
	v_pk_mul_f32 v[36:37], v[32:33], s[20:21] op_sel:[0,0] op_sel_hi:[0,1]
	v_pk_fma_f32 v[32:33], v[32:33], s[20:21], v[36:37] op_sel:[1,1,0] op_sel_hi:[1,0,1] neg_lo:[0,1,0]
	v_pk_mul_f32 v[36:37], v[42:43], s[26:27] op_sel:[0,0] op_sel_hi:[0,1]
	v_pk_fma_f32 v[36:37], v[42:43], s[26:27], v[36:37] op_sel:[1,1,0] op_sel_hi:[1,0,1] neg_lo:[0,1,0]
	v_pk_mul_f32 v[42:43], v[44:45], s[36:37] op_sel:[0,0] op_sel_hi:[0,1]
	v_pk_fma_f32 v[42:43], v[44:45], s[36:37], v[42:43] op_sel:[1,1,0] op_sel_hi:[1,0,1] neg_lo:[0,1,0]
	v_pk_mul_f32 v[44:45], v[26:27], s[26:27] op_sel:[0,0] op_sel_hi:[0,1]
	v_pk_fma_f32 v[26:27], v[26:27], s[26:27], v[44:45] op_sel:[1,1,0] op_sel_hi:[1,0,1] neg_lo:[0,1,0]
	v_pk_mul_f32 v[44:45], v[28:29], s[40:41] op_sel:[0,0] op_sel_hi:[0,1]
	v_pk_fma_f32 v[28:29], v[28:29], s[40:41], v[44:45] op_sel:[1,1,0] op_sel_hi:[1,0,1] neg_lo:[0,1,0]
	v_pk_mul_f32 v[44:45], v[34:35], s[44:45] op_sel:[0,0] op_sel_hi:[0,1]
	v_pk_fma_f32 v[34:35], v[34:35], s[44:45], v[44:45] op_sel:[1,1,0] op_sel_hi:[1,0,1] neg_lo:[0,1,0]
	v_pk_mul_f32 v[44:45], v[20:21], s[36:37] op_sel:[0,0] op_sel_hi:[0,1]
	v_pk_fma_f32 v[20:21], v[20:21], s[36:37], v[44:45] op_sel:[1,1,0] op_sel_hi:[1,0,1] neg_lo:[0,1,0]
	v_pk_mul_f32 v[44:45], v[22:23], s[44:45] op_sel:[0,0] op_sel_hi:[0,1]
	v_pk_fma_f32 v[22:23], v[22:23], s[44:45], v[44:45] op_sel:[1,1,0] op_sel_hi:[1,0,1] neg_lo:[0,1,0]
	v_pk_mul_f32 v[44:45], v[24:25], s[46:47] op_sel:[0,0] op_sel_hi:[0,1]
	v_pk_fma_f32 v[24:25], v[24:25], s[46:47], v[44:45] op_sel:[1,1,0] op_sel_hi:[1,0,1] neg_lo:[0,1,0]
	v_pk_add_f32 v[44:45], v[38:39], v[46:47]
	v_pk_add_f32 v[38:39], v[38:39], v[46:47] neg_lo:[0,1] neg_hi:[0,1]
	v_pk_add_f32 v[46:47], v[40:41], v[48:49]
	v_pk_add_f32 v[40:41], v[40:41], v[48:49] neg_lo:[0,1] neg_hi:[0,1]
	v_pk_add_f32 v[48:49], v[44:45], v[46:47]
	v_pk_add_f32 v[44:45], v[44:45], v[46:47] neg_lo:[0,1] neg_hi:[0,1]
	v_pk_add_f32 v[46:47], v[38:39], v[40:41] op_sel:[0,1] op_sel_hi:[1,0] neg_hi:[0,1]
	v_pk_add_f32 v[38:39], v[38:39], v[40:41] op_sel:[0,1] op_sel_hi:[1,0] neg_lo:[0,1]
	v_pk_add_f32 v[40:41], v[50:51], v[36:37]
	v_pk_add_f32 v[36:37], v[50:51], v[36:37] neg_lo:[0,1] neg_hi:[0,1]
	v_pk_add_f32 v[50:51], v[32:33], v[42:43]
	v_pk_add_f32 v[32:33], v[32:33], v[42:43] neg_lo:[0,1] neg_hi:[0,1]
	v_pk_add_f32 v[42:43], v[40:41], v[50:51]
	v_pk_add_f32 v[40:41], v[40:41], v[50:51] neg_lo:[0,1] neg_hi:[0,1]
	v_pk_add_f32 v[50:51], v[36:37], v[32:33] op_sel:[0,1] op_sel_hi:[1,0] neg_hi:[0,1]
	v_pk_add_f32 v[32:33], v[36:37], v[32:33] op_sel:[0,1] op_sel_hi:[1,0] neg_lo:[0,1]
	v_pk_add_f32 v[36:37], v[30:31], v[28:29]
	v_pk_add_f32 v[28:29], v[30:31], v[28:29] neg_lo:[0,1] neg_hi:[0,1]
	v_pk_add_f32 v[30:31], v[26:27], v[34:35]
	v_pk_add_f32 v[26:27], v[26:27], v[34:35] neg_lo:[0,1] neg_hi:[0,1]
	v_pk_add_f32 v[34:35], v[36:37], v[30:31]
	v_pk_add_f32 v[30:31], v[36:37], v[30:31] neg_lo:[0,1] neg_hi:[0,1]
	v_pk_add_f32 v[36:37], v[28:29], v[26:27] op_sel:[0,1] op_sel_hi:[1,0] neg_hi:[0,1]
	v_pk_add_f32 v[26:27], v[28:29], v[26:27] op_sel:[0,1] op_sel_hi:[1,0] neg_lo:[0,1]
	v_pk_add_f32 v[28:29], v[18:19], v[22:23]
	v_pk_add_f32 v[18:19], v[18:19], v[22:23] neg_lo:[0,1] neg_hi:[0,1]
	v_pk_add_f32 v[22:23], v[20:21], v[24:25]
	v_pk_add_f32 v[20:21], v[20:21], v[24:25] neg_lo:[0,1] neg_hi:[0,1]
	v_pk_add_f32 v[24:25], v[28:29], v[22:23]
	v_pk_add_f32 v[22:23], v[28:29], v[22:23] neg_lo:[0,1] neg_hi:[0,1]
	v_pk_add_f32 v[28:29], v[18:19], v[20:21] op_sel:[0,1] op_sel_hi:[1,0] neg_hi:[0,1]
	v_pk_add_f32 v[18:19], v[18:19], v[20:21] op_sel:[0,1] op_sel_hi:[1,0] neg_lo:[0,1]
	v_mov_b32_e32 v21, v63
	v_mov_b32_e32 v20, v54
	s_nop 0
	v_pk_mul_f32 v[66:67], v[42:43], v[20:21] op_sel:[0,0] op_sel_hi:[0,1]
	v_pk_fma_f32 v[42:43], v[42:43], v[20:21], v[66:67] op_sel:[1,1,0] op_sel_hi:[1,0,1] neg_lo:[0,1,0]
	ds_write2_b64 v60, v[48:49], v[42:43] offset1:17
	v_pk_mul_f32 v[42:43], v[20:21], v[20:21] op_sel:[0,0] op_sel_hi:[0,1]
	v_pk_fma_f32 v[42:43], v[20:21], v[20:21], v[42:43] op_sel:[1,1,0] op_sel_hi:[1,0,1] neg_lo:[0,1,0]
	v_pk_mul_f32 v[48:49], v[34:35], v[42:43] op_sel:[0,0] op_sel_hi:[0,1]
	v_pk_fma_f32 v[34:35], v[34:35], v[42:43], v[48:49] op_sel:[1,1,0] op_sel_hi:[1,0,1] neg_lo:[0,1,0]
	v_pk_mul_f32 v[48:49], v[42:43], v[20:21] op_sel:[0,0] op_sel_hi:[0,1]
	v_pk_fma_f32 v[42:43], v[42:43], v[20:21], v[48:49] op_sel:[1,1,0] op_sel_hi:[1,0,1] neg_lo:[0,1,0]
	v_pk_mul_f32 v[48:49], v[24:25], v[42:43] op_sel:[0,0] op_sel_hi:[0,1]
	v_pk_fma_f32 v[24:25], v[24:25], v[42:43], v[48:49] op_sel:[1,1,0] op_sel_hi:[1,0,1] neg_lo:[0,1,0]
	ds_write2_b64 v60, v[34:35], v[24:25] offset0:34 offset1:51
	v_pk_mul_f32 v[24:25], v[42:43], v[20:21] op_sel:[0,0] op_sel_hi:[0,1]
	v_pk_fma_f32 v[24:25], v[42:43], v[20:21], v[24:25] op_sel:[1,1,0] op_sel_hi:[1,0,1] neg_lo:[0,1,0]
	v_pk_mul_f32 v[34:35], v[46:47], v[24:25] op_sel:[0,0] op_sel_hi:[0,1]
	v_pk_mul_f32 v[42:43], v[24:25], v[20:21] op_sel:[0,0] op_sel_hi:[0,1]
	v_pk_fma_f32 v[34:35], v[46:47], v[24:25], v[34:35] op_sel:[1,1,0] op_sel_hi:[1,0,1] neg_lo:[0,1,0]
	v_pk_fma_f32 v[24:25], v[24:25], v[20:21], v[42:43] op_sel:[1,1,0] op_sel_hi:[1,0,1] neg_lo:[0,1,0]
	v_pk_mul_f32 v[42:43], v[50:51], v[24:25] op_sel:[0,0] op_sel_hi:[0,1]
	v_pk_fma_f32 v[42:43], v[50:51], v[24:25], v[42:43] op_sel:[1,1,0] op_sel_hi:[1,0,1] neg_lo:[0,1,0]
	ds_write2_b64 v60, v[34:35], v[42:43] offset0:68 offset1:85
	v_pk_mul_f32 v[34:35], v[24:25], v[20:21] op_sel:[0,0] op_sel_hi:[0,1]
	v_pk_fma_f32 v[24:25], v[24:25], v[20:21], v[34:35] op_sel:[1,1,0] op_sel_hi:[1,0,1] neg_lo:[0,1,0]
	v_pk_mul_f32 v[34:35], v[36:37], v[24:25] op_sel:[0,0] op_sel_hi:[0,1]
	v_pk_fma_f32 v[34:35], v[36:37], v[24:25], v[34:35] op_sel:[1,1,0] op_sel_hi:[1,0,1] neg_lo:[0,1,0]
	v_pk_mul_f32 v[36:37], v[24:25], v[20:21] op_sel:[0,0] op_sel_hi:[0,1]
	v_pk_fma_f32 v[24:25], v[24:25], v[20:21], v[36:37] op_sel:[1,1,0] op_sel_hi:[1,0,1] neg_lo:[0,1,0]
	v_pk_mul_f32 v[36:37], v[28:29], v[24:25] op_sel:[0,0] op_sel_hi:[0,1]
	v_pk_fma_f32 v[28:29], v[28:29], v[24:25], v[36:37] op_sel:[1,1,0] op_sel_hi:[1,0,1] neg_lo:[0,1,0]
	ds_write2_b64 v60, v[34:35], v[28:29] offset0:102 offset1:119
	v_pk_mul_f32 v[28:29], v[24:25], v[20:21] op_sel:[0,0] op_sel_hi:[0,1]
	v_pk_fma_f32 v[24:25], v[24:25], v[20:21], v[28:29] op_sel:[1,1,0] op_sel_hi:[1,0,1] neg_lo:[0,1,0]
	v_pk_mul_f32 v[28:29], v[44:45], v[24:25] op_sel:[0,0] op_sel_hi:[0,1]
	v_pk_mul_f32 v[34:35], v[24:25], v[20:21] op_sel:[0,0] op_sel_hi:[0,1]
	v_pk_fma_f32 v[28:29], v[44:45], v[24:25], v[28:29] op_sel:[1,1,0] op_sel_hi:[1,0,1] neg_lo:[0,1,0]
	v_pk_fma_f32 v[24:25], v[24:25], v[20:21], v[34:35] op_sel:[1,1,0] op_sel_hi:[1,0,1] neg_lo:[0,1,0]
	v_pk_mul_f32 v[34:35], v[40:41], v[24:25] op_sel:[0,0] op_sel_hi:[0,1]
	v_pk_fma_f32 v[34:35], v[40:41], v[24:25], v[34:35] op_sel:[1,1,0] op_sel_hi:[1,0,1] neg_lo:[0,1,0]
	ds_write2_b64 v60, v[28:29], v[34:35] offset0:136 offset1:153
	v_pk_mul_f32 v[28:29], v[24:25], v[20:21] op_sel:[0,0] op_sel_hi:[0,1]
	v_pk_fma_f32 v[24:25], v[24:25], v[20:21], v[28:29] op_sel:[1,1,0] op_sel_hi:[1,0,1] neg_lo:[0,1,0]
	v_pk_mul_f32 v[28:29], v[30:31], v[24:25] op_sel:[0,0] op_sel_hi:[0,1]
	v_pk_fma_f32 v[28:29], v[30:31], v[24:25], v[28:29] op_sel:[1,1,0] op_sel_hi:[1,0,1] neg_lo:[0,1,0]
	v_pk_mul_f32 v[30:31], v[24:25], v[20:21] op_sel:[0,0] op_sel_hi:[0,1]
	v_pk_fma_f32 v[24:25], v[24:25], v[20:21], v[30:31] op_sel:[1,1,0] op_sel_hi:[1,0,1] neg_lo:[0,1,0]
	v_pk_mul_f32 v[30:31], v[22:23], v[24:25] op_sel:[0,0] op_sel_hi:[0,1]
	v_pk_fma_f32 v[22:23], v[22:23], v[24:25], v[30:31] op_sel:[1,1,0] op_sel_hi:[1,0,1] neg_lo:[0,1,0]
	ds_write2_b64 v60, v[28:29], v[22:23] offset0:170 offset1:187
	v_pk_mul_f32 v[22:23], v[24:25], v[20:21] op_sel:[0,0] op_sel_hi:[0,1]
	v_pk_fma_f32 v[22:23], v[24:25], v[20:21], v[22:23] op_sel:[1,1,0] op_sel_hi:[1,0,1] neg_lo:[0,1,0]
	v_pk_mul_f32 v[24:25], v[38:39], v[22:23] op_sel:[0,0] op_sel_hi:[0,1]
	v_pk_mul_f32 v[28:29], v[22:23], v[20:21] op_sel:[0,0] op_sel_hi:[0,1]
	v_pk_fma_f32 v[24:25], v[38:39], v[22:23], v[24:25] op_sel:[1,1,0] op_sel_hi:[1,0,1] neg_lo:[0,1,0]
	v_pk_fma_f32 v[22:23], v[22:23], v[20:21], v[28:29] op_sel:[1,1,0] op_sel_hi:[1,0,1] neg_lo:[0,1,0]
	v_pk_mul_f32 v[28:29], v[32:33], v[22:23] op_sel:[0,0] op_sel_hi:[0,1]
	v_pk_fma_f32 v[28:29], v[32:33], v[22:23], v[28:29] op_sel:[1,1,0] op_sel_hi:[1,0,1] neg_lo:[0,1,0]
	ds_write2_b64 v60, v[24:25], v[28:29] offset0:204 offset1:221
	v_pk_mul_f32 v[24:25], v[22:23], v[20:21] op_sel:[0,0] op_sel_hi:[0,1]
	v_pk_fma_f32 v[22:23], v[22:23], v[20:21], v[24:25] op_sel:[1,1,0] op_sel_hi:[1,0,1] neg_lo:[0,1,0]
	v_pk_mul_f32 v[24:25], v[26:27], v[22:23] op_sel:[0,0] op_sel_hi:[0,1]
	v_pk_fma_f32 v[24:25], v[26:27], v[22:23], v[24:25] op_sel:[1,1,0] op_sel_hi:[1,0,1] neg_lo:[0,1,0]
	v_pk_mul_f32 v[26:27], v[22:23], v[20:21] op_sel:[0,0] op_sel_hi:[0,1]
	v_pk_fma_f32 v[20:21], v[22:23], v[20:21], v[26:27] op_sel:[1,1,0] op_sel_hi:[1,0,1] neg_lo:[0,1,0]
	v_pk_mul_f32 v[22:23], v[18:19], v[20:21] op_sel:[0,0] op_sel_hi:[0,1]
	v_pk_fma_f32 v[18:19], v[18:19], v[20:21], v[22:23] op_sel:[1,1,0] op_sel_hi:[1,0,1] neg_lo:[0,1,0]
	ds_write2_b64 v60, v[24:25], v[18:19] offset0:238 offset1:255
	s_waitcnt lgkmcnt(0)
	s_barrier
	ds_read2_b64 v[18:21], v64 offset1:1
	ds_read2_b64 v[22:25], v64 offset0:2 offset1:3
	ds_read2_b64 v[26:29], v64 offset0:8 offset1:9
	ds_read2_b64 v[30:33], v64 offset0:4 offset1:5
	ds_read2_b64 v[34:37], v64 offset0:6 offset1:7
	ds_read2_b64 v[38:41], v64 offset0:12 offset1:13
	ds_read2_b64 v[42:45], v64 offset0:10 offset1:11
	ds_read2_b64 v[46:49], v64 offset0:14 offset1:15
	s_waitcnt lgkmcnt(5)
	v_pk_add_f32 v[50:51], v[18:19], v[26:27]
	v_pk_add_f32 v[18:19], v[18:19], v[26:27] neg_lo:[0,1] neg_hi:[0,1]
	s_waitcnt lgkmcnt(2)
	v_pk_add_f32 v[26:27], v[30:31], v[38:39]
	v_pk_add_f32 v[30:31], v[30:31], v[38:39] neg_lo:[0,1] neg_hi:[0,1]
	v_pk_add_f32 v[38:39], v[50:51], v[26:27]
	v_pk_add_f32 v[26:27], v[50:51], v[26:27] neg_lo:[0,1] neg_hi:[0,1]
	v_pk_add_f32 v[50:51], v[18:19], v[30:31] op_sel:[0,1] op_sel_hi:[1,0] neg_hi:[0,1]
	v_pk_add_f32 v[18:19], v[18:19], v[30:31] op_sel:[0,1] op_sel_hi:[1,0] neg_lo:[0,1]
	v_pk_add_f32 v[30:31], v[20:21], v[28:29]
	v_pk_add_f32 v[20:21], v[20:21], v[28:29] neg_lo:[0,1] neg_hi:[0,1]
	v_pk_add_f32 v[28:29], v[32:33], v[40:41]
	v_pk_add_f32 v[32:33], v[32:33], v[40:41] neg_lo:[0,1] neg_hi:[0,1]
	v_pk_add_f32 v[40:41], v[30:31], v[28:29]
	v_pk_add_f32 v[28:29], v[30:31], v[28:29] neg_lo:[0,1] neg_hi:[0,1]
	v_pk_add_f32 v[30:31], v[20:21], v[32:33] op_sel:[0,1] op_sel_hi:[1,0] neg_hi:[0,1]
	v_pk_add_f32 v[20:21], v[20:21], v[32:33] op_sel:[0,1] op_sel_hi:[1,0] neg_lo:[0,1]
	s_waitcnt lgkmcnt(1)
	v_pk_add_f32 v[32:33], v[22:23], v[42:43]
	v_pk_add_f32 v[22:23], v[22:23], v[42:43] neg_lo:[0,1] neg_hi:[0,1]
	s_waitcnt lgkmcnt(0)
	v_pk_add_f32 v[42:43], v[34:35], v[46:47]
	v_pk_add_f32 v[34:35], v[34:35], v[46:47] neg_lo:[0,1] neg_hi:[0,1]
	v_pk_add_f32 v[46:47], v[32:33], v[42:43]
	v_pk_add_f32 v[32:33], v[32:33], v[42:43] neg_lo:[0,1] neg_hi:[0,1]
	v_pk_add_f32 v[42:43], v[22:23], v[34:35] op_sel:[0,1] op_sel_hi:[1,0] neg_hi:[0,1]
	v_pk_add_f32 v[22:23], v[22:23], v[34:35] op_sel:[0,1] op_sel_hi:[1,0] neg_lo:[0,1]
	v_pk_add_f32 v[34:35], v[24:25], v[44:45]
	v_pk_add_f32 v[24:25], v[24:25], v[44:45] neg_lo:[0,1] neg_hi:[0,1]
	v_pk_add_f32 v[44:45], v[36:37], v[48:49]
	v_pk_add_f32 v[36:37], v[36:37], v[48:49] neg_lo:[0,1] neg_hi:[0,1]
	v_pk_add_f32 v[48:49], v[34:35], v[44:45]
	v_pk_add_f32 v[34:35], v[34:35], v[44:45] neg_lo:[0,1] neg_hi:[0,1]
	v_pk_add_f32 v[44:45], v[24:25], v[36:37] op_sel:[0,1] op_sel_hi:[1,0] neg_hi:[0,1]
	v_pk_add_f32 v[24:25], v[24:25], v[36:37] op_sel:[0,1] op_sel_hi:[1,0] neg_lo:[0,1]
	v_pk_mul_f32 v[36:37], v[30:31], s[20:21] op_sel:[0,0] op_sel_hi:[0,1]
	v_pk_fma_f32 v[8:9], v[30:31], s[20:21], v[36:37] op_sel:[1,1,0] op_sel_hi:[1,0,1] neg_lo:[0,1,0]
	v_pk_mul_f32 v[30:31], v[42:43], s[26:27] op_sel:[0,0] op_sel_hi:[0,1]
	v_pk_mul_f32 v[36:37], v[44:45], s[36:37] op_sel:[0,0] op_sel_hi:[0,1]
	s_barrier
	v_pk_fma_f32 v[30:31], v[42:43], s[26:27], v[30:31] op_sel:[1,1,0] op_sel_hi:[1,0,1] neg_lo:[0,1,0]
	v_pk_mul_f32 v[42:43], v[28:29], s[26:27] op_sel:[0,0] op_sel_hi:[0,1]
	v_pk_fma_f32 v[36:37], v[44:45], s[36:37], v[36:37] op_sel:[1,1,0] op_sel_hi:[1,0,1] neg_lo:[0,1,0]
	v_pk_fma_f32 v[4:5], v[28:29], s[26:27], v[42:43] op_sel:[1,1,0] op_sel_hi:[1,0,1] neg_lo:[0,1,0]
	v_pk_mul_f32 v[28:29], v[32:33], s[40:41] op_sel:[0,0] op_sel_hi:[0,1]
	v_pk_fma_f32 v[14:15], v[32:33], s[40:41], v[28:29] op_sel:[1,1,0] op_sel_hi:[1,0,1] neg_lo:[0,1,0]
	v_pk_mul_f32 v[28:29], v[34:35], s[44:45] op_sel:[0,0] op_sel_hi:[0,1]
	v_pk_mul_f32 v[32:33], v[20:21], s[36:37] op_sel:[0,0] op_sel_hi:[0,1]
	v_pk_fma_f32 v[2:3], v[20:21], s[36:37], v[32:33] op_sel:[1,1,0] op_sel_hi:[1,0,1] neg_lo:[0,1,0]
	v_pk_mul_f32 v[20:21], v[22:23], s[44:45] op_sel:[0,0] op_sel_hi:[0,1]
	v_pk_fma_f32 v[28:29], v[34:35], s[44:45], v[28:29] op_sel:[1,1,0] op_sel_hi:[1,0,1] neg_lo:[0,1,0]
	v_pk_add_f32 v[32:33], v[40:41], v[48:49] neg_lo:[0,1] neg_hi:[0,1]
	v_pk_fma_f32 v[6:7], v[22:23], s[44:45], v[20:21] op_sel:[1,1,0] op_sel_hi:[1,0,1] neg_lo:[0,1,0]
	v_pk_mul_f32 v[20:21], v[24:25], s[46:47] op_sel:[0,0] op_sel_hi:[0,1]
	v_pk_add_f32 v[22:23], v[38:39], v[46:47] neg_lo:[0,1] neg_hi:[0,1]
	v_pk_fma_f32 v[16:17], v[24:25], s[46:47], v[20:21] op_sel:[1,1,0] op_sel_hi:[1,0,1] neg_lo:[0,1,0]
	v_pk_add_f32 v[20:21], v[38:39], v[46:47]
	v_pk_add_f32 v[24:25], v[40:41], v[48:49]
	v_pk_add_f32 v[38:39], v[8:9], v[36:37]
	v_pk_add_f32 v[34:35], v[20:21], v[24:25]
	v_pk_add_f32 v[20:21], v[20:21], v[24:25] neg_lo:[0,1] neg_hi:[0,1]
	v_pk_add_f32 v[24:25], v[22:23], v[32:33] op_sel:[0,1] op_sel_hi:[1,0] neg_hi:[0,1]
	v_pk_add_f32 v[22:23], v[22:23], v[32:33] op_sel:[0,1] op_sel_hi:[1,0] neg_lo:[0,1]
	v_pk_add_f32 v[32:33], v[50:51], v[30:31]
	v_pk_add_f32 v[30:31], v[50:51], v[30:31] neg_lo:[0,1] neg_hi:[0,1]
	v_pk_add_f32 v[8:9], v[8:9], v[36:37] neg_lo:[0,1] neg_hi:[0,1]
	v_pk_add_f32 v[36:37], v[32:33], v[38:39]
	v_pk_add_f32 v[32:33], v[32:33], v[38:39] neg_lo:[0,1] neg_hi:[0,1]
	v_pk_add_f32 v[38:39], v[30:31], v[8:9] op_sel:[0,1] op_sel_hi:[1,0] neg_hi:[0,1]
	v_pk_add_f32 v[8:9], v[30:31], v[8:9] op_sel:[0,1] op_sel_hi:[1,0] neg_lo:[0,1]
	v_pk_add_f32 v[30:31], v[26:27], v[14:15]
	v_pk_add_f32 v[14:15], v[26:27], v[14:15] neg_lo:[0,1] neg_hi:[0,1]
	v_pk_add_f32 v[26:27], v[4:5], v[28:29]
	v_pk_add_f32 v[4:5], v[4:5], v[28:29] neg_lo:[0,1] neg_hi:[0,1]
	v_pk_add_f32 v[28:29], v[30:31], v[26:27]
	v_pk_add_f32 v[26:27], v[30:31], v[26:27] neg_lo:[0,1] neg_hi:[0,1]
	v_pk_add_f32 v[30:31], v[14:15], v[4:5] op_sel:[0,1] op_sel_hi:[1,0] neg_hi:[0,1]
	v_pk_add_f32 v[4:5], v[14:15], v[4:5] op_sel:[0,1] op_sel_hi:[1,0] neg_lo:[0,1]
	v_pk_add_f32 v[14:15], v[18:19], v[6:7]
	v_pk_add_f32 v[6:7], v[18:19], v[6:7] neg_lo:[0,1] neg_hi:[0,1]
	v_pk_add_f32 v[18:19], v[2:3], v[16:17]
	v_pk_add_f32 v[2:3], v[2:3], v[16:17] neg_lo:[0,1] neg_hi:[0,1]
	v_pk_add_f32 v[16:17], v[14:15], v[18:19]
	v_pk_add_f32 v[14:15], v[14:15], v[18:19] neg_lo:[0,1] neg_hi:[0,1]
	v_pk_add_f32 v[18:19], v[6:7], v[2:3] op_sel:[0,1] op_sel_hi:[1,0] neg_hi:[0,1]
	v_pk_add_f32 v[2:3], v[6:7], v[2:3] op_sel:[0,1] op_sel_hi:[1,0] neg_lo:[0,1]
	v_add_f32_e32 v6, 0x358637bd, v10
	v_mul_f32_e32 v6, 0x46000000, v6
	v_div_scale_f32 v7, s[28:29], v6, v6, 1.0
	v_rcp_f32_e32 v10, v7
	s_nop 0
	v_fma_f32 v40, -v7, v10, 1.0
	v_fmac_f32_e32 v10, v40, v10
	v_div_scale_f32 v40, vcc, 1.0, v6, 1.0
	v_mul_f32_e32 v41, v40, v10
	v_fma_f32 v42, -v7, v41, v40
	v_fmac_f32_e32 v41, v42, v10
	v_fma_f32 v7, -v7, v41, v40
	v_div_fmas_f32 v7, v7, v10, v41
	v_div_fixup_f32 v6, v7, v6, 1.0
	v_pk_mul_f32 v[34:35], v[6:7], v[34:35] op_sel_hi:[0,1]
	v_pk_mul_f32 v[24:25], v[6:7], v[24:25] op_sel_hi:[0,1]
	v_pk_mul_f32 v[20:21], v[6:7], v[20:21] op_sel_hi:[0,1]
	v_pk_mul_f32 v[22:23], v[6:7], v[22:23] op_sel_hi:[0,1]
	v_pk_mul_f32 v[36:37], v[6:7], v[36:37] op_sel_hi:[0,1]
	v_pk_mul_f32 v[38:39], v[6:7], v[38:39] op_sel_hi:[0,1]
	v_pk_mul_f32 v[32:33], v[6:7], v[32:33] op_sel_hi:[0,1]
	v_pk_mul_f32 v[8:9], v[6:7], v[8:9] op_sel_hi:[0,1]
	v_pk_mul_f32 v[28:29], v[6:7], v[28:29] op_sel_hi:[0,1]
	v_pk_mul_f32 v[30:31], v[6:7], v[30:31] op_sel_hi:[0,1]
	v_pk_mul_f32 v[26:27], v[6:7], v[26:27] op_sel_hi:[0,1]
	v_pk_mul_f32 v[4:5], v[6:7], v[4:5] op_sel_hi:[0,1]
	v_pk_mul_f32 v[16:17], v[6:7], v[16:17] op_sel_hi:[0,1]
	v_pk_mul_f32 v[18:19], v[6:7], v[18:19] op_sel_hi:[0,1]
	v_pk_mul_f32 v[14:15], v[6:7], v[14:15] op_sel_hi:[0,1]
	v_pk_mul_f32 v[2:3], v[6:7], v[2:3] op_sel_hi:[0,1]
	v_lshl_add_u64 v[6:7], s[12:13], 3, v[12:13]
	global_store_dwordx2 v[6:7], v[34:35], off
	v_add_co_u32_e32 v34, vcc, s57, v6
	s_nop 1
	v_addc_co_u32_e32 v35, vcc, 0, v7, vcc
	global_store_dwordx2 v[34:35], v[24:25], off offset:-4096
	global_store_dwordx2 v[34:35], v[20:21], off
	v_add_co_u32_e32 v20, vcc, s58, v6
	s_nop 1
	v_addc_co_u32_e32 v21, vcc, 0, v7, vcc
	global_store_dwordx2 v[20:21], v[22:23], off offset:-4096
	global_store_dwordx2 v[20:21], v[36:37], off
	v_add_co_u32_e32 v20, vcc, s59, v6
	s_nop 1
	v_addc_co_u32_e32 v21, vcc, 0, v7, vcc
	global_store_dwordx2 v[20:21], v[38:39], off offset:-4096
	global_store_dwordx2 v[20:21], v[32:33], off
	v_add_co_u32_e32 v20, vcc, s60, v6
	s_nop 1
	v_addc_co_u32_e32 v21, vcc, 0, v7, vcc
	global_store_dwordx2 v[20:21], v[8:9], off offset:-4096
	global_store_dwordx2 v[20:21], v[28:29], off
	v_add_co_u32_e32 v8, vcc, s61, v6
	s_nop 1
	v_addc_co_u32_e32 v9, vcc, 0, v7, vcc
	global_store_dwordx2 v[8:9], v[30:31], off offset:-4096
	global_store_dwordx2 v[8:9], v[26:27], off
	v_add_co_u32_e32 v8, vcc, s62, v6
	s_nop 1
	v_addc_co_u32_e32 v9, vcc, 0, v7, vcc
	global_store_dwordx2 v[8:9], v[4:5], off offset:-4096
	global_store_dwordx2 v[8:9], v[16:17], off
	v_add_co_u32_e32 v4, vcc, s63, v6
	s_nop 1
	v_addc_co_u32_e32 v5, vcc, 0, v7, vcc
	global_store_dwordx2 v[4:5], v[18:19], off
	v_add_co_u32_e32 v4, vcc, 0xe000, v6
	s_nop 1
	v_addc_co_u32_e32 v5, vcc, 0, v7, vcc
	global_store_dwordx2 v[4:5], v[14:15], off
	v_add_co_u32_e32 v4, vcc, 0xf000, v6
	s_nop 1
	v_addc_co_u32_e32 v5, vcc, 0, v7, vcc
	s_and_b64 vcc, exec, s[50:51]
	global_store_dwordx2 v[4:5], v[2:3], off
	s_barrier
	s_cbranch_vccnz .LBB0_3098

.LBB0_3135:
	s_or_b64 exec, exec, s[50:51]
	v_mov_b32_e32 v2, s56
	v_mov_b32_e32 v16, v55
	v_mov_b32_e32 v17, v61
	s_waitcnt lgkmcnt(0)
	s_barrier
	ds_read_b128 v[6:9], v2
	ds_read_b128 v[2:5], v2 offset:16
	ds_read_b64 v[18:19], v57
	ds_read_b64 v[20:21], v58
	s_and_saveexec_b64 s[28:29], s[6:7]
	s_xor_b64 s[50:51], exec, s[28:29]
	s_cbranch_execz .LBB0_3137
	v_pk_mul_f32 v[22:23], v[16:17], s[14:15] op_sel:[0,0] op_sel_hi:[0,1]
	s_waitcnt lgkmcnt(0)
	v_sub_f32_e32 v10, v20, v18
	v_pk_fma_f32 v[14:15], v[16:17], s[14:15], v[22:23] op_sel:[1,1,0] op_sel_hi:[1,0,1] neg_lo:[0,1,0]
	s_nop 0
	v_pk_mul_f32 v[14:15], v[10:11], v[14:15] op_sel_hi:[0,1]

.LBB0_3139:
	s_or_b64 exec, exec, s[50:51]
	s_waitcnt lgkmcnt(0)
	ds_read_b64 v[20:21], v57 offset:2176
	ds_read_b64 v[22:23], v58 offset:2176
	s_and_saveexec_b64 s[28:29], s[6:7]
	s_xor_b64 s[50:51], exec, s[28:29]
	s_cbranch_execz .LBB0_3141
	v_pk_mul_f32 v[24:25], v[16:17], s[16:17] op_sel:[0,0] op_sel_hi:[0,1]
	s_waitcnt lgkmcnt(0)
	v_sub_f32_e32 v10, v22, v20
	v_pk_fma_f32 v[18:19], v[16:17], s[16:17], v[24:25] op_sel:[1,1,0] op_sel_hi:[1,0,1] neg_lo:[0,1,0]
	s_nop 0
	v_pk_mul_f32 v[18:19], v[10:11], v[18:19] op_sel_hi:[0,1]

.LBB0_3143:
	s_or_b64 exec, exec, s[50:51]
	s_waitcnt lgkmcnt(0)
	ds_read_b64 v[22:23], v57 offset:4352
	ds_read_b64 v[24:25], v58 offset:4352
	s_and_saveexec_b64 s[28:29], s[6:7]
	s_xor_b64 s[50:51], exec, s[28:29]
	s_cbranch_execz .LBB0_3145
	v_pk_mul_f32 v[26:27], v[16:17], s[20:21] op_sel:[0,0] op_sel_hi:[0,1]
	s_waitcnt lgkmcnt(0)
	v_sub_f32_e32 v10, v24, v22
	v_pk_fma_f32 v[20:21], v[16:17], s[20:21], v[26:27] op_sel:[1,1,0] op_sel_hi:[1,0,1] neg_lo:[0,1,0]
	s_nop 0
	v_pk_mul_f32 v[20:21], v[10:11], v[20:21] op_sel_hi:[0,1]

.LBB0_3147:
	s_or_b64 exec, exec, s[50:51]
	s_waitcnt lgkmcnt(0)
	ds_read_b64 v[24:25], v57 offset:6528
	ds_read_b64 v[26:27], v58 offset:6528
	s_and_saveexec_b64 s[28:29], s[6:7]
	s_xor_b64 s[50:51], exec, s[28:29]
	s_cbranch_execz .LBB0_3149
	v_pk_mul_f32 v[28:29], v[16:17], s[22:23] op_sel:[0,0] op_sel_hi:[0,1]
	s_waitcnt lgkmcnt(0)
	v_sub_f32_e32 v10, v26, v24
	v_pk_fma_f32 v[22:23], v[16:17], s[22:23], v[28:29] op_sel:[1,1,0] op_sel_hi:[1,0,1] neg_lo:[0,1,0]
	s_nop 0
	v_pk_mul_f32 v[22:23], v[10:11], v[22:23] op_sel_hi:[0,1]

.LBB0_3151:
	s_or_b64 exec, exec, s[50:51]
	s_waitcnt lgkmcnt(0)
	ds_read_b64 v[26:27], v57 offset:8704
	ds_read_b64 v[28:29], v58 offset:8704
	s_and_saveexec_b64 s[28:29], s[6:7]
	s_xor_b64 s[50:51], exec, s[28:29]
	s_cbranch_execz .LBB0_3153
	v_pk_mul_f32 v[30:31], v[16:17], s[26:27] op_sel:[0,0] op_sel_hi:[0,1]
	s_waitcnt lgkmcnt(0)
	v_sub_f32_e32 v10, v28, v26
	v_pk_fma_f32 v[24:25], v[16:17], s[26:27], v[30:31] op_sel:[1,1,0] op_sel_hi:[1,0,1] neg_lo:[0,1,0]
	s_nop 0
	v_pk_mul_f32 v[24:25], v[10:11], v[24:25] op_sel_hi:[0,1]

.LBB0_3155:
	s_or_b64 exec, exec, s[50:51]
	s_waitcnt lgkmcnt(0)
	ds_read_b64 v[28:29], v57 offset:10880
	ds_read_b64 v[30:31], v58 offset:10880
	s_and_saveexec_b64 s[28:29], s[6:7]
	s_xor_b64 s[50:51], exec, s[28:29]
	s_cbranch_execz .LBB0_3157
	v_pk_mul_f32 v[32:33], v[16:17], s[34:35] op_sel:[0,0] op_sel_hi:[0,1]
	s_waitcnt lgkmcnt(0)
	v_sub_f32_e32 v10, v30, v28
	v_pk_fma_f32 v[26:27], v[16:17], s[34:35], v[32:33] op_sel:[1,1,0] op_sel_hi:[1,0,1] neg_lo:[0,1,0]
	s_nop 0
	v_pk_mul_f32 v[26:27], v[10:11], v[26:27] op_sel_hi:[0,1]

.LBB0_3159:
	s_or_b64 exec, exec, s[50:51]
	s_waitcnt lgkmcnt(0)
	ds_read_b64 v[30:31], v57 offset:13056
	ds_read_b64 v[32:33], v58 offset:13056
	s_and_saveexec_b64 s[28:29], s[6:7]
	s_xor_b64 s[50:51], exec, s[28:29]
	s_cbranch_execz .LBB0_3161
	v_pk_mul_f32 v[34:35], v[16:17], s[36:37] op_sel:[0,0] op_sel_hi:[0,1]
	s_waitcnt lgkmcnt(0)
	v_sub_f32_e32 v10, v32, v30
	v_pk_fma_f32 v[28:29], v[16:17], s[36:37], v[34:35] op_sel:[1,1,0] op_sel_hi:[1,0,1] neg_lo:[0,1,0]
	s_nop 0
	v_pk_mul_f32 v[28:29], v[10:11], v[28:29] op_sel_hi:[0,1]

.LBB0_3163:
	s_or_b64 exec, exec, s[50:51]
	s_waitcnt lgkmcnt(0)
	ds_read_b64 v[32:33], v57 offset:15232
	ds_read_b64 v[34:35], v58 offset:15232
	s_and_saveexec_b64 s[28:29], s[6:7]
	s_xor_b64 s[50:51], exec, s[28:29]
	s_cbranch_execz .LBB0_3165
	v_pk_mul_f32 v[36:37], v[16:17], s[38:39] op_sel:[0,0] op_sel_hi:[0,1]
	s_waitcnt lgkmcnt(0)
	v_sub_f32_e32 v10, v34, v32
	v_pk_fma_f32 v[30:31], v[16:17], s[38:39], v[36:37] op_sel:[1,1,0] op_sel_hi:[1,0,1] neg_lo:[0,1,0]
	s_nop 0
	v_pk_mul_f32 v[30:31], v[10:11], v[30:31] op_sel_hi:[0,1]

.LBB0_3167:
	s_or_b64 exec, exec, s[50:51]
	s_waitcnt lgkmcnt(0)
	ds_read_b64 v[34:35], v57 offset:17408
	ds_read_b64 v[36:37], v58 offset:17408
	s_and_saveexec_b64 s[28:29], s[6:7]
	s_xor_b64 s[50:51], exec, s[28:29]
	s_cbranch_execz .LBB0_3169
	v_pk_mul_f32 v[38:39], v[16:17], s[40:41] op_sel:[0,0] op_sel_hi:[0,1]
	s_waitcnt lgkmcnt(0)
	v_sub_f32_e32 v10, v36, v34
	v_pk_fma_f32 v[32:33], v[16:17], s[40:41], v[38:39] op_sel:[1,1,0] op_sel_hi:[1,0,1] neg_lo:[0,1,0]
	s_nop 0
	v_pk_mul_f32 v[32:33], v[10:11], v[32:33] op_sel_hi:[0,1]

.LBB0_3171:
	s_or_b64 exec, exec, s[50:51]
	s_waitcnt lgkmcnt(0)
	ds_read_b64 v[36:37], v57 offset:19584
	ds_read_b64 v[38:39], v58 offset:19584
	s_and_saveexec_b64 s[28:29], s[6:7]
	s_xor_b64 s[50:51], exec, s[28:29]
	s_cbranch_execz .LBB0_3173
	s_mov_b32 s28, s17
	s_mov_b32 s29, s39
	v_pk_mul_f32 v[40:41], v[16:17], s[28:29] op_sel:[0,0] op_sel_hi:[0,1]
	s_waitcnt lgkmcnt(0)
	v_sub_f32_e32 v10, v38, v36
	v_pk_fma_f32 v[34:35], v[16:17], s[28:29], v[40:41] op_sel:[1,1,0] op_sel_hi:[1,0,1] neg_lo:[0,1,0]
	s_nop 0
	v_pk_mul_f32 v[34:35], v[10:11], v[34:35] op_sel_hi:[0,1]

.LBB0_3175:
	s_or_b64 exec, exec, s[50:51]
	s_waitcnt lgkmcnt(0)
	ds_read_b64 v[38:39], v57 offset:21760
	ds_read_b64 v[40:41], v58 offset:21760
	s_and_saveexec_b64 s[28:29], s[6:7]
	s_xor_b64 s[50:51], exec, s[28:29]
	s_cbranch_execz .LBB0_3177
	v_pk_mul_f32 v[42:43], v[16:17], s[18:19] op_sel:[0,0] op_sel_hi:[0,1]
	s_waitcnt lgkmcnt(0)
	v_sub_f32_e32 v10, v40, v38
	v_pk_fma_f32 v[36:37], v[16:17], s[18:19], v[42:43] op_sel:[1,1,0] op_sel_hi:[1,0,1] neg_lo:[0,1,0]
	s_nop 0
	v_pk_mul_f32 v[36:37], v[10:11], v[36:37] op_sel_hi:[0,1]

.LBB0_3179:
	s_or_b64 exec, exec, s[50:51]
	s_waitcnt lgkmcnt(0)
	ds_read_b64 v[40:41], v57 offset:23936
	ds_read_b64 v[42:43], v58 offset:23936
	s_and_saveexec_b64 s[28:29], s[6:7]
	s_xor_b64 s[50:51], exec, s[28:29]
	s_cbranch_execz .LBB0_3181
	s_mov_b32 s28, s23
	s_mov_b32 s29, s35
	v_pk_mul_f32 v[44:45], v[16:17], s[28:29] op_sel:[0,0] op_sel_hi:[0,1]
	s_waitcnt lgkmcnt(0)
	v_sub_f32_e32 v10, v42, v40
	v_pk_fma_f32 v[38:39], v[16:17], s[28:29], v[44:45] op_sel:[1,1,0] op_sel_hi:[1,0,1] neg_lo:[0,1,0]
	s_nop 0
	v_pk_mul_f32 v[38:39], v[10:11], v[38:39] op_sel_hi:[0,1]

.LBB0_3183:
	s_or_b64 exec, exec, s[50:51]
	s_waitcnt lgkmcnt(0)
	ds_read_b64 v[42:43], v57 offset:26112
	ds_read_b64 v[44:45], v58 offset:26112
	s_and_saveexec_b64 s[28:29], s[6:7]
	s_xor_b64 s[50:51], exec, s[28:29]
	s_cbranch_execz .LBB0_3185
	v_pk_mul_f32 v[46:47], v[16:17], s[44:45] op_sel:[0,0] op_sel_hi:[0,1]
	s_waitcnt lgkmcnt(0)
	v_sub_f32_e32 v10, v44, v42
	v_pk_fma_f32 v[40:41], v[16:17], s[44:45], v[46:47] op_sel:[1,1,0] op_sel_hi:[1,0,1] neg_lo:[0,1,0]
	s_nop 0
	v_pk_mul_f32 v[40:41], v[10:11], v[40:41] op_sel_hi:[0,1]

.LBB0_3187:
	s_or_b64 exec, exec, s[50:51]
	s_waitcnt lgkmcnt(0)
	ds_read_b64 v[44:45], v57 offset:28288
	ds_read_b64 v[46:47], v58 offset:28288
	s_and_saveexec_b64 s[28:29], s[6:7]
	s_xor_b64 s[50:51], exec, s[28:29]
	s_cbranch_execz .LBB0_3189
	s_mov_b32 s28, s35
	s_mov_b32 s29, s23
	v_pk_mul_f32 v[48:49], v[16:17], s[28:29] op_sel:[0,0] op_sel_hi:[0,1]
	s_waitcnt lgkmcnt(0)
	v_sub_f32_e32 v10, v46, v44
	v_pk_fma_f32 v[42:43], v[16:17], s[28:29], v[48:49] op_sel:[1,1,0] op_sel_hi:[1,0,1] neg_lo:[0,1,0]
	s_nop 0
	v_pk_mul_f32 v[42:43], v[10:11], v[42:43] op_sel_hi:[0,1]

.LBB0_3191:
	s_or_b64 exec, exec, s[50:51]
	s_waitcnt lgkmcnt(0)
	ds_read_b64 v[46:47], v57 offset:30464
	ds_read_b64 v[48:49], v58 offset:30464
	s_and_saveexec_b64 s[28:29], s[6:7]
	s_xor_b64 s[50:51], exec, s[28:29]
	s_cbranch_execz .LBB0_3193
	s_mov_b32 s28, s19
	s_mov_b32 s29, s18
	v_pk_mul_f32 v[50:51], v[16:17], s[28:29] op_sel:[0,0] op_sel_hi:[0,1]
	s_waitcnt lgkmcnt(0)
	v_sub_f32_e32 v10, v48, v46
	v_pk_fma_f32 v[44:45], v[16:17], s[28:29], v[50:51] op_sel:[1,1,0] op_sel_hi:[1,0,1] neg_lo:[0,1,0]
	s_nop 0
	v_pk_mul_f32 v[44:45], v[10:11], v[44:45] op_sel_hi:[0,1]

.LBB0_3195:
	s_or_b64 exec, exec, s[50:51]
	s_waitcnt lgkmcnt(0)
	ds_read_b64 v[48:49], v57 offset:32640
	ds_read_b64 v[50:51], v58 offset:32640
	s_and_saveexec_b64 s[28:29], s[6:7]
	s_xor_b64 s[50:51], exec, s[28:29]
	s_cbranch_execz .LBB0_3197
	s_mov_b32 s28, s39
	s_mov_b32 s29, s17
	s_waitcnt lgkmcnt(0)
	v_sub_f32_e32 v10, v50, v48
	v_pk_mul_f32 v[66:67], v[16:17], s[28:29] op_sel:[0,0] op_sel_hi:[0,1]
	s_nop 0
	v_pk_fma_f32 v[16:17], v[16:17], s[28:29], v[66:67] op_sel:[1,1,0] op_sel_hi:[1,0,1] neg_lo:[0,1,0]
	s_nop 0
	v_pk_mul_f32 v[46:47], v[10:11], v[16:17] op_sel_hi:[0,1]

.LBB0_3296:
	v_and_b32_e32 v37, 15, v133
	v_cvt_f32_ubyte0_e32 v27, v126
	v_cvt_f32_ubyte0_e32 v37, v37
	v_mul_f32_e32 v36, 0x39800000, v27
	v_mul_f32_e32 v37, 0x3b800000, v37
	v_mul_f32_e32 v27, 0x39000000, v27
	v_cos_f32_e32 v38, v36
	v_sin_f32_e32 v39, v36
	v_cos_f32_e32 v40, v37
	v_sin_f32_e32 v41, v37
	v_cos_f32_e32 v36, v27
	v_sin_f32_e32 v37, v27
	v_lshrrev_b32_e32 v131, 4, v126
	v_mad_i32_i24 v27, v130, s92, 0
	v_sub_u32_e32 v43, 1, v130
	v_add_u32_e32 v45, v131, v126
	v_mul_lo_u32 v43, v43, s92
	v_lshl_add_u32 v47, v126, 3, v27
	v_lshlrev_b32_e32 v138, 3, v45
	s_andn2_b64 vcc, exec, s[0:1]
	s_movk_i32 s0, 0x88
	v_lshl_add_u32 v132, v131, 3, v47
	v_add3_u32 v136, 0, v43, v138
	v_lshl_add_u32 v134, v131, 11, v47
	v_mad_u32_u24 v135, v126, s0, v27
	s_cbranch_vccnz .LBB0_3396
	v_add_f32_e64 v27, |v42|, |v34|
	v_add_f32_e64 v27, |v44|, v27
	v_add_f32_e64 v27, |v46|, v27
	v_add_f32_e64 v27, |v50|, v27
	v_add_f32_e64 v27, |v54|, v27
	v_add_f32_e64 v27, |v48|, v27
	v_add_f32_e64 v27, |v52|, v27
	v_add_f32_e64 v27, |v56|, v27
	v_add_f32_e64 v27, |v58|, v27
	v_add_f32_e64 v27, |v60|, v27
	v_add_f32_e64 v27, |v62|, v27
	s_waitcnt vmcnt(13)
	v_and_b32_e32 v28, 64, v125
	v_add_f32_e64 v27, |v64|, v27
	v_add_u32_e32 v28, 64, v28
	v_xor_b32_e32 v29, 32, v125
	v_add_f32_e64 v27, |v66|, v27
	v_cmp_lt_i32_e32 vcc, v29, v28
	v_add_f32_e64 v27, |v68|, v27
	v_add_f32_e64 v27, |v26|, v27
	v_cndmask_b32_e32 v29, v125, v29, vcc
	v_lshlrev_b32_e32 v29, 2, v29
	ds_bpermute_b32 v29, v29, v27
	v_mov_b32_e32 v43, v35
	v_mov_b32_e32 v45, v35
	v_mov_b32_e32 v47, v35
	v_mov_b32_e32 v51, v35
	s_waitcnt lgkmcnt(0)
	v_add_f32_e32 v27, v27, v29
	v_xor_b32_e32 v29, 16, v125
	v_cmp_lt_i32_e32 vcc, v29, v28
	v_mov_b32_e32 v55, v35
	v_mov_b32_e32 v49, v35
	v_cndmask_b32_e32 v29, v125, v29, vcc
	v_lshlrev_b32_e32 v29, 2, v29
	ds_bpermute_b32 v29, v29, v27
	v_mov_b32_e32 v53, v35
	v_mov_b32_e32 v57, v35
	v_mov_b32_e32 v59, v35
	v_mov_b32_e32 v61, v35
	s_waitcnt lgkmcnt(0)
	v_add_f32_e32 v27, v27, v29
	v_xor_b32_e32 v29, 8, v125
	v_cmp_lt_i32_e32 vcc, v29, v28
	v_mov_b32_e32 v63, v35
	v_mov_b32_e32 v65, v35
	v_cndmask_b32_e32 v29, v125, v29, vcc
	v_lshlrev_b32_e32 v29, 2, v29
	ds_bpermute_b32 v29, v29, v27
	v_mov_b32_e32 v67, v35
	v_mov_b32_e32 v69, v35
	ds_write_b64 v132, v[34:35]
	ds_write_b64 v132, v[42:43] offset:2176
	s_waitcnt lgkmcnt(2)
	v_add_f32_e32 v27, v27, v29
	v_xor_b32_e32 v29, 4, v125
	v_cmp_lt_i32_e32 vcc, v29, v28
	ds_write_b64 v132, v[44:45] offset:4352
	ds_write_b64 v132, v[46:47] offset:6528
	v_cndmask_b32_e32 v29, v125, v29, vcc
	v_lshlrev_b32_e32 v29, 2, v29
	ds_bpermute_b32 v29, v29, v27
	ds_write_b64 v132, v[50:51] offset:8704
	ds_write_b64 v132, v[54:55] offset:10880
	ds_write_b64 v132, v[48:49] offset:13056
	ds_write_b64 v132, v[52:53] offset:15232
	s_waitcnt lgkmcnt(4)
	v_add_f32_e32 v29, v27, v29
	v_xor_b32_e32 v27, 2, v125
	v_cmp_lt_i32_e32 vcc, v27, v28
	ds_write_b64 v132, v[56:57] offset:17408
	ds_write_b64 v132, v[58:59] offset:19584
	v_cndmask_b32_e32 v27, v125, v27, vcc
	v_lshlrev_b32_e32 v27, 2, v27
	ds_bpermute_b32 v30, v27, v29
	v_mov_b32_e32 v27, v35
	ds_write_b64 v132, v[26:27] offset:32640
	v_xor_b32_e32 v27, 1, v125
	v_cmp_lt_i32_e32 vcc, v27, v28
	s_waitcnt lgkmcnt(1)
	v_add_f32_e32 v26, v29, v30
	v_mov_b32_e32 v28, v0
	v_cndmask_b32_e32 v27, v125, v27, vcc
	v_lshlrev_b32_e32 v27, 2, v27
	ds_bpermute_b32 v27, v27, v26
	ds_write_b64 v132, v[60:61] offset:21760
	ds_write_b64 v132, v[62:63] offset:23936
	ds_write_b64 v132, v[64:65] offset:26112
	ds_write_b64 v132, v[66:67] offset:28288
	ds_write_b64 v132, v[68:69] offset:30464
	s_waitcnt lgkmcnt(0)
	s_barrier
	s_nop 0
	v_and_b32_e32 v29, 63, v28
	v_cmp_eq_u32_e32 vcc, 0, v29
	s_and_saveexec_b64 s[0:1], vcc
	v_add_f32_e32 v26, v26, v27
	v_ashrrev_i32_e32 v27, 4, v28
	v_add_u32_e32 v27, 0, v27
	v_add_u32_e32 v27, 0x11000, v27
	ds_write_b32 v27, v26
	s_or_b64 exec, exec, s[0:1]
	s_add_i32 s0, 0, 0x11000
	v_mov_b32_e32 v26, s0
	v_xor_b32_e32 v45, 0x80000000, v37
	v_mov_b32_e32 v44, v36
	s_waitcnt lgkmcnt(0)
	s_barrier
	s_waitcnt vmcnt(12)
	ds_read_b128 v[30:33], v26
	ds_read_b128 v[26:29], v26 offset:16
	ds_read_b64 v[46:47], v132
	ds_read_b64 v[48:49], v136
	s_and_saveexec_b64 s[0:1], s[4:5]
	s_xor_b64 s[0:1], exec, s[0:1]
	s_cbranch_execz .LBB0_3301
	v_pk_mul_f32 v[50:51], v[44:45], s[12:13] op_sel:[0,0] op_sel_hi:[0,1]
	s_waitcnt lgkmcnt(0)
	v_sub_f32_e32 v34, v48, v46
	v_pk_fma_f32 v[42:43], v[44:45], s[12:13], v[50:51] op_sel:[1,1,0] op_sel_hi:[1,0,1] neg_lo:[0,1,0]
	s_nop 0
	v_pk_mul_f32 v[42:43], v[34:35], v[42:43] op_sel_hi:[0,1]

.LBB0_3303:
	s_or_b64 exec, exec, s[0:1]
	s_waitcnt lgkmcnt(0)
	ds_read_b64 v[48:49], v132 offset:2176
	ds_read_b64 v[50:51], v136 offset:2176
	s_and_saveexec_b64 s[0:1], s[4:5]
	s_xor_b64 s[0:1], exec, s[0:1]
	s_cbranch_execz .LBB0_3305
	v_pk_mul_f32 v[52:53], v[44:45], s[16:17] op_sel:[0,0] op_sel_hi:[0,1]
	s_waitcnt lgkmcnt(0)
	v_sub_f32_e32 v34, v50, v48
	v_pk_fma_f32 v[46:47], v[44:45], s[16:17], v[52:53] op_sel:[1,1,0] op_sel_hi:[1,0,1] neg_lo:[0,1,0]
	s_nop 0
	v_pk_mul_f32 v[46:47], v[34:35], v[46:47] op_sel_hi:[0,1]

.LBB0_3307:
	s_or_b64 exec, exec, s[0:1]
	s_waitcnt lgkmcnt(0)
	ds_read_b64 v[50:51], v132 offset:4352
	ds_read_b64 v[52:53], v136 offset:4352
	s_and_saveexec_b64 s[0:1], s[4:5]
	s_xor_b64 s[0:1], exec, s[0:1]
	s_cbranch_execz .LBB0_3309
	v_pk_mul_f32 v[54:55], v[44:45], s[20:21] op_sel:[0,0] op_sel_hi:[0,1]
	s_waitcnt lgkmcnt(0)
	v_sub_f32_e32 v34, v52, v50
	v_pk_fma_f32 v[48:49], v[44:45], s[20:21], v[54:55] op_sel:[1,1,0] op_sel_hi:[1,0,1] neg_lo:[0,1,0]
	s_nop 0
	v_pk_mul_f32 v[48:49], v[34:35], v[48:49] op_sel_hi:[0,1]

.LBB0_3311:
	s_or_b64 exec, exec, s[0:1]
	s_waitcnt lgkmcnt(0)
	ds_read_b64 v[52:53], v132 offset:6528
	ds_read_b64 v[54:55], v136 offset:6528
	s_and_saveexec_b64 s[0:1], s[4:5]
	s_xor_b64 s[0:1], exec, s[0:1]
	s_cbranch_execz .LBB0_3313
	v_pk_mul_f32 v[56:57], v[44:45], s[22:23] op_sel:[0,0] op_sel_hi:[0,1]
	s_waitcnt lgkmcnt(0)
	v_sub_f32_e32 v34, v54, v52
	v_pk_fma_f32 v[50:51], v[44:45], s[22:23], v[56:57] op_sel:[1,1,0] op_sel_hi:[1,0,1] neg_lo:[0,1,0]
	s_nop 0
	v_pk_mul_f32 v[50:51], v[34:35], v[50:51] op_sel_hi:[0,1]

.LBB0_3315:
	s_or_b64 exec, exec, s[0:1]
	s_waitcnt lgkmcnt(0)
	ds_read_b64 v[54:55], v132 offset:8704
	ds_read_b64 v[56:57], v136 offset:8704
	s_and_saveexec_b64 s[0:1], s[4:5]
	s_xor_b64 s[0:1], exec, s[0:1]
	s_cbranch_execz .LBB0_3317
	v_pk_mul_f32 v[58:59], v[44:45], s[46:47] op_sel:[0,0] op_sel_hi:[0,1]
	s_waitcnt lgkmcnt(0)
	v_sub_f32_e32 v34, v56, v54
	v_pk_fma_f32 v[52:53], v[44:45], s[46:47], v[58:59] op_sel:[1,1,0] op_sel_hi:[1,0,1] neg_lo:[0,1,0]
	s_nop 0
	v_pk_mul_f32 v[52:53], v[34:35], v[52:53] op_sel_hi:[0,1]

.LBB0_3319:
	s_or_b64 exec, exec, s[0:1]
	s_waitcnt lgkmcnt(0)
	ds_read_b64 v[56:57], v132 offset:10880
	ds_read_b64 v[58:59], v136 offset:10880
	s_and_saveexec_b64 s[0:1], s[4:5]
	s_xor_b64 s[0:1], exec, s[0:1]
	s_cbranch_execz .LBB0_3321
	v_pk_mul_f32 v[60:61], v[44:45], s[48:49] op_sel:[0,0] op_sel_hi:[0,1]
	s_waitcnt lgkmcnt(0)
	v_sub_f32_e32 v34, v58, v56
	v_pk_fma_f32 v[54:55], v[44:45], s[48:49], v[60:61] op_sel:[1,1,0] op_sel_hi:[1,0,1] neg_lo:[0,1,0]
	s_nop 0
	v_pk_mul_f32 v[54:55], v[34:35], v[54:55] op_sel_hi:[0,1]

.LBB0_3323:
	s_or_b64 exec, exec, s[0:1]
	s_waitcnt lgkmcnt(0)
	ds_read_b64 v[58:59], v132 offset:13056
	ds_read_b64 v[60:61], v136 offset:13056
	s_and_saveexec_b64 s[0:1], s[4:5]
	s_xor_b64 s[0:1], exec, s[0:1]
	s_cbranch_execz .LBB0_3325
	v_pk_mul_f32 v[62:63], v[44:45], s[50:51] op_sel:[0,0] op_sel_hi:[0,1]
	s_waitcnt lgkmcnt(0)
	v_sub_f32_e32 v34, v60, v58
	v_pk_fma_f32 v[56:57], v[44:45], s[50:51], v[62:63] op_sel:[1,1,0] op_sel_hi:[1,0,1] neg_lo:[0,1,0]
	s_nop 0
	v_pk_mul_f32 v[56:57], v[34:35], v[56:57] op_sel_hi:[0,1]

.LBB0_3327:
	s_or_b64 exec, exec, s[0:1]
	s_waitcnt lgkmcnt(0)
	ds_read_b64 v[60:61], v132 offset:15232
	ds_read_b64 v[62:63], v136 offset:15232
	s_and_saveexec_b64 s[0:1], s[4:5]
	s_xor_b64 s[0:1], exec, s[0:1]
	s_cbranch_execz .LBB0_3329
	v_pk_mul_f32 v[64:65], v[44:45], s[52:53] op_sel:[0,0] op_sel_hi:[0,1]
	s_waitcnt lgkmcnt(0)
	v_sub_f32_e32 v34, v62, v60
	v_pk_fma_f32 v[58:59], v[44:45], s[52:53], v[64:65] op_sel:[1,1,0] op_sel_hi:[1,0,1] neg_lo:[0,1,0]
	s_nop 0
	v_pk_mul_f32 v[58:59], v[34:35], v[58:59] op_sel_hi:[0,1]

.LBB0_3331:
	s_or_b64 exec, exec, s[0:1]
	s_waitcnt lgkmcnt(0)
	ds_read_b64 v[62:63], v132 offset:17408
	ds_read_b64 v[64:65], v136 offset:17408
	s_and_saveexec_b64 s[0:1], s[4:5]
	s_xor_b64 s[0:1], exec, s[0:1]
	s_cbranch_execz .LBB0_3333
	v_pk_mul_f32 v[66:67], v[44:45], s[8:9] op_sel:[0,0] op_sel_hi:[0,1]
	s_waitcnt lgkmcnt(0)
	v_sub_f32_e32 v34, v64, v62
	v_pk_fma_f32 v[60:61], v[44:45], s[8:9], v[66:67] op_sel:[1,1,0] op_sel_hi:[1,0,1] neg_lo:[0,1,0]
	s_nop 0
	v_pk_mul_f32 v[60:61], v[34:35], v[60:61] op_sel_hi:[0,1]

.LBB0_3335:
	s_or_b64 exec, exec, s[0:1]
	s_waitcnt lgkmcnt(0)
	ds_read_b64 v[64:65], v132 offset:19584
	ds_read_b64 v[66:67], v136 offset:19584
	s_and_saveexec_b64 s[0:1], s[4:5]
	s_xor_b64 s[0:1], exec, s[0:1]
	s_cbranch_execz .LBB0_3337
	s_mov_b32 s15, s53
	v_pk_mul_f32 v[68:69], v[44:45], s[14:15] op_sel:[0,0] op_sel_hi:[0,1]
	s_waitcnt lgkmcnt(0)
	v_sub_f32_e32 v34, v66, v64
	v_pk_fma_f32 v[62:63], v[44:45], s[14:15], v[68:69] op_sel:[1,1,0] op_sel_hi:[1,0,1] neg_lo:[0,1,0]
	s_nop 0
	v_pk_mul_f32 v[62:63], v[34:35], v[62:63] op_sel_hi:[0,1]

.LBB0_3339:
	s_or_b64 exec, exec, s[0:1]
	s_waitcnt lgkmcnt(0)
	ds_read_b64 v[66:67], v132 offset:21760
	ds_read_b64 v[68:69], v136 offset:21760
	s_and_saveexec_b64 s[0:1], s[4:5]
	s_xor_b64 s[0:1], exec, s[0:1]
	s_cbranch_execz .LBB0_3341
	v_pk_mul_f32 v[70:71], v[44:45], s[18:19] op_sel:[0,0] op_sel_hi:[0,1]
	s_waitcnt lgkmcnt(0)
	v_sub_f32_e32 v34, v68, v66
	v_pk_fma_f32 v[64:65], v[44:45], s[18:19], v[70:71] op_sel:[1,1,0] op_sel_hi:[1,0,1] neg_lo:[0,1,0]
	s_nop 0
	v_pk_mul_f32 v[64:65], v[34:35], v[64:65] op_sel_hi:[0,1]

.LBB0_3343:
	s_or_b64 exec, exec, s[0:1]
	s_waitcnt lgkmcnt(0)
	ds_read_b64 v[68:69], v132 offset:23936
	ds_read_b64 v[70:71], v136 offset:23936
	s_and_saveexec_b64 s[0:1], s[4:5]
	s_xor_b64 s[0:1], exec, s[0:1]
	s_cbranch_execz .LBB0_3345
	s_mov_b32 s28, s23
	s_mov_b32 s29, s49
	s_waitcnt vmcnt(9)
	v_pk_mul_f32 v[72:73], v[44:45], s[28:29] op_sel:[0,0] op_sel_hi:[0,1]
	s_waitcnt lgkmcnt(0)
	v_sub_f32_e32 v34, v70, v68
	v_pk_fma_f32 v[66:67], v[44:45], s[28:29], v[72:73] op_sel:[1,1,0] op_sel_hi:[1,0,1] neg_lo:[0,1,0]
	s_nop 0
	v_pk_mul_f32 v[66:67], v[34:35], v[66:67] op_sel_hi:[0,1]

.LBB0_3347:
	s_or_b64 exec, exec, s[0:1]
	s_waitcnt lgkmcnt(0)
	ds_read_b64 v[70:71], v132 offset:26112
	s_waitcnt vmcnt(9)
	ds_read_b64 v[72:73], v136 offset:26112
	s_and_saveexec_b64 s[0:1], s[4:5]
	s_xor_b64 s[0:1], exec, s[0:1]
	s_cbranch_execz .LBB0_3349
	v_pk_mul_f32 v[74:75], v[44:45], s[54:55] op_sel:[0,0] op_sel_hi:[0,1]
	s_waitcnt lgkmcnt(0)
	v_sub_f32_e32 v34, v72, v70
	v_pk_fma_f32 v[68:69], v[44:45], s[54:55], v[74:75] op_sel:[1,1,0] op_sel_hi:[1,0,1] neg_lo:[0,1,0]
	s_nop 0
	v_pk_mul_f32 v[68:69], v[34:35], v[68:69] op_sel_hi:[0,1]

.LBB0_3351:
	s_or_b64 exec, exec, s[0:1]
	s_waitcnt lgkmcnt(0)
	ds_read_b64 v[72:73], v132 offset:28288
	ds_read_b64 v[74:75], v136 offset:28288
	s_and_saveexec_b64 s[0:1], s[4:5]
	s_xor_b64 s[0:1], exec, s[0:1]
	s_cbranch_execz .LBB0_3353
	s_mov_b32 s28, s49
	s_mov_b32 s29, s23
	s_waitcnt vmcnt(8)
	v_pk_mul_f32 v[76:77], v[44:45], s[28:29] op_sel:[0,0] op_sel_hi:[0,1]
	s_waitcnt lgkmcnt(0)
	v_sub_f32_e32 v34, v74, v72
	v_pk_fma_f32 v[70:71], v[44:45], s[28:29], v[76:77] op_sel:[1,1,0] op_sel_hi:[1,0,1] neg_lo:[0,1,0]
	s_nop 0
	v_pk_mul_f32 v[70:71], v[34:35], v[70:71] op_sel_hi:[0,1]

.LBB0_3355:
	s_or_b64 exec, exec, s[0:1]
	s_waitcnt lgkmcnt(0)
	ds_read_b64 v[74:75], v132 offset:30464
	s_waitcnt vmcnt(8)
	ds_read_b64 v[76:77], v136 offset:30464
	s_and_saveexec_b64 s[0:1], s[4:5]
	s_xor_b64 s[0:1], exec, s[0:1]
	s_cbranch_execz .LBB0_3357
	v_pk_mul_f32 v[78:79], v[44:45], s[68:69] op_sel:[0,0] op_sel_hi:[0,1]
	s_waitcnt lgkmcnt(0)
	v_sub_f32_e32 v34, v76, v74
	v_pk_fma_f32 v[72:73], v[44:45], s[68:69], v[78:79] op_sel:[1,1,0] op_sel_hi:[1,0,1] neg_lo:[0,1,0]
	s_nop 0
	v_pk_mul_f32 v[72:73], v[34:35], v[72:73] op_sel_hi:[0,1]

.LBB0_3359:
	s_or_b64 exec, exec, s[0:1]
	s_waitcnt lgkmcnt(0)
	ds_read_b64 v[76:77], v132 offset:32640
	ds_read_b64 v[78:79], v136 offset:32640
	s_and_saveexec_b64 s[0:1], s[4:5]
	s_xor_b64 s[0:1], exec, s[0:1]
	s_cbranch_execz .LBB0_3361
	s_mov_b32 s28, s53
	s_mov_b32 s29, s14
	s_waitcnt lgkmcnt(0)
	v_sub_f32_e32 v34, v78, v76
	s_waitcnt vmcnt(5)
	v_pk_mul_f32 v[80:81], v[44:45], s[28:29] op_sel:[0,0] op_sel_hi:[0,1]
	s_nop 0
	v_pk_fma_f32 v[44:45], v[44:45], s[28:29], v[80:81] op_sel:[1,1,0] op_sel_hi:[1,0,1] neg_lo:[0,1,0]
	s_nop 0
	v_pk_mul_f32 v[74:75], v[34:35], v[44:45] op_sel_hi:[0,1]

.LBB0_3363:
	s_or_b64 exec, exec, s[0:1]
	v_pk_add_f32 v[44:45], v[42:43], v[60:61]
	v_pk_add_f32 v[42:43], v[42:43], v[60:61] neg_lo:[0,1] neg_hi:[0,1]
	v_pk_add_f32 v[60:61], v[52:53], v[68:69]
	v_pk_add_f32 v[52:53], v[52:53], v[68:69] neg_lo:[0,1] neg_hi:[0,1]
	v_pk_add_f32 v[68:69], v[44:45], v[60:61]
	v_pk_add_f32 v[60:61], v[44:45], v[60:61] neg_lo:[0,1] neg_hi:[0,1]
	s_waitcnt lgkmcnt(1)
	v_pk_add_f32 v[76:77], v[42:43], v[52:53] op_sel:[0,1] op_sel_hi:[1,0] neg_hi:[0,1]
	s_waitcnt lgkmcnt(0)
	v_pk_add_f32 v[78:79], v[42:43], v[52:53] op_sel:[0,1] op_sel_hi:[1,0] neg_lo:[0,1]
	v_pk_add_f32 v[42:43], v[46:47], v[62:63]
	v_pk_add_f32 v[44:45], v[46:47], v[62:63] neg_lo:[0,1] neg_hi:[0,1]
	v_pk_add_f32 v[46:47], v[54:55], v[70:71]
	v_pk_add_f32 v[52:53], v[54:55], v[70:71] neg_lo:[0,1] neg_hi:[0,1]
	v_pk_add_f32 v[54:55], v[42:43], v[46:47]
	v_pk_add_f32 v[46:47], v[42:43], v[46:47] neg_lo:[0,1] neg_hi:[0,1]
	v_pk_add_f32 v[42:43], v[44:45], v[52:53] op_sel:[0,1] op_sel_hi:[1,0] neg_hi:[0,1]
	v_pk_add_f32 v[52:53], v[44:45], v[52:53] op_sel:[0,1] op_sel_hi:[1,0] neg_lo:[0,1]
	v_pk_add_f32 v[44:45], v[48:49], v[64:65]
	v_pk_add_f32 v[48:49], v[48:49], v[64:65] neg_lo:[0,1] neg_hi:[0,1]
	v_pk_add_f32 v[62:63], v[56:57], v[72:73]
	v_pk_add_f32 v[56:57], v[56:57], v[72:73] neg_lo:[0,1] neg_hi:[0,1]
	v_pk_add_f32 v[64:65], v[44:45], v[62:63]
	v_pk_add_f32 v[62:63], v[44:45], v[62:63] neg_lo:[0,1] neg_hi:[0,1]
	v_pk_add_f32 v[70:71], v[48:49], v[56:57] op_sel:[0,1] op_sel_hi:[1,0] neg_hi:[0,1]
	v_pk_add_f32 v[56:57], v[48:49], v[56:57] op_sel:[0,1] op_sel_hi:[1,0] neg_lo:[0,1]
	v_pk_add_f32 v[44:45], v[50:51], v[66:67]
	v_pk_add_f32 v[48:49], v[50:51], v[66:67] neg_lo:[0,1] neg_hi:[0,1]
	v_pk_add_f32 v[50:51], v[58:59], v[74:75]
	v_pk_add_f32 v[58:59], v[58:59], v[74:75] neg_lo:[0,1] neg_hi:[0,1]
	v_pk_add_f32 v[66:67], v[44:45], v[50:51]
	v_pk_add_f32 v[72:73], v[44:45], v[50:51] neg_lo:[0,1] neg_hi:[0,1]
	v_pk_add_f32 v[50:51], v[48:49], v[58:59] op_sel:[0,1] op_sel_hi:[1,0] neg_hi:[0,1]
	v_pk_add_f32 v[58:59], v[48:49], v[58:59] op_sel:[0,1] op_sel_hi:[1,0] neg_lo:[0,1]
	v_pk_mul_f32 v[44:45], v[42:43], s[20:21] op_sel:[0,0] op_sel_hi:[0,1]
	v_pk_fma_f32 v[74:75], v[42:43], s[20:21], v[44:45] op_sel:[1,1,0] op_sel_hi:[1,0,1] neg_lo:[0,1,0]
	v_pk_mul_f32 v[42:43], v[70:71], s[46:47] op_sel:[0,0] op_sel_hi:[0,1]
	s_barrier
	v_pk_fma_f32 v[70:71], v[70:71], s[46:47], v[42:43] op_sel:[1,1,0] op_sel_hi:[1,0,1] neg_lo:[0,1,0]
	s_waitcnt vmcnt(5)
	v_pk_mul_f32 v[80:81], v[50:51], s[50:51] op_sel:[0,0] op_sel_hi:[0,1]
	v_pk_fma_f32 v[80:81], v[50:51], s[50:51], v[80:81] op_sel:[1,1,0] op_sel_hi:[1,0,1] neg_lo:[0,1,0]
	v_pk_mul_f32 v[50:51], v[46:47], s[46:47] op_sel:[0,0] op_sel_hi:[0,1]
	s_lshl_b64 s[0:1], s[70:71], 14
	v_pk_fma_f32 v[82:83], v[46:47], s[46:47], v[50:51] op_sel:[1,1,0] op_sel_hi:[1,0,1] neg_lo:[0,1,0]
	v_pk_mul_f32 v[46:47], v[62:63], s[8:9] op_sel:[0,0] op_sel_hi:[0,1]
	s_add_u32 s0, s96, s0
	v_pk_fma_f32 v[62:63], v[62:63], s[8:9], v[46:47] op_sel:[1,1,0] op_sel_hi:[1,0,1] neg_lo:[0,1,0]
	s_waitcnt vmcnt(4)
	v_pk_mul_f32 v[84:85], v[72:73], s[54:55] op_sel:[0,0] op_sel_hi:[0,1]
	v_lshlrev_b32_e32 v34, 14, v133
	v_pk_fma_f32 v[72:73], v[72:73], s[54:55], v[84:85] op_sel:[1,1,0] op_sel_hi:[1,0,1] neg_lo:[0,1,0]
	v_pk_mul_f32 v[84:85], v[52:53], s[50:51] op_sel:[0,0] op_sel_hi:[0,1]
	s_addc_u32 s1, s97, s1
	v_pk_fma_f32 v[84:85], v[52:53], s[50:51], v[84:85] op_sel:[1,1,0] op_sel_hi:[1,0,1] neg_lo:[0,1,0]
	v_pk_mul_f32 v[52:53], v[56:57], s[54:55] op_sel:[0,0] op_sel_hi:[0,1]
	v_and_b32_e32 v139, 0xffc00000, v34
	v_pk_fma_f32 v[56:57], v[56:57], s[54:55], v[52:53] op_sel:[1,1,0] op_sel_hi:[1,0,1] neg_lo:[0,1,0]
	v_pk_mul_f32 v[86:87], v[58:59], s[56:57] op_sel:[0,0] op_sel_hi:[0,1]
	s_add_u32 s0, s0, 0x2000000
	v_pk_fma_f32 v[58:59], v[58:59], s[56:57], v[86:87] op_sel:[1,1,0] op_sel_hi:[1,0,1] neg_lo:[0,1,0]
	v_pk_add_f32 v[86:87], v[68:69], v[64:65]
	v_pk_add_f32 v[64:65], v[68:69], v[64:65] neg_lo:[0,1] neg_hi:[0,1]
	v_pk_add_f32 v[68:69], v[54:55], v[66:67]
	v_pk_add_f32 v[54:55], v[54:55], v[66:67] neg_lo:[0,1] neg_hi:[0,1]
	v_pk_add_f32 v[66:67], v[86:87], v[68:69]
	v_pk_add_f32 v[68:69], v[86:87], v[68:69] neg_lo:[0,1] neg_hi:[0,1]
	v_pk_add_f32 v[86:87], v[64:65], v[54:55] op_sel:[0,1] op_sel_hi:[1,0] neg_hi:[0,1]
	v_pk_add_f32 v[54:55], v[64:65], v[54:55] op_sel:[0,1] op_sel_hi:[1,0] neg_lo:[0,1]
	v_pk_add_f32 v[64:65], v[76:77], v[70:71]
	v_pk_add_f32 v[70:71], v[76:77], v[70:71] neg_lo:[0,1] neg_hi:[0,1]
	v_pk_add_f32 v[76:77], v[74:75], v[80:81]
	v_pk_add_f32 v[74:75], v[74:75], v[80:81] neg_lo:[0,1] neg_hi:[0,1]
	v_pk_add_f32 v[80:81], v[64:65], v[76:77]
	v_pk_add_f32 v[64:65], v[64:65], v[76:77] neg_lo:[0,1] neg_hi:[0,1]
	v_pk_add_f32 v[76:77], v[70:71], v[74:75] op_sel:[0,1] op_sel_hi:[1,0] neg_hi:[0,1]
	v_pk_add_f32 v[70:71], v[70:71], v[74:75] op_sel:[0,1] op_sel_hi:[1,0] neg_lo:[0,1]
	v_pk_add_f32 v[74:75], v[60:61], v[62:63]
	v_pk_add_f32 v[60:61], v[60:61], v[62:63] neg_lo:[0,1] neg_hi:[0,1]
	v_pk_add_f32 v[62:63], v[82:83], v[72:73]
	v_pk_add_f32 v[72:73], v[82:83], v[72:73] neg_lo:[0,1] neg_hi:[0,1]
	v_pk_add_f32 v[82:83], v[74:75], v[62:63]
	v_pk_add_f32 v[62:63], v[74:75], v[62:63] neg_lo:[0,1] neg_hi:[0,1]
	v_pk_add_f32 v[74:75], v[60:61], v[72:73] op_sel:[0,1] op_sel_hi:[1,0] neg_hi:[0,1]
	v_pk_add_f32 v[60:61], v[60:61], v[72:73] op_sel:[0,1] op_sel_hi:[1,0] neg_lo:[0,1]
	v_pk_add_f32 v[72:73], v[78:79], v[56:57]
	v_pk_add_f32 v[56:57], v[78:79], v[56:57] neg_lo:[0,1] neg_hi:[0,1]
	v_pk_add_f32 v[78:79], v[84:85], v[58:59]
	v_pk_add_f32 v[58:59], v[84:85], v[58:59] neg_lo:[0,1] neg_hi:[0,1]
	v_pk_add_f32 v[84:85], v[72:73], v[78:79]
	v_pk_add_f32 v[72:73], v[72:73], v[78:79] neg_lo:[0,1] neg_hi:[0,1]
	v_pk_add_f32 v[78:79], v[56:57], v[58:59] op_sel:[0,1] op_sel_hi:[1,0] neg_hi:[0,1]
	v_pk_add_f32 v[56:57], v[56:57], v[58:59] op_sel:[0,1] op_sel_hi:[1,0] neg_lo:[0,1]
	v_xor_b32_e32 v59, 0x80000000, v39
	v_mov_b32_e32 v58, v38
	ds_write_b64 v132, v[66:67]
	v_pk_mul_f32 v[66:67], v[80:81], v[58:59] op_sel:[0,0] op_sel_hi:[0,1]
	s_addc_u32 s1, s1, 0
	v_pk_fma_f32 v[66:67], v[80:81], v[58:59], v[66:67] op_sel:[1,1,0] op_sel_hi:[1,0,1] neg_lo:[0,1,0]
	ds_write_b64 v132, v[66:67] offset:2176
	v_pk_mul_f32 v[66:67], v[58:59], v[58:59] op_sel:[0,0] op_sel_hi:[0,1]
	v_pk_fma_f32 v[66:67], v[58:59], v[58:59], v[66:67] op_sel:[1,1,0] op_sel_hi:[1,0,1] neg_lo:[0,1,0]
	v_pk_mul_f32 v[80:81], v[82:83], v[66:67] op_sel:[0,0] op_sel_hi:[0,1]
	v_pk_fma_f32 v[80:81], v[82:83], v[66:67], v[80:81] op_sel:[1,1,0] op_sel_hi:[1,0,1] neg_lo:[0,1,0]
	ds_write_b64 v132, v[80:81] offset:4352
	v_pk_mul_f32 v[80:81], v[66:67], v[58:59] op_sel:[0,0] op_sel_hi:[0,1]
	v_pk_fma_f32 v[66:67], v[66:67], v[58:59], v[80:81] op_sel:[1,1,0] op_sel_hi:[1,0,1] neg_lo:[0,1,0]
	v_pk_mul_f32 v[80:81], v[84:85], v[66:67] op_sel:[0,0] op_sel_hi:[0,1]
	v_pk_fma_f32 v[80:81], v[84:85], v[66:67], v[80:81] op_sel:[1,1,0] op_sel_hi:[1,0,1] neg_lo:[0,1,0]
	ds_write_b64 v132, v[80:81] offset:6528
	v_pk_mul_f32 v[80:81], v[66:67], v[58:59] op_sel:[0,0] op_sel_hi:[0,1]
	v_pk_fma_f32 v[66:67], v[66:67], v[58:59], v[80:81] op_sel:[1,1,0] op_sel_hi:[1,0,1] neg_lo:[0,1,0]
	v_pk_mul_f32 v[80:81], v[86:87], v[66:67] op_sel:[0,0] op_sel_hi:[0,1]
	v_pk_fma_f32 v[80:81], v[86:87], v[66:67], v[80:81] op_sel:[1,1,0] op_sel_hi:[1,0,1] neg_lo:[0,1,0]
	ds_write_b64 v132, v[80:81] offset:8704
	v_pk_mul_f32 v[80:81], v[66:67], v[58:59] op_sel:[0,0] op_sel_hi:[0,1]
	v_pk_fma_f32 v[66:67], v[66:67], v[58:59], v[80:81] op_sel:[1,1,0] op_sel_hi:[1,0,1] neg_lo:[0,1,0]
	v_pk_mul_f32 v[80:81], v[76:77], v[66:67] op_sel:[0,0] op_sel_hi:[0,1]
	v_pk_fma_f32 v[76:77], v[76:77], v[66:67], v[80:81] op_sel:[1,1,0] op_sel_hi:[1,0,1] neg_lo:[0,1,0]
	ds_write_b64 v132, v[76:77] offset:10880
	v_pk_mul_f32 v[76:77], v[66:67], v[58:59] op_sel:[0,0] op_sel_hi:[0,1]
	v_pk_fma_f32 v[66:67], v[66:67], v[58:59], v[76:77] op_sel:[1,1,0] op_sel_hi:[1,0,1] neg_lo:[0,1,0]
	v_pk_mul_f32 v[76:77], v[74:75], v[66:67] op_sel:[0,0] op_sel_hi:[0,1]
	v_pk_fma_f32 v[74:75], v[74:75], v[66:67], v[76:77] op_sel:[1,1,0] op_sel_hi:[1,0,1] neg_lo:[0,1,0]
	ds_write_b64 v132, v[74:75] offset:13056
	v_pk_mul_f32 v[74:75], v[66:67], v[58:59] op_sel:[0,0] op_sel_hi:[0,1]
	v_pk_fma_f32 v[66:67], v[66:67], v[58:59], v[74:75] op_sel:[1,1,0] op_sel_hi:[1,0,1] neg_lo:[0,1,0]
	v_pk_mul_f32 v[74:75], v[78:79], v[66:67] op_sel:[0,0] op_sel_hi:[0,1]
	v_pk_fma_f32 v[74:75], v[78:79], v[66:67], v[74:75] op_sel:[1,1,0] op_sel_hi:[1,0,1] neg_lo:[0,1,0]
	ds_write_b64 v132, v[74:75] offset:15232
	v_pk_mul_f32 v[74:75], v[66:67], v[58:59] op_sel:[0,0] op_sel_hi:[0,1]
	v_pk_fma_f32 v[66:67], v[66:67], v[58:59], v[74:75] op_sel:[1,1,0] op_sel_hi:[1,0,1] neg_lo:[0,1,0]
	v_pk_mul_f32 v[74:75], v[68:69], v[66:67] op_sel:[0,0] op_sel_hi:[0,1]
	v_pk_fma_f32 v[68:69], v[68:69], v[66:67], v[74:75] op_sel:[1,1,0] op_sel_hi:[1,0,1] neg_lo:[0,1,0]
	ds_write_b64 v132, v[68:69] offset:17408
	v_pk_mul_f32 v[68:69], v[66:67], v[58:59] op_sel:[0,0] op_sel_hi:[0,1]
	v_pk_fma_f32 v[66:67], v[66:67], v[58:59], v[68:69] op_sel:[1,1,0] op_sel_hi:[1,0,1] neg_lo:[0,1,0]
	v_pk_mul_f32 v[68:69], v[64:65], v[66:67] op_sel:[0,0] op_sel_hi:[0,1]
	v_pk_fma_f32 v[64:65], v[64:65], v[66:67], v[68:69] op_sel:[1,1,0] op_sel_hi:[1,0,1] neg_lo:[0,1,0]
	ds_write_b64 v132, v[64:65] offset:19584
	v_pk_mul_f32 v[64:65], v[66:67], v[58:59] op_sel:[0,0] op_sel_hi:[0,1]
	v_pk_fma_f32 v[64:65], v[66:67], v[58:59], v[64:65] op_sel:[1,1,0] op_sel_hi:[1,0,1] neg_lo:[0,1,0]
	v_pk_mul_f32 v[66:67], v[62:63], v[64:65] op_sel:[0,0] op_sel_hi:[0,1]
	v_pk_fma_f32 v[62:63], v[62:63], v[64:65], v[66:67] op_sel:[1,1,0] op_sel_hi:[1,0,1] neg_lo:[0,1,0]
	ds_write_b64 v132, v[62:63] offset:21760
	v_pk_mul_f32 v[62:63], v[64:65], v[58:59] op_sel:[0,0] op_sel_hi:[0,1]
	v_pk_fma_f32 v[62:63], v[64:65], v[58:59], v[62:63] op_sel:[1,1,0] op_sel_hi:[1,0,1] neg_lo:[0,1,0]
	v_pk_mul_f32 v[64:65], v[72:73], v[62:63] op_sel:[0,0] op_sel_hi:[0,1]
	v_pk_fma_f32 v[64:65], v[72:73], v[62:63], v[64:65] op_sel:[1,1,0] op_sel_hi:[1,0,1] neg_lo:[0,1,0]
	ds_write_b64 v132, v[64:65] offset:23936
	v_pk_mul_f32 v[64:65], v[62:63], v[58:59] op_sel:[0,0] op_sel_hi:[0,1]
	v_pk_fma_f32 v[62:63], v[62:63], v[58:59], v[64:65] op_sel:[1,1,0] op_sel_hi:[1,0,1] neg_lo:[0,1,0]
	v_pk_mul_f32 v[64:65], v[54:55], v[62:63] op_sel:[0,0] op_sel_hi:[0,1]
	v_pk_fma_f32 v[54:55], v[54:55], v[62:63], v[64:65] op_sel:[1,1,0] op_sel_hi:[1,0,1] neg_lo:[0,1,0]
	ds_write_b64 v132, v[54:55] offset:26112
	v_pk_mul_f32 v[54:55], v[62:63], v[58:59] op_sel:[0,0] op_sel_hi:[0,1]
	v_pk_fma_f32 v[54:55], v[62:63], v[58:59], v[54:55] op_sel:[1,1,0] op_sel_hi:[1,0,1] neg_lo:[0,1,0]
	v_pk_mul_f32 v[62:63], v[70:71], v[54:55] op_sel:[0,0] op_sel_hi:[0,1]
	v_pk_fma_f32 v[62:63], v[70:71], v[54:55], v[62:63] op_sel:[1,1,0] op_sel_hi:[1,0,1] neg_lo:[0,1,0]
	ds_write_b64 v132, v[62:63] offset:28288
	v_pk_mul_f32 v[62:63], v[54:55], v[58:59] op_sel:[0,0] op_sel_hi:[0,1]
	v_pk_fma_f32 v[54:55], v[54:55], v[58:59], v[62:63] op_sel:[1,1,0] op_sel_hi:[1,0,1] neg_lo:[0,1,0]
	v_pk_mul_f32 v[62:63], v[60:61], v[54:55] op_sel:[0,0] op_sel_hi:[0,1]
	v_pk_fma_f32 v[60:61], v[60:61], v[54:55], v[62:63] op_sel:[1,1,0] op_sel_hi:[1,0,1] neg_lo:[0,1,0]
	ds_write_b64 v132, v[60:61] offset:30464
	v_pk_mul_f32 v[60:61], v[54:55], v[58:59] op_sel:[0,0] op_sel_hi:[0,1]
	v_pk_fma_f32 v[54:55], v[54:55], v[58:59], v[60:61] op_sel:[1,1,0] op_sel_hi:[1,0,1] neg_lo:[0,1,0]
	v_pk_mul_f32 v[58:59], v[56:57], v[54:55] op_sel:[0,0] op_sel_hi:[0,1]
	v_pk_fma_f32 v[54:55], v[56:57], v[54:55], v[58:59] op_sel:[1,1,0] op_sel_hi:[1,0,1] neg_lo:[0,1,0]
	ds_write_b64 v132, v[54:55] offset:32640
	s_waitcnt lgkmcnt(0)
	s_barrier
	ds_read2_b64 v[54:57], v134 offset1:17
	ds_read2_b64 v[58:61], v134 offset0:34 offset1:51
	ds_read2_b64 v[62:65], v134 offset0:68 offset1:85
	ds_read2_b64 v[66:69], v134 offset0:136 offset1:153
	ds_read2_b64 v[70:73], v134 offset0:102 offset1:119
	ds_read2_b64 v[74:77], v134 offset0:204 offset1:221
	ds_read2_b64 v[78:81], v134 offset0:170 offset1:187
	ds_read2_b64 v[82:85], v134 offset0:238 offset1:255
	s_waitcnt lgkmcnt(4)
	v_pk_add_f32 v[86:87], v[54:55], v[66:67]
	v_pk_add_f32 v[54:55], v[54:55], v[66:67] neg_lo:[0,1] neg_hi:[0,1]
	s_waitcnt lgkmcnt(2)
	v_pk_add_f32 v[66:67], v[62:63], v[74:75]
	v_pk_add_f32 v[62:63], v[62:63], v[74:75] neg_lo:[0,1] neg_hi:[0,1]
	v_pk_add_f32 v[74:75], v[86:87], v[66:67]
	v_pk_add_f32 v[66:67], v[86:87], v[66:67] neg_lo:[0,1] neg_hi:[0,1]
	v_pk_add_f32 v[86:87], v[54:55], v[62:63] op_sel:[0,1] op_sel_hi:[1,0] neg_hi:[0,1]
	v_pk_add_f32 v[54:55], v[54:55], v[62:63] op_sel:[0,1] op_sel_hi:[1,0] neg_lo:[0,1]
	v_pk_add_f32 v[62:63], v[56:57], v[68:69]
	v_pk_add_f32 v[56:57], v[56:57], v[68:69] neg_lo:[0,1] neg_hi:[0,1]
	v_pk_add_f32 v[68:69], v[64:65], v[76:77]
	v_pk_add_f32 v[64:65], v[64:65], v[76:77] neg_lo:[0,1] neg_hi:[0,1]
	v_pk_add_f32 v[76:77], v[62:63], v[68:69]
	v_pk_add_f32 v[62:63], v[62:63], v[68:69] neg_lo:[0,1] neg_hi:[0,1]
	v_pk_add_f32 v[68:69], v[56:57], v[64:65] op_sel:[0,1] op_sel_hi:[1,0] neg_hi:[0,1]
	v_pk_add_f32 v[56:57], v[56:57], v[64:65] op_sel:[0,1] op_sel_hi:[1,0] neg_lo:[0,1]
	s_waitcnt lgkmcnt(1)
	v_pk_add_f32 v[64:65], v[58:59], v[78:79]
	v_pk_add_f32 v[58:59], v[58:59], v[78:79] neg_lo:[0,1] neg_hi:[0,1]
	s_waitcnt lgkmcnt(0)
	v_pk_add_f32 v[78:79], v[70:71], v[82:83]
	v_pk_add_f32 v[70:71], v[70:71], v[82:83] neg_lo:[0,1] neg_hi:[0,1]
	v_pk_add_f32 v[82:83], v[64:65], v[78:79]
	v_pk_add_f32 v[64:65], v[64:65], v[78:79] neg_lo:[0,1] neg_hi:[0,1]
	v_pk_add_f32 v[78:79], v[58:59], v[70:71] op_sel:[0,1] op_sel_hi:[1,0] neg_hi:[0,1]
	v_pk_add_f32 v[58:59], v[58:59], v[70:71] op_sel:[0,1] op_sel_hi:[1,0] neg_lo:[0,1]
	v_pk_add_f32 v[70:71], v[60:61], v[80:81]
	v_pk_add_f32 v[60:61], v[60:61], v[80:81] neg_lo:[0,1] neg_hi:[0,1]
	v_pk_add_f32 v[80:81], v[72:73], v[84:85]
	v_pk_add_f32 v[72:73], v[72:73], v[84:85] neg_lo:[0,1] neg_hi:[0,1]
	v_pk_add_f32 v[84:85], v[70:71], v[80:81]
	v_pk_add_f32 v[70:71], v[70:71], v[80:81] neg_lo:[0,1] neg_hi:[0,1]
	v_pk_add_f32 v[80:81], v[60:61], v[72:73] op_sel:[0,1] op_sel_hi:[1,0] neg_hi:[0,1]
	v_pk_add_f32 v[60:61], v[60:61], v[72:73] op_sel:[0,1] op_sel_hi:[1,0] neg_lo:[0,1]
	v_pk_mul_f32 v[72:73], v[68:69], s[20:21] op_sel:[0,0] op_sel_hi:[0,1]
	v_pk_fma_f32 v[68:69], v[68:69], s[20:21], v[72:73] op_sel:[1,1,0] op_sel_hi:[1,0,1] neg_lo:[0,1,0]
	v_pk_mul_f32 v[72:73], v[78:79], s[46:47] op_sel:[0,0] op_sel_hi:[0,1]
	v_pk_fma_f32 v[72:73], v[78:79], s[46:47], v[72:73] op_sel:[1,1,0] op_sel_hi:[1,0,1] neg_lo:[0,1,0]
	v_pk_mul_f32 v[78:79], v[80:81], s[50:51] op_sel:[0,0] op_sel_hi:[0,1]
	v_pk_fma_f32 v[78:79], v[80:81], s[50:51], v[78:79] op_sel:[1,1,0] op_sel_hi:[1,0,1] neg_lo:[0,1,0]
	v_pk_mul_f32 v[80:81], v[62:63], s[46:47] op_sel:[0,0] op_sel_hi:[0,1]
	v_pk_fma_f32 v[62:63], v[62:63], s[46:47], v[80:81] op_sel:[1,1,0] op_sel_hi:[1,0,1] neg_lo:[0,1,0]
	v_pk_mul_f32 v[80:81], v[64:65], s[8:9] op_sel:[0,0] op_sel_hi:[0,1]
	v_pk_fma_f32 v[64:65], v[64:65], s[8:9], v[80:81] op_sel:[1,1,0] op_sel_hi:[1,0,1] neg_lo:[0,1,0]
	v_pk_mul_f32 v[80:81], v[70:71], s[54:55] op_sel:[0,0] op_sel_hi:[0,1]
	v_pk_fma_f32 v[70:71], v[70:71], s[54:55], v[80:81] op_sel:[1,1,0] op_sel_hi:[1,0,1] neg_lo:[0,1,0]
	v_pk_mul_f32 v[80:81], v[56:57], s[50:51] op_sel:[0,0] op_sel_hi:[0,1]
	v_pk_fma_f32 v[56:57], v[56:57], s[50:51], v[80:81] op_sel:[1,1,0] op_sel_hi:[1,0,1] neg_lo:[0,1,0]
	v_pk_mul_f32 v[80:81], v[58:59], s[54:55] op_sel:[0,0] op_sel_hi:[0,1]
	v_pk_fma_f32 v[58:59], v[58:59], s[54:55], v[80:81] op_sel:[1,1,0] op_sel_hi:[1,0,1] neg_lo:[0,1,0]
	v_pk_mul_f32 v[80:81], v[60:61], s[56:57] op_sel:[0,0] op_sel_hi:[0,1]
	v_pk_fma_f32 v[60:61], v[60:61], s[56:57], v[80:81] op_sel:[1,1,0] op_sel_hi:[1,0,1] neg_lo:[0,1,0]
	v_pk_add_f32 v[80:81], v[74:75], v[82:83]
	v_pk_add_f32 v[74:75], v[74:75], v[82:83] neg_lo:[0,1] neg_hi:[0,1]
	v_pk_add_f32 v[82:83], v[76:77], v[84:85]
	v_pk_add_f32 v[76:77], v[76:77], v[84:85] neg_lo:[0,1] neg_hi:[0,1]
	v_pk_add_f32 v[84:85], v[80:81], v[82:83]
	v_pk_add_f32 v[80:81], v[80:81], v[82:83] neg_lo:[0,1] neg_hi:[0,1]
	v_pk_add_f32 v[82:83], v[74:75], v[76:77] op_sel:[0,1] op_sel_hi:[1,0] neg_hi:[0,1]
	v_pk_add_f32 v[74:75], v[74:75], v[76:77] op_sel:[0,1] op_sel_hi:[1,0] neg_lo:[0,1]
	v_pk_add_f32 v[76:77], v[86:87], v[72:73]
	v_pk_add_f32 v[72:73], v[86:87], v[72:73] neg_lo:[0,1] neg_hi:[0,1]
	v_pk_add_f32 v[86:87], v[68:69], v[78:79]
	v_pk_add_f32 v[68:69], v[68:69], v[78:79] neg_lo:[0,1] neg_hi:[0,1]
	v_pk_add_f32 v[78:79], v[76:77], v[86:87]
	v_pk_add_f32 v[76:77], v[76:77], v[86:87] neg_lo:[0,1] neg_hi:[0,1]
	v_pk_add_f32 v[86:87], v[72:73], v[68:69] op_sel:[0,1] op_sel_hi:[1,0] neg_hi:[0,1]
	v_pk_add_f32 v[68:69], v[72:73], v[68:69] op_sel:[0,1] op_sel_hi:[1,0] neg_lo:[0,1]
	v_pk_add_f32 v[72:73], v[66:67], v[64:65]
	v_pk_add_f32 v[64:65], v[66:67], v[64:65] neg_lo:[0,1] neg_hi:[0,1]
	v_pk_add_f32 v[66:67], v[62:63], v[70:71]
	v_pk_add_f32 v[62:63], v[62:63], v[70:71] neg_lo:[0,1] neg_hi:[0,1]
	v_pk_add_f32 v[70:71], v[72:73], v[66:67]
	v_pk_add_f32 v[66:67], v[72:73], v[66:67] neg_lo:[0,1] neg_hi:[0,1]
	v_pk_add_f32 v[72:73], v[64:65], v[62:63] op_sel:[0,1] op_sel_hi:[1,0] neg_hi:[0,1]
	v_pk_add_f32 v[62:63], v[64:65], v[62:63] op_sel:[0,1] op_sel_hi:[1,0] neg_lo:[0,1]
	v_pk_add_f32 v[64:65], v[54:55], v[58:59]
	v_pk_add_f32 v[54:55], v[54:55], v[58:59] neg_lo:[0,1] neg_hi:[0,1]
	v_pk_add_f32 v[58:59], v[56:57], v[60:61]
	v_pk_add_f32 v[56:57], v[56:57], v[60:61] neg_lo:[0,1] neg_hi:[0,1]
	v_pk_add_f32 v[60:61], v[64:65], v[58:59]
	v_pk_add_f32 v[58:59], v[64:65], v[58:59] neg_lo:[0,1] neg_hi:[0,1]
	v_pk_add_f32 v[64:65], v[54:55], v[56:57] op_sel:[0,1] op_sel_hi:[1,0] neg_hi:[0,1]
	v_pk_add_f32 v[54:55], v[54:55], v[56:57] op_sel:[0,1] op_sel_hi:[1,0] neg_lo:[0,1]
	v_xor_b32_e32 v57, 0x80000000, v41
	v_mov_b32_e32 v56, v40
	s_waitcnt vmcnt(1)
	v_pk_mul_f32 v[88:89], v[78:79], v[56:57] op_sel:[0,0] op_sel_hi:[0,1]
	v_pk_fma_f32 v[78:79], v[78:79], v[56:57], v[88:89] op_sel:[1,1,0] op_sel_hi:[1,0,1] neg_lo:[0,1,0]
	ds_write2_b64 v134, v[84:85], v[78:79] offset1:17
	v_pk_mul_f32 v[78:79], v[56:57], v[56:57] op_sel:[0,0] op_sel_hi:[0,1]
	v_pk_fma_f32 v[78:79], v[56:57], v[56:57], v[78:79] op_sel:[1,1,0] op_sel_hi:[1,0,1] neg_lo:[0,1,0]
	v_pk_mul_f32 v[84:85], v[70:71], v[78:79] op_sel:[0,0] op_sel_hi:[0,1]
	v_pk_fma_f32 v[70:71], v[70:71], v[78:79], v[84:85] op_sel:[1,1,0] op_sel_hi:[1,0,1] neg_lo:[0,1,0]
	v_pk_mul_f32 v[84:85], v[78:79], v[56:57] op_sel:[0,0] op_sel_hi:[0,1]
	v_pk_fma_f32 v[78:79], v[78:79], v[56:57], v[84:85] op_sel:[1,1,0] op_sel_hi:[1,0,1] neg_lo:[0,1,0]
	v_pk_mul_f32 v[84:85], v[60:61], v[78:79] op_sel:[0,0] op_sel_hi:[0,1]
	v_pk_fma_f32 v[60:61], v[60:61], v[78:79], v[84:85] op_sel:[1,1,0] op_sel_hi:[1,0,1] neg_lo:[0,1,0]
	ds_write2_b64 v134, v[70:71], v[60:61] offset0:34 offset1:51
	v_pk_mul_f32 v[60:61], v[78:79], v[56:57] op_sel:[0,0] op_sel_hi:[0,1]
	v_pk_fma_f32 v[60:61], v[78:79], v[56:57], v[60:61] op_sel:[1,1,0] op_sel_hi:[1,0,1] neg_lo:[0,1,0]
	v_pk_mul_f32 v[70:71], v[82:83], v[60:61] op_sel:[0,0] op_sel_hi:[0,1]
	v_pk_mul_f32 v[78:79], v[60:61], v[56:57] op_sel:[0,0] op_sel_hi:[0,1]
	v_pk_fma_f32 v[70:71], v[82:83], v[60:61], v[70:71] op_sel:[1,1,0] op_sel_hi:[1,0,1] neg_lo:[0,1,0]
	v_pk_fma_f32 v[60:61], v[60:61], v[56:57], v[78:79] op_sel:[1,1,0] op_sel_hi:[1,0,1] neg_lo:[0,1,0]
	v_pk_mul_f32 v[78:79], v[86:87], v[60:61] op_sel:[0,0] op_sel_hi:[0,1]
	v_pk_fma_f32 v[78:79], v[86:87], v[60:61], v[78:79] op_sel:[1,1,0] op_sel_hi:[1,0,1] neg_lo:[0,1,0]
	ds_write2_b64 v134, v[70:71], v[78:79] offset0:68 offset1:85
	v_pk_mul_f32 v[70:71], v[60:61], v[56:57] op_sel:[0,0] op_sel_hi:[0,1]
	v_pk_fma_f32 v[60:61], v[60:61], v[56:57], v[70:71] op_sel:[1,1,0] op_sel_hi:[1,0,1] neg_lo:[0,1,0]
	v_pk_mul_f32 v[70:71], v[72:73], v[60:61] op_sel:[0,0] op_sel_hi:[0,1]
	v_pk_fma_f32 v[70:71], v[72:73], v[60:61], v[70:71] op_sel:[1,1,0] op_sel_hi:[1,0,1] neg_lo:[0,1,0]
	v_pk_mul_f32 v[72:73], v[60:61], v[56:57] op_sel:[0,0] op_sel_hi:[0,1]
	v_pk_fma_f32 v[60:61], v[60:61], v[56:57], v[72:73] op_sel:[1,1,0] op_sel_hi:[1,0,1] neg_lo:[0,1,0]
	v_pk_mul_f32 v[72:73], v[64:65], v[60:61] op_sel:[0,0] op_sel_hi:[0,1]
	v_pk_fma_f32 v[64:65], v[64:65], v[60:61], v[72:73] op_sel:[1,1,0] op_sel_hi:[1,0,1] neg_lo:[0,1,0]
	ds_write2_b64 v134, v[70:71], v[64:65] offset0:102 offset1:119
	v_pk_mul_f32 v[64:65], v[60:61], v[56:57] op_sel:[0,0] op_sel_hi:[0,1]
	v_pk_fma_f32 v[60:61], v[60:61], v[56:57], v[64:65] op_sel:[1,1,0] op_sel_hi:[1,0,1] neg_lo:[0,1,0]
	v_pk_mul_f32 v[64:65], v[80:81], v[60:61] op_sel:[0,0] op_sel_hi:[0,1]
	v_pk_mul_f32 v[70:71], v[60:61], v[56:57] op_sel:[0,0] op_sel_hi:[0,1]
	v_pk_fma_f32 v[64:65], v[80:81], v[60:61], v[64:65] op_sel:[1,1,0] op_sel_hi:[1,0,1] neg_lo:[0,1,0]
	v_pk_fma_f32 v[60:61], v[60:61], v[56:57], v[70:71] op_sel:[1,1,0] op_sel_hi:[1,0,1] neg_lo:[0,1,0]
	v_pk_mul_f32 v[70:71], v[76:77], v[60:61] op_sel:[0,0] op_sel_hi:[0,1]
	v_pk_fma_f32 v[70:71], v[76:77], v[60:61], v[70:71] op_sel:[1,1,0] op_sel_hi:[1,0,1] neg_lo:[0,1,0]
	ds_write2_b64 v134, v[64:65], v[70:71] offset0:136 offset1:153
	v_pk_mul_f32 v[64:65], v[60:61], v[56:57] op_sel:[0,0] op_sel_hi:[0,1]
	v_pk_fma_f32 v[60:61], v[60:61], v[56:57], v[64:65] op_sel:[1,1,0] op_sel_hi:[1,0,1] neg_lo:[0,1,0]
	v_pk_mul_f32 v[64:65], v[66:67], v[60:61] op_sel:[0,0] op_sel_hi:[0,1]
	v_pk_fma_f32 v[64:65], v[66:67], v[60:61], v[64:65] op_sel:[1,1,0] op_sel_hi:[1,0,1] neg_lo:[0,1,0]
	v_pk_mul_f32 v[66:67], v[60:61], v[56:57] op_sel:[0,0] op_sel_hi:[0,1]
	v_pk_fma_f32 v[60:61], v[60:61], v[56:57], v[66:67] op_sel:[1,1,0] op_sel_hi:[1,0,1] neg_lo:[0,1,0]
	v_pk_mul_f32 v[66:67], v[58:59], v[60:61] op_sel:[0,0] op_sel_hi:[0,1]
	v_pk_fma_f32 v[58:59], v[58:59], v[60:61], v[66:67] op_sel:[1,1,0] op_sel_hi:[1,0,1] neg_lo:[0,1,0]
	ds_write2_b64 v134, v[64:65], v[58:59] offset0:170 offset1:187
	v_pk_mul_f32 v[58:59], v[60:61], v[56:57] op_sel:[0,0] op_sel_hi:[0,1]
	v_pk_fma_f32 v[58:59], v[60:61], v[56:57], v[58:59] op_sel:[1,1,0] op_sel_hi:[1,0,1] neg_lo:[0,1,0]
	v_pk_mul_f32 v[60:61], v[74:75], v[58:59] op_sel:[0,0] op_sel_hi:[0,1]
	v_pk_mul_f32 v[64:65], v[58:59], v[56:57] op_sel:[0,0] op_sel_hi:[0,1]
	v_pk_fma_f32 v[60:61], v[74:75], v[58:59], v[60:61] op_sel:[1,1,0] op_sel_hi:[1,0,1] neg_lo:[0,1,0]
	v_pk_fma_f32 v[58:59], v[58:59], v[56:57], v[64:65] op_sel:[1,1,0] op_sel_hi:[1,0,1] neg_lo:[0,1,0]
	v_pk_mul_f32 v[64:65], v[68:69], v[58:59] op_sel:[0,0] op_sel_hi:[0,1]
	v_pk_fma_f32 v[64:65], v[68:69], v[58:59], v[64:65] op_sel:[1,1,0] op_sel_hi:[1,0,1] neg_lo:[0,1,0]
	ds_write2_b64 v134, v[60:61], v[64:65] offset0:204 offset1:221
	v_pk_mul_f32 v[60:61], v[58:59], v[56:57] op_sel:[0,0] op_sel_hi:[0,1]
	v_pk_fma_f32 v[58:59], v[58:59], v[56:57], v[60:61] op_sel:[1,1,0] op_sel_hi:[1,0,1] neg_lo:[0,1,0]
	v_pk_mul_f32 v[60:61], v[62:63], v[58:59] op_sel:[0,0] op_sel_hi:[0,1]
	v_pk_fma_f32 v[60:61], v[62:63], v[58:59], v[60:61] op_sel:[1,1,0] op_sel_hi:[1,0,1] neg_lo:[0,1,0]
	v_pk_mul_f32 v[62:63], v[58:59], v[56:57] op_sel:[0,0] op_sel_hi:[0,1]
	v_pk_fma_f32 v[56:57], v[58:59], v[56:57], v[62:63] op_sel:[1,1,0] op_sel_hi:[1,0,1] neg_lo:[0,1,0]
	v_pk_mul_f32 v[58:59], v[54:55], v[56:57] op_sel:[0,0] op_sel_hi:[0,1]
	v_pk_fma_f32 v[54:55], v[54:55], v[56:57], v[58:59] op_sel:[1,1,0] op_sel_hi:[1,0,1] neg_lo:[0,1,0]
	ds_write2_b64 v134, v[60:61], v[54:55] offset0:238 offset1:255
	s_waitcnt lgkmcnt(0)
	s_barrier
	ds_read2_b64 v[54:57], v135 offset1:1
	ds_read2_b64 v[58:61], v135 offset0:2 offset1:3
	ds_read2_b64 v[62:65], v135 offset0:8 offset1:9
	ds_read2_b64 v[66:69], v135 offset0:4 offset1:5
	ds_read2_b64 v[80:83], v135 offset0:6 offset1:7
	ds_read2_b64 v[76:79], v135 offset0:12 offset1:13
	ds_read2_b64 v[84:87], v135 offset0:10 offset1:11
	ds_read2_b64 v[88:91], v135 offset0:14 offset1:15
	s_waitcnt lgkmcnt(5)
	v_pk_add_f32 v[70:71], v[54:55], v[62:63]
	v_pk_add_f32 v[54:55], v[54:55], v[62:63] neg_lo:[0,1] neg_hi:[0,1]
	s_waitcnt lgkmcnt(2)
	v_pk_add_f32 v[62:63], v[66:67], v[76:77]
	v_pk_add_f32 v[66:67], v[66:67], v[76:77] neg_lo:[0,1] neg_hi:[0,1]
	v_pk_add_f32 v[76:77], v[70:71], v[62:63]
	v_pk_add_f32 v[70:71], v[70:71], v[62:63] neg_lo:[0,1] neg_hi:[0,1]
	v_pk_add_f32 v[74:75], v[54:55], v[66:67] op_sel:[0,1] op_sel_hi:[1,0] neg_hi:[0,1]
	v_pk_add_f32 v[72:73], v[54:55], v[66:67] op_sel:[0,1] op_sel_hi:[1,0] neg_lo:[0,1]
	v_pk_add_f32 v[54:55], v[56:57], v[64:65]
	v_pk_add_f32 v[56:57], v[56:57], v[64:65] neg_lo:[0,1] neg_hi:[0,1]
	v_pk_add_f32 v[62:63], v[68:69], v[78:79]
	v_pk_add_f32 v[64:65], v[68:69], v[78:79] neg_lo:[0,1] neg_hi:[0,1]
	v_pk_add_f32 v[78:79], v[54:55], v[62:63]
	v_pk_add_f32 v[54:55], v[54:55], v[62:63] neg_lo:[0,1] neg_hi:[0,1]
	v_pk_add_f32 v[62:63], v[56:57], v[64:65] op_sel:[0,1] op_sel_hi:[1,0] neg_hi:[0,1]
	v_pk_add_f32 v[56:57], v[56:57], v[64:65] op_sel:[0,1] op_sel_hi:[1,0] neg_lo:[0,1]
	s_waitcnt lgkmcnt(1)
	v_pk_add_f32 v[64:65], v[58:59], v[84:85]
	v_pk_add_f32 v[58:59], v[58:59], v[84:85] neg_lo:[0,1] neg_hi:[0,1]
	s_waitcnt lgkmcnt(0)
	v_pk_add_f32 v[66:67], v[80:81], v[88:89]
	v_pk_add_f32 v[68:69], v[80:81], v[88:89] neg_lo:[0,1] neg_hi:[0,1]
	v_pk_add_f32 v[80:81], v[64:65], v[66:67]
	v_pk_add_f32 v[64:65], v[64:65], v[66:67] neg_lo:[0,1] neg_hi:[0,1]
	v_pk_add_f32 v[66:67], v[58:59], v[68:69] op_sel:[0,1] op_sel_hi:[1,0] neg_hi:[0,1]
	v_pk_add_f32 v[58:59], v[58:59], v[68:69] op_sel:[0,1] op_sel_hi:[1,0] neg_lo:[0,1]
	v_pk_add_f32 v[68:69], v[60:61], v[86:87]
	v_pk_add_f32 v[84:85], v[82:83], v[90:91]
	v_pk_add_f32 v[60:61], v[60:61], v[86:87] neg_lo:[0,1] neg_hi:[0,1]
	v_pk_add_f32 v[86:87], v[82:83], v[90:91] neg_lo:[0,1] neg_hi:[0,1]
	v_pk_add_f32 v[82:83], v[68:69], v[84:85]
	v_pk_add_f32 v[68:69], v[68:69], v[84:85] neg_lo:[0,1] neg_hi:[0,1]
	v_pk_mul_f32 v[84:85], v[62:63], s[20:21] op_sel:[0,0] op_sel_hi:[0,1]
	v_pk_add_f32 v[88:89], v[60:61], v[86:87] op_sel:[0,1] op_sel_hi:[1,0] neg_hi:[0,1]
	v_pk_add_f32 v[60:61], v[60:61], v[86:87] op_sel:[0,1] op_sel_hi:[1,0] neg_lo:[0,1]
	v_pk_fma_f32 v[84:85], v[62:63], s[20:21], v[84:85] op_sel:[1,1,0] op_sel_hi:[1,0,1] neg_lo:[0,1,0]
	v_pk_mul_f32 v[48:49], v[66:67], s[46:47] op_sel:[0,0] op_sel_hi:[0,1]
	s_barrier
	v_pk_fma_f32 v[86:87], v[66:67], s[46:47], v[48:49] op_sel:[1,1,0] op_sel_hi:[1,0,1] neg_lo:[0,1,0]
	v_pk_mul_f32 v[48:49], v[88:89], s[50:51] op_sel:[0,0] op_sel_hi:[0,1]
	v_pk_fma_f32 v[90:91], v[88:89], s[50:51], v[48:49] op_sel:[1,1,0] op_sel_hi:[1,0,1] neg_lo:[0,1,0]
	v_pk_mul_f32 v[48:49], v[54:55], s[46:47] op_sel:[0,0] op_sel_hi:[0,1]
	v_pk_fma_f32 v[88:89], v[54:55], s[46:47], v[48:49] op_sel:[1,1,0] op_sel_hi:[1,0,1] neg_lo:[0,1,0]
	v_pk_mul_f32 v[44:45], v[64:65], s[8:9] op_sel:[0,0] op_sel_hi:[0,1]
	s_waitcnt vmcnt(0)
	v_pk_fma_f32 v[92:93], v[64:65], s[8:9], v[44:45] op_sel:[1,1,0] op_sel_hi:[1,0,1] neg_lo:[0,1,0]
	v_pk_mul_f32 v[44:45], v[68:69], s[54:55] op_sel:[0,0] op_sel_hi:[0,1]
	v_pk_fma_f32 v[96:97], v[68:69], s[54:55], v[44:45] op_sel:[1,1,0] op_sel_hi:[1,0,1] neg_lo:[0,1,0]
	v_pk_mul_f32 v[44:45], v[56:57], s[50:51] op_sel:[0,0] op_sel_hi:[0,1]
	v_pk_fma_f32 v[94:95], v[56:57], s[50:51], v[44:45] op_sel:[1,1,0] op_sel_hi:[1,0,1] neg_lo:[0,1,0]
	v_pk_mul_f32 v[42:43], v[58:59], s[54:55] op_sel:[0,0] op_sel_hi:[0,1]
	v_pk_add_f32 v[44:45], v[78:79], v[82:83] neg_lo:[0,1] neg_hi:[0,1]
	v_pk_fma_f32 v[100:101], v[58:59], s[54:55], v[42:43] op_sel:[1,1,0] op_sel_hi:[1,0,1] neg_lo:[0,1,0]
	v_pk_mul_f32 v[42:43], v[60:61], s[56:57] op_sel:[0,0] op_sel_hi:[0,1]
	v_pk_fma_f32 v[106:107], v[60:61], s[56:57], v[42:43] op_sel:[1,1,0] op_sel_hi:[1,0,1] neg_lo:[0,1,0]
	v_pk_add_f32 v[42:43], v[76:77], v[80:81] neg_lo:[0,1] neg_hi:[0,1]
	s_nop 0
	v_pk_add_f32 v[98:99], v[42:43], v[44:45] op_sel:[0,1] op_sel_hi:[1,0] neg_hi:[0,1]
	v_pk_add_f32 v[102:103], v[42:43], v[44:45] op_sel:[0,1] op_sel_hi:[1,0] neg_lo:[0,1]
	v_pk_add_f32 v[42:43], v[74:75], v[86:87] neg_lo:[0,1] neg_hi:[0,1]
	v_pk_add_f32 v[44:45], v[84:85], v[90:91] neg_lo:[0,1] neg_hi:[0,1]
	s_nop 0
	v_pk_add_f32 v[104:105], v[42:43], v[44:45] op_sel:[0,1] op_sel_hi:[1,0] neg_hi:[0,1]
	v_pk_add_f32 v[108:109], v[42:43], v[44:45] op_sel:[0,1] op_sel_hi:[1,0] neg_lo:[0,1]
	v_pk_add_f32 v[42:43], v[70:71], v[92:93] neg_lo:[0,1] neg_hi:[0,1]
	v_pk_add_f32 v[44:45], v[88:89], v[96:97] neg_lo:[0,1] neg_hi:[0,1]
	s_nop 0
	v_pk_add_f32 v[110:111], v[42:43], v[44:45] op_sel:[0,1] op_sel_hi:[1,0] neg_hi:[0,1]
	v_pk_add_f32 v[112:113], v[42:43], v[44:45] op_sel:[0,1] op_sel_hi:[1,0] neg_lo:[0,1]
	v_pk_add_f32 v[42:43], v[72:73], v[100:101] neg_lo:[0,1] neg_hi:[0,1]
	v_pk_add_f32 v[44:45], v[94:95], v[106:107] neg_lo:[0,1] neg_hi:[0,1]
	s_nop 0
	v_pk_add_f32 v[114:115], v[42:43], v[44:45] op_sel:[0,1] op_sel_hi:[1,0] neg_hi:[0,1]
	v_pk_add_f32 v[116:117], v[42:43], v[44:45] op_sel:[0,1] op_sel_hi:[1,0] neg_lo:[0,1]
	v_mov_b32_e32 v43, v126
	v_mov_b32_e32 v44, 0
	v_sub_u32_e32 v34, 0x1000, v43
	v_cndmask_b32_e64 v42, v34, v43, s[6:7]
	v_cmp_gt_i32_e32 vcc, s86, v42
	v_mov_b32_e32 v34, 0
	s_and_saveexec_b64 s[82:83], vcc
	s_cbranch_execz .LBB0_3365
	v_add_u32_e32 v46, v42, v139
	v_ashrrev_i32_e32 v47, 31, v46
	v_lshl_add_u64 v[46:47], v[46:47], 2, s[0:1]
	global_load_dword v34, v[46:47], off

.LBB0_3397:
	s_or_b64 exec, exec, s[0:1]
	s_addk_i32 s6, 0x800
	s_waitcnt lgkmcnt(0)
	ds_write_b64 v27, v[98:99]
	s_cmpk_lg_u32 s6, 0x8000
	v_add_u32_e32 v27, 0x880, v27
	v_pk_mul_f32 v[100:101], v[96:97], s[16:17] op_sel:[0,0] op_sel_hi:[0,1]
	v_pk_fma_f32 v[96:97], v[96:97], s[16:17], v[100:101] op_sel:[1,1,0] op_sel_hi:[1,0,1] neg_lo:[0,1,0]
	s_cbranch_scc0 .LBB0_3400

.LBB0_3400:
	ds_read_b64 v[96:97], v132
	ds_read_b64 v[98:99], v132 offset:2176
	ds_read_b64 v[100:101], v132 offset:4352
	ds_read_b64 v[102:103], v132 offset:6528
	ds_read_b64 v[104:105], v132 offset:8704
	ds_read_b64 v[106:107], v132 offset:10880
	ds_read_b64 v[110:111], v132 offset:13056
	ds_read_b64 v[112:113], v132 offset:15232
	ds_read_b64 v[114:115], v132 offset:17408
	ds_read_b64 v[116:117], v132 offset:19584
	ds_read_b64 v[140:141], v132 offset:21760
	ds_read_b64 v[142:143], v132 offset:23936
	ds_read_b64 v[144:145], v132 offset:26112
	ds_read_b64 v[146:147], v132 offset:28288
	ds_read_b64 v[148:149], v132 offset:30464
	ds_read_b64 v[150:151], v132 offset:32640
	s_waitcnt lgkmcnt(7)
	v_pk_add_f32 v[152:153], v[96:97], v[114:115]
	v_pk_add_f32 v[96:97], v[96:97], v[114:115] neg_lo:[0,1] neg_hi:[0,1]
	s_waitcnt lgkmcnt(3)
	v_pk_add_f32 v[114:115], v[104:105], v[144:145]
	v_pk_add_f32 v[104:105], v[104:105], v[144:145] neg_lo:[0,1] neg_hi:[0,1]
	v_pk_add_f32 v[144:145], v[152:153], v[114:115]
	v_pk_add_f32 v[114:115], v[152:153], v[114:115] neg_lo:[0,1] neg_hi:[0,1]
	v_pk_add_f32 v[152:153], v[96:97], v[104:105] op_sel:[0,1] op_sel_hi:[1,0] neg_hi:[0,1]
	v_pk_add_f32 v[154:155], v[96:97], v[104:105] op_sel:[0,1] op_sel_hi:[1,0] neg_lo:[0,1]
	v_pk_add_f32 v[96:97], v[98:99], v[116:117]
	v_pk_add_f32 v[98:99], v[98:99], v[116:117] neg_lo:[0,1] neg_hi:[0,1]
	s_waitcnt lgkmcnt(2)
	v_pk_add_f32 v[104:105], v[106:107], v[146:147]
	v_pk_add_f32 v[106:107], v[106:107], v[146:147] neg_lo:[0,1] neg_hi:[0,1]
	v_pk_add_f32 v[116:117], v[96:97], v[104:105]
	v_pk_add_f32 v[104:105], v[96:97], v[104:105] neg_lo:[0,1] neg_hi:[0,1]
	v_pk_add_f32 v[96:97], v[98:99], v[106:107] op_sel:[0,1] op_sel_hi:[1,0] neg_hi:[0,1]
	v_pk_add_f32 v[106:107], v[98:99], v[106:107] op_sel:[0,1] op_sel_hi:[1,0] neg_lo:[0,1]
	v_pk_add_f32 v[98:99], v[100:101], v[140:141]
	v_pk_add_f32 v[100:101], v[100:101], v[140:141] neg_lo:[0,1] neg_hi:[0,1]
	s_waitcnt lgkmcnt(1)
	v_pk_add_f32 v[140:141], v[110:111], v[148:149]
	v_pk_add_f32 v[110:111], v[110:111], v[148:149] neg_lo:[0,1] neg_hi:[0,1]
	v_pk_add_f32 v[146:147], v[98:99], v[140:141]
	v_pk_add_f32 v[140:141], v[98:99], v[140:141] neg_lo:[0,1] neg_hi:[0,1]
	v_pk_add_f32 v[148:149], v[100:101], v[110:111] op_sel:[0,1] op_sel_hi:[1,0] neg_hi:[0,1]
	v_pk_add_f32 v[110:111], v[100:101], v[110:111] op_sel:[0,1] op_sel_hi:[1,0] neg_lo:[0,1]
	v_pk_add_f32 v[98:99], v[102:103], v[142:143]
	v_pk_add_f32 v[100:101], v[102:103], v[142:143] neg_lo:[0,1] neg_hi:[0,1]
	s_waitcnt lgkmcnt(0)
	v_pk_add_f32 v[102:103], v[112:113], v[150:151]
	v_pk_add_f32 v[112:113], v[112:113], v[150:151] neg_lo:[0,1] neg_hi:[0,1]
	v_pk_add_f32 v[142:143], v[98:99], v[102:103]
	v_pk_add_f32 v[150:151], v[98:99], v[102:103] neg_lo:[0,1] neg_hi:[0,1]
	v_pk_mul_f32 v[98:99], v[96:97], s[20:21] op_sel:[0,0] op_sel_hi:[0,1]
	v_pk_add_f32 v[156:157], v[100:101], v[112:113] op_sel:[0,1] op_sel_hi:[1,0] neg_hi:[0,1]
	v_pk_add_f32 v[112:113], v[100:101], v[112:113] op_sel:[0,1] op_sel_hi:[1,0] neg_lo:[0,1]
	v_xor_b32_e32 v39, 0x80000000, v39
	v_pk_fma_f32 v[158:159], v[96:97], s[20:21], v[98:99] op_sel:[1,1,0] op_sel_hi:[1,0,1] neg_lo:[0,1,0]
	v_pk_mul_f32 v[96:97], v[148:149], s[46:47] op_sel:[0,0] op_sel_hi:[0,1]
	v_xor_b32_e32 v41, 0x80000000, v41
	v_pk_fma_f32 v[148:149], v[148:149], s[46:47], v[96:97] op_sel:[1,1,0] op_sel_hi:[1,0,1] neg_lo:[0,1,0]
	v_pk_mul_f32 v[100:101], v[156:157], s[50:51] op_sel:[0,0] op_sel_hi:[0,1]
	v_pk_fma_f32 v[156:157], v[156:157], s[50:51], v[100:101] op_sel:[1,1,0] op_sel_hi:[1,0,1] neg_lo:[0,1,0]
	v_pk_mul_f32 v[100:101], v[104:105], s[46:47] op_sel:[0,0] op_sel_hi:[0,1]
	v_pk_fma_f32 v[160:161], v[104:105], s[46:47], v[100:101] op_sel:[1,1,0] op_sel_hi:[1,0,1] neg_lo:[0,1,0]
	v_pk_mul_f32 v[100:101], v[140:141], s[8:9] op_sel:[0,0] op_sel_hi:[0,1]
	v_pk_fma_f32 v[140:141], v[140:141], s[8:9], v[100:101] op_sel:[1,1,0] op_sel_hi:[1,0,1] neg_lo:[0,1,0]
	v_pk_mul_f32 v[162:163], v[150:151], s[54:55] op_sel:[0,0] op_sel_hi:[0,1]
	v_pk_fma_f32 v[150:151], v[150:151], s[54:55], v[162:163] op_sel:[1,1,0] op_sel_hi:[1,0,1] neg_lo:[0,1,0]
	v_pk_mul_f32 v[162:163], v[106:107], s[50:51] op_sel:[0,0] op_sel_hi:[0,1]
	v_pk_fma_f32 v[162:163], v[106:107], s[50:51], v[162:163] op_sel:[1,1,0] op_sel_hi:[1,0,1] neg_lo:[0,1,0]
	v_pk_mul_f32 v[106:107], v[110:111], s[54:55] op_sel:[0,0] op_sel_hi:[0,1]
	v_pk_fma_f32 v[110:111], v[110:111], s[54:55], v[106:107] op_sel:[1,1,0] op_sel_hi:[1,0,1] neg_lo:[0,1,0]
	v_pk_mul_f32 v[164:165], v[112:113], s[56:57] op_sel:[0,0] op_sel_hi:[0,1]
	v_pk_fma_f32 v[112:113], v[112:113], s[56:57], v[164:165] op_sel:[1,1,0] op_sel_hi:[1,0,1] neg_lo:[0,1,0]
	v_pk_add_f32 v[164:165], v[144:145], v[146:147]
	v_pk_add_f32 v[144:145], v[144:145], v[146:147] neg_lo:[0,1] neg_hi:[0,1]
	v_pk_add_f32 v[146:147], v[116:117], v[142:143]
	v_pk_add_f32 v[116:117], v[116:117], v[142:143] neg_lo:[0,1] neg_hi:[0,1]
	v_pk_add_f32 v[142:143], v[164:165], v[146:147]
	v_pk_add_f32 v[146:147], v[164:165], v[146:147] neg_lo:[0,1] neg_hi:[0,1]
	v_pk_add_f32 v[164:165], v[144:145], v[116:117] op_sel:[0,1] op_sel_hi:[1,0] neg_hi:[0,1]
	v_pk_add_f32 v[116:117], v[144:145], v[116:117] op_sel:[0,1] op_sel_hi:[1,0] neg_lo:[0,1]
	v_pk_add_f32 v[144:145], v[152:153], v[148:149]
	v_pk_add_f32 v[148:149], v[152:153], v[148:149] neg_lo:[0,1] neg_hi:[0,1]
	v_pk_add_f32 v[152:153], v[158:159], v[156:157]
	v_pk_add_f32 v[156:157], v[158:159], v[156:157] neg_lo:[0,1] neg_hi:[0,1]
	v_pk_add_f32 v[158:159], v[144:145], v[152:153]
	v_pk_add_f32 v[144:145], v[144:145], v[152:153] neg_lo:[0,1] neg_hi:[0,1]
	v_pk_add_f32 v[152:153], v[148:149], v[156:157] op_sel:[0,1] op_sel_hi:[1,0] neg_hi:[0,1]
	v_pk_add_f32 v[148:149], v[148:149], v[156:157] op_sel:[0,1] op_sel_hi:[1,0] neg_lo:[0,1]
	v_pk_add_f32 v[156:157], v[114:115], v[140:141]
	v_pk_add_f32 v[114:115], v[114:115], v[140:141] neg_lo:[0,1] neg_hi:[0,1]
	v_pk_add_f32 v[140:141], v[160:161], v[150:151]
	v_pk_add_f32 v[150:151], v[160:161], v[150:151] neg_lo:[0,1] neg_hi:[0,1]
	v_pk_add_f32 v[160:161], v[156:157], v[140:141]
	v_pk_add_f32 v[140:141], v[156:157], v[140:141] neg_lo:[0,1] neg_hi:[0,1]
	v_pk_add_f32 v[156:157], v[114:115], v[150:151] op_sel:[0,1] op_sel_hi:[1,0] neg_hi:[0,1]
	v_pk_add_f32 v[114:115], v[114:115], v[150:151] op_sel:[0,1] op_sel_hi:[1,0] neg_lo:[0,1]
	v_pk_add_f32 v[150:151], v[154:155], v[110:111]
	v_pk_add_f32 v[110:111], v[154:155], v[110:111] neg_lo:[0,1] neg_hi:[0,1]
	v_pk_add_f32 v[154:155], v[162:163], v[112:113]
	v_pk_add_f32 v[112:113], v[162:163], v[112:113] neg_lo:[0,1] neg_hi:[0,1]
	v_pk_add_f32 v[162:163], v[150:151], v[154:155]
	v_pk_add_f32 v[150:151], v[150:151], v[154:155] neg_lo:[0,1] neg_hi:[0,1]
	v_pk_add_f32 v[154:155], v[110:111], v[112:113] op_sel:[0,1] op_sel_hi:[1,0] neg_hi:[0,1]
	v_pk_add_f32 v[110:111], v[110:111], v[112:113] op_sel:[0,1] op_sel_hi:[1,0] neg_lo:[0,1]
	v_mov_b32_e32 v113, v39
	v_mov_b32_e32 v112, v38
	ds_write_b64 v132, v[142:143]
	v_pk_mul_f32 v[142:143], v[158:159], v[112:113] op_sel:[0,0] op_sel_hi:[0,1]
	v_pk_fma_f32 v[142:143], v[158:159], v[112:113], v[142:143] op_sel:[1,1,0] op_sel_hi:[1,0,1] neg_lo:[0,1,0]
	ds_write_b64 v132, v[142:143] offset:2176
	v_pk_mul_f32 v[142:143], v[112:113], v[112:113] op_sel:[0,0] op_sel_hi:[0,1]
	v_pk_fma_f32 v[142:143], v[112:113], v[112:113], v[142:143] op_sel:[1,1,0] op_sel_hi:[1,0,1] neg_lo:[0,1,0]
	v_pk_mul_f32 v[158:159], v[160:161], v[142:143] op_sel:[0,0] op_sel_hi:[0,1]
	v_pk_fma_f32 v[158:159], v[160:161], v[142:143], v[158:159] op_sel:[1,1,0] op_sel_hi:[1,0,1] neg_lo:[0,1,0]
	ds_write_b64 v132, v[158:159] offset:4352
	v_pk_mul_f32 v[158:159], v[142:143], v[112:113] op_sel:[0,0] op_sel_hi:[0,1]
	v_pk_fma_f32 v[142:143], v[142:143], v[112:113], v[158:159] op_sel:[1,1,0] op_sel_hi:[1,0,1] neg_lo:[0,1,0]
	v_pk_mul_f32 v[158:159], v[162:163], v[142:143] op_sel:[0,0] op_sel_hi:[0,1]
	v_pk_fma_f32 v[158:159], v[162:163], v[142:143], v[158:159] op_sel:[1,1,0] op_sel_hi:[1,0,1] neg_lo:[0,1,0]
	ds_write_b64 v132, v[158:159] offset:6528
	v_pk_mul_f32 v[158:159], v[142:143], v[112:113] op_sel:[0,0] op_sel_hi:[0,1]
	v_pk_fma_f32 v[142:143], v[142:143], v[112:113], v[158:159] op_sel:[1,1,0] op_sel_hi:[1,0,1] neg_lo:[0,1,0]
	v_pk_mul_f32 v[158:159], v[164:165], v[142:143] op_sel:[0,0] op_sel_hi:[0,1]
	v_pk_fma_f32 v[158:159], v[164:165], v[142:143], v[158:159] op_sel:[1,1,0] op_sel_hi:[1,0,1] neg_lo:[0,1,0]
	ds_write_b64 v132, v[158:159] offset:8704
	v_pk_mul_f32 v[158:159], v[142:143], v[112:113] op_sel:[0,0] op_sel_hi:[0,1]
	v_pk_fma_f32 v[142:143], v[142:143], v[112:113], v[158:159] op_sel:[1,1,0] op_sel_hi:[1,0,1] neg_lo:[0,1,0]
	v_pk_mul_f32 v[158:159], v[152:153], v[142:143] op_sel:[0,0] op_sel_hi:[0,1]
	v_pk_fma_f32 v[152:153], v[152:153], v[142:143], v[158:159] op_sel:[1,1,0] op_sel_hi:[1,0,1] neg_lo:[0,1,0]
	ds_write_b64 v132, v[152:153] offset:10880
	v_pk_mul_f32 v[152:153], v[142:143], v[112:113] op_sel:[0,0] op_sel_hi:[0,1]
	v_pk_fma_f32 v[142:143], v[142:143], v[112:113], v[152:153] op_sel:[1,1,0] op_sel_hi:[1,0,1] neg_lo:[0,1,0]
	v_pk_mul_f32 v[152:153], v[156:157], v[142:143] op_sel:[0,0] op_sel_hi:[0,1]
	v_pk_fma_f32 v[152:153], v[156:157], v[142:143], v[152:153] op_sel:[1,1,0] op_sel_hi:[1,0,1] neg_lo:[0,1,0]
	ds_write_b64 v132, v[152:153] offset:13056
	v_pk_mul_f32 v[152:153], v[142:143], v[112:113] op_sel:[0,0] op_sel_hi:[0,1]
	v_pk_fma_f32 v[142:143], v[142:143], v[112:113], v[152:153] op_sel:[1,1,0] op_sel_hi:[1,0,1] neg_lo:[0,1,0]
	v_pk_mul_f32 v[152:153], v[154:155], v[142:143] op_sel:[0,0] op_sel_hi:[0,1]
	v_pk_fma_f32 v[152:153], v[154:155], v[142:143], v[152:153] op_sel:[1,1,0] op_sel_hi:[1,0,1] neg_lo:[0,1,0]
	ds_write_b64 v132, v[152:153] offset:15232
	v_pk_mul_f32 v[152:153], v[142:143], v[112:113] op_sel:[0,0] op_sel_hi:[0,1]
	v_pk_fma_f32 v[142:143], v[142:143], v[112:113], v[152:153] op_sel:[1,1,0] op_sel_hi:[1,0,1] neg_lo:[0,1,0]
	v_pk_mul_f32 v[152:153], v[146:147], v[142:143] op_sel:[0,0] op_sel_hi:[0,1]
	v_pk_fma_f32 v[146:147], v[146:147], v[142:143], v[152:153] op_sel:[1,1,0] op_sel_hi:[1,0,1] neg_lo:[0,1,0]
	ds_write_b64 v132, v[146:147] offset:17408
	v_pk_mul_f32 v[146:147], v[142:143], v[112:113] op_sel:[0,0] op_sel_hi:[0,1]
	v_pk_fma_f32 v[142:143], v[142:143], v[112:113], v[146:147] op_sel:[1,1,0] op_sel_hi:[1,0,1] neg_lo:[0,1,0]
	v_pk_mul_f32 v[146:147], v[144:145], v[142:143] op_sel:[0,0] op_sel_hi:[0,1]
	v_pk_fma_f32 v[144:145], v[144:145], v[142:143], v[146:147] op_sel:[1,1,0] op_sel_hi:[1,0,1] neg_lo:[0,1,0]
	ds_write_b64 v132, v[144:145] offset:19584
	v_pk_mul_f32 v[144:145], v[142:143], v[112:113] op_sel:[0,0] op_sel_hi:[0,1]
	v_pk_fma_f32 v[142:143], v[142:143], v[112:113], v[144:145] op_sel:[1,1,0] op_sel_hi:[1,0,1] neg_lo:[0,1,0]
	v_pk_mul_f32 v[144:145], v[140:141], v[142:143] op_sel:[0,0] op_sel_hi:[0,1]
	v_pk_fma_f32 v[140:141], v[140:141], v[142:143], v[144:145] op_sel:[1,1,0] op_sel_hi:[1,0,1] neg_lo:[0,1,0]
	ds_write_b64 v132, v[140:141] offset:21760
	v_pk_mul_f32 v[140:141], v[142:143], v[112:113] op_sel:[0,0] op_sel_hi:[0,1]
	v_pk_fma_f32 v[140:141], v[142:143], v[112:113], v[140:141] op_sel:[1,1,0] op_sel_hi:[1,0,1] neg_lo:[0,1,0]
	v_pk_mul_f32 v[142:143], v[150:151], v[140:141] op_sel:[0,0] op_sel_hi:[0,1]
	v_pk_fma_f32 v[142:143], v[150:151], v[140:141], v[142:143] op_sel:[1,1,0] op_sel_hi:[1,0,1] neg_lo:[0,1,0]
	ds_write_b64 v132, v[142:143] offset:23936
	v_pk_mul_f32 v[142:143], v[140:141], v[112:113] op_sel:[0,0] op_sel_hi:[0,1]
	v_pk_fma_f32 v[140:141], v[140:141], v[112:113], v[142:143] op_sel:[1,1,0] op_sel_hi:[1,0,1] neg_lo:[0,1,0]
	v_pk_mul_f32 v[142:143], v[116:117], v[140:141] op_sel:[0,0] op_sel_hi:[0,1]
	v_pk_fma_f32 v[116:117], v[116:117], v[140:141], v[142:143] op_sel:[1,1,0] op_sel_hi:[1,0,1] neg_lo:[0,1,0]
	ds_write_b64 v132, v[116:117] offset:26112
	v_pk_mul_f32 v[116:117], v[140:141], v[112:113] op_sel:[0,0] op_sel_hi:[0,1]
	v_pk_fma_f32 v[116:117], v[140:141], v[112:113], v[116:117] op_sel:[1,1,0] op_sel_hi:[1,0,1] neg_lo:[0,1,0]
	v_pk_mul_f32 v[140:141], v[148:149], v[116:117] op_sel:[0,0] op_sel_hi:[0,1]
	v_pk_fma_f32 v[140:141], v[148:149], v[116:117], v[140:141] op_sel:[1,1,0] op_sel_hi:[1,0,1] neg_lo:[0,1,0]
	ds_write_b64 v132, v[140:141] offset:28288
	v_pk_mul_f32 v[140:141], v[116:117], v[112:113] op_sel:[0,0] op_sel_hi:[0,1]
	v_pk_fma_f32 v[116:117], v[116:117], v[112:113], v[140:141] op_sel:[1,1,0] op_sel_hi:[1,0,1] neg_lo:[0,1,0]
	v_pk_mul_f32 v[140:141], v[114:115], v[116:117] op_sel:[0,0] op_sel_hi:[0,1]
	v_pk_fma_f32 v[114:115], v[114:115], v[116:117], v[140:141] op_sel:[1,1,0] op_sel_hi:[1,0,1] neg_lo:[0,1,0]
	ds_write_b64 v132, v[114:115] offset:30464
	v_pk_mul_f32 v[114:115], v[116:117], v[112:113] op_sel:[0,0] op_sel_hi:[0,1]
	v_pk_fma_f32 v[112:113], v[116:117], v[112:113], v[114:115] op_sel:[1,1,0] op_sel_hi:[1,0,1] neg_lo:[0,1,0]
	v_pk_mul_f32 v[114:115], v[110:111], v[112:113] op_sel:[0,0] op_sel_hi:[0,1]
	v_pk_fma_f32 v[110:111], v[110:111], v[112:113], v[114:115] op_sel:[1,1,0] op_sel_hi:[1,0,1] neg_lo:[0,1,0]
	ds_write_b64 v132, v[110:111] offset:32640
	s_waitcnt lgkmcnt(0)
	s_barrier
	ds_read2_b64 v[110:113], v134 offset1:17
	ds_read2_b64 v[114:117], v134 offset0:34 offset1:51
	ds_read2_b64 v[140:143], v134 offset0:68 offset1:85
	ds_read2_b64 v[144:147], v134 offset0:136 offset1:153
	ds_read2_b64 v[148:151], v134 offset0:102 offset1:119
	ds_read2_b64 v[152:155], v134 offset0:204 offset1:221
	ds_read2_b64 v[156:159], v134 offset0:170 offset1:187
	ds_read2_b64 v[160:163], v134 offset0:238 offset1:255
	s_waitcnt lgkmcnt(4)
	v_pk_add_f32 v[164:165], v[110:111], v[144:145]
	v_pk_add_f32 v[110:111], v[110:111], v[144:145] neg_lo:[0,1] neg_hi:[0,1]
	s_waitcnt lgkmcnt(2)
	v_pk_add_f32 v[144:145], v[140:141], v[152:153]
	v_pk_add_f32 v[140:141], v[140:141], v[152:153] neg_lo:[0,1] neg_hi:[0,1]
	v_pk_add_f32 v[152:153], v[164:165], v[144:145]
	v_pk_add_f32 v[144:145], v[164:165], v[144:145] neg_lo:[0,1] neg_hi:[0,1]
	v_pk_add_f32 v[164:165], v[110:111], v[140:141] op_sel:[0,1] op_sel_hi:[1,0] neg_hi:[0,1]
	v_pk_add_f32 v[110:111], v[110:111], v[140:141] op_sel:[0,1] op_sel_hi:[1,0] neg_lo:[0,1]
	v_pk_add_f32 v[140:141], v[112:113], v[146:147]
	v_pk_add_f32 v[112:113], v[112:113], v[146:147] neg_lo:[0,1] neg_hi:[0,1]
	v_pk_add_f32 v[146:147], v[142:143], v[154:155]
	v_pk_add_f32 v[142:143], v[142:143], v[154:155] neg_lo:[0,1] neg_hi:[0,1]
	v_pk_add_f32 v[154:155], v[140:141], v[146:147]
	v_pk_add_f32 v[140:141], v[140:141], v[146:147] neg_lo:[0,1] neg_hi:[0,1]
	v_pk_add_f32 v[146:147], v[112:113], v[142:143] op_sel:[0,1] op_sel_hi:[1,0] neg_hi:[0,1]
	v_pk_add_f32 v[112:113], v[112:113], v[142:143] op_sel:[0,1] op_sel_hi:[1,0] neg_lo:[0,1]
	s_waitcnt lgkmcnt(1)
	v_pk_add_f32 v[142:143], v[114:115], v[156:157]
	v_pk_add_f32 v[114:115], v[114:115], v[156:157] neg_lo:[0,1] neg_hi:[0,1]
	s_waitcnt lgkmcnt(0)
	v_pk_add_f32 v[156:157], v[148:149], v[160:161]
	v_pk_add_f32 v[148:149], v[148:149], v[160:161] neg_lo:[0,1] neg_hi:[0,1]
	v_pk_add_f32 v[160:161], v[142:143], v[156:157]
	v_pk_add_f32 v[142:143], v[142:143], v[156:157] neg_lo:[0,1] neg_hi:[0,1]
	v_pk_add_f32 v[156:157], v[114:115], v[148:149] op_sel:[0,1] op_sel_hi:[1,0] neg_hi:[0,1]
	v_pk_add_f32 v[114:115], v[114:115], v[148:149] op_sel:[0,1] op_sel_hi:[1,0] neg_lo:[0,1]
	v_pk_add_f32 v[148:149], v[116:117], v[158:159]
	v_pk_add_f32 v[116:117], v[116:117], v[158:159] neg_lo:[0,1] neg_hi:[0,1]
	v_pk_add_f32 v[158:159], v[150:151], v[162:163]
	v_pk_add_f32 v[150:151], v[150:151], v[162:163] neg_lo:[0,1] neg_hi:[0,1]
	v_pk_add_f32 v[162:163], v[148:149], v[158:159]
	v_pk_add_f32 v[148:149], v[148:149], v[158:159] neg_lo:[0,1] neg_hi:[0,1]
	v_pk_add_f32 v[158:159], v[116:117], v[150:151] op_sel:[0,1] op_sel_hi:[1,0] neg_hi:[0,1]
	v_pk_add_f32 v[116:117], v[116:117], v[150:151] op_sel:[0,1] op_sel_hi:[1,0] neg_lo:[0,1]
	v_pk_mul_f32 v[150:151], v[146:147], s[20:21] op_sel:[0,0] op_sel_hi:[0,1]
	v_pk_fma_f32 v[146:147], v[146:147], s[20:21], v[150:151] op_sel:[1,1,0] op_sel_hi:[1,0,1] neg_lo:[0,1,0]
	v_pk_mul_f32 v[150:151], v[156:157], s[46:47] op_sel:[0,0] op_sel_hi:[0,1]
	v_pk_fma_f32 v[150:151], v[156:157], s[46:47], v[150:151] op_sel:[1,1,0] op_sel_hi:[1,0,1] neg_lo:[0,1,0]
	v_pk_mul_f32 v[156:157], v[158:159], s[50:51] op_sel:[0,0] op_sel_hi:[0,1]
	v_pk_fma_f32 v[156:157], v[158:159], s[50:51], v[156:157] op_sel:[1,1,0] op_sel_hi:[1,0,1] neg_lo:[0,1,0]
	v_pk_mul_f32 v[158:159], v[140:141], s[46:47] op_sel:[0,0] op_sel_hi:[0,1]
	v_pk_fma_f32 v[140:141], v[140:141], s[46:47], v[158:159] op_sel:[1,1,0] op_sel_hi:[1,0,1] neg_lo:[0,1,0]
	v_pk_mul_f32 v[158:159], v[142:143], s[8:9] op_sel:[0,0] op_sel_hi:[0,1]
	v_pk_fma_f32 v[142:143], v[142:143], s[8:9], v[158:159] op_sel:[1,1,0] op_sel_hi:[1,0,1] neg_lo:[0,1,0]
	v_pk_mul_f32 v[158:159], v[148:149], s[54:55] op_sel:[0,0] op_sel_hi:[0,1]
	v_pk_fma_f32 v[148:149], v[148:149], s[54:55], v[158:159] op_sel:[1,1,0] op_sel_hi:[1,0,1] neg_lo:[0,1,0]
	v_pk_mul_f32 v[158:159], v[112:113], s[50:51] op_sel:[0,0] op_sel_hi:[0,1]
	v_pk_fma_f32 v[112:113], v[112:113], s[50:51], v[158:159] op_sel:[1,1,0] op_sel_hi:[1,0,1] neg_lo:[0,1,0]
	v_pk_mul_f32 v[158:159], v[114:115], s[54:55] op_sel:[0,0] op_sel_hi:[0,1]
	v_pk_fma_f32 v[114:115], v[114:115], s[54:55], v[158:159] op_sel:[1,1,0] op_sel_hi:[1,0,1] neg_lo:[0,1,0]
	v_pk_mul_f32 v[158:159], v[116:117], s[56:57] op_sel:[0,0] op_sel_hi:[0,1]
	v_pk_fma_f32 v[116:117], v[116:117], s[56:57], v[158:159] op_sel:[1,1,0] op_sel_hi:[1,0,1] neg_lo:[0,1,0]
	v_pk_add_f32 v[158:159], v[152:153], v[160:161]
	v_pk_add_f32 v[152:153], v[152:153], v[160:161] neg_lo:[0,1] neg_hi:[0,1]
	v_pk_add_f32 v[160:161], v[154:155], v[162:163]
	v_pk_add_f32 v[154:155], v[154:155], v[162:163] neg_lo:[0,1] neg_hi:[0,1]
	v_pk_add_f32 v[162:163], v[158:159], v[160:161]
	v_pk_add_f32 v[158:159], v[158:159], v[160:161] neg_lo:[0,1] neg_hi:[0,1]
	v_pk_add_f32 v[160:161], v[152:153], v[154:155] op_sel:[0,1] op_sel_hi:[1,0] neg_hi:[0,1]
	v_pk_add_f32 v[152:153], v[152:153], v[154:155] op_sel:[0,1] op_sel_hi:[1,0] neg_lo:[0,1]
	v_pk_add_f32 v[154:155], v[164:165], v[150:151]
	v_pk_add_f32 v[150:151], v[164:165], v[150:151] neg_lo:[0,1] neg_hi:[0,1]
	v_pk_add_f32 v[164:165], v[146:147], v[156:157]
	v_pk_add_f32 v[146:147], v[146:147], v[156:157] neg_lo:[0,1] neg_hi:[0,1]
	v_pk_add_f32 v[156:157], v[154:155], v[164:165]
	v_pk_add_f32 v[154:155], v[154:155], v[164:165] neg_lo:[0,1] neg_hi:[0,1]
	v_pk_add_f32 v[164:165], v[150:151], v[146:147] op_sel:[0,1] op_sel_hi:[1,0] neg_hi:[0,1]
	v_pk_add_f32 v[146:147], v[150:151], v[146:147] op_sel:[0,1] op_sel_hi:[1,0] neg_lo:[0,1]
	v_pk_add_f32 v[150:151], v[144:145], v[142:143]
	v_pk_add_f32 v[142:143], v[144:145], v[142:143] neg_lo:[0,1] neg_hi:[0,1]
	v_pk_add_f32 v[144:145], v[140:141], v[148:149]
	v_pk_add_f32 v[140:141], v[140:141], v[148:149] neg_lo:[0,1] neg_hi:[0,1]
	v_pk_add_f32 v[148:149], v[150:151], v[144:145]
	v_pk_add_f32 v[144:145], v[150:151], v[144:145] neg_lo:[0,1] neg_hi:[0,1]
	v_pk_add_f32 v[150:151], v[142:143], v[140:141] op_sel:[0,1] op_sel_hi:[1,0] neg_hi:[0,1]
	v_pk_add_f32 v[140:141], v[142:143], v[140:141] op_sel:[0,1] op_sel_hi:[1,0] neg_lo:[0,1]
	v_pk_add_f32 v[142:143], v[110:111], v[114:115]
	v_pk_add_f32 v[110:111], v[110:111], v[114:115] neg_lo:[0,1] neg_hi:[0,1]
	v_pk_add_f32 v[114:115], v[112:113], v[116:117]
	v_pk_add_f32 v[112:113], v[112:113], v[116:117] neg_lo:[0,1] neg_hi:[0,1]
	v_pk_add_f32 v[116:117], v[142:143], v[114:115]
	v_pk_add_f32 v[114:115], v[142:143], v[114:115] neg_lo:[0,1] neg_hi:[0,1]
	v_pk_add_f32 v[142:143], v[110:111], v[112:113] op_sel:[0,1] op_sel_hi:[1,0] neg_hi:[0,1]
	v_pk_add_f32 v[110:111], v[110:111], v[112:113] op_sel:[0,1] op_sel_hi:[1,0] neg_lo:[0,1]
	v_mov_b32_e32 v112, v40
	v_mov_b32_e32 v113, v41
	s_nop 0
	v_pk_mul_f32 v[166:167], v[156:157], v[112:113] op_sel:[0,0] op_sel_hi:[0,1]
	v_pk_fma_f32 v[156:157], v[156:157], v[112:113], v[166:167] op_sel:[1,1,0] op_sel_hi:[1,0,1] neg_lo:[0,1,0]
	ds_write2_b64 v134, v[162:163], v[156:157] offset1:17
	v_pk_mul_f32 v[156:157], v[112:113], v[112:113] op_sel:[0,0] op_sel_hi:[0,1]
	v_pk_fma_f32 v[156:157], v[112:113], v[112:113], v[156:157] op_sel:[1,1,0] op_sel_hi:[1,0,1] neg_lo:[0,1,0]
	v_pk_mul_f32 v[162:163], v[148:149], v[156:157] op_sel:[0,0] op_sel_hi:[0,1]
	v_pk_fma_f32 v[148:149], v[148:149], v[156:157], v[162:163] op_sel:[1,1,0] op_sel_hi:[1,0,1] neg_lo:[0,1,0]
	v_pk_mul_f32 v[162:163], v[156:157], v[112:113] op_sel:[0,0] op_sel_hi:[0,1]
	v_pk_fma_f32 v[156:157], v[156:157], v[112:113], v[162:163] op_sel:[1,1,0] op_sel_hi:[1,0,1] neg_lo:[0,1,0]
	v_pk_mul_f32 v[162:163], v[116:117], v[156:157] op_sel:[0,0] op_sel_hi:[0,1]
	v_pk_fma_f32 v[116:117], v[116:117], v[156:157], v[162:163] op_sel:[1,1,0] op_sel_hi:[1,0,1] neg_lo:[0,1,0]
	ds_write2_b64 v134, v[148:149], v[116:117] offset0:34 offset1:51
	v_pk_mul_f32 v[116:117], v[156:157], v[112:113] op_sel:[0,0] op_sel_hi:[0,1]
	v_pk_fma_f32 v[116:117], v[156:157], v[112:113], v[116:117] op_sel:[1,1,0] op_sel_hi:[1,0,1] neg_lo:[0,1,0]
	v_pk_mul_f32 v[148:149], v[160:161], v[116:117] op_sel:[0,0] op_sel_hi:[0,1]
	v_pk_mul_f32 v[156:157], v[116:117], v[112:113] op_sel:[0,0] op_sel_hi:[0,1]
	v_pk_fma_f32 v[148:149], v[160:161], v[116:117], v[148:149] op_sel:[1,1,0] op_sel_hi:[1,0,1] neg_lo:[0,1,0]
	v_pk_fma_f32 v[116:117], v[116:117], v[112:113], v[156:157] op_sel:[1,1,0] op_sel_hi:[1,0,1] neg_lo:[0,1,0]
	v_pk_mul_f32 v[156:157], v[164:165], v[116:117] op_sel:[0,0] op_sel_hi:[0,1]
	v_pk_fma_f32 v[156:157], v[164:165], v[116:117], v[156:157] op_sel:[1,1,0] op_sel_hi:[1,0,1] neg_lo:[0,1,0]
	ds_write2_b64 v134, v[148:149], v[156:157] offset0:68 offset1:85
	v_pk_mul_f32 v[148:149], v[116:117], v[112:113] op_sel:[0,0] op_sel_hi:[0,1]
	v_pk_fma_f32 v[116:117], v[116:117], v[112:113], v[148:149] op_sel:[1,1,0] op_sel_hi:[1,0,1] neg_lo:[0,1,0]
	v_pk_mul_f32 v[148:149], v[150:151], v[116:117] op_sel:[0,0] op_sel_hi:[0,1]
	v_pk_fma_f32 v[148:149], v[150:151], v[116:117], v[148:149] op_sel:[1,1,0] op_sel_hi:[1,0,1] neg_lo:[0,1,0]
	v_pk_mul_f32 v[150:151], v[116:117], v[112:113] op_sel:[0,0] op_sel_hi:[0,1]
	v_pk_fma_f32 v[116:117], v[116:117], v[112:113], v[150:151] op_sel:[1,1,0] op_sel_hi:[1,0,1] neg_lo:[0,1,0]
	v_pk_mul_f32 v[150:151], v[142:143], v[116:117] op_sel:[0,0] op_sel_hi:[0,1]
	v_pk_fma_f32 v[142:143], v[142:143], v[116:117], v[150:151] op_sel:[1,1,0] op_sel_hi:[1,0,1] neg_lo:[0,1,0]
	ds_write2_b64 v134, v[148:149], v[142:143] offset0:102 offset1:119
	v_pk_mul_f32 v[142:143], v[116:117], v[112:113] op_sel:[0,0] op_sel_hi:[0,1]
	v_pk_fma_f32 v[116:117], v[116:117], v[112:113], v[142:143] op_sel:[1,1,0] op_sel_hi:[1,0,1] neg_lo:[0,1,0]
	v_pk_mul_f32 v[142:143], v[158:159], v[116:117] op_sel:[0,0] op_sel_hi:[0,1]
	v_pk_mul_f32 v[148:149], v[116:117], v[112:113] op_sel:[0,0] op_sel_hi:[0,1]
	v_pk_fma_f32 v[142:143], v[158:159], v[116:117], v[142:143] op_sel:[1,1,0] op_sel_hi:[1,0,1] neg_lo:[0,1,0]
	v_pk_fma_f32 v[116:117], v[116:117], v[112:113], v[148:149] op_sel:[1,1,0] op_sel_hi:[1,0,1] neg_lo:[0,1,0]
	v_pk_mul_f32 v[148:149], v[154:155], v[116:117] op_sel:[0,0] op_sel_hi:[0,1]
	v_pk_fma_f32 v[148:149], v[154:155], v[116:117], v[148:149] op_sel:[1,1,0] op_sel_hi:[1,0,1] neg_lo:[0,1,0]
	ds_write2_b64 v134, v[142:143], v[148:149] offset0:136 offset1:153
	v_pk_mul_f32 v[142:143], v[116:117], v[112:113] op_sel:[0,0] op_sel_hi:[0,1]
	v_pk_fma_f32 v[116:117], v[116:117], v[112:113], v[142:143] op_sel:[1,1,0] op_sel_hi:[1,0,1] neg_lo:[0,1,0]
	v_pk_mul_f32 v[142:143], v[144:145], v[116:117] op_sel:[0,0] op_sel_hi:[0,1]
	v_pk_fma_f32 v[142:143], v[144:145], v[116:117], v[142:143] op_sel:[1,1,0] op_sel_hi:[1,0,1] neg_lo:[0,1,0]
	v_pk_mul_f32 v[144:145], v[116:117], v[112:113] op_sel:[0,0] op_sel_hi:[0,1]
	v_pk_fma_f32 v[116:117], v[116:117], v[112:113], v[144:145] op_sel:[1,1,0] op_sel_hi:[1,0,1] neg_lo:[0,1,0]
	v_pk_mul_f32 v[144:145], v[114:115], v[116:117] op_sel:[0,0] op_sel_hi:[0,1]
	v_pk_fma_f32 v[114:115], v[114:115], v[116:117], v[144:145] op_sel:[1,1,0] op_sel_hi:[1,0,1] neg_lo:[0,1,0]
	ds_write2_b64 v134, v[142:143], v[114:115] offset0:170 offset1:187
	v_pk_mul_f32 v[114:115], v[116:117], v[112:113] op_sel:[0,0] op_sel_hi:[0,1]
	v_pk_fma_f32 v[114:115], v[116:117], v[112:113], v[114:115] op_sel:[1,1,0] op_sel_hi:[1,0,1] neg_lo:[0,1,0]
	v_pk_mul_f32 v[116:117], v[152:153], v[114:115] op_sel:[0,0] op_sel_hi:[0,1]
	v_pk_mul_f32 v[142:143], v[114:115], v[112:113] op_sel:[0,0] op_sel_hi:[0,1]
	v_pk_fma_f32 v[116:117], v[152:153], v[114:115], v[116:117] op_sel:[1,1,0] op_sel_hi:[1,0,1] neg_lo:[0,1,0]
	v_pk_fma_f32 v[114:115], v[114:115], v[112:113], v[142:143] op_sel:[1,1,0] op_sel_hi:[1,0,1] neg_lo:[0,1,0]
	v_pk_mul_f32 v[142:143], v[146:147], v[114:115] op_sel:[0,0] op_sel_hi:[0,1]
	v_pk_fma_f32 v[142:143], v[146:147], v[114:115], v[142:143] op_sel:[1,1,0] op_sel_hi:[1,0,1] neg_lo:[0,1,0]
	ds_write2_b64 v134, v[116:117], v[142:143] offset0:204 offset1:221
	v_pk_mul_f32 v[116:117], v[114:115], v[112:113] op_sel:[0,0] op_sel_hi:[0,1]
	v_pk_fma_f32 v[114:115], v[114:115], v[112:113], v[116:117] op_sel:[1,1,0] op_sel_hi:[1,0,1] neg_lo:[0,1,0]
	v_pk_mul_f32 v[116:117], v[140:141], v[114:115] op_sel:[0,0] op_sel_hi:[0,1]
	v_pk_fma_f32 v[116:117], v[140:141], v[114:115], v[116:117] op_sel:[1,1,0] op_sel_hi:[1,0,1] neg_lo:[0,1,0]
	v_pk_mul_f32 v[140:141], v[114:115], v[112:113] op_sel:[0,0] op_sel_hi:[0,1]
	v_pk_fma_f32 v[112:113], v[114:115], v[112:113], v[140:141] op_sel:[1,1,0] op_sel_hi:[1,0,1] neg_lo:[0,1,0]
	v_pk_mul_f32 v[114:115], v[110:111], v[112:113] op_sel:[0,0] op_sel_hi:[0,1]
	v_pk_fma_f32 v[110:111], v[110:111], v[112:113], v[114:115] op_sel:[1,1,0] op_sel_hi:[1,0,1] neg_lo:[0,1,0]
	ds_write2_b64 v134, v[116:117], v[110:111] offset0:238 offset1:255
	s_waitcnt lgkmcnt(0)
	s_barrier
	ds_read2_b64 v[110:113], v135 offset1:1
	ds_read2_b64 v[114:117], v135 offset0:2 offset1:3
	ds_read2_b64 v[140:143], v135 offset0:8 offset1:9
	ds_read2_b64 v[144:147], v135 offset0:4 offset1:5
	ds_read2_b64 v[148:151], v135 offset0:6 offset1:7
	ds_read2_b64 v[152:155], v135 offset0:12 offset1:13
	ds_read2_b64 v[156:159], v135 offset0:10 offset1:11
	ds_read2_b64 v[160:163], v135 offset0:14 offset1:15
	s_waitcnt lgkmcnt(5)
	v_pk_add_f32 v[164:165], v[110:111], v[140:141]
	v_pk_add_f32 v[110:111], v[110:111], v[140:141] neg_lo:[0,1] neg_hi:[0,1]
	s_waitcnt lgkmcnt(2)
	v_pk_add_f32 v[140:141], v[144:145], v[152:153]
	v_pk_add_f32 v[144:145], v[144:145], v[152:153] neg_lo:[0,1] neg_hi:[0,1]
	v_pk_add_f32 v[152:153], v[164:165], v[140:141]
	v_pk_add_f32 v[140:141], v[164:165], v[140:141] neg_lo:[0,1] neg_hi:[0,1]
	v_pk_add_f32 v[164:165], v[110:111], v[144:145] op_sel:[0,1] op_sel_hi:[1,0] neg_hi:[0,1]
	v_pk_add_f32 v[110:111], v[110:111], v[144:145] op_sel:[0,1] op_sel_hi:[1,0] neg_lo:[0,1]
	v_pk_add_f32 v[144:145], v[112:113], v[142:143]
	v_pk_add_f32 v[112:113], v[112:113], v[142:143] neg_lo:[0,1] neg_hi:[0,1]
	v_pk_add_f32 v[142:143], v[146:147], v[154:155]
	v_pk_add_f32 v[146:147], v[146:147], v[154:155] neg_lo:[0,1] neg_hi:[0,1]
	v_pk_add_f32 v[154:155], v[144:145], v[142:143]
	v_pk_add_f32 v[142:143], v[144:145], v[142:143] neg_lo:[0,1] neg_hi:[0,1]
	v_pk_add_f32 v[144:145], v[112:113], v[146:147] op_sel:[0,1] op_sel_hi:[1,0] neg_hi:[0,1]
	v_pk_add_f32 v[112:113], v[112:113], v[146:147] op_sel:[0,1] op_sel_hi:[1,0] neg_lo:[0,1]
	s_waitcnt lgkmcnt(1)
	v_pk_add_f32 v[146:147], v[114:115], v[156:157]
	v_pk_add_f32 v[114:115], v[114:115], v[156:157] neg_lo:[0,1] neg_hi:[0,1]
	s_waitcnt lgkmcnt(0)
	v_pk_add_f32 v[156:157], v[148:149], v[160:161]
	v_pk_add_f32 v[148:149], v[148:149], v[160:161] neg_lo:[0,1] neg_hi:[0,1]
	v_pk_add_f32 v[160:161], v[146:147], v[156:157]
	v_pk_add_f32 v[146:147], v[146:147], v[156:157] neg_lo:[0,1] neg_hi:[0,1]
	v_pk_add_f32 v[156:157], v[114:115], v[148:149] op_sel:[0,1] op_sel_hi:[1,0] neg_hi:[0,1]
	v_pk_add_f32 v[114:115], v[114:115], v[148:149] op_sel:[0,1] op_sel_hi:[1,0] neg_lo:[0,1]
	v_pk_add_f32 v[148:149], v[116:117], v[158:159]
	v_pk_add_f32 v[116:117], v[116:117], v[158:159] neg_lo:[0,1] neg_hi:[0,1]
	v_pk_add_f32 v[158:159], v[150:151], v[162:163]
	v_pk_add_f32 v[150:151], v[150:151], v[162:163] neg_lo:[0,1] neg_hi:[0,1]
	v_pk_add_f32 v[162:163], v[148:149], v[158:159]
	v_pk_add_f32 v[148:149], v[148:149], v[158:159] neg_lo:[0,1] neg_hi:[0,1]
	v_pk_add_f32 v[158:159], v[116:117], v[150:151] op_sel:[0,1] op_sel_hi:[1,0] neg_hi:[0,1]
	v_pk_add_f32 v[116:117], v[116:117], v[150:151] op_sel:[0,1] op_sel_hi:[1,0] neg_lo:[0,1]
	v_pk_mul_f32 v[150:151], v[144:145], s[20:21] op_sel:[0,0] op_sel_hi:[0,1]
	v_pk_fma_f32 v[102:103], v[144:145], s[20:21], v[150:151] op_sel:[1,1,0] op_sel_hi:[1,0,1] neg_lo:[0,1,0]
	v_pk_mul_f32 v[144:145], v[156:157], s[46:47] op_sel:[0,0] op_sel_hi:[0,1]
	v_pk_mul_f32 v[150:151], v[158:159], s[50:51] op_sel:[0,0] op_sel_hi:[0,1]
	v_pk_fma_f32 v[144:145], v[156:157], s[46:47], v[144:145] op_sel:[1,1,0] op_sel_hi:[1,0,1] neg_lo:[0,1,0]
	v_pk_mul_f32 v[156:157], v[142:143], s[46:47] op_sel:[0,0] op_sel_hi:[0,1]
	v_pk_fma_f32 v[150:151], v[158:159], s[50:51], v[150:151] op_sel:[1,1,0] op_sel_hi:[1,0,1] neg_lo:[0,1,0]
	v_pk_fma_f32 v[98:99], v[142:143], s[46:47], v[156:157] op_sel:[1,1,0] op_sel_hi:[1,0,1] neg_lo:[0,1,0]
	v_pk_mul_f32 v[142:143], v[146:147], s[8:9] op_sel:[0,0] op_sel_hi:[0,1]
	v_pk_fma_f32 v[104:105], v[146:147], s[8:9], v[142:143] op_sel:[1,1,0] op_sel_hi:[1,0,1] neg_lo:[0,1,0]
	v_pk_mul_f32 v[142:143], v[148:149], s[54:55] op_sel:[0,0] op_sel_hi:[0,1]
	v_pk_mul_f32 v[146:147], v[112:113], s[50:51] op_sel:[0,0] op_sel_hi:[0,1]
	v_pk_fma_f32 v[96:97], v[112:113], s[50:51], v[146:147] op_sel:[1,1,0] op_sel_hi:[1,0,1] neg_lo:[0,1,0]
	v_pk_mul_f32 v[112:113], v[114:115], s[54:55] op_sel:[0,0] op_sel_hi:[0,1]
	v_pk_fma_f32 v[142:143], v[148:149], s[54:55], v[142:143] op_sel:[1,1,0] op_sel_hi:[1,0,1] neg_lo:[0,1,0]
	v_pk_add_f32 v[146:147], v[154:155], v[162:163] neg_lo:[0,1] neg_hi:[0,1]
	v_pk_fma_f32 v[100:101], v[114:115], s[54:55], v[112:113] op_sel:[1,1,0] op_sel_hi:[1,0,1] neg_lo:[0,1,0]
	v_pk_mul_f32 v[112:113], v[116:117], s[56:57] op_sel:[0,0] op_sel_hi:[0,1]
	v_pk_add_f32 v[114:115], v[152:153], v[160:161] neg_lo:[0,1] neg_hi:[0,1]
	v_pk_fma_f32 v[106:107], v[116:117], s[56:57], v[112:113] op_sel:[1,1,0] op_sel_hi:[1,0,1] neg_lo:[0,1,0]
	v_pk_add_f32 v[112:113], v[152:153], v[160:161]
	v_pk_add_f32 v[116:117], v[154:155], v[162:163]
	v_pk_add_f32 v[152:153], v[102:103], v[150:151]
	v_pk_add_f32 v[148:149], v[112:113], v[116:117]
	v_pk_add_f32 v[112:113], v[112:113], v[116:117] neg_lo:[0,1] neg_hi:[0,1]
	v_pk_add_f32 v[116:117], v[114:115], v[146:147] op_sel:[0,1] op_sel_hi:[1,0] neg_hi:[0,1]
	v_pk_add_f32 v[114:115], v[114:115], v[146:147] op_sel:[0,1] op_sel_hi:[1,0] neg_lo:[0,1]
	v_pk_add_f32 v[146:147], v[164:165], v[144:145]
	v_pk_add_f32 v[144:145], v[164:165], v[144:145] neg_lo:[0,1] neg_hi:[0,1]
	v_pk_add_f32 v[102:103], v[102:103], v[150:151] neg_lo:[0,1] neg_hi:[0,1]
	v_pk_add_f32 v[150:151], v[146:147], v[152:153]
	v_pk_add_f32 v[146:147], v[146:147], v[152:153] neg_lo:[0,1] neg_hi:[0,1]
	v_pk_add_f32 v[152:153], v[144:145], v[102:103] op_sel:[0,1] op_sel_hi:[1,0] neg_hi:[0,1]
	v_pk_add_f32 v[102:103], v[144:145], v[102:103] op_sel:[0,1] op_sel_hi:[1,0] neg_lo:[0,1]
	v_pk_add_f32 v[144:145], v[140:141], v[104:105]
	v_pk_add_f32 v[104:105], v[140:141], v[104:105] neg_lo:[0,1] neg_hi:[0,1]
	v_pk_add_f32 v[140:141], v[98:99], v[142:143]
	v_pk_add_f32 v[98:99], v[98:99], v[142:143] neg_lo:[0,1] neg_hi:[0,1]
	v_pk_add_f32 v[142:143], v[144:145], v[140:141]
	v_pk_add_f32 v[140:141], v[144:145], v[140:141] neg_lo:[0,1] neg_hi:[0,1]
	v_pk_add_f32 v[144:145], v[104:105], v[98:99] op_sel:[0,1] op_sel_hi:[1,0] neg_hi:[0,1]
	v_pk_add_f32 v[98:99], v[104:105], v[98:99] op_sel:[0,1] op_sel_hi:[1,0] neg_lo:[0,1]
	v_pk_add_f32 v[104:105], v[110:111], v[100:101]
	v_pk_add_f32 v[100:101], v[110:111], v[100:101] neg_lo:[0,1] neg_hi:[0,1]
	v_pk_add_f32 v[110:111], v[96:97], v[106:107]
	v_pk_add_f32 v[96:97], v[96:97], v[106:107] neg_lo:[0,1] neg_hi:[0,1]
	v_pk_add_f32 v[106:107], v[104:105], v[110:111]
	v_pk_add_f32 v[104:105], v[104:105], v[110:111] neg_lo:[0,1] neg_hi:[0,1]
	v_pk_add_f32 v[110:111], v[100:101], v[96:97] op_sel:[0,1] op_sel_hi:[1,0] neg_hi:[0,1]
	v_pk_add_f32 v[96:97], v[100:101], v[96:97] op_sel:[0,1] op_sel_hi:[1,0] neg_lo:[0,1]
	s_waitcnt vmcnt(15)
	v_pk_mul_f32 v[100:101], v[148:149], v[70:71] op_sel:[0,0] op_sel_hi:[0,1]
	v_pk_fma_f32 v[70:71], v[148:149], v[70:71], v[100:101] op_sel:[1,1,0] op_sel_hi:[1,0,1] neg_lo:[0,1,0]
	s_waitcnt vmcnt(14)
	v_pk_mul_f32 v[100:101], v[116:117], v[30:31] op_sel:[0,0] op_sel_hi:[0,1]
	v_pk_fma_f32 v[30:31], v[116:117], v[30:31], v[100:101] op_sel:[1,1,0] op_sel_hi:[1,0,1] neg_lo:[0,1,0]
	s_waitcnt vmcnt(13)
	v_pk_mul_f32 v[100:101], v[112:113], v[28:29] op_sel:[0,0] op_sel_hi:[0,1]
	v_pk_fma_f32 v[28:29], v[112:113], v[28:29], v[100:101] op_sel:[1,1,0] op_sel_hi:[1,0,1] neg_lo:[0,1,0]
	s_waitcnt vmcnt(12)
	v_pk_mul_f32 v[100:101], v[114:115], v[32:33] op_sel:[0,0] op_sel_hi:[0,1]
	v_pk_fma_f32 v[32:33], v[114:115], v[32:33], v[100:101] op_sel:[1,1,0] op_sel_hi:[1,0,1] neg_lo:[0,1,0]
	s_waitcnt vmcnt(11)
	v_pk_mul_f32 v[100:101], v[150:151], v[78:79] op_sel:[0,0] op_sel_hi:[0,1]
	v_pk_fma_f32 v[78:79], v[150:151], v[78:79], v[100:101] op_sel:[1,1,0] op_sel_hi:[1,0,1] neg_lo:[0,1,0]
	s_waitcnt vmcnt(10)
	v_pk_mul_f32 v[100:101], v[152:153], v[74:75] op_sel:[0,0] op_sel_hi:[0,1]
	v_pk_fma_f32 v[74:75], v[152:153], v[74:75], v[100:101] op_sel:[1,1,0] op_sel_hi:[1,0,1] neg_lo:[0,1,0]
	s_waitcnt vmcnt(9)
	v_pk_mul_f32 v[100:101], v[146:147], v[72:73] op_sel:[0,0] op_sel_hi:[0,1]
	v_pk_fma_f32 v[72:73], v[146:147], v[72:73], v[100:101] op_sel:[1,1,0] op_sel_hi:[1,0,1] neg_lo:[0,1,0]
	s_waitcnt vmcnt(8)
	v_pk_mul_f32 v[100:101], v[102:103], v[76:77] op_sel:[0,0] op_sel_hi:[0,1]
	v_pk_fma_f32 v[76:77], v[102:103], v[76:77], v[100:101] op_sel:[1,1,0] op_sel_hi:[1,0,1] neg_lo:[0,1,0]
	s_waitcnt vmcnt(7)
	v_pk_mul_f32 v[100:101], v[142:143], v[86:87] op_sel:[0,0] op_sel_hi:[0,1]
	v_pk_fma_f32 v[86:87], v[142:143], v[86:87], v[100:101] op_sel:[1,1,0] op_sel_hi:[1,0,1] neg_lo:[0,1,0]
	s_waitcnt vmcnt(6)
	v_pk_mul_f32 v[100:101], v[144:145], v[82:83] op_sel:[0,0] op_sel_hi:[0,1]
	v_pk_fma_f32 v[82:83], v[144:145], v[82:83], v[100:101] op_sel:[1,1,0] op_sel_hi:[1,0,1] neg_lo:[0,1,0]
	s_waitcnt vmcnt(5)
	v_pk_mul_f32 v[100:101], v[140:141], v[80:81] op_sel:[0,0] op_sel_hi:[0,1]
	v_pk_fma_f32 v[80:81], v[140:141], v[80:81], v[100:101] op_sel:[1,1,0] op_sel_hi:[1,0,1] neg_lo:[0,1,0]
	s_waitcnt vmcnt(4)
	v_pk_mul_f32 v[100:101], v[98:99], v[84:85] op_sel:[0,0] op_sel_hi:[0,1]
	v_pk_fma_f32 v[84:85], v[98:99], v[84:85], v[100:101] op_sel:[1,1,0] op_sel_hi:[1,0,1] neg_lo:[0,1,0]
	s_waitcnt vmcnt(3)
	v_pk_mul_f32 v[98:99], v[106:107], v[94:95] op_sel:[0,0] op_sel_hi:[0,1]
	v_pk_fma_f32 v[94:95], v[106:107], v[94:95], v[98:99] op_sel:[1,1,0] op_sel_hi:[1,0,1] neg_lo:[0,1,0]
	s_waitcnt vmcnt(2)
	v_pk_mul_f32 v[98:99], v[110:111], v[90:91] op_sel:[0,0] op_sel_hi:[0,1]
	v_pk_fma_f32 v[90:91], v[110:111], v[90:91], v[98:99] op_sel:[1,1,0] op_sel_hi:[1,0,1] neg_lo:[0,1,0]
	s_waitcnt vmcnt(1)
	v_pk_mul_f32 v[98:99], v[104:105], v[88:89] op_sel:[0,0] op_sel_hi:[0,1]
	v_pk_fma_f32 v[88:89], v[104:105], v[88:89], v[98:99] op_sel:[1,1,0] op_sel_hi:[1,0,1] neg_lo:[0,1,0]
	s_waitcnt vmcnt(0)
	v_pk_mul_f32 v[98:99], v[96:97], v[92:93] op_sel:[0,0] op_sel_hi:[0,1]
	v_pk_fma_f32 v[92:93], v[96:97], v[92:93], v[98:99] op_sel:[1,1,0] op_sel_hi:[1,0,1] neg_lo:[0,1,0]
	v_pk_add_f32 v[96:97], v[70:71], v[28:29]
	v_pk_add_f32 v[28:29], v[70:71], v[28:29] neg_lo:[0,1] neg_hi:[0,1]
	v_pk_add_f32 v[70:71], v[30:31], v[32:33]
	v_pk_add_f32 v[30:31], v[30:31], v[32:33] neg_lo:[0,1] neg_hi:[0,1]
	v_pk_add_f32 v[98:99], v[96:97], v[70:71]
	v_pk_add_f32 v[96:97], v[96:97], v[70:71] neg_lo:[0,1] neg_hi:[0,1]
	v_pk_add_f32 v[100:101], v[28:29], v[30:31] op_sel:[0,1] op_sel_hi:[1,0] neg_lo:[0,1]
	v_pk_add_f32 v[102:103], v[28:29], v[30:31] op_sel:[0,1] op_sel_hi:[1,0] neg_hi:[0,1]
	v_pk_add_f32 v[28:29], v[78:79], v[72:73]
	v_pk_add_f32 v[30:31], v[78:79], v[72:73] neg_lo:[0,1] neg_hi:[0,1]
	v_pk_add_f32 v[32:33], v[74:75], v[76:77]
	v_pk_add_f32 v[70:71], v[74:75], v[76:77] neg_lo:[0,1] neg_hi:[0,1]
	v_pk_add_f32 v[76:77], v[28:29], v[32:33]
	v_pk_add_f32 v[32:33], v[28:29], v[32:33] neg_lo:[0,1] neg_hi:[0,1]
	v_pk_add_f32 v[28:29], v[30:31], v[70:71] op_sel:[0,1] op_sel_hi:[1,0] neg_lo:[0,1]
	v_pk_add_f32 v[74:75], v[30:31], v[70:71] op_sel:[0,1] op_sel_hi:[1,0] neg_hi:[0,1]
	v_pk_add_f32 v[30:31], v[86:87], v[80:81]
	v_pk_add_f32 v[70:71], v[86:87], v[80:81] neg_lo:[0,1] neg_hi:[0,1]
	v_pk_add_f32 v[72:73], v[82:83], v[84:85]
	v_pk_add_f32 v[78:79], v[82:83], v[84:85] neg_lo:[0,1] neg_hi:[0,1]
	v_pk_add_f32 v[80:81], v[30:31], v[72:73]
	v_pk_add_f32 v[82:83], v[30:31], v[72:73] neg_lo:[0,1] neg_hi:[0,1]
	v_pk_add_f32 v[72:73], v[70:71], v[78:79] op_sel:[0,1] op_sel_hi:[1,0] neg_lo:[0,1]
	v_pk_add_f32 v[78:79], v[70:71], v[78:79] op_sel:[0,1] op_sel_hi:[1,0] neg_hi:[0,1]
	v_pk_add_f32 v[30:31], v[94:95], v[88:89]
	v_pk_add_f32 v[70:71], v[94:95], v[88:89] neg_lo:[0,1] neg_hi:[0,1]
	v_pk_add_f32 v[84:85], v[90:91], v[92:93]
	v_pk_add_f32 v[86:87], v[90:91], v[92:93] neg_lo:[0,1] neg_hi:[0,1]
	v_pk_add_f32 v[88:89], v[30:31], v[84:85]
	v_pk_add_f32 v[84:85], v[30:31], v[84:85] neg_lo:[0,1] neg_hi:[0,1]
	v_pk_add_f32 v[90:91], v[70:71], v[86:87] op_sel:[0,1] op_sel_hi:[1,0] neg_lo:[0,1]
	v_pk_add_f32 v[86:87], v[70:71], v[86:87] op_sel:[0,1] op_sel_hi:[1,0] neg_hi:[0,1]
	v_pk_mul_f32 v[30:31], v[28:29], s[58:59] op_sel:[0,0] op_sel_hi:[0,1]
	v_pk_fma_f32 v[92:93], v[28:29], s[58:59], v[30:31] op_sel:[1,1,0] op_sel_hi:[1,0,1] neg_lo:[0,1,0]
	v_pk_mul_f32 v[28:29], v[72:73], s[60:61] op_sel:[0,0] op_sel_hi:[0,1]
	v_pk_fma_f32 v[94:95], v[72:73], s[60:61], v[28:29] op_sel:[1,1,0] op_sel_hi:[1,0,1] neg_lo:[0,1,0]
	v_pk_mul_f32 v[72:73], v[90:91], s[62:63] op_sel:[0,0] op_sel_hi:[0,1]
	v_pk_fma_f32 v[90:91], v[90:91], s[62:63], v[72:73] op_sel:[1,1,0] op_sel_hi:[1,0,1] neg_lo:[0,1,0]
	v_pk_mul_f32 v[72:73], v[32:33], s[60:61] op_sel:[0,0] op_sel_hi:[0,1]
	v_pk_fma_f32 v[104:105], v[32:33], s[60:61], v[72:73] op_sel:[1,1,0] op_sel_hi:[1,0,1] neg_lo:[0,1,0]
	v_pk_mul_f32 v[32:33], v[82:83], s[64:65] op_sel:[0,0] op_sel_hi:[0,1]
	v_pk_fma_f32 v[82:83], v[82:83], s[64:65], v[32:33] op_sel:[1,1,0] op_sel_hi:[1,0,1] neg_lo:[0,1,0]
	v_pk_mul_f32 v[106:107], v[84:85], s[66:67] op_sel:[0,0] op_sel_hi:[0,1]
	v_pk_fma_f32 v[84:85], v[84:85], s[66:67], v[106:107] op_sel:[1,1,0] op_sel_hi:[1,0,1] neg_lo:[0,1,0]
	v_pk_mul_f32 v[106:107], v[74:75], s[62:63] op_sel:[0,0] op_sel_hi:[0,1]
	v_pk_fma_f32 v[106:107], v[74:75], s[62:63], v[106:107] op_sel:[1,1,0] op_sel_hi:[1,0,1] neg_lo:[0,1,0]
	v_pk_mul_f32 v[74:75], v[78:79], s[66:67] op_sel:[0,0] op_sel_hi:[0,1]
	v_pk_fma_f32 v[78:79], v[78:79], s[66:67], v[74:75] op_sel:[1,1,0] op_sel_hi:[1,0,1] neg_lo:[0,1,0]
	v_pk_mul_f32 v[110:111], v[86:87], s[68:69] op_sel:[0,0] op_sel_hi:[0,1]
	v_pk_fma_f32 v[86:87], v[86:87], s[68:69], v[110:111] op_sel:[1,1,0] op_sel_hi:[1,0,1] neg_lo:[0,1,0]
	v_pk_add_f32 v[110:111], v[98:99], v[80:81]
	v_pk_add_f32 v[80:81], v[98:99], v[80:81] neg_lo:[0,1] neg_hi:[0,1]
	v_pk_add_f32 v[98:99], v[76:77], v[88:89]
	v_pk_add_f32 v[76:77], v[76:77], v[88:89] neg_lo:[0,1] neg_hi:[0,1]
	v_pk_add_f32 v[88:89], v[110:111], v[98:99]
	v_pk_add_f32 v[98:99], v[110:111], v[98:99] neg_lo:[0,1] neg_hi:[0,1]
	v_pk_add_f32 v[110:111], v[80:81], v[76:77] op_sel:[0,1] op_sel_hi:[1,0] neg_lo:[0,1]
	v_pk_add_f32 v[76:77], v[80:81], v[76:77] op_sel:[0,1] op_sel_hi:[1,0] neg_hi:[0,1]
	v_pk_add_f32 v[80:81], v[100:101], v[94:95]
	v_pk_add_f32 v[94:95], v[100:101], v[94:95] neg_lo:[0,1] neg_hi:[0,1]
	v_pk_add_f32 v[100:101], v[92:93], v[90:91]
	v_pk_add_f32 v[90:91], v[92:93], v[90:91] neg_lo:[0,1] neg_hi:[0,1]
	v_pk_add_f32 v[92:93], v[80:81], v[100:101]
	v_pk_add_f32 v[80:81], v[80:81], v[100:101] neg_lo:[0,1] neg_hi:[0,1]
	v_pk_add_f32 v[100:101], v[94:95], v[90:91] op_sel:[0,1] op_sel_hi:[1,0] neg_lo:[0,1]
	v_pk_add_f32 v[90:91], v[94:95], v[90:91] op_sel:[0,1] op_sel_hi:[1,0] neg_hi:[0,1]
	v_pk_add_f32 v[94:95], v[96:97], v[82:83]
	v_pk_add_f32 v[82:83], v[96:97], v[82:83] neg_lo:[0,1] neg_hi:[0,1]
	v_pk_add_f32 v[96:97], v[104:105], v[84:85]
	v_pk_add_f32 v[84:85], v[104:105], v[84:85] neg_lo:[0,1] neg_hi:[0,1]
	v_pk_add_f32 v[104:105], v[94:95], v[96:97]
	v_pk_add_f32 v[94:95], v[94:95], v[96:97] neg_lo:[0,1] neg_hi:[0,1]
	v_pk_add_f32 v[96:97], v[82:83], v[84:85] op_sel:[0,1] op_sel_hi:[1,0] neg_lo:[0,1]
	v_pk_add_f32 v[82:83], v[82:83], v[84:85] op_sel:[0,1] op_sel_hi:[1,0] neg_hi:[0,1]
	v_pk_add_f32 v[84:85], v[102:103], v[78:79]
	v_pk_add_f32 v[78:79], v[102:103], v[78:79] neg_lo:[0,1] neg_hi:[0,1]
	v_pk_add_f32 v[102:103], v[106:107], v[86:87]
	v_pk_add_f32 v[86:87], v[106:107], v[86:87] neg_lo:[0,1] neg_hi:[0,1]
	v_pk_add_f32 v[106:107], v[84:85], v[102:103]
	v_pk_add_f32 v[84:85], v[84:85], v[102:103] neg_lo:[0,1] neg_hi:[0,1]
	v_pk_add_f32 v[102:103], v[78:79], v[86:87] op_sel:[0,1] op_sel_hi:[1,0] neg_lo:[0,1]
	v_pk_add_f32 v[78:79], v[78:79], v[86:87] op_sel:[0,1] op_sel_hi:[1,0] neg_hi:[0,1]
	v_mov_b32_e32 v86, v40
	v_mov_b32_e32 v87, v41
	ds_write2_b64 v135, v[88:89], v[92:93] offset1:1
	ds_write2_b64 v135, v[104:105], v[106:107] offset0:2 offset1:3
	ds_write2_b64 v135, v[110:111], v[100:101] offset0:4 offset1:5
	ds_write2_b64 v135, v[96:97], v[102:103] offset0:6 offset1:7
	ds_write2_b64 v135, v[98:99], v[80:81] offset0:8 offset1:9
	ds_write2_b64 v135, v[94:95], v[84:85] offset0:10 offset1:11
	ds_write2_b64 v135, v[76:77], v[90:91] offset0:12 offset1:13
	ds_write2_b64 v135, v[82:83], v[78:79] offset0:14 offset1:15
	s_waitcnt lgkmcnt(0)
	s_barrier
	ds_read2_b64 v[76:79], v134 offset1:17
	ds_read2_b64 v[80:83], v134 offset0:34 offset1:51
	s_waitcnt lgkmcnt(1)
	v_pk_mul_f32 v[84:85], v[78:79], v[86:87] op_sel:[0,0] op_sel_hi:[0,1] neg_hi:[0,1]
	v_pk_fma_f32 v[88:89], v[78:79], v[86:87], v[84:85] op_sel:[1,1,0] op_sel_hi:[1,0,1]
	v_pk_mul_f32 v[78:79], v[86:87], v[86:87] op_sel:[0,0] op_sel_hi:[0,1]
	v_pk_fma_f32 v[78:79], v[86:87], v[86:87], v[78:79] op_sel:[1,1,0] op_sel_hi:[1,0,1] neg_lo:[0,1,0]
	s_waitcnt lgkmcnt(0)
	v_pk_mul_f32 v[84:85], v[80:81], v[78:79] op_sel:[0,0] op_sel_hi:[0,1] neg_hi:[0,1]
	v_pk_fma_f32 v[90:91], v[80:81], v[78:79], v[84:85] op_sel:[1,1,0] op_sel_hi:[1,0,1]
	v_pk_mul_f32 v[80:81], v[78:79], v[86:87] op_sel:[0,0] op_sel_hi:[0,1]
	v_pk_fma_f32 v[84:85], v[78:79], v[86:87], v[80:81] op_sel:[1,1,0] op_sel_hi:[1,0,1] neg_lo:[0,1,0]
	ds_read2_b64 v[78:81], v134 offset0:68 offset1:85
	v_pk_mul_f32 v[92:93], v[82:83], v[84:85] op_sel:[0,0] op_sel_hi:[0,1] neg_hi:[0,1]
	v_pk_fma_f32 v[92:93], v[82:83], v[84:85], v[92:93] op_sel:[1,1,0] op_sel_hi:[1,0,1]
	v_pk_mul_f32 v[82:83], v[84:85], v[86:87] op_sel:[0,0] op_sel_hi:[0,1]
	v_pk_fma_f32 v[82:83], v[84:85], v[86:87], v[82:83] op_sel:[1,1,0] op_sel_hi:[1,0,1] neg_lo:[0,1,0]
	s_waitcnt lgkmcnt(0)
	v_pk_mul_f32 v[84:85], v[78:79], v[82:83] op_sel:[0,0] op_sel_hi:[0,1] neg_hi:[0,1]
	v_pk_fma_f32 v[94:95], v[78:79], v[82:83], v[84:85] op_sel:[1,1,0] op_sel_hi:[1,0,1]
	v_pk_mul_f32 v[78:79], v[82:83], v[86:87] op_sel:[0,0] op_sel_hi:[0,1]
	v_pk_fma_f32 v[78:79], v[82:83], v[86:87], v[78:79] op_sel:[1,1,0] op_sel_hi:[1,0,1] neg_lo:[0,1,0]
	ds_read2_b64 v[82:85], v134 offset0:102 offset1:119
	v_pk_mul_f32 v[96:97], v[80:81], v[78:79] op_sel:[0,0] op_sel_hi:[0,1] neg_hi:[0,1]
	v_pk_fma_f32 v[96:97], v[80:81], v[78:79], v[96:97] op_sel:[1,1,0] op_sel_hi:[1,0,1]
	v_pk_mul_f32 v[80:81], v[78:79], v[86:87] op_sel:[0,0] op_sel_hi:[0,1]
	v_pk_fma_f32 v[78:79], v[78:79], v[86:87], v[80:81] op_sel:[1,1,0] op_sel_hi:[1,0,1] neg_lo:[0,1,0]
	s_waitcnt lgkmcnt(0)
	v_pk_mul_f32 v[80:81], v[82:83], v[78:79] op_sel:[0,0] op_sel_hi:[0,1] neg_hi:[0,1]
	v_pk_fma_f32 v[98:99], v[82:83], v[78:79], v[80:81] op_sel:[1,1,0] op_sel_hi:[1,0,1]
	v_pk_mul_f32 v[80:81], v[78:79], v[86:87] op_sel:[0,0] op_sel_hi:[0,1]
	v_pk_fma_f32 v[82:83], v[78:79], v[86:87], v[80:81] op_sel:[1,1,0] op_sel_hi:[1,0,1] neg_lo:[0,1,0]
	ds_read2_b64 v[78:81], v134 offset0:136 offset1:153
	v_pk_mul_f32 v[100:101], v[84:85], v[82:83] op_sel:[0,0] op_sel_hi:[0,1] neg_hi:[0,1]
	v_pk_fma_f32 v[100:101], v[84:85], v[82:83], v[100:101] op_sel:[1,1,0] op_sel_hi:[1,0,1]
	v_pk_mul_f32 v[84:85], v[82:83], v[86:87] op_sel:[0,0] op_sel_hi:[0,1]
	v_pk_fma_f32 v[82:83], v[82:83], v[86:87], v[84:85] op_sel:[1,1,0] op_sel_hi:[1,0,1] neg_lo:[0,1,0]
	s_waitcnt lgkmcnt(0)
	v_pk_mul_f32 v[84:85], v[78:79], v[82:83] op_sel:[0,0] op_sel_hi:[0,1] neg_hi:[0,1]
	v_pk_fma_f32 v[102:103], v[78:79], v[82:83], v[84:85] op_sel:[1,1,0] op_sel_hi:[1,0,1]
	v_pk_mul_f32 v[78:79], v[82:83], v[86:87] op_sel:[0,0] op_sel_hi:[0,1]
	v_pk_fma_f32 v[78:79], v[82:83], v[86:87], v[78:79] op_sel:[1,1,0] op_sel_hi:[1,0,1] neg_lo:[0,1,0]
	ds_read2_b64 v[82:85], v134 offset0:170 offset1:187
	v_pk_mul_f32 v[104:105], v[80:81], v[78:79] op_sel:[0,0] op_sel_hi:[0,1] neg_hi:[0,1]
	v_pk_fma_f32 v[104:105], v[80:81], v[78:79], v[104:105] op_sel:[1,1,0] op_sel_hi:[1,0,1]
	v_pk_mul_f32 v[80:81], v[78:79], v[86:87] op_sel:[0,0] op_sel_hi:[0,1]
	v_pk_fma_f32 v[78:79], v[78:79], v[86:87], v[80:81] op_sel:[1,1,0] op_sel_hi:[1,0,1] neg_lo:[0,1,0]
	s_waitcnt lgkmcnt(0)
	v_pk_mul_f32 v[80:81], v[82:83], v[78:79] op_sel:[0,0] op_sel_hi:[0,1] neg_hi:[0,1]
	v_pk_fma_f32 v[106:107], v[82:83], v[78:79], v[80:81] op_sel:[1,1,0] op_sel_hi:[1,0,1]
	v_pk_mul_f32 v[80:81], v[78:79], v[86:87] op_sel:[0,0] op_sel_hi:[0,1]
	v_pk_fma_f32 v[82:83], v[78:79], v[86:87], v[80:81] op_sel:[1,1,0] op_sel_hi:[1,0,1] neg_lo:[0,1,0]
	ds_read2_b64 v[78:81], v134 offset0:204 offset1:221
	v_pk_mul_f32 v[110:111], v[84:85], v[82:83] op_sel:[0,0] op_sel_hi:[0,1] neg_hi:[0,1]
	v_pk_fma_f32 v[110:111], v[84:85], v[82:83], v[110:111] op_sel:[1,1,0] op_sel_hi:[1,0,1]
	v_pk_mul_f32 v[84:85], v[82:83], v[86:87] op_sel:[0,0] op_sel_hi:[0,1]
	v_pk_fma_f32 v[82:83], v[82:83], v[86:87], v[84:85] op_sel:[1,1,0] op_sel_hi:[1,0,1] neg_lo:[0,1,0]
	s_waitcnt lgkmcnt(0)
	v_pk_mul_f32 v[84:85], v[78:79], v[82:83] op_sel:[0,0] op_sel_hi:[0,1] neg_hi:[0,1]
	v_pk_fma_f32 v[78:79], v[78:79], v[82:83], v[84:85] op_sel:[1,1,0] op_sel_hi:[1,0,1]
	v_pk_mul_f32 v[84:85], v[82:83], v[86:87] op_sel:[0,0] op_sel_hi:[0,1]
	v_pk_fma_f32 v[112:113], v[82:83], v[86:87], v[84:85] op_sel:[1,1,0] op_sel_hi:[1,0,1] neg_lo:[0,1,0]
	ds_read2_b64 v[82:85], v134 offset0:238 offset1:255
	v_pk_mul_f32 v[114:115], v[80:81], v[112:113] op_sel:[0,0] op_sel_hi:[0,1] neg_hi:[0,1]
	v_pk_fma_f32 v[80:81], v[80:81], v[112:113], v[114:115] op_sel:[1,1,0] op_sel_hi:[1,0,1]
	v_pk_mul_f32 v[114:115], v[112:113], v[86:87] op_sel:[0,0] op_sel_hi:[0,1]
	v_pk_fma_f32 v[112:113], v[112:113], v[86:87], v[114:115] op_sel:[1,1,0] op_sel_hi:[1,0,1] neg_lo:[0,1,0]
	s_waitcnt lgkmcnt(0)
	v_pk_mul_f32 v[114:115], v[82:83], v[112:113] op_sel:[0,0] op_sel_hi:[0,1] neg_hi:[0,1]
	v_pk_fma_f32 v[82:83], v[82:83], v[112:113], v[114:115] op_sel:[1,1,0] op_sel_hi:[1,0,1]
	v_pk_mul_f32 v[114:115], v[112:113], v[86:87] op_sel:[0,0] op_sel_hi:[0,1]
	v_pk_fma_f32 v[86:87], v[112:113], v[86:87], v[114:115] op_sel:[1,1,0] op_sel_hi:[1,0,1] neg_lo:[0,1,0]
	v_pk_mul_f32 v[112:113], v[84:85], v[86:87] op_sel:[0,0] op_sel_hi:[0,1] neg_hi:[0,1]
	v_pk_fma_f32 v[84:85], v[84:85], v[86:87], v[112:113] op_sel:[1,1,0] op_sel_hi:[1,0,1]
	v_pk_add_f32 v[86:87], v[76:77], v[102:103]
	v_pk_add_f32 v[76:77], v[76:77], v[102:103] neg_lo:[0,1] neg_hi:[0,1]
	v_pk_add_f32 v[102:103], v[94:95], v[78:79]
	v_pk_add_f32 v[78:79], v[94:95], v[78:79] neg_lo:[0,1] neg_hi:[0,1]
	v_pk_add_f32 v[94:95], v[86:87], v[102:103]
	v_pk_add_f32 v[86:87], v[86:87], v[102:103] neg_lo:[0,1] neg_hi:[0,1]
	v_pk_add_f32 v[102:103], v[76:77], v[78:79] op_sel:[0,1] op_sel_hi:[1,0] neg_lo:[0,1]
	v_pk_add_f32 v[76:77], v[76:77], v[78:79] op_sel:[0,1] op_sel_hi:[1,0] neg_hi:[0,1]
	v_pk_add_f32 v[78:79], v[88:89], v[104:105]
	v_pk_add_f32 v[88:89], v[88:89], v[104:105] neg_lo:[0,1] neg_hi:[0,1]
	v_pk_add_f32 v[104:105], v[96:97], v[80:81]
	v_pk_add_f32 v[80:81], v[96:97], v[80:81] neg_lo:[0,1] neg_hi:[0,1]
	v_pk_add_f32 v[96:97], v[78:79], v[104:105]
	v_pk_add_f32 v[78:79], v[78:79], v[104:105] neg_lo:[0,1] neg_hi:[0,1]
	v_pk_add_f32 v[104:105], v[88:89], v[80:81] op_sel:[0,1] op_sel_hi:[1,0] neg_lo:[0,1]
	v_pk_add_f32 v[80:81], v[88:89], v[80:81] op_sel:[0,1] op_sel_hi:[1,0] neg_hi:[0,1]
	v_pk_add_f32 v[88:89], v[90:91], v[106:107]
	v_pk_add_f32 v[90:91], v[90:91], v[106:107] neg_lo:[0,1] neg_hi:[0,1]
	v_pk_add_f32 v[106:107], v[98:99], v[82:83]
	v_pk_add_f32 v[82:83], v[98:99], v[82:83] neg_lo:[0,1] neg_hi:[0,1]
	v_pk_add_f32 v[98:99], v[88:89], v[106:107]
	v_pk_add_f32 v[88:89], v[88:89], v[106:107] neg_lo:[0,1] neg_hi:[0,1]
	v_pk_add_f32 v[106:107], v[90:91], v[82:83] op_sel:[0,1] op_sel_hi:[1,0] neg_lo:[0,1]
	v_pk_add_f32 v[82:83], v[90:91], v[82:83] op_sel:[0,1] op_sel_hi:[1,0] neg_hi:[0,1]
	v_pk_add_f32 v[90:91], v[92:93], v[110:111]
	v_pk_add_f32 v[92:93], v[92:93], v[110:111] neg_lo:[0,1] neg_hi:[0,1]
	v_pk_add_f32 v[110:111], v[100:101], v[84:85]
	v_pk_add_f32 v[84:85], v[100:101], v[84:85] neg_lo:[0,1] neg_hi:[0,1]
	v_pk_add_f32 v[100:101], v[90:91], v[110:111]
	v_pk_add_f32 v[90:91], v[90:91], v[110:111] neg_lo:[0,1] neg_hi:[0,1]
	v_pk_add_f32 v[110:111], v[92:93], v[84:85] op_sel:[0,1] op_sel_hi:[1,0] neg_lo:[0,1]
	v_pk_add_f32 v[84:85], v[92:93], v[84:85] op_sel:[0,1] op_sel_hi:[1,0] neg_hi:[0,1]
	v_pk_mul_f32 v[92:93], v[104:105], s[58:59] op_sel:[0,0] op_sel_hi:[0,1]
	v_pk_fma_f32 v[92:93], v[104:105], s[58:59], v[92:93] op_sel:[1,1,0] op_sel_hi:[1,0,1] neg_lo:[0,1,0]
	v_pk_mul_f32 v[104:105], v[106:107], s[60:61] op_sel:[0,0] op_sel_hi:[0,1]
	v_pk_fma_f32 v[104:105], v[106:107], s[60:61], v[104:105] op_sel:[1,1,0] op_sel_hi:[1,0,1] neg_lo:[0,1,0]
	v_pk_mul_f32 v[106:107], v[110:111], s[62:63] op_sel:[0,0] op_sel_hi:[0,1]
	v_pk_fma_f32 v[106:107], v[110:111], s[62:63], v[106:107] op_sel:[1,1,0] op_sel_hi:[1,0,1] neg_lo:[0,1,0]
	v_pk_mul_f32 v[110:111], v[78:79], s[60:61] op_sel:[0,0] op_sel_hi:[0,1]
	v_pk_fma_f32 v[78:79], v[78:79], s[60:61], v[110:111] op_sel:[1,1,0] op_sel_hi:[1,0,1] neg_lo:[0,1,0]
	v_pk_mul_f32 v[110:111], v[88:89], s[64:65] op_sel:[0,0] op_sel_hi:[0,1]
	v_pk_fma_f32 v[88:89], v[88:89], s[64:65], v[110:111] op_sel:[1,1,0] op_sel_hi:[1,0,1] neg_lo:[0,1,0]
	v_pk_mul_f32 v[110:111], v[90:91], s[66:67] op_sel:[0,0] op_sel_hi:[0,1]
	v_pk_fma_f32 v[90:91], v[90:91], s[66:67], v[110:111] op_sel:[1,1,0] op_sel_hi:[1,0,1] neg_lo:[0,1,0]
	v_pk_mul_f32 v[110:111], v[80:81], s[62:63] op_sel:[0,0] op_sel_hi:[0,1]
	v_pk_fma_f32 v[80:81], v[80:81], s[62:63], v[110:111] op_sel:[1,1,0] op_sel_hi:[1,0,1] neg_lo:[0,1,0]
	v_pk_mul_f32 v[110:111], v[82:83], s[66:67] op_sel:[0,0] op_sel_hi:[0,1]
	v_pk_fma_f32 v[82:83], v[82:83], s[66:67], v[110:111] op_sel:[1,1,0] op_sel_hi:[1,0,1] neg_lo:[0,1,0]
	v_pk_mul_f32 v[110:111], v[84:85], s[68:69] op_sel:[0,0] op_sel_hi:[0,1]
	v_pk_fma_f32 v[84:85], v[84:85], s[68:69], v[110:111] op_sel:[1,1,0] op_sel_hi:[1,0,1] neg_lo:[0,1,0]
	v_pk_add_f32 v[110:111], v[94:95], v[98:99]
	v_pk_add_f32 v[94:95], v[94:95], v[98:99] neg_lo:[0,1] neg_hi:[0,1]
	v_pk_add_f32 v[98:99], v[96:97], v[100:101]
	v_pk_add_f32 v[96:97], v[96:97], v[100:101] neg_lo:[0,1] neg_hi:[0,1]
	v_pk_add_f32 v[100:101], v[110:111], v[98:99]
	v_pk_add_f32 v[98:99], v[110:111], v[98:99] neg_lo:[0,1] neg_hi:[0,1]
	v_pk_add_f32 v[110:111], v[94:95], v[96:97] op_sel:[0,1] op_sel_hi:[1,0] neg_lo:[0,1]
	v_pk_add_f32 v[94:95], v[94:95], v[96:97] op_sel:[0,1] op_sel_hi:[1,0] neg_hi:[0,1]
	v_pk_add_f32 v[96:97], v[102:103], v[104:105]
	v_pk_add_f32 v[102:103], v[102:103], v[104:105] neg_lo:[0,1] neg_hi:[0,1]
	v_pk_add_f32 v[104:105], v[92:93], v[106:107]
	v_pk_add_f32 v[92:93], v[92:93], v[106:107] neg_lo:[0,1] neg_hi:[0,1]
	v_pk_add_f32 v[106:107], v[96:97], v[104:105]
	v_pk_add_f32 v[96:97], v[96:97], v[104:105] neg_lo:[0,1] neg_hi:[0,1]
	v_pk_add_f32 v[104:105], v[102:103], v[92:93] op_sel:[0,1] op_sel_hi:[1,0] neg_lo:[0,1]
	v_pk_add_f32 v[92:93], v[102:103], v[92:93] op_sel:[0,1] op_sel_hi:[1,0] neg_hi:[0,1]
	v_pk_add_f32 v[102:103], v[86:87], v[88:89]
	v_pk_add_f32 v[86:87], v[86:87], v[88:89] neg_lo:[0,1] neg_hi:[0,1]
	v_pk_add_f32 v[88:89], v[78:79], v[90:91]
	v_pk_add_f32 v[78:79], v[78:79], v[90:91] neg_lo:[0,1] neg_hi:[0,1]
	v_pk_add_f32 v[90:91], v[102:103], v[88:89]
	v_pk_add_f32 v[88:89], v[102:103], v[88:89] neg_lo:[0,1] neg_hi:[0,1]
	v_pk_add_f32 v[102:103], v[86:87], v[78:79] op_sel:[0,1] op_sel_hi:[1,0] neg_lo:[0,1]
	v_pk_add_f32 v[78:79], v[86:87], v[78:79] op_sel:[0,1] op_sel_hi:[1,0] neg_hi:[0,1]
	v_pk_add_f32 v[86:87], v[76:77], v[82:83]
	v_pk_add_f32 v[76:77], v[76:77], v[82:83] neg_lo:[0,1] neg_hi:[0,1]
	v_pk_add_f32 v[82:83], v[80:81], v[84:85]
	v_pk_add_f32 v[80:81], v[80:81], v[84:85] neg_lo:[0,1] neg_hi:[0,1]
	v_pk_add_f32 v[84:85], v[86:87], v[82:83]
	v_pk_add_f32 v[82:83], v[86:87], v[82:83] neg_lo:[0,1] neg_hi:[0,1]
	v_pk_add_f32 v[86:87], v[76:77], v[80:81] op_sel:[0,1] op_sel_hi:[1,0] neg_lo:[0,1]
	v_pk_add_f32 v[76:77], v[76:77], v[80:81] op_sel:[0,1] op_sel_hi:[1,0] neg_hi:[0,1]
	ds_write2_b64 v134, v[100:101], v[106:107] offset1:17
	ds_write2_b64 v134, v[90:91], v[84:85] offset0:34 offset1:51
	ds_write2_b64 v134, v[110:111], v[104:105] offset0:68 offset1:85
	ds_write2_b64 v134, v[102:103], v[86:87] offset0:102 offset1:119
	ds_write2_b64 v134, v[98:99], v[96:97] offset0:136 offset1:153
	ds_write2_b64 v134, v[88:89], v[82:83] offset0:170 offset1:187
	ds_write2_b64 v134, v[94:95], v[92:93] offset0:204 offset1:221
	ds_write2_b64 v134, v[78:79], v[76:77] offset0:238 offset1:255
	v_mov_b32_e32 v77, v39
	v_mov_b32_e32 v76, v38
	s_waitcnt lgkmcnt(0)
	s_barrier
	ds_read_b64 v[78:79], v132 offset:2176
	ds_read_b64 v[80:81], v132 offset:4352
	ds_read_b64 v[82:83], v132 offset:6528
	ds_read_b64 v[84:85], v132
	s_waitcnt lgkmcnt(3)
	v_pk_mul_f32 v[86:87], v[78:79], v[76:77] op_sel:[0,0] op_sel_hi:[0,1] neg_hi:[0,1]
	v_pk_fma_f32 v[78:79], v[78:79], v[76:77], v[86:87] op_sel:[1,1,0] op_sel_hi:[1,0,1]
	v_pk_mul_f32 v[86:87], v[76:77], v[76:77] op_sel:[0,0] op_sel_hi:[0,1]
	ds_read_b64 v[90:91], v132 offset:8704
	v_pk_fma_f32 v[86:87], v[76:77], v[76:77], v[86:87] op_sel:[1,1,0] op_sel_hi:[1,0,1] neg_lo:[0,1,0]
	s_waitcnt lgkmcnt(3)
	v_pk_mul_f32 v[88:89], v[80:81], v[86:87] op_sel:[0,0] op_sel_hi:[0,1] neg_hi:[0,1]
	v_pk_fma_f32 v[80:81], v[80:81], v[86:87], v[88:89] op_sel:[1,1,0] op_sel_hi:[1,0,1]
	v_pk_mul_f32 v[88:89], v[86:87], v[76:77] op_sel:[0,0] op_sel_hi:[0,1]
	v_pk_fma_f32 v[86:87], v[86:87], v[76:77], v[88:89] op_sel:[1,1,0] op_sel_hi:[1,0,1] neg_lo:[0,1,0]
	s_waitcnt lgkmcnt(2)
	v_pk_mul_f32 v[88:89], v[82:83], v[86:87] op_sel:[0,0] op_sel_hi:[0,1] neg_hi:[0,1]
	v_pk_fma_f32 v[82:83], v[82:83], v[86:87], v[88:89] op_sel:[1,1,0] op_sel_hi:[1,0,1]
	v_pk_mul_f32 v[88:89], v[86:87], v[76:77] op_sel:[0,0] op_sel_hi:[0,1]
	v_pk_fma_f32 v[86:87], v[86:87], v[76:77], v[88:89] op_sel:[1,1,0] op_sel_hi:[1,0,1] neg_lo:[0,1,0]
	ds_read_b64 v[88:89], v132 offset:10880
	ds_read_b64 v[92:93], v132 offset:13056
	ds_read_b64 v[94:95], v132 offset:15232
	s_waitcnt lgkmcnt(3)
	v_pk_mul_f32 v[96:97], v[90:91], v[86:87] op_sel:[0,0] op_sel_hi:[0,1] neg_hi:[0,1]
	ds_read_b64 v[98:99], v132 offset:17408
	v_pk_fma_f32 v[90:91], v[90:91], v[86:87], v[96:97] op_sel:[1,1,0] op_sel_hi:[1,0,1]
	v_pk_mul_f32 v[96:97], v[86:87], v[76:77] op_sel:[0,0] op_sel_hi:[0,1]
	v_pk_fma_f32 v[86:87], v[86:87], v[76:77], v[96:97] op_sel:[1,1,0] op_sel_hi:[1,0,1] neg_lo:[0,1,0]
	s_waitcnt lgkmcnt(3)
	v_pk_mul_f32 v[96:97], v[88:89], v[86:87] op_sel:[0,0] op_sel_hi:[0,1] neg_hi:[0,1]
	v_pk_fma_f32 v[88:89], v[88:89], v[86:87], v[96:97] op_sel:[1,1,0] op_sel_hi:[1,0,1]
	v_pk_mul_f32 v[96:97], v[86:87], v[76:77] op_sel:[0,0] op_sel_hi:[0,1]
	v_pk_fma_f32 v[86:87], v[86:87], v[76:77], v[96:97] op_sel:[1,1,0] op_sel_hi:[1,0,1] neg_lo:[0,1,0]
	s_waitcnt lgkmcnt(2)
	v_pk_mul_f32 v[96:97], v[92:93], v[86:87] op_sel:[0,0] op_sel_hi:[0,1] neg_hi:[0,1]
	v_pk_fma_f32 v[92:93], v[92:93], v[86:87], v[96:97] op_sel:[1,1,0] op_sel_hi:[1,0,1]
	v_pk_mul_f32 v[96:97], v[86:87], v[76:77] op_sel:[0,0] op_sel_hi:[0,1]
	v_pk_fma_f32 v[86:87], v[86:87], v[76:77], v[96:97] op_sel:[1,1,0] op_sel_hi:[1,0,1] neg_lo:[0,1,0]
	s_waitcnt lgkmcnt(1)
	v_pk_mul_f32 v[96:97], v[94:95], v[86:87] op_sel:[0,0] op_sel_hi:[0,1] neg_hi:[0,1]
	v_pk_fma_f32 v[94:95], v[94:95], v[86:87], v[96:97] op_sel:[1,1,0] op_sel_hi:[1,0,1]
	v_pk_mul_f32 v[96:97], v[86:87], v[76:77] op_sel:[0,0] op_sel_hi:[0,1]
	v_pk_fma_f32 v[86:87], v[86:87], v[76:77], v[96:97] op_sel:[1,1,0] op_sel_hi:[1,0,1] neg_lo:[0,1,0]
	ds_read_b64 v[96:97], v132 offset:19584
	ds_read_b64 v[100:101], v132 offset:21760
	ds_read_b64 v[102:103], v132 offset:23936
	s_waitcnt lgkmcnt(3)
	v_pk_mul_f32 v[104:105], v[98:99], v[86:87] op_sel:[0,0] op_sel_hi:[0,1] neg_hi:[0,1]
	ds_read_b64 v[106:107], v132 offset:26112
	v_pk_fma_f32 v[98:99], v[98:99], v[86:87], v[104:105] op_sel:[1,1,0] op_sel_hi:[1,0,1]
	v_pk_mul_f32 v[104:105], v[86:87], v[76:77] op_sel:[0,0] op_sel_hi:[0,1]
	v_pk_fma_f32 v[86:87], v[86:87], v[76:77], v[104:105] op_sel:[1,1,0] op_sel_hi:[1,0,1] neg_lo:[0,1,0]
	s_waitcnt lgkmcnt(3)
	v_pk_mul_f32 v[104:105], v[96:97], v[86:87] op_sel:[0,0] op_sel_hi:[0,1] neg_hi:[0,1]
	v_pk_fma_f32 v[96:97], v[96:97], v[86:87], v[104:105] op_sel:[1,1,0] op_sel_hi:[1,0,1]
	v_pk_mul_f32 v[104:105], v[86:87], v[76:77] op_sel:[0,0] op_sel_hi:[0,1]
	v_pk_fma_f32 v[86:87], v[86:87], v[76:77], v[104:105] op_sel:[1,1,0] op_sel_hi:[1,0,1] neg_lo:[0,1,0]
	s_waitcnt lgkmcnt(2)
	v_pk_mul_f32 v[104:105], v[100:101], v[86:87] op_sel:[0,0] op_sel_hi:[0,1] neg_hi:[0,1]
	v_pk_fma_f32 v[100:101], v[100:101], v[86:87], v[104:105] op_sel:[1,1,0] op_sel_hi:[1,0,1]
	v_pk_mul_f32 v[104:105], v[86:87], v[76:77] op_sel:[0,0] op_sel_hi:[0,1]
	v_pk_fma_f32 v[86:87], v[86:87], v[76:77], v[104:105] op_sel:[1,1,0] op_sel_hi:[1,0,1] neg_lo:[0,1,0]
	s_waitcnt lgkmcnt(1)
	v_pk_mul_f32 v[104:105], v[102:103], v[86:87] op_sel:[0,0] op_sel_hi:[0,1] neg_hi:[0,1]
	v_pk_fma_f32 v[102:103], v[102:103], v[86:87], v[104:105] op_sel:[1,1,0] op_sel_hi:[1,0,1]
	v_pk_mul_f32 v[104:105], v[86:87], v[76:77] op_sel:[0,0] op_sel_hi:[0,1]
	v_pk_fma_f32 v[86:87], v[86:87], v[76:77], v[104:105] op_sel:[1,1,0] op_sel_hi:[1,0,1] neg_lo:[0,1,0]
	ds_read_b64 v[104:105], v132 offset:28288
	ds_read_b64 v[110:111], v132 offset:30464
	ds_read_b64 v[112:113], v132 offset:32640
	s_waitcnt lgkmcnt(3)
	v_pk_mul_f32 v[114:115], v[106:107], v[86:87] op_sel:[0,0] op_sel_hi:[0,1] neg_hi:[0,1]
	v_pk_fma_f32 v[106:107], v[106:107], v[86:87], v[114:115] op_sel:[1,1,0] op_sel_hi:[1,0,1]
	v_pk_mul_f32 v[114:115], v[86:87], v[76:77] op_sel:[0,0] op_sel_hi:[0,1]
	v_pk_fma_f32 v[86:87], v[86:87], v[76:77], v[114:115] op_sel:[1,1,0] op_sel_hi:[1,0,1] neg_lo:[0,1,0]
	s_waitcnt lgkmcnt(2)
	v_pk_mul_f32 v[114:115], v[104:105], v[86:87] op_sel:[0,0] op_sel_hi:[0,1] neg_hi:[0,1]
	v_pk_fma_f32 v[104:105], v[104:105], v[86:87], v[114:115] op_sel:[1,1,0] op_sel_hi:[1,0,1]
	v_pk_mul_f32 v[114:115], v[86:87], v[76:77] op_sel:[0,0] op_sel_hi:[0,1]
	v_pk_fma_f32 v[86:87], v[86:87], v[76:77], v[114:115] op_sel:[1,1,0] op_sel_hi:[1,0,1] neg_lo:[0,1,0]
	s_waitcnt lgkmcnt(1)
	v_pk_mul_f32 v[114:115], v[110:111], v[86:87] op_sel:[0,0] op_sel_hi:[0,1] neg_hi:[0,1]
	v_pk_fma_f32 v[110:111], v[110:111], v[86:87], v[114:115] op_sel:[1,1,0] op_sel_hi:[1,0,1]
	v_pk_mul_f32 v[114:115], v[86:87], v[76:77] op_sel:[0,0] op_sel_hi:[0,1]
	v_pk_fma_f32 v[76:77], v[86:87], v[76:77], v[114:115] op_sel:[1,1,0] op_sel_hi:[1,0,1] neg_lo:[0,1,0]
	s_waitcnt lgkmcnt(0)
	v_pk_mul_f32 v[86:87], v[112:113], v[76:77] op_sel:[0,0] op_sel_hi:[0,1] neg_hi:[0,1]
	v_pk_fma_f32 v[76:77], v[112:113], v[76:77], v[86:87] op_sel:[1,1,0] op_sel_hi:[1,0,1]
	v_pk_add_f32 v[86:87], v[84:85], v[98:99]
	v_pk_add_f32 v[84:85], v[84:85], v[98:99] neg_lo:[0,1] neg_hi:[0,1]
	v_pk_add_f32 v[98:99], v[90:91], v[106:107]
	v_pk_add_f32 v[90:91], v[90:91], v[106:107] neg_lo:[0,1] neg_hi:[0,1]
	v_pk_add_f32 v[106:107], v[86:87], v[98:99]
	v_pk_add_f32 v[98:99], v[86:87], v[98:99] neg_lo:[0,1] neg_hi:[0,1]
	v_pk_add_f32 v[86:87], v[84:85], v[90:91] op_sel:[0,1] op_sel_hi:[1,0] neg_lo:[0,1]
	v_pk_add_f32 v[112:113], v[84:85], v[90:91] op_sel:[0,1] op_sel_hi:[1,0] neg_hi:[0,1]
	v_pk_add_f32 v[84:85], v[78:79], v[96:97]
	v_pk_add_f32 v[78:79], v[78:79], v[96:97] neg_lo:[0,1] neg_hi:[0,1]
	v_pk_add_f32 v[90:91], v[88:89], v[104:105]
	v_pk_add_f32 v[88:89], v[88:89], v[104:105] neg_lo:[0,1] neg_hi:[0,1]
	v_pk_add_f32 v[96:97], v[84:85], v[90:91]
	v_pk_add_f32 v[84:85], v[84:85], v[90:91] neg_lo:[0,1] neg_hi:[0,1]
	v_pk_add_f32 v[90:91], v[78:79], v[88:89] op_sel:[0,1] op_sel_hi:[1,0] neg_lo:[0,1]
	v_pk_add_f32 v[78:79], v[78:79], v[88:89] op_sel:[0,1] op_sel_hi:[1,0] neg_hi:[0,1]
	v_pk_add_f32 v[88:89], v[80:81], v[100:101]
	v_pk_add_f32 v[80:81], v[80:81], v[100:101] neg_lo:[0,1] neg_hi:[0,1]
	v_pk_add_f32 v[100:101], v[92:93], v[110:111]
	v_pk_add_f32 v[92:93], v[92:93], v[110:111] neg_lo:[0,1] neg_hi:[0,1]
	v_pk_add_f32 v[104:105], v[88:89], v[100:101]
	v_pk_add_f32 v[88:89], v[88:89], v[100:101] neg_lo:[0,1] neg_hi:[0,1]
	v_pk_add_f32 v[100:101], v[80:81], v[92:93] op_sel:[0,1] op_sel_hi:[1,0] neg_lo:[0,1]
	v_pk_add_f32 v[80:81], v[80:81], v[92:93] op_sel:[0,1] op_sel_hi:[1,0] neg_hi:[0,1]
	v_pk_add_f32 v[92:93], v[82:83], v[102:103]
	v_pk_add_f32 v[82:83], v[82:83], v[102:103] neg_lo:[0,1] neg_hi:[0,1]
	v_pk_add_f32 v[102:103], v[94:95], v[76:77]
	v_pk_add_f32 v[76:77], v[94:95], v[76:77] neg_lo:[0,1] neg_hi:[0,1]
	v_pk_add_f32 v[94:95], v[92:93], v[102:103]
	v_pk_add_f32 v[92:93], v[92:93], v[102:103] neg_lo:[0,1] neg_hi:[0,1]
	v_pk_add_f32 v[102:103], v[82:83], v[76:77] op_sel:[0,1] op_sel_hi:[1,0] neg_lo:[0,1]
	v_pk_add_f32 v[76:77], v[82:83], v[76:77] op_sel:[0,1] op_sel_hi:[1,0] neg_hi:[0,1]
	v_pk_mul_f32 v[82:83], v[90:91], s[58:59] op_sel:[0,0] op_sel_hi:[0,1]
	v_pk_fma_f32 v[70:71], v[90:91], s[58:59], v[82:83] op_sel:[1,1,0] op_sel_hi:[1,0,1] neg_lo:[0,1,0]
	v_pk_mul_f32 v[82:83], v[100:101], s[60:61] op_sel:[0,0] op_sel_hi:[0,1]
	v_pk_mul_f32 v[90:91], v[102:103], s[62:63] op_sel:[0,0] op_sel_hi:[0,1]
	v_pk_fma_f32 v[82:83], v[100:101], s[60:61], v[82:83] op_sel:[1,1,0] op_sel_hi:[1,0,1] neg_lo:[0,1,0]
	v_pk_mul_f32 v[100:101], v[84:85], s[60:61] op_sel:[0,0] op_sel_hi:[0,1]
	v_pk_fma_f32 v[90:91], v[102:103], s[62:63], v[90:91] op_sel:[1,1,0] op_sel_hi:[1,0,1] neg_lo:[0,1,0]
	v_pk_fma_f32 v[110:111], v[84:85], s[60:61], v[100:101] op_sel:[1,1,0] op_sel_hi:[1,0,1] neg_lo:[0,1,0]
	v_pk_mul_f32 v[30:31], v[88:89], s[64:65] op_sel:[0,0] op_sel_hi:[0,1]
	v_pk_add_f32 v[84:85], v[70:71], v[90:91]
	v_pk_fma_f32 v[72:73], v[88:89], s[64:65], v[30:31] op_sel:[1,1,0] op_sel_hi:[1,0,1] neg_lo:[0,1,0]
	v_pk_mul_f32 v[30:31], v[92:93], s[66:67] op_sel:[0,0] op_sel_hi:[0,1]
	v_pk_fma_f32 v[88:89], v[92:93], s[66:67], v[30:31] op_sel:[1,1,0] op_sel_hi:[1,0,1] neg_lo:[0,1,0]
	v_pk_mul_f32 v[30:31], v[78:79], s[62:63] op_sel:[0,0] op_sel_hi:[0,1]
	v_pk_fma_f32 v[114:115], v[78:79], s[62:63], v[30:31] op_sel:[1,1,0] op_sel_hi:[1,0,1] neg_lo:[0,1,0]
	v_pk_mul_f32 v[28:29], v[80:81], s[66:67] op_sel:[0,0] op_sel_hi:[0,1]
	v_pk_add_f32 v[30:31], v[96:97], v[94:95] neg_lo:[0,1] neg_hi:[0,1]
	v_pk_fma_f32 v[116:117], v[80:81], s[66:67], v[28:29] op_sel:[1,1,0] op_sel_hi:[1,0,1] neg_lo:[0,1,0]
	v_pk_mul_f32 v[28:29], v[76:77], s[68:69] op_sel:[0,0] op_sel_hi:[0,1]
	v_pk_add_f32 v[32:33], v[70:71], v[90:91] neg_lo:[0,1] neg_hi:[0,1]
	v_pk_fma_f32 v[140:141], v[76:77], s[68:69], v[28:29] op_sel:[1,1,0] op_sel_hi:[1,0,1] neg_lo:[0,1,0]
	v_pk_add_f32 v[28:29], v[106:107], v[104:105] neg_lo:[0,1] neg_hi:[0,1]
	v_pk_add_f32 v[80:81], v[86:87], v[82:83]
	v_pk_add_f32 v[76:77], v[28:29], v[30:31] op_sel:[0,1] op_sel_hi:[1,0] neg_lo:[0,1]
	v_pk_add_f32 v[28:29], v[28:29], v[30:31] op_sel:[0,1] op_sel_hi:[1,0] neg_hi:[0,1]
	v_pk_add_f32 v[30:31], v[86:87], v[82:83] neg_lo:[0,1] neg_hi:[0,1]
	v_pk_add_f32 v[70:71], v[110:111], v[88:89] neg_lo:[0,1] neg_hi:[0,1]
	v_pk_add_f32 v[82:83], v[30:31], v[32:33] op_sel:[0,1] op_sel_hi:[1,0] neg_lo:[0,1]
	v_pk_add_f32 v[30:31], v[30:31], v[32:33] op_sel:[0,1] op_sel_hi:[1,0] neg_hi:[0,1]
	v_pk_add_f32 v[32:33], v[98:99], v[72:73] neg_lo:[0,1] neg_hi:[0,1]
	v_pk_add_f32 v[74:75], v[106:107], v[104:105]
	v_pk_add_f32 v[78:79], v[96:97], v[94:95]
	v_pk_add_f32 v[86:87], v[98:99], v[72:73]
	v_pk_add_f32 v[90:91], v[110:111], v[88:89]
	v_pk_add_f32 v[88:89], v[32:33], v[70:71] op_sel:[0,1] op_sel_hi:[1,0] neg_lo:[0,1]
	v_pk_add_f32 v[32:33], v[32:33], v[70:71] op_sel:[0,1] op_sel_hi:[1,0] neg_hi:[0,1]
	v_pk_add_f32 v[92:93], v[112:113], v[116:117]
	v_pk_add_f32 v[70:71], v[112:113], v[116:117] neg_lo:[0,1] neg_hi:[0,1]
	v_pk_add_f32 v[96:97], v[114:115], v[140:141]
	v_pk_add_f32 v[72:73], v[114:115], v[140:141] neg_lo:[0,1] neg_hi:[0,1]
	v_pk_add_f32 v[100:101], v[74:75], v[78:79]
	v_pk_add_f32 v[102:103], v[80:81], v[84:85]
	v_pk_add_f32 v[104:105], v[86:87], v[90:91]
	v_pk_add_f32 v[98:99], v[92:93], v[96:97]
	v_pk_add_f32 v[94:95], v[70:71], v[72:73] op_sel:[0,1] op_sel_hi:[1,0] neg_lo:[0,1]
	v_pk_add_f32 v[70:71], v[70:71], v[72:73] op_sel:[0,1] op_sel_hi:[1,0] neg_hi:[0,1]
	v_mov_b32_e32 v73, v37
	v_mov_b32_e32 v72, v36
	s_and_saveexec_b64 s[0:1], s[4:5]
	s_xor_b64 s[0:1], exec, s[0:1]
	s_cbranch_execz .LBB0_3402
	v_pk_mul_f32 v[110:111], v[72:73], s[12:13] op_sel:[0,0] op_sel_hi:[0,1]
	v_pk_fma_f32 v[106:107], v[72:73], s[12:13], v[110:111] op_sel:[1,1,0] op_sel_hi:[1,0,1] neg_lo:[0,1,0]
	v_pk_mul_f32 v[110:111], v[100:101], v[106:107] op_sel:[0,0] op_sel_hi:[0,1] neg_hi:[0,1]
	v_pk_fma_f32 v[100:101], v[100:101], v[106:107], v[110:111] op_sel:[1,1,0] op_sel_hi:[1,0,1]
	v_pk_mul_f32 v[110:111], v[72:73], s[16:17] op_sel:[0,0] op_sel_hi:[0,1]
	v_pk_fma_f32 v[106:107], v[72:73], s[16:17], v[110:111] op_sel:[1,1,0] op_sel_hi:[1,0,1] neg_lo:[0,1,0]
	v_pk_mul_f32 v[110:111], v[102:103], v[106:107] op_sel:[0,0] op_sel_hi:[0,1] neg_hi:[0,1]
	v_pk_fma_f32 v[102:103], v[102:103], v[106:107], v[110:111] op_sel:[1,1,0] op_sel_hi:[1,0,1]
	v_pk_mul_f32 v[110:111], v[72:73], s[20:21] op_sel:[0,0] op_sel_hi:[0,1]
	v_pk_fma_f32 v[106:107], v[72:73], s[20:21], v[110:111] op_sel:[1,1,0] op_sel_hi:[1,0,1] neg_lo:[0,1,0]
	v_pk_mul_f32 v[110:111], v[104:105], v[106:107] op_sel:[0,0] op_sel_hi:[0,1] neg_hi:[0,1]
	v_pk_fma_f32 v[104:105], v[104:105], v[106:107], v[110:111] op_sel:[1,1,0] op_sel_hi:[1,0,1]
	v_pk_mul_f32 v[110:111], v[72:73], s[22:23] op_sel:[0,0] op_sel_hi:[0,1]
	v_pk_fma_f32 v[106:107], v[72:73], s[22:23], v[110:111] op_sel:[1,1,0] op_sel_hi:[1,0,1] neg_lo:[0,1,0]
	v_pk_mul_f32 v[110:111], v[98:99], v[106:107] op_sel:[0,0] op_sel_hi:[0,1] neg_hi:[0,1]
	v_pk_fma_f32 v[98:99], v[98:99], v[106:107], v[110:111] op_sel:[1,1,0] op_sel_hi:[1,0,1]
	ds_write_b64 v132, v[100:101]
	ds_write_b64 v132, v[102:103] offset:2176
	ds_write_b64 v132, v[104:105] offset:4352
	ds_write_b64 v132, v[98:99] offset:6528
	v_pk_mul_f32 v[100:101], v[72:73], s[46:47] op_sel:[0,0] op_sel_hi:[0,1]
	s_nop 0
	v_pk_fma_f32 v[98:99], v[72:73], s[46:47], v[100:101] op_sel:[1,1,0] op_sel_hi:[1,0,1] neg_lo:[0,1,0]
	v_pk_mul_f32 v[100:101], v[76:77], v[98:99] op_sel:[0,0] op_sel_hi:[0,1] neg_hi:[0,1]
	v_pk_fma_f32 v[76:77], v[76:77], v[98:99], v[100:101] op_sel:[1,1,0] op_sel_hi:[1,0,1]
	v_pk_mul_f32 v[100:101], v[72:73], s[48:49] op_sel:[0,0] op_sel_hi:[0,1]
	v_pk_fma_f32 v[98:99], v[72:73], s[48:49], v[100:101] op_sel:[1,1,0] op_sel_hi:[1,0,1] neg_lo:[0,1,0]
	v_pk_mul_f32 v[100:101], v[82:83], v[98:99] op_sel:[0,0] op_sel_hi:[0,1] neg_hi:[0,1]
	v_pk_fma_f32 v[82:83], v[82:83], v[98:99], v[100:101] op_sel:[1,1,0] op_sel_hi:[1,0,1]
	v_pk_mul_f32 v[100:101], v[72:73], s[50:51] op_sel:[0,0] op_sel_hi:[0,1]
	v_pk_fma_f32 v[98:99], v[72:73], s[50:51], v[100:101] op_sel:[1,1,0] op_sel_hi:[1,0,1] neg_lo:[0,1,0]
	v_pk_mul_f32 v[100:101], v[88:89], v[98:99] op_sel:[0,0] op_sel_hi:[0,1] neg_hi:[0,1]
	v_pk_fma_f32 v[88:89], v[88:89], v[98:99], v[100:101] op_sel:[1,1,0] op_sel_hi:[1,0,1]
	v_pk_mul_f32 v[100:101], v[72:73], s[52:53] op_sel:[0,0] op_sel_hi:[0,1]
	v_pk_fma_f32 v[98:99], v[72:73], s[52:53], v[100:101] op_sel:[1,1,0] op_sel_hi:[1,0,1] neg_lo:[0,1,0]
	v_pk_mul_f32 v[100:101], v[94:95], v[98:99] op_sel:[0,0] op_sel_hi:[0,1] neg_hi:[0,1]
	s_nop 0
	v_pk_fma_f32 v[94:95], v[94:95], v[98:99], v[100:101] op_sel:[1,1,0] op_sel_hi:[1,0,1]

.LBB0_3404:
	s_or_b64 exec, exec, s[0:1]
	v_pk_add_f32 v[98:99], v[74:75], v[78:79] neg_lo:[0,1] neg_hi:[0,1]
	v_pk_add_f32 v[80:81], v[80:81], v[84:85] neg_lo:[0,1] neg_hi:[0,1]
	v_pk_add_f32 v[78:79], v[86:87], v[90:91] neg_lo:[0,1] neg_hi:[0,1]
	v_pk_add_f32 v[74:75], v[92:93], v[96:97] neg_lo:[0,1] neg_hi:[0,1]
	ds_write_b64 v132, v[76:77] offset:8704
	ds_write_b64 v132, v[82:83] offset:10880
	ds_write_b64 v132, v[88:89] offset:13056
	ds_write_b64 v132, v[94:95] offset:15232
	s_and_saveexec_b64 s[0:1], s[4:5]
	s_xor_b64 s[0:1], exec, s[0:1]
	s_cbranch_execz .LBB0_3406
	v_pk_mul_f32 v[82:83], v[72:73], s[8:9] op_sel:[0,0] op_sel_hi:[0,1]
	s_mov_b32 s15, s53
	v_pk_fma_f32 v[76:77], v[72:73], s[8:9], v[82:83] op_sel:[1,1,0] op_sel_hi:[1,0,1] neg_lo:[0,1,0]
	s_mov_b32 s6, s23
	v_pk_mul_f32 v[82:83], v[98:99], v[76:77] op_sel:[0,0] op_sel_hi:[0,1] neg_hi:[0,1]
	s_mov_b32 s7, s49
	v_pk_fma_f32 v[76:77], v[98:99], v[76:77], v[82:83] op_sel:[1,1,0] op_sel_hi:[1,0,1]
	v_pk_mul_f32 v[84:85], v[72:73], s[14:15] op_sel:[0,0] op_sel_hi:[0,1]
	s_nop 0
	v_pk_fma_f32 v[82:83], v[72:73], s[14:15], v[84:85] op_sel:[1,1,0] op_sel_hi:[1,0,1] neg_lo:[0,1,0]
	v_pk_mul_f32 v[84:85], v[80:81], v[82:83] op_sel:[0,0] op_sel_hi:[0,1] neg_hi:[0,1]
	v_pk_fma_f32 v[80:81], v[80:81], v[82:83], v[84:85] op_sel:[1,1,0] op_sel_hi:[1,0,1]
	v_pk_mul_f32 v[84:85], v[72:73], s[18:19] op_sel:[0,0] op_sel_hi:[0,1]
	v_pk_fma_f32 v[82:83], v[72:73], s[18:19], v[84:85] op_sel:[1,1,0] op_sel_hi:[1,0,1] neg_lo:[0,1,0]
	v_pk_mul_f32 v[84:85], v[78:79], v[82:83] op_sel:[0,0] op_sel_hi:[0,1] neg_hi:[0,1]
	v_pk_fma_f32 v[78:79], v[78:79], v[82:83], v[84:85] op_sel:[1,1,0] op_sel_hi:[1,0,1]
	v_mov_b64_e32 v[82:83], s[6:7]
	v_pk_mul_f32 v[84:85], v[72:73], v[82:83] op_sel:[0,0] op_sel_hi:[0,1]
	s_mov_b32 s6, s49
	v_pk_fma_f32 v[82:83], v[72:73], v[82:83], v[84:85] op_sel:[1,1,0] op_sel_hi:[1,0,1] neg_lo:[0,1,0]
	s_mov_b32 s7, s23
	v_pk_mul_f32 v[84:85], v[74:75], v[82:83] op_sel:[0,0] op_sel_hi:[0,1] neg_hi:[0,1]
	v_pk_fma_f32 v[74:75], v[74:75], v[82:83], v[84:85] op_sel:[1,1,0] op_sel_hi:[1,0,1]
	ds_write_b64 v132, v[76:77] offset:17408
	ds_write_b64 v132, v[80:81] offset:19584
	ds_write_b64 v132, v[78:79] offset:21760
	ds_write_b64 v132, v[74:75] offset:23936
	v_pk_mul_f32 v[76:77], v[72:73], s[54:55] op_sel:[0,0] op_sel_hi:[0,1]
	s_nop 0
	v_pk_fma_f32 v[74:75], v[72:73], s[54:55], v[76:77] op_sel:[1,1,0] op_sel_hi:[1,0,1] neg_lo:[0,1,0]
	v_pk_mul_f32 v[76:77], v[28:29], v[74:75] op_sel:[0,0] op_sel_hi:[0,1] neg_hi:[0,1]
	v_pk_fma_f32 v[28:29], v[28:29], v[74:75], v[76:77] op_sel:[1,1,0] op_sel_hi:[1,0,1]
	v_mov_b64_e32 v[74:75], s[6:7]
	v_pk_mul_f32 v[76:77], v[72:73], v[74:75] op_sel:[0,0] op_sel_hi:[0,1]
	s_mov_b32 s6, s53
	v_pk_fma_f32 v[74:75], v[72:73], v[74:75], v[76:77] op_sel:[1,1,0] op_sel_hi:[1,0,1] neg_lo:[0,1,0]
	s_mov_b32 s7, s14
	v_pk_mul_f32 v[76:77], v[30:31], v[74:75] op_sel:[0,0] op_sel_hi:[0,1] neg_hi:[0,1]
	v_pk_fma_f32 v[30:31], v[30:31], v[74:75], v[76:77] op_sel:[1,1,0] op_sel_hi:[1,0,1]
	v_pk_mul_f32 v[76:77], v[72:73], s[68:69] op_sel:[0,0] op_sel_hi:[0,1]
	v_pk_fma_f32 v[74:75], v[72:73], s[68:69], v[76:77] op_sel:[1,1,0] op_sel_hi:[1,0,1] neg_lo:[0,1,0]
	v_pk_mul_f32 v[76:77], v[32:33], v[74:75] op_sel:[0,0] op_sel_hi:[0,1] neg_hi:[0,1]
	v_pk_fma_f32 v[32:33], v[32:33], v[74:75], v[76:77] op_sel:[1,1,0] op_sel_hi:[1,0,1]
	v_pk_mul_f32 v[76:77], v[72:73], s[6:7] op_sel:[0,0] op_sel_hi:[0,1]
	v_pk_fma_f32 v[72:73], v[72:73], s[6:7], v[76:77] op_sel:[1,1,0] op_sel_hi:[1,0,1] neg_lo:[0,1,0]
	v_pk_mul_f32 v[74:75], v[70:71], v[72:73] op_sel:[0,0] op_sel_hi:[0,1] neg_hi:[0,1]
	s_nop 0
	v_pk_fma_f32 v[70:71], v[70:71], v[72:73], v[74:75] op_sel:[1,1,0] op_sel_hi:[1,0,1]

.LBB0_3412:
	s_andn2_b64 vcc, exec, s[0:1]
	s_cbranch_vccnz .LBB0_3480
	v_add_f32_e64 v27, |v42|, |v34|
	v_add_f32_e64 v27, |v44|, v27
	v_add_f32_e64 v27, |v46|, v27
	v_add_f32_e64 v27, |v50|, v27
	v_add_f32_e64 v27, |v54|, v27
	v_add_f32_e64 v27, |v48|, v27
	v_add_f32_e64 v27, |v52|, v27
	v_add_f32_e64 v27, |v56|, v27
	v_add_f32_e64 v27, |v58|, v27
	v_add_f32_e64 v27, |v60|, v27
	v_add_f32_e64 v27, |v62|, v27
	s_waitcnt vmcnt(13)
	v_and_b32_e32 v28, 64, v125
	v_add_f32_e64 v27, |v64|, v27
	v_add_u32_e32 v28, 64, v28
	v_xor_b32_e32 v29, 32, v125
	v_add_f32_e64 v27, |v66|, v27
	v_cmp_lt_i32_e32 vcc, v29, v28
	v_add_f32_e64 v27, |v68|, v27
	v_add_f32_e64 v27, |v26|, v27
	v_cndmask_b32_e32 v29, v125, v29, vcc
	v_lshlrev_b32_e32 v29, 2, v29
	ds_bpermute_b32 v29, v29, v27
	v_mov_b32_e32 v43, v35
	v_mov_b32_e32 v45, v35
	v_mov_b32_e32 v47, v35
	v_mov_b32_e32 v51, v35
	s_waitcnt lgkmcnt(0)
	v_add_f32_e32 v27, v27, v29
	v_xor_b32_e32 v29, 16, v125
	v_cmp_lt_i32_e32 vcc, v29, v28
	v_mov_b32_e32 v55, v35
	v_mov_b32_e32 v49, v35
	v_cndmask_b32_e32 v29, v125, v29, vcc
	v_lshlrev_b32_e32 v29, 2, v29
	ds_bpermute_b32 v29, v29, v27
	v_mov_b32_e32 v53, v35
	v_mov_b32_e32 v57, v35
	v_mov_b32_e32 v59, v35
	v_mov_b32_e32 v61, v35
	s_waitcnt lgkmcnt(0)
	v_add_f32_e32 v27, v27, v29
	v_xor_b32_e32 v29, 8, v125
	v_cmp_lt_i32_e32 vcc, v29, v28
	v_mov_b32_e32 v63, v35
	v_mov_b32_e32 v65, v35
	v_cndmask_b32_e32 v29, v125, v29, vcc
	v_lshlrev_b32_e32 v29, 2, v29
	ds_bpermute_b32 v29, v29, v27
	v_mov_b32_e32 v67, v35
	v_mov_b32_e32 v69, v35
	ds_write_b64 v132, v[34:35]
	ds_write_b64 v132, v[42:43] offset:2176
	s_waitcnt lgkmcnt(2)
	v_add_f32_e32 v27, v27, v29
	v_xor_b32_e32 v29, 4, v125
	v_cmp_lt_i32_e32 vcc, v29, v28
	ds_write_b64 v132, v[44:45] offset:4352
	ds_write_b64 v132, v[46:47] offset:6528
	v_cndmask_b32_e32 v29, v125, v29, vcc
	v_lshlrev_b32_e32 v29, 2, v29
	ds_bpermute_b32 v29, v29, v27
	ds_write_b64 v132, v[50:51] offset:8704
	ds_write_b64 v132, v[54:55] offset:10880
	ds_write_b64 v132, v[48:49] offset:13056
	ds_write_b64 v132, v[52:53] offset:15232
	s_waitcnt lgkmcnt(4)
	v_add_f32_e32 v29, v27, v29
	v_xor_b32_e32 v27, 2, v125
	v_cmp_lt_i32_e32 vcc, v27, v28
	ds_write_b64 v132, v[56:57] offset:17408
	ds_write_b64 v132, v[58:59] offset:19584
	v_cndmask_b32_e32 v27, v125, v27, vcc
	v_lshlrev_b32_e32 v27, 2, v27
	ds_bpermute_b32 v30, v27, v29
	v_mov_b32_e32 v27, v35
	ds_write_b64 v132, v[26:27] offset:32640
	v_xor_b32_e32 v27, 1, v125
	v_cmp_lt_i32_e32 vcc, v27, v28
	s_waitcnt lgkmcnt(1)
	v_add_f32_e32 v26, v29, v30
	v_mov_b32_e32 v28, v0
	v_cndmask_b32_e32 v27, v125, v27, vcc
	v_lshlrev_b32_e32 v27, 2, v27
	ds_bpermute_b32 v27, v27, v26
	ds_write_b64 v132, v[60:61] offset:21760
	ds_write_b64 v132, v[62:63] offset:23936
	ds_write_b64 v132, v[64:65] offset:26112
	ds_write_b64 v132, v[66:67] offset:28288
	ds_write_b64 v132, v[68:69] offset:30464
	s_waitcnt lgkmcnt(0)
	s_barrier
	s_nop 0
	v_and_b32_e32 v29, 63, v28
	v_cmp_eq_u32_e32 vcc, 0, v29
	s_and_saveexec_b64 s[0:1], vcc
	v_add_f32_e32 v26, v26, v27
	v_ashrrev_i32_e32 v27, 4, v28
	v_add_u32_e32 v27, 0, v27
	v_add_u32_e32 v27, 0x11000, v27
	ds_write_b32 v27, v26
	s_or_b64 exec, exec, s[0:1]
	s_add_i32 s0, 0, 0x11000
	v_mov_b32_e32 v26, s0
	v_mov_b32_e32 v44, v36
	v_mov_b32_e32 v45, v37
	s_waitcnt lgkmcnt(0)
	s_barrier
	s_waitcnt vmcnt(12)
	ds_read_b128 v[30:33], v26
	ds_read_b128 v[26:29], v26 offset:16
	ds_read_b64 v[46:47], v132
	ds_read_b64 v[48:49], v136
	s_and_saveexec_b64 s[0:1], s[4:5]
	s_xor_b64 s[0:1], exec, s[0:1]
	s_cbranch_execz .LBB0_3417
	v_pk_mul_f32 v[50:51], v[44:45], s[12:13] op_sel:[0,0] op_sel_hi:[0,1]
	s_waitcnt lgkmcnt(0)
	v_sub_f32_e32 v34, v48, v46
	v_pk_fma_f32 v[42:43], v[44:45], s[12:13], v[50:51] op_sel:[1,1,0] op_sel_hi:[1,0,1] neg_lo:[0,1,0]
	s_nop 0
	v_pk_mul_f32 v[42:43], v[34:35], v[42:43] op_sel_hi:[0,1]

.LBB0_3479:
	s_or_b64 exec, exec, s[0:1]
	v_mov_b32_e32 v44, v30
	v_mov_b32_e32 v45, v26
	v_mov_b32_e32 v26, v31
	v_mov_b32_e32 v30, v32
	v_mov_b32_e32 v31, v28
	v_mov_b32_e32 v28, v33
	v_pk_add_f32 v[26:27], v[44:45], v[26:27]
	v_pk_add_f32 v[28:29], v[30:31], v[28:29]
	v_pk_add_f32 v[30:31], v[52:53], v[68:69]
	v_pk_add_f32 v[26:27], v[26:27], v[28:29]
	v_pk_add_f32 v[28:29], v[42:43], v[60:61] neg_lo:[0,1] neg_hi:[0,1]
	v_add_f32_e32 v34, v26, v27
	v_pk_add_f32 v[26:27], v[42:43], v[60:61]
	v_pk_add_f32 v[32:33], v[52:53], v[68:69] neg_lo:[0,1] neg_hi:[0,1]
	v_pk_add_f32 v[52:53], v[26:27], v[30:31]
	v_pk_add_f32 v[60:61], v[26:27], v[30:31] neg_lo:[0,1] neg_hi:[0,1]
	v_pk_add_f32 v[68:69], v[28:29], v[32:33] op_sel:[0,1] op_sel_hi:[1,0] neg_hi:[0,1]
	s_waitcnt lgkmcnt(1)
	v_pk_add_f32 v[76:77], v[28:29], v[32:33] op_sel:[0,1] op_sel_hi:[1,0] neg_lo:[0,1]
	v_pk_add_f32 v[26:27], v[46:47], v[62:63]
	v_pk_add_f32 v[28:29], v[46:47], v[62:63] neg_lo:[0,1] neg_hi:[0,1]
	v_pk_add_f32 v[30:31], v[54:55], v[70:71]
	v_pk_add_f32 v[32:33], v[54:55], v[70:71] neg_lo:[0,1] neg_hi:[0,1]
	v_pk_add_f32 v[46:47], v[26:27], v[30:31]
	v_pk_add_f32 v[30:31], v[26:27], v[30:31] neg_lo:[0,1] neg_hi:[0,1]
	v_pk_add_f32 v[26:27], v[28:29], v[32:33] op_sel:[0,1] op_sel_hi:[1,0] neg_hi:[0,1]
	v_pk_add_f32 v[44:45], v[28:29], v[32:33] op_sel:[0,1] op_sel_hi:[1,0] neg_lo:[0,1]
	v_pk_add_f32 v[28:29], v[48:49], v[64:65]
	v_pk_add_f32 v[32:33], v[48:49], v[64:65] neg_lo:[0,1] neg_hi:[0,1]
	v_pk_add_f32 v[42:43], v[56:57], v[72:73]
	v_pk_add_f32 v[48:49], v[56:57], v[72:73] neg_lo:[0,1] neg_hi:[0,1]
	v_pk_add_f32 v[54:55], v[28:29], v[42:43]
	v_pk_add_f32 v[56:57], v[28:29], v[42:43] neg_lo:[0,1] neg_hi:[0,1]
	v_pk_add_f32 v[42:43], v[32:33], v[48:49] op_sel:[0,1] op_sel_hi:[1,0] neg_hi:[0,1]
	v_pk_add_f32 v[48:49], v[32:33], v[48:49] op_sel:[0,1] op_sel_hi:[1,0] neg_lo:[0,1]
	v_pk_add_f32 v[28:29], v[50:51], v[66:67]
	v_pk_add_f32 v[32:33], v[50:51], v[66:67] neg_lo:[0,1] neg_hi:[0,1]
	v_pk_add_f32 v[50:51], v[58:59], v[74:75]
	v_pk_add_f32 v[58:59], v[58:59], v[74:75] neg_lo:[0,1] neg_hi:[0,1]
	v_pk_add_f32 v[62:63], v[28:29], v[50:51]
	v_pk_add_f32 v[50:51], v[28:29], v[50:51] neg_lo:[0,1] neg_hi:[0,1]
	v_pk_add_f32 v[64:65], v[32:33], v[58:59] op_sel:[0,1] op_sel_hi:[1,0] neg_hi:[0,1]
	v_pk_add_f32 v[58:59], v[32:33], v[58:59] op_sel:[0,1] op_sel_hi:[1,0] neg_lo:[0,1]
	v_pk_mul_f32 v[28:29], v[26:27], s[20:21] op_sel:[0,0] op_sel_hi:[0,1]
	s_waitcnt lgkmcnt(0)
	v_pk_fma_f32 v[66:67], v[26:27], s[20:21], v[28:29] op_sel:[1,1,0] op_sel_hi:[1,0,1] neg_lo:[0,1,0]
	v_pk_mul_f32 v[26:27], v[42:43], s[46:47] op_sel:[0,0] op_sel_hi:[0,1]
	s_barrier
	v_pk_fma_f32 v[70:71], v[42:43], s[46:47], v[26:27] op_sel:[1,1,0] op_sel_hi:[1,0,1] neg_lo:[0,1,0]
	v_pk_mul_f32 v[42:43], v[64:65], s[50:51] op_sel:[0,0] op_sel_hi:[0,1]
	v_pk_fma_f32 v[64:65], v[64:65], s[50:51], v[42:43] op_sel:[1,1,0] op_sel_hi:[1,0,1] neg_lo:[0,1,0]
	v_pk_mul_f32 v[42:43], v[30:31], s[46:47] op_sel:[0,0] op_sel_hi:[0,1]
	v_pk_fma_f32 v[72:73], v[30:31], s[46:47], v[42:43] op_sel:[1,1,0] op_sel_hi:[1,0,1] neg_lo:[0,1,0]
	v_pk_mul_f32 v[30:31], v[56:57], s[8:9] op_sel:[0,0] op_sel_hi:[0,1]
	v_pk_fma_f32 v[56:57], v[56:57], s[8:9], v[30:31] op_sel:[1,1,0] op_sel_hi:[1,0,1] neg_lo:[0,1,0]
	v_pk_mul_f32 v[74:75], v[50:51], s[54:55] op_sel:[0,0] op_sel_hi:[0,1]
	v_pk_fma_f32 v[50:51], v[50:51], s[54:55], v[74:75] op_sel:[1,1,0] op_sel_hi:[1,0,1] neg_lo:[0,1,0]
	v_pk_mul_f32 v[74:75], v[44:45], s[50:51] op_sel:[0,0] op_sel_hi:[0,1]
	v_pk_fma_f32 v[74:75], v[44:45], s[50:51], v[74:75] op_sel:[1,1,0] op_sel_hi:[1,0,1] neg_lo:[0,1,0]
	v_pk_mul_f32 v[44:45], v[48:49], s[54:55] op_sel:[0,0] op_sel_hi:[0,1]
	v_pk_fma_f32 v[48:49], v[48:49], s[54:55], v[44:45] op_sel:[1,1,0] op_sel_hi:[1,0,1] neg_lo:[0,1,0]
	v_pk_mul_f32 v[78:79], v[58:59], s[56:57] op_sel:[0,0] op_sel_hi:[0,1]
	v_pk_fma_f32 v[58:59], v[58:59], s[56:57], v[78:79] op_sel:[1,1,0] op_sel_hi:[1,0,1] neg_lo:[0,1,0]
	v_pk_add_f32 v[78:79], v[52:53], v[54:55]
	v_pk_add_f32 v[52:53], v[52:53], v[54:55] neg_lo:[0,1] neg_hi:[0,1]
	v_pk_add_f32 v[54:55], v[46:47], v[62:63]
	v_pk_add_f32 v[46:47], v[46:47], v[62:63] neg_lo:[0,1] neg_hi:[0,1]
	v_pk_add_f32 v[62:63], v[78:79], v[54:55]
	v_pk_add_f32 v[54:55], v[78:79], v[54:55] neg_lo:[0,1] neg_hi:[0,1]
	v_pk_add_f32 v[78:79], v[52:53], v[46:47] op_sel:[0,1] op_sel_hi:[1,0] neg_hi:[0,1]
	v_pk_add_f32 v[46:47], v[52:53], v[46:47] op_sel:[0,1] op_sel_hi:[1,0] neg_lo:[0,1]
	v_pk_add_f32 v[52:53], v[68:69], v[70:71]
	v_pk_add_f32 v[68:69], v[68:69], v[70:71] neg_lo:[0,1] neg_hi:[0,1]
	v_pk_add_f32 v[70:71], v[66:67], v[64:65]
	v_pk_add_f32 v[64:65], v[66:67], v[64:65] neg_lo:[0,1] neg_hi:[0,1]
	v_pk_add_f32 v[66:67], v[52:53], v[70:71]
	v_pk_add_f32 v[52:53], v[52:53], v[70:71] neg_lo:[0,1] neg_hi:[0,1]
	v_pk_add_f32 v[70:71], v[68:69], v[64:65] op_sel:[0,1] op_sel_hi:[1,0] neg_hi:[0,1]
	v_pk_add_f32 v[64:65], v[68:69], v[64:65] op_sel:[0,1] op_sel_hi:[1,0] neg_lo:[0,1]
	v_pk_add_f32 v[68:69], v[60:61], v[56:57]
	v_pk_add_f32 v[56:57], v[60:61], v[56:57] neg_lo:[0,1] neg_hi:[0,1]
	v_pk_add_f32 v[60:61], v[72:73], v[50:51]
	v_pk_add_f32 v[50:51], v[72:73], v[50:51] neg_lo:[0,1] neg_hi:[0,1]
	v_pk_add_f32 v[72:73], v[68:69], v[60:61]
	v_pk_add_f32 v[60:61], v[68:69], v[60:61] neg_lo:[0,1] neg_hi:[0,1]
	v_pk_add_f32 v[68:69], v[56:57], v[50:51] op_sel:[0,1] op_sel_hi:[1,0] neg_hi:[0,1]
	v_pk_add_f32 v[50:51], v[56:57], v[50:51] op_sel:[0,1] op_sel_hi:[1,0] neg_lo:[0,1]
	v_pk_add_f32 v[56:57], v[76:77], v[48:49]
	v_pk_add_f32 v[48:49], v[76:77], v[48:49] neg_lo:[0,1] neg_hi:[0,1]
	v_pk_add_f32 v[76:77], v[74:75], v[58:59]
	v_pk_add_f32 v[58:59], v[74:75], v[58:59] neg_lo:[0,1] neg_hi:[0,1]
	v_pk_add_f32 v[74:75], v[56:57], v[76:77]
	v_pk_add_f32 v[56:57], v[56:57], v[76:77] neg_lo:[0,1] neg_hi:[0,1]
	v_pk_add_f32 v[76:77], v[48:49], v[58:59] op_sel:[0,1] op_sel_hi:[1,0] neg_hi:[0,1]
	v_pk_add_f32 v[48:49], v[48:49], v[58:59] op_sel:[0,1] op_sel_hi:[1,0] neg_lo:[0,1]
	v_mov_b32_e32 v58, v38
	v_mov_b32_e32 v59, v39
	ds_write_b64 v132, v[62:63]
	v_pk_mul_f32 v[62:63], v[66:67], v[58:59] op_sel:[0,0] op_sel_hi:[0,1]
	v_pk_fma_f32 v[62:63], v[66:67], v[58:59], v[62:63] op_sel:[1,1,0] op_sel_hi:[1,0,1] neg_lo:[0,1,0]
	ds_write_b64 v132, v[62:63] offset:2176
	v_pk_mul_f32 v[62:63], v[58:59], v[58:59] op_sel:[0,0] op_sel_hi:[0,1]
	v_pk_fma_f32 v[62:63], v[58:59], v[58:59], v[62:63] op_sel:[1,1,0] op_sel_hi:[1,0,1] neg_lo:[0,1,0]
	v_pk_mul_f32 v[66:67], v[72:73], v[62:63] op_sel:[0,0] op_sel_hi:[0,1]
	v_pk_fma_f32 v[66:67], v[72:73], v[62:63], v[66:67] op_sel:[1,1,0] op_sel_hi:[1,0,1] neg_lo:[0,1,0]
	ds_write_b64 v132, v[66:67] offset:4352
	v_pk_mul_f32 v[66:67], v[62:63], v[58:59] op_sel:[0,0] op_sel_hi:[0,1]
	v_pk_fma_f32 v[62:63], v[62:63], v[58:59], v[66:67] op_sel:[1,1,0] op_sel_hi:[1,0,1] neg_lo:[0,1,0]
	v_pk_mul_f32 v[66:67], v[74:75], v[62:63] op_sel:[0,0] op_sel_hi:[0,1]
	v_pk_fma_f32 v[66:67], v[74:75], v[62:63], v[66:67] op_sel:[1,1,0] op_sel_hi:[1,0,1] neg_lo:[0,1,0]
	ds_write_b64 v132, v[66:67] offset:6528
	v_pk_mul_f32 v[66:67], v[62:63], v[58:59] op_sel:[0,0] op_sel_hi:[0,1]
	v_pk_fma_f32 v[62:63], v[62:63], v[58:59], v[66:67] op_sel:[1,1,0] op_sel_hi:[1,0,1] neg_lo:[0,1,0]
	v_pk_mul_f32 v[66:67], v[78:79], v[62:63] op_sel:[0,0] op_sel_hi:[0,1]
	v_pk_fma_f32 v[66:67], v[78:79], v[62:63], v[66:67] op_sel:[1,1,0] op_sel_hi:[1,0,1] neg_lo:[0,1,0]
	ds_write_b64 v132, v[66:67] offset:8704
	v_pk_mul_f32 v[66:67], v[62:63], v[58:59] op_sel:[0,0] op_sel_hi:[0,1]
	v_pk_fma_f32 v[62:63], v[62:63], v[58:59], v[66:67] op_sel:[1,1,0] op_sel_hi:[1,0,1] neg_lo:[0,1,0]
	v_pk_mul_f32 v[66:67], v[70:71], v[62:63] op_sel:[0,0] op_sel_hi:[0,1]
	v_pk_fma_f32 v[66:67], v[70:71], v[62:63], v[66:67] op_sel:[1,1,0] op_sel_hi:[1,0,1] neg_lo:[0,1,0]
	ds_write_b64 v132, v[66:67] offset:10880
	v_pk_mul_f32 v[66:67], v[62:63], v[58:59] op_sel:[0,0] op_sel_hi:[0,1]
	v_pk_fma_f32 v[62:63], v[62:63], v[58:59], v[66:67] op_sel:[1,1,0] op_sel_hi:[1,0,1] neg_lo:[0,1,0]
	v_pk_mul_f32 v[66:67], v[68:69], v[62:63] op_sel:[0,0] op_sel_hi:[0,1]
	v_pk_fma_f32 v[66:67], v[68:69], v[62:63], v[66:67] op_sel:[1,1,0] op_sel_hi:[1,0,1] neg_lo:[0,1,0]
	ds_write_b64 v132, v[66:67] offset:13056
	v_pk_mul_f32 v[66:67], v[62:63], v[58:59] op_sel:[0,0] op_sel_hi:[0,1]
	v_pk_fma_f32 v[62:63], v[62:63], v[58:59], v[66:67] op_sel:[1,1,0] op_sel_hi:[1,0,1] neg_lo:[0,1,0]
	v_pk_mul_f32 v[66:67], v[76:77], v[62:63] op_sel:[0,0] op_sel_hi:[0,1]
	v_pk_fma_f32 v[66:67], v[76:77], v[62:63], v[66:67] op_sel:[1,1,0] op_sel_hi:[1,0,1] neg_lo:[0,1,0]
	ds_write_b64 v132, v[66:67] offset:15232
	v_pk_mul_f32 v[66:67], v[62:63], v[58:59] op_sel:[0,0] op_sel_hi:[0,1]
	v_pk_fma_f32 v[62:63], v[62:63], v[58:59], v[66:67] op_sel:[1,1,0] op_sel_hi:[1,0,1] neg_lo:[0,1,0]
	v_pk_mul_f32 v[66:67], v[54:55], v[62:63] op_sel:[0,0] op_sel_hi:[0,1]
	v_pk_fma_f32 v[54:55], v[54:55], v[62:63], v[66:67] op_sel:[1,1,0] op_sel_hi:[1,0,1] neg_lo:[0,1,0]
	ds_write_b64 v132, v[54:55] offset:17408
	v_pk_mul_f32 v[54:55], v[62:63], v[58:59] op_sel:[0,0] op_sel_hi:[0,1]
	v_pk_fma_f32 v[54:55], v[62:63], v[58:59], v[54:55] op_sel:[1,1,0] op_sel_hi:[1,0,1] neg_lo:[0,1,0]
	v_pk_mul_f32 v[62:63], v[52:53], v[54:55] op_sel:[0,0] op_sel_hi:[0,1]
	v_pk_fma_f32 v[52:53], v[52:53], v[54:55], v[62:63] op_sel:[1,1,0] op_sel_hi:[1,0,1] neg_lo:[0,1,0]
	ds_write_b64 v132, v[52:53] offset:19584
	v_pk_mul_f32 v[52:53], v[54:55], v[58:59] op_sel:[0,0] op_sel_hi:[0,1]
	v_pk_fma_f32 v[52:53], v[54:55], v[58:59], v[52:53] op_sel:[1,1,0] op_sel_hi:[1,0,1] neg_lo:[0,1,0]
	v_pk_mul_f32 v[54:55], v[60:61], v[52:53] op_sel:[0,0] op_sel_hi:[0,1]
	v_pk_fma_f32 v[54:55], v[60:61], v[52:53], v[54:55] op_sel:[1,1,0] op_sel_hi:[1,0,1] neg_lo:[0,1,0]
	ds_write_b64 v132, v[54:55] offset:21760
	v_pk_mul_f32 v[54:55], v[52:53], v[58:59] op_sel:[0,0] op_sel_hi:[0,1]
	v_pk_fma_f32 v[52:53], v[52:53], v[58:59], v[54:55] op_sel:[1,1,0] op_sel_hi:[1,0,1] neg_lo:[0,1,0]
	v_pk_mul_f32 v[54:55], v[56:57], v[52:53] op_sel:[0,0] op_sel_hi:[0,1]
	v_pk_fma_f32 v[54:55], v[56:57], v[52:53], v[54:55] op_sel:[1,1,0] op_sel_hi:[1,0,1] neg_lo:[0,1,0]
	ds_write_b64 v132, v[54:55] offset:23936
	v_pk_mul_f32 v[54:55], v[52:53], v[58:59] op_sel:[0,0] op_sel_hi:[0,1]
	v_pk_fma_f32 v[52:53], v[52:53], v[58:59], v[54:55] op_sel:[1,1,0] op_sel_hi:[1,0,1] neg_lo:[0,1,0]
	v_pk_mul_f32 v[54:55], v[46:47], v[52:53] op_sel:[0,0] op_sel_hi:[0,1]
	v_pk_fma_f32 v[46:47], v[46:47], v[52:53], v[54:55] op_sel:[1,1,0] op_sel_hi:[1,0,1] neg_lo:[0,1,0]
	ds_write_b64 v132, v[46:47] offset:26112
	v_pk_mul_f32 v[46:47], v[52:53], v[58:59] op_sel:[0,0] op_sel_hi:[0,1]
	v_pk_fma_f32 v[46:47], v[52:53], v[58:59], v[46:47] op_sel:[1,1,0] op_sel_hi:[1,0,1] neg_lo:[0,1,0]
	v_pk_mul_f32 v[52:53], v[64:65], v[46:47] op_sel:[0,0] op_sel_hi:[0,1]
	v_pk_fma_f32 v[52:53], v[64:65], v[46:47], v[52:53] op_sel:[1,1,0] op_sel_hi:[1,0,1] neg_lo:[0,1,0]
	ds_write_b64 v132, v[52:53] offset:28288
	v_pk_mul_f32 v[52:53], v[46:47], v[58:59] op_sel:[0,0] op_sel_hi:[0,1]
	v_pk_fma_f32 v[46:47], v[46:47], v[58:59], v[52:53] op_sel:[1,1,0] op_sel_hi:[1,0,1] neg_lo:[0,1,0]
	v_pk_mul_f32 v[52:53], v[50:51], v[46:47] op_sel:[0,0] op_sel_hi:[0,1]
	v_pk_fma_f32 v[50:51], v[50:51], v[46:47], v[52:53] op_sel:[1,1,0] op_sel_hi:[1,0,1] neg_lo:[0,1,0]
	ds_write_b64 v132, v[50:51] offset:30464
	v_pk_mul_f32 v[50:51], v[46:47], v[58:59] op_sel:[0,0] op_sel_hi:[0,1]
	v_pk_fma_f32 v[46:47], v[46:47], v[58:59], v[50:51] op_sel:[1,1,0] op_sel_hi:[1,0,1] neg_lo:[0,1,0]
	v_pk_mul_f32 v[50:51], v[48:49], v[46:47] op_sel:[0,0] op_sel_hi:[0,1]
	v_pk_fma_f32 v[46:47], v[48:49], v[46:47], v[50:51] op_sel:[1,1,0] op_sel_hi:[1,0,1] neg_lo:[0,1,0]
	ds_write_b64 v132, v[46:47] offset:32640
	s_waitcnt lgkmcnt(0)
	s_barrier
	ds_read2_b64 v[46:49], v134 offset1:17
	ds_read2_b64 v[50:53], v134 offset0:34 offset1:51
	ds_read2_b64 v[54:57], v134 offset0:68 offset1:85
	ds_read2_b64 v[58:61], v134 offset0:136 offset1:153
	ds_read2_b64 v[62:65], v134 offset0:102 offset1:119
	ds_read2_b64 v[66:69], v134 offset0:204 offset1:221
	ds_read2_b64 v[70:73], v134 offset0:170 offset1:187
	ds_read2_b64 v[74:77], v134 offset0:238 offset1:255
	s_waitcnt lgkmcnt(4)
	v_pk_add_f32 v[78:79], v[46:47], v[58:59]
	v_pk_add_f32 v[46:47], v[46:47], v[58:59] neg_lo:[0,1] neg_hi:[0,1]
	s_waitcnt lgkmcnt(2)
	v_pk_add_f32 v[58:59], v[54:55], v[66:67]
	v_pk_add_f32 v[54:55], v[54:55], v[66:67] neg_lo:[0,1] neg_hi:[0,1]
	v_pk_add_f32 v[66:67], v[78:79], v[58:59]
	v_pk_add_f32 v[58:59], v[78:79], v[58:59] neg_lo:[0,1] neg_hi:[0,1]
	v_pk_add_f32 v[78:79], v[46:47], v[54:55] op_sel:[0,1] op_sel_hi:[1,0] neg_hi:[0,1]
	v_pk_add_f32 v[46:47], v[46:47], v[54:55] op_sel:[0,1] op_sel_hi:[1,0] neg_lo:[0,1]
	v_pk_add_f32 v[54:55], v[48:49], v[60:61]
	v_pk_add_f32 v[48:49], v[48:49], v[60:61] neg_lo:[0,1] neg_hi:[0,1]
	v_pk_add_f32 v[60:61], v[56:57], v[68:69]
	v_pk_add_f32 v[56:57], v[56:57], v[68:69] neg_lo:[0,1] neg_hi:[0,1]
	v_pk_add_f32 v[68:69], v[54:55], v[60:61]
	v_pk_add_f32 v[54:55], v[54:55], v[60:61] neg_lo:[0,1] neg_hi:[0,1]
	v_pk_add_f32 v[60:61], v[48:49], v[56:57] op_sel:[0,1] op_sel_hi:[1,0] neg_hi:[0,1]
	v_pk_add_f32 v[48:49], v[48:49], v[56:57] op_sel:[0,1] op_sel_hi:[1,0] neg_lo:[0,1]
	s_waitcnt lgkmcnt(1)
	v_pk_add_f32 v[56:57], v[50:51], v[70:71]
	v_pk_add_f32 v[50:51], v[50:51], v[70:71] neg_lo:[0,1] neg_hi:[0,1]
	s_waitcnt lgkmcnt(0)
	v_pk_add_f32 v[70:71], v[62:63], v[74:75]
	v_pk_add_f32 v[62:63], v[62:63], v[74:75] neg_lo:[0,1] neg_hi:[0,1]
	v_pk_add_f32 v[74:75], v[56:57], v[70:71]
	v_pk_add_f32 v[56:57], v[56:57], v[70:71] neg_lo:[0,1] neg_hi:[0,1]
	v_pk_add_f32 v[70:71], v[50:51], v[62:63] op_sel:[0,1] op_sel_hi:[1,0] neg_hi:[0,1]
	v_pk_add_f32 v[50:51], v[50:51], v[62:63] op_sel:[0,1] op_sel_hi:[1,0] neg_lo:[0,1]
	v_pk_add_f32 v[62:63], v[52:53], v[72:73]
	v_pk_add_f32 v[52:53], v[52:53], v[72:73] neg_lo:[0,1] neg_hi:[0,1]
	v_pk_add_f32 v[72:73], v[64:65], v[76:77]
	v_pk_add_f32 v[64:65], v[64:65], v[76:77] neg_lo:[0,1] neg_hi:[0,1]
	v_pk_add_f32 v[76:77], v[62:63], v[72:73]
	v_pk_add_f32 v[62:63], v[62:63], v[72:73] neg_lo:[0,1] neg_hi:[0,1]
	v_pk_add_f32 v[72:73], v[52:53], v[64:65] op_sel:[0,1] op_sel_hi:[1,0] neg_hi:[0,1]
	v_pk_add_f32 v[52:53], v[52:53], v[64:65] op_sel:[0,1] op_sel_hi:[1,0] neg_lo:[0,1]
	v_pk_mul_f32 v[64:65], v[60:61], s[20:21] op_sel:[0,0] op_sel_hi:[0,1]
	v_pk_fma_f32 v[60:61], v[60:61], s[20:21], v[64:65] op_sel:[1,1,0] op_sel_hi:[1,0,1] neg_lo:[0,1,0]
	v_pk_mul_f32 v[64:65], v[70:71], s[46:47] op_sel:[0,0] op_sel_hi:[0,1]
	v_pk_fma_f32 v[64:65], v[70:71], s[46:47], v[64:65] op_sel:[1,1,0] op_sel_hi:[1,0,1] neg_lo:[0,1,0]
	v_pk_mul_f32 v[70:71], v[72:73], s[50:51] op_sel:[0,0] op_sel_hi:[0,1]
	v_pk_fma_f32 v[70:71], v[72:73], s[50:51], v[70:71] op_sel:[1,1,0] op_sel_hi:[1,0,1] neg_lo:[0,1,0]
	v_pk_mul_f32 v[72:73], v[54:55], s[46:47] op_sel:[0,0] op_sel_hi:[0,1]
	v_pk_fma_f32 v[54:55], v[54:55], s[46:47], v[72:73] op_sel:[1,1,0] op_sel_hi:[1,0,1] neg_lo:[0,1,0]
	v_pk_mul_f32 v[72:73], v[56:57], s[8:9] op_sel:[0,0] op_sel_hi:[0,1]
	v_pk_fma_f32 v[56:57], v[56:57], s[8:9], v[72:73] op_sel:[1,1,0] op_sel_hi:[1,0,1] neg_lo:[0,1,0]
	v_pk_mul_f32 v[72:73], v[62:63], s[54:55] op_sel:[0,0] op_sel_hi:[0,1]
	v_pk_fma_f32 v[62:63], v[62:63], s[54:55], v[72:73] op_sel:[1,1,0] op_sel_hi:[1,0,1] neg_lo:[0,1,0]
	v_pk_mul_f32 v[72:73], v[48:49], s[50:51] op_sel:[0,0] op_sel_hi:[0,1]
	v_pk_fma_f32 v[48:49], v[48:49], s[50:51], v[72:73] op_sel:[1,1,0] op_sel_hi:[1,0,1] neg_lo:[0,1,0]
	v_pk_mul_f32 v[72:73], v[50:51], s[54:55] op_sel:[0,0] op_sel_hi:[0,1]
	v_pk_fma_f32 v[50:51], v[50:51], s[54:55], v[72:73] op_sel:[1,1,0] op_sel_hi:[1,0,1] neg_lo:[0,1,0]
	v_pk_mul_f32 v[72:73], v[52:53], s[56:57] op_sel:[0,0] op_sel_hi:[0,1]
	v_pk_fma_f32 v[52:53], v[52:53], s[56:57], v[72:73] op_sel:[1,1,0] op_sel_hi:[1,0,1] neg_lo:[0,1,0]
	v_pk_add_f32 v[72:73], v[66:67], v[74:75]
	v_pk_add_f32 v[66:67], v[66:67], v[74:75] neg_lo:[0,1] neg_hi:[0,1]
	v_pk_add_f32 v[74:75], v[68:69], v[76:77]
	v_pk_add_f32 v[68:69], v[68:69], v[76:77] neg_lo:[0,1] neg_hi:[0,1]
	v_pk_add_f32 v[76:77], v[72:73], v[74:75]
	v_pk_add_f32 v[72:73], v[72:73], v[74:75] neg_lo:[0,1] neg_hi:[0,1]
	v_pk_add_f32 v[74:75], v[66:67], v[68:69] op_sel:[0,1] op_sel_hi:[1,0] neg_hi:[0,1]
	v_pk_add_f32 v[66:67], v[66:67], v[68:69] op_sel:[0,1] op_sel_hi:[1,0] neg_lo:[0,1]
	v_pk_add_f32 v[68:69], v[78:79], v[64:65]
	v_pk_add_f32 v[64:65], v[78:79], v[64:65] neg_lo:[0,1] neg_hi:[0,1]
	v_pk_add_f32 v[78:79], v[60:61], v[70:71]
	v_pk_add_f32 v[60:61], v[60:61], v[70:71] neg_lo:[0,1] neg_hi:[0,1]
	v_pk_add_f32 v[70:71], v[68:69], v[78:79]
	v_pk_add_f32 v[68:69], v[68:69], v[78:79] neg_lo:[0,1] neg_hi:[0,1]
	v_pk_add_f32 v[78:79], v[64:65], v[60:61] op_sel:[0,1] op_sel_hi:[1,0] neg_hi:[0,1]
	v_pk_add_f32 v[60:61], v[64:65], v[60:61] op_sel:[0,1] op_sel_hi:[1,0] neg_lo:[0,1]
	v_pk_add_f32 v[64:65], v[58:59], v[56:57]
	v_pk_add_f32 v[56:57], v[58:59], v[56:57] neg_lo:[0,1] neg_hi:[0,1]
	v_pk_add_f32 v[58:59], v[54:55], v[62:63]
	v_pk_add_f32 v[54:55], v[54:55], v[62:63] neg_lo:[0,1] neg_hi:[0,1]
	v_pk_add_f32 v[62:63], v[64:65], v[58:59]
	v_pk_add_f32 v[58:59], v[64:65], v[58:59] neg_lo:[0,1] neg_hi:[0,1]
	v_pk_add_f32 v[64:65], v[56:57], v[54:55] op_sel:[0,1] op_sel_hi:[1,0] neg_hi:[0,1]
	v_pk_add_f32 v[54:55], v[56:57], v[54:55] op_sel:[0,1] op_sel_hi:[1,0] neg_lo:[0,1]
	v_pk_add_f32 v[56:57], v[46:47], v[50:51]
	v_pk_add_f32 v[46:47], v[46:47], v[50:51] neg_lo:[0,1] neg_hi:[0,1]
	v_pk_add_f32 v[50:51], v[48:49], v[52:53]
	v_pk_add_f32 v[48:49], v[48:49], v[52:53] neg_lo:[0,1] neg_hi:[0,1]
	v_pk_add_f32 v[52:53], v[56:57], v[50:51]
	v_pk_add_f32 v[50:51], v[56:57], v[50:51] neg_lo:[0,1] neg_hi:[0,1]
	v_pk_add_f32 v[56:57], v[46:47], v[48:49] op_sel:[0,1] op_sel_hi:[1,0] neg_hi:[0,1]
	v_pk_add_f32 v[46:47], v[46:47], v[48:49] op_sel:[0,1] op_sel_hi:[1,0] neg_lo:[0,1]
	v_mov_b32_e32 v48, v40
	v_mov_b32_e32 v49, v41
	s_waitcnt vmcnt(5)
	v_pk_mul_f32 v[80:81], v[70:71], v[48:49] op_sel:[0,0] op_sel_hi:[0,1]
	v_pk_fma_f32 v[70:71], v[70:71], v[48:49], v[80:81] op_sel:[1,1,0] op_sel_hi:[1,0,1] neg_lo:[0,1,0]
	ds_write2_b64 v134, v[76:77], v[70:71] offset1:17
	v_pk_mul_f32 v[70:71], v[48:49], v[48:49] op_sel:[0,0] op_sel_hi:[0,1]
	v_pk_fma_f32 v[70:71], v[48:49], v[48:49], v[70:71] op_sel:[1,1,0] op_sel_hi:[1,0,1] neg_lo:[0,1,0]
	v_pk_mul_f32 v[76:77], v[62:63], v[70:71] op_sel:[0,0] op_sel_hi:[0,1]
	v_pk_fma_f32 v[62:63], v[62:63], v[70:71], v[76:77] op_sel:[1,1,0] op_sel_hi:[1,0,1] neg_lo:[0,1,0]
	v_pk_mul_f32 v[76:77], v[70:71], v[48:49] op_sel:[0,0] op_sel_hi:[0,1]
	v_pk_fma_f32 v[70:71], v[70:71], v[48:49], v[76:77] op_sel:[1,1,0] op_sel_hi:[1,0,1] neg_lo:[0,1,0]
	v_pk_mul_f32 v[76:77], v[52:53], v[70:71] op_sel:[0,0] op_sel_hi:[0,1]
	v_pk_fma_f32 v[52:53], v[52:53], v[70:71], v[76:77] op_sel:[1,1,0] op_sel_hi:[1,0,1] neg_lo:[0,1,0]
	ds_write2_b64 v134, v[62:63], v[52:53] offset0:34 offset1:51
	v_pk_mul_f32 v[52:53], v[70:71], v[48:49] op_sel:[0,0] op_sel_hi:[0,1]
	v_pk_fma_f32 v[52:53], v[70:71], v[48:49], v[52:53] op_sel:[1,1,0] op_sel_hi:[1,0,1] neg_lo:[0,1,0]
	v_pk_mul_f32 v[62:63], v[74:75], v[52:53] op_sel:[0,0] op_sel_hi:[0,1]
	v_pk_mul_f32 v[70:71], v[52:53], v[48:49] op_sel:[0,0] op_sel_hi:[0,1]
	v_pk_fma_f32 v[62:63], v[74:75], v[52:53], v[62:63] op_sel:[1,1,0] op_sel_hi:[1,0,1] neg_lo:[0,1,0]
	v_pk_fma_f32 v[52:53], v[52:53], v[48:49], v[70:71] op_sel:[1,1,0] op_sel_hi:[1,0,1] neg_lo:[0,1,0]
	v_pk_mul_f32 v[70:71], v[78:79], v[52:53] op_sel:[0,0] op_sel_hi:[0,1]
	v_pk_fma_f32 v[70:71], v[78:79], v[52:53], v[70:71] op_sel:[1,1,0] op_sel_hi:[1,0,1] neg_lo:[0,1,0]
	ds_write2_b64 v134, v[62:63], v[70:71] offset0:68 offset1:85
	v_pk_mul_f32 v[62:63], v[52:53], v[48:49] op_sel:[0,0] op_sel_hi:[0,1]
	v_pk_fma_f32 v[52:53], v[52:53], v[48:49], v[62:63] op_sel:[1,1,0] op_sel_hi:[1,0,1] neg_lo:[0,1,0]
	v_pk_mul_f32 v[62:63], v[64:65], v[52:53] op_sel:[0,0] op_sel_hi:[0,1]
	v_pk_fma_f32 v[62:63], v[64:65], v[52:53], v[62:63] op_sel:[1,1,0] op_sel_hi:[1,0,1] neg_lo:[0,1,0]
	v_pk_mul_f32 v[64:65], v[52:53], v[48:49] op_sel:[0,0] op_sel_hi:[0,1]
	v_pk_fma_f32 v[52:53], v[52:53], v[48:49], v[64:65] op_sel:[1,1,0] op_sel_hi:[1,0,1] neg_lo:[0,1,0]
	v_pk_mul_f32 v[64:65], v[56:57], v[52:53] op_sel:[0,0] op_sel_hi:[0,1]
	v_pk_fma_f32 v[56:57], v[56:57], v[52:53], v[64:65] op_sel:[1,1,0] op_sel_hi:[1,0,1] neg_lo:[0,1,0]
	ds_write2_b64 v134, v[62:63], v[56:57] offset0:102 offset1:119
	v_pk_mul_f32 v[56:57], v[52:53], v[48:49] op_sel:[0,0] op_sel_hi:[0,1]
	v_pk_fma_f32 v[52:53], v[52:53], v[48:49], v[56:57] op_sel:[1,1,0] op_sel_hi:[1,0,1] neg_lo:[0,1,0]
	v_pk_mul_f32 v[56:57], v[72:73], v[52:53] op_sel:[0,0] op_sel_hi:[0,1]
	v_pk_mul_f32 v[62:63], v[52:53], v[48:49] op_sel:[0,0] op_sel_hi:[0,1]
	v_pk_fma_f32 v[56:57], v[72:73], v[52:53], v[56:57] op_sel:[1,1,0] op_sel_hi:[1,0,1] neg_lo:[0,1,0]
	v_pk_fma_f32 v[52:53], v[52:53], v[48:49], v[62:63] op_sel:[1,1,0] op_sel_hi:[1,0,1] neg_lo:[0,1,0]
	v_pk_mul_f32 v[62:63], v[68:69], v[52:53] op_sel:[0,0] op_sel_hi:[0,1]
	v_pk_fma_f32 v[62:63], v[68:69], v[52:53], v[62:63] op_sel:[1,1,0] op_sel_hi:[1,0,1] neg_lo:[0,1,0]
	ds_write2_b64 v134, v[56:57], v[62:63] offset0:136 offset1:153
	v_pk_mul_f32 v[56:57], v[52:53], v[48:49] op_sel:[0,0] op_sel_hi:[0,1]
	v_pk_fma_f32 v[52:53], v[52:53], v[48:49], v[56:57] op_sel:[1,1,0] op_sel_hi:[1,0,1] neg_lo:[0,1,0]
	v_pk_mul_f32 v[56:57], v[58:59], v[52:53] op_sel:[0,0] op_sel_hi:[0,1]
	v_pk_fma_f32 v[56:57], v[58:59], v[52:53], v[56:57] op_sel:[1,1,0] op_sel_hi:[1,0,1] neg_lo:[0,1,0]
	v_pk_mul_f32 v[58:59], v[52:53], v[48:49] op_sel:[0,0] op_sel_hi:[0,1]
	v_pk_fma_f32 v[52:53], v[52:53], v[48:49], v[58:59] op_sel:[1,1,0] op_sel_hi:[1,0,1] neg_lo:[0,1,0]
	v_pk_mul_f32 v[58:59], v[50:51], v[52:53] op_sel:[0,0] op_sel_hi:[0,1]
	v_pk_fma_f32 v[50:51], v[50:51], v[52:53], v[58:59] op_sel:[1,1,0] op_sel_hi:[1,0,1] neg_lo:[0,1,0]
	ds_write2_b64 v134, v[56:57], v[50:51] offset0:170 offset1:187
	v_pk_mul_f32 v[50:51], v[52:53], v[48:49] op_sel:[0,0] op_sel_hi:[0,1]
	v_pk_fma_f32 v[50:51], v[52:53], v[48:49], v[50:51] op_sel:[1,1,0] op_sel_hi:[1,0,1] neg_lo:[0,1,0]
	v_pk_mul_f32 v[52:53], v[66:67], v[50:51] op_sel:[0,0] op_sel_hi:[0,1]
	v_pk_mul_f32 v[56:57], v[50:51], v[48:49] op_sel:[0,0] op_sel_hi:[0,1]
	v_pk_fma_f32 v[52:53], v[66:67], v[50:51], v[52:53] op_sel:[1,1,0] op_sel_hi:[1,0,1] neg_lo:[0,1,0]
	v_pk_fma_f32 v[50:51], v[50:51], v[48:49], v[56:57] op_sel:[1,1,0] op_sel_hi:[1,0,1] neg_lo:[0,1,0]
	v_pk_mul_f32 v[56:57], v[60:61], v[50:51] op_sel:[0,0] op_sel_hi:[0,1]
	v_pk_fma_f32 v[56:57], v[60:61], v[50:51], v[56:57] op_sel:[1,1,0] op_sel_hi:[1,0,1] neg_lo:[0,1,0]
	ds_write2_b64 v134, v[52:53], v[56:57] offset0:204 offset1:221
	v_pk_mul_f32 v[52:53], v[50:51], v[48:49] op_sel:[0,0] op_sel_hi:[0,1]
	v_pk_fma_f32 v[50:51], v[50:51], v[48:49], v[52:53] op_sel:[1,1,0] op_sel_hi:[1,0,1] neg_lo:[0,1,0]
	v_pk_mul_f32 v[52:53], v[54:55], v[50:51] op_sel:[0,0] op_sel_hi:[0,1]
	v_pk_fma_f32 v[52:53], v[54:55], v[50:51], v[52:53] op_sel:[1,1,0] op_sel_hi:[1,0,1] neg_lo:[0,1,0]
	v_pk_mul_f32 v[54:55], v[50:51], v[48:49] op_sel:[0,0] op_sel_hi:[0,1]
	v_pk_fma_f32 v[48:49], v[50:51], v[48:49], v[54:55] op_sel:[1,1,0] op_sel_hi:[1,0,1] neg_lo:[0,1,0]
	v_pk_mul_f32 v[50:51], v[46:47], v[48:49] op_sel:[0,0] op_sel_hi:[0,1]
	v_pk_fma_f32 v[46:47], v[46:47], v[48:49], v[50:51] op_sel:[1,1,0] op_sel_hi:[1,0,1] neg_lo:[0,1,0]
	ds_write2_b64 v134, v[52:53], v[46:47] offset0:238 offset1:255
	s_waitcnt lgkmcnt(0)
	s_barrier
	ds_read2_b64 v[46:49], v135 offset1:1
	ds_read2_b64 v[50:53], v135 offset0:2 offset1:3
	ds_read2_b64 v[54:57], v135 offset0:8 offset1:9
	ds_read2_b64 v[58:61], v135 offset0:4 offset1:5
	ds_read2_b64 v[62:65], v135 offset0:6 offset1:7
	ds_read2_b64 v[66:69], v135 offset0:12 offset1:13
	ds_read2_b64 v[70:73], v135 offset0:10 offset1:11
	ds_read2_b64 v[74:77], v135 offset0:14 offset1:15
	s_waitcnt lgkmcnt(5)
	v_pk_add_f32 v[78:79], v[46:47], v[54:55]
	v_pk_add_f32 v[46:47], v[46:47], v[54:55] neg_lo:[0,1] neg_hi:[0,1]
	s_waitcnt lgkmcnt(2)
	v_pk_add_f32 v[54:55], v[58:59], v[66:67]
	v_pk_add_f32 v[58:59], v[58:59], v[66:67] neg_lo:[0,1] neg_hi:[0,1]
	v_pk_add_f32 v[66:67], v[78:79], v[54:55]
	v_pk_add_f32 v[54:55], v[78:79], v[54:55] neg_lo:[0,1] neg_hi:[0,1]
	v_pk_add_f32 v[78:79], v[46:47], v[58:59] op_sel:[0,1] op_sel_hi:[1,0] neg_hi:[0,1]
	v_pk_add_f32 v[46:47], v[46:47], v[58:59] op_sel:[0,1] op_sel_hi:[1,0] neg_lo:[0,1]
	v_pk_add_f32 v[58:59], v[48:49], v[56:57]
	v_pk_add_f32 v[48:49], v[48:49], v[56:57] neg_lo:[0,1] neg_hi:[0,1]
	v_pk_add_f32 v[56:57], v[60:61], v[68:69]
	v_pk_add_f32 v[60:61], v[60:61], v[68:69] neg_lo:[0,1] neg_hi:[0,1]
	v_pk_add_f32 v[68:69], v[58:59], v[56:57]
	v_pk_add_f32 v[56:57], v[58:59], v[56:57] neg_lo:[0,1] neg_hi:[0,1]
	v_pk_add_f32 v[58:59], v[48:49], v[60:61] op_sel:[0,1] op_sel_hi:[1,0] neg_hi:[0,1]
	v_pk_add_f32 v[48:49], v[48:49], v[60:61] op_sel:[0,1] op_sel_hi:[1,0] neg_lo:[0,1]
	s_waitcnt lgkmcnt(1)
	v_pk_add_f32 v[60:61], v[50:51], v[70:71]
	v_pk_add_f32 v[50:51], v[50:51], v[70:71] neg_lo:[0,1] neg_hi:[0,1]
	s_waitcnt lgkmcnt(0)
	v_pk_add_f32 v[70:71], v[62:63], v[74:75]
	v_pk_add_f32 v[62:63], v[62:63], v[74:75] neg_lo:[0,1] neg_hi:[0,1]
	v_pk_add_f32 v[74:75], v[60:61], v[70:71]
	v_pk_add_f32 v[60:61], v[60:61], v[70:71] neg_lo:[0,1] neg_hi:[0,1]
	v_pk_add_f32 v[70:71], v[50:51], v[62:63] op_sel:[0,1] op_sel_hi:[1,0] neg_hi:[0,1]
	v_pk_add_f32 v[50:51], v[50:51], v[62:63] op_sel:[0,1] op_sel_hi:[1,0] neg_lo:[0,1]
	v_pk_add_f32 v[62:63], v[52:53], v[72:73]
	v_pk_add_f32 v[52:53], v[52:53], v[72:73] neg_lo:[0,1] neg_hi:[0,1]
	v_pk_add_f32 v[72:73], v[64:65], v[76:77]
	v_pk_add_f32 v[64:65], v[64:65], v[76:77] neg_lo:[0,1] neg_hi:[0,1]
	v_pk_add_f32 v[76:77], v[62:63], v[72:73]
	v_pk_add_f32 v[62:63], v[62:63], v[72:73] neg_lo:[0,1] neg_hi:[0,1]
	v_pk_add_f32 v[72:73], v[52:53], v[64:65] op_sel:[0,1] op_sel_hi:[1,0] neg_hi:[0,1]
	v_pk_add_f32 v[52:53], v[52:53], v[64:65] op_sel:[0,1] op_sel_hi:[1,0] neg_lo:[0,1]
	v_pk_mul_f32 v[64:65], v[58:59], s[20:21] op_sel:[0,0] op_sel_hi:[0,1]
	v_pk_fma_f32 v[32:33], v[58:59], s[20:21], v[64:65] op_sel:[1,1,0] op_sel_hi:[1,0,1] neg_lo:[0,1,0]
	v_pk_mul_f32 v[58:59], v[70:71], s[46:47] op_sel:[0,0] op_sel_hi:[0,1]
	v_pk_mul_f32 v[64:65], v[72:73], s[50:51] op_sel:[0,0] op_sel_hi:[0,1]
	s_barrier
	v_pk_fma_f32 v[58:59], v[70:71], s[46:47], v[58:59] op_sel:[1,1,0] op_sel_hi:[1,0,1] neg_lo:[0,1,0]
	v_pk_mul_f32 v[70:71], v[56:57], s[46:47] op_sel:[0,0] op_sel_hi:[0,1]
	v_pk_fma_f32 v[64:65], v[72:73], s[50:51], v[64:65] op_sel:[1,1,0] op_sel_hi:[1,0,1] neg_lo:[0,1,0]
	v_pk_fma_f32 v[28:29], v[56:57], s[46:47], v[70:71] op_sel:[1,1,0] op_sel_hi:[1,0,1] neg_lo:[0,1,0]
	v_pk_mul_f32 v[56:57], v[60:61], s[8:9] op_sel:[0,0] op_sel_hi:[0,1]
	v_pk_fma_f32 v[42:43], v[60:61], s[8:9], v[56:57] op_sel:[1,1,0] op_sel_hi:[1,0,1] neg_lo:[0,1,0]
	v_pk_mul_f32 v[56:57], v[62:63], s[54:55] op_sel:[0,0] op_sel_hi:[0,1]
	v_pk_mul_f32 v[60:61], v[48:49], s[50:51] op_sel:[0,0] op_sel_hi:[0,1]
	v_pk_fma_f32 v[26:27], v[48:49], s[50:51], v[60:61] op_sel:[1,1,0] op_sel_hi:[1,0,1] neg_lo:[0,1,0]
	v_pk_mul_f32 v[48:49], v[50:51], s[54:55] op_sel:[0,0] op_sel_hi:[0,1]
	v_pk_fma_f32 v[56:57], v[62:63], s[54:55], v[56:57] op_sel:[1,1,0] op_sel_hi:[1,0,1] neg_lo:[0,1,0]
	v_pk_add_f32 v[60:61], v[68:69], v[76:77] neg_lo:[0,1] neg_hi:[0,1]
	v_pk_fma_f32 v[30:31], v[50:51], s[54:55], v[48:49] op_sel:[1,1,0] op_sel_hi:[1,0,1] neg_lo:[0,1,0]
	v_pk_mul_f32 v[48:49], v[52:53], s[56:57] op_sel:[0,0] op_sel_hi:[0,1]
	v_pk_add_f32 v[50:51], v[66:67], v[74:75] neg_lo:[0,1] neg_hi:[0,1]
	v_pk_fma_f32 v[44:45], v[52:53], s[56:57], v[48:49] op_sel:[1,1,0] op_sel_hi:[1,0,1] neg_lo:[0,1,0]
	v_pk_add_f32 v[48:49], v[66:67], v[74:75]
	v_pk_add_f32 v[52:53], v[68:69], v[76:77]
	v_pk_add_f32 v[66:67], v[32:33], v[64:65]
	v_pk_add_f32 v[62:63], v[48:49], v[52:53]
	v_pk_add_f32 v[48:49], v[48:49], v[52:53] neg_lo:[0,1] neg_hi:[0,1]
	v_pk_add_f32 v[52:53], v[50:51], v[60:61] op_sel:[0,1] op_sel_hi:[1,0] neg_hi:[0,1]
	v_pk_add_f32 v[50:51], v[50:51], v[60:61] op_sel:[0,1] op_sel_hi:[1,0] neg_lo:[0,1]
	v_pk_add_f32 v[60:61], v[78:79], v[58:59]
	v_pk_add_f32 v[58:59], v[78:79], v[58:59] neg_lo:[0,1] neg_hi:[0,1]
	v_pk_add_f32 v[32:33], v[32:33], v[64:65] neg_lo:[0,1] neg_hi:[0,1]
	v_pk_add_f32 v[64:65], v[60:61], v[66:67]
	v_pk_add_f32 v[60:61], v[60:61], v[66:67] neg_lo:[0,1] neg_hi:[0,1]
	v_pk_add_f32 v[66:67], v[58:59], v[32:33] op_sel:[0,1] op_sel_hi:[1,0] neg_hi:[0,1]
	v_pk_add_f32 v[58:59], v[58:59], v[32:33] op_sel:[0,1] op_sel_hi:[1,0] neg_lo:[0,1]
	v_pk_add_f32 v[32:33], v[54:55], v[42:43]
	v_pk_add_f32 v[42:43], v[54:55], v[42:43] neg_lo:[0,1] neg_hi:[0,1]
	v_pk_add_f32 v[54:55], v[28:29], v[56:57]
	v_pk_add_f32 v[28:29], v[28:29], v[56:57] neg_lo:[0,1] neg_hi:[0,1]
	v_pk_add_f32 v[56:57], v[32:33], v[54:55]
	v_pk_add_f32 v[54:55], v[32:33], v[54:55] neg_lo:[0,1] neg_hi:[0,1]
	v_pk_add_f32 v[68:69], v[42:43], v[28:29] op_sel:[0,1] op_sel_hi:[1,0] neg_hi:[0,1]
	v_pk_add_f32 v[42:43], v[42:43], v[28:29] op_sel:[0,1] op_sel_hi:[1,0] neg_lo:[0,1]
	v_pk_add_f32 v[28:29], v[46:47], v[30:31]
	v_pk_add_f32 v[32:33], v[26:27], v[44:45]
	v_pk_add_f32 v[30:31], v[46:47], v[30:31] neg_lo:[0,1] neg_hi:[0,1]
	v_pk_add_f32 v[26:27], v[26:27], v[44:45] neg_lo:[0,1] neg_hi:[0,1]
	v_pk_add_f32 v[44:45], v[28:29], v[32:33]
	v_pk_add_f32 v[46:47], v[28:29], v[32:33] neg_lo:[0,1] neg_hi:[0,1]
	v_add_f32_e32 v28, 0x358637bd, v34
	v_mul_f32_e32 v28, 0x46000000, v28
	v_div_scale_f32 v29, s[0:1], v28, v28, 1.0
	s_waitcnt vmcnt(1)
	v_pk_add_f32 v[88:89], v[30:31], v[26:27] op_sel:[0,1] op_sel_hi:[1,0] neg_hi:[0,1]
	v_pk_add_f32 v[26:27], v[30:31], v[26:27] op_sel:[0,1] op_sel_hi:[1,0] neg_lo:[0,1]
	v_rcp_f32_e32 v30, v29
	s_nop 0
	v_fma_f32 v31, -v29, v30, 1.0
	v_fmac_f32_e32 v30, v31, v30
	v_div_scale_f32 v31, vcc, 1.0, v28, 1.0
	v_mul_f32_e32 v32, v31, v30
	v_fma_f32 v33, -v29, v32, v31
	v_fmac_f32_e32 v32, v33, v30
	v_fma_f32 v29, -v29, v32, v31
	v_div_fmas_f32 v29, v29, v30, v32
	v_div_fixup_f32 v34, v29, v28, 1.0
	v_pk_mul_f32 v[70:71], v[34:35], v[62:63] op_sel_hi:[0,1]
	v_pk_mul_f32 v[30:31], v[34:35], v[52:53] op_sel_hi:[0,1]
	v_pk_mul_f32 v[28:29], v[34:35], v[48:49] op_sel_hi:[0,1]
	v_pk_mul_f32 v[32:33], v[34:35], v[50:51] op_sel_hi:[0,1]
	v_pk_mul_f32 v[78:79], v[34:35], v[64:65] op_sel_hi:[0,1]
	v_pk_mul_f32 v[74:75], v[34:35], v[66:67] op_sel_hi:[0,1]
	v_pk_mul_f32 v[72:73], v[34:35], v[60:61] op_sel_hi:[0,1]
	v_pk_mul_f32 v[76:77], v[34:35], v[58:59] op_sel_hi:[0,1]
	v_pk_mul_f32 v[86:87], v[34:35], v[56:57] op_sel_hi:[0,1]
	v_pk_mul_f32 v[82:83], v[34:35], v[68:69] op_sel_hi:[0,1]
	v_pk_mul_f32 v[80:81], v[34:35], v[54:55] op_sel_hi:[0,1]
	v_pk_mul_f32 v[84:85], v[34:35], v[42:43] op_sel_hi:[0,1]
	v_pk_mul_f32 v[94:95], v[34:35], v[44:45] op_sel_hi:[0,1]
	v_pk_mul_f32 v[90:91], v[34:35], v[88:89] op_sel_hi:[0,1]
	v_pk_mul_f32 v[88:89], v[34:35], v[46:47] op_sel_hi:[0,1]
	s_waitcnt vmcnt(0)
	v_pk_mul_f32 v[92:93], v[34:35], v[26:27] op_sel_hi:[0,1]

.LBB0_3481:
	s_or_b64 exec, exec, s[0:1]
	s_addk_i32 s15, 0x800
	s_waitcnt lgkmcnt(0)
	ds_write_b64 v34, v[42:43]
	s_cmpk_lg_u32 s15, 0x8000
	v_add_u32_e32 v34, 0x880, v34
	v_pk_mul_f32 v[44:45], v[26:27], s[16:17] op_sel:[0,0] op_sel_hi:[0,1]
	v_pk_fma_f32 v[26:27], v[26:27], s[16:17], v[44:45] op_sel:[1,1,0] op_sel_hi:[1,0,1] neg_lo:[0,1,0]
	s_cbranch_scc0 .LBB0_3484

.LBB0_3484:
	ds_read_b64 v[26:27], v132
	ds_read_b64 v[42:43], v132 offset:2176
	ds_read_b64 v[44:45], v132 offset:4352
	ds_read_b64 v[46:47], v132 offset:6528
	ds_read_b64 v[48:49], v132 offset:8704
	ds_read_b64 v[50:51], v132 offset:10880
	ds_read_b64 v[52:53], v132 offset:13056
	ds_read_b64 v[54:55], v132 offset:15232
	ds_read_b64 v[56:57], v132 offset:17408
	ds_read_b64 v[58:59], v132 offset:19584
	ds_read_b64 v[60:61], v132 offset:21760
	ds_read_b64 v[62:63], v132 offset:23936
	ds_read_b64 v[64:65], v132 offset:26112
	ds_read_b64 v[66:67], v132 offset:28288
	ds_read_b64 v[68:69], v132 offset:30464
	ds_read_b64 v[98:99], v132 offset:32640
	s_waitcnt lgkmcnt(7)
	v_pk_add_f32 v[100:101], v[26:27], v[56:57]
	v_pk_add_f32 v[26:27], v[26:27], v[56:57] neg_lo:[0,1] neg_hi:[0,1]
	s_waitcnt lgkmcnt(3)
	v_pk_add_f32 v[56:57], v[48:49], v[64:65]
	v_pk_add_f32 v[48:49], v[48:49], v[64:65] neg_lo:[0,1] neg_hi:[0,1]
	v_pk_add_f32 v[64:65], v[100:101], v[56:57]
	v_pk_add_f32 v[56:57], v[100:101], v[56:57] neg_lo:[0,1] neg_hi:[0,1]
	v_pk_add_f32 v[100:101], v[26:27], v[48:49] op_sel:[0,1] op_sel_hi:[1,0] neg_hi:[0,1]
	v_pk_add_f32 v[102:103], v[26:27], v[48:49] op_sel:[0,1] op_sel_hi:[1,0] neg_lo:[0,1]
	v_pk_add_f32 v[26:27], v[42:43], v[58:59]
	v_pk_add_f32 v[42:43], v[42:43], v[58:59] neg_lo:[0,1] neg_hi:[0,1]
	s_waitcnt lgkmcnt(2)
	v_pk_add_f32 v[48:49], v[50:51], v[66:67]
	v_pk_add_f32 v[50:51], v[50:51], v[66:67] neg_lo:[0,1] neg_hi:[0,1]
	v_pk_add_f32 v[58:59], v[26:27], v[48:49]
	v_pk_add_f32 v[48:49], v[26:27], v[48:49] neg_lo:[0,1] neg_hi:[0,1]
	v_pk_add_f32 v[26:27], v[42:43], v[50:51] op_sel:[0,1] op_sel_hi:[1,0] neg_hi:[0,1]
	v_pk_add_f32 v[50:51], v[42:43], v[50:51] op_sel:[0,1] op_sel_hi:[1,0] neg_lo:[0,1]
	v_pk_add_f32 v[42:43], v[44:45], v[60:61]
	v_pk_add_f32 v[44:45], v[44:45], v[60:61] neg_lo:[0,1] neg_hi:[0,1]
	s_waitcnt lgkmcnt(1)
	v_pk_add_f32 v[60:61], v[52:53], v[68:69]
	v_pk_add_f32 v[52:53], v[52:53], v[68:69] neg_lo:[0,1] neg_hi:[0,1]
	v_pk_add_f32 v[66:67], v[42:43], v[60:61]
	v_pk_add_f32 v[60:61], v[42:43], v[60:61] neg_lo:[0,1] neg_hi:[0,1]
	v_pk_add_f32 v[68:69], v[44:45], v[52:53] op_sel:[0,1] op_sel_hi:[1,0] neg_hi:[0,1]
	v_pk_add_f32 v[52:53], v[44:45], v[52:53] op_sel:[0,1] op_sel_hi:[1,0] neg_lo:[0,1]
	v_pk_add_f32 v[42:43], v[46:47], v[62:63]
	v_pk_add_f32 v[44:45], v[46:47], v[62:63] neg_lo:[0,1] neg_hi:[0,1]
	s_waitcnt lgkmcnt(0)
	v_pk_add_f32 v[46:47], v[54:55], v[98:99]
	v_pk_add_f32 v[54:55], v[54:55], v[98:99] neg_lo:[0,1] neg_hi:[0,1]
	v_pk_add_f32 v[62:63], v[42:43], v[46:47]
	v_pk_add_f32 v[98:99], v[42:43], v[46:47] neg_lo:[0,1] neg_hi:[0,1]
	v_pk_mul_f32 v[42:43], v[26:27], s[20:21] op_sel:[0,0] op_sel_hi:[0,1]
	v_pk_add_f32 v[104:105], v[44:45], v[54:55] op_sel:[0,1] op_sel_hi:[1,0] neg_hi:[0,1]
	v_pk_add_f32 v[54:55], v[44:45], v[54:55] op_sel:[0,1] op_sel_hi:[1,0] neg_lo:[0,1]
	s_add_i32 s78, s70, s24
	v_pk_fma_f32 v[106:107], v[26:27], s[20:21], v[42:43] op_sel:[1,1,0] op_sel_hi:[1,0,1] neg_lo:[0,1,0]
	v_pk_mul_f32 v[26:27], v[68:69], s[46:47] op_sel:[0,0] op_sel_hi:[0,1]
	s_cmpk_gt_i32 s78, 0x3ff
	v_pk_fma_f32 v[68:69], v[68:69], s[46:47], v[26:27] op_sel:[1,1,0] op_sel_hi:[1,0,1] neg_lo:[0,1,0]
	v_pk_mul_f32 v[44:45], v[104:105], s[50:51] op_sel:[0,0] op_sel_hi:[0,1]
	s_cselect_b64 s[76:77], -1, 0
	v_pk_fma_f32 v[104:105], v[104:105], s[50:51], v[44:45] op_sel:[1,1,0] op_sel_hi:[1,0,1] neg_lo:[0,1,0]
	v_pk_mul_f32 v[44:45], v[48:49], s[46:47] op_sel:[0,0] op_sel_hi:[0,1]
	s_cmpk_lt_i32 s78, 0x400
	v_pk_fma_f32 v[110:111], v[48:49], s[46:47], v[44:45] op_sel:[1,1,0] op_sel_hi:[1,0,1] neg_lo:[0,1,0]
	v_pk_mul_f32 v[44:45], v[60:61], s[8:9] op_sel:[0,0] op_sel_hi:[0,1]
	s_cselect_b32 s0, s78, -1
	v_pk_fma_f32 v[60:61], v[60:61], s[8:9], v[44:45] op_sel:[1,1,0] op_sel_hi:[1,0,1] neg_lo:[0,1,0]
	v_pk_mul_f32 v[112:113], v[98:99], s[54:55] op_sel:[0,0] op_sel_hi:[0,1]
	s_cmp_lt_i32 s0, 0
	v_pk_fma_f32 v[98:99], v[98:99], s[54:55], v[112:113] op_sel:[1,1,0] op_sel_hi:[1,0,1] neg_lo:[0,1,0]
	v_pk_mul_f32 v[112:113], v[50:51], s[50:51] op_sel:[0,0] op_sel_hi:[0,1]
	v_pk_fma_f32 v[112:113], v[50:51], s[50:51], v[112:113] op_sel:[1,1,0] op_sel_hi:[1,0,1] neg_lo:[0,1,0]
	v_pk_mul_f32 v[50:51], v[52:53], s[54:55] op_sel:[0,0] op_sel_hi:[0,1]
	v_pk_fma_f32 v[52:53], v[52:53], s[54:55], v[50:51] op_sel:[1,1,0] op_sel_hi:[1,0,1] neg_lo:[0,1,0]
	v_pk_mul_f32 v[114:115], v[54:55], s[56:57] op_sel:[0,0] op_sel_hi:[0,1]
	v_pk_fma_f32 v[54:55], v[54:55], s[56:57], v[114:115] op_sel:[1,1,0] op_sel_hi:[1,0,1] neg_lo:[0,1,0]
	v_pk_add_f32 v[114:115], v[64:65], v[66:67]
	v_pk_add_f32 v[64:65], v[64:65], v[66:67] neg_lo:[0,1] neg_hi:[0,1]
	v_pk_add_f32 v[66:67], v[58:59], v[62:63]
	v_pk_add_f32 v[58:59], v[58:59], v[62:63] neg_lo:[0,1] neg_hi:[0,1]
	v_pk_add_f32 v[62:63], v[114:115], v[66:67]
	v_pk_add_f32 v[66:67], v[114:115], v[66:67] neg_lo:[0,1] neg_hi:[0,1]
	v_pk_add_f32 v[114:115], v[64:65], v[58:59] op_sel:[0,1] op_sel_hi:[1,0] neg_hi:[0,1]
	v_pk_add_f32 v[58:59], v[64:65], v[58:59] op_sel:[0,1] op_sel_hi:[1,0] neg_lo:[0,1]
	v_pk_add_f32 v[64:65], v[100:101], v[68:69]
	v_pk_add_f32 v[68:69], v[100:101], v[68:69] neg_lo:[0,1] neg_hi:[0,1]
	v_pk_add_f32 v[100:101], v[106:107], v[104:105]
	v_pk_add_f32 v[104:105], v[106:107], v[104:105] neg_lo:[0,1] neg_hi:[0,1]
	v_pk_add_f32 v[106:107], v[64:65], v[100:101]
	v_pk_add_f32 v[64:65], v[64:65], v[100:101] neg_lo:[0,1] neg_hi:[0,1]
	v_pk_add_f32 v[100:101], v[68:69], v[104:105] op_sel:[0,1] op_sel_hi:[1,0] neg_hi:[0,1]
	v_pk_add_f32 v[68:69], v[68:69], v[104:105] op_sel:[0,1] op_sel_hi:[1,0] neg_lo:[0,1]
	v_pk_add_f32 v[104:105], v[56:57], v[60:61]
	v_pk_add_f32 v[56:57], v[56:57], v[60:61] neg_lo:[0,1] neg_hi:[0,1]
	v_pk_add_f32 v[60:61], v[110:111], v[98:99]
	v_pk_add_f32 v[98:99], v[110:111], v[98:99] neg_lo:[0,1] neg_hi:[0,1]
	v_pk_add_f32 v[110:111], v[104:105], v[60:61]
	v_pk_add_f32 v[60:61], v[104:105], v[60:61] neg_lo:[0,1] neg_hi:[0,1]
	v_pk_add_f32 v[104:105], v[56:57], v[98:99] op_sel:[0,1] op_sel_hi:[1,0] neg_hi:[0,1]
	v_pk_add_f32 v[56:57], v[56:57], v[98:99] op_sel:[0,1] op_sel_hi:[1,0] neg_lo:[0,1]
	v_pk_add_f32 v[98:99], v[102:103], v[52:53]
	v_pk_add_f32 v[52:53], v[102:103], v[52:53] neg_lo:[0,1] neg_hi:[0,1]
	v_pk_add_f32 v[102:103], v[112:113], v[54:55]
	v_pk_add_f32 v[54:55], v[112:113], v[54:55] neg_lo:[0,1] neg_hi:[0,1]
	v_pk_add_f32 v[112:113], v[98:99], v[102:103]
	v_pk_add_f32 v[98:99], v[98:99], v[102:103] neg_lo:[0,1] neg_hi:[0,1]
	v_pk_add_f32 v[102:103], v[52:53], v[54:55] op_sel:[0,1] op_sel_hi:[1,0] neg_hi:[0,1]
	v_pk_add_f32 v[52:53], v[52:53], v[54:55] op_sel:[0,1] op_sel_hi:[1,0] neg_lo:[0,1]
	v_mov_b32_e32 v55, v39
	v_mov_b32_e32 v54, v38
	ds_write_b64 v132, v[62:63]
	v_pk_mul_f32 v[62:63], v[106:107], v[54:55] op_sel:[0,0] op_sel_hi:[0,1]
	v_pk_fma_f32 v[62:63], v[106:107], v[54:55], v[62:63] op_sel:[1,1,0] op_sel_hi:[1,0,1] neg_lo:[0,1,0]
	ds_write_b64 v132, v[62:63] offset:2176
	v_pk_mul_f32 v[62:63], v[54:55], v[54:55] op_sel:[0,0] op_sel_hi:[0,1]
	v_pk_fma_f32 v[62:63], v[54:55], v[54:55], v[62:63] op_sel:[1,1,0] op_sel_hi:[1,0,1] neg_lo:[0,1,0]
	v_pk_mul_f32 v[106:107], v[110:111], v[62:63] op_sel:[0,0] op_sel_hi:[0,1]
	v_pk_fma_f32 v[106:107], v[110:111], v[62:63], v[106:107] op_sel:[1,1,0] op_sel_hi:[1,0,1] neg_lo:[0,1,0]
	ds_write_b64 v132, v[106:107] offset:4352
	v_pk_mul_f32 v[106:107], v[62:63], v[54:55] op_sel:[0,0] op_sel_hi:[0,1]
	v_pk_fma_f32 v[62:63], v[62:63], v[54:55], v[106:107] op_sel:[1,1,0] op_sel_hi:[1,0,1] neg_lo:[0,1,0]
	v_pk_mul_f32 v[106:107], v[112:113], v[62:63] op_sel:[0,0] op_sel_hi:[0,1]
	v_pk_fma_f32 v[106:107], v[112:113], v[62:63], v[106:107] op_sel:[1,1,0] op_sel_hi:[1,0,1] neg_lo:[0,1,0]
	ds_write_b64 v132, v[106:107] offset:6528
	v_pk_mul_f32 v[106:107], v[62:63], v[54:55] op_sel:[0,0] op_sel_hi:[0,1]
	v_pk_fma_f32 v[62:63], v[62:63], v[54:55], v[106:107] op_sel:[1,1,0] op_sel_hi:[1,0,1] neg_lo:[0,1,0]
	v_pk_mul_f32 v[106:107], v[114:115], v[62:63] op_sel:[0,0] op_sel_hi:[0,1]
	v_pk_fma_f32 v[106:107], v[114:115], v[62:63], v[106:107] op_sel:[1,1,0] op_sel_hi:[1,0,1] neg_lo:[0,1,0]
	ds_write_b64 v132, v[106:107] offset:8704
	v_pk_mul_f32 v[106:107], v[62:63], v[54:55] op_sel:[0,0] op_sel_hi:[0,1]
	v_pk_fma_f32 v[62:63], v[62:63], v[54:55], v[106:107] op_sel:[1,1,0] op_sel_hi:[1,0,1] neg_lo:[0,1,0]
	v_pk_mul_f32 v[106:107], v[100:101], v[62:63] op_sel:[0,0] op_sel_hi:[0,1]
	v_pk_fma_f32 v[100:101], v[100:101], v[62:63], v[106:107] op_sel:[1,1,0] op_sel_hi:[1,0,1] neg_lo:[0,1,0]
	ds_write_b64 v132, v[100:101] offset:10880
	v_pk_mul_f32 v[100:101], v[62:63], v[54:55] op_sel:[0,0] op_sel_hi:[0,1]
	v_pk_fma_f32 v[62:63], v[62:63], v[54:55], v[100:101] op_sel:[1,1,0] op_sel_hi:[1,0,1] neg_lo:[0,1,0]
	v_pk_mul_f32 v[100:101], v[104:105], v[62:63] op_sel:[0,0] op_sel_hi:[0,1]
	v_pk_fma_f32 v[100:101], v[104:105], v[62:63], v[100:101] op_sel:[1,1,0] op_sel_hi:[1,0,1] neg_lo:[0,1,0]
	ds_write_b64 v132, v[100:101] offset:13056
	v_pk_mul_f32 v[100:101], v[62:63], v[54:55] op_sel:[0,0] op_sel_hi:[0,1]
	v_pk_fma_f32 v[62:63], v[62:63], v[54:55], v[100:101] op_sel:[1,1,0] op_sel_hi:[1,0,1] neg_lo:[0,1,0]
	v_pk_mul_f32 v[100:101], v[102:103], v[62:63] op_sel:[0,0] op_sel_hi:[0,1]
	v_pk_fma_f32 v[100:101], v[102:103], v[62:63], v[100:101] op_sel:[1,1,0] op_sel_hi:[1,0,1] neg_lo:[0,1,0]
	ds_write_b64 v132, v[100:101] offset:15232
	v_pk_mul_f32 v[100:101], v[62:63], v[54:55] op_sel:[0,0] op_sel_hi:[0,1]
	v_pk_fma_f32 v[62:63], v[62:63], v[54:55], v[100:101] op_sel:[1,1,0] op_sel_hi:[1,0,1] neg_lo:[0,1,0]
	v_pk_mul_f32 v[100:101], v[66:67], v[62:63] op_sel:[0,0] op_sel_hi:[0,1]
	v_pk_fma_f32 v[66:67], v[66:67], v[62:63], v[100:101] op_sel:[1,1,0] op_sel_hi:[1,0,1] neg_lo:[0,1,0]
	ds_write_b64 v132, v[66:67] offset:17408
	v_pk_mul_f32 v[66:67], v[62:63], v[54:55] op_sel:[0,0] op_sel_hi:[0,1]
	v_pk_fma_f32 v[62:63], v[62:63], v[54:55], v[66:67] op_sel:[1,1,0] op_sel_hi:[1,0,1] neg_lo:[0,1,0]
	v_pk_mul_f32 v[66:67], v[64:65], v[62:63] op_sel:[0,0] op_sel_hi:[0,1]
	v_pk_fma_f32 v[64:65], v[64:65], v[62:63], v[66:67] op_sel:[1,1,0] op_sel_hi:[1,0,1] neg_lo:[0,1,0]
	ds_write_b64 v132, v[64:65] offset:19584
	v_pk_mul_f32 v[64:65], v[62:63], v[54:55] op_sel:[0,0] op_sel_hi:[0,1]
	v_pk_fma_f32 v[62:63], v[62:63], v[54:55], v[64:65] op_sel:[1,1,0] op_sel_hi:[1,0,1] neg_lo:[0,1,0]
	v_pk_mul_f32 v[64:65], v[60:61], v[62:63] op_sel:[0,0] op_sel_hi:[0,1]
	v_pk_fma_f32 v[60:61], v[60:61], v[62:63], v[64:65] op_sel:[1,1,0] op_sel_hi:[1,0,1] neg_lo:[0,1,0]
	ds_write_b64 v132, v[60:61] offset:21760
	v_pk_mul_f32 v[60:61], v[62:63], v[54:55] op_sel:[0,0] op_sel_hi:[0,1]
	v_pk_fma_f32 v[60:61], v[62:63], v[54:55], v[60:61] op_sel:[1,1,0] op_sel_hi:[1,0,1] neg_lo:[0,1,0]
	v_pk_mul_f32 v[62:63], v[98:99], v[60:61] op_sel:[0,0] op_sel_hi:[0,1]
	v_pk_fma_f32 v[62:63], v[98:99], v[60:61], v[62:63] op_sel:[1,1,0] op_sel_hi:[1,0,1] neg_lo:[0,1,0]
	ds_write_b64 v132, v[62:63] offset:23936
	v_pk_mul_f32 v[62:63], v[60:61], v[54:55] op_sel:[0,0] op_sel_hi:[0,1]
	v_pk_fma_f32 v[60:61], v[60:61], v[54:55], v[62:63] op_sel:[1,1,0] op_sel_hi:[1,0,1] neg_lo:[0,1,0]
	v_pk_mul_f32 v[62:63], v[58:59], v[60:61] op_sel:[0,0] op_sel_hi:[0,1]
	v_pk_fma_f32 v[58:59], v[58:59], v[60:61], v[62:63] op_sel:[1,1,0] op_sel_hi:[1,0,1] neg_lo:[0,1,0]
	ds_write_b64 v132, v[58:59] offset:26112
	v_pk_mul_f32 v[58:59], v[60:61], v[54:55] op_sel:[0,0] op_sel_hi:[0,1]
	v_pk_fma_f32 v[58:59], v[60:61], v[54:55], v[58:59] op_sel:[1,1,0] op_sel_hi:[1,0,1] neg_lo:[0,1,0]
	v_pk_mul_f32 v[60:61], v[68:69], v[58:59] op_sel:[0,0] op_sel_hi:[0,1]
	v_pk_fma_f32 v[60:61], v[68:69], v[58:59], v[60:61] op_sel:[1,1,0] op_sel_hi:[1,0,1] neg_lo:[0,1,0]
	ds_write_b64 v132, v[60:61] offset:28288
	v_pk_mul_f32 v[60:61], v[58:59], v[54:55] op_sel:[0,0] op_sel_hi:[0,1]
	v_pk_fma_f32 v[58:59], v[58:59], v[54:55], v[60:61] op_sel:[1,1,0] op_sel_hi:[1,0,1] neg_lo:[0,1,0]
	v_pk_mul_f32 v[60:61], v[56:57], v[58:59] op_sel:[0,0] op_sel_hi:[0,1]
	v_pk_fma_f32 v[56:57], v[56:57], v[58:59], v[60:61] op_sel:[1,1,0] op_sel_hi:[1,0,1] neg_lo:[0,1,0]
	ds_write_b64 v132, v[56:57] offset:30464
	v_pk_mul_f32 v[56:57], v[58:59], v[54:55] op_sel:[0,0] op_sel_hi:[0,1]
	v_pk_fma_f32 v[54:55], v[58:59], v[54:55], v[56:57] op_sel:[1,1,0] op_sel_hi:[1,0,1] neg_lo:[0,1,0]
	v_pk_mul_f32 v[56:57], v[52:53], v[54:55] op_sel:[0,0] op_sel_hi:[0,1]
	v_pk_fma_f32 v[52:53], v[52:53], v[54:55], v[56:57] op_sel:[1,1,0] op_sel_hi:[1,0,1] neg_lo:[0,1,0]
	ds_write_b64 v132, v[52:53] offset:32640
	s_waitcnt lgkmcnt(0)
	s_barrier
	ds_read2_b64 v[52:55], v134 offset1:17
	ds_read2_b64 v[56:59], v134 offset0:34 offset1:51
	ds_read2_b64 v[60:63], v134 offset0:68 offset1:85
	ds_read2_b64 v[64:67], v134 offset0:136 offset1:153
	ds_read2_b64 v[98:101], v134 offset0:102 offset1:119
	ds_read2_b64 v[102:105], v134 offset0:204 offset1:221
	ds_read2_b64 v[110:113], v134 offset0:170 offset1:187
	ds_read2_b64 v[114:117], v134 offset0:238 offset1:255
	s_waitcnt lgkmcnt(4)
	v_pk_add_f32 v[68:69], v[52:53], v[64:65]
	v_pk_add_f32 v[52:53], v[52:53], v[64:65] neg_lo:[0,1] neg_hi:[0,1]
	s_waitcnt lgkmcnt(2)
	v_pk_add_f32 v[64:65], v[60:61], v[102:103]
	v_pk_add_f32 v[60:61], v[60:61], v[102:103] neg_lo:[0,1] neg_hi:[0,1]
	v_pk_add_f32 v[102:103], v[68:69], v[64:65]
	v_pk_add_f32 v[64:65], v[68:69], v[64:65] neg_lo:[0,1] neg_hi:[0,1]
	v_pk_add_f32 v[68:69], v[52:53], v[60:61] op_sel:[0,1] op_sel_hi:[1,0] neg_hi:[0,1]
	v_pk_add_f32 v[52:53], v[52:53], v[60:61] op_sel:[0,1] op_sel_hi:[1,0] neg_lo:[0,1]
	v_pk_add_f32 v[60:61], v[54:55], v[66:67]
	v_pk_add_f32 v[54:55], v[54:55], v[66:67] neg_lo:[0,1] neg_hi:[0,1]
	v_pk_add_f32 v[66:67], v[62:63], v[104:105]
	v_pk_add_f32 v[62:63], v[62:63], v[104:105] neg_lo:[0,1] neg_hi:[0,1]
	v_pk_add_f32 v[104:105], v[60:61], v[66:67]
	v_pk_add_f32 v[60:61], v[60:61], v[66:67] neg_lo:[0,1] neg_hi:[0,1]
	v_pk_add_f32 v[66:67], v[54:55], v[62:63] op_sel:[0,1] op_sel_hi:[1,0] neg_hi:[0,1]
	v_pk_add_f32 v[54:55], v[54:55], v[62:63] op_sel:[0,1] op_sel_hi:[1,0] neg_lo:[0,1]
	s_waitcnt lgkmcnt(1)
	v_pk_add_f32 v[62:63], v[56:57], v[110:111]
	v_pk_add_f32 v[56:57], v[56:57], v[110:111] neg_lo:[0,1] neg_hi:[0,1]
	s_waitcnt lgkmcnt(0)
	v_pk_add_f32 v[106:107], v[98:99], v[114:115]
	v_pk_add_f32 v[98:99], v[98:99], v[114:115] neg_lo:[0,1] neg_hi:[0,1]
	v_pk_add_f32 v[110:111], v[62:63], v[106:107]
	v_pk_add_f32 v[62:63], v[62:63], v[106:107] neg_lo:[0,1] neg_hi:[0,1]
	v_pk_add_f32 v[106:107], v[56:57], v[98:99] op_sel:[0,1] op_sel_hi:[1,0] neg_hi:[0,1]
	v_pk_add_f32 v[56:57], v[56:57], v[98:99] op_sel:[0,1] op_sel_hi:[1,0] neg_lo:[0,1]
	v_pk_add_f32 v[98:99], v[58:59], v[112:113]
	v_pk_add_f32 v[58:59], v[58:59], v[112:113] neg_lo:[0,1] neg_hi:[0,1]
	v_pk_add_f32 v[112:113], v[100:101], v[116:117]
	v_pk_add_f32 v[100:101], v[100:101], v[116:117] neg_lo:[0,1] neg_hi:[0,1]
	v_pk_add_f32 v[114:115], v[98:99], v[112:113]
	v_pk_add_f32 v[98:99], v[98:99], v[112:113] neg_lo:[0,1] neg_hi:[0,1]
	v_pk_add_f32 v[112:113], v[58:59], v[100:101] op_sel:[0,1] op_sel_hi:[1,0] neg_hi:[0,1]
	v_pk_add_f32 v[58:59], v[58:59], v[100:101] op_sel:[0,1] op_sel_hi:[1,0] neg_lo:[0,1]
	v_pk_mul_f32 v[100:101], v[66:67], s[20:21] op_sel:[0,0] op_sel_hi:[0,1]
	v_pk_fma_f32 v[66:67], v[66:67], s[20:21], v[100:101] op_sel:[1,1,0] op_sel_hi:[1,0,1] neg_lo:[0,1,0]
	v_pk_mul_f32 v[100:101], v[106:107], s[46:47] op_sel:[0,0] op_sel_hi:[0,1]
	v_pk_fma_f32 v[100:101], v[106:107], s[46:47], v[100:101] op_sel:[1,1,0] op_sel_hi:[1,0,1] neg_lo:[0,1,0]
	v_pk_mul_f32 v[106:107], v[112:113], s[50:51] op_sel:[0,0] op_sel_hi:[0,1]
	v_pk_fma_f32 v[106:107], v[112:113], s[50:51], v[106:107] op_sel:[1,1,0] op_sel_hi:[1,0,1] neg_lo:[0,1,0]
	v_pk_mul_f32 v[112:113], v[60:61], s[46:47] op_sel:[0,0] op_sel_hi:[0,1]
	v_pk_fma_f32 v[60:61], v[60:61], s[46:47], v[112:113] op_sel:[1,1,0] op_sel_hi:[1,0,1] neg_lo:[0,1,0]
	v_pk_mul_f32 v[112:113], v[62:63], s[8:9] op_sel:[0,0] op_sel_hi:[0,1]
	v_pk_fma_f32 v[62:63], v[62:63], s[8:9], v[112:113] op_sel:[1,1,0] op_sel_hi:[1,0,1] neg_lo:[0,1,0]
	v_pk_mul_f32 v[112:113], v[98:99], s[54:55] op_sel:[0,0] op_sel_hi:[0,1]
	v_pk_fma_f32 v[98:99], v[98:99], s[54:55], v[112:113] op_sel:[1,1,0] op_sel_hi:[1,0,1] neg_lo:[0,1,0]
	v_pk_mul_f32 v[112:113], v[54:55], s[50:51] op_sel:[0,0] op_sel_hi:[0,1]
	v_pk_fma_f32 v[54:55], v[54:55], s[50:51], v[112:113] op_sel:[1,1,0] op_sel_hi:[1,0,1] neg_lo:[0,1,0]
	v_pk_mul_f32 v[112:113], v[56:57], s[54:55] op_sel:[0,0] op_sel_hi:[0,1]
	v_pk_fma_f32 v[56:57], v[56:57], s[54:55], v[112:113] op_sel:[1,1,0] op_sel_hi:[1,0,1] neg_lo:[0,1,0]
	v_pk_mul_f32 v[112:113], v[58:59], s[56:57] op_sel:[0,0] op_sel_hi:[0,1]
	v_pk_fma_f32 v[58:59], v[58:59], s[56:57], v[112:113] op_sel:[1,1,0] op_sel_hi:[1,0,1] neg_lo:[0,1,0]
	v_pk_add_f32 v[112:113], v[102:103], v[110:111]
	v_pk_add_f32 v[102:103], v[102:103], v[110:111] neg_lo:[0,1] neg_hi:[0,1]
	v_pk_add_f32 v[110:111], v[104:105], v[114:115]
	v_pk_add_f32 v[104:105], v[104:105], v[114:115] neg_lo:[0,1] neg_hi:[0,1]
	v_pk_add_f32 v[114:115], v[112:113], v[110:111]
	v_pk_add_f32 v[110:111], v[112:113], v[110:111] neg_lo:[0,1] neg_hi:[0,1]
	v_pk_add_f32 v[112:113], v[102:103], v[104:105] op_sel:[0,1] op_sel_hi:[1,0] neg_hi:[0,1]
	v_pk_add_f32 v[102:103], v[102:103], v[104:105] op_sel:[0,1] op_sel_hi:[1,0] neg_lo:[0,1]
	v_pk_add_f32 v[104:105], v[68:69], v[100:101]
	v_pk_add_f32 v[68:69], v[68:69], v[100:101] neg_lo:[0,1] neg_hi:[0,1]
	v_pk_add_f32 v[100:101], v[66:67], v[106:107]
	v_pk_add_f32 v[66:67], v[66:67], v[106:107] neg_lo:[0,1] neg_hi:[0,1]
	v_pk_add_f32 v[106:107], v[104:105], v[100:101]
	v_pk_add_f32 v[100:101], v[104:105], v[100:101] neg_lo:[0,1] neg_hi:[0,1]
	v_pk_add_f32 v[104:105], v[68:69], v[66:67] op_sel:[0,1] op_sel_hi:[1,0] neg_hi:[0,1]
	v_pk_add_f32 v[66:67], v[68:69], v[66:67] op_sel:[0,1] op_sel_hi:[1,0] neg_lo:[0,1]
	v_pk_add_f32 v[68:69], v[64:65], v[62:63]
	v_pk_add_f32 v[62:63], v[64:65], v[62:63] neg_lo:[0,1] neg_hi:[0,1]
	v_pk_add_f32 v[64:65], v[60:61], v[98:99]
	v_pk_add_f32 v[60:61], v[60:61], v[98:99] neg_lo:[0,1] neg_hi:[0,1]
	v_pk_add_f32 v[98:99], v[68:69], v[64:65]
	v_pk_add_f32 v[64:65], v[68:69], v[64:65] neg_lo:[0,1] neg_hi:[0,1]
	v_pk_add_f32 v[68:69], v[62:63], v[60:61] op_sel:[0,1] op_sel_hi:[1,0] neg_hi:[0,1]
	v_pk_add_f32 v[60:61], v[62:63], v[60:61] op_sel:[0,1] op_sel_hi:[1,0] neg_lo:[0,1]
	v_pk_add_f32 v[62:63], v[52:53], v[56:57]
	v_pk_add_f32 v[52:53], v[52:53], v[56:57] neg_lo:[0,1] neg_hi:[0,1]
	v_pk_add_f32 v[56:57], v[54:55], v[58:59]
	v_pk_add_f32 v[54:55], v[54:55], v[58:59] neg_lo:[0,1] neg_hi:[0,1]
	v_pk_add_f32 v[58:59], v[62:63], v[56:57]
	v_pk_add_f32 v[56:57], v[62:63], v[56:57] neg_lo:[0,1] neg_hi:[0,1]
	v_pk_add_f32 v[62:63], v[52:53], v[54:55] op_sel:[0,1] op_sel_hi:[1,0] neg_hi:[0,1]
	v_pk_add_f32 v[52:53], v[52:53], v[54:55] op_sel:[0,1] op_sel_hi:[1,0] neg_lo:[0,1]
	v_mov_b32_e32 v55, v41
	v_mov_b32_e32 v54, v40
	s_nop 0
	v_pk_mul_f32 v[116:117], v[106:107], v[54:55] op_sel:[0,0] op_sel_hi:[0,1]
	v_pk_fma_f32 v[106:107], v[106:107], v[54:55], v[116:117] op_sel:[1,1,0] op_sel_hi:[1,0,1] neg_lo:[0,1,0]
	ds_write2_b64 v134, v[114:115], v[106:107] offset1:17
	v_pk_mul_f32 v[106:107], v[54:55], v[54:55] op_sel:[0,0] op_sel_hi:[0,1]
	v_pk_fma_f32 v[106:107], v[54:55], v[54:55], v[106:107] op_sel:[1,1,0] op_sel_hi:[1,0,1] neg_lo:[0,1,0]
	v_pk_mul_f32 v[114:115], v[98:99], v[106:107] op_sel:[0,0] op_sel_hi:[0,1]
	v_pk_fma_f32 v[98:99], v[98:99], v[106:107], v[114:115] op_sel:[1,1,0] op_sel_hi:[1,0,1] neg_lo:[0,1,0]
	v_pk_mul_f32 v[114:115], v[106:107], v[54:55] op_sel:[0,0] op_sel_hi:[0,1]
	v_pk_fma_f32 v[106:107], v[106:107], v[54:55], v[114:115] op_sel:[1,1,0] op_sel_hi:[1,0,1] neg_lo:[0,1,0]
	v_pk_mul_f32 v[114:115], v[58:59], v[106:107] op_sel:[0,0] op_sel_hi:[0,1]
	v_pk_fma_f32 v[58:59], v[58:59], v[106:107], v[114:115] op_sel:[1,1,0] op_sel_hi:[1,0,1] neg_lo:[0,1,0]
	ds_write2_b64 v134, v[98:99], v[58:59] offset0:34 offset1:51
	v_pk_mul_f32 v[58:59], v[106:107], v[54:55] op_sel:[0,0] op_sel_hi:[0,1]
	v_pk_fma_f32 v[58:59], v[106:107], v[54:55], v[58:59] op_sel:[1,1,0] op_sel_hi:[1,0,1] neg_lo:[0,1,0]
	v_pk_mul_f32 v[98:99], v[112:113], v[58:59] op_sel:[0,0] op_sel_hi:[0,1]
	v_pk_mul_f32 v[106:107], v[58:59], v[54:55] op_sel:[0,0] op_sel_hi:[0,1]
	v_pk_fma_f32 v[98:99], v[112:113], v[58:59], v[98:99] op_sel:[1,1,0] op_sel_hi:[1,0,1] neg_lo:[0,1,0]
	v_pk_fma_f32 v[58:59], v[58:59], v[54:55], v[106:107] op_sel:[1,1,0] op_sel_hi:[1,0,1] neg_lo:[0,1,0]
	v_pk_mul_f32 v[106:107], v[104:105], v[58:59] op_sel:[0,0] op_sel_hi:[0,1]
	v_pk_fma_f32 v[104:105], v[104:105], v[58:59], v[106:107] op_sel:[1,1,0] op_sel_hi:[1,0,1] neg_lo:[0,1,0]
	ds_write2_b64 v134, v[98:99], v[104:105] offset0:68 offset1:85
	v_pk_mul_f32 v[98:99], v[58:59], v[54:55] op_sel:[0,0] op_sel_hi:[0,1]
	v_pk_fma_f32 v[58:59], v[58:59], v[54:55], v[98:99] op_sel:[1,1,0] op_sel_hi:[1,0,1] neg_lo:[0,1,0]
	v_pk_mul_f32 v[98:99], v[68:69], v[58:59] op_sel:[0,0] op_sel_hi:[0,1]
	v_pk_fma_f32 v[68:69], v[68:69], v[58:59], v[98:99] op_sel:[1,1,0] op_sel_hi:[1,0,1] neg_lo:[0,1,0]
	v_pk_mul_f32 v[98:99], v[58:59], v[54:55] op_sel:[0,0] op_sel_hi:[0,1]
	v_pk_fma_f32 v[58:59], v[58:59], v[54:55], v[98:99] op_sel:[1,1,0] op_sel_hi:[1,0,1] neg_lo:[0,1,0]
	v_pk_mul_f32 v[98:99], v[62:63], v[58:59] op_sel:[0,0] op_sel_hi:[0,1]
	v_pk_fma_f32 v[62:63], v[62:63], v[58:59], v[98:99] op_sel:[1,1,0] op_sel_hi:[1,0,1] neg_lo:[0,1,0]
	ds_write2_b64 v134, v[68:69], v[62:63] offset0:102 offset1:119
	v_pk_mul_f32 v[62:63], v[58:59], v[54:55] op_sel:[0,0] op_sel_hi:[0,1]
	v_pk_fma_f32 v[58:59], v[58:59], v[54:55], v[62:63] op_sel:[1,1,0] op_sel_hi:[1,0,1] neg_lo:[0,1,0]
	v_pk_mul_f32 v[62:63], v[110:111], v[58:59] op_sel:[0,0] op_sel_hi:[0,1]
	v_pk_mul_f32 v[68:69], v[58:59], v[54:55] op_sel:[0,0] op_sel_hi:[0,1]
	v_pk_fma_f32 v[62:63], v[110:111], v[58:59], v[62:63] op_sel:[1,1,0] op_sel_hi:[1,0,1] neg_lo:[0,1,0]
	v_pk_fma_f32 v[58:59], v[58:59], v[54:55], v[68:69] op_sel:[1,1,0] op_sel_hi:[1,0,1] neg_lo:[0,1,0]
	v_pk_mul_f32 v[68:69], v[100:101], v[58:59] op_sel:[0,0] op_sel_hi:[0,1]
	v_pk_fma_f32 v[68:69], v[100:101], v[58:59], v[68:69] op_sel:[1,1,0] op_sel_hi:[1,0,1] neg_lo:[0,1,0]
	ds_write2_b64 v134, v[62:63], v[68:69] offset0:136 offset1:153
	v_pk_mul_f32 v[62:63], v[58:59], v[54:55] op_sel:[0,0] op_sel_hi:[0,1]
	v_pk_fma_f32 v[58:59], v[58:59], v[54:55], v[62:63] op_sel:[1,1,0] op_sel_hi:[1,0,1] neg_lo:[0,1,0]
	v_pk_mul_f32 v[62:63], v[64:65], v[58:59] op_sel:[0,0] op_sel_hi:[0,1]
	v_pk_fma_f32 v[62:63], v[64:65], v[58:59], v[62:63] op_sel:[1,1,0] op_sel_hi:[1,0,1] neg_lo:[0,1,0]
	v_pk_mul_f32 v[64:65], v[58:59], v[54:55] op_sel:[0,0] op_sel_hi:[0,1]
	v_pk_fma_f32 v[58:59], v[58:59], v[54:55], v[64:65] op_sel:[1,1,0] op_sel_hi:[1,0,1] neg_lo:[0,1,0]
	v_pk_mul_f32 v[64:65], v[56:57], v[58:59] op_sel:[0,0] op_sel_hi:[0,1]
	v_pk_fma_f32 v[56:57], v[56:57], v[58:59], v[64:65] op_sel:[1,1,0] op_sel_hi:[1,0,1] neg_lo:[0,1,0]
	ds_write2_b64 v134, v[62:63], v[56:57] offset0:170 offset1:187
	v_pk_mul_f32 v[56:57], v[58:59], v[54:55] op_sel:[0,0] op_sel_hi:[0,1]
	v_pk_fma_f32 v[56:57], v[58:59], v[54:55], v[56:57] op_sel:[1,1,0] op_sel_hi:[1,0,1] neg_lo:[0,1,0]
	v_pk_mul_f32 v[58:59], v[102:103], v[56:57] op_sel:[0,0] op_sel_hi:[0,1]
	v_pk_mul_f32 v[62:63], v[56:57], v[54:55] op_sel:[0,0] op_sel_hi:[0,1]
	v_pk_fma_f32 v[58:59], v[102:103], v[56:57], v[58:59] op_sel:[1,1,0] op_sel_hi:[1,0,1] neg_lo:[0,1,0]
	v_pk_fma_f32 v[56:57], v[56:57], v[54:55], v[62:63] op_sel:[1,1,0] op_sel_hi:[1,0,1] neg_lo:[0,1,0]
	v_pk_mul_f32 v[62:63], v[66:67], v[56:57] op_sel:[0,0] op_sel_hi:[0,1]
	v_pk_fma_f32 v[62:63], v[66:67], v[56:57], v[62:63] op_sel:[1,1,0] op_sel_hi:[1,0,1] neg_lo:[0,1,0]
	ds_write2_b64 v134, v[58:59], v[62:63] offset0:204 offset1:221
	v_pk_mul_f32 v[58:59], v[56:57], v[54:55] op_sel:[0,0] op_sel_hi:[0,1]
	v_pk_fma_f32 v[56:57], v[56:57], v[54:55], v[58:59] op_sel:[1,1,0] op_sel_hi:[1,0,1] neg_lo:[0,1,0]
	v_pk_mul_f32 v[58:59], v[60:61], v[56:57] op_sel:[0,0] op_sel_hi:[0,1]
	v_pk_fma_f32 v[58:59], v[60:61], v[56:57], v[58:59] op_sel:[1,1,0] op_sel_hi:[1,0,1] neg_lo:[0,1,0]
	v_pk_mul_f32 v[60:61], v[56:57], v[54:55] op_sel:[0,0] op_sel_hi:[0,1]
	v_pk_fma_f32 v[54:55], v[56:57], v[54:55], v[60:61] op_sel:[1,1,0] op_sel_hi:[1,0,1] neg_lo:[0,1,0]
	v_pk_mul_f32 v[56:57], v[52:53], v[54:55] op_sel:[0,0] op_sel_hi:[0,1]
	v_pk_fma_f32 v[52:53], v[52:53], v[54:55], v[56:57] op_sel:[1,1,0] op_sel_hi:[1,0,1] neg_lo:[0,1,0]
	ds_write2_b64 v134, v[58:59], v[52:53] offset0:238 offset1:255
	s_waitcnt lgkmcnt(0)
	s_barrier
	ds_read2_b64 v[52:55], v135 offset1:1
	ds_read2_b64 v[56:59], v135 offset0:2 offset1:3
	ds_read2_b64 v[60:63], v135 offset0:8 offset1:9
	ds_read2_b64 v[64:67], v135 offset0:4 offset1:5
	ds_read2_b64 v[98:101], v135 offset0:6 offset1:7
	ds_read2_b64 v[102:105], v135 offset0:12 offset1:13
	ds_read2_b64 v[110:113], v135 offset0:10 offset1:11
	ds_read2_b64 v[114:117], v135 offset0:14 offset1:15
	s_waitcnt lgkmcnt(5)
	v_pk_add_f32 v[68:69], v[52:53], v[60:61]
	v_pk_add_f32 v[52:53], v[52:53], v[60:61] neg_lo:[0,1] neg_hi:[0,1]
	s_waitcnt lgkmcnt(2)
	v_pk_add_f32 v[60:61], v[64:65], v[102:103]
	v_pk_add_f32 v[64:65], v[64:65], v[102:103] neg_lo:[0,1] neg_hi:[0,1]
	v_pk_add_f32 v[102:103], v[68:69], v[60:61]
	v_pk_add_f32 v[60:61], v[68:69], v[60:61] neg_lo:[0,1] neg_hi:[0,1]
	v_pk_add_f32 v[68:69], v[52:53], v[64:65] op_sel:[0,1] op_sel_hi:[1,0] neg_hi:[0,1]
	v_pk_add_f32 v[52:53], v[52:53], v[64:65] op_sel:[0,1] op_sel_hi:[1,0] neg_lo:[0,1]
	v_pk_add_f32 v[64:65], v[54:55], v[62:63]
	v_pk_add_f32 v[54:55], v[54:55], v[62:63] neg_lo:[0,1] neg_hi:[0,1]
	v_pk_add_f32 v[62:63], v[66:67], v[104:105]
	v_pk_add_f32 v[66:67], v[66:67], v[104:105] neg_lo:[0,1] neg_hi:[0,1]
	v_pk_add_f32 v[104:105], v[64:65], v[62:63]
	v_pk_add_f32 v[62:63], v[64:65], v[62:63] neg_lo:[0,1] neg_hi:[0,1]
	v_pk_add_f32 v[64:65], v[54:55], v[66:67] op_sel:[0,1] op_sel_hi:[1,0] neg_hi:[0,1]
	v_pk_add_f32 v[54:55], v[54:55], v[66:67] op_sel:[0,1] op_sel_hi:[1,0] neg_lo:[0,1]
	s_waitcnt lgkmcnt(1)
	v_pk_add_f32 v[66:67], v[56:57], v[110:111]
	v_pk_add_f32 v[56:57], v[56:57], v[110:111] neg_lo:[0,1] neg_hi:[0,1]
	s_waitcnt lgkmcnt(0)
	v_pk_add_f32 v[106:107], v[98:99], v[114:115]
	v_pk_add_f32 v[98:99], v[98:99], v[114:115] neg_lo:[0,1] neg_hi:[0,1]
	v_pk_add_f32 v[110:111], v[66:67], v[106:107]
	v_pk_add_f32 v[66:67], v[66:67], v[106:107] neg_lo:[0,1] neg_hi:[0,1]
	v_pk_add_f32 v[106:107], v[56:57], v[98:99] op_sel:[0,1] op_sel_hi:[1,0] neg_hi:[0,1]
	v_pk_add_f32 v[56:57], v[56:57], v[98:99] op_sel:[0,1] op_sel_hi:[1,0] neg_lo:[0,1]
	v_pk_add_f32 v[98:99], v[58:59], v[112:113]
	v_pk_add_f32 v[58:59], v[58:59], v[112:113] neg_lo:[0,1] neg_hi:[0,1]
	v_pk_add_f32 v[112:113], v[100:101], v[116:117]
	v_pk_add_f32 v[100:101], v[100:101], v[116:117] neg_lo:[0,1] neg_hi:[0,1]
	v_pk_add_f32 v[114:115], v[98:99], v[112:113]
	v_pk_add_f32 v[98:99], v[98:99], v[112:113] neg_lo:[0,1] neg_hi:[0,1]
	v_pk_add_f32 v[112:113], v[58:59], v[100:101] op_sel:[0,1] op_sel_hi:[1,0] neg_hi:[0,1]
	v_pk_add_f32 v[58:59], v[58:59], v[100:101] op_sel:[0,1] op_sel_hi:[1,0] neg_lo:[0,1]
	v_pk_mul_f32 v[100:101], v[64:65], s[20:21] op_sel:[0,0] op_sel_hi:[0,1]
	v_pk_fma_f32 v[46:47], v[64:65], s[20:21], v[100:101] op_sel:[1,1,0] op_sel_hi:[1,0,1] neg_lo:[0,1,0]
	v_pk_mul_f32 v[64:65], v[106:107], s[46:47] op_sel:[0,0] op_sel_hi:[0,1]
	v_pk_mul_f32 v[100:101], v[112:113], s[50:51] op_sel:[0,0] op_sel_hi:[0,1]
	v_pk_fma_f32 v[64:65], v[106:107], s[46:47], v[64:65] op_sel:[1,1,0] op_sel_hi:[1,0,1] neg_lo:[0,1,0]
	v_pk_mul_f32 v[106:107], v[62:63], s[46:47] op_sel:[0,0] op_sel_hi:[0,1]
	v_pk_fma_f32 v[100:101], v[112:113], s[50:51], v[100:101] op_sel:[1,1,0] op_sel_hi:[1,0,1] neg_lo:[0,1,0]
	v_pk_fma_f32 v[42:43], v[62:63], s[46:47], v[106:107] op_sel:[1,1,0] op_sel_hi:[1,0,1] neg_lo:[0,1,0]
	v_pk_mul_f32 v[62:63], v[66:67], s[8:9] op_sel:[0,0] op_sel_hi:[0,1]
	v_pk_fma_f32 v[48:49], v[66:67], s[8:9], v[62:63] op_sel:[1,1,0] op_sel_hi:[1,0,1] neg_lo:[0,1,0]
	v_pk_mul_f32 v[62:63], v[98:99], s[54:55] op_sel:[0,0] op_sel_hi:[0,1]
	v_pk_mul_f32 v[66:67], v[54:55], s[50:51] op_sel:[0,0] op_sel_hi:[0,1]
	v_pk_fma_f32 v[26:27], v[54:55], s[50:51], v[66:67] op_sel:[1,1,0] op_sel_hi:[1,0,1] neg_lo:[0,1,0]
	v_pk_mul_f32 v[54:55], v[56:57], s[54:55] op_sel:[0,0] op_sel_hi:[0,1]
	v_pk_fma_f32 v[62:63], v[98:99], s[54:55], v[62:63] op_sel:[1,1,0] op_sel_hi:[1,0,1] neg_lo:[0,1,0]
	v_pk_add_f32 v[66:67], v[104:105], v[114:115] neg_lo:[0,1] neg_hi:[0,1]
	v_pk_fma_f32 v[44:45], v[56:57], s[54:55], v[54:55] op_sel:[1,1,0] op_sel_hi:[1,0,1] neg_lo:[0,1,0]
	v_pk_mul_f32 v[54:55], v[58:59], s[56:57] op_sel:[0,0] op_sel_hi:[0,1]
	v_pk_add_f32 v[56:57], v[102:103], v[110:111] neg_lo:[0,1] neg_hi:[0,1]
	v_pk_fma_f32 v[50:51], v[58:59], s[56:57], v[54:55] op_sel:[1,1,0] op_sel_hi:[1,0,1] neg_lo:[0,1,0]
	v_pk_add_f32 v[54:55], v[102:103], v[110:111]
	v_pk_add_f32 v[58:59], v[104:105], v[114:115]
	s_nop 0
	v_pk_add_f32 v[98:99], v[54:55], v[58:59]
	v_pk_add_f32 v[54:55], v[54:55], v[58:59] neg_lo:[0,1] neg_hi:[0,1]
	v_pk_add_f32 v[58:59], v[56:57], v[66:67] op_sel:[0,1] op_sel_hi:[1,0] neg_hi:[0,1]
	v_pk_add_f32 v[56:57], v[56:57], v[66:67] op_sel:[0,1] op_sel_hi:[1,0] neg_lo:[0,1]
	v_pk_add_f32 v[66:67], v[68:69], v[64:65]
	v_pk_add_f32 v[64:65], v[68:69], v[64:65] neg_lo:[0,1] neg_hi:[0,1]
	v_pk_add_f32 v[68:69], v[46:47], v[100:101]
	v_pk_add_f32 v[46:47], v[46:47], v[100:101] neg_lo:[0,1] neg_hi:[0,1]
	v_pk_add_f32 v[100:101], v[66:67], v[68:69]
	v_pk_add_f32 v[66:67], v[66:67], v[68:69] neg_lo:[0,1] neg_hi:[0,1]
	v_pk_add_f32 v[68:69], v[64:65], v[46:47] op_sel:[0,1] op_sel_hi:[1,0] neg_hi:[0,1]
	v_pk_add_f32 v[46:47], v[64:65], v[46:47] op_sel:[0,1] op_sel_hi:[1,0] neg_lo:[0,1]
	v_pk_add_f32 v[64:65], v[60:61], v[48:49]
	v_pk_add_f32 v[48:49], v[60:61], v[48:49] neg_lo:[0,1] neg_hi:[0,1]
	v_pk_add_f32 v[60:61], v[42:43], v[62:63]
	v_pk_add_f32 v[42:43], v[42:43], v[62:63] neg_lo:[0,1] neg_hi:[0,1]
	v_pk_add_f32 v[62:63], v[64:65], v[60:61]
	v_pk_add_f32 v[60:61], v[64:65], v[60:61] neg_lo:[0,1] neg_hi:[0,1]
	v_pk_add_f32 v[64:65], v[48:49], v[42:43] op_sel:[0,1] op_sel_hi:[1,0] neg_hi:[0,1]
	v_pk_add_f32 v[102:103], v[48:49], v[42:43] op_sel:[0,1] op_sel_hi:[1,0] neg_lo:[0,1]
	v_pk_add_f32 v[42:43], v[52:53], v[44:45]
	v_pk_add_f32 v[48:49], v[26:27], v[50:51]
	v_pk_add_f32 v[44:45], v[52:53], v[44:45] neg_lo:[0,1] neg_hi:[0,1]
	v_pk_add_f32 v[104:105], v[42:43], v[48:49]
	v_pk_add_f32 v[106:107], v[42:43], v[48:49] neg_lo:[0,1] neg_hi:[0,1]
	s_waitcnt vmcnt(14)
	v_pk_mul_f32 v[42:43], v[58:59], v[30:31] op_sel:[0,0] op_sel_hi:[0,1]
	v_pk_add_f32 v[26:27], v[26:27], v[50:51] neg_lo:[0,1] neg_hi:[0,1]
	v_pk_fma_f32 v[30:31], v[58:59], v[30:31], v[42:43] op_sel:[1,1,0] op_sel_hi:[1,0,1] neg_lo:[0,1,0]
	s_waitcnt vmcnt(13)
	v_pk_mul_f32 v[42:43], v[54:55], v[28:29] op_sel:[0,0] op_sel_hi:[0,1]
	s_waitcnt vmcnt(8)
	v_pk_mul_f32 v[50:51], v[46:47], v[76:77] op_sel:[0,0] op_sel_hi:[0,1]
	v_pk_mul_f32 v[48:49], v[66:67], v[72:73] op_sel:[0,0] op_sel_hi:[0,1]
	v_pk_fma_f32 v[42:43], v[54:55], v[28:29], v[42:43] op_sel:[1,1,0] op_sel_hi:[1,0,1] neg_lo:[0,1,0]
	s_waitcnt vmcnt(5)
	v_pk_mul_f32 v[54:55], v[60:61], v[80:81] op_sel:[0,0] op_sel_hi:[0,1]
	v_pk_add_f32 v[110:111], v[44:45], v[26:27] op_sel:[0,1] op_sel_hi:[1,0] neg_hi:[0,1]
	v_pk_add_f32 v[112:113], v[44:45], v[26:27] op_sel:[0,1] op_sel_hi:[1,0] neg_lo:[0,1]
	v_pk_mul_f32 v[28:29], v[56:57], v[32:33] op_sel:[0,0] op_sel_hi:[0,1]
	v_pk_fma_f32 v[52:53], v[46:47], v[76:77], v[50:51] op_sel:[1,1,0] op_sel_hi:[1,0,1] neg_lo:[0,1,0]
	v_pk_mul_f32 v[46:47], v[62:63], v[86:87] op_sel:[0,0] op_sel_hi:[0,1]
	v_pk_mul_f32 v[50:51], v[64:65], v[82:83] op_sel:[0,0] op_sel_hi:[0,1]
	v_pk_mul_f32 v[26:27], v[98:99], v[70:71] op_sel:[0,0] op_sel_hi:[0,1]
	s_waitcnt vmcnt(2)
	v_pk_mul_f32 v[58:59], v[110:111], v[90:91] op_sel:[0,0] op_sel_hi:[0,1]
	v_pk_fma_f32 v[44:45], v[56:57], v[32:33], v[28:29] op_sel:[1,1,0] op_sel_hi:[1,0,1] neg_lo:[0,1,0]
	v_pk_fma_f32 v[56:57], v[60:61], v[80:81], v[54:55] op_sel:[1,1,0] op_sel_hi:[1,0,1] neg_lo:[0,1,0]
	v_pk_mul_f32 v[54:55], v[102:103], v[84:85] op_sel:[0,0] op_sel_hi:[0,1]
	v_pk_mul_f32 v[28:29], v[100:101], v[78:79] op_sel:[0,0] op_sel_hi:[0,1]
	v_pk_mul_f32 v[32:33], v[68:69], v[74:75] op_sel:[0,0] op_sel_hi:[0,1]
	v_pk_fma_f32 v[46:47], v[62:63], v[86:87], v[46:47] op_sel:[1,1,0] op_sel_hi:[1,0,1] neg_lo:[0,1,0]
	v_pk_fma_f32 v[50:51], v[64:65], v[82:83], v[50:51] op_sel:[1,1,0] op_sel_hi:[1,0,1] neg_lo:[0,1,0]
	s_waitcnt vmcnt(1)
	v_pk_mul_f32 v[62:63], v[106:107], v[88:89] op_sel:[0,0] op_sel_hi:[0,1]
	v_pk_fma_f32 v[60:61], v[102:103], v[84:85], v[54:55] op_sel:[1,1,0] op_sel_hi:[1,0,1] neg_lo:[0,1,0]
	v_pk_mul_f32 v[54:55], v[104:105], v[94:95] op_sel:[0,0] op_sel_hi:[0,1]
	s_waitcnt vmcnt(0)
	v_pk_mul_f32 v[64:65], v[112:113], v[92:93] op_sel:[0,0] op_sel_hi:[0,1]
	v_pk_fma_f32 v[26:27], v[98:99], v[70:71], v[26:27] op_sel:[1,1,0] op_sel_hi:[1,0,1] neg_lo:[0,1,0]
	v_pk_fma_f32 v[28:29], v[100:101], v[78:79], v[28:29] op_sel:[1,1,0] op_sel_hi:[1,0,1] neg_lo:[0,1,0]
	v_pk_fma_f32 v[32:33], v[68:69], v[74:75], v[32:33] op_sel:[1,1,0] op_sel_hi:[1,0,1] neg_lo:[0,1,0]
	v_pk_fma_f32 v[48:49], v[66:67], v[72:73], v[48:49] op_sel:[1,1,0] op_sel_hi:[1,0,1] neg_lo:[0,1,0]
	v_pk_fma_f32 v[54:55], v[104:105], v[94:95], v[54:55] op_sel:[1,1,0] op_sel_hi:[1,0,1] neg_lo:[0,1,0]
	v_pk_fma_f32 v[58:59], v[110:111], v[90:91], v[58:59] op_sel:[1,1,0] op_sel_hi:[1,0,1] neg_lo:[0,1,0]
	v_pk_fma_f32 v[62:63], v[106:107], v[88:89], v[62:63] op_sel:[1,1,0] op_sel_hi:[1,0,1] neg_lo:[0,1,0]
	v_pk_fma_f32 v[64:65], v[112:113], v[92:93], v[64:65] op_sel:[1,1,0] op_sel_hi:[1,0,1] neg_lo:[0,1,0]
	s_cbranch_scc1 .LBB0_3486
	s_mul_i32 s15, s0, 0x4400
	s_mul_hi_u32 s1, s0, 0x4400
	s_add_u32 s28, s11, s15
	s_addc_u32 s29, s10, s1
	s_add_i32 s1, s0, 0x400
	s_add_i32 s79, s15, 0x1100000
	s_mul_hi_u32 s1, s1, 0x4400
	v_lshlrev_b32_e32 v2, 3, v133
	s_add_u32 s80, s11, s79
	v_ashrrev_i32_e32 v3, 31, v2
	s_addc_u32 s81, s10, s1
	s_addk_i32 s0, 0x800
	s_add_i32 s15, s15, 0x2200000
	v_lshlrev_b64 v[18:19], 1, v[2:3]
	v_add_u32_e32 v2, 0x1000, v2
	s_mul_hi_u32 s1, s0, 0x4400
	s_add_u32 s0, s11, s15
	v_ashrrev_i32_e32 v3, 31, v2
	s_addc_u32 s1, s10, s1
	v_lshlrev_b64 v[20:21], 1, v[2:3]
	v_lshl_add_u64 v[4:5], s[28:29], 0, v[18:19]
	v_lshl_add_u64 v[6:7], s[28:29], 0, v[20:21]
	v_lshl_add_u64 v[10:11], s[80:81], 0, v[18:19]
	v_lshl_add_u64 v[14:15], s[80:81], 0, v[20:21]
	v_lshl_add_u64 v[18:19], s[0:1], 0, v[18:19]
	v_lshl_add_u64 v[22:23], s[0:1], 0, v[20:21]
	global_load_dwordx4 v[2:5], v[4:5], off
	s_nop 0
	global_load_dwordx4 v[6:9], v[6:7], off
	s_nop 0
	global_load_dwordx4 v[10:13], v[10:11], off
	s_nop 0
	global_load_dwordx4 v[14:17], v[14:15], off
	s_nop 0
	global_load_dwordx4 v[18:21], v[18:19], off
	s_nop 0
	global_load_dwordx4 v[22:25], v[22:23], off
.LBB0_3486:
	v_pk_add_f32 v[66:67], v[26:27], v[42:43]
	v_pk_add_f32 v[26:27], v[26:27], v[42:43] neg_lo:[0,1] neg_hi:[0,1]
	v_pk_add_f32 v[42:43], v[30:31], v[44:45]
	v_pk_add_f32 v[30:31], v[30:31], v[44:45] neg_lo:[0,1] neg_hi:[0,1]
	v_pk_add_f32 v[68:69], v[66:67], v[42:43]
	v_pk_add_f32 v[70:71], v[26:27], v[30:31] op_sel:[0,1] op_sel_hi:[1,0] neg_lo:[0,1]
	v_pk_add_f32 v[72:73], v[26:27], v[30:31] op_sel:[0,1] op_sel_hi:[1,0] neg_hi:[0,1]
	v_pk_add_f32 v[26:27], v[28:29], v[48:49]
	v_pk_add_f32 v[28:29], v[28:29], v[48:49] neg_lo:[0,1] neg_hi:[0,1]
	v_pk_add_f32 v[30:31], v[32:33], v[52:53]
	v_pk_add_f32 v[32:33], v[32:33], v[52:53] neg_lo:[0,1] neg_hi:[0,1]
	v_pk_add_f32 v[66:67], v[66:67], v[42:43] neg_lo:[0,1] neg_hi:[0,1]
	v_pk_add_f32 v[48:49], v[26:27], v[30:31]
	v_pk_add_f32 v[30:31], v[26:27], v[30:31] neg_lo:[0,1] neg_hi:[0,1]
	v_pk_add_f32 v[26:27], v[28:29], v[32:33] op_sel:[0,1] op_sel_hi:[1,0] neg_lo:[0,1]
	v_pk_add_f32 v[44:45], v[28:29], v[32:33] op_sel:[0,1] op_sel_hi:[1,0] neg_hi:[0,1]
	v_pk_add_f32 v[28:29], v[46:47], v[56:57]
	v_pk_add_f32 v[32:33], v[46:47], v[56:57] neg_lo:[0,1] neg_hi:[0,1]
	v_pk_add_f32 v[42:43], v[50:51], v[60:61]
	v_pk_add_f32 v[46:47], v[50:51], v[60:61] neg_lo:[0,1] neg_hi:[0,1]
	v_pk_add_f32 v[50:51], v[28:29], v[42:43]
	v_pk_add_f32 v[52:53], v[28:29], v[42:43] neg_lo:[0,1] neg_hi:[0,1]
	v_pk_add_f32 v[42:43], v[32:33], v[46:47] op_sel:[0,1] op_sel_hi:[1,0] neg_lo:[0,1]
	v_pk_add_f32 v[46:47], v[32:33], v[46:47] op_sel:[0,1] op_sel_hi:[1,0] neg_hi:[0,1]
	v_pk_add_f32 v[28:29], v[54:55], v[62:63]
	v_pk_add_f32 v[32:33], v[54:55], v[62:63] neg_lo:[0,1] neg_hi:[0,1]
	v_pk_add_f32 v[54:55], v[58:59], v[64:65]
	v_pk_add_f32 v[56:57], v[58:59], v[64:65] neg_lo:[0,1] neg_hi:[0,1]
	v_pk_add_f32 v[58:59], v[28:29], v[54:55]
	v_pk_add_f32 v[54:55], v[28:29], v[54:55] neg_lo:[0,1] neg_hi:[0,1]
	v_pk_add_f32 v[60:61], v[32:33], v[56:57] op_sel:[0,1] op_sel_hi:[1,0] neg_lo:[0,1]
	v_pk_add_f32 v[56:57], v[32:33], v[56:57] op_sel:[0,1] op_sel_hi:[1,0] neg_hi:[0,1]
	v_pk_mul_f32 v[28:29], v[26:27], s[58:59] op_sel:[0,0] op_sel_hi:[0,1]
	v_pk_fma_f32 v[62:63], v[26:27], s[58:59], v[28:29] op_sel:[1,1,0] op_sel_hi:[1,0,1] neg_lo:[0,1,0]
	v_pk_mul_f32 v[26:27], v[42:43], s[60:61] op_sel:[0,0] op_sel_hi:[0,1]
	v_pk_fma_f32 v[64:65], v[42:43], s[60:61], v[26:27] op_sel:[1,1,0] op_sel_hi:[1,0,1] neg_lo:[0,1,0]
	v_pk_mul_f32 v[42:43], v[60:61], s[62:63] op_sel:[0,0] op_sel_hi:[0,1]
	v_pk_fma_f32 v[60:61], v[60:61], s[62:63], v[42:43] op_sel:[1,1,0] op_sel_hi:[1,0,1] neg_lo:[0,1,0]
	v_pk_mul_f32 v[42:43], v[30:31], s[60:61] op_sel:[0,0] op_sel_hi:[0,1]
	v_pk_fma_f32 v[74:75], v[30:31], s[60:61], v[42:43] op_sel:[1,1,0] op_sel_hi:[1,0,1] neg_lo:[0,1,0]
	v_pk_mul_f32 v[30:31], v[52:53], s[64:65] op_sel:[0,0] op_sel_hi:[0,1]
	v_pk_fma_f32 v[52:53], v[52:53], s[64:65], v[30:31] op_sel:[1,1,0] op_sel_hi:[1,0,1] neg_lo:[0,1,0]
	v_pk_mul_f32 v[76:77], v[54:55], s[66:67] op_sel:[0,0] op_sel_hi:[0,1]
	v_pk_fma_f32 v[54:55], v[54:55], s[66:67], v[76:77] op_sel:[1,1,0] op_sel_hi:[1,0,1] neg_lo:[0,1,0]
	v_pk_mul_f32 v[76:77], v[44:45], s[62:63] op_sel:[0,0] op_sel_hi:[0,1]
	v_pk_fma_f32 v[76:77], v[44:45], s[62:63], v[76:77] op_sel:[1,1,0] op_sel_hi:[1,0,1] neg_lo:[0,1,0]
	v_pk_mul_f32 v[44:45], v[46:47], s[66:67] op_sel:[0,0] op_sel_hi:[0,1]
	v_pk_fma_f32 v[46:47], v[46:47], s[66:67], v[44:45] op_sel:[1,1,0] op_sel_hi:[1,0,1] neg_lo:[0,1,0]
	v_pk_mul_f32 v[78:79], v[56:57], s[68:69] op_sel:[0,0] op_sel_hi:[0,1]
	v_pk_fma_f32 v[56:57], v[56:57], s[68:69], v[78:79] op_sel:[1,1,0] op_sel_hi:[1,0,1] neg_lo:[0,1,0]
	v_pk_add_f32 v[78:79], v[68:69], v[50:51]
	v_pk_add_f32 v[50:51], v[68:69], v[50:51] neg_lo:[0,1] neg_hi:[0,1]
	v_pk_add_f32 v[68:69], v[48:49], v[58:59]
	v_pk_add_f32 v[48:49], v[48:49], v[58:59] neg_lo:[0,1] neg_hi:[0,1]
	v_pk_add_f32 v[58:59], v[78:79], v[68:69]
	v_pk_add_f32 v[68:69], v[78:79], v[68:69] neg_lo:[0,1] neg_hi:[0,1]
	v_pk_add_f32 v[78:79], v[50:51], v[48:49] op_sel:[0,1] op_sel_hi:[1,0] neg_lo:[0,1]
	v_pk_add_f32 v[48:49], v[50:51], v[48:49] op_sel:[0,1] op_sel_hi:[1,0] neg_hi:[0,1]
	v_pk_add_f32 v[50:51], v[70:71], v[64:65]
	v_pk_add_f32 v[64:65], v[70:71], v[64:65] neg_lo:[0,1] neg_hi:[0,1]
	v_pk_add_f32 v[70:71], v[62:63], v[60:61]
	v_pk_add_f32 v[60:61], v[62:63], v[60:61] neg_lo:[0,1] neg_hi:[0,1]
	v_pk_add_f32 v[62:63], v[50:51], v[70:71]
	v_pk_add_f32 v[50:51], v[50:51], v[70:71] neg_lo:[0,1] neg_hi:[0,1]
	v_pk_add_f32 v[70:71], v[64:65], v[60:61] op_sel:[0,1] op_sel_hi:[1,0] neg_lo:[0,1]
	v_pk_add_f32 v[60:61], v[64:65], v[60:61] op_sel:[0,1] op_sel_hi:[1,0] neg_hi:[0,1]
	v_pk_add_f32 v[64:65], v[66:67], v[52:53]
	v_pk_add_f32 v[52:53], v[66:67], v[52:53] neg_lo:[0,1] neg_hi:[0,1]
	v_pk_add_f32 v[66:67], v[74:75], v[54:55]
	v_pk_add_f32 v[54:55], v[74:75], v[54:55] neg_lo:[0,1] neg_hi:[0,1]
	v_pk_add_f32 v[74:75], v[64:65], v[66:67]
	v_pk_add_f32 v[64:65], v[64:65], v[66:67] neg_lo:[0,1] neg_hi:[0,1]
	v_pk_add_f32 v[66:67], v[52:53], v[54:55] op_sel:[0,1] op_sel_hi:[1,0] neg_lo:[0,1]
	v_pk_add_f32 v[52:53], v[52:53], v[54:55] op_sel:[0,1] op_sel_hi:[1,0] neg_hi:[0,1]
	v_pk_add_f32 v[54:55], v[72:73], v[46:47]
	v_pk_add_f32 v[46:47], v[72:73], v[46:47] neg_lo:[0,1] neg_hi:[0,1]
	v_pk_add_f32 v[72:73], v[76:77], v[56:57]
	v_pk_add_f32 v[56:57], v[76:77], v[56:57] neg_lo:[0,1] neg_hi:[0,1]
	v_pk_add_f32 v[76:77], v[54:55], v[72:73]
	v_pk_add_f32 v[54:55], v[54:55], v[72:73] neg_lo:[0,1] neg_hi:[0,1]
	v_pk_add_f32 v[72:73], v[46:47], v[56:57] op_sel:[0,1] op_sel_hi:[1,0] neg_lo:[0,1]
	v_pk_add_f32 v[46:47], v[46:47], v[56:57] op_sel:[0,1] op_sel_hi:[1,0] neg_hi:[0,1]
	ds_write2_b64 v135, v[58:59], v[62:63] offset1:1
	ds_write2_b64 v135, v[74:75], v[76:77] offset0:2 offset1:3
	ds_write2_b64 v135, v[78:79], v[70:71] offset0:4 offset1:5
	ds_write2_b64 v135, v[66:67], v[72:73] offset0:6 offset1:7
	ds_write2_b64 v135, v[68:69], v[50:51] offset0:8 offset1:9
	ds_write2_b64 v135, v[64:65], v[54:55] offset0:10 offset1:11
	ds_write2_b64 v135, v[48:49], v[60:61] offset0:12 offset1:13
	ds_write2_b64 v135, v[52:53], v[46:47] offset0:14 offset1:15
	s_waitcnt lgkmcnt(0)
	s_barrier
	ds_read2_b64 v[46:49], v134 offset1:17
	ds_read2_b64 v[50:53], v134 offset0:34 offset1:51
	s_waitcnt lgkmcnt(1)
	v_pk_mul_f32 v[54:55], v[48:49], v[40:41] op_sel:[0,0] op_sel_hi:[0,1] neg_hi:[0,1]
	v_pk_fma_f32 v[56:57], v[48:49], v[40:41], v[54:55] op_sel:[1,1,0] op_sel_hi:[1,0,1]
	v_pk_mul_f32 v[48:49], v[40:41], v[40:41] op_sel:[0,0] op_sel_hi:[0,1]
	v_pk_fma_f32 v[48:49], v[40:41], v[40:41], v[48:49] op_sel:[1,1,0] op_sel_hi:[1,0,1] neg_lo:[0,1,0]
	s_waitcnt lgkmcnt(0)
	v_pk_mul_f32 v[54:55], v[50:51], v[48:49] op_sel:[0,0] op_sel_hi:[0,1] neg_hi:[0,1]
	v_pk_fma_f32 v[58:59], v[50:51], v[48:49], v[54:55] op_sel:[1,1,0] op_sel_hi:[1,0,1]
	v_pk_mul_f32 v[50:51], v[48:49], v[40:41] op_sel:[0,0] op_sel_hi:[0,1]
	v_pk_fma_f32 v[54:55], v[48:49], v[40:41], v[50:51] op_sel:[1,1,0] op_sel_hi:[1,0,1] neg_lo:[0,1,0]
	ds_read2_b64 v[48:51], v134 offset0:68 offset1:85
	v_pk_mul_f32 v[60:61], v[52:53], v[54:55] op_sel:[0,0] op_sel_hi:[0,1] neg_hi:[0,1]
	v_pk_fma_f32 v[60:61], v[52:53], v[54:55], v[60:61] op_sel:[1,1,0] op_sel_hi:[1,0,1]
	v_pk_mul_f32 v[52:53], v[54:55], v[40:41] op_sel:[0,0] op_sel_hi:[0,1]
	v_pk_fma_f32 v[52:53], v[54:55], v[40:41], v[52:53] op_sel:[1,1,0] op_sel_hi:[1,0,1] neg_lo:[0,1,0]
	s_waitcnt lgkmcnt(0)
	v_pk_mul_f32 v[54:55], v[48:49], v[52:53] op_sel:[0,0] op_sel_hi:[0,1] neg_hi:[0,1]
	v_pk_fma_f32 v[62:63], v[48:49], v[52:53], v[54:55] op_sel:[1,1,0] op_sel_hi:[1,0,1]
	v_pk_mul_f32 v[48:49], v[52:53], v[40:41] op_sel:[0,0] op_sel_hi:[0,1]
	v_pk_fma_f32 v[48:49], v[52:53], v[40:41], v[48:49] op_sel:[1,1,0] op_sel_hi:[1,0,1] neg_lo:[0,1,0]
	ds_read2_b64 v[52:55], v134 offset0:102 offset1:119
	v_pk_mul_f32 v[64:65], v[50:51], v[48:49] op_sel:[0,0] op_sel_hi:[0,1] neg_hi:[0,1]
	v_pk_fma_f32 v[64:65], v[50:51], v[48:49], v[64:65] op_sel:[1,1,0] op_sel_hi:[1,0,1]
	v_pk_mul_f32 v[50:51], v[48:49], v[40:41] op_sel:[0,0] op_sel_hi:[0,1]
	v_pk_fma_f32 v[48:49], v[48:49], v[40:41], v[50:51] op_sel:[1,1,0] op_sel_hi:[1,0,1] neg_lo:[0,1,0]
	s_waitcnt lgkmcnt(0)
	v_pk_mul_f32 v[50:51], v[52:53], v[48:49] op_sel:[0,0] op_sel_hi:[0,1] neg_hi:[0,1]
	v_pk_fma_f32 v[66:67], v[52:53], v[48:49], v[50:51] op_sel:[1,1,0] op_sel_hi:[1,0,1]
	v_pk_mul_f32 v[50:51], v[48:49], v[40:41] op_sel:[0,0] op_sel_hi:[0,1]
	v_pk_fma_f32 v[52:53], v[48:49], v[40:41], v[50:51] op_sel:[1,1,0] op_sel_hi:[1,0,1] neg_lo:[0,1,0]
	ds_read2_b64 v[48:51], v134 offset0:136 offset1:153
	v_pk_mul_f32 v[68:69], v[54:55], v[52:53] op_sel:[0,0] op_sel_hi:[0,1] neg_hi:[0,1]
	v_pk_fma_f32 v[68:69], v[54:55], v[52:53], v[68:69] op_sel:[1,1,0] op_sel_hi:[1,0,1]
	v_pk_mul_f32 v[54:55], v[52:53], v[40:41] op_sel:[0,0] op_sel_hi:[0,1]
	v_pk_fma_f32 v[52:53], v[52:53], v[40:41], v[54:55] op_sel:[1,1,0] op_sel_hi:[1,0,1] neg_lo:[0,1,0]
	s_waitcnt lgkmcnt(0)
	v_pk_mul_f32 v[54:55], v[48:49], v[52:53] op_sel:[0,0] op_sel_hi:[0,1] neg_hi:[0,1]
	v_pk_fma_f32 v[70:71], v[48:49], v[52:53], v[54:55] op_sel:[1,1,0] op_sel_hi:[1,0,1]
	v_pk_mul_f32 v[48:49], v[52:53], v[40:41] op_sel:[0,0] op_sel_hi:[0,1]
	v_pk_fma_f32 v[48:49], v[52:53], v[40:41], v[48:49] op_sel:[1,1,0] op_sel_hi:[1,0,1] neg_lo:[0,1,0]
	ds_read2_b64 v[52:55], v134 offset0:170 offset1:187
	v_pk_mul_f32 v[72:73], v[50:51], v[48:49] op_sel:[0,0] op_sel_hi:[0,1] neg_hi:[0,1]
	v_pk_fma_f32 v[72:73], v[50:51], v[48:49], v[72:73] op_sel:[1,1,0] op_sel_hi:[1,0,1]
	v_pk_mul_f32 v[50:51], v[48:49], v[40:41] op_sel:[0,0] op_sel_hi:[0,1]
	v_pk_fma_f32 v[48:49], v[48:49], v[40:41], v[50:51] op_sel:[1,1,0] op_sel_hi:[1,0,1] neg_lo:[0,1,0]
	s_waitcnt lgkmcnt(0)
	v_pk_mul_f32 v[50:51], v[52:53], v[48:49] op_sel:[0,0] op_sel_hi:[0,1] neg_hi:[0,1]
	v_pk_fma_f32 v[74:75], v[52:53], v[48:49], v[50:51] op_sel:[1,1,0] op_sel_hi:[1,0,1]
	v_pk_mul_f32 v[50:51], v[48:49], v[40:41] op_sel:[0,0] op_sel_hi:[0,1]
	v_pk_fma_f32 v[52:53], v[48:49], v[40:41], v[50:51] op_sel:[1,1,0] op_sel_hi:[1,0,1] neg_lo:[0,1,0]
	ds_read2_b64 v[48:51], v134 offset0:204 offset1:221
	v_pk_mul_f32 v[76:77], v[54:55], v[52:53] op_sel:[0,0] op_sel_hi:[0,1] neg_hi:[0,1]
	v_pk_fma_f32 v[76:77], v[54:55], v[52:53], v[76:77] op_sel:[1,1,0] op_sel_hi:[1,0,1]
	v_pk_mul_f32 v[54:55], v[52:53], v[40:41] op_sel:[0,0] op_sel_hi:[0,1]
	v_pk_fma_f32 v[52:53], v[52:53], v[40:41], v[54:55] op_sel:[1,1,0] op_sel_hi:[1,0,1] neg_lo:[0,1,0]
	s_waitcnt lgkmcnt(0)
	v_pk_mul_f32 v[54:55], v[48:49], v[52:53] op_sel:[0,0] op_sel_hi:[0,1] neg_hi:[0,1]
	v_pk_fma_f32 v[48:49], v[48:49], v[52:53], v[54:55] op_sel:[1,1,0] op_sel_hi:[1,0,1]
	v_pk_mul_f32 v[54:55], v[52:53], v[40:41] op_sel:[0,0] op_sel_hi:[0,1]
	v_pk_fma_f32 v[78:79], v[52:53], v[40:41], v[54:55] op_sel:[1,1,0] op_sel_hi:[1,0,1] neg_lo:[0,1,0]
	ds_read2_b64 v[52:55], v134 offset0:238 offset1:255
	v_pk_mul_f32 v[80:81], v[50:51], v[78:79] op_sel:[0,0] op_sel_hi:[0,1] neg_hi:[0,1]
	v_pk_fma_f32 v[50:51], v[50:51], v[78:79], v[80:81] op_sel:[1,1,0] op_sel_hi:[1,0,1]
	v_pk_mul_f32 v[80:81], v[78:79], v[40:41] op_sel:[0,0] op_sel_hi:[0,1]
	v_pk_fma_f32 v[78:79], v[78:79], v[40:41], v[80:81] op_sel:[1,1,0] op_sel_hi:[1,0,1] neg_lo:[0,1,0]
	s_waitcnt lgkmcnt(0)
	v_pk_mul_f32 v[80:81], v[52:53], v[78:79] op_sel:[0,0] op_sel_hi:[0,1] neg_hi:[0,1]
	v_pk_fma_f32 v[52:53], v[52:53], v[78:79], v[80:81] op_sel:[1,1,0] op_sel_hi:[1,0,1]
	v_pk_mul_f32 v[80:81], v[78:79], v[40:41] op_sel:[0,0] op_sel_hi:[0,1]
	v_pk_fma_f32 v[40:41], v[78:79], v[40:41], v[80:81] op_sel:[1,1,0] op_sel_hi:[1,0,1] neg_lo:[0,1,0]
	v_pk_mul_f32 v[78:79], v[54:55], v[40:41] op_sel:[0,0] op_sel_hi:[0,1] neg_hi:[0,1]
	v_pk_fma_f32 v[40:41], v[54:55], v[40:41], v[78:79] op_sel:[1,1,0] op_sel_hi:[1,0,1]
	v_pk_add_f32 v[54:55], v[46:47], v[70:71]
	v_pk_add_f32 v[46:47], v[46:47], v[70:71] neg_lo:[0,1] neg_hi:[0,1]
	v_pk_add_f32 v[70:71], v[62:63], v[48:49]
	v_pk_add_f32 v[48:49], v[62:63], v[48:49] neg_lo:[0,1] neg_hi:[0,1]
	v_pk_add_f32 v[62:63], v[54:55], v[70:71]
	v_pk_add_f32 v[54:55], v[54:55], v[70:71] neg_lo:[0,1] neg_hi:[0,1]
	v_pk_add_f32 v[70:71], v[46:47], v[48:49] op_sel:[0,1] op_sel_hi:[1,0] neg_lo:[0,1]
	v_pk_add_f32 v[46:47], v[46:47], v[48:49] op_sel:[0,1] op_sel_hi:[1,0] neg_hi:[0,1]
	v_pk_add_f32 v[48:49], v[56:57], v[72:73]
	v_pk_add_f32 v[56:57], v[56:57], v[72:73] neg_lo:[0,1] neg_hi:[0,1]
	v_pk_add_f32 v[72:73], v[64:65], v[50:51]
	v_pk_add_f32 v[50:51], v[64:65], v[50:51] neg_lo:[0,1] neg_hi:[0,1]
	v_pk_add_f32 v[64:65], v[48:49], v[72:73]
	v_pk_add_f32 v[48:49], v[48:49], v[72:73] neg_lo:[0,1] neg_hi:[0,1]
	v_pk_add_f32 v[72:73], v[56:57], v[50:51] op_sel:[0,1] op_sel_hi:[1,0] neg_lo:[0,1]
	v_pk_add_f32 v[50:51], v[56:57], v[50:51] op_sel:[0,1] op_sel_hi:[1,0] neg_hi:[0,1]
	v_pk_add_f32 v[56:57], v[58:59], v[74:75]
	v_pk_add_f32 v[58:59], v[58:59], v[74:75] neg_lo:[0,1] neg_hi:[0,1]
	v_pk_add_f32 v[74:75], v[66:67], v[52:53]
	v_pk_add_f32 v[52:53], v[66:67], v[52:53] neg_lo:[0,1] neg_hi:[0,1]
	v_pk_add_f32 v[66:67], v[56:57], v[74:75]
	v_pk_add_f32 v[56:57], v[56:57], v[74:75] neg_lo:[0,1] neg_hi:[0,1]
	v_pk_add_f32 v[74:75], v[58:59], v[52:53] op_sel:[0,1] op_sel_hi:[1,0] neg_lo:[0,1]
	v_pk_add_f32 v[52:53], v[58:59], v[52:53] op_sel:[0,1] op_sel_hi:[1,0] neg_hi:[0,1]
	v_pk_add_f32 v[58:59], v[60:61], v[76:77]
	v_pk_add_f32 v[60:61], v[60:61], v[76:77] neg_lo:[0,1] neg_hi:[0,1]
	v_pk_add_f32 v[76:77], v[68:69], v[40:41]
	v_pk_add_f32 v[40:41], v[68:69], v[40:41] neg_lo:[0,1] neg_hi:[0,1]
	v_pk_add_f32 v[68:69], v[58:59], v[76:77]
	v_pk_add_f32 v[58:59], v[58:59], v[76:77] neg_lo:[0,1] neg_hi:[0,1]
	v_pk_add_f32 v[76:77], v[60:61], v[40:41] op_sel:[0,1] op_sel_hi:[1,0] neg_lo:[0,1]
	v_pk_add_f32 v[40:41], v[60:61], v[40:41] op_sel:[0,1] op_sel_hi:[1,0] neg_hi:[0,1]
	v_pk_mul_f32 v[60:61], v[72:73], s[58:59] op_sel:[0,0] op_sel_hi:[0,1]
	v_pk_fma_f32 v[60:61], v[72:73], s[58:59], v[60:61] op_sel:[1,1,0] op_sel_hi:[1,0,1] neg_lo:[0,1,0]
	v_pk_mul_f32 v[72:73], v[74:75], s[60:61] op_sel:[0,0] op_sel_hi:[0,1]
	v_pk_fma_f32 v[72:73], v[74:75], s[60:61], v[72:73] op_sel:[1,1,0] op_sel_hi:[1,0,1] neg_lo:[0,1,0]
	v_pk_mul_f32 v[74:75], v[76:77], s[62:63] op_sel:[0,0] op_sel_hi:[0,1]
	v_pk_fma_f32 v[74:75], v[76:77], s[62:63], v[74:75] op_sel:[1,1,0] op_sel_hi:[1,0,1] neg_lo:[0,1,0]
	v_pk_mul_f32 v[76:77], v[48:49], s[60:61] op_sel:[0,0] op_sel_hi:[0,1]
	v_pk_fma_f32 v[48:49], v[48:49], s[60:61], v[76:77] op_sel:[1,1,0] op_sel_hi:[1,0,1] neg_lo:[0,1,0]
	v_pk_mul_f32 v[76:77], v[56:57], s[64:65] op_sel:[0,0] op_sel_hi:[0,1]
	v_pk_fma_f32 v[56:57], v[56:57], s[64:65], v[76:77] op_sel:[1,1,0] op_sel_hi:[1,0,1] neg_lo:[0,1,0]
	v_pk_mul_f32 v[76:77], v[58:59], s[66:67] op_sel:[0,0] op_sel_hi:[0,1]
	v_pk_fma_f32 v[58:59], v[58:59], s[66:67], v[76:77] op_sel:[1,1,0] op_sel_hi:[1,0,1] neg_lo:[0,1,0]
	v_pk_mul_f32 v[76:77], v[50:51], s[62:63] op_sel:[0,0] op_sel_hi:[0,1]
	v_pk_fma_f32 v[50:51], v[50:51], s[62:63], v[76:77] op_sel:[1,1,0] op_sel_hi:[1,0,1] neg_lo:[0,1,0]
	v_pk_mul_f32 v[76:77], v[52:53], s[66:67] op_sel:[0,0] op_sel_hi:[0,1]
	v_pk_fma_f32 v[52:53], v[52:53], s[66:67], v[76:77] op_sel:[1,1,0] op_sel_hi:[1,0,1] neg_lo:[0,1,0]
	v_pk_mul_f32 v[76:77], v[40:41], s[68:69] op_sel:[0,0] op_sel_hi:[0,1]
	v_pk_fma_f32 v[40:41], v[40:41], s[68:69], v[76:77] op_sel:[1,1,0] op_sel_hi:[1,0,1] neg_lo:[0,1,0]
	v_pk_add_f32 v[76:77], v[62:63], v[66:67]
	v_pk_add_f32 v[62:63], v[62:63], v[66:67] neg_lo:[0,1] neg_hi:[0,1]
	v_pk_add_f32 v[66:67], v[64:65], v[68:69]
	v_pk_add_f32 v[64:65], v[64:65], v[68:69] neg_lo:[0,1] neg_hi:[0,1]
	v_pk_add_f32 v[68:69], v[76:77], v[66:67]
	v_pk_add_f32 v[66:67], v[76:77], v[66:67] neg_lo:[0,1] neg_hi:[0,1]
	v_pk_add_f32 v[76:77], v[62:63], v[64:65] op_sel:[0,1] op_sel_hi:[1,0] neg_lo:[0,1]
	v_pk_add_f32 v[62:63], v[62:63], v[64:65] op_sel:[0,1] op_sel_hi:[1,0] neg_hi:[0,1]
	v_pk_add_f32 v[64:65], v[70:71], v[72:73]
	v_pk_add_f32 v[70:71], v[70:71], v[72:73] neg_lo:[0,1] neg_hi:[0,1]
	v_pk_add_f32 v[72:73], v[60:61], v[74:75]
	v_pk_add_f32 v[60:61], v[60:61], v[74:75] neg_lo:[0,1] neg_hi:[0,1]
	v_pk_add_f32 v[74:75], v[64:65], v[72:73]
	v_pk_add_f32 v[64:65], v[64:65], v[72:73] neg_lo:[0,1] neg_hi:[0,1]
	v_pk_add_f32 v[72:73], v[70:71], v[60:61] op_sel:[0,1] op_sel_hi:[1,0] neg_lo:[0,1]
	v_pk_add_f32 v[60:61], v[70:71], v[60:61] op_sel:[0,1] op_sel_hi:[1,0] neg_hi:[0,1]
	v_pk_add_f32 v[70:71], v[54:55], v[56:57]
	v_pk_add_f32 v[54:55], v[54:55], v[56:57] neg_lo:[0,1] neg_hi:[0,1]
	v_pk_add_f32 v[56:57], v[48:49], v[58:59]
	v_pk_add_f32 v[48:49], v[48:49], v[58:59] neg_lo:[0,1] neg_hi:[0,1]
	v_pk_add_f32 v[58:59], v[70:71], v[56:57]
	v_pk_add_f32 v[56:57], v[70:71], v[56:57] neg_lo:[0,1] neg_hi:[0,1]
	v_pk_add_f32 v[70:71], v[54:55], v[48:49] op_sel:[0,1] op_sel_hi:[1,0] neg_lo:[0,1]
	v_pk_add_f32 v[48:49], v[54:55], v[48:49] op_sel:[0,1] op_sel_hi:[1,0] neg_hi:[0,1]
	v_pk_add_f32 v[54:55], v[46:47], v[52:53]
	v_pk_add_f32 v[46:47], v[46:47], v[52:53] neg_lo:[0,1] neg_hi:[0,1]
	v_pk_add_f32 v[52:53], v[50:51], v[40:41]
	v_pk_add_f32 v[40:41], v[50:51], v[40:41] neg_lo:[0,1] neg_hi:[0,1]
	v_pk_add_f32 v[50:51], v[54:55], v[52:53]
	v_pk_add_f32 v[52:53], v[54:55], v[52:53] neg_lo:[0,1] neg_hi:[0,1]
	v_pk_add_f32 v[54:55], v[46:47], v[40:41] op_sel:[0,1] op_sel_hi:[1,0] neg_lo:[0,1]
	v_pk_add_f32 v[40:41], v[46:47], v[40:41] op_sel:[0,1] op_sel_hi:[1,0] neg_hi:[0,1]
	ds_write2_b64 v134, v[68:69], v[74:75] offset1:17
	ds_write2_b64 v134, v[58:59], v[50:51] offset0:34 offset1:51
	ds_write2_b64 v134, v[76:77], v[72:73] offset0:68 offset1:85
	ds_write2_b64 v134, v[70:71], v[54:55] offset0:102 offset1:119
	ds_write2_b64 v134, v[66:67], v[64:65] offset0:136 offset1:153
	ds_write2_b64 v134, v[56:57], v[52:53] offset0:170 offset1:187
	ds_write2_b64 v134, v[62:63], v[60:61] offset0:204 offset1:221
	ds_write2_b64 v134, v[48:49], v[40:41] offset0:238 offset1:255
	s_waitcnt lgkmcnt(0)
	s_barrier
	ds_read_b64 v[40:41], v132 offset:2176
	ds_read_b64 v[46:47], v132 offset:4352
	ds_read_b64 v[48:49], v132 offset:6528
	ds_read_b64 v[50:51], v132
	s_waitcnt lgkmcnt(3)
	v_pk_mul_f32 v[52:53], v[40:41], v[38:39] op_sel:[0,0] op_sel_hi:[0,1] neg_hi:[0,1]
	v_pk_fma_f32 v[40:41], v[40:41], v[38:39], v[52:53] op_sel:[1,1,0] op_sel_hi:[1,0,1]
	v_pk_mul_f32 v[52:53], v[38:39], v[38:39] op_sel:[0,0] op_sel_hi:[0,1]
	ds_read_b64 v[56:57], v132 offset:8704
	v_pk_fma_f32 v[52:53], v[38:39], v[38:39], v[52:53] op_sel:[1,1,0] op_sel_hi:[1,0,1] neg_lo:[0,1,0]
	s_waitcnt lgkmcnt(3)
	v_pk_mul_f32 v[54:55], v[46:47], v[52:53] op_sel:[0,0] op_sel_hi:[0,1] neg_hi:[0,1]
	v_pk_fma_f32 v[46:47], v[46:47], v[52:53], v[54:55] op_sel:[1,1,0] op_sel_hi:[1,0,1]
	v_pk_mul_f32 v[54:55], v[52:53], v[38:39] op_sel:[0,0] op_sel_hi:[0,1]
	v_pk_fma_f32 v[52:53], v[52:53], v[38:39], v[54:55] op_sel:[1,1,0] op_sel_hi:[1,0,1] neg_lo:[0,1,0]
	s_waitcnt lgkmcnt(2)
	v_pk_mul_f32 v[54:55], v[48:49], v[52:53] op_sel:[0,0] op_sel_hi:[0,1] neg_hi:[0,1]
	v_pk_fma_f32 v[48:49], v[48:49], v[52:53], v[54:55] op_sel:[1,1,0] op_sel_hi:[1,0,1]
	v_pk_mul_f32 v[54:55], v[52:53], v[38:39] op_sel:[0,0] op_sel_hi:[0,1]
	v_pk_fma_f32 v[52:53], v[52:53], v[38:39], v[54:55] op_sel:[1,1,0] op_sel_hi:[1,0,1] neg_lo:[0,1,0]
	ds_read_b64 v[54:55], v132 offset:10880
	ds_read_b64 v[58:59], v132 offset:13056
	ds_read_b64 v[60:61], v132 offset:15232
	s_waitcnt lgkmcnt(3)
	v_pk_mul_f32 v[62:63], v[56:57], v[52:53] op_sel:[0,0] op_sel_hi:[0,1] neg_hi:[0,1]
	ds_read_b64 v[64:65], v132 offset:17408
	v_pk_fma_f32 v[56:57], v[56:57], v[52:53], v[62:63] op_sel:[1,1,0] op_sel_hi:[1,0,1]
	v_pk_mul_f32 v[62:63], v[52:53], v[38:39] op_sel:[0,0] op_sel_hi:[0,1]
	v_pk_fma_f32 v[52:53], v[52:53], v[38:39], v[62:63] op_sel:[1,1,0] op_sel_hi:[1,0,1] neg_lo:[0,1,0]
	s_waitcnt lgkmcnt(3)
	v_pk_mul_f32 v[62:63], v[54:55], v[52:53] op_sel:[0,0] op_sel_hi:[0,1] neg_hi:[0,1]
	v_pk_fma_f32 v[54:55], v[54:55], v[52:53], v[62:63] op_sel:[1,1,0] op_sel_hi:[1,0,1]
	v_pk_mul_f32 v[62:63], v[52:53], v[38:39] op_sel:[0,0] op_sel_hi:[0,1]
	v_pk_fma_f32 v[52:53], v[52:53], v[38:39], v[62:63] op_sel:[1,1,0] op_sel_hi:[1,0,1] neg_lo:[0,1,0]
	s_waitcnt lgkmcnt(2)
	v_pk_mul_f32 v[62:63], v[58:59], v[52:53] op_sel:[0,0] op_sel_hi:[0,1] neg_hi:[0,1]
	v_pk_fma_f32 v[58:59], v[58:59], v[52:53], v[62:63] op_sel:[1,1,0] op_sel_hi:[1,0,1]
	v_pk_mul_f32 v[62:63], v[52:53], v[38:39] op_sel:[0,0] op_sel_hi:[0,1]
	v_pk_fma_f32 v[52:53], v[52:53], v[38:39], v[62:63] op_sel:[1,1,0] op_sel_hi:[1,0,1] neg_lo:[0,1,0]
	s_waitcnt lgkmcnt(1)
	v_pk_mul_f32 v[62:63], v[60:61], v[52:53] op_sel:[0,0] op_sel_hi:[0,1] neg_hi:[0,1]
	v_pk_fma_f32 v[60:61], v[60:61], v[52:53], v[62:63] op_sel:[1,1,0] op_sel_hi:[1,0,1]
	v_pk_mul_f32 v[62:63], v[52:53], v[38:39] op_sel:[0,0] op_sel_hi:[0,1]
	v_pk_fma_f32 v[52:53], v[52:53], v[38:39], v[62:63] op_sel:[1,1,0] op_sel_hi:[1,0,1] neg_lo:[0,1,0]
	ds_read_b64 v[62:63], v132 offset:19584
	ds_read_b64 v[66:67], v132 offset:21760
	ds_read_b64 v[68:69], v132 offset:23936
	s_waitcnt lgkmcnt(3)
	v_pk_mul_f32 v[70:71], v[64:65], v[52:53] op_sel:[0,0] op_sel_hi:[0,1] neg_hi:[0,1]
	ds_read_b64 v[72:73], v132 offset:26112
	v_pk_fma_f32 v[64:65], v[64:65], v[52:53], v[70:71] op_sel:[1,1,0] op_sel_hi:[1,0,1]
	v_pk_mul_f32 v[70:71], v[52:53], v[38:39] op_sel:[0,0] op_sel_hi:[0,1]
	v_pk_fma_f32 v[52:53], v[52:53], v[38:39], v[70:71] op_sel:[1,1,0] op_sel_hi:[1,0,1] neg_lo:[0,1,0]
	s_waitcnt lgkmcnt(3)
	v_pk_mul_f32 v[70:71], v[62:63], v[52:53] op_sel:[0,0] op_sel_hi:[0,1] neg_hi:[0,1]
	v_pk_fma_f32 v[62:63], v[62:63], v[52:53], v[70:71] op_sel:[1,1,0] op_sel_hi:[1,0,1]
	v_pk_mul_f32 v[70:71], v[52:53], v[38:39] op_sel:[0,0] op_sel_hi:[0,1]
	v_pk_fma_f32 v[52:53], v[52:53], v[38:39], v[70:71] op_sel:[1,1,0] op_sel_hi:[1,0,1] neg_lo:[0,1,0]
	s_waitcnt lgkmcnt(2)
	v_pk_mul_f32 v[70:71], v[66:67], v[52:53] op_sel:[0,0] op_sel_hi:[0,1] neg_hi:[0,1]
	v_pk_fma_f32 v[66:67], v[66:67], v[52:53], v[70:71] op_sel:[1,1,0] op_sel_hi:[1,0,1]
	v_pk_mul_f32 v[70:71], v[52:53], v[38:39] op_sel:[0,0] op_sel_hi:[0,1]
	v_pk_fma_f32 v[52:53], v[52:53], v[38:39], v[70:71] op_sel:[1,1,0] op_sel_hi:[1,0,1] neg_lo:[0,1,0]
	s_waitcnt lgkmcnt(1)
	v_pk_mul_f32 v[70:71], v[68:69], v[52:53] op_sel:[0,0] op_sel_hi:[0,1] neg_hi:[0,1]
	v_pk_fma_f32 v[68:69], v[68:69], v[52:53], v[70:71] op_sel:[1,1,0] op_sel_hi:[1,0,1]
	v_pk_mul_f32 v[70:71], v[52:53], v[38:39] op_sel:[0,0] op_sel_hi:[0,1]
	v_pk_fma_f32 v[52:53], v[52:53], v[38:39], v[70:71] op_sel:[1,1,0] op_sel_hi:[1,0,1] neg_lo:[0,1,0]
	ds_read_b64 v[70:71], v132 offset:28288
	ds_read_b64 v[74:75], v132 offset:30464
	ds_read_b64 v[76:77], v132 offset:32640
	s_waitcnt lgkmcnt(3)
	v_pk_mul_f32 v[78:79], v[72:73], v[52:53] op_sel:[0,0] op_sel_hi:[0,1] neg_hi:[0,1]
	s_nop 0
	v_pk_fma_f32 v[72:73], v[72:73], v[52:53], v[78:79] op_sel:[1,1,0] op_sel_hi:[1,0,1]
	v_pk_mul_f32 v[78:79], v[52:53], v[38:39] op_sel:[0,0] op_sel_hi:[0,1]
	v_pk_fma_f32 v[52:53], v[52:53], v[38:39], v[78:79] op_sel:[1,1,0] op_sel_hi:[1,0,1] neg_lo:[0,1,0]
	s_waitcnt lgkmcnt(2)
	v_pk_mul_f32 v[78:79], v[70:71], v[52:53] op_sel:[0,0] op_sel_hi:[0,1] neg_hi:[0,1]
	v_pk_fma_f32 v[70:71], v[70:71], v[52:53], v[78:79] op_sel:[1,1,0] op_sel_hi:[1,0,1]
	v_pk_mul_f32 v[78:79], v[52:53], v[38:39] op_sel:[0,0] op_sel_hi:[0,1]
	v_pk_fma_f32 v[52:53], v[52:53], v[38:39], v[78:79] op_sel:[1,1,0] op_sel_hi:[1,0,1] neg_lo:[0,1,0]
	s_waitcnt lgkmcnt(1)
	v_pk_mul_f32 v[78:79], v[74:75], v[52:53] op_sel:[0,0] op_sel_hi:[0,1] neg_hi:[0,1]
	v_pk_fma_f32 v[74:75], v[74:75], v[52:53], v[78:79] op_sel:[1,1,0] op_sel_hi:[1,0,1]
	v_pk_mul_f32 v[78:79], v[52:53], v[38:39] op_sel:[0,0] op_sel_hi:[0,1]
	v_pk_fma_f32 v[38:39], v[52:53], v[38:39], v[78:79] op_sel:[1,1,0] op_sel_hi:[1,0,1] neg_lo:[0,1,0]
	s_waitcnt lgkmcnt(0)
	v_pk_mul_f32 v[52:53], v[76:77], v[38:39] op_sel:[0,0] op_sel_hi:[0,1] neg_hi:[0,1]
	v_pk_fma_f32 v[38:39], v[76:77], v[38:39], v[52:53] op_sel:[1,1,0] op_sel_hi:[1,0,1]
	v_pk_add_f32 v[52:53], v[50:51], v[64:65]
	v_pk_add_f32 v[50:51], v[50:51], v[64:65] neg_lo:[0,1] neg_hi:[0,1]
	v_pk_add_f32 v[64:65], v[56:57], v[72:73]
	v_pk_add_f32 v[56:57], v[56:57], v[72:73] neg_lo:[0,1] neg_hi:[0,1]
	v_pk_add_f32 v[72:73], v[52:53], v[64:65]
	v_pk_add_f32 v[76:77], v[50:51], v[56:57] op_sel:[0,1] op_sel_hi:[1,0] neg_lo:[0,1]
	v_pk_add_f32 v[78:79], v[50:51], v[56:57] op_sel:[0,1] op_sel_hi:[1,0] neg_hi:[0,1]
	v_pk_add_f32 v[50:51], v[40:41], v[62:63]
	v_pk_add_f32 v[40:41], v[40:41], v[62:63] neg_lo:[0,1] neg_hi:[0,1]
	v_pk_add_f32 v[56:57], v[54:55], v[70:71]
	v_pk_add_f32 v[54:55], v[54:55], v[70:71] neg_lo:[0,1] neg_hi:[0,1]
	v_pk_add_f32 v[52:53], v[52:53], v[64:65] neg_lo:[0,1] neg_hi:[0,1]
	v_pk_add_f32 v[62:63], v[50:51], v[56:57]
	v_pk_add_f32 v[50:51], v[50:51], v[56:57] neg_lo:[0,1] neg_hi:[0,1]
	v_pk_add_f32 v[56:57], v[40:41], v[54:55] op_sel:[0,1] op_sel_hi:[1,0] neg_lo:[0,1]
	v_pk_add_f32 v[40:41], v[40:41], v[54:55] op_sel:[0,1] op_sel_hi:[1,0] neg_hi:[0,1]
	v_pk_add_f32 v[54:55], v[46:47], v[66:67]
	v_pk_add_f32 v[46:47], v[46:47], v[66:67] neg_lo:[0,1] neg_hi:[0,1]
	v_pk_add_f32 v[64:65], v[58:59], v[74:75]
	v_pk_add_f32 v[58:59], v[58:59], v[74:75] neg_lo:[0,1] neg_hi:[0,1]
	v_pk_add_f32 v[66:67], v[54:55], v[64:65]
	v_pk_add_f32 v[54:55], v[54:55], v[64:65] neg_lo:[0,1] neg_hi:[0,1]
	v_pk_add_f32 v[64:65], v[46:47], v[58:59] op_sel:[0,1] op_sel_hi:[1,0] neg_lo:[0,1]
	v_pk_add_f32 v[46:47], v[46:47], v[58:59] op_sel:[0,1] op_sel_hi:[1,0] neg_hi:[0,1]
	v_pk_add_f32 v[58:59], v[48:49], v[68:69]
	v_pk_add_f32 v[48:49], v[48:49], v[68:69] neg_lo:[0,1] neg_hi:[0,1]
	v_pk_add_f32 v[68:69], v[60:61], v[38:39]
	v_pk_add_f32 v[38:39], v[60:61], v[38:39] neg_lo:[0,1] neg_hi:[0,1]
	v_pk_add_f32 v[60:61], v[58:59], v[68:69]
	v_pk_add_f32 v[58:59], v[58:59], v[68:69] neg_lo:[0,1] neg_hi:[0,1]
	v_pk_add_f32 v[68:69], v[48:49], v[38:39] op_sel:[0,1] op_sel_hi:[1,0] neg_lo:[0,1]
	v_pk_add_f32 v[38:39], v[48:49], v[38:39] op_sel:[0,1] op_sel_hi:[1,0] neg_hi:[0,1]
	v_pk_mul_f32 v[48:49], v[56:57], s[58:59] op_sel:[0,0] op_sel_hi:[0,1]
	v_pk_fma_f32 v[32:33], v[56:57], s[58:59], v[48:49] op_sel:[1,1,0] op_sel_hi:[1,0,1] neg_lo:[0,1,0]
	v_pk_mul_f32 v[48:49], v[64:65], s[60:61] op_sel:[0,0] op_sel_hi:[0,1]
	v_pk_mul_f32 v[56:57], v[68:69], s[62:63] op_sel:[0,0] op_sel_hi:[0,1]
	v_pk_fma_f32 v[48:49], v[64:65], s[60:61], v[48:49] op_sel:[1,1,0] op_sel_hi:[1,0,1] neg_lo:[0,1,0]
	v_pk_fma_f32 v[56:57], v[68:69], s[62:63], v[56:57] op_sel:[1,1,0] op_sel_hi:[1,0,1] neg_lo:[0,1,0]
	v_pk_mul_f32 v[64:65], v[50:51], s[60:61] op_sel:[0,0] op_sel_hi:[0,1]
	v_pk_fma_f32 v[68:69], v[50:51], s[60:61], v[64:65] op_sel:[1,1,0] op_sel_hi:[1,0,1] neg_lo:[0,1,0]
	v_pk_mul_f32 v[28:29], v[54:55], s[64:65] op_sel:[0,0] op_sel_hi:[0,1]
	v_pk_fma_f32 v[54:55], v[54:55], s[64:65], v[28:29] op_sel:[1,1,0] op_sel_hi:[1,0,1] neg_lo:[0,1,0]
	v_pk_mul_f32 v[28:29], v[58:59], s[66:67] op_sel:[0,0] op_sel_hi:[0,1]
	v_pk_add_f32 v[42:43], v[62:63], v[60:61]
	v_pk_fma_f32 v[58:59], v[58:59], s[66:67], v[28:29] op_sel:[1,1,0] op_sel_hi:[1,0,1] neg_lo:[0,1,0]
	v_pk_mul_f32 v[28:29], v[40:41], s[62:63] op_sel:[0,0] op_sel_hi:[0,1]
	v_pk_add_f32 v[50:51], v[52:53], v[54:55]
	v_pk_fma_f32 v[70:71], v[40:41], s[62:63], v[28:29] op_sel:[1,1,0] op_sel_hi:[1,0,1] neg_lo:[0,1,0]
	v_pk_mul_f32 v[26:27], v[46:47], s[66:67] op_sel:[0,0] op_sel_hi:[0,1]
	v_pk_add_f32 v[28:29], v[62:63], v[60:61] neg_lo:[0,1] neg_hi:[0,1]
	v_pk_fma_f32 v[74:75], v[46:47], s[66:67], v[26:27] op_sel:[1,1,0] op_sel_hi:[1,0,1] neg_lo:[0,1,0]
	v_pk_mul_f32 v[26:27], v[38:39], s[68:69] op_sel:[0,0] op_sel_hi:[0,1]
	v_pk_add_f32 v[30:31], v[32:33], v[56:57] neg_lo:[0,1] neg_hi:[0,1]
	v_pk_fma_f32 v[80:81], v[38:39], s[68:69], v[26:27] op_sel:[1,1,0] op_sel_hi:[1,0,1] neg_lo:[0,1,0]
	v_pk_add_f32 v[26:27], v[72:73], v[66:67] neg_lo:[0,1] neg_hi:[0,1]
	v_pk_add_f32 v[38:39], v[72:73], v[66:67]
	v_pk_add_f32 v[40:41], v[26:27], v[28:29] op_sel:[0,1] op_sel_hi:[1,0] neg_lo:[0,1]
	v_pk_add_f32 v[26:27], v[26:27], v[28:29] op_sel:[0,1] op_sel_hi:[1,0] neg_hi:[0,1]
	v_pk_add_f32 v[28:29], v[76:77], v[48:49] neg_lo:[0,1] neg_hi:[0,1]
	v_pk_add_f32 v[44:45], v[76:77], v[48:49]
	v_pk_add_f32 v[48:49], v[32:33], v[56:57]
	v_pk_add_f32 v[46:47], v[28:29], v[30:31] op_sel:[0,1] op_sel_hi:[1,0] neg_lo:[0,1]
	v_pk_add_f32 v[28:29], v[28:29], v[30:31] op_sel:[0,1] op_sel_hi:[1,0] neg_hi:[0,1]
	v_pk_add_f32 v[30:31], v[52:53], v[54:55] neg_lo:[0,1] neg_hi:[0,1]
	v_pk_add_f32 v[54:55], v[68:69], v[58:59]
	v_pk_add_f32 v[32:33], v[68:69], v[58:59] neg_lo:[0,1] neg_hi:[0,1]
	v_pk_add_f32 v[56:57], v[78:79], v[74:75]
	v_pk_add_f32 v[60:61], v[70:71], v[80:81]
	v_pk_add_f32 v[64:65], v[38:39], v[42:43]
	v_pk_add_f32 v[66:67], v[44:45], v[48:49]
	v_pk_add_f32 v[68:69], v[50:51], v[54:55]
	v_pk_add_f32 v[52:53], v[30:31], v[32:33] op_sel:[0,1] op_sel_hi:[1,0] neg_lo:[0,1]
	v_pk_add_f32 v[30:31], v[30:31], v[32:33] op_sel:[0,1] op_sel_hi:[1,0] neg_hi:[0,1]
	v_pk_add_f32 v[32:33], v[78:79], v[74:75] neg_lo:[0,1] neg_hi:[0,1]
	v_pk_add_f32 v[62:63], v[56:57], v[60:61]
	v_pk_add_f32 v[70:71], v[70:71], v[80:81] neg_lo:[0,1] neg_hi:[0,1]
	s_nop 0
	v_pk_add_f32 v[58:59], v[32:33], v[70:71] op_sel:[0,1] op_sel_hi:[1,0] neg_lo:[0,1]
	v_pk_add_f32 v[32:33], v[32:33], v[70:71] op_sel:[0,1] op_sel_hi:[1,0] neg_hi:[0,1]
	s_and_saveexec_b64 s[0:1], s[4:5]
	s_xor_b64 s[0:1], exec, s[0:1]
	s_cbranch_execz .LBB0_3488
	v_pk_mul_f32 v[72:73], v[36:37], s[12:13] op_sel:[0,0] op_sel_hi:[0,1]
	v_pk_fma_f32 v[70:71], v[36:37], s[12:13], v[72:73] op_sel:[1,1,0] op_sel_hi:[1,0,1] neg_lo:[0,1,0]
	v_pk_mul_f32 v[72:73], v[64:65], v[70:71] op_sel:[0,0] op_sel_hi:[0,1] neg_hi:[0,1]
	v_pk_fma_f32 v[64:65], v[64:65], v[70:71], v[72:73] op_sel:[1,1,0] op_sel_hi:[1,0,1]
	v_pk_mul_f32 v[72:73], v[36:37], s[16:17] op_sel:[0,0] op_sel_hi:[0,1]
	v_pk_fma_f32 v[70:71], v[36:37], s[16:17], v[72:73] op_sel:[1,1,0] op_sel_hi:[1,0,1] neg_lo:[0,1,0]
	v_pk_mul_f32 v[72:73], v[66:67], v[70:71] op_sel:[0,0] op_sel_hi:[0,1] neg_hi:[0,1]
	v_pk_fma_f32 v[66:67], v[66:67], v[70:71], v[72:73] op_sel:[1,1,0] op_sel_hi:[1,0,1]
	v_pk_mul_f32 v[72:73], v[36:37], s[20:21] op_sel:[0,0] op_sel_hi:[0,1]
	v_pk_fma_f32 v[70:71], v[36:37], s[20:21], v[72:73] op_sel:[1,1,0] op_sel_hi:[1,0,1] neg_lo:[0,1,0]
	v_pk_mul_f32 v[72:73], v[68:69], v[70:71] op_sel:[0,0] op_sel_hi:[0,1] neg_hi:[0,1]
	v_pk_fma_f32 v[68:69], v[68:69], v[70:71], v[72:73] op_sel:[1,1,0] op_sel_hi:[1,0,1]
	v_pk_mul_f32 v[72:73], v[36:37], s[22:23] op_sel:[0,0] op_sel_hi:[0,1]
	v_pk_fma_f32 v[70:71], v[36:37], s[22:23], v[72:73] op_sel:[1,1,0] op_sel_hi:[1,0,1] neg_lo:[0,1,0]
	v_pk_mul_f32 v[72:73], v[62:63], v[70:71] op_sel:[0,0] op_sel_hi:[0,1] neg_hi:[0,1]
	v_pk_fma_f32 v[62:63], v[62:63], v[70:71], v[72:73] op_sel:[1,1,0] op_sel_hi:[1,0,1]
	ds_write_b64 v132, v[64:65]
	ds_write_b64 v132, v[66:67] offset:2176
	ds_write_b64 v132, v[68:69] offset:4352
	ds_write_b64 v132, v[62:63] offset:6528
	v_pk_mul_f32 v[64:65], v[36:37], s[46:47] op_sel:[0,0] op_sel_hi:[0,1]
	s_nop 0
	v_pk_fma_f32 v[62:63], v[36:37], s[46:47], v[64:65] op_sel:[1,1,0] op_sel_hi:[1,0,1] neg_lo:[0,1,0]
	v_pk_mul_f32 v[64:65], v[40:41], v[62:63] op_sel:[0,0] op_sel_hi:[0,1] neg_hi:[0,1]
	v_pk_fma_f32 v[40:41], v[40:41], v[62:63], v[64:65] op_sel:[1,1,0] op_sel_hi:[1,0,1]
	v_pk_mul_f32 v[64:65], v[36:37], s[48:49] op_sel:[0,0] op_sel_hi:[0,1]
	v_pk_fma_f32 v[62:63], v[36:37], s[48:49], v[64:65] op_sel:[1,1,0] op_sel_hi:[1,0,1] neg_lo:[0,1,0]
	v_pk_mul_f32 v[64:65], v[46:47], v[62:63] op_sel:[0,0] op_sel_hi:[0,1] neg_hi:[0,1]
	v_pk_fma_f32 v[46:47], v[46:47], v[62:63], v[64:65] op_sel:[1,1,0] op_sel_hi:[1,0,1]
	v_pk_mul_f32 v[64:65], v[36:37], s[50:51] op_sel:[0,0] op_sel_hi:[0,1]
	v_pk_fma_f32 v[62:63], v[36:37], s[50:51], v[64:65] op_sel:[1,1,0] op_sel_hi:[1,0,1] neg_lo:[0,1,0]
	v_pk_mul_f32 v[64:65], v[52:53], v[62:63] op_sel:[0,0] op_sel_hi:[0,1] neg_hi:[0,1]
	v_pk_fma_f32 v[52:53], v[52:53], v[62:63], v[64:65] op_sel:[1,1,0] op_sel_hi:[1,0,1]
	v_pk_mul_f32 v[64:65], v[36:37], s[52:53] op_sel:[0,0] op_sel_hi:[0,1]
	v_pk_fma_f32 v[62:63], v[36:37], s[52:53], v[64:65] op_sel:[1,1,0] op_sel_hi:[1,0,1] neg_lo:[0,1,0]
	v_pk_mul_f32 v[64:65], v[58:59], v[62:63] op_sel:[0,0] op_sel_hi:[0,1] neg_hi:[0,1]
	s_nop 0
	v_pk_fma_f32 v[58:59], v[58:59], v[62:63], v[64:65] op_sel:[1,1,0] op_sel_hi:[1,0,1]

.LBB0_3490:
	s_or_b64 exec, exec, s[0:1]
	v_pk_add_f32 v[62:63], v[38:39], v[42:43] neg_lo:[0,1] neg_hi:[0,1]
	v_pk_add_f32 v[44:45], v[44:45], v[48:49] neg_lo:[0,1] neg_hi:[0,1]
	v_pk_add_f32 v[42:43], v[50:51], v[54:55] neg_lo:[0,1] neg_hi:[0,1]
	v_pk_add_f32 v[38:39], v[56:57], v[60:61] neg_lo:[0,1] neg_hi:[0,1]
	ds_write_b64 v132, v[40:41] offset:8704
	ds_write_b64 v132, v[46:47] offset:10880
	ds_write_b64 v132, v[52:53] offset:13056
	ds_write_b64 v132, v[58:59] offset:15232
	s_and_saveexec_b64 s[0:1], s[4:5]
	s_xor_b64 s[0:1], exec, s[0:1]
	s_cbranch_execz .LBB0_3492
	v_pk_mul_f32 v[46:47], v[36:37], s[8:9] op_sel:[0,0] op_sel_hi:[0,1]
	s_mov_b32 s15, s53
	v_pk_fma_f32 v[40:41], v[36:37], s[8:9], v[46:47] op_sel:[1,1,0] op_sel_hi:[1,0,1] neg_lo:[0,1,0]
	s_mov_b32 s4, s23
	v_pk_mul_f32 v[46:47], v[62:63], v[40:41] op_sel:[0,0] op_sel_hi:[0,1] neg_hi:[0,1]
	s_mov_b32 s5, s49
	v_pk_fma_f32 v[40:41], v[62:63], v[40:41], v[46:47] op_sel:[1,1,0] op_sel_hi:[1,0,1]
	v_pk_mul_f32 v[48:49], v[36:37], s[14:15] op_sel:[0,0] op_sel_hi:[0,1]
	s_nop 0
	v_pk_fma_f32 v[46:47], v[36:37], s[14:15], v[48:49] op_sel:[1,1,0] op_sel_hi:[1,0,1] neg_lo:[0,1,0]
	v_pk_mul_f32 v[48:49], v[44:45], v[46:47] op_sel:[0,0] op_sel_hi:[0,1] neg_hi:[0,1]
	v_pk_fma_f32 v[44:45], v[44:45], v[46:47], v[48:49] op_sel:[1,1,0] op_sel_hi:[1,0,1]
	v_pk_mul_f32 v[48:49], v[36:37], s[18:19] op_sel:[0,0] op_sel_hi:[0,1]
	v_pk_fma_f32 v[46:47], v[36:37], s[18:19], v[48:49] op_sel:[1,1,0] op_sel_hi:[1,0,1] neg_lo:[0,1,0]
	v_pk_mul_f32 v[48:49], v[42:43], v[46:47] op_sel:[0,0] op_sel_hi:[0,1] neg_hi:[0,1]
	v_pk_fma_f32 v[42:43], v[42:43], v[46:47], v[48:49] op_sel:[1,1,0] op_sel_hi:[1,0,1]
	v_mov_b64_e32 v[46:47], s[4:5]
	v_pk_mul_f32 v[48:49], v[36:37], v[46:47] op_sel:[0,0] op_sel_hi:[0,1]
	s_mov_b32 s4, s49
	v_pk_fma_f32 v[46:47], v[36:37], v[46:47], v[48:49] op_sel:[1,1,0] op_sel_hi:[1,0,1] neg_lo:[0,1,0]
	s_mov_b32 s5, s23
	v_pk_mul_f32 v[48:49], v[38:39], v[46:47] op_sel:[0,0] op_sel_hi:[0,1] neg_hi:[0,1]
	v_pk_fma_f32 v[38:39], v[38:39], v[46:47], v[48:49] op_sel:[1,1,0] op_sel_hi:[1,0,1]
	ds_write_b64 v132, v[40:41] offset:17408
	ds_write_b64 v132, v[44:45] offset:19584
	ds_write_b64 v132, v[42:43] offset:21760
	ds_write_b64 v132, v[38:39] offset:23936
	v_pk_mul_f32 v[40:41], v[36:37], s[54:55] op_sel:[0,0] op_sel_hi:[0,1]
	s_nop 0
	v_pk_fma_f32 v[38:39], v[36:37], s[54:55], v[40:41] op_sel:[1,1,0] op_sel_hi:[1,0,1] neg_lo:[0,1,0]
	v_pk_mul_f32 v[40:41], v[26:27], v[38:39] op_sel:[0,0] op_sel_hi:[0,1] neg_hi:[0,1]
	v_pk_fma_f32 v[26:27], v[26:27], v[38:39], v[40:41] op_sel:[1,1,0] op_sel_hi:[1,0,1]
	v_mov_b64_e32 v[38:39], s[4:5]
	v_pk_mul_f32 v[40:41], v[36:37], v[38:39] op_sel:[0,0] op_sel_hi:[0,1]
	s_mov_b32 s4, s53
	v_pk_fma_f32 v[38:39], v[36:37], v[38:39], v[40:41] op_sel:[1,1,0] op_sel_hi:[1,0,1] neg_lo:[0,1,0]
	s_mov_b32 s5, s14
	v_pk_mul_f32 v[40:41], v[28:29], v[38:39] op_sel:[0,0] op_sel_hi:[0,1] neg_hi:[0,1]
	v_pk_fma_f32 v[28:29], v[28:29], v[38:39], v[40:41] op_sel:[1,1,0] op_sel_hi:[1,0,1]
	v_pk_mul_f32 v[40:41], v[36:37], s[68:69] op_sel:[0,0] op_sel_hi:[0,1]
	v_pk_fma_f32 v[38:39], v[36:37], s[68:69], v[40:41] op_sel:[1,1,0] op_sel_hi:[1,0,1] neg_lo:[0,1,0]
	v_pk_mul_f32 v[40:41], v[30:31], v[38:39] op_sel:[0,0] op_sel_hi:[0,1] neg_hi:[0,1]
	v_pk_fma_f32 v[30:31], v[30:31], v[38:39], v[40:41] op_sel:[1,1,0] op_sel_hi:[1,0,1]
	v_pk_mul_f32 v[40:41], v[36:37], s[4:5] op_sel:[0,0] op_sel_hi:[0,1]
	v_pk_fma_f32 v[36:37], v[36:37], s[4:5], v[40:41] op_sel:[1,1,0] op_sel_hi:[1,0,1] neg_lo:[0,1,0]
	v_pk_mul_f32 v[38:39], v[32:33], v[36:37] op_sel:[0,0] op_sel_hi:[0,1] neg_hi:[0,1]
	s_nop 0
	v_pk_fma_f32 v[32:33], v[32:33], v[36:37], v[38:39] op_sel:[1,1,0] op_sel_hi:[1,0,1]

.LBB0_3752:
	v_ashrrev_i32_e32 v37, 8, v18
	v_and_b32_e32 v34, 0xff, v18
	v_lshlrev_b32_e32 v19, 13, v37
	v_lshlrev_b32_e32 v20, 1, v34
	v_add3_u32 v38, s25, v19, v20
	v_add3_u32 v19, s53, v19, v20
	ds_read_u16 v20, v38
	ds_read_u16 v22, v38 offset:512
	ds_read_u16 v24, v38 offset:1024
	ds_read_u16 v26, v38 offset:1536
	ds_read_u16 v28, v38 offset:2048
	ds_read_u16 v39, v38 offset:2560
	ds_read_u16 v42, v38 offset:3072
	ds_read_u16 v44, v38 offset:3584
	ds_read_u16 v21, v19
	ds_read_u16 v23, v19 offset:512
	ds_read_u16 v25, v19 offset:1024
	ds_read_u16 v27, v19 offset:1536
	ds_read_u16 v29, v19 offset:2048
	ds_read_u16 v41, v19 offset:2560
	ds_read_u16 v43, v19 offset:3072
	ds_read_u16 v45, v19 offset:3584
	s_waitcnt lgkmcnt(7)
	v_lshlrev_b32_e32 v21, 16, v21
	v_lshlrev_b32_e32 v40, 16, v39
	s_waitcnt lgkmcnt(2)
	v_lshlrev_b32_e32 v39, 16, v41
	v_xor_b32_e32 v41, 0x80000000, v39
	s_waitcnt lgkmcnt(1)
	v_lshlrev_b32_e32 v39, 16, v43
	v_xor_b32_e32 v43, 0x80000000, v39
	s_waitcnt lgkmcnt(0)
	v_lshlrev_b32_e32 v39, 16, v45
	v_xor_b32_e32 v45, 0x80000000, v39
	ds_read_u16 v39, v38 offset:4096
	ds_read_u16 v48, v38 offset:4608
	ds_read_u16 v50, v38 offset:5120
	ds_read_u16 v52, v38 offset:5632
	ds_read_u16 v54, v38 offset:6144
	ds_read_u16 v56, v38 offset:6656
	ds_read_u16 v58, v38 offset:7168
	ds_read_u16 v38, v38 offset:7680
	s_waitcnt lgkmcnt(7)
	v_lshlrev_b32_e32 v46, 16, v39
	ds_read_u16 v39, v19 offset:4096
	ds_read_u16 v49, v19 offset:4608
	ds_read_u16 v51, v19 offset:5120
	ds_read_u16 v53, v19 offset:5632
	ds_read_u16 v55, v19 offset:6144
	ds_read_u16 v57, v19 offset:6656
	ds_read_u16 v59, v19 offset:7168
	ds_read_u16 v19, v19 offset:7680
	s_waitcnt lgkmcnt(7)
	v_lshlrev_b32_e32 v39, 16, v39
	v_xor_b32_e32 v47, 0x80000000, v39
	s_waitcnt lgkmcnt(6)
	v_lshlrev_b32_e32 v39, 16, v49
	v_xor_b32_e32 v49, 0x80000000, v39
	s_waitcnt lgkmcnt(5)
	v_lshlrev_b32_e32 v39, 16, v51
	v_xor_b32_e32 v51, 0x80000000, v39
	s_waitcnt lgkmcnt(4)
	v_lshlrev_b32_e32 v39, 16, v53
	v_lshlrev_b32_e32 v29, 16, v29
	v_xor_b32_e32 v53, 0x80000000, v39
	s_waitcnt lgkmcnt(3)
	v_lshlrev_b32_e32 v39, 16, v55
	v_lshlrev_b32_e32 v20, 16, v20
	v_xor_b32_e32 v21, 0x80000000, v21
	v_lshlrev_b32_e32 v23, 16, v23
	v_lshlrev_b32_e32 v28, 16, v28
	v_xor_b32_e32 v29, 0x80000000, v29
	v_lshlrev_b32_e32 v54, 16, v54
	v_xor_b32_e32 v55, 0x80000000, v39
	s_waitcnt lgkmcnt(2)
	v_lshlrev_b32_e32 v39, 16, v57
	s_waitcnt lgkmcnt(0)
	v_lshlrev_b32_e32 v19, 16, v19
	v_lshlrev_b32_e32 v22, 16, v22
	v_xor_b32_e32 v23, 0x80000000, v23
	v_lshlrev_b32_e32 v25, 16, v25
	v_lshlrev_b32_e32 v48, 16, v48
	v_lshlrev_b32_e32 v56, 16, v56
	v_xor_b32_e32 v57, 0x80000000, v39
	v_lshlrev_b32_e32 v39, 16, v59
	v_lshlrev_b32_e32 v60, 16, v38
	v_xor_b32_e32 v61, 0x80000000, v19
	v_bfe_u32 v38, v18, 4, 4
	v_pk_add_f32 v[18:19], v[20:21], v[46:47]
	v_pk_add_f32 v[20:21], v[20:21], v[46:47] neg_lo:[0,1] neg_hi:[0,1]
	v_pk_add_f32 v[46:47], v[28:29], v[54:55]
	v_pk_add_f32 v[28:29], v[28:29], v[54:55] neg_lo:[0,1] neg_hi:[0,1]
	v_lshlrev_b32_e32 v24, 16, v24
	v_xor_b32_e32 v25, 0x80000000, v25
	v_lshlrev_b32_e32 v27, 16, v27
	v_lshlrev_b32_e32 v42, 16, v42
	v_lshlrev_b32_e32 v50, 16, v50
	v_lshlrev_b32_e32 v58, 16, v58
	v_xor_b32_e32 v59, 0x80000000, v39
	v_pk_add_f32 v[54:55], v[18:19], v[46:47]
	v_pk_add_f32 v[46:47], v[18:19], v[46:47] neg_lo:[0,1] neg_hi:[0,1]
	v_pk_add_f32 v[62:63], v[20:21], v[28:29] op_sel:[0,1] op_sel_hi:[1,0] neg_hi:[0,1]
	v_pk_add_f32 v[64:65], v[20:21], v[28:29] op_sel:[0,1] op_sel_hi:[1,0] neg_lo:[0,1]
	v_pk_add_f32 v[18:19], v[22:23], v[48:49]
	v_pk_add_f32 v[20:21], v[22:23], v[48:49] neg_lo:[0,1] neg_hi:[0,1]
	v_pk_add_f32 v[22:23], v[40:41], v[56:57]
	v_pk_add_f32 v[28:29], v[40:41], v[56:57] neg_lo:[0,1] neg_hi:[0,1]
	v_lshlrev_b32_e32 v26, 16, v26
	v_xor_b32_e32 v27, 0x80000000, v27
	v_lshlrev_b32_e32 v44, 16, v44
	v_lshlrev_b32_e32 v52, 16, v52
	v_pk_add_f32 v[40:41], v[18:19], v[22:23]
	v_pk_add_f32 v[22:23], v[18:19], v[22:23] neg_lo:[0,1] neg_hi:[0,1]
	v_pk_add_f32 v[18:19], v[20:21], v[28:29] op_sel:[0,1] op_sel_hi:[1,0] neg_hi:[0,1]
	v_pk_add_f32 v[28:29], v[20:21], v[28:29] op_sel:[0,1] op_sel_hi:[1,0] neg_lo:[0,1]
	v_pk_add_f32 v[20:21], v[24:25], v[50:51]
	v_pk_add_f32 v[24:25], v[24:25], v[50:51] neg_lo:[0,1] neg_hi:[0,1]
	v_pk_add_f32 v[48:49], v[42:43], v[58:59]
	v_pk_add_f32 v[42:43], v[42:43], v[58:59] neg_lo:[0,1] neg_hi:[0,1]
	v_pk_add_f32 v[50:51], v[20:21], v[48:49]
	v_pk_add_f32 v[48:49], v[20:21], v[48:49] neg_lo:[0,1] neg_hi:[0,1]
	v_pk_add_f32 v[56:57], v[24:25], v[42:43] op_sel:[0,1] op_sel_hi:[1,0] neg_hi:[0,1]
	v_pk_add_f32 v[42:43], v[24:25], v[42:43] op_sel:[0,1] op_sel_hi:[1,0] neg_lo:[0,1]
	v_pk_add_f32 v[20:21], v[26:27], v[52:53]
	v_pk_add_f32 v[24:25], v[26:27], v[52:53] neg_lo:[0,1] neg_hi:[0,1]
	v_pk_add_f32 v[26:27], v[44:45], v[60:61]
	v_pk_add_f32 v[44:45], v[44:45], v[60:61] neg_lo:[0,1] neg_hi:[0,1]
	v_pk_add_f32 v[52:53], v[20:21], v[26:27]
	v_pk_add_f32 v[58:59], v[20:21], v[26:27] neg_lo:[0,1] neg_hi:[0,1]
	v_pk_add_f32 v[26:27], v[24:25], v[44:45] op_sel:[0,1] op_sel_hi:[1,0] neg_hi:[0,1]
	v_pk_add_f32 v[44:45], v[24:25], v[44:45] op_sel:[0,1] op_sel_hi:[1,0] neg_lo:[0,1]
	v_pk_mul_f32 v[20:21], v[18:19], s[26:27] op_sel:[0,0] op_sel_hi:[0,1]
	v_mad_i32_i24 v35, v37, s3, 0
	v_pk_fma_f32 v[60:61], v[18:19], s[26:27], v[20:21] op_sel:[1,1,0] op_sel_hi:[1,0,1] neg_lo:[0,1,0]
	v_pk_mul_f32 v[18:19], v[56:57], s[34:35] op_sel:[0,0] op_sel_hi:[0,1]
	v_lshlrev_b32_e32 v39, 3, v34
	v_pk_fma_f32 v[56:57], v[56:57], s[34:35], v[18:19] op_sel:[1,1,0] op_sel_hi:[1,0,1] neg_lo:[0,1,0]
	v_pk_mul_f32 v[66:67], v[26:27], s[36:37] op_sel:[0,0] op_sel_hi:[0,1]
	v_lshlrev_b32_e32 v74, 3, v38
	v_pk_fma_f32 v[66:67], v[26:27], s[36:37], v[66:67] op_sel:[1,1,0] op_sel_hi:[1,0,1] neg_lo:[0,1,0]
	v_pk_mul_f32 v[26:27], v[22:23], s[34:35] op_sel:[0,0] op_sel_hi:[0,1]
	v_add3_u32 v74, v35, v39, v74
	v_pk_fma_f32 v[68:69], v[22:23], s[34:35], v[26:27] op_sel:[1,1,0] op_sel_hi:[1,0,1] neg_lo:[0,1,0]
	v_pk_mul_f32 v[22:23], v[48:49], s[22:23] op_sel:[0,0] op_sel_hi:[0,1]
	v_lshl_add_u32 v78, v38, 11, v35
	v_pk_fma_f32 v[48:49], v[48:49], s[22:23], v[22:23] op_sel:[1,1,0] op_sel_hi:[1,0,1] neg_lo:[0,1,0]
	v_pk_mul_f32 v[70:71], v[58:59], s[38:39] op_sel:[0,0] op_sel_hi:[0,1]
	v_add_u32_e32 v39, v78, v39
	v_pk_fma_f32 v[58:59], v[58:59], s[38:39], v[70:71] op_sel:[1,1,0] op_sel_hi:[1,0,1] neg_lo:[0,1,0]
	v_pk_mul_f32 v[70:71], v[28:29], s[36:37] op_sel:[0,0] op_sel_hi:[0,1]
	v_pk_fma_f32 v[70:71], v[28:29], s[36:37], v[70:71] op_sel:[1,1,0] op_sel_hi:[1,0,1] neg_lo:[0,1,0]
	v_pk_mul_f32 v[28:29], v[42:43], s[38:39] op_sel:[0,0] op_sel_hi:[0,1]
	v_pk_fma_f32 v[42:43], v[42:43], s[38:39], v[28:29] op_sel:[1,1,0] op_sel_hi:[1,0,1] neg_lo:[0,1,0]
	v_pk_mul_f32 v[72:73], v[44:45], s[40:41] op_sel:[0,0] op_sel_hi:[0,1]
	v_pk_fma_f32 v[44:45], v[44:45], s[40:41], v[72:73] op_sel:[1,1,0] op_sel_hi:[1,0,1] neg_lo:[0,1,0]
	v_pk_add_f32 v[72:73], v[54:55], v[50:51]
	v_pk_add_f32 v[50:51], v[54:55], v[50:51] neg_lo:[0,1] neg_hi:[0,1]
	v_pk_add_f32 v[54:55], v[40:41], v[52:53]
	v_pk_add_f32 v[40:41], v[40:41], v[52:53] neg_lo:[0,1] neg_hi:[0,1]
	v_pk_add_f32 v[52:53], v[72:73], v[54:55]
	v_pk_add_f32 v[54:55], v[72:73], v[54:55] neg_lo:[0,1] neg_hi:[0,1]
	v_pk_add_f32 v[72:73], v[50:51], v[40:41] op_sel:[0,1] op_sel_hi:[1,0] neg_hi:[0,1]
	v_pk_add_f32 v[40:41], v[50:51], v[40:41] op_sel:[0,1] op_sel_hi:[1,0] neg_lo:[0,1]
	v_pk_add_f32 v[50:51], v[62:63], v[56:57]
	v_pk_add_f32 v[56:57], v[62:63], v[56:57] neg_lo:[0,1] neg_hi:[0,1]
	v_pk_add_f32 v[62:63], v[60:61], v[66:67]
	v_pk_add_f32 v[60:61], v[60:61], v[66:67] neg_lo:[0,1] neg_hi:[0,1]
	v_pk_add_f32 v[66:67], v[50:51], v[62:63]
	v_pk_add_f32 v[50:51], v[50:51], v[62:63] neg_lo:[0,1] neg_hi:[0,1]
	v_pk_add_f32 v[62:63], v[56:57], v[60:61] op_sel:[0,1] op_sel_hi:[1,0] neg_hi:[0,1]
	v_pk_add_f32 v[56:57], v[56:57], v[60:61] op_sel:[0,1] op_sel_hi:[1,0] neg_lo:[0,1]
	v_pk_add_f32 v[60:61], v[46:47], v[48:49]
	v_pk_add_f32 v[46:47], v[46:47], v[48:49] neg_lo:[0,1] neg_hi:[0,1]
	v_pk_add_f32 v[48:49], v[68:69], v[58:59]
	v_pk_add_f32 v[58:59], v[68:69], v[58:59] neg_lo:[0,1] neg_hi:[0,1]
	v_pk_add_f32 v[68:69], v[60:61], v[48:49]
	v_pk_add_f32 v[48:49], v[60:61], v[48:49] neg_lo:[0,1] neg_hi:[0,1]
	v_pk_add_f32 v[60:61], v[46:47], v[58:59] op_sel:[0,1] op_sel_hi:[1,0] neg_hi:[0,1]
	v_pk_add_f32 v[46:47], v[46:47], v[58:59] op_sel:[0,1] op_sel_hi:[1,0] neg_lo:[0,1]
	v_pk_add_f32 v[58:59], v[64:65], v[42:43]
	v_pk_add_f32 v[42:43], v[64:65], v[42:43] neg_lo:[0,1] neg_hi:[0,1]
	v_pk_add_f32 v[64:65], v[70:71], v[44:45]
	v_pk_add_f32 v[44:45], v[70:71], v[44:45] neg_lo:[0,1] neg_hi:[0,1]
	v_pk_add_f32 v[70:71], v[58:59], v[64:65]
	v_pk_add_f32 v[58:59], v[58:59], v[64:65] neg_lo:[0,1] neg_hi:[0,1]
	v_pk_add_f32 v[64:65], v[42:43], v[44:45] op_sel:[0,1] op_sel_hi:[1,0] neg_hi:[0,1]
	v_pk_add_f32 v[42:43], v[42:43], v[44:45] op_sel:[0,1] op_sel_hi:[1,0] neg_lo:[0,1]
	v_mov_b32_e32 v45, v31
	v_mov_b32_e32 v44, v1
	ds_write_b64 v74, v[52:53]
	v_pk_mul_f32 v[52:53], v[66:67], v[44:45] op_sel:[0,0] op_sel_hi:[0,1]
	v_pk_fma_f32 v[52:53], v[66:67], v[44:45], v[52:53] op_sel:[1,1,0] op_sel_hi:[1,0,1] neg_lo:[0,1,0]
	ds_write_b64 v74, v[52:53] offset:2176
	v_pk_mul_f32 v[52:53], v[44:45], v[44:45] op_sel:[0,0] op_sel_hi:[0,1]
	v_pk_fma_f32 v[52:53], v[44:45], v[44:45], v[52:53] op_sel:[1,1,0] op_sel_hi:[1,0,1] neg_lo:[0,1,0]
	v_pk_mul_f32 v[66:67], v[68:69], v[52:53] op_sel:[0,0] op_sel_hi:[0,1]
	v_pk_fma_f32 v[66:67], v[68:69], v[52:53], v[66:67] op_sel:[1,1,0] op_sel_hi:[1,0,1] neg_lo:[0,1,0]
	ds_write_b64 v74, v[66:67] offset:4352
	v_pk_mul_f32 v[66:67], v[52:53], v[44:45] op_sel:[0,0] op_sel_hi:[0,1]
	v_pk_fma_f32 v[52:53], v[52:53], v[44:45], v[66:67] op_sel:[1,1,0] op_sel_hi:[1,0,1] neg_lo:[0,1,0]
	v_pk_mul_f32 v[66:67], v[70:71], v[52:53] op_sel:[0,0] op_sel_hi:[0,1]
	v_pk_fma_f32 v[66:67], v[70:71], v[52:53], v[66:67] op_sel:[1,1,0] op_sel_hi:[1,0,1] neg_lo:[0,1,0]
	ds_write_b64 v74, v[66:67] offset:6528
	v_pk_mul_f32 v[66:67], v[52:53], v[44:45] op_sel:[0,0] op_sel_hi:[0,1]
	v_pk_fma_f32 v[52:53], v[52:53], v[44:45], v[66:67] op_sel:[1,1,0] op_sel_hi:[1,0,1] neg_lo:[0,1,0]
	v_pk_mul_f32 v[66:67], v[72:73], v[52:53] op_sel:[0,0] op_sel_hi:[0,1]
	v_pk_fma_f32 v[66:67], v[72:73], v[52:53], v[66:67] op_sel:[1,1,0] op_sel_hi:[1,0,1] neg_lo:[0,1,0]
	ds_write_b64 v74, v[66:67] offset:8704
	v_pk_mul_f32 v[66:67], v[52:53], v[44:45] op_sel:[0,0] op_sel_hi:[0,1]
	v_pk_fma_f32 v[52:53], v[52:53], v[44:45], v[66:67] op_sel:[1,1,0] op_sel_hi:[1,0,1] neg_lo:[0,1,0]
	v_pk_mul_f32 v[66:67], v[62:63], v[52:53] op_sel:[0,0] op_sel_hi:[0,1]
	v_pk_fma_f32 v[62:63], v[62:63], v[52:53], v[66:67] op_sel:[1,1,0] op_sel_hi:[1,0,1] neg_lo:[0,1,0]
	ds_write_b64 v74, v[62:63] offset:10880
	v_pk_mul_f32 v[62:63], v[52:53], v[44:45] op_sel:[0,0] op_sel_hi:[0,1]
	v_pk_fma_f32 v[52:53], v[52:53], v[44:45], v[62:63] op_sel:[1,1,0] op_sel_hi:[1,0,1] neg_lo:[0,1,0]
	v_pk_mul_f32 v[62:63], v[60:61], v[52:53] op_sel:[0,0] op_sel_hi:[0,1]
	v_pk_fma_f32 v[60:61], v[60:61], v[52:53], v[62:63] op_sel:[1,1,0] op_sel_hi:[1,0,1] neg_lo:[0,1,0]
	ds_write_b64 v74, v[60:61] offset:13056
	v_pk_mul_f32 v[60:61], v[52:53], v[44:45] op_sel:[0,0] op_sel_hi:[0,1]
	v_pk_fma_f32 v[52:53], v[52:53], v[44:45], v[60:61] op_sel:[1,1,0] op_sel_hi:[1,0,1] neg_lo:[0,1,0]
	v_pk_mul_f32 v[60:61], v[64:65], v[52:53] op_sel:[0,0] op_sel_hi:[0,1]
	v_pk_fma_f32 v[60:61], v[64:65], v[52:53], v[60:61] op_sel:[1,1,0] op_sel_hi:[1,0,1] neg_lo:[0,1,0]
	ds_write_b64 v74, v[60:61] offset:15232
	v_pk_mul_f32 v[60:61], v[52:53], v[44:45] op_sel:[0,0] op_sel_hi:[0,1]
	v_pk_fma_f32 v[52:53], v[52:53], v[44:45], v[60:61] op_sel:[1,1,0] op_sel_hi:[1,0,1] neg_lo:[0,1,0]
	v_pk_mul_f32 v[60:61], v[54:55], v[52:53] op_sel:[0,0] op_sel_hi:[0,1]
	v_pk_fma_f32 v[54:55], v[54:55], v[52:53], v[60:61] op_sel:[1,1,0] op_sel_hi:[1,0,1] neg_lo:[0,1,0]
	ds_write_b64 v74, v[54:55] offset:17408
	v_pk_mul_f32 v[54:55], v[52:53], v[44:45] op_sel:[0,0] op_sel_hi:[0,1]
	v_pk_fma_f32 v[52:53], v[52:53], v[44:45], v[54:55] op_sel:[1,1,0] op_sel_hi:[1,0,1] neg_lo:[0,1,0]
	v_pk_mul_f32 v[54:55], v[50:51], v[52:53] op_sel:[0,0] op_sel_hi:[0,1]
	v_pk_fma_f32 v[50:51], v[50:51], v[52:53], v[54:55] op_sel:[1,1,0] op_sel_hi:[1,0,1] neg_lo:[0,1,0]
	ds_write_b64 v74, v[50:51] offset:19584
	v_pk_mul_f32 v[50:51], v[52:53], v[44:45] op_sel:[0,0] op_sel_hi:[0,1]
	v_pk_fma_f32 v[50:51], v[52:53], v[44:45], v[50:51] op_sel:[1,1,0] op_sel_hi:[1,0,1] neg_lo:[0,1,0]
	v_pk_mul_f32 v[52:53], v[48:49], v[50:51] op_sel:[0,0] op_sel_hi:[0,1]
	v_pk_fma_f32 v[48:49], v[48:49], v[50:51], v[52:53] op_sel:[1,1,0] op_sel_hi:[1,0,1] neg_lo:[0,1,0]
	ds_write_b64 v74, v[48:49] offset:21760
	v_pk_mul_f32 v[48:49], v[50:51], v[44:45] op_sel:[0,0] op_sel_hi:[0,1]
	v_pk_fma_f32 v[48:49], v[50:51], v[44:45], v[48:49] op_sel:[1,1,0] op_sel_hi:[1,0,1] neg_lo:[0,1,0]
	v_pk_mul_f32 v[50:51], v[58:59], v[48:49] op_sel:[0,0] op_sel_hi:[0,1]
	v_pk_fma_f32 v[50:51], v[58:59], v[48:49], v[50:51] op_sel:[1,1,0] op_sel_hi:[1,0,1] neg_lo:[0,1,0]
	ds_write_b64 v74, v[50:51] offset:23936
	v_pk_mul_f32 v[50:51], v[48:49], v[44:45] op_sel:[0,0] op_sel_hi:[0,1]
	v_pk_fma_f32 v[48:49], v[48:49], v[44:45], v[50:51] op_sel:[1,1,0] op_sel_hi:[1,0,1] neg_lo:[0,1,0]
	v_pk_mul_f32 v[50:51], v[40:41], v[48:49] op_sel:[0,0] op_sel_hi:[0,1]
	v_pk_fma_f32 v[40:41], v[40:41], v[48:49], v[50:51] op_sel:[1,1,0] op_sel_hi:[1,0,1] neg_lo:[0,1,0]
	ds_write_b64 v74, v[40:41] offset:26112
	v_pk_mul_f32 v[40:41], v[48:49], v[44:45] op_sel:[0,0] op_sel_hi:[0,1]
	v_pk_fma_f32 v[40:41], v[48:49], v[44:45], v[40:41] op_sel:[1,1,0] op_sel_hi:[1,0,1] neg_lo:[0,1,0]
	v_pk_mul_f32 v[48:49], v[56:57], v[40:41] op_sel:[0,0] op_sel_hi:[0,1]
	v_pk_fma_f32 v[48:49], v[56:57], v[40:41], v[48:49] op_sel:[1,1,0] op_sel_hi:[1,0,1] neg_lo:[0,1,0]
	ds_write_b64 v74, v[48:49] offset:28288
	v_pk_mul_f32 v[48:49], v[40:41], v[44:45] op_sel:[0,0] op_sel_hi:[0,1]
	v_pk_fma_f32 v[40:41], v[40:41], v[44:45], v[48:49] op_sel:[1,1,0] op_sel_hi:[1,0,1] neg_lo:[0,1,0]
	v_pk_mul_f32 v[48:49], v[46:47], v[40:41] op_sel:[0,0] op_sel_hi:[0,1]
	v_pk_fma_f32 v[46:47], v[46:47], v[40:41], v[48:49] op_sel:[1,1,0] op_sel_hi:[1,0,1] neg_lo:[0,1,0]
	ds_write_b64 v74, v[46:47] offset:30464
	v_pk_mul_f32 v[46:47], v[40:41], v[44:45] op_sel:[0,0] op_sel_hi:[0,1]
	v_pk_fma_f32 v[40:41], v[40:41], v[44:45], v[46:47] op_sel:[1,1,0] op_sel_hi:[1,0,1] neg_lo:[0,1,0]
	v_pk_mul_f32 v[44:45], v[42:43], v[40:41] op_sel:[0,0] op_sel_hi:[0,1]
	v_pk_fma_f32 v[40:41], v[42:43], v[40:41], v[44:45] op_sel:[1,1,0] op_sel_hi:[1,0,1] neg_lo:[0,1,0]
	ds_write_b64 v74, v[40:41] offset:32640
	s_waitcnt lgkmcnt(0)
	s_barrier
	ds_read2_b64 v[40:43], v39 offset1:17
	ds_read2_b64 v[44:47], v39 offset0:34 offset1:51
	ds_read2_b64 v[48:51], v39 offset0:68 offset1:85
	ds_read2_b64 v[52:55], v39 offset0:136 offset1:153
	ds_read2_b64 v[56:59], v39 offset0:102 offset1:119
	ds_read2_b64 v[60:63], v39 offset0:204 offset1:221
	ds_read2_b64 v[64:67], v39 offset0:170 offset1:187
	ds_read2_b64 v[68:71], v39 offset0:238 offset1:255
	s_waitcnt lgkmcnt(4)
	v_pk_add_f32 v[72:73], v[40:41], v[52:53]
	v_pk_add_f32 v[40:41], v[40:41], v[52:53] neg_lo:[0,1] neg_hi:[0,1]
	s_waitcnt lgkmcnt(2)
	v_pk_add_f32 v[52:53], v[48:49], v[60:61]
	v_pk_add_f32 v[48:49], v[48:49], v[60:61] neg_lo:[0,1] neg_hi:[0,1]
	v_pk_add_f32 v[60:61], v[72:73], v[52:53]
	v_pk_add_f32 v[52:53], v[72:73], v[52:53] neg_lo:[0,1] neg_hi:[0,1]
	v_pk_add_f32 v[72:73], v[40:41], v[48:49] op_sel:[0,1] op_sel_hi:[1,0] neg_hi:[0,1]
	v_pk_add_f32 v[40:41], v[40:41], v[48:49] op_sel:[0,1] op_sel_hi:[1,0] neg_lo:[0,1]
	v_pk_add_f32 v[48:49], v[42:43], v[54:55]
	v_pk_add_f32 v[42:43], v[42:43], v[54:55] neg_lo:[0,1] neg_hi:[0,1]
	v_pk_add_f32 v[54:55], v[50:51], v[62:63]
	v_pk_add_f32 v[50:51], v[50:51], v[62:63] neg_lo:[0,1] neg_hi:[0,1]
	v_pk_add_f32 v[62:63], v[48:49], v[54:55]
	v_pk_add_f32 v[48:49], v[48:49], v[54:55] neg_lo:[0,1] neg_hi:[0,1]
	v_pk_add_f32 v[54:55], v[42:43], v[50:51] op_sel:[0,1] op_sel_hi:[1,0] neg_hi:[0,1]
	v_pk_add_f32 v[42:43], v[42:43], v[50:51] op_sel:[0,1] op_sel_hi:[1,0] neg_lo:[0,1]
	s_waitcnt lgkmcnt(1)
	v_pk_add_f32 v[50:51], v[44:45], v[64:65]
	v_pk_add_f32 v[44:45], v[44:45], v[64:65] neg_lo:[0,1] neg_hi:[0,1]
	s_waitcnt lgkmcnt(0)
	v_pk_add_f32 v[64:65], v[56:57], v[68:69]
	v_pk_add_f32 v[56:57], v[56:57], v[68:69] neg_lo:[0,1] neg_hi:[0,1]
	v_pk_add_f32 v[68:69], v[50:51], v[64:65]
	v_pk_add_f32 v[50:51], v[50:51], v[64:65] neg_lo:[0,1] neg_hi:[0,1]
	v_pk_add_f32 v[64:65], v[44:45], v[56:57] op_sel:[0,1] op_sel_hi:[1,0] neg_hi:[0,1]
	v_pk_add_f32 v[44:45], v[44:45], v[56:57] op_sel:[0,1] op_sel_hi:[1,0] neg_lo:[0,1]
	v_pk_add_f32 v[56:57], v[46:47], v[66:67]
	v_pk_add_f32 v[46:47], v[46:47], v[66:67] neg_lo:[0,1] neg_hi:[0,1]
	v_pk_add_f32 v[66:67], v[58:59], v[70:71]
	v_pk_add_f32 v[58:59], v[58:59], v[70:71] neg_lo:[0,1] neg_hi:[0,1]
	v_pk_add_f32 v[70:71], v[56:57], v[66:67]
	v_pk_add_f32 v[56:57], v[56:57], v[66:67] neg_lo:[0,1] neg_hi:[0,1]
	v_pk_add_f32 v[66:67], v[46:47], v[58:59] op_sel:[0,1] op_sel_hi:[1,0] neg_hi:[0,1]
	v_pk_add_f32 v[46:47], v[46:47], v[58:59] op_sel:[0,1] op_sel_hi:[1,0] neg_lo:[0,1]
	v_pk_mul_f32 v[58:59], v[54:55], s[26:27] op_sel:[0,0] op_sel_hi:[0,1]
	v_pk_fma_f32 v[54:55], v[54:55], s[26:27], v[58:59] op_sel:[1,1,0] op_sel_hi:[1,0,1] neg_lo:[0,1,0]
	v_pk_mul_f32 v[58:59], v[64:65], s[34:35] op_sel:[0,0] op_sel_hi:[0,1]
	v_pk_fma_f32 v[58:59], v[64:65], s[34:35], v[58:59] op_sel:[1,1,0] op_sel_hi:[1,0,1] neg_lo:[0,1,0]
	v_pk_mul_f32 v[64:65], v[66:67], s[36:37] op_sel:[0,0] op_sel_hi:[0,1]
	v_pk_fma_f32 v[64:65], v[66:67], s[36:37], v[64:65] op_sel:[1,1,0] op_sel_hi:[1,0,1] neg_lo:[0,1,0]
	v_pk_mul_f32 v[66:67], v[48:49], s[34:35] op_sel:[0,0] op_sel_hi:[0,1]
	v_pk_fma_f32 v[48:49], v[48:49], s[34:35], v[66:67] op_sel:[1,1,0] op_sel_hi:[1,0,1] neg_lo:[0,1,0]
	v_pk_mul_f32 v[66:67], v[50:51], s[22:23] op_sel:[0,0] op_sel_hi:[0,1]
	v_pk_fma_f32 v[50:51], v[50:51], s[22:23], v[66:67] op_sel:[1,1,0] op_sel_hi:[1,0,1] neg_lo:[0,1,0]
	v_pk_mul_f32 v[66:67], v[56:57], s[38:39] op_sel:[0,0] op_sel_hi:[0,1]
	v_pk_fma_f32 v[56:57], v[56:57], s[38:39], v[66:67] op_sel:[1,1,0] op_sel_hi:[1,0,1] neg_lo:[0,1,0]
	v_pk_mul_f32 v[66:67], v[42:43], s[36:37] op_sel:[0,0] op_sel_hi:[0,1]
	v_pk_fma_f32 v[42:43], v[42:43], s[36:37], v[66:67] op_sel:[1,1,0] op_sel_hi:[1,0,1] neg_lo:[0,1,0]
	v_pk_mul_f32 v[66:67], v[44:45], s[38:39] op_sel:[0,0] op_sel_hi:[0,1]
	v_pk_fma_f32 v[44:45], v[44:45], s[38:39], v[66:67] op_sel:[1,1,0] op_sel_hi:[1,0,1] neg_lo:[0,1,0]
	v_pk_mul_f32 v[66:67], v[46:47], s[40:41] op_sel:[0,0] op_sel_hi:[0,1]
	v_pk_fma_f32 v[46:47], v[46:47], s[40:41], v[66:67] op_sel:[1,1,0] op_sel_hi:[1,0,1] neg_lo:[0,1,0]
	v_pk_add_f32 v[66:67], v[60:61], v[68:69]
	v_pk_add_f32 v[60:61], v[60:61], v[68:69] neg_lo:[0,1] neg_hi:[0,1]
	v_pk_add_f32 v[68:69], v[62:63], v[70:71]
	v_pk_add_f32 v[62:63], v[62:63], v[70:71] neg_lo:[0,1] neg_hi:[0,1]
	v_pk_add_f32 v[70:71], v[66:67], v[68:69]
	v_pk_add_f32 v[66:67], v[66:67], v[68:69] neg_lo:[0,1] neg_hi:[0,1]
	v_pk_add_f32 v[68:69], v[60:61], v[62:63] op_sel:[0,1] op_sel_hi:[1,0] neg_hi:[0,1]
	v_pk_add_f32 v[60:61], v[60:61], v[62:63] op_sel:[0,1] op_sel_hi:[1,0] neg_lo:[0,1]
	v_pk_add_f32 v[62:63], v[72:73], v[58:59]
	v_pk_add_f32 v[58:59], v[72:73], v[58:59] neg_lo:[0,1] neg_hi:[0,1]
	v_pk_add_f32 v[72:73], v[54:55], v[64:65]
	v_pk_add_f32 v[54:55], v[54:55], v[64:65] neg_lo:[0,1] neg_hi:[0,1]
	v_pk_add_f32 v[64:65], v[62:63], v[72:73]
	v_pk_add_f32 v[62:63], v[62:63], v[72:73] neg_lo:[0,1] neg_hi:[0,1]
	v_pk_add_f32 v[72:73], v[58:59], v[54:55] op_sel:[0,1] op_sel_hi:[1,0] neg_hi:[0,1]
	v_pk_add_f32 v[54:55], v[58:59], v[54:55] op_sel:[0,1] op_sel_hi:[1,0] neg_lo:[0,1]
	v_pk_add_f32 v[58:59], v[52:53], v[50:51]
	v_pk_add_f32 v[50:51], v[52:53], v[50:51] neg_lo:[0,1] neg_hi:[0,1]
	v_pk_add_f32 v[52:53], v[48:49], v[56:57]
	v_pk_add_f32 v[48:49], v[48:49], v[56:57] neg_lo:[0,1] neg_hi:[0,1]
	v_pk_add_f32 v[56:57], v[58:59], v[52:53]
	v_pk_add_f32 v[52:53], v[58:59], v[52:53] neg_lo:[0,1] neg_hi:[0,1]
	v_pk_add_f32 v[58:59], v[50:51], v[48:49] op_sel:[0,1] op_sel_hi:[1,0] neg_hi:[0,1]
	v_pk_add_f32 v[48:49], v[50:51], v[48:49] op_sel:[0,1] op_sel_hi:[1,0] neg_lo:[0,1]
	v_pk_add_f32 v[50:51], v[40:41], v[44:45]
	v_pk_add_f32 v[40:41], v[40:41], v[44:45] neg_lo:[0,1] neg_hi:[0,1]
	v_pk_add_f32 v[44:45], v[42:43], v[46:47]
	v_pk_add_f32 v[42:43], v[42:43], v[46:47] neg_lo:[0,1] neg_hi:[0,1]
	v_pk_add_f32 v[46:47], v[50:51], v[44:45]
	v_pk_add_f32 v[44:45], v[50:51], v[44:45] neg_lo:[0,1] neg_hi:[0,1]
	v_pk_add_f32 v[50:51], v[40:41], v[42:43] op_sel:[0,1] op_sel_hi:[1,0] neg_hi:[0,1]
	v_pk_add_f32 v[40:41], v[40:41], v[42:43] op_sel:[0,1] op_sel_hi:[1,0] neg_lo:[0,1]
	v_mov_b32_e32 v42, v30
	v_mov_b32_e32 v43, v32
	s_nop 0
	v_pk_mul_f32 v[74:75], v[64:65], v[42:43] op_sel:[0,0] op_sel_hi:[0,1]
	v_pk_fma_f32 v[64:65], v[64:65], v[42:43], v[74:75] op_sel:[1,1,0] op_sel_hi:[1,0,1] neg_lo:[0,1,0]
	ds_write2_b64 v39, v[70:71], v[64:65] offset1:17
	v_pk_mul_f32 v[64:65], v[42:43], v[42:43] op_sel:[0,0] op_sel_hi:[0,1]
	v_pk_fma_f32 v[64:65], v[42:43], v[42:43], v[64:65] op_sel:[1,1,0] op_sel_hi:[1,0,1] neg_lo:[0,1,0]
	v_pk_mul_f32 v[70:71], v[56:57], v[64:65] op_sel:[0,0] op_sel_hi:[0,1]
	v_pk_fma_f32 v[56:57], v[56:57], v[64:65], v[70:71] op_sel:[1,1,0] op_sel_hi:[1,0,1] neg_lo:[0,1,0]
	v_pk_mul_f32 v[70:71], v[64:65], v[42:43] op_sel:[0,0] op_sel_hi:[0,1]
	v_pk_fma_f32 v[64:65], v[64:65], v[42:43], v[70:71] op_sel:[1,1,0] op_sel_hi:[1,0,1] neg_lo:[0,1,0]
	v_pk_mul_f32 v[70:71], v[46:47], v[64:65] op_sel:[0,0] op_sel_hi:[0,1]
	v_pk_fma_f32 v[46:47], v[46:47], v[64:65], v[70:71] op_sel:[1,1,0] op_sel_hi:[1,0,1] neg_lo:[0,1,0]
	ds_write2_b64 v39, v[56:57], v[46:47] offset0:34 offset1:51
	v_pk_mul_f32 v[46:47], v[64:65], v[42:43] op_sel:[0,0] op_sel_hi:[0,1]
	v_pk_fma_f32 v[46:47], v[64:65], v[42:43], v[46:47] op_sel:[1,1,0] op_sel_hi:[1,0,1] neg_lo:[0,1,0]
	v_pk_mul_f32 v[56:57], v[68:69], v[46:47] op_sel:[0,0] op_sel_hi:[0,1]
	v_pk_mul_f32 v[64:65], v[46:47], v[42:43] op_sel:[0,0] op_sel_hi:[0,1]
	v_pk_fma_f32 v[56:57], v[68:69], v[46:47], v[56:57] op_sel:[1,1,0] op_sel_hi:[1,0,1] neg_lo:[0,1,0]
	v_pk_fma_f32 v[46:47], v[46:47], v[42:43], v[64:65] op_sel:[1,1,0] op_sel_hi:[1,0,1] neg_lo:[0,1,0]
	v_pk_mul_f32 v[64:65], v[72:73], v[46:47] op_sel:[0,0] op_sel_hi:[0,1]
	v_pk_fma_f32 v[64:65], v[72:73], v[46:47], v[64:65] op_sel:[1,1,0] op_sel_hi:[1,0,1] neg_lo:[0,1,0]
	ds_write2_b64 v39, v[56:57], v[64:65] offset0:68 offset1:85
	v_pk_mul_f32 v[56:57], v[46:47], v[42:43] op_sel:[0,0] op_sel_hi:[0,1]
	v_pk_fma_f32 v[46:47], v[46:47], v[42:43], v[56:57] op_sel:[1,1,0] op_sel_hi:[1,0,1] neg_lo:[0,1,0]
	v_pk_mul_f32 v[56:57], v[58:59], v[46:47] op_sel:[0,0] op_sel_hi:[0,1]
	v_pk_fma_f32 v[56:57], v[58:59], v[46:47], v[56:57] op_sel:[1,1,0] op_sel_hi:[1,0,1] neg_lo:[0,1,0]
	v_pk_mul_f32 v[58:59], v[46:47], v[42:43] op_sel:[0,0] op_sel_hi:[0,1]
	v_pk_fma_f32 v[46:47], v[46:47], v[42:43], v[58:59] op_sel:[1,1,0] op_sel_hi:[1,0,1] neg_lo:[0,1,0]
	v_pk_mul_f32 v[58:59], v[50:51], v[46:47] op_sel:[0,0] op_sel_hi:[0,1]
	v_pk_fma_f32 v[50:51], v[50:51], v[46:47], v[58:59] op_sel:[1,1,0] op_sel_hi:[1,0,1] neg_lo:[0,1,0]
	ds_write2_b64 v39, v[56:57], v[50:51] offset0:102 offset1:119
	v_pk_mul_f32 v[50:51], v[46:47], v[42:43] op_sel:[0,0] op_sel_hi:[0,1]
	v_pk_fma_f32 v[46:47], v[46:47], v[42:43], v[50:51] op_sel:[1,1,0] op_sel_hi:[1,0,1] neg_lo:[0,1,0]
	v_pk_mul_f32 v[50:51], v[66:67], v[46:47] op_sel:[0,0] op_sel_hi:[0,1]
	v_pk_mul_f32 v[56:57], v[46:47], v[42:43] op_sel:[0,0] op_sel_hi:[0,1]
	v_pk_fma_f32 v[50:51], v[66:67], v[46:47], v[50:51] op_sel:[1,1,0] op_sel_hi:[1,0,1] neg_lo:[0,1,0]
	v_pk_fma_f32 v[46:47], v[46:47], v[42:43], v[56:57] op_sel:[1,1,0] op_sel_hi:[1,0,1] neg_lo:[0,1,0]
	v_pk_mul_f32 v[56:57], v[62:63], v[46:47] op_sel:[0,0] op_sel_hi:[0,1]
	v_pk_fma_f32 v[56:57], v[62:63], v[46:47], v[56:57] op_sel:[1,1,0] op_sel_hi:[1,0,1] neg_lo:[0,1,0]
	ds_write2_b64 v39, v[50:51], v[56:57] offset0:136 offset1:153
	v_pk_mul_f32 v[50:51], v[46:47], v[42:43] op_sel:[0,0] op_sel_hi:[0,1]
	v_pk_fma_f32 v[46:47], v[46:47], v[42:43], v[50:51] op_sel:[1,1,0] op_sel_hi:[1,0,1] neg_lo:[0,1,0]
	v_pk_mul_f32 v[50:51], v[52:53], v[46:47] op_sel:[0,0] op_sel_hi:[0,1]
	v_pk_fma_f32 v[50:51], v[52:53], v[46:47], v[50:51] op_sel:[1,1,0] op_sel_hi:[1,0,1] neg_lo:[0,1,0]
	v_pk_mul_f32 v[52:53], v[46:47], v[42:43] op_sel:[0,0] op_sel_hi:[0,1]
	v_pk_fma_f32 v[46:47], v[46:47], v[42:43], v[52:53] op_sel:[1,1,0] op_sel_hi:[1,0,1] neg_lo:[0,1,0]
	v_pk_mul_f32 v[52:53], v[44:45], v[46:47] op_sel:[0,0] op_sel_hi:[0,1]
	v_pk_fma_f32 v[44:45], v[44:45], v[46:47], v[52:53] op_sel:[1,1,0] op_sel_hi:[1,0,1] neg_lo:[0,1,0]
	ds_write2_b64 v39, v[50:51], v[44:45] offset0:170 offset1:187
	v_pk_mul_f32 v[44:45], v[46:47], v[42:43] op_sel:[0,0] op_sel_hi:[0,1]
	v_pk_fma_f32 v[44:45], v[46:47], v[42:43], v[44:45] op_sel:[1,1,0] op_sel_hi:[1,0,1] neg_lo:[0,1,0]
	v_pk_mul_f32 v[46:47], v[60:61], v[44:45] op_sel:[0,0] op_sel_hi:[0,1]
	v_pk_mul_f32 v[50:51], v[44:45], v[42:43] op_sel:[0,0] op_sel_hi:[0,1]
	v_pk_fma_f32 v[46:47], v[60:61], v[44:45], v[46:47] op_sel:[1,1,0] op_sel_hi:[1,0,1] neg_lo:[0,1,0]
	v_pk_fma_f32 v[44:45], v[44:45], v[42:43], v[50:51] op_sel:[1,1,0] op_sel_hi:[1,0,1] neg_lo:[0,1,0]
	v_pk_mul_f32 v[50:51], v[54:55], v[44:45] op_sel:[0,0] op_sel_hi:[0,1]
	v_pk_fma_f32 v[50:51], v[54:55], v[44:45], v[50:51] op_sel:[1,1,0] op_sel_hi:[1,0,1] neg_lo:[0,1,0]
	ds_write2_b64 v39, v[46:47], v[50:51] offset0:204 offset1:221
	v_pk_mul_f32 v[46:47], v[44:45], v[42:43] op_sel:[0,0] op_sel_hi:[0,1]
	v_pk_fma_f32 v[44:45], v[44:45], v[42:43], v[46:47] op_sel:[1,1,0] op_sel_hi:[1,0,1] neg_lo:[0,1,0]
	v_pk_mul_f32 v[46:47], v[48:49], v[44:45] op_sel:[0,0] op_sel_hi:[0,1]
	v_pk_fma_f32 v[46:47], v[48:49], v[44:45], v[46:47] op_sel:[1,1,0] op_sel_hi:[1,0,1] neg_lo:[0,1,0]
	v_pk_mul_f32 v[48:49], v[44:45], v[42:43] op_sel:[0,0] op_sel_hi:[0,1]
	v_pk_fma_f32 v[42:43], v[44:45], v[42:43], v[48:49] op_sel:[1,1,0] op_sel_hi:[1,0,1] neg_lo:[0,1,0]
	v_pk_mul_f32 v[44:45], v[40:41], v[42:43] op_sel:[0,0] op_sel_hi:[0,1]
	v_pk_fma_f32 v[40:41], v[40:41], v[42:43], v[44:45] op_sel:[1,1,0] op_sel_hi:[1,0,1] neg_lo:[0,1,0]
	ds_write2_b64 v39, v[46:47], v[40:41] offset0:238 offset1:255
	v_mad_u32_u24 v39, v34, s54, v35
	s_waitcnt lgkmcnt(0)
	s_barrier
	ds_read2_b64 v[40:43], v39 offset1:1
	ds_read2_b64 v[44:47], v39 offset0:2 offset1:3
	ds_read2_b64 v[48:51], v39 offset0:8 offset1:9
	ds_read2_b64 v[52:55], v39 offset0:4 offset1:5
	ds_read2_b64 v[56:59], v39 offset0:6 offset1:7
	ds_read2_b64 v[60:63], v39 offset0:12 offset1:13
	ds_read2_b64 v[64:67], v39 offset0:10 offset1:11
	ds_read2_b64 v[68:71], v39 offset0:14 offset1:15
	s_waitcnt lgkmcnt(5)
	v_pk_add_f32 v[72:73], v[40:41], v[48:49]
	v_pk_add_f32 v[40:41], v[40:41], v[48:49] neg_lo:[0,1] neg_hi:[0,1]
	s_waitcnt lgkmcnt(2)
	v_pk_add_f32 v[48:49], v[52:53], v[60:61]
	v_pk_add_f32 v[52:53], v[52:53], v[60:61] neg_lo:[0,1] neg_hi:[0,1]
	v_pk_add_f32 v[60:61], v[72:73], v[48:49]
	v_pk_add_f32 v[48:49], v[72:73], v[48:49] neg_lo:[0,1] neg_hi:[0,1]
	v_pk_add_f32 v[72:73], v[40:41], v[52:53] op_sel:[0,1] op_sel_hi:[1,0] neg_hi:[0,1]
	v_pk_add_f32 v[40:41], v[40:41], v[52:53] op_sel:[0,1] op_sel_hi:[1,0] neg_lo:[0,1]
	v_pk_add_f32 v[52:53], v[42:43], v[50:51]
	v_pk_add_f32 v[42:43], v[42:43], v[50:51] neg_lo:[0,1] neg_hi:[0,1]
	v_pk_add_f32 v[50:51], v[54:55], v[62:63]
	v_pk_add_f32 v[54:55], v[54:55], v[62:63] neg_lo:[0,1] neg_hi:[0,1]
	v_pk_add_f32 v[62:63], v[52:53], v[50:51]
	v_pk_add_f32 v[50:51], v[52:53], v[50:51] neg_lo:[0,1] neg_hi:[0,1]
	v_pk_add_f32 v[52:53], v[42:43], v[54:55] op_sel:[0,1] op_sel_hi:[1,0] neg_hi:[0,1]
	v_pk_add_f32 v[42:43], v[42:43], v[54:55] op_sel:[0,1] op_sel_hi:[1,0] neg_lo:[0,1]
	s_waitcnt lgkmcnt(1)
	v_pk_add_f32 v[54:55], v[44:45], v[64:65]
	v_pk_add_f32 v[44:45], v[44:45], v[64:65] neg_lo:[0,1] neg_hi:[0,1]
	s_waitcnt lgkmcnt(0)
	v_pk_add_f32 v[64:65], v[56:57], v[68:69]
	v_pk_add_f32 v[56:57], v[56:57], v[68:69] neg_lo:[0,1] neg_hi:[0,1]
	v_pk_add_f32 v[68:69], v[54:55], v[64:65]
	v_pk_add_f32 v[54:55], v[54:55], v[64:65] neg_lo:[0,1] neg_hi:[0,1]
	v_pk_add_f32 v[64:65], v[44:45], v[56:57] op_sel:[0,1] op_sel_hi:[1,0] neg_hi:[0,1]
	v_pk_add_f32 v[44:45], v[44:45], v[56:57] op_sel:[0,1] op_sel_hi:[1,0] neg_lo:[0,1]
	v_pk_add_f32 v[56:57], v[46:47], v[66:67]
	v_pk_add_f32 v[46:47], v[46:47], v[66:67] neg_lo:[0,1] neg_hi:[0,1]
	v_pk_add_f32 v[66:67], v[58:59], v[70:71]
	v_pk_add_f32 v[58:59], v[58:59], v[70:71] neg_lo:[0,1] neg_hi:[0,1]
	v_pk_add_f32 v[70:71], v[56:57], v[66:67]
	v_pk_add_f32 v[56:57], v[56:57], v[66:67] neg_lo:[0,1] neg_hi:[0,1]
	v_pk_add_f32 v[66:67], v[46:47], v[58:59] op_sel:[0,1] op_sel_hi:[1,0] neg_hi:[0,1]
	v_pk_add_f32 v[46:47], v[46:47], v[58:59] op_sel:[0,1] op_sel_hi:[1,0] neg_lo:[0,1]
	v_pk_mul_f32 v[58:59], v[52:53], s[26:27] op_sel:[0,0] op_sel_hi:[0,1]
	v_pk_fma_f32 v[24:25], v[52:53], s[26:27], v[58:59] op_sel:[1,1,0] op_sel_hi:[1,0,1] neg_lo:[0,1,0]
	v_pk_mul_f32 v[52:53], v[64:65], s[34:35] op_sel:[0,0] op_sel_hi:[0,1]
	v_pk_mul_f32 v[58:59], v[66:67], s[36:37] op_sel:[0,0] op_sel_hi:[0,1]
	s_barrier
	v_pk_fma_f32 v[52:53], v[64:65], s[34:35], v[52:53] op_sel:[1,1,0] op_sel_hi:[1,0,1] neg_lo:[0,1,0]
	v_pk_mul_f32 v[64:65], v[50:51], s[34:35] op_sel:[0,0] op_sel_hi:[0,1]
	v_pk_fma_f32 v[58:59], v[66:67], s[36:37], v[58:59] op_sel:[1,1,0] op_sel_hi:[1,0,1] neg_lo:[0,1,0]
	v_pk_fma_f32 v[20:21], v[50:51], s[34:35], v[64:65] op_sel:[1,1,0] op_sel_hi:[1,0,1] neg_lo:[0,1,0]
	v_pk_mul_f32 v[50:51], v[54:55], s[22:23] op_sel:[0,0] op_sel_hi:[0,1]
	v_pk_fma_f32 v[26:27], v[54:55], s[22:23], v[50:51] op_sel:[1,1,0] op_sel_hi:[1,0,1] neg_lo:[0,1,0]
	v_pk_mul_f32 v[50:51], v[56:57], s[38:39] op_sel:[0,0] op_sel_hi:[0,1]
	v_pk_mul_f32 v[54:55], v[42:43], s[36:37] op_sel:[0,0] op_sel_hi:[0,1]
	v_pk_fma_f32 v[18:19], v[42:43], s[36:37], v[54:55] op_sel:[1,1,0] op_sel_hi:[1,0,1] neg_lo:[0,1,0]
	v_pk_mul_f32 v[42:43], v[44:45], s[38:39] op_sel:[0,0] op_sel_hi:[0,1]
	v_pk_fma_f32 v[50:51], v[56:57], s[38:39], v[50:51] op_sel:[1,1,0] op_sel_hi:[1,0,1] neg_lo:[0,1,0]
	v_pk_add_f32 v[54:55], v[24:25], v[58:59] neg_lo:[0,1] neg_hi:[0,1]
	v_pk_fma_f32 v[22:23], v[44:45], s[38:39], v[42:43] op_sel:[1,1,0] op_sel_hi:[1,0,1] neg_lo:[0,1,0]
	v_pk_mul_f32 v[42:43], v[46:47], s[40:41] op_sel:[0,0] op_sel_hi:[0,1]
	v_pk_add_f32 v[44:45], v[62:63], v[70:71] neg_lo:[0,1] neg_hi:[0,1]
	v_pk_fma_f32 v[28:29], v[46:47], s[40:41], v[42:43] op_sel:[1,1,0] op_sel_hi:[1,0,1] neg_lo:[0,1,0]
	v_pk_add_f32 v[42:43], v[60:61], v[68:69] neg_lo:[0,1] neg_hi:[0,1]
	v_pk_add_f32 v[74:75], v[18:19], v[28:29] neg_lo:[0,1] neg_hi:[0,1]
	v_pk_add_f32 v[46:47], v[42:43], v[44:45] op_sel:[0,1] op_sel_hi:[1,0] neg_hi:[0,1]
	v_pk_add_f32 v[42:43], v[42:43], v[44:45] op_sel:[0,1] op_sel_hi:[1,0] neg_lo:[0,1]
	v_pk_add_f32 v[44:45], v[72:73], v[52:53] neg_lo:[0,1] neg_hi:[0,1]
	v_and_b32_e32 v19, 0xf0, v36
	v_pk_add_f32 v[56:57], v[44:45], v[54:55] op_sel:[0,1] op_sel_hi:[1,0] neg_hi:[0,1]
	v_pk_add_f32 v[44:45], v[44:45], v[54:55] op_sel:[0,1] op_sel_hi:[1,0] neg_lo:[0,1]
	v_pk_add_f32 v[54:55], v[48:49], v[26:27] neg_lo:[0,1] neg_hi:[0,1]
	v_pk_add_f32 v[64:65], v[20:21], v[50:51] neg_lo:[0,1] neg_hi:[0,1]
	v_mul_i32_i24_e32 v21, 0xfffff804, v38
	v_lshlrev_b32_e32 v19, 2, v19
	v_pk_add_f32 v[66:67], v[54:55], v[64:65] op_sel:[0,1] op_sel_hi:[1,0] neg_hi:[0,1]
	v_pk_add_f32 v[54:55], v[54:55], v[64:65] op_sel:[0,1] op_sel_hi:[1,0] neg_lo:[0,1]
	v_pk_add_f32 v[64:65], v[40:41], v[22:23] neg_lo:[0,1] neg_hi:[0,1]
	v_add3_u32 v19, v78, v21, v19
	v_add_f32_e32 v21, v62, v70
	v_add_f32_e32 v23, v60, v68
	v_add_f32_e32 v24, v24, v58
	v_add_f32_e32 v27, v72, v52
	v_add_f32_e32 v25, v23, v21
	v_add_f32_e32 v29, v27, v24
	v_mul_f32_e32 v25, 0x3a800000, v25
	v_mul_f32_e32 v29, 0x3a800000, v29
	ds_write2st64_b32 v19, v25, v29 offset1:4
	v_add_f32_e32 v20, v20, v50
	v_add_f32_e32 v25, v48, v26
	v_add_f32_e32 v18, v18, v28
	v_add_f32_e32 v22, v40, v22
	v_add_f32_e32 v26, v25, v20
	v_add_f32_e32 v28, v22, v18
	v_sub_f32_e32 v20, v25, v20
	v_sub_f32_e32 v18, v22, v18
	v_mul_f32_e32 v26, 0x3a800000, v26
	v_mul_f32_e32 v28, 0x3a800000, v28
	v_mul_f32_e32 v20, 0x3a800000, v20
	v_mul_f32_e32 v18, 0x3a800000, v18
	ds_write2st64_b32 v19, v26, v28 offset0:8 offset1:12
	v_mul_f32_e32 v26, 0x3a800000, v46
	v_mul_f32_e32 v28, 0x3a800000, v56
	v_sub_f32_e32 v21, v23, v21
	v_sub_f32_e32 v23, v27, v24
	ds_write2st64_b32 v19, v20, v18 offset0:40 offset1:44
	v_mul_f32_e32 v18, 0x3a800000, v42
	v_mul_f32_e32 v20, 0x3a800000, v44
	v_pk_add_f32 v[76:77], v[64:65], v[74:75] op_sel:[0,1] op_sel_hi:[1,0] neg_hi:[0,1]
	v_pk_add_f32 v[64:65], v[64:65], v[74:75] op_sel:[0,1] op_sel_hi:[1,0] neg_lo:[0,1]
	ds_write2st64_b32 v19, v26, v28 offset0:16 offset1:20
	v_mul_f32_e32 v26, 0x3a800000, v66
	v_mul_f32_e32 v28, 0x3a800000, v76
	v_mul_f32_e32 v21, 0x3a800000, v21
	v_mul_f32_e32 v23, 0x3a800000, v23
	ds_write2st64_b32 v19, v18, v20 offset0:48 offset1:52
	v_mul_f32_e32 v18, 0x3a800000, v54
	v_mul_f32_e32 v20, 0x3a800000, v64
	v_mov_b32_e32 v22, v34
	ds_write2st64_b32 v19, v26, v28 offset0:24 offset1:28
	ds_write2st64_b32 v19, v21, v23 offset0:32 offset1:36
	ds_write2st64_b32 v19, v18, v20 offset0:56 offset1:60
	s_waitcnt lgkmcnt(0)
	s_barrier
	v_lshlrev_b32_e32 v26, 12, v37
	v_lshl_add_u32 v23, v22, 5, v35
	ds_read_b128 v[18:21], v23
	v_lshlrev_b32_e32 v28, 3, v22
	ds_read_b128 v[22:25], v23 offset:16
	v_ashrrev_i32_e32 v27, 31, v26
	v_lshlrev_b64 v[26:27], 1, v[26:27]
	s_waitcnt lgkmcnt(1)
	v_cvt_pk_bf16_f32 v18, v18, v18
	v_lshrrev_b32_e32 v18, 16, v18
	v_cvt_pk_bf16_f32 v19, v19, v19
	v_and_or_b32 v18, v19, s56, v18
	v_cvt_pk_bf16_f32 v19, v20, v21
	s_waitcnt lgkmcnt(0)
	v_cvt_pk_bf16_f32 v20, v22, v23
	v_cvt_pk_bf16_f32 v21, v24, v25
	v_ashrrev_i32_e32 v29, 31, v28
	v_lshl_add_u64 v[22:23], v[28:29], 1, v[26:27]
	v_lshl_add_u64 v[22:23], s[6:7], 0, v[22:23]
	global_store_dwordx4 v[22:23], v[18:21], off
	s_nop 0
	v_lshl_add_u32 v22, v34, 5, v35
	ds_read_b128 v[18:21], v22 offset:8192
	ds_read_b128 v[22:25], v22 offset:8208
	v_lshl_add_u32 v28, v34, 3, v33
	s_waitcnt lgkmcnt(1)
	v_cvt_pk_bf16_f32 v18, v18, v18
	v_lshrrev_b32_e32 v18, 16, v18
	v_cvt_pk_bf16_f32 v19, v19, v19
	v_and_or_b32 v18, v19, s56, v18
	v_cvt_pk_bf16_f32 v19, v20, v21
	s_waitcnt lgkmcnt(0)
	v_cvt_pk_bf16_f32 v20, v22, v23
	v_cvt_pk_bf16_f32 v21, v24, v25
	v_ashrrev_i32_e32 v29, 31, v28
	v_lshl_add_u64 v[22:23], v[28:29], 1, v[26:27]
	v_lshl_add_u64 v[22:23], s[6:7], 0, v[22:23]
	s_add_u32 s6, s6, s20
	s_addc_u32 s7, s7, s21
	s_and_b64 vcc, exec, s[44:45]
	global_store_dwordx4 v[22:23], v[18:21], off
	s_barrier
	s_cbranch_vccnz .LBB0_3755
